# attention: static s_setprio 1 for waves 0-3 + no vmcnt(0) drain at unit end
# baseline (speedup 1.0000x reference)
.LBB0_57:
	v_lshl_add_u64 v[154:155], v[144:145], 0, s[8:9]
	v_add_co_u32_e32 v164, vcc, s14, v154
	ds_read_b128 v[12:15], v158
	ds_read_b128 v[4:7], v158 offset:16
	ds_read_b128 v[0:3], v158 offset:4096
	ds_read_b128 v[8:11], v158 offset:4112
	ds_read_b128 v[48:51], v158 offset:8192
	ds_read_b128 v[40:43], v158 offset:8208
	ds_read_b128 v[20:23], v158 offset:12288
	ds_read_b128 v[16:19], v158 offset:12304
	ds_read_b128 v[52:55], v158 offset:16384
	ds_read_b128 v[44:47], v158 offset:16400
	ds_read_b128 v[28:31], v158 offset:20480
	ds_read_b128 v[24:27], v158 offset:20496
	ds_read_b128 v[64:67], v158 offset:24576
	ds_read_b128 v[56:59], v158 offset:24592
	ds_read_b128 v[36:39], v158 offset:28672
	ds_read_b128 v[32:35], v158 offset:28688
	v_addc_co_u32_e32 v165, vcc, 0, v155, vcc
	v_add_co_u32_e32 v166, vcc, s15, v154
	ds_read_b128 v[68:71], v158 offset:32768
	ds_read_b128 v[60:63], v158 offset:32784
	ds_read_b128 v[80:83], v158 offset:32
	ds_read_b128 v[76:79], v158 offset:48
	ds_read_b128 v[72:75], v158 offset:4128
	ds_read_b128 v[84:87], v158 offset:4144
	ds_read_b128 v[116:119], v158 offset:8224
	ds_read_b128 v[112:115], v158 offset:8240
	ds_read_b128 v[92:95], v158 offset:12320
	ds_read_b128 v[88:91], v158 offset:12336
	ds_read_b128 v[128:131], v158 offset:16416
	ds_read_b128 v[120:123], v158 offset:16432
	ds_read_b128 v[100:103], v158 offset:20512
	ds_read_b128 v[96:99], v158 offset:20528
	ds_read_b128 v[132:135], v158 offset:24608
	ds_read_b128 v[124:127], v158 offset:24624
	ds_read_b128 v[108:111], v158 offset:28704
	ds_read_b128 v[104:107], v158 offset:28720
	ds_read_b128 v[160:163], v158 offset:32800
	ds_read_b128 v[136:139], v158 offset:32816
	v_addc_co_u32_e32 v167, vcc, 0, v155, vcc
	v_add_co_u32_e32 v168, vcc, s33, v154
	s_waitcnt lgkmcnt(14)
	v_mov_b32_e32 v194, v12
	v_addc_co_u32_e32 v169, vcc, 0, v155, vcc
	v_add_co_u32_e32 v170, vcc, s82, v154
	v_mov_b32_e32 v195, v0
	s_nop 0
	v_addc_co_u32_e32 v171, vcc, 0, v155, vcc
	v_add_co_u32_e32 v172, vcc, s83, v154
	v_mov_b32_e32 v0, v13
	s_nop 0
	v_addc_co_u32_e32 v173, vcc, 0, v155, vcc
	v_add_co_u32_e32 v174, vcc, s84, v154
	v_mov_b32_e32 v12, v14
	s_nop 0
	v_addc_co_u32_e32 v175, vcc, 0, v155, vcc
	v_add_co_u32_e32 v176, vcc, s85, v154
	v_mov_b32_e32 v13, v2
	s_nop 0
	v_addc_co_u32_e32 v177, vcc, 0, v155, vcc
	v_add_co_u32_e32 v178, vcc, s86, v154
	v_mov_b32_e32 v2, v15
	s_nop 0
	v_addc_co_u32_e32 v179, vcc, 0, v155, vcc
	v_add_co_u32_e32 v180, vcc, s87, v154
	v_mov_b32_e32 v14, v48
	s_nop 0
	v_addc_co_u32_e32 v181, vcc, 0, v155, vcc
	v_add_co_u32_e32 v182, vcc, s88, v154
	v_mov_b32_e32 v15, v20
	s_nop 0
	v_addc_co_u32_e32 v183, vcc, 0, v155, vcc
	v_add_co_u32_e32 v184, vcc, s89, v154
	v_mov_b32_e32 v20, v49
	s_nop 0
	v_addc_co_u32_e32 v185, vcc, 0, v155, vcc
	v_add_co_u32_e32 v186, vcc, s90, v154
	v_mov_b32_e32 v48, v50
	s_nop 0
	v_addc_co_u32_e32 v187, vcc, 0, v155, vcc
	v_add_co_u32_e32 v188, vcc, s91, v154
	v_mov_b32_e32 v49, v22
	s_nop 0
	v_addc_co_u32_e32 v189, vcc, 0, v155, vcc
	v_add_co_u32_e32 v190, vcc, s92, v154
	v_mov_b32_e32 v22, v51
	s_nop 0
	v_addc_co_u32_e32 v191, vcc, 0, v155, vcc
	v_add_co_u32_e32 v192, vcc, s93, v154
	v_mov_b32_e32 v50, v52
	s_nop 0
	v_addc_co_u32_e32 v193, vcc, 0, v155, vcc
	global_load_dword v164, v[164:165], off
	s_nop 0
	global_load_dword v166, v[166:167], off
	s_nop 0
	global_load_dword v168, v[168:169], off
	s_nop 0
	global_load_dword v170, v[170:171], off
	s_nop 0
	global_load_dword v172, v[172:173], off
	s_nop 0
	global_load_dword v174, v[174:175], off
	s_nop 0
	global_load_dword v176, v[176:177], off
	s_nop 0
	global_load_dword v154, v[154:155], off
	s_nop 0
	global_load_dword v178, v[178:179], off
	s_nop 0
	global_load_dword v180, v[180:181], off
	s_nop 0
	global_load_dword v182, v[182:183], off
	s_nop 0
	global_load_dword v184, v[184:185], off
	s_nop 0
	global_load_dword v186, v[186:187], off
	s_nop 0
	global_load_dword v188, v[188:189], off
	s_nop 0
	global_load_dword v190, v[190:191], off
	s_nop 0
	global_load_dword v192, v[192:193], off
	v_mov_b32_e32 v51, v28
	v_mov_b32_e32 v28, v53
	v_mov_b32_e32 v52, v54
	v_mov_b32_e32 v53, v30
	v_mov_b32_e32 v30, v55
	v_mov_b32_e32 v54, v64
	v_mov_b32_e32 v55, v36
	v_mov_b32_e32 v36, v65
	v_mov_b32_e32 v64, v66
	v_mov_b32_e32 v65, v38
	v_mov_b32_e32 v38, v67
	v_mov_b32_e32 v66, v4
	v_mov_b32_e32 v67, v8
	v_mov_b32_e32 v8, v5
	v_mov_b32_e32 v4, v6
	v_mov_b32_e32 v5, v10
	v_mov_b32_e32 v10, v7
	v_mov_b32_e32 v6, v40
	v_mov_b32_e32 v7, v16
	v_mov_b32_e32 v16, v41
	v_mov_b32_e32 v40, v42
	v_mov_b32_e32 v41, v18
	v_mov_b32_e32 v18, v43
	v_mov_b32_e32 v42, v44
	v_mov_b32_e32 v43, v24
	v_mov_b32_e32 v24, v45
	v_mov_b32_e32 v44, v46
	v_mov_b32_e32 v45, v26
	v_mov_b32_e32 v26, v47
	v_mov_b32_e32 v46, v56
	v_mov_b32_e32 v47, v32
	v_mov_b32_e32 v32, v57
	v_mov_b32_e32 v56, v58
	v_mov_b32_e32 v57, v34
	v_mov_b32_e32 v34, v59
	v_mov_b32_e32 v58, v80
	v_mov_b32_e32 v59, v72
	v_mov_b32_e32 v72, v81
	v_mov_b32_e32 v80, v82
	v_mov_b32_e32 v81, v74
	v_mov_b32_e32 v74, v83
	s_waitcnt lgkmcnt(13)
	v_mov_b32_e32 v82, v116
	s_waitcnt lgkmcnt(11)
	v_mov_b32_e32 v83, v92
	v_mov_b32_e32 v92, v117
	v_mov_b32_e32 v116, v118
	v_mov_b32_e32 v117, v94
	v_mov_b32_e32 v94, v119
	s_waitcnt lgkmcnt(9)
	v_mov_b32_e32 v118, v128
	s_waitcnt lgkmcnt(7)
	v_mov_b32_e32 v119, v100
	v_mov_b32_e32 v100, v129
	v_mov_b32_e32 v128, v130
	v_mov_b32_e32 v129, v102
	v_mov_b32_e32 v102, v131
	s_waitcnt lgkmcnt(5)
	v_mov_b32_e32 v130, v132
	s_waitcnt lgkmcnt(3)
	v_mov_b32_e32 v131, v108
	v_mov_b32_e32 v108, v133
	v_mov_b32_e32 v132, v134
	v_mov_b32_e32 v133, v110
	v_mov_b32_e32 v110, v135
	v_mov_b32_e32 v134, v76
	v_mov_b32_e32 v135, v84
	v_mov_b32_e32 v84, v77
	v_mov_b32_e32 v76, v78
	v_mov_b32_e32 v77, v86
	v_mov_b32_e32 v86, v79
	v_mov_b32_e32 v78, v112
	v_mov_b32_e32 v79, v88
	v_mov_b32_e32 v88, v113
	v_mov_b32_e32 v112, v114
	v_mov_b32_e32 v113, v90
	v_mov_b32_e32 v90, v115
	v_mov_b32_e32 v114, v120
	v_mov_b32_e32 v115, v96
	v_mov_b32_e32 v96, v121
	v_mov_b32_e32 v120, v122
	v_mov_b32_e32 v121, v98
	v_mov_b32_e32 v98, v123
	v_mov_b32_e32 v122, v124
	s_waitcnt lgkmcnt(2)
	v_mov_b32_e32 v123, v104
	v_mov_b32_e32 v104, v125
	v_mov_b32_e32 v124, v126
	v_mov_b32_e32 v125, v106
	v_mov_b32_e32 v106, v127
	s_waitcnt vmcnt(8)
	v_pk_fma_f32 v[126:127], v[154:155], v[194:195], v[146:147] op_sel_hi:[0,1,1]
	v_pk_fma_f32 v[14:15], v[154:155], v[14:15], v[148:149] op_sel_hi:[0,1,1]
	v_pk_fma_f32 v[50:51], v[154:155], v[50:51], v[150:151] op_sel_hi:[0,1,1]
	v_pk_fma_f32 v[54:55], v[154:155], v[54:55], v[152:153] op_sel_hi:[0,1,1]
	v_fmac_f32_e32 v159, v154, v68
	v_pk_fma_f32 v[0:1], v[164:165], v[0:1], v[126:127] op_sel_hi:[0,1,1]
	v_pk_fma_f32 v[14:15], v[164:165], v[20:21], v[14:15] op_sel_hi:[0,1,1]
	v_pk_fma_f32 v[20:21], v[164:165], v[28:29], v[50:51] op_sel_hi:[0,1,1]
	v_pk_fma_f32 v[28:29], v[164:165], v[36:37], v[54:55] op_sel_hi:[0,1,1]
	v_fmac_f32_e32 v159, v164, v69
	v_pk_fma_f32 v[0:1], v[166:167], v[12:13], v[0:1] op_sel_hi:[0,1,1]
	v_pk_fma_f32 v[12:13], v[166:167], v[48:49], v[14:15] op_sel_hi:[0,1,1]
	v_pk_fma_f32 v[14:15], v[166:167], v[52:53], v[20:21] op_sel_hi:[0,1,1]
	v_pk_fma_f32 v[20:21], v[166:167], v[64:65], v[28:29] op_sel_hi:[0,1,1]
	v_fmac_f32_e32 v159, v166, v70
	v_pk_fma_f32 v[0:1], v[168:169], v[2:3], v[0:1] op_sel_hi:[0,1,1]
	v_pk_fma_f32 v[2:3], v[168:169], v[22:23], v[12:13] op_sel_hi:[0,1,1]
	v_pk_fma_f32 v[12:13], v[168:169], v[30:31], v[14:15] op_sel_hi:[0,1,1]
	v_pk_fma_f32 v[14:15], v[168:169], v[38:39], v[20:21] op_sel_hi:[0,1,1]
	v_fmac_f32_e32 v159, v168, v71
	v_pk_fma_f32 v[0:1], v[170:171], v[66:67], v[0:1] op_sel_hi:[0,1,1]
	v_pk_fma_f32 v[2:3], v[170:171], v[6:7], v[2:3] op_sel_hi:[0,1,1]
	v_pk_fma_f32 v[6:7], v[170:171], v[42:43], v[12:13] op_sel_hi:[0,1,1]
	v_pk_fma_f32 v[12:13], v[170:171], v[46:47], v[14:15] op_sel_hi:[0,1,1]
	v_fmac_f32_e32 v159, v170, v60
	v_pk_fma_f32 v[0:1], v[172:173], v[8:9], v[0:1] op_sel_hi:[0,1,1]
	v_pk_fma_f32 v[2:3], v[172:173], v[16:17], v[2:3] op_sel_hi:[0,1,1]
	v_pk_fma_f32 v[6:7], v[172:173], v[24:25], v[6:7] op_sel_hi:[0,1,1]
	v_pk_fma_f32 v[8:9], v[172:173], v[32:33], v[12:13] op_sel_hi:[0,1,1]
	v_fmac_f32_e32 v159, v172, v61
	v_pk_fma_f32 v[0:1], v[174:175], v[4:5], v[0:1] op_sel_hi:[0,1,1]
	v_pk_fma_f32 v[2:3], v[174:175], v[40:41], v[2:3] op_sel_hi:[0,1,1]
	v_pk_fma_f32 v[4:5], v[174:175], v[44:45], v[6:7] op_sel_hi:[0,1,1]
	v_pk_fma_f32 v[6:7], v[174:175], v[56:57], v[8:9] op_sel_hi:[0,1,1]
	v_fmac_f32_e32 v159, v174, v62
	v_pk_fma_f32 v[0:1], v[176:177], v[10:11], v[0:1] op_sel_hi:[0,1,1]
	v_pk_fma_f32 v[2:3], v[176:177], v[18:19], v[2:3] op_sel_hi:[0,1,1]
	v_pk_fma_f32 v[4:5], v[176:177], v[26:27], v[4:5] op_sel_hi:[0,1,1]
	v_pk_fma_f32 v[6:7], v[176:177], v[34:35], v[6:7] op_sel_hi:[0,1,1]
	v_fmac_f32_e32 v159, v176, v63
	s_waitcnt vmcnt(7)
	v_pk_fma_f32 v[0:1], v[178:179], v[58:59], v[0:1] op_sel_hi:[0,1,1]
	v_pk_fma_f32 v[2:3], v[178:179], v[82:83], v[2:3] op_sel_hi:[0,1,1]
	v_pk_fma_f32 v[4:5], v[178:179], v[118:119], v[4:5] op_sel_hi:[0,1,1]
	v_pk_fma_f32 v[6:7], v[178:179], v[130:131], v[6:7] op_sel_hi:[0,1,1]
	s_waitcnt lgkmcnt(1)
	v_fmac_f32_e32 v159, v178, v160
	s_waitcnt vmcnt(6)
	v_pk_fma_f32 v[0:1], v[180:181], v[72:73], v[0:1] op_sel_hi:[0,1,1]
	v_pk_fma_f32 v[2:3], v[180:181], v[92:93], v[2:3] op_sel_hi:[0,1,1]
	v_pk_fma_f32 v[4:5], v[180:181], v[100:101], v[4:5] op_sel_hi:[0,1,1]
	v_pk_fma_f32 v[6:7], v[180:181], v[108:109], v[6:7] op_sel_hi:[0,1,1]
	v_fmac_f32_e32 v159, v180, v161
	s_waitcnt vmcnt(5)
	v_pk_fma_f32 v[0:1], v[182:183], v[80:81], v[0:1] op_sel_hi:[0,1,1]
	v_pk_fma_f32 v[2:3], v[182:183], v[116:117], v[2:3] op_sel_hi:[0,1,1]
	v_pk_fma_f32 v[4:5], v[182:183], v[128:129], v[4:5] op_sel_hi:[0,1,1]
	v_pk_fma_f32 v[6:7], v[182:183], v[132:133], v[6:7] op_sel_hi:[0,1,1]
	v_fmac_f32_e32 v159, v182, v162
	s_waitcnt vmcnt(4)
	v_pk_fma_f32 v[0:1], v[184:185], v[74:75], v[0:1] op_sel_hi:[0,1,1]
	v_pk_fma_f32 v[2:3], v[184:185], v[94:95], v[2:3] op_sel_hi:[0,1,1]
	v_pk_fma_f32 v[4:5], v[184:185], v[102:103], v[4:5] op_sel_hi:[0,1,1]
	v_pk_fma_f32 v[6:7], v[184:185], v[110:111], v[6:7] op_sel_hi:[0,1,1]
	v_fmac_f32_e32 v159, v184, v163
	s_waitcnt vmcnt(3)
	v_pk_fma_f32 v[0:1], v[186:187], v[134:135], v[0:1] op_sel_hi:[0,1,1]
	v_pk_fma_f32 v[2:3], v[186:187], v[78:79], v[2:3] op_sel_hi:[0,1,1]
	v_pk_fma_f32 v[4:5], v[186:187], v[114:115], v[4:5] op_sel_hi:[0,1,1]
	v_pk_fma_f32 v[6:7], v[186:187], v[122:123], v[6:7] op_sel_hi:[0,1,1]
	s_waitcnt lgkmcnt(0)
	v_fmac_f32_e32 v159, v186, v136
	s_add_u32 s8, s8, 0x30000
	s_waitcnt vmcnt(2)
	v_pk_fma_f32 v[0:1], v[188:189], v[84:85], v[0:1] op_sel_hi:[0,1,1]
	v_pk_fma_f32 v[2:3], v[188:189], v[88:89], v[2:3] op_sel_hi:[0,1,1]
	v_pk_fma_f32 v[4:5], v[188:189], v[96:97], v[4:5] op_sel_hi:[0,1,1]
	v_pk_fma_f32 v[6:7], v[188:189], v[104:105], v[6:7] op_sel_hi:[0,1,1]
	v_fmac_f32_e32 v159, v188, v137
	s_addc_u32 s9, s9, 0
	s_waitcnt vmcnt(1)
	v_pk_fma_f32 v[0:1], v[190:191], v[76:77], v[0:1] op_sel_hi:[0,1,1]
	v_pk_fma_f32 v[2:3], v[190:191], v[112:113], v[2:3] op_sel_hi:[0,1,1]
	v_pk_fma_f32 v[4:5], v[190:191], v[120:121], v[4:5] op_sel_hi:[0,1,1]
	v_pk_fma_f32 v[6:7], v[190:191], v[124:125], v[6:7] op_sel_hi:[0,1,1]
	v_fmac_f32_e32 v159, v190, v138
	v_add_u32_e32 v158, 64, v158
	s_cmp_eq_u32 s8, 0xc0000
	s_waitcnt vmcnt(0)
	v_pk_fma_f32 v[146:147], v[192:193], v[86:87], v[0:1] op_sel_hi:[0,1,1]
	v_pk_fma_f32 v[148:149], v[192:193], v[90:91], v[2:3] op_sel_hi:[0,1,1]
	v_pk_fma_f32 v[150:151], v[192:193], v[98:99], v[4:5] op_sel_hi:[0,1,1]
	v_pk_fma_f32 v[152:153], v[192:193], v[106:107], v[6:7] op_sel_hi:[0,1,1]
	v_fmac_f32_e32 v159, v192, v139
	s_cbranch_scc0 .LBB0_57
	v_lshl_add_u32 v0, v140, 2, 0
	v_mad_u64_u32 v[2:3], s[8:9], v143, s94, v[0:1]
	v_add_u32_e32 v1, 0x9000, v2
	v_cmp_gt_i32_e32 vcc, s95, v142
	ds_write2_b32 v1, v146, v147 offset1:32
	ds_write2_b32 v1, v148, v149 offset0:64 offset1:96
	ds_write2_b32 v1, v150, v151 offset0:128 offset1:160
	ds_write2_b32 v1, v152, v153 offset0:192 offset1:224
	ds_write_b32 v2, v159 offset:37888
	s_waitcnt lgkmcnt(0)
	s_barrier
	s_and_saveexec_b64 s[8:9], vcc
	s_cbranch_execz .LBB0_52
	s_mul_i32 s7, s10, 0xc00
	s_add_i32 s7, s7, s6
	v_or_b32_e32 v2, s7, v140
	v_ashrrev_i32_e32 v3, 31, v2
	v_lshl_add_u64 v[2:3], v[2:3], 2, s[62:63]
	global_load_dword v1, v[2:3], off
	v_lshl_add_u32 v16, v143, 7, v0
	ds_read_b32 v0, v16 offset:36864
	ds_read_b32 v2, v16 offset:38016
	ds_read_b32 v3, v16 offset:39168
	ds_read_b32 v4, v16 offset:40320
	ds_read_b32 v5, v16 offset:41472
	ds_read_b32 v6, v16 offset:42624
	ds_read_b32 v7, v16 offset:43776
	ds_read_b32 v8, v16 offset:44928
	ds_read_b32 v9, v16 offset:46080
	ds_read_b32 v10, v16 offset:47232
	ds_read_b32 v11, v16 offset:48384
	ds_read_b32 v12, v16 offset:49536
	ds_read_b32 v13, v16 offset:50688
	ds_read_b32 v14, v16 offset:51840
	ds_read_b32 v15, v16 offset:52992
	ds_read_b32 v16, v16 offset:54144
	s_add_i32 s7, s97, 0x5f
	s_cmpk_lt_u32 s7, 0xbf
	s_cselect_b64 s[12:13], -1, 0
	s_and_b64 vcc, exec, s[12:13]
	s_cbranch_vccnz .LBB0_61
	v_cmp_gt_i32_e32 vcc, 8, v143
	s_andn2_b64 s[12:13], s[12:13], exec
	s_and_b64 vcc, vcc, exec
	s_mov_b64 s[10:11], 0x151b000
	s_or_b64 s[12:13], s[12:13], vcc
	s_and_b64 exec, exec, s[12:13]
	s_cbranch_execz .LBB0_52
	s_branch .LBB0_51

.LBB0_104:
	v_lshl_add_u64 v[28:29], v[8:9], 0, s[8:9]
	global_load_dword v30, v[28:29], off
	global_load_dword v32, v[28:29], off offset:256
	global_load_dword v36, v[28:29], off offset:512
	global_load_dword v38, v[28:29], off offset:768
	global_load_dword v40, v[28:29], off offset:1024
	global_load_dword v42, v[28:29], off offset:1280
	global_load_dword v44, v[28:29], off offset:1536
	global_load_dword v46, v[28:29], off offset:1792
	global_load_dword v48, v[28:29], off offset:2048
	global_load_dword v50, v[28:29], off offset:2304
	s_nop 0
	global_load_dword v28, v[28:29], off offset:2560
	ds_read2_b32 v[52:53], v0 offset1:1
	ds_read2_b32 v[54:55], v0 offset0:2 offset1:3
	ds_read2_b32 v[56:57], v0 offset0:4 offset1:5
	ds_read2_b32 v[58:59], v0 offset0:6 offset1:7
	ds_read2_b32 v[60:61], v0 offset0:128 offset1:129
	ds_read2_b32 v[62:63], v0 offset0:130 offset1:131
	ds_read2_b32 v[64:65], v0 offset0:132 offset1:133
	ds_read2_b32 v[66:67], v0 offset0:8 offset1:9
	ds_read2_b32 v[68:69], v0 offset0:134 offset1:135
	ds_read2_b32 v[70:71], v0 offset0:136 offset1:137
	ds_read2_b32 v[72:73], v0 offset0:10 offset1:138
	s_waitcnt lgkmcnt(10)
	v_mov_b32_e32 v74, v52
	s_waitcnt lgkmcnt(6)
	v_mov_b32_e32 v75, v60
	v_mov_b32_e32 v60, v53
	v_mov_b32_e32 v52, v54
	s_waitcnt lgkmcnt(5)
	v_mov_b32_e32 v53, v62
	v_mov_b32_e32 v62, v55
	v_mov_b32_e32 v54, v56
	s_waitcnt lgkmcnt(4)
	v_mov_b32_e32 v55, v64
	v_mov_b32_e32 v64, v57
	v_mov_b32_e32 v56, v58
	s_waitcnt lgkmcnt(2)
	v_mov_b32_e32 v57, v68
	v_mov_b32_e32 v68, v59
	v_mov_b32_e32 v58, v66
	s_waitcnt lgkmcnt(1)
	v_mov_b32_e32 v59, v70
	s_add_u32 s8, s8, 0xb00
	v_mov_b32_e32 v70, v67
	s_addc_u32 s9, s9, 0
	v_add_u32_e32 v0, 44, v0
	s_cmpk_eq_i32 s8, 0x2100
	s_waitcnt vmcnt(10)
	v_pk_fma_f32 v[12:13], v[30:31], v[74:75], v[12:13] op_sel_hi:[0,1,1]
	s_waitcnt vmcnt(9)
	v_pk_fma_f32 v[12:13], v[32:33], v[60:61], v[12:13] op_sel_hi:[0,1,1]
	s_waitcnt vmcnt(8)
	v_pk_fma_f32 v[12:13], v[36:37], v[52:53], v[12:13] op_sel_hi:[0,1,1]
	s_waitcnt vmcnt(7)
	v_pk_fma_f32 v[12:13], v[38:39], v[62:63], v[12:13] op_sel_hi:[0,1,1]
	s_waitcnt vmcnt(6)
	v_pk_fma_f32 v[12:13], v[40:41], v[54:55], v[12:13] op_sel_hi:[0,1,1]
	s_waitcnt vmcnt(5)
	v_pk_fma_f32 v[12:13], v[42:43], v[64:65], v[12:13] op_sel_hi:[0,1,1]
	s_waitcnt vmcnt(4)
	v_pk_fma_f32 v[12:13], v[44:45], v[56:57], v[12:13] op_sel_hi:[0,1,1]
	s_waitcnt vmcnt(3)
	v_pk_fma_f32 v[12:13], v[46:47], v[68:69], v[12:13] op_sel_hi:[0,1,1]
	s_waitcnt vmcnt(2)
	v_pk_fma_f32 v[12:13], v[48:49], v[58:59], v[12:13] op_sel_hi:[0,1,1]
	s_waitcnt vmcnt(1)
	v_pk_fma_f32 v[12:13], v[50:51], v[70:71], v[12:13] op_sel_hi:[0,1,1]
	s_waitcnt vmcnt(0) lgkmcnt(0)
	v_pk_fma_f32 v[12:13], v[28:29], v[72:73], v[12:13] op_sel_hi:[0,1,1]
	s_cbranch_scc0 .LBB0_104
	global_load_dword v27, v[4:5], off
	s_waitcnt vmcnt(0)
	v_mul_f32_e32 v12, v12, v27
	v_and_b32_e32 v28, 0x7fffffff, v12
	v_cmp_nlt_f32_e64 s[8:9], |v12|, s33
	s_and_saveexec_b64 s[10:11], s[8:9]
	s_xor_b64 s[42:43], exec, s[10:11]
	s_cbranch_execz .LBB0_107
	v_lshrrev_b32_e32 v0, 23, v28
	v_add_u32_e32 v0, 0xffffff88, v0
	v_cmp_lt_u32_e64 s[8:9], 63, v0
	s_nop 1
	v_cndmask_b32_e64 v29, 0, v22, s[8:9]
	v_add_u32_e32 v0, v29, v0
	v_cmp_lt_u32_e64 s[10:11], 31, v0
	s_nop 1
	v_cndmask_b32_e64 v29, 0, v23, s[10:11]
	v_add_u32_e32 v0, v29, v0
	v_cmp_lt_u32_e64 s[12:13], 31, v0
	s_nop 1
	v_cndmask_b32_e64 v29, 0, v23, s[12:13]
	v_add_u32_e32 v29, v29, v0
	v_and_b32_e32 v0, 0x7fffff, v28
	v_or_b32_e32 v35, 0x800000, v0
	v_mad_u64_u32 v[30:31], s[14:15], v35, s68, 0
	v_mov_b32_e32 v0, v31
	v_mad_u64_u32 v[32:33], s[14:15], v35, s69, v[0:1]
	v_mov_b32_e32 v0, v33
	v_mad_u64_u32 v[36:37], s[14:15], v35, s82, v[0:1]
	v_mov_b32_e32 v0, v37
	v_mad_u64_u32 v[38:39], s[14:15], v35, s83, v[0:1]
	v_mov_b32_e32 v0, v39
	v_mad_u64_u32 v[40:41], s[14:15], v35, s84, v[0:1]
	v_mov_b32_e32 v0, v41
	v_mad_u64_u32 v[42:43], s[14:15], v35, s85, v[0:1]
	v_mov_b32_e32 v0, v43
	v_mad_u64_u32 v[44:45], s[14:15], v35, s86, v[0:1]
	v_cndmask_b32_e64 v31, v42, v38, s[8:9]
	v_cndmask_b32_e64 v0, v44, v40, s[8:9]
	v_cndmask_b32_e64 v35, v45, v42, s[8:9]
	v_cndmask_b32_e64 v33, v0, v31, s[10:11]
	v_cndmask_b32_e64 v0, v35, v0, s[10:11]
	v_cndmask_b32_e64 v35, v40, v36, s[8:9]
	v_cndmask_b32_e64 v31, v31, v35, s[10:11]
	v_sub_u32_e32 v37, 32, v29
	v_cmp_eq_u32_e64 s[14:15], 0, v29
	v_cndmask_b32_e64 v29, v38, v32, s[8:9]
	v_cndmask_b32_e64 v0, v0, v33, s[12:13]
	v_cndmask_b32_e64 v33, v33, v31, s[12:13]
	v_cndmask_b32_e64 v32, v35, v29, s[10:11]
	v_alignbit_b32 v39, v0, v33, v37
	v_cndmask_b32_e64 v31, v31, v32, s[12:13]
	v_cndmask_b32_e64 v0, v39, v0, s[14:15]
	v_alignbit_b32 v35, v33, v31, v37
	v_cndmask_b32_e64 v30, v36, v30, s[8:9]
	v_cndmask_b32_e64 v33, v35, v33, s[14:15]
	v_bfe_u32 v39, v0, 29, 1
	v_cndmask_b32_e64 v29, v29, v30, s[10:11]
	v_alignbit_b32 v35, v0, v33, 30
	v_sub_u32_e32 v40, 0, v39
	v_cndmask_b32_e64 v29, v32, v29, s[12:13]
	v_xor_b32_e32 v35, v35, v40
	v_alignbit_b32 v30, v31, v29, v37
	v_cndmask_b32_e64 v30, v30, v31, s[14:15]
	v_ffbh_u32_e32 v32, v35
	v_alignbit_b32 v31, v33, v30, 30
	v_min_u32_e32 v32, 32, v32
	v_alignbit_b32 v29, v30, v29, 30
	v_xor_b32_e32 v31, v31, v40
	v_sub_u32_e32 v33, 31, v32
	v_xor_b32_e32 v29, v29, v40
	v_alignbit_b32 v35, v35, v31, v33
	v_alignbit_b32 v29, v31, v29, v33
	v_alignbit_b32 v30, v35, v29, 9
	v_ffbh_u32_e32 v31, v30
	v_min_u32_e32 v31, 32, v31
	v_lshrrev_b32_e32 v38, 29, v0
	v_not_b32_e32 v33, v31
	v_alignbit_b32 v29, v30, v29, v33
	v_lshlrev_b32_e32 v30, 31, v38
	v_or_b32_e32 v33, 0x33000000, v30
	v_add_lshl_u32 v31, v31, v32, 23
	v_lshrrev_b32_e32 v29, 9, v29
	v_sub_u32_e32 v31, v33, v31
	v_or_b32_e32 v30, 0.5, v30
	v_lshlrev_b32_e32 v32, 23, v32
	v_or_b32_e32 v29, v31, v29
	v_lshrrev_b32_e32 v31, 9, v35
	v_sub_u32_e32 v30, v30, v32
	v_or_b32_e32 v30, v31, v30
	v_mul_f32_e32 v31, 0x3fc90fda, v30
	v_fma_f32 v32, v30, s87, -v31
	v_fmac_f32_e32 v32, 0x33a22168, v30
	v_fmac_f32_e32 v32, 0x3fc90fda, v29
	v_lshrrev_b32_e32 v0, 30, v0
	v_add_f32_e32 v29, v31, v32
	v_add_u32_e32 v0, v39, v0

.LBB0_114:
	v_lshl_add_u64 v[28:29], v[10:11], 0, s[8:9]
	global_load_dword v32, v[28:29], off
	global_load_dword v64, v[28:29], off offset:256
	global_load_dword v66, v[28:29], off offset:512
	global_load_dword v68, v[28:29], off offset:768
	global_load_dword v70, v[28:29], off offset:1024
	global_load_dword v72, v[28:29], off offset:1280
	global_load_dword v74, v[28:29], off offset:1536
	global_load_dword v76, v[28:29], off offset:1792
	global_load_dword v78, v[28:29], off offset:2048
	global_load_dword v80, v[28:29], off offset:2304
	global_load_dword v82, v[28:29], off offset:2560
	global_load_dword v84, v[28:29], off offset:2816
	global_load_dword v86, v[28:29], off offset:3072
	global_load_dword v88, v[28:29], off offset:3328
	global_load_dword v90, v[28:29], off offset:3584
	global_load_dword v92, v[28:29], off offset:3840
	ds_read_b128 v[28:31], v0
	ds_read_b128 v[36:39], v0 offset:16
	ds_read_b128 v[40:43], v0 offset:32
	ds_read_b128 v[44:47], v0 offset:48
	ds_read_b128 v[48:51], v0 offset:512
	ds_read_b128 v[52:55], v0 offset:528
	ds_read_b128 v[56:59], v0 offset:544
	ds_read_b128 v[60:63], v0 offset:560
	s_waitcnt lgkmcnt(7)
	v_mov_b32_e32 v95, v28
	s_waitcnt lgkmcnt(3)
	v_mov_b32_e32 v94, v48
	v_mov_b32_e32 v28, v49
	v_mov_b32_e32 v48, v50
	v_mov_b32_e32 v49, v30
	v_mov_b32_e32 v30, v51
	s_waitcnt lgkmcnt(2)
	v_mov_b32_e32 v50, v52
	v_mov_b32_e32 v51, v36
	v_mov_b32_e32 v36, v53
	v_mov_b32_e32 v52, v54
	v_mov_b32_e32 v53, v38
	v_mov_b32_e32 v38, v55
	s_waitcnt lgkmcnt(1)
	v_mov_b32_e32 v54, v56
	v_mov_b32_e32 v55, v40
	v_mov_b32_e32 v40, v57
	v_mov_b32_e32 v56, v58
	v_mov_b32_e32 v57, v42
	v_mov_b32_e32 v42, v59
	s_waitcnt lgkmcnt(0)
	v_mov_b32_e32 v58, v60
	v_mov_b32_e32 v59, v44
	v_mov_b32_e32 v44, v61
	s_add_u32 s8, s8, 0x1000
	v_mov_b32_e32 v60, v62
	v_mov_b32_e32 v61, v46
	s_addc_u32 s9, s9, 0
	v_mov_b32_e32 v46, v63
	v_add_u32_e32 v0, 64, v0
	s_cmpk_eq_i32 s8, 0x4000
	s_waitcnt vmcnt(15)
	v_pk_fma_f32 v[12:13], v[32:33], v[94:95], v[12:13] op_sel_hi:[0,1,1]
	s_waitcnt vmcnt(14)
	v_pk_fma_f32 v[12:13], v[64:65], v[28:29], v[12:13] op_sel_hi:[0,1,1]
	s_waitcnt vmcnt(13)
	v_pk_fma_f32 v[12:13], v[66:67], v[48:49], v[12:13] op_sel_hi:[0,1,1]
	s_waitcnt vmcnt(12)
	v_pk_fma_f32 v[12:13], v[68:69], v[30:31], v[12:13] op_sel_hi:[0,1,1]
	s_waitcnt vmcnt(11)
	v_pk_fma_f32 v[12:13], v[70:71], v[50:51], v[12:13] op_sel_hi:[0,1,1]
	s_waitcnt vmcnt(10)
	v_pk_fma_f32 v[12:13], v[72:73], v[36:37], v[12:13] op_sel_hi:[0,1,1]
	s_waitcnt vmcnt(9)
	v_pk_fma_f32 v[12:13], v[74:75], v[52:53], v[12:13] op_sel_hi:[0,1,1]
	s_waitcnt vmcnt(8)
	v_pk_fma_f32 v[12:13], v[76:77], v[38:39], v[12:13] op_sel_hi:[0,1,1]
	s_waitcnt vmcnt(7)
	v_pk_fma_f32 v[12:13], v[78:79], v[54:55], v[12:13] op_sel_hi:[0,1,1]
	s_waitcnt vmcnt(6)
	v_pk_fma_f32 v[12:13], v[80:81], v[40:41], v[12:13] op_sel_hi:[0,1,1]
	s_waitcnt vmcnt(5)
	v_pk_fma_f32 v[12:13], v[82:83], v[56:57], v[12:13] op_sel_hi:[0,1,1]
	s_waitcnt vmcnt(4)
	v_pk_fma_f32 v[12:13], v[84:85], v[42:43], v[12:13] op_sel_hi:[0,1,1]
	s_waitcnt vmcnt(3)
	v_pk_fma_f32 v[12:13], v[86:87], v[58:59], v[12:13] op_sel_hi:[0,1,1]
	s_waitcnt vmcnt(2)
	v_pk_fma_f32 v[12:13], v[88:89], v[44:45], v[12:13] op_sel_hi:[0,1,1]
	s_waitcnt vmcnt(1)
	v_pk_fma_f32 v[12:13], v[90:91], v[60:61], v[12:13] op_sel_hi:[0,1,1]
	s_waitcnt vmcnt(0)
	v_pk_fma_f32 v[12:13], v[92:93], v[46:47], v[12:13] op_sel_hi:[0,1,1]
	s_cbranch_scc0 .LBB0_114
	v_mul_f32_e32 v13, v27, v13
	v_and_b32_e32 v28, 0x7fffffff, v13
	v_cmp_nlt_f32_e64 s[8:9], |v13|, s33
	s_and_saveexec_b64 s[10:11], s[8:9]
	s_xor_b64 s[42:43], exec, s[10:11]
	s_cbranch_execz .LBB0_117
	v_lshrrev_b32_e32 v0, 23, v28
	v_add_u32_e32 v0, 0xffffff88, v0
	v_cmp_lt_u32_e64 s[8:9], 63, v0
	s_nop 1
	v_cndmask_b32_e64 v29, 0, v22, s[8:9]
	v_add_u32_e32 v0, v29, v0
	v_cmp_lt_u32_e64 s[10:11], 31, v0
	s_nop 1
	v_cndmask_b32_e64 v29, 0, v23, s[10:11]
	v_add_u32_e32 v0, v29, v0
	v_cmp_lt_u32_e64 s[12:13], 31, v0
	s_nop 1
	v_cndmask_b32_e64 v29, 0, v23, s[12:13]
	v_add_u32_e32 v29, v29, v0
	v_and_b32_e32 v0, 0x7fffff, v28
	v_or_b32_e32 v35, 0x800000, v0
	v_mad_u64_u32 v[30:31], s[14:15], v35, s68, 0
	v_mov_b32_e32 v0, v31
	v_mad_u64_u32 v[32:33], s[14:15], v35, s69, v[0:1]
	v_mov_b32_e32 v0, v33
	v_mad_u64_u32 v[36:37], s[14:15], v35, s82, v[0:1]
	v_mov_b32_e32 v0, v37
	v_mad_u64_u32 v[38:39], s[14:15], v35, s83, v[0:1]
	v_mov_b32_e32 v0, v39
	v_mad_u64_u32 v[40:41], s[14:15], v35, s84, v[0:1]
	v_mov_b32_e32 v0, v41
	v_mad_u64_u32 v[42:43], s[14:15], v35, s85, v[0:1]
	v_mov_b32_e32 v0, v43
	v_mad_u64_u32 v[44:45], s[14:15], v35, s86, v[0:1]
	v_cndmask_b32_e64 v31, v42, v38, s[8:9]
	v_cndmask_b32_e64 v0, v44, v40, s[8:9]
	v_cndmask_b32_e64 v35, v45, v42, s[8:9]
	v_cndmask_b32_e64 v33, v0, v31, s[10:11]
	v_cndmask_b32_e64 v0, v35, v0, s[10:11]
	v_cndmask_b32_e64 v35, v40, v36, s[8:9]
	v_cndmask_b32_e64 v31, v31, v35, s[10:11]
	v_sub_u32_e32 v37, 32, v29
	v_cmp_eq_u32_e64 s[14:15], 0, v29
	v_cndmask_b32_e64 v29, v38, v32, s[8:9]
	v_cndmask_b32_e64 v0, v0, v33, s[12:13]
	v_cndmask_b32_e64 v33, v33, v31, s[12:13]
	v_cndmask_b32_e64 v32, v35, v29, s[10:11]
	v_alignbit_b32 v39, v0, v33, v37
	v_cndmask_b32_e64 v31, v31, v32, s[12:13]
	v_cndmask_b32_e64 v0, v39, v0, s[14:15]
	v_alignbit_b32 v35, v33, v31, v37
	v_cndmask_b32_e64 v30, v36, v30, s[8:9]
	v_cndmask_b32_e64 v33, v35, v33, s[14:15]
	v_bfe_u32 v39, v0, 29, 1
	v_cndmask_b32_e64 v29, v29, v30, s[10:11]
	v_alignbit_b32 v35, v0, v33, 30
	v_sub_u32_e32 v40, 0, v39
	v_cndmask_b32_e64 v29, v32, v29, s[12:13]
	v_xor_b32_e32 v35, v35, v40
	v_alignbit_b32 v30, v31, v29, v37
	v_cndmask_b32_e64 v30, v30, v31, s[14:15]
	v_ffbh_u32_e32 v32, v35
	v_alignbit_b32 v31, v33, v30, 30
	v_min_u32_e32 v32, 32, v32
	v_alignbit_b32 v29, v30, v29, 30
	v_xor_b32_e32 v31, v31, v40
	v_sub_u32_e32 v33, 31, v32
	v_xor_b32_e32 v29, v29, v40
	v_alignbit_b32 v35, v35, v31, v33
	v_alignbit_b32 v29, v31, v29, v33
	v_alignbit_b32 v30, v35, v29, 9
	v_ffbh_u32_e32 v31, v30
	v_min_u32_e32 v31, 32, v31
	v_lshrrev_b32_e32 v38, 29, v0
	v_not_b32_e32 v33, v31
	v_alignbit_b32 v29, v30, v29, v33
	v_lshlrev_b32_e32 v30, 31, v38
	v_or_b32_e32 v33, 0x33000000, v30
	v_add_lshl_u32 v31, v31, v32, 23
	v_lshrrev_b32_e32 v29, 9, v29
	v_sub_u32_e32 v31, v33, v31
	v_or_b32_e32 v30, 0.5, v30
	v_lshlrev_b32_e32 v32, 23, v32
	v_or_b32_e32 v29, v31, v29
	v_lshrrev_b32_e32 v31, 9, v35
	v_sub_u32_e32 v30, v30, v32
	v_or_b32_e32 v30, v31, v30
	v_mul_f32_e32 v31, 0x3fc90fda, v30
	v_fma_f32 v32, v30, s87, -v31
	v_fmac_f32_e32 v32, 0x33a22168, v30
	v_fmac_f32_e32 v32, 0x3fc90fda, v29
	v_lshrrev_b32_e32 v0, 30, v0
	v_add_f32_e32 v29, v31, v32
	v_add_u32_e32 v0, v39, v0

.LBB0_663:
	v_add_u32_e32 v74, s6, v28
	v_min_i32_e32 v56, 0x8000, v28
	v_cmp_gt_i32_e32 vcc, s3, v74
	s_waitcnt vmcnt(0)
	v_pk_mul_f32 v[40:41], v[2:3], v[2:3]
	v_pk_mul_f32 v[42:43], v[6:7], v[6:7]
	v_pk_mul_f32 v[44:45], v[0:1], v[0:1]
	v_pk_mul_f32 v[46:47], v[4:5], v[4:5]
	v_pk_mul_f32 v[48:49], v[14:15], v[14:15]
	v_pk_mul_f32 v[50:51], v[10:11], v[10:11]
	v_pk_mul_f32 v[52:53], v[12:13], v[12:13]
	v_pk_mul_f32 v[54:55], v[8:9], v[8:9]
	v_cndmask_b32_e32 v28, v28, v74, vcc
	v_ashrrev_i32_e32 v60, 12, v56
	v_mov_b32_e32 v56, v52
	v_mov_b32_e32 v57, v54
	v_mov_b32_e32 v54, v53
	v_mov_b32_e32 v52, v48
	v_mov_b32_e32 v53, v50
	v_mov_b32_e32 v50, v49
	v_mov_b32_e32 v48, v44
	v_mov_b32_e32 v49, v46
	v_mov_b32_e32 v46, v45
	v_mov_b32_e32 v44, v40
	v_mov_b32_e32 v45, v42
	v_mov_b32_e32 v42, v41
	v_add_u32_e32 v41, 0xffff8000, v28
	v_mul_i32_i24_e32 v40, 0xc00, v60
	v_cmp_gt_i32_e32 vcc, s14, v28
	v_pk_add_f32 v[46:47], v[48:49], v[46:47]
	global_load_dwordx4 v[36:39], v[18:19], off
	v_cndmask_b32_e32 v48, v41, v28, vcc
	v_ashrrev_i32_e32 v41, 31, v40
	v_lshl_add_u64 v[40:41], v[40:41], 2, s[4:5]
	v_pk_add_f32 v[44:45], v[44:45], v[46:47]
	v_lshl_add_u64 v[66:67], v[40:41], 0, s[12:13]
	v_pk_add_f32 v[64:65], v[42:43], v[44:45]
	v_lshl_add_u64 v[68:69], v[40:41], 0, v[16:17]
	v_lshl_add_u64 v[44:45], v[66:67], 0, v[16:17]
	global_load_dwordx4 v[40:43], v[68:69], off
	s_nop 0
	global_load_dwordx4 v[44:47], v[44:45], off
	v_pk_add_f32 v[54:55], v[56:57], v[54:55]
	v_mov_b32_e32 v25, s57
	v_pk_add_f32 v[52:53], v[52:53], v[54:55]
	v_mov_b32_e32 v27, s53
	v_pk_add_f32 v[50:51], v[50:51], v[52:53]
	v_cndmask_b32_e32 v57, v25, v27, vcc
	v_add_f32_e32 v25, v50, v51
	v_mov_b32_e32 v23, v17
	v_add_f32_e32 v25, v65, v25
	v_lshl_add_u64 v[72:73], v[66:67], 0, v[22:23]
	v_add_f32_e32 v23, v64, v25
	ds_bpermute_b32 v25, v30, v23
	v_mov_b32_e32 v58, s56
	v_mov_b32_e32 v59, s52
	v_ashrrev_i32_e32 v61, 31, v28
	v_cndmask_b32_e32 v49, 0, v61, vcc
	s_waitcnt lgkmcnt(0)
	v_add_f32_e32 v23, v23, v25
	ds_bpermute_b32 v25, v31, v23
	v_cndmask_b32_e32 v56, v58, v59, vcc
	v_lshlrev_b64 v[48:49], 12, v[48:49]
	v_lshl_add_u64 v[48:49], v[56:57], 0, v[48:49]
	v_lshl_add_u64 v[70:71], v[48:49], 0, v[16:17]
	s_waitcnt lgkmcnt(0)
	v_add_f32_e32 v23, v23, v25
	ds_bpermute_b32 v25, v32, v23
	global_load_dwordx4 v[48:51], v[70:71], off
	global_load_dwordx4 v[52:55], v[70:71], off offset:1024
	global_load_dwordx4 v[56:59], v[70:71], off offset:2048
	global_load_dwordx4 v[60:63], v[70:71], off offset:3072
	v_mov_b32_e32 v27, v17
	v_mov_b32_e32 v28, v74
	s_waitcnt lgkmcnt(0)
	v_add_f32_e32 v23, v23, v25
	ds_bpermute_b32 v25, v33, v23
	s_waitcnt lgkmcnt(0)
	v_add_f32_e32 v23, v23, v25
	ds_bpermute_b32 v25, v34, v23
	s_waitcnt lgkmcnt(0)
	v_add_f32_e32 v23, v23, v25
	ds_bpermute_b32 v25, v35, v23
	s_waitcnt lgkmcnt(0)
	v_add_f32_e32 v23, v23, v25
	v_fmamk_f32 v23, v23, 0x3a800000, v29
	v_mul_f32_e32 v25, 0x4b800000, v23
	v_cmp_gt_f32_e32 vcc, s15, v23
	s_nop 1
	v_cndmask_b32_e32 v23, v23, v25, vcc
	v_rsq_f32_e32 v23, v23
	s_nop 0
	v_mul_f32_e32 v25, 0x45800000, v23
	v_cndmask_b32_e32 v64, v23, v25, vcc
	v_pk_mul_f32 v[12:13], v[12:13], v[64:65] op_sel_hi:[1,0]
	v_pk_mul_f32 v[14:15], v[14:15], v[64:65] op_sel_hi:[1,0]
	v_pk_mul_f32 v[8:9], v[8:9], v[64:65] op_sel_hi:[1,0]
	v_pk_mul_f32 v[10:11], v[10:11], v[64:65] op_sel_hi:[1,0]
	v_mov_b32_e32 v25, v17
	v_pk_mul_f32 v[4:5], v[4:5], v[64:65] op_sel_hi:[1,0]
	v_pk_mul_f32 v[6:7], v[6:7], v[64:65] op_sel_hi:[1,0]
	v_cmp_lt_i32_e32 vcc, s7, v74
	s_or_b64 s[10:11], vcc, s[10:11]
	s_waitcnt vmcnt(6)
	v_pk_mul_f32 v[12:13], v[36:37], v[12:13]
	v_pk_mul_f32 v[14:15], v[38:39], v[14:15]
	s_waitcnt vmcnt(4)
	v_pk_add_f32 v[36:37], v[44:45], 1.0 op_sel_hi:[1,0]
	v_pk_add_f32 v[38:39], v[46:47], 1.0 op_sel_hi:[1,0]
	v_pk_fma_f32 v[12:13], v[36:37], v[12:13], v[40:41]
	v_pk_fma_f32 v[14:15], v[38:39], v[14:15], v[42:43]
	v_cvt_pk_bf16_f32 v12, v12, v13
	v_cvt_pk_bf16_f32 v13, v14, v15
	global_store_dwordx2 v[20:21], v[12:13], off
	global_load_dwordx4 v[12:15], v[18:19], off offset:1024
	s_nop 0
	global_load_dwordx4 v[36:39], v[72:73], off
	global_load_dwordx4 v[40:43], v[68:69], off offset:1024
	v_lshl_add_u64 v[44:45], v[66:67], 0, v[24:25]
	v_lshl_add_u64 v[66:67], v[66:67], 0, v[26:27]
	s_waitcnt vmcnt(2)
	v_pk_mul_f32 v[8:9], v[12:13], v[8:9]
	s_waitcnt vmcnt(1)
	v_pk_add_f32 v[12:13], v[36:37], 1.0 op_sel_hi:[1,0]
	v_pk_mul_f32 v[10:11], v[14:15], v[10:11]
	v_pk_add_f32 v[14:15], v[38:39], 1.0 op_sel_hi:[1,0]
	s_waitcnt vmcnt(0)
	v_pk_fma_f32 v[8:9], v[12:13], v[8:9], v[40:41]
	v_pk_fma_f32 v[10:11], v[14:15], v[10:11], v[42:43]
	v_cvt_pk_bf16_f32 v8, v8, v9
	v_cvt_pk_bf16_f32 v9, v10, v11
	global_store_dwordx2 v[20:21], v[8:9], off offset:512
	global_load_dwordx4 v[8:11], v[18:19], off offset:2048
	s_nop 0
	global_load_dwordx4 v[12:15], v[44:45], off
	global_load_dwordx4 v[36:39], v[68:69], off offset:2048
	s_waitcnt vmcnt(2)
	v_pk_mul_f32 v[4:5], v[8:9], v[4:5]
	s_waitcnt vmcnt(1)
	v_pk_add_f32 v[8:9], v[12:13], 1.0 op_sel_hi:[1,0]
	v_pk_mul_f32 v[6:7], v[10:11], v[6:7]
	v_pk_add_f32 v[10:11], v[14:15], 1.0 op_sel_hi:[1,0]
	s_waitcnt vmcnt(0)
	v_pk_fma_f32 v[4:5], v[4:5], v[8:9], v[36:37]
	v_pk_fma_f32 v[6:7], v[6:7], v[10:11], v[38:39]
	v_cvt_pk_bf16_f32 v4, v4, v5
	v_cvt_pk_bf16_f32 v5, v6, v7
	global_store_dwordx2 v[20:21], v[4:5], off offset:1024
	global_load_dwordx4 v[36:39], v[18:19], off offset:3072
	global_load_dwordx4 v[40:43], v[66:67], off
	global_load_dwordx4 v[44:47], v[68:69], off offset:3072
	v_pk_mul_f32 v[66:67], v[0:1], v[64:65] op_sel_hi:[1,0]
	v_pk_mul_f32 v[64:65], v[2:3], v[64:65] op_sel_hi:[1,0]
	v_mov_b32_e32 v12, v48
	v_mov_b32_e32 v13, v49
	v_mov_b32_e32 v14, v50
	v_mov_b32_e32 v15, v51
	v_mov_b32_e32 v8, v52
	v_mov_b32_e32 v9, v53
	v_mov_b32_e32 v10, v54
	v_mov_b32_e32 v11, v55
	v_mov_b32_e32 v4, v56
	v_mov_b32_e32 v5, v57
	v_mov_b32_e32 v6, v58
	v_mov_b32_e32 v7, v59
	v_mov_b32_e32 v0, v60
	v_mov_b32_e32 v1, v61
	v_mov_b32_e32 v2, v62
	v_mov_b32_e32 v3, v63
	s_waitcnt vmcnt(2)
	v_pk_mul_f32 v[36:37], v[66:67], v[36:37]
	s_waitcnt vmcnt(1)
	v_pk_add_f32 v[40:41], v[40:41], 1.0 op_sel_hi:[1,0]
	v_pk_mul_f32 v[38:39], v[64:65], v[38:39]
	v_pk_add_f32 v[42:43], v[42:43], 1.0 op_sel_hi:[1,0]
	s_waitcnt vmcnt(0)
	v_pk_fma_f32 v[36:37], v[36:37], v[40:41], v[44:45]
	v_pk_fma_f32 v[38:39], v[38:39], v[42:43], v[46:47]
	v_cvt_pk_bf16_f32 v36, v36, v37
	v_cvt_pk_bf16_f32 v37, v38, v39
	global_store_dwordx2 v[20:21], v[36:37], off offset:1536
	v_lshl_add_u64 v[20:21], v[20:21], 0, s[8:9]
	s_andn2_b64 exec, exec, s[10:11]
	s_cbranch_execnz .LBB0_663

.LBB0_772:
.LBB0_773:
	v_and_b32_e32 v128, 16, v128
	v_cmp_eq_u32_e64 s[6:7], 0, v128
	v_cndmask_b32_e64 v128, 0, 1, s[28:29]
	v_cmp_gt_i32_e64 s[8:9], 2, v129
	s_lshr_b32 s17, s16, 6
	v_cmp_ne_u32_e64 s[10:11], 1, v128
	s_andn2_b64 vcc, exec, s[28:29]
	v_mov_b32_e32 v133, v115
	v_mov_b32_e32 v132, v114
	v_mov_b32_e32 v135, v113
	v_mov_b32_e32 v134, v112
	v_mov_b32_e32 v131, v119
	s_waitcnt lgkmcnt(0)
	v_mov_b32_e32 v130, v118
	v_mov_b32_e32 v129, v117
	v_mov_b32_e32 v128, v116
	s_cbranch_vccnz .LBB0_775
	v_mov_b32_e32 v128, s17
	v_cndmask_b32_e64 v128, v139, v128, s[8:9]
	v_lshlrev_b32_e32 v128, 5, v128
	v_and_b32_e32 v136, 0x7e0, v128
	global_load_dwordx4 v[128:131], v136, s[48:49] offset:2048
	global_load_dwordx4 v[132:135], v136, s[48:49] offset:2064
	global_load_dwordx4 v[144:147], v136, s[48:49]
	global_load_dwordx4 v[148:151], v136, s[48:49] offset:16
	ds_bpermute_b32 v136, v138, v116
	ds_bpermute_b32 v172, v138, v112
	ds_bpermute_b32 v137, v138, v117
	ds_bpermute_b32 v173, v138, v113
	ds_bpermute_b32 v174, v138, v118
	ds_bpermute_b32 v175, v138, v119
	ds_bpermute_b32 v176, v138, v114
	ds_bpermute_b32 v177, v138, v115
	s_waitcnt vmcnt(0) lgkmcnt(0)
	v_pk_mul_f32 v[128:129], v[128:129], v[136:137]
	v_pk_mul_f32 v[130:131], v[130:131], v[174:175]
	v_pk_mul_f32 v[132:133], v[132:133], v[172:173]
	v_pk_mul_f32 v[134:135], v[134:135], v[176:177]
	v_xor_b32_e32 v136, 0x80000000, v130
	v_xor_b32_e32 v137, 0x80000000, v131
	v_xor_b32_e32 v141, 0x80000000, v128
	v_xor_b32_e32 v160, 0x80000000, v129
	v_xor_b32_e32 v172, 0x80000000, v134
	v_xor_b32_e32 v173, 0x80000000, v135
	v_xor_b32_e32 v174, 0x80000000, v132
	v_xor_b32_e32 v175, 0x80000000, v133
	v_cndmask_b32_e64 v129, v129, v160, s[6:7]
	v_cndmask_b32_e64 v128, v128, v141, s[6:7]
	v_cndmask_b32_e64 v131, v131, v137, s[6:7]
	v_cndmask_b32_e64 v130, v130, v136, s[6:7]
	v_cndmask_b32_e64 v137, v133, v175, s[6:7]
	v_cndmask_b32_e64 v136, v132, v174, s[6:7]
	v_cndmask_b32_e64 v133, v135, v173, s[6:7]
	v_cndmask_b32_e64 v132, v134, v172, s[6:7]
	v_pk_fma_f32 v[130:131], v[118:119], v[146:147], v[130:131]
	v_pk_fma_f32 v[128:129], v[116:117], v[144:145], v[128:129]
	v_pk_fma_f32 v[132:133], v[114:115], v[150:151], v[132:133]
	v_pk_fma_f32 v[134:135], v[112:113], v[148:149], v[136:137]
.LBB0_775:
	s_add_i32 s12, s16, 0xffff8000
	s_lshr_b32 s19, s12, 8
	s_mul_hi_u32 s18, s19, 0x1100
	s_mulk_i32 s19, 0x1100
	v_cmp_lt_i32_e32 vcc, s83, v140
	v_cvt_pk_bf16_f32 v128, v128, v129
	v_cvt_pk_bf16_f32 v129, v130, v131
	v_cvt_pk_bf16_f32 v130, v134, v135
	v_cvt_pk_bf16_f32 v131, v132, v133
	s_and_saveexec_b64 s[12:13], vcc
	s_xor_b64 s[12:13], exec, s[12:13]
	v_and_b32_e32 v132, 0xcf, v140
	v_or_b32_e32 v132, s19, v132
	v_mov_b32_e32 v133, s18
	s_or_saveexec_b64 s[14:15], s[12:13]
	s_ashr_i32 s12, s16, 12
	s_mul_hi_i32 s13, s12, 0x1100
	s_mulk_i32 s12, 0x1100
	s_xor_b64 exec, exec, s[14:15]
	v_and_b32_e32 v132, 0xfcf, v140
	v_add_u32_e32 v160, 0x100, v132
	v_lshl_add_u64 v[132:133], s[12:13], 0, v[160:161]
	s_or_b64 exec, exec, s[14:15]
	v_mov_b64_e32 v[134:135], s[78:79]
	s_movk_i32 s20, 0x600
	v_mad_u64_u32 v[134:135], s[14:15], v132, s20, v[134:135]
	v_mov_b32_e32 v132, v135
	v_mad_u64_u32 v[132:133], s[14:15], v133, s20, v[132:133]
	v_mov_b32_e32 v135, v132
	v_lshl_add_u64 v[132:133], v[142:143], 1, v[134:135]
	s_mov_b64 s[14:15], 0x1b400080
	v_lshl_add_u64 v[134:135], v[132:133], 0, s[14:15]
	v_add_co_u32_e32 v132, vcc, 0x1b400000, v132
	v_or_b32_e32 v136, 16, v140
	s_nop 0
	v_addc_co_u32_e32 v133, vcc, 0, v133, vcc
	global_store_dwordx4 v[132:133], v[128:131], off offset:128
	global_store_dwordx4 v[134:135], v[128:131], off offset:192
	global_store_dwordx4 v[134:135], v[128:131], off offset:384
	global_store_dwordx4 v[134:135], v[128:131], off offset:576
	global_store_dwordx4 v[134:135], v[128:131], off offset:768
	global_store_dwordx4 v[134:135], v[128:131], off offset:960
	global_store_dwordx4 v[134:135], v[128:131], off offset:1152
	global_store_dwordx4 v[134:135], v[128:131], off offset:1344
	s_and_b64 vcc, exec, s[10:11]
	v_mov_b32_e32 v133, v99
	v_mov_b32_e32 v132, v98
	v_mov_b32_e32 v135, v97
	v_mov_b32_e32 v134, v96
	v_mov_b32_e32 v131, v103
	v_mov_b32_e32 v130, v102
	v_mov_b32_e32 v129, v101
	v_mov_b32_e32 v128, v100
	s_cbranch_vccnz .LBB0_781
	v_mov_b32_e32 v128, s17
	v_cndmask_b32_e64 v128, v136, v128, s[8:9]
	v_lshlrev_b32_e32 v128, 5, v128
	v_and_b32_e32 v137, 0x7e0, v128
	global_load_dwordx4 v[128:131], v137, s[48:49] offset:2048
	global_load_dwordx4 v[132:135], v137, s[48:49] offset:2064
	global_load_dwordx4 v[144:147], v137, s[48:49]
	global_load_dwordx4 v[148:151], v137, s[48:49] offset:16
	ds_bpermute_b32 v172, v138, v100
	ds_bpermute_b32 v174, v138, v96
	ds_bpermute_b32 v173, v138, v101
	ds_bpermute_b32 v175, v138, v97
	ds_bpermute_b32 v176, v138, v102
	ds_bpermute_b32 v177, v138, v103
	ds_bpermute_b32 v178, v138, v98
	ds_bpermute_b32 v179, v138, v99
	s_waitcnt vmcnt(0) lgkmcnt(0)
	v_pk_mul_f32 v[128:129], v[128:129], v[172:173]
	v_pk_mul_f32 v[130:131], v[130:131], v[176:177]
	v_pk_mul_f32 v[132:133], v[132:133], v[174:175]
	v_pk_mul_f32 v[134:135], v[134:135], v[178:179]
	v_xor_b32_e32 v137, 0x80000000, v130
	v_xor_b32_e32 v141, 0x80000000, v131
	v_xor_b32_e32 v160, 0x80000000, v128
	v_xor_b32_e32 v172, 0x80000000, v129
	v_xor_b32_e32 v174, 0x80000000, v134
	v_xor_b32_e32 v175, 0x80000000, v135
	v_xor_b32_e32 v176, 0x80000000, v132
	v_xor_b32_e32 v173, 0x80000000, v133
	v_cndmask_b32_e64 v129, v129, v172, s[6:7]
	v_cndmask_b32_e64 v128, v128, v160, s[6:7]
	v_cndmask_b32_e64 v131, v131, v141, s[6:7]
	v_cndmask_b32_e64 v130, v130, v137, s[6:7]
	v_cndmask_b32_e64 v173, v133, v173, s[6:7]
	v_cndmask_b32_e64 v172, v132, v176, s[6:7]
	v_cndmask_b32_e64 v133, v135, v175, s[6:7]
	v_cndmask_b32_e64 v132, v134, v174, s[6:7]
	v_pk_fma_f32 v[130:131], v[102:103], v[146:147], v[130:131]
	v_pk_fma_f32 v[128:129], v[100:101], v[144:145], v[128:129]
	v_pk_fma_f32 v[132:133], v[98:99], v[150:151], v[132:133]
	v_pk_fma_f32 v[134:135], v[96:97], v[148:149], v[172:173]
.LBB0_781:
	v_cmp_lt_i32_e32 vcc, s83, v136
	v_cvt_pk_bf16_f32 v128, v128, v129
	v_cvt_pk_bf16_f32 v129, v130, v131
	v_cvt_pk_bf16_f32 v130, v134, v135
	v_cvt_pk_bf16_f32 v131, v132, v133
	s_and_saveexec_b64 s[14:15], vcc
	s_xor_b64 s[14:15], exec, s[14:15]
	v_and_b32_e32 v132, 0xdf, v136
	v_or_b32_e32 v132, s19, v132
	v_mov_b32_e32 v133, s18
	s_andn2_saveexec_b64 s[14:15], s[14:15]
	v_and_b32_e32 v132, 0xfdf, v136
	v_add_u32_e32 v160, 0x100, v132
	v_lshl_add_u64 v[132:133], s[12:13], 0, v[160:161]
	s_or_b64 exec, exec, s[14:15]
	v_mov_b64_e32 v[134:135], s[78:79]
	v_mad_u64_u32 v[134:135], s[14:15], v132, s20, v[134:135]
	v_mov_b32_e32 v132, v135
	v_mad_u64_u32 v[132:133], s[14:15], v133, s20, v[132:133]
	v_mov_b32_e32 v135, v132
	v_lshl_add_u64 v[132:133], v[142:143], 1, v[134:135]
	s_mov_b64 s[14:15], 0x1b400080
	v_lshl_add_u64 v[134:135], v[132:133], 0, s[14:15]
	v_add_co_u32_e32 v132, vcc, 0x1b400000, v132
	v_or_b32_e32 v136, 32, v140
	s_nop 0
	v_addc_co_u32_e32 v133, vcc, 0, v133, vcc
	global_store_dwordx4 v[132:133], v[128:131], off offset:128
	global_store_dwordx4 v[134:135], v[128:131], off offset:192
	global_store_dwordx4 v[134:135], v[128:131], off offset:384
	global_store_dwordx4 v[134:135], v[128:131], off offset:576
	global_store_dwordx4 v[134:135], v[128:131], off offset:768
	global_store_dwordx4 v[134:135], v[128:131], off offset:960
	global_store_dwordx4 v[134:135], v[128:131], off offset:1152
	global_store_dwordx4 v[134:135], v[128:131], off offset:1344
	s_and_b64 vcc, exec, s[10:11]
	v_mov_b32_e32 v133, v83
	v_mov_b32_e32 v132, v82
	v_mov_b32_e32 v135, v81
	v_mov_b32_e32 v134, v80
	v_mov_b32_e32 v131, v87
	v_mov_b32_e32 v130, v86
	v_mov_b32_e32 v129, v85
	v_mov_b32_e32 v128, v84
	s_cbranch_vccnz .LBB0_787
	v_mov_b32_e32 v128, s17
	v_cndmask_b32_e64 v128, v136, v128, s[8:9]
	v_lshlrev_b32_e32 v128, 5, v128
	v_and_b32_e32 v137, 0x7e0, v128
	global_load_dwordx4 v[128:131], v137, s[48:49] offset:2048
	global_load_dwordx4 v[132:135], v137, s[48:49] offset:2064
	global_load_dwordx4 v[144:147], v137, s[48:49]
	global_load_dwordx4 v[148:151], v137, s[48:49] offset:16
	ds_bpermute_b32 v172, v138, v84
	ds_bpermute_b32 v174, v138, v80
	ds_bpermute_b32 v173, v138, v85
	ds_bpermute_b32 v175, v138, v81
	ds_bpermute_b32 v176, v138, v86
	ds_bpermute_b32 v177, v138, v87
	ds_bpermute_b32 v178, v138, v82
	ds_bpermute_b32 v179, v138, v83
	s_waitcnt vmcnt(0) lgkmcnt(0)
	v_pk_mul_f32 v[128:129], v[128:129], v[172:173]
	v_pk_mul_f32 v[130:131], v[130:131], v[176:177]
	v_pk_mul_f32 v[132:133], v[132:133], v[174:175]
	v_pk_mul_f32 v[134:135], v[134:135], v[178:179]
	v_xor_b32_e32 v137, 0x80000000, v130
	v_xor_b32_e32 v141, 0x80000000, v131
	v_xor_b32_e32 v160, 0x80000000, v128
	v_xor_b32_e32 v172, 0x80000000, v129
	v_xor_b32_e32 v174, 0x80000000, v134
	v_xor_b32_e32 v175, 0x80000000, v135
	v_xor_b32_e32 v176, 0x80000000, v132
	v_xor_b32_e32 v173, 0x80000000, v133
	v_cndmask_b32_e64 v129, v129, v172, s[6:7]
	v_cndmask_b32_e64 v128, v128, v160, s[6:7]
	v_cndmask_b32_e64 v131, v131, v141, s[6:7]
	v_cndmask_b32_e64 v130, v130, v137, s[6:7]
	v_cndmask_b32_e64 v173, v133, v173, s[6:7]
	v_cndmask_b32_e64 v172, v132, v176, s[6:7]
	v_cndmask_b32_e64 v133, v135, v175, s[6:7]
	v_cndmask_b32_e64 v132, v134, v174, s[6:7]
	v_pk_fma_f32 v[130:131], v[86:87], v[146:147], v[130:131]
	v_pk_fma_f32 v[128:129], v[84:85], v[144:145], v[128:129]
	v_pk_fma_f32 v[132:133], v[82:83], v[150:151], v[132:133]
	v_pk_fma_f32 v[134:135], v[80:81], v[148:149], v[172:173]
.LBB0_787:
	v_cmp_lt_i32_e32 vcc, s83, v136
	v_cvt_pk_bf16_f32 v128, v128, v129
	v_cvt_pk_bf16_f32 v129, v130, v131
	v_cvt_pk_bf16_f32 v130, v134, v135
	v_cvt_pk_bf16_f32 v131, v132, v133
	s_and_saveexec_b64 s[14:15], vcc
	s_xor_b64 s[14:15], exec, s[14:15]
	v_and_b32_e32 v132, 0xef, v136
	v_or_b32_e32 v132, s19, v132
	v_mov_b32_e32 v133, s18
	s_andn2_saveexec_b64 s[14:15], s[14:15]
	v_and_b32_e32 v132, 0xfef, v136
	v_add_u32_e32 v160, 0x100, v132
	v_lshl_add_u64 v[132:133], s[12:13], 0, v[160:161]
	s_or_b64 exec, exec, s[14:15]
	v_mov_b64_e32 v[134:135], s[78:79]
	v_mad_u64_u32 v[134:135], s[14:15], v132, s20, v[134:135]
	v_mov_b32_e32 v132, v135
	v_mad_u64_u32 v[132:133], s[14:15], v133, s20, v[132:133]
	v_mov_b32_e32 v135, v132
	v_lshl_add_u64 v[132:133], v[142:143], 1, v[134:135]
	s_mov_b64 s[14:15], 0x1b400080
	v_lshl_add_u64 v[134:135], v[132:133], 0, s[14:15]
	v_add_co_u32_e32 v132, vcc, 0x1b400000, v132
	v_or_b32_e32 v136, 48, v140
	s_nop 0
	v_addc_co_u32_e32 v133, vcc, 0, v133, vcc
	global_store_dwordx4 v[132:133], v[128:131], off offset:128
	global_store_dwordx4 v[134:135], v[128:131], off offset:192
	global_store_dwordx4 v[134:135], v[128:131], off offset:384
	global_store_dwordx4 v[134:135], v[128:131], off offset:576
	global_store_dwordx4 v[134:135], v[128:131], off offset:768
	global_store_dwordx4 v[134:135], v[128:131], off offset:960
	global_store_dwordx4 v[134:135], v[128:131], off offset:1152
	global_store_dwordx4 v[134:135], v[128:131], off offset:1344
	s_and_b64 vcc, exec, s[10:11]
	v_mov_b32_e32 v133, v67
	v_mov_b32_e32 v132, v66
	v_mov_b32_e32 v135, v65
	v_mov_b32_e32 v134, v64
	v_mov_b32_e32 v131, v71
	v_mov_b32_e32 v130, v70
	v_mov_b32_e32 v129, v69
	v_mov_b32_e32 v128, v68
	s_cbranch_vccnz .LBB0_793
	v_mov_b32_e32 v128, s17
	v_cndmask_b32_e64 v128, v136, v128, s[8:9]
	v_lshlrev_b32_e32 v128, 5, v128
	v_and_b32_e32 v137, 0x7e0, v128
	global_load_dwordx4 v[128:131], v137, s[48:49] offset:2048
	global_load_dwordx4 v[132:135], v137, s[48:49] offset:2064
	global_load_dwordx4 v[144:147], v137, s[48:49]
	global_load_dwordx4 v[148:151], v137, s[48:49] offset:16
	ds_bpermute_b32 v172, v138, v68
	ds_bpermute_b32 v174, v138, v64
	ds_bpermute_b32 v173, v138, v69
	ds_bpermute_b32 v175, v138, v65
	ds_bpermute_b32 v176, v138, v70
	ds_bpermute_b32 v177, v138, v71
	ds_bpermute_b32 v178, v138, v66
	ds_bpermute_b32 v179, v138, v67
	s_waitcnt vmcnt(0) lgkmcnt(0)
	v_pk_mul_f32 v[128:129], v[128:129], v[172:173]
	v_pk_mul_f32 v[130:131], v[130:131], v[176:177]
	v_pk_mul_f32 v[132:133], v[132:133], v[174:175]
	v_pk_mul_f32 v[134:135], v[134:135], v[178:179]
	v_xor_b32_e32 v137, 0x80000000, v130
	v_xor_b32_e32 v141, 0x80000000, v131
	v_xor_b32_e32 v160, 0x80000000, v128
	v_xor_b32_e32 v172, 0x80000000, v129
	v_xor_b32_e32 v174, 0x80000000, v134
	v_xor_b32_e32 v175, 0x80000000, v135
	v_xor_b32_e32 v176, 0x80000000, v132
	v_xor_b32_e32 v173, 0x80000000, v133
	v_cndmask_b32_e64 v129, v129, v172, s[6:7]
	v_cndmask_b32_e64 v128, v128, v160, s[6:7]
	v_cndmask_b32_e64 v131, v131, v141, s[6:7]
	v_cndmask_b32_e64 v130, v130, v137, s[6:7]
	v_cndmask_b32_e64 v173, v133, v173, s[6:7]
	v_cndmask_b32_e64 v172, v132, v176, s[6:7]
	v_cndmask_b32_e64 v133, v135, v175, s[6:7]
	v_cndmask_b32_e64 v132, v134, v174, s[6:7]
	v_pk_fma_f32 v[130:131], v[70:71], v[146:147], v[130:131]
	v_pk_fma_f32 v[128:129], v[68:69], v[144:145], v[128:129]
	v_pk_fma_f32 v[132:133], v[66:67], v[150:151], v[132:133]
	v_pk_fma_f32 v[134:135], v[64:65], v[148:149], v[172:173]
.LBB0_793:
	v_cmp_lt_i32_e32 vcc, s83, v136
	v_cvt_pk_bf16_f32 v128, v128, v129
	v_cvt_pk_bf16_f32 v129, v130, v131
	v_cvt_pk_bf16_f32 v130, v134, v135
	v_cvt_pk_bf16_f32 v131, v132, v133
	s_and_saveexec_b64 s[14:15], vcc
	s_xor_b64 s[14:15], exec, s[14:15]
	v_or_b32_sdwa v132, s19, v136 dst_sel:DWORD dst_unused:UNUSED_PAD src0_sel:DWORD src1_sel:BYTE_0
	v_mov_b32_e32 v133, s18
	s_andn2_saveexec_b64 s[14:15], s[14:15]
	v_and_b32_e32 v132, 0xfff, v136
	v_add_u32_e32 v160, 0x100, v132
	v_lshl_add_u64 v[132:133], s[12:13], 0, v[160:161]
	s_or_b64 exec, exec, s[14:15]
	v_mov_b64_e32 v[134:135], s[78:79]
	s_movk_i32 s14, 0x600
	v_mad_u64_u32 v[134:135], s[12:13], v132, s14, v[134:135]
	v_mov_b32_e32 v132, v135
	v_mad_u64_u32 v[132:133], s[12:13], v133, s14, v[132:133]
	v_mov_b32_e32 v135, v132
	v_lshl_add_u64 v[132:133], v[142:143], 1, v[134:135]
	s_mov_b64 s[12:13], 0x1b400080
	v_lshl_add_u64 v[134:135], v[132:133], 0, s[12:13]
	v_add_co_u32_e32 v132, vcc, 0x1b400000, v132
	v_add_u32_e32 v136, 0x80, v140
	s_nop 0
	v_addc_co_u32_e32 v133, vcc, 0, v133, vcc
	global_store_dwordx4 v[132:133], v[128:131], off offset:128
	global_store_dwordx4 v[134:135], v[128:131], off offset:192
	global_store_dwordx4 v[134:135], v[128:131], off offset:384
	global_store_dwordx4 v[134:135], v[128:131], off offset:576
	global_store_dwordx4 v[134:135], v[128:131], off offset:768
	global_store_dwordx4 v[134:135], v[128:131], off offset:960
	global_store_dwordx4 v[134:135], v[128:131], off offset:1152
	global_store_dwordx4 v[134:135], v[128:131], off offset:1344
	v_lshrrev_b32_e32 v141, 6, v136
	s_and_b64 vcc, exec, s[10:11]
	v_mov_b32_e32 v133, v51
	v_mov_b32_e32 v132, v50
	v_mov_b32_e32 v135, v49
	v_mov_b32_e32 v134, v48
	v_mov_b32_e32 v131, v55
	v_mov_b32_e32 v130, v54
	v_mov_b32_e32 v129, v53
	v_mov_b32_e32 v128, v52
	s_cbranch_vccnz .LBB0_799
	v_cndmask_b32_e64 v128, v139, v141, s[8:9]
	v_lshlrev_b32_e32 v128, 5, v128
	v_and_b32_e32 v137, 0x7e0, v128
	global_load_dwordx4 v[128:131], v137, s[48:49] offset:2048
	global_load_dwordx4 v[132:135], v137, s[48:49] offset:2064
	global_load_dwordx4 v[144:147], v137, s[48:49]
	global_load_dwordx4 v[148:151], v137, s[48:49] offset:16
	ds_bpermute_b32 v172, v138, v52
	ds_bpermute_b32 v174, v138, v48
	ds_bpermute_b32 v173, v138, v53
	ds_bpermute_b32 v175, v138, v49
	ds_bpermute_b32 v176, v138, v54
	ds_bpermute_b32 v177, v138, v55
	ds_bpermute_b32 v178, v138, v50
	ds_bpermute_b32 v179, v138, v51
	s_waitcnt vmcnt(0) lgkmcnt(0)
	v_pk_mul_f32 v[128:129], v[128:129], v[172:173]
	v_pk_mul_f32 v[130:131], v[130:131], v[176:177]
	v_pk_mul_f32 v[132:133], v[132:133], v[174:175]
	v_pk_mul_f32 v[134:135], v[134:135], v[178:179]
	v_xor_b32_e32 v137, 0x80000000, v130
	v_xor_b32_e32 v160, 0x80000000, v131
	v_xor_b32_e32 v172, 0x80000000, v128
	v_xor_b32_e32 v173, 0x80000000, v129
	v_xor_b32_e32 v174, 0x80000000, v134
	v_xor_b32_e32 v175, 0x80000000, v135
	v_xor_b32_e32 v176, 0x80000000, v132
	v_xor_b32_e32 v177, 0x80000000, v133
	v_cndmask_b32_e64 v129, v129, v173, s[6:7]
	v_cndmask_b32_e64 v128, v128, v172, s[6:7]
	v_cndmask_b32_e64 v131, v131, v160, s[6:7]
	v_cndmask_b32_e64 v130, v130, v137, s[6:7]
	v_cndmask_b32_e64 v173, v133, v177, s[6:7]
	v_cndmask_b32_e64 v172, v132, v176, s[6:7]
	v_cndmask_b32_e64 v133, v135, v175, s[6:7]
	v_cndmask_b32_e64 v132, v134, v174, s[6:7]
	v_pk_fma_f32 v[130:131], v[54:55], v[146:147], v[130:131]
	v_pk_fma_f32 v[128:129], v[52:53], v[144:145], v[128:129]
	v_pk_fma_f32 v[132:133], v[50:51], v[150:151], v[132:133]
	v_pk_fma_f32 v[134:135], v[48:49], v[148:149], v[172:173]
.LBB0_799:
	s_add_i32 s12, s16, 0xffff8080
	s_lshr_b32 s15, s12, 8
	s_movk_i32 s12, 0x7f7f
	s_mul_hi_u32 s14, s15, 0x1100
	s_mulk_i32 s15, 0x1100
	v_cmp_lt_i32_e32 vcc, s12, v140
	v_cvt_pk_bf16_f32 v128, v128, v129
	v_cvt_pk_bf16_f32 v129, v130, v131
	v_cvt_pk_bf16_f32 v130, v134, v135
	v_cvt_pk_bf16_f32 v131, v132, v133
	s_and_saveexec_b64 s[12:13], vcc
	s_xor_b64 s[12:13], exec, s[12:13]
	v_and_b32_e32 v132, 0xcf, v136
	v_or_b32_e32 v134, s15, v132
	v_mov_b32_e32 v135, s14
	s_or_saveexec_b64 s[12:13], s[12:13]
	v_ashrrev_i32_e32 v132, 12, v136
	v_mul_hi_i32_i24_e32 v133, 0x1100, v132
	v_mul_i32_i24_e32 v132, 0x1100, v132
	s_xor_b64 exec, exec, s[12:13]
	v_and_b32_e32 v134, 0xfcf, v136
	v_add_u32_e32 v160, 0x100, v134
	v_lshl_add_u64 v[134:135], v[132:133], 0, v[160:161]
	s_or_b64 exec, exec, s[12:13]
	v_mov_b64_e32 v[136:137], s[78:79]
	s_movk_i32 s17, 0x600
	v_mad_u64_u32 v[136:137], s[12:13], v134, s17, v[136:137]
	v_mov_b32_e32 v134, v137
	v_mad_u64_u32 v[134:135], s[12:13], v135, s17, v[134:135]
	v_mov_b32_e32 v137, v134
	v_lshl_add_u64 v[134:135], v[142:143], 1, v[136:137]
	s_mov_b64 s[12:13], 0x1b400080
	v_lshl_add_u64 v[136:137], v[134:135], 0, s[12:13]
	v_add_co_u32_e32 v134, vcc, 0x1b400000, v134
	v_add_u32_e32 v144, 0x90, v140
	s_nop 0
	v_addc_co_u32_e32 v135, vcc, 0, v135, vcc
	global_store_dwordx4 v[134:135], v[128:131], off offset:128
	global_store_dwordx4 v[136:137], v[128:131], off offset:192
	global_store_dwordx4 v[136:137], v[128:131], off offset:384
	global_store_dwordx4 v[136:137], v[128:131], off offset:576
	global_store_dwordx4 v[136:137], v[128:131], off offset:768
	global_store_dwordx4 v[136:137], v[128:131], off offset:960
	global_store_dwordx4 v[136:137], v[128:131], off offset:1152
	global_store_dwordx4 v[136:137], v[128:131], off offset:1344
	s_and_b64 vcc, exec, s[10:11]
	v_mov_b32_e32 v135, v35
	v_mov_b32_e32 v134, v34
	v_mov_b32_e32 v137, v33
	v_mov_b32_e32 v136, v32
	v_mov_b32_e32 v131, v39
	v_mov_b32_e32 v130, v38
	v_mov_b32_e32 v129, v37
	v_mov_b32_e32 v128, v36
	s_cbranch_vccnz .LBB0_805
	v_cndmask_b32_e64 v128, v144, v141, s[8:9]
	v_lshlrev_b32_e32 v128, 5, v128
	v_and_b32_e32 v145, 0x7e0, v128
	global_load_dwordx4 v[128:131], v145, s[48:49] offset:2048
	global_load_dwordx4 v[134:137], v145, s[48:49] offset:2064
	global_load_dwordx4 v[146:149], v145, s[48:49]
	global_load_dwordx4 v[172:175], v145, s[48:49] offset:16
	ds_bpermute_b32 v150, v138, v36
	ds_bpermute_b32 v176, v138, v32
	ds_bpermute_b32 v151, v138, v37
	ds_bpermute_b32 v177, v138, v33
	ds_bpermute_b32 v178, v138, v38
	ds_bpermute_b32 v179, v138, v39
	ds_bpermute_b32 v180, v138, v34
	ds_bpermute_b32 v181, v138, v35
	s_waitcnt vmcnt(0) lgkmcnt(0)
	v_pk_mul_f32 v[128:129], v[128:129], v[150:151]
	v_pk_mul_f32 v[130:131], v[130:131], v[178:179]
	v_pk_mul_f32 v[134:135], v[134:135], v[176:177]
	v_pk_mul_f32 v[136:137], v[136:137], v[180:181]
	v_xor_b32_e32 v145, 0x80000000, v130
	v_xor_b32_e32 v150, 0x80000000, v131
	v_xor_b32_e32 v151, 0x80000000, v128
	v_xor_b32_e32 v160, 0x80000000, v129
	v_xor_b32_e32 v176, 0x80000000, v136
	v_xor_b32_e32 v177, 0x80000000, v137
	v_xor_b32_e32 v178, 0x80000000, v134
	v_xor_b32_e32 v179, 0x80000000, v135
	v_cndmask_b32_e64 v129, v129, v160, s[6:7]
	v_cndmask_b32_e64 v128, v128, v151, s[6:7]
	v_cndmask_b32_e64 v131, v131, v150, s[6:7]
	v_cndmask_b32_e64 v130, v130, v145, s[6:7]
	v_cndmask_b32_e64 v151, v135, v179, s[6:7]
	v_cndmask_b32_e64 v150, v134, v178, s[6:7]
	v_cndmask_b32_e64 v135, v137, v177, s[6:7]
	v_cndmask_b32_e64 v134, v136, v176, s[6:7]
	v_pk_fma_f32 v[130:131], v[38:39], v[148:149], v[130:131]
	v_pk_fma_f32 v[128:129], v[36:37], v[146:147], v[128:129]
	v_pk_fma_f32 v[134:135], v[34:35], v[174:175], v[134:135]
	v_pk_fma_f32 v[136:137], v[32:33], v[172:173], v[150:151]
.LBB0_805:
	s_movk_i32 s12, 0x7f6f
	v_cmp_lt_i32_e32 vcc, s12, v140
	v_cvt_pk_bf16_f32 v128, v128, v129
	v_cvt_pk_bf16_f32 v129, v130, v131
	v_cvt_pk_bf16_f32 v130, v136, v137
	v_cvt_pk_bf16_f32 v131, v134, v135
	s_and_saveexec_b64 s[12:13], vcc
	s_xor_b64 s[12:13], exec, s[12:13]
	v_and_b32_e32 v134, 0xdf, v144
	v_or_b32_e32 v134, s15, v134
	v_mov_b32_e32 v135, s14
	s_andn2_saveexec_b64 s[12:13], s[12:13]
	v_and_b32_e32 v134, 0xfdf, v144
	v_add_u32_e32 v160, 0x100, v134
	v_lshl_add_u64 v[134:135], v[132:133], 0, v[160:161]
	s_or_b64 exec, exec, s[12:13]
	v_mov_b64_e32 v[136:137], s[78:79]
	v_mad_u64_u32 v[136:137], s[12:13], v134, s17, v[136:137]
	v_mov_b32_e32 v134, v137
	v_mad_u64_u32 v[134:135], s[12:13], v135, s17, v[134:135]
	v_mov_b32_e32 v137, v134
	v_lshl_add_u64 v[134:135], v[142:143], 1, v[136:137]
	s_mov_b64 s[12:13], 0x1b400080
	v_lshl_add_u64 v[136:137], v[134:135], 0, s[12:13]
	v_add_co_u32_e32 v134, vcc, 0x1b400000, v134
	v_add_u32_e32 v144, 0xa0, v140
	s_nop 0
	v_addc_co_u32_e32 v135, vcc, 0, v135, vcc
	global_store_dwordx4 v[134:135], v[128:131], off offset:128
	global_store_dwordx4 v[136:137], v[128:131], off offset:192
	global_store_dwordx4 v[136:137], v[128:131], off offset:384
	global_store_dwordx4 v[136:137], v[128:131], off offset:576
	global_store_dwordx4 v[136:137], v[128:131], off offset:768
	global_store_dwordx4 v[136:137], v[128:131], off offset:960
	global_store_dwordx4 v[136:137], v[128:131], off offset:1152
	global_store_dwordx4 v[136:137], v[128:131], off offset:1344
	s_and_b64 vcc, exec, s[10:11]
	v_mov_b32_e32 v135, v19
	v_mov_b32_e32 v134, v18
	v_mov_b32_e32 v137, v17
	v_mov_b32_e32 v136, v16
	v_mov_b32_e32 v131, v23
	v_mov_b32_e32 v130, v22
	v_mov_b32_e32 v129, v21
	v_mov_b32_e32 v128, v20
	s_cbranch_vccnz .LBB0_811
	v_cndmask_b32_e64 v128, v144, v141, s[8:9]
	v_lshlrev_b32_e32 v128, 5, v128
	v_and_b32_e32 v145, 0x7e0, v128
	global_load_dwordx4 v[128:131], v145, s[48:49] offset:2048
	global_load_dwordx4 v[134:137], v145, s[48:49] offset:2064
	global_load_dwordx4 v[146:149], v145, s[48:49]
	global_load_dwordx4 v[172:175], v145, s[48:49] offset:16
	ds_bpermute_b32 v150, v138, v20
	ds_bpermute_b32 v176, v138, v16
	ds_bpermute_b32 v151, v138, v21
	ds_bpermute_b32 v177, v138, v17
	ds_bpermute_b32 v178, v138, v22
	ds_bpermute_b32 v179, v138, v23
	ds_bpermute_b32 v180, v138, v18
	ds_bpermute_b32 v181, v138, v19
	s_waitcnt vmcnt(0) lgkmcnt(0)
	v_pk_mul_f32 v[128:129], v[128:129], v[150:151]
	v_pk_mul_f32 v[130:131], v[130:131], v[178:179]
	v_pk_mul_f32 v[134:135], v[134:135], v[176:177]
	v_pk_mul_f32 v[136:137], v[136:137], v[180:181]
	v_xor_b32_e32 v145, 0x80000000, v130
	v_xor_b32_e32 v150, 0x80000000, v131
	v_xor_b32_e32 v151, 0x80000000, v128
	v_xor_b32_e32 v160, 0x80000000, v129
	v_xor_b32_e32 v176, 0x80000000, v136
	v_xor_b32_e32 v177, 0x80000000, v137
	v_xor_b32_e32 v178, 0x80000000, v134
	v_xor_b32_e32 v179, 0x80000000, v135
	v_cndmask_b32_e64 v129, v129, v160, s[6:7]
	v_cndmask_b32_e64 v128, v128, v151, s[6:7]
	v_cndmask_b32_e64 v131, v131, v150, s[6:7]
	v_cndmask_b32_e64 v130, v130, v145, s[6:7]
	v_cndmask_b32_e64 v151, v135, v179, s[6:7]
	v_cndmask_b32_e64 v150, v134, v178, s[6:7]
	v_cndmask_b32_e64 v135, v137, v177, s[6:7]
	v_cndmask_b32_e64 v134, v136, v176, s[6:7]
	v_pk_fma_f32 v[130:131], v[22:23], v[148:149], v[130:131]
	v_pk_fma_f32 v[128:129], v[20:21], v[146:147], v[128:129]
	v_pk_fma_f32 v[134:135], v[18:19], v[174:175], v[134:135]
	v_pk_fma_f32 v[136:137], v[16:17], v[172:173], v[150:151]
.LBB0_811:
	s_movk_i32 s12, 0x7f5f
	v_cmp_lt_i32_e32 vcc, s12, v140
	v_cvt_pk_bf16_f32 v128, v128, v129
	v_cvt_pk_bf16_f32 v129, v130, v131
	v_cvt_pk_bf16_f32 v130, v136, v137
	v_cvt_pk_bf16_f32 v131, v134, v135
	s_and_saveexec_b64 s[12:13], vcc
	s_xor_b64 s[12:13], exec, s[12:13]
	v_and_b32_e32 v134, 0xef, v144
	v_or_b32_e32 v134, s15, v134
	v_mov_b32_e32 v135, s14
	s_andn2_saveexec_b64 s[12:13], s[12:13]
	v_and_b32_e32 v134, 0xfef, v144
	v_add_u32_e32 v160, 0x100, v134
	v_lshl_add_u64 v[134:135], v[132:133], 0, v[160:161]
	s_or_b64 exec, exec, s[12:13]
	v_mov_b64_e32 v[136:137], s[78:79]
	v_mad_u64_u32 v[136:137], s[12:13], v134, s17, v[136:137]
	v_mov_b32_e32 v134, v137
	v_mad_u64_u32 v[134:135], s[12:13], v135, s17, v[134:135]
	v_mov_b32_e32 v137, v134
	v_lshl_add_u64 v[134:135], v[142:143], 1, v[136:137]
	s_mov_b64 s[12:13], 0x1b400080
	v_lshl_add_u64 v[136:137], v[134:135], 0, s[12:13]
	v_add_co_u32_e32 v134, vcc, 0x1b400000, v134
	v_add_u32_e32 v144, 0xb0, v140
	s_nop 0
	v_addc_co_u32_e32 v135, vcc, 0, v135, vcc
	global_store_dwordx4 v[134:135], v[128:131], off offset:128
	global_store_dwordx4 v[136:137], v[128:131], off offset:192
	global_store_dwordx4 v[136:137], v[128:131], off offset:384
	global_store_dwordx4 v[136:137], v[128:131], off offset:576
	global_store_dwordx4 v[136:137], v[128:131], off offset:768
	global_store_dwordx4 v[136:137], v[128:131], off offset:960
	global_store_dwordx4 v[136:137], v[128:131], off offset:1152
	global_store_dwordx4 v[136:137], v[128:131], off offset:1344
	s_and_b64 vcc, exec, s[10:11]
	v_mov_b32_e32 v135, v3
	v_mov_b32_e32 v134, v2
	v_mov_b32_e32 v137, v1
	v_mov_b32_e32 v136, v0
	v_mov_b32_e32 v131, v7
	v_mov_b32_e32 v130, v6
	v_mov_b32_e32 v129, v5
	v_mov_b32_e32 v128, v4
	s_cbranch_vccnz .LBB0_817
	v_cndmask_b32_e64 v128, v144, v141, s[8:9]
	v_lshlrev_b32_e32 v128, 5, v128
	v_and_b32_e32 v141, 0x7e0, v128
	global_load_dwordx4 v[128:131], v141, s[48:49] offset:2048
	global_load_dwordx4 v[134:137], v141, s[48:49] offset:2064
	global_load_dwordx4 v[146:149], v141, s[48:49]
	global_load_dwordx4 v[172:175], v141, s[48:49] offset:16
	ds_bpermute_b32 v150, v138, v4
	ds_bpermute_b32 v176, v138, v0
	ds_bpermute_b32 v151, v138, v5
	ds_bpermute_b32 v177, v138, v1
	ds_bpermute_b32 v178, v138, v6
	ds_bpermute_b32 v179, v138, v7
	ds_bpermute_b32 v180, v138, v2
	ds_bpermute_b32 v181, v138, v3
	s_waitcnt vmcnt(0) lgkmcnt(0)
	v_pk_mul_f32 v[128:129], v[128:129], v[150:151]
	v_pk_mul_f32 v[130:131], v[130:131], v[178:179]
	v_pk_mul_f32 v[134:135], v[134:135], v[176:177]
	v_pk_mul_f32 v[136:137], v[136:137], v[180:181]
	v_xor_b32_e32 v138, 0x80000000, v130
	v_xor_b32_e32 v141, 0x80000000, v131
	v_xor_b32_e32 v145, 0x80000000, v128
	v_xor_b32_e32 v150, 0x80000000, v129
	v_xor_b32_e32 v160, 0x80000000, v136
	v_xor_b32_e32 v176, 0x80000000, v137
	v_xor_b32_e32 v177, 0x80000000, v134
	v_xor_b32_e32 v151, 0x80000000, v135
	v_cndmask_b32_e64 v129, v129, v150, s[6:7]
	v_cndmask_b32_e64 v128, v128, v145, s[6:7]
	v_cndmask_b32_e64 v131, v131, v141, s[6:7]
	v_cndmask_b32_e64 v130, v130, v138, s[6:7]
	v_cndmask_b32_e64 v151, v135, v151, s[6:7]
	v_cndmask_b32_e64 v150, v134, v177, s[6:7]
	v_cndmask_b32_e64 v135, v137, v176, s[6:7]
	v_cndmask_b32_e64 v134, v136, v160, s[6:7]
	v_pk_fma_f32 v[130:131], v[6:7], v[148:149], v[130:131]
	v_pk_fma_f32 v[128:129], v[4:5], v[146:147], v[128:129]
	v_pk_fma_f32 v[134:135], v[2:3], v[174:175], v[134:135]
	v_pk_fma_f32 v[136:137], v[0:1], v[172:173], v[150:151]

.LBB0_822:
	v_readlane_b32 s6, v254, 16
	v_readlane_b32 s7, v254, 17
	s_waitcnt vmcnt(0) lgkmcnt(0)
	s_barrier
	v_lshl_add_u64 v[132:133], v[142:143], 2, s[6:7]
	global_load_dwordx4 v[128:131], v[132:133], off offset:16
	s_nop 0
	global_load_dwordx4 v[132:135], v[132:133], off
	s_add_i32 s6, s16, 0xffff8000
	s_lshr_b32 s11, s6, 8
	v_readlane_b32 s6, v254, 32
	s_mul_hi_u32 s10, s11, 0x1100
	s_mulk_i32 s11, 0x1100
	v_lshl_add_u32 v141, v139, 2, s6
	ds_read2st64_b32 v[136:137], v141 offset1:2
	ds_read2st64_b32 v[138:139], v141 offset0:4 offset1:6
	s_waitcnt lgkmcnt(1)
	v_mov_b32_e32 v144, v136
	s_waitcnt lgkmcnt(0)
	v_mov_b32_e32 v145, v138
	v_mov_b32_e32 v138, v137
	v_pk_add_f32 v[136:137], v[144:145], v[138:139]
	s_nop 0
	v_add_f32_e32 v136, v136, v137
	v_fmamk_f32 v136, v136, 0x3c000000, v205
	v_cmp_gt_f32_e32 vcc, s84, v136
	v_mul_f32_e32 v137, 0x4b800000, v136
	s_nop 0
	v_cndmask_b32_e32 v136, v136, v137, vcc
	v_rsq_f32_e32 v136, v136
	s_nop 0
	v_mul_f32_e32 v137, 0x45800000, v136
	v_cndmask_b32_e32 v136, v136, v137, vcc
	v_pk_mul_f32 v[138:139], v[124:125], v[136:137] op_sel_hi:[1,0]
	v_pk_mul_f32 v[144:145], v[126:127], v[136:137] op_sel_hi:[1,0]
	v_pk_mul_f32 v[146:147], v[120:121], v[136:137] op_sel_hi:[1,0]
	v_pk_mul_f32 v[136:137], v[122:123], v[136:137] op_sel_hi:[1,0]
	v_cmp_lt_i32_e32 vcc, s83, v140
	s_waitcnt vmcnt(1)
	v_pk_mul_f32 v[148:149], v[130:131], v[136:137]
	s_waitcnt vmcnt(0)
	v_pk_mul_f32 v[144:145], v[134:135], v[144:145]
	v_pk_mul_f32 v[138:139], v[132:133], v[138:139]
	v_pk_mul_f32 v[146:147], v[128:129], v[146:147]
	v_cvt_pk_bf16_f32 v136, v138, v139
	v_cvt_pk_bf16_f32 v137, v144, v145
	s_nop 0
	v_cvt_pk_bf16_f32 v138, v146, v147
	v_cvt_pk_bf16_f32 v139, v148, v149
	s_and_saveexec_b64 s[6:7], vcc
	s_xor_b64 s[6:7], exec, s[6:7]
	v_and_b32_e32 v144, 0xcf, v140
	v_or_b32_e32 v144, s11, v144
	v_mov_b32_e32 v145, s10
	s_or_saveexec_b64 s[8:9], s[6:7]
	s_ashr_i32 s6, s16, 12
	s_mul_hi_i32 s7, s6, 0x1100
	s_mulk_i32 s6, 0x1100
	s_xor_b64 exec, exec, s[8:9]
	v_and_b32_e32 v144, 0xfcf, v140
	v_add_u32_e32 v160, 0x100, v144
	v_lshl_add_u64 v[144:145], s[6:7], 0, v[160:161]
	s_or_b64 exec, exec, s[8:9]
	v_readlane_b32 s8, v254, 18
	v_readlane_b32 s9, v254, 19
	v_lshlrev_b64 v[144:145], 8, v[144:145]
	v_add_u32_e32 v148, 64, v141
	v_lshl_add_u64 v[142:143], v[142:143], 1, s[8:9]
	v_lshl_add_u64 v[144:145], v[142:143], 0, v[144:145]
	global_store_dwordx4 v[144:145], v[136:139], off
	ds_read2_b32 v[136:137], v141 offset0:16 offset1:144
	ds_read2st64_b32 v[138:139], v148 offset0:4 offset1:6
	v_or_b32_e32 v146, 16, v140
	s_waitcnt lgkmcnt(1)
	v_mov_b32_e32 v144, v136
	s_waitcnt lgkmcnt(0)
	v_mov_b32_e32 v145, v138
	v_mov_b32_e32 v138, v137
	v_pk_add_f32 v[136:137], v[144:145], v[138:139]
	s_nop 0
	v_add_f32_e32 v136, v136, v137
	v_fmamk_f32 v136, v136, 0x3c000000, v205
	v_cmp_gt_f32_e32 vcc, s84, v136
	v_mul_f32_e32 v137, 0x4b800000, v136
	s_nop 0
	v_cndmask_b32_e32 v136, v136, v137, vcc
	v_rsq_f32_e32 v136, v136
	s_nop 0
	v_mul_f32_e32 v137, 0x45800000, v136
	v_cndmask_b32_e32 v136, v136, v137, vcc
	v_pk_mul_f32 v[138:139], v[108:109], v[136:137] op_sel_hi:[1,0]
	v_pk_mul_f32 v[144:145], v[110:111], v[136:137] op_sel_hi:[1,0]
	v_pk_mul_f32 v[138:139], v[132:133], v[138:139]
	v_pk_mul_f32 v[144:145], v[134:135], v[144:145]
	v_pk_mul_f32 v[150:151], v[104:105], v[136:137] op_sel_hi:[1,0]
	v_pk_mul_f32 v[136:137], v[106:107], v[136:137] op_sel_hi:[1,0]
	v_cmp_lt_i32_e32 vcc, s83, v146
	v_pk_mul_f32 v[172:173], v[130:131], v[136:137]
	v_pk_mul_f32 v[150:151], v[128:129], v[150:151]
	v_cvt_pk_bf16_f32 v136, v138, v139
	v_cvt_pk_bf16_f32 v137, v144, v145
	s_nop 0
	v_cvt_pk_bf16_f32 v138, v150, v151
	v_cvt_pk_bf16_f32 v139, v172, v173
	s_and_saveexec_b64 s[8:9], vcc
	s_xor_b64 s[8:9], exec, s[8:9]
	v_and_b32_e32 v144, 0xdf, v146
	v_or_b32_e32 v144, s11, v144
	v_mov_b32_e32 v145, s10
	s_andn2_saveexec_b64 s[8:9], s[8:9]
	v_and_b32_e32 v144, 0xfdf, v146
	v_add_u32_e32 v160, 0x100, v144
	v_lshl_add_u64 v[144:145], s[6:7], 0, v[160:161]
	s_or_b64 exec, exec, s[8:9]
	v_lshlrev_b64 v[144:145], 8, v[144:145]
	v_lshl_add_u64 v[144:145], v[142:143], 0, v[144:145]
	v_add_u32_e32 v149, 0x80, v141
	global_store_dwordx4 v[144:145], v[136:139], off
	ds_read2_b32 v[136:137], v141 offset0:32 offset1:160
	ds_read2st64_b32 v[138:139], v149 offset0:4 offset1:6
	v_or_b32_e32 v146, 32, v140
	s_waitcnt lgkmcnt(1)
	v_mov_b32_e32 v144, v136
	s_waitcnt lgkmcnt(0)
	v_mov_b32_e32 v145, v138
	v_mov_b32_e32 v138, v137
	v_pk_add_f32 v[136:137], v[144:145], v[138:139]
	s_nop 0
	v_add_f32_e32 v136, v136, v137
	v_fmamk_f32 v136, v136, 0x3c000000, v205
	v_cmp_gt_f32_e32 vcc, s84, v136
	v_mul_f32_e32 v137, 0x4b800000, v136
	s_nop 0
	v_cndmask_b32_e32 v136, v136, v137, vcc
	v_rsq_f32_e32 v136, v136
	s_nop 0
	v_mul_f32_e32 v137, 0x45800000, v136
	v_cndmask_b32_e32 v136, v136, v137, vcc
	v_pk_mul_f32 v[138:139], v[92:93], v[136:137] op_sel_hi:[1,0]
	v_pk_mul_f32 v[144:145], v[94:95], v[136:137] op_sel_hi:[1,0]
	v_pk_mul_f32 v[138:139], v[132:133], v[138:139]
	v_pk_mul_f32 v[144:145], v[134:135], v[144:145]
	v_pk_mul_f32 v[150:151], v[88:89], v[136:137] op_sel_hi:[1,0]
	v_pk_mul_f32 v[136:137], v[90:91], v[136:137] op_sel_hi:[1,0]
	v_cmp_lt_i32_e32 vcc, s83, v146
	v_pk_mul_f32 v[172:173], v[130:131], v[136:137]
	v_pk_mul_f32 v[150:151], v[128:129], v[150:151]
	v_cvt_pk_bf16_f32 v136, v138, v139
	v_cvt_pk_bf16_f32 v137, v144, v145
	s_nop 0
	v_cvt_pk_bf16_f32 v138, v150, v151
	v_cvt_pk_bf16_f32 v139, v172, v173
	s_and_saveexec_b64 s[8:9], vcc
	s_xor_b64 s[8:9], exec, s[8:9]
	v_and_b32_e32 v144, 0xef, v146
	v_or_b32_e32 v144, s11, v144
	v_mov_b32_e32 v145, s10
	s_andn2_saveexec_b64 s[8:9], s[8:9]
	v_and_b32_e32 v144, 0xfef, v146
	v_add_u32_e32 v160, 0x100, v144
	v_lshl_add_u64 v[144:145], s[6:7], 0, v[160:161]
	s_or_b64 exec, exec, s[8:9]
	v_lshlrev_b64 v[144:145], 8, v[144:145]
	v_lshl_add_u64 v[144:145], v[142:143], 0, v[144:145]
	v_add_u32_e32 v150, 0xc0, v141
	global_store_dwordx4 v[144:145], v[136:139], off
	ds_read2_b32 v[136:137], v141 offset0:48 offset1:176
	ds_read2st64_b32 v[138:139], v150 offset0:4 offset1:6
	v_or_b32_e32 v146, 48, v140
	s_waitcnt lgkmcnt(1)
	v_mov_b32_e32 v144, v136
	s_waitcnt lgkmcnt(0)
	v_mov_b32_e32 v145, v138
	v_mov_b32_e32 v138, v137
	v_pk_add_f32 v[136:137], v[144:145], v[138:139]
	s_nop 0
	v_add_f32_e32 v136, v136, v137
	v_fmamk_f32 v136, v136, 0x3c000000, v205
	v_cmp_gt_f32_e32 vcc, s84, v136
	v_mul_f32_e32 v137, 0x4b800000, v136
	s_nop 0
	v_cndmask_b32_e32 v136, v136, v137, vcc
	v_rsq_f32_e32 v136, v136
	s_nop 0
	v_mul_f32_e32 v137, 0x45800000, v136
	v_cndmask_b32_e32 v136, v136, v137, vcc
	v_pk_mul_f32 v[138:139], v[76:77], v[136:137] op_sel_hi:[1,0]
	v_pk_mul_f32 v[144:145], v[78:79], v[136:137] op_sel_hi:[1,0]
	v_pk_mul_f32 v[138:139], v[132:133], v[138:139]
	v_pk_mul_f32 v[144:145], v[134:135], v[144:145]
	v_pk_mul_f32 v[172:173], v[72:73], v[136:137] op_sel_hi:[1,0]
	v_pk_mul_f32 v[136:137], v[74:75], v[136:137] op_sel_hi:[1,0]
	v_cmp_lt_i32_e32 vcc, s83, v146
	v_pk_mul_f32 v[174:175], v[130:131], v[136:137]
	v_pk_mul_f32 v[172:173], v[128:129], v[172:173]
	v_cvt_pk_bf16_f32 v136, v138, v139
	v_cvt_pk_bf16_f32 v137, v144, v145
	s_nop 0
	v_cvt_pk_bf16_f32 v138, v172, v173
	v_cvt_pk_bf16_f32 v139, v174, v175
	s_and_saveexec_b64 s[8:9], vcc
	s_xor_b64 s[8:9], exec, s[8:9]
	v_or_b32_sdwa v144, s11, v146 dst_sel:DWORD dst_unused:UNUSED_PAD src0_sel:DWORD src1_sel:BYTE_0
	v_mov_b32_e32 v145, s10
	s_andn2_saveexec_b64 s[8:9], s[8:9]
	v_and_b32_e32 v144, 0xfff, v146
	v_add_u32_e32 v160, 0x100, v144
	v_lshl_add_u64 v[144:145], s[6:7], 0, v[160:161]
	s_or_b64 exec, exec, s[8:9]
	v_lshlrev_b64 v[144:145], 8, v[144:145]
	v_lshl_add_u64 v[144:145], v[142:143], 0, v[144:145]
	global_store_dwordx4 v[144:145], v[136:139], off
	ds_read2st64_b32 v[136:137], v141 offset0:1 offset1:3
	ds_read2st64_b32 v[138:139], v141 offset0:5 offset1:7
	s_addk_i32 s16, 0x8080
	s_lshr_b32 s9, s16, 8
	s_movk_i32 s6, 0x7f7f
	s_waitcnt lgkmcnt(1)
	v_mov_b32_e32 v144, v136
	s_waitcnt lgkmcnt(0)
	v_mov_b32_e32 v145, v138
	v_mov_b32_e32 v138, v137
	v_pk_add_f32 v[136:137], v[144:145], v[138:139]
	v_add_u32_e32 v151, 0x80, v140
	v_add_f32_e32 v136, v136, v137
	v_fmamk_f32 v136, v136, 0x3c000000, v205
	v_cmp_gt_f32_e32 vcc, s84, v136
	v_mul_f32_e32 v137, 0x4b800000, v136
	s_mul_hi_u32 s8, s9, 0x1100
	v_cndmask_b32_e32 v136, v136, v137, vcc
	v_rsq_f32_e32 v136, v136
	s_mulk_i32 s9, 0x1100
	v_mul_f32_e32 v137, 0x45800000, v136
	v_cndmask_b32_e32 v136, v136, v137, vcc
	v_pk_mul_f32 v[138:139], v[60:61], v[136:137] op_sel_hi:[1,0]
	v_pk_mul_f32 v[146:147], v[56:57], v[136:137] op_sel_hi:[1,0]
	v_pk_mul_f32 v[144:145], v[62:63], v[136:137] op_sel_hi:[1,0]
	v_pk_mul_f32 v[138:139], v[132:133], v[138:139]
	v_pk_mul_f32 v[136:137], v[58:59], v[136:137] op_sel_hi:[1,0]
	v_pk_mul_f32 v[146:147], v[128:129], v[146:147]
	v_cmp_lt_i32_e32 vcc, s6, v140
	v_pk_mul_f32 v[144:145], v[134:135], v[144:145]
	v_pk_mul_f32 v[172:173], v[130:131], v[136:137]
	v_cvt_pk_bf16_f32 v136, v138, v139
	v_cvt_pk_bf16_f32 v137, v144, v145
	v_cvt_pk_bf16_f32 v138, v146, v147
	s_nop 0
	v_cvt_pk_bf16_f32 v139, v172, v173
	s_and_saveexec_b64 s[6:7], vcc
	s_xor_b64 s[6:7], exec, s[6:7]
	v_and_b32_e32 v144, 0xcf, v151
	v_or_b32_e32 v146, s9, v144
	v_mov_b32_e32 v147, s8
	s_or_saveexec_b64 s[6:7], s[6:7]
	v_ashrrev_i32_e32 v144, 12, v151
	v_mul_hi_i32_i24_e32 v145, 0x1100, v144
	v_mul_i32_i24_e32 v144, 0x1100, v144
	s_xor_b64 exec, exec, s[6:7]
	v_and_b32_e32 v146, 0xfcf, v151
	v_add_u32_e32 v160, 0x100, v146
	v_lshl_add_u64 v[146:147], v[144:145], 0, v[160:161]
	s_or_b64 exec, exec, s[6:7]
	v_lshlrev_b64 v[146:147], 8, v[146:147]
	v_lshl_add_u64 v[146:147], v[142:143], 0, v[146:147]
	global_store_dwordx4 v[146:147], v[136:139], off
	ds_read2_b32 v[136:137], v141 offset0:80 offset1:208
	ds_read2st64_b32 v[138:139], v148 offset0:5 offset1:7
	s_movk_i32 s6, 0x7f6f
	v_add_u32_e32 v151, 0x90, v140
	s_waitcnt lgkmcnt(1)
	v_mov_b32_e32 v146, v136
	s_waitcnt lgkmcnt(0)
	v_mov_b32_e32 v147, v138
	v_mov_b32_e32 v138, v137
	v_pk_add_f32 v[136:137], v[146:147], v[138:139]
	s_nop 0
	v_add_f32_e32 v136, v136, v137
	v_fmamk_f32 v136, v136, 0x3c000000, v205
	v_cmp_gt_f32_e32 vcc, s84, v136
	v_mul_f32_e32 v137, 0x4b800000, v136
	s_nop 0
	v_cndmask_b32_e32 v136, v136, v137, vcc
	v_rsq_f32_e32 v136, v136
	s_nop 0
	v_mul_f32_e32 v137, 0x45800000, v136
	v_cndmask_b32_e32 v136, v136, v137, vcc
	v_pk_mul_f32 v[138:139], v[44:45], v[136:137] op_sel_hi:[1,0]
	v_pk_mul_f32 v[146:147], v[46:47], v[136:137] op_sel_hi:[1,0]
	v_pk_mul_f32 v[138:139], v[132:133], v[138:139]
	v_pk_mul_f32 v[146:147], v[134:135], v[146:147]
	v_pk_mul_f32 v[172:173], v[40:41], v[136:137] op_sel_hi:[1,0]
	v_pk_mul_f32 v[136:137], v[42:43], v[136:137] op_sel_hi:[1,0]
	v_cmp_lt_i32_e32 vcc, s6, v140
	v_pk_mul_f32 v[174:175], v[130:131], v[136:137]
	v_pk_mul_f32 v[172:173], v[128:129], v[172:173]
	v_cvt_pk_bf16_f32 v136, v138, v139
	v_cvt_pk_bf16_f32 v137, v146, v147
	s_nop 0
	v_cvt_pk_bf16_f32 v138, v172, v173
	v_cvt_pk_bf16_f32 v139, v174, v175
	s_and_saveexec_b64 s[6:7], vcc
	s_xor_b64 s[6:7], exec, s[6:7]
	v_and_b32_e32 v146, 0xdf, v151
	v_or_b32_e32 v146, s9, v146
	v_mov_b32_e32 v147, s8
	s_andn2_saveexec_b64 s[6:7], s[6:7]
	v_and_b32_e32 v146, 0xfdf, v151
	v_add_u32_e32 v160, 0x100, v146
	v_lshl_add_u64 v[146:147], v[144:145], 0, v[160:161]
	s_or_b64 exec, exec, s[6:7]
	v_lshlrev_b64 v[146:147], 8, v[146:147]
	v_lshl_add_u64 v[146:147], v[142:143], 0, v[146:147]
	global_store_dwordx4 v[146:147], v[136:139], off
	ds_read2_b32 v[136:137], v141 offset0:96 offset1:224
	ds_read2st64_b32 v[138:139], v149 offset0:5 offset1:7
	s_movk_i32 s6, 0x7f5f
	v_add_u32_e32 v148, 0xa0, v140
	s_waitcnt lgkmcnt(1)
	v_mov_b32_e32 v146, v136
	s_waitcnt lgkmcnt(0)
	v_mov_b32_e32 v147, v138
	v_mov_b32_e32 v138, v137
	v_pk_add_f32 v[136:137], v[146:147], v[138:139]
	s_nop 0
	v_add_f32_e32 v136, v136, v137
	v_fmamk_f32 v136, v136, 0x3c000000, v205
	v_cmp_gt_f32_e32 vcc, s84, v136
	v_mul_f32_e32 v137, 0x4b800000, v136
	s_nop 0
	v_cndmask_b32_e32 v136, v136, v137, vcc
	v_rsq_f32_e32 v136, v136
	s_nop 0
	v_mul_f32_e32 v137, 0x45800000, v136
	v_cndmask_b32_e32 v136, v136, v137, vcc
	v_pk_mul_f32 v[138:139], v[28:29], v[136:137] op_sel_hi:[1,0]
	v_pk_mul_f32 v[146:147], v[30:31], v[136:137] op_sel_hi:[1,0]
	v_pk_mul_f32 v[138:139], v[132:133], v[138:139]
	v_pk_mul_f32 v[146:147], v[134:135], v[146:147]
	v_pk_mul_f32 v[172:173], v[24:25], v[136:137] op_sel_hi:[1,0]
	v_pk_mul_f32 v[136:137], v[26:27], v[136:137] op_sel_hi:[1,0]
	v_cmp_lt_i32_e32 vcc, s6, v140
	v_pk_mul_f32 v[174:175], v[130:131], v[136:137]
	v_pk_mul_f32 v[172:173], v[128:129], v[172:173]
	v_cvt_pk_bf16_f32 v136, v138, v139
	v_cvt_pk_bf16_f32 v137, v146, v147
	s_nop 0
	v_cvt_pk_bf16_f32 v138, v172, v173
	v_cvt_pk_bf16_f32 v139, v174, v175
	s_and_saveexec_b64 s[6:7], vcc
	s_xor_b64 s[6:7], exec, s[6:7]
	v_and_b32_e32 v146, 0xef, v148
	v_or_b32_e32 v146, s9, v146
	v_mov_b32_e32 v147, s8
	s_andn2_saveexec_b64 s[6:7], s[6:7]
	v_and_b32_e32 v146, 0xfef, v148
	v_add_u32_e32 v160, 0x100, v146
	v_lshl_add_u64 v[146:147], v[144:145], 0, v[160:161]
	s_or_b64 exec, exec, s[6:7]
	v_lshlrev_b64 v[146:147], 8, v[146:147]
	v_lshl_add_u64 v[146:147], v[142:143], 0, v[146:147]
	global_store_dwordx4 v[146:147], v[136:139], off
	ds_read2_b32 v[138:139], v141 offset0:112 offset1:240
	ds_read2st64_b32 v[146:147], v150 offset0:5 offset1:7
	s_movk_i32 s6, 0x7f4f
	v_add_u32_e32 v136, 0xb0, v140
	s_waitcnt lgkmcnt(1)
	v_mov_b32_e32 v148, v138
	s_waitcnt lgkmcnt(0)
	v_mov_b32_e32 v149, v146
	v_mov_b32_e32 v146, v139
	v_pk_add_f32 v[138:139], v[148:149], v[146:147]
	s_nop 0
	v_add_f32_e32 v137, v138, v139
	v_fmamk_f32 v137, v137, 0x3c000000, v205
	v_cmp_gt_f32_e32 vcc, s84, v137
	v_mul_f32_e32 v138, 0x4b800000, v137
	s_nop 0
	v_cndmask_b32_e32 v137, v137, v138, vcc
	v_rsq_f32_e32 v137, v137
	s_nop 0
	v_mul_f32_e32 v138, 0x45800000, v137
	v_cndmask_b32_e32 v138, v137, v138, vcc
	v_pk_mul_f32 v[146:147], v[12:13], v[138:139] op_sel_hi:[1,0]
	v_pk_mul_f32 v[148:149], v[14:15], v[138:139] op_sel_hi:[1,0]
	v_pk_mul_f32 v[132:133], v[132:133], v[146:147]
	v_pk_mul_f32 v[146:147], v[8:9], v[138:139] op_sel_hi:[1,0]
	v_pk_mul_f32 v[138:139], v[10:11], v[138:139] op_sel_hi:[1,0]
	v_cmp_lt_i32_e32 vcc, s6, v140
	v_pk_mul_f32 v[138:139], v[130:131], v[138:139]
	v_pk_mul_f32 v[130:131], v[128:129], v[146:147]
	v_pk_mul_f32 v[134:135], v[134:135], v[148:149]
	v_cvt_pk_bf16_f32 v128, v132, v133
	s_nop 0
	v_cvt_pk_bf16_f32 v129, v134, v135
	v_cvt_pk_bf16_f32 v130, v130, v131
	v_cvt_pk_bf16_f32 v131, v138, v139
	s_and_saveexec_b64 s[6:7], vcc
	s_xor_b64 s[6:7], exec, s[6:7]
	v_or_b32_sdwa v132, s9, v136 dst_sel:DWORD dst_unused:UNUSED_PAD src0_sel:DWORD src1_sel:BYTE_0
	v_mov_b32_e32 v133, s8
	s_andn2_saveexec_b64 s[6:7], s[6:7]
	v_and_b32_e32 v132, 0xfff, v136
	v_add_u32_e32 v160, 0x100, v132
	v_lshl_add_u64 v[132:133], v[144:145], 0, v[160:161]
	s_or_b64 exec, exec, s[6:7]
	v_lshlrev_b64 v[132:133], 8, v[132:133]
	v_lshl_add_u64 v[132:133], v[142:143], 0, v[132:133]
	global_store_dwordx4 v[132:133], v[128:131], off

.LBB0_874:
	s_or_b64 exec, exec, s[6:7]
	v_ashrrev_i32_e32 v128, 1, v129
	v_and_b32_e32 v144, -8, v128
	v_readlane_b32 s6, v254, 20
	v_ashrrev_i32_e32 v145, 31, v144
	v_readlane_b32 s7, v254, 21
	v_and_b32_e32 v149, 15, v129
	s_waitcnt vmcnt(0) lgkmcnt(0)
	v_lshl_add_u64 v[132:133], v[144:145], 2, s[6:7]
	s_barrier
	global_load_dwordx4 v[136:139], v[132:133], off offset:16
	global_load_dwordx4 v[140:143], v[132:133], off
	global_load_dwordx4 v[128:131], v[132:133], off offset:528
	s_nop 0
	global_load_dwordx4 v[132:135], v[132:133], off offset:512
	v_readlane_b32 s6, v254, 22
	v_or_b32_e32 v146, s68, v149
	v_readlane_b32 s7, v254, 23
	v_add_u32_e32 v148, s81, v146
	s_nop 0
	v_lshl_add_u64 v[146:147], v[144:145], 1, s[6:7]
	v_readlane_b32 s6, v254, 32
	s_nop 1
	v_lshl_add_u32 v160, v149, 2, s6
	ds_read2st64_b32 v[144:145], v160 offset1:2
	ds_read2st64_b32 v[150:151], v160 offset0:4 offset1:6
	v_ashrrev_i32_e32 v149, 31, v148
	v_add_u32_e32 v184, 0xc0, v160
	s_mov_b64 s[6:7], 0x10000
	s_waitcnt lgkmcnt(1)
	v_mov_b32_e32 v172, v144
	s_waitcnt lgkmcnt(0)
	v_mov_b32_e32 v173, v150
	v_mov_b32_e32 v150, v145
	v_pk_add_f32 v[144:145], v[172:173], v[150:151]
	s_nop 0
	v_add_f32_e32 v144, v144, v145
	v_fmamk_f32 v144, v144, 0x3b800000, v205
	v_cmp_gt_f32_e32 vcc, s84, v144
	v_mul_f32_e32 v145, 0x4b800000, v144
	s_nop 0
	v_cndmask_b32_e32 v144, v144, v145, vcc
	v_rsq_f32_e32 v144, v144
	s_nop 0
	v_mul_f32_e32 v145, 0x45800000, v144
	v_cndmask_b32_e32 v150, v144, v145, vcc
	v_pk_mul_f32 v[172:173], v[124:125], v[150:151] op_sel_hi:[1,0]
	v_pk_mul_f32 v[174:175], v[126:127], v[150:151] op_sel_hi:[1,0]
	v_lshlrev_b64 v[144:145], 9, v[148:149]
	v_pk_mul_f32 v[176:177], v[120:121], v[150:151] op_sel_hi:[1,0]
	v_pk_mul_f32 v[178:179], v[122:123], v[150:151] op_sel_hi:[1,0]
	v_lshl_add_u64 v[144:145], v[146:147], 0, v[144:145]
	v_add_u32_e32 v149, 64, v160
	s_waitcnt vmcnt(3)
	v_pk_mul_f32 v[178:179], v[138:139], v[178:179]
	s_waitcnt vmcnt(2)
	v_pk_mul_f32 v[174:175], v[142:143], v[174:175]
	v_pk_mul_f32 v[172:173], v[140:141], v[172:173]
	v_pk_mul_f32 v[176:177], v[136:137], v[176:177]
	v_cvt_pk_bf16_f32 v172, v172, v173
	v_cvt_pk_bf16_f32 v173, v174, v175
	s_nop 0
	v_cvt_pk_bf16_f32 v174, v176, v177
	v_cvt_pk_bf16_f32 v175, v178, v179
	global_store_dwordx4 v[144:145], v[172:175], off
	v_pk_mul_f32 v[176:177], v[112:113], v[150:151] op_sel_hi:[1,0]
	s_nop 0
	v_pk_mul_f32 v[172:173], v[116:117], v[150:151] op_sel_hi:[1,0]
	v_pk_mul_f32 v[174:175], v[118:119], v[150:151] op_sel_hi:[1,0]
	s_waitcnt vmcnt(1)
	v_pk_mul_f32 v[172:173], v[132:133], v[172:173]
	v_pk_mul_f32 v[174:175], v[134:135], v[174:175]
	v_pk_mul_f32 v[150:151], v[114:115], v[150:151] op_sel_hi:[1,0]
	v_pk_mul_f32 v[176:177], v[128:129], v[176:177]
	v_pk_mul_f32 v[150:151], v[130:131], v[150:151]
	v_cvt_pk_bf16_f32 v172, v172, v173
	v_cvt_pk_bf16_f32 v173, v174, v175
	v_cvt_pk_bf16_f32 v174, v176, v177
	s_nop 0
	v_cvt_pk_bf16_f32 v175, v150, v151
	global_store_dwordx4 v[144:145], v[172:175], off offset:256
	ds_read2_b32 v[172:173], v160 offset0:16 offset1:144
	ds_read2st64_b32 v[174:175], v149 offset0:4 offset1:6
	v_or_b32_e32 v150, 16, v148
	s_waitcnt lgkmcnt(1)
	v_mov_b32_e32 v176, v172
	s_waitcnt lgkmcnt(0)
	v_mov_b32_e32 v177, v174
	v_mov_b32_e32 v174, v173
	v_pk_add_f32 v[172:173], v[176:177], v[174:175]
	s_nop 0
	v_add_f32_e32 v151, v172, v173
	v_fmamk_f32 v151, v151, 0x3b800000, v205
	v_cmp_gt_f32_e32 vcc, s84, v151
	v_mul_f32_e32 v172, 0x4b800000, v151
	s_nop 0
	v_cndmask_b32_e32 v151, v151, v172, vcc
	v_rsq_f32_e32 v151, v151
	s_nop 0
	v_mul_f32_e32 v172, 0x45800000, v151
	v_cndmask_b32_e32 v176, v151, v172, vcc
	v_ashrrev_i32_e32 v151, 31, v150
	v_pk_mul_f32 v[172:173], v[108:109], v[176:177] op_sel_hi:[1,0]
	v_pk_mul_f32 v[174:175], v[110:111], v[176:177] op_sel_hi:[1,0]
	v_lshlrev_b64 v[150:151], 9, v[150:151]
	v_pk_mul_f32 v[174:175], v[142:143], v[174:175]
	v_pk_mul_f32 v[172:173], v[140:141], v[172:173]
	v_pk_mul_f32 v[178:179], v[104:105], v[176:177] op_sel_hi:[1,0]
	v_pk_mul_f32 v[180:181], v[106:107], v[176:177] op_sel_hi:[1,0]
	v_lshl_add_u64 v[150:151], v[146:147], 0, v[150:151]
	v_pk_mul_f32 v[180:181], v[138:139], v[180:181]
	v_pk_mul_f32 v[178:179], v[136:137], v[178:179]
	v_cvt_pk_bf16_f32 v172, v172, v173
	v_cvt_pk_bf16_f32 v173, v174, v175
	s_nop 0
	v_cvt_pk_bf16_f32 v174, v178, v179
	v_cvt_pk_bf16_f32 v175, v180, v181
	global_store_dwordx4 v[150:151], v[172:175], off
	v_pk_mul_f32 v[178:179], v[96:97], v[176:177] op_sel_hi:[1,0]
	s_nop 0
	v_pk_mul_f32 v[172:173], v[100:101], v[176:177] op_sel_hi:[1,0]
	v_pk_mul_f32 v[174:175], v[102:103], v[176:177] op_sel_hi:[1,0]
	v_pk_mul_f32 v[172:173], v[132:133], v[172:173]
	v_pk_mul_f32 v[174:175], v[134:135], v[174:175]
	v_pk_mul_f32 v[176:177], v[98:99], v[176:177] op_sel_hi:[1,0]
	v_pk_mul_f32 v[178:179], v[128:129], v[178:179]
	v_cvt_pk_bf16_f32 v172, v172, v173
	v_cvt_pk_bf16_f32 v173, v174, v175
	v_pk_mul_f32 v[176:177], v[130:131], v[176:177]
	v_cvt_pk_bf16_f32 v174, v178, v179
	s_nop 0
	v_cvt_pk_bf16_f32 v175, v176, v177
	global_store_dwordx4 v[150:151], v[172:175], off offset:256
	ds_read2_b32 v[172:173], v160 offset0:32 offset1:160
	v_or_b32_e32 v150, 32, v148
	v_add_u32_e32 v174, 0x80, v160
	ds_read2st64_b32 v[176:177], v174 offset0:4 offset1:6
	s_waitcnt lgkmcnt(1)
	v_mov_b32_e32 v178, v172
	s_waitcnt lgkmcnt(0)
	v_mov_b32_e32 v179, v176
	v_mov_b32_e32 v176, v173
	v_pk_add_f32 v[172:173], v[178:179], v[176:177]
	s_nop 0
	v_add_f32_e32 v151, v172, v173
	v_fmamk_f32 v151, v151, 0x3b800000, v205
	v_cmp_gt_f32_e32 vcc, s84, v151
	v_mul_f32_e32 v172, 0x4b800000, v151
	s_nop 0
	v_cndmask_b32_e32 v151, v151, v172, vcc
	v_rsq_f32_e32 v151, v151
	s_nop 0
	v_mul_f32_e32 v172, 0x45800000, v151
	v_cndmask_b32_e32 v172, v151, v172, vcc
	v_ashrrev_i32_e32 v151, 31, v150
	v_pk_mul_f32 v[176:177], v[92:93], v[172:173] op_sel_hi:[1,0]
	v_lshlrev_b64 v[150:151], 9, v[150:151]
	v_pk_mul_f32 v[178:179], v[94:95], v[172:173] op_sel_hi:[1,0]
	v_pk_mul_f32 v[176:177], v[140:141], v[176:177]
	v_lshl_add_u64 v[150:151], v[146:147], 0, v[150:151]
	v_pk_mul_f32 v[178:179], v[142:143], v[178:179]
	v_pk_mul_f32 v[180:181], v[88:89], v[172:173] op_sel_hi:[1,0]
	v_pk_mul_f32 v[182:183], v[90:91], v[172:173] op_sel_hi:[1,0]
	v_cvt_pk_bf16_f32 v176, v176, v177
	v_cvt_pk_bf16_f32 v177, v178, v179
	v_pk_mul_f32 v[180:181], v[136:137], v[180:181]
	v_pk_mul_f32 v[182:183], v[138:139], v[182:183]
	v_cvt_pk_bf16_f32 v178, v180, v181
	v_pk_mul_f32 v[180:181], v[80:81], v[172:173] op_sel_hi:[1,0]
	v_cvt_pk_bf16_f32 v179, v182, v183
	global_store_dwordx4 v[150:151], v[176:179], off
	v_pk_mul_f32 v[180:181], v[128:129], v[180:181]
	s_nop 0
	v_pk_mul_f32 v[176:177], v[84:85], v[172:173] op_sel_hi:[1,0]
	v_pk_mul_f32 v[178:179], v[86:87], v[172:173] op_sel_hi:[1,0]
	v_pk_mul_f32 v[176:177], v[132:133], v[176:177]
	v_pk_mul_f32 v[172:173], v[82:83], v[172:173] op_sel_hi:[1,0]
	v_pk_mul_f32 v[178:179], v[134:135], v[178:179]
	v_pk_mul_f32 v[172:173], v[130:131], v[172:173]
	v_cvt_pk_bf16_f32 v176, v176, v177
	v_cvt_pk_bf16_f32 v177, v178, v179
	v_cvt_pk_bf16_f32 v178, v180, v181
	s_nop 0
	v_cvt_pk_bf16_f32 v179, v172, v173
	global_store_dwordx4 v[150:151], v[176:179], off offset:256
	ds_read2_b32 v[172:173], v160 offset0:48 offset1:176
	ds_read2st64_b32 v[176:177], v184 offset0:4 offset1:6
	v_or_b32_e32 v150, 48, v148
	s_waitcnt lgkmcnt(1)
	v_mov_b32_e32 v178, v172
	s_waitcnt lgkmcnt(0)
	v_mov_b32_e32 v179, v176
	v_mov_b32_e32 v176, v173
	v_pk_add_f32 v[172:173], v[178:179], v[176:177]
	s_nop 0
	v_add_f32_e32 v148, v172, v173
	v_fmamk_f32 v148, v148, 0x3b800000, v205
	v_cmp_gt_f32_e32 vcc, s84, v148
	v_mul_f32_e32 v151, 0x4b800000, v148
	s_nop 0
	v_cndmask_b32_e32 v148, v148, v151, vcc
	v_rsq_f32_e32 v148, v148
	s_nop 0
	v_mul_f32_e32 v151, 0x45800000, v148
	v_cndmask_b32_e32 v148, v148, v151, vcc
	v_ashrrev_i32_e32 v151, 31, v150
	v_lshlrev_b64 v[150:151], 9, v[150:151]
	v_pk_mul_f32 v[176:177], v[72:73], v[148:149] op_sel_hi:[1,0]
	v_pk_mul_f32 v[178:179], v[74:75], v[148:149] op_sel_hi:[1,0]
	v_lshl_add_u64 v[146:147], v[146:147], 0, v[150:151]
	v_pk_mul_f32 v[150:151], v[76:77], v[148:149] op_sel_hi:[1,0]
	v_pk_mul_f32 v[172:173], v[78:79], v[148:149] op_sel_hi:[1,0]
	v_pk_mul_f32 v[180:181], v[138:139], v[178:179]
	v_pk_mul_f32 v[178:179], v[136:137], v[176:177]
	v_pk_mul_f32 v[172:173], v[142:143], v[172:173]
	v_pk_mul_f32 v[150:151], v[140:141], v[150:151]
	s_nop 0
	v_cvt_pk_bf16_f32 v176, v150, v151
	v_cvt_pk_bf16_f32 v177, v172, v173
	v_cvt_pk_bf16_f32 v178, v178, v179
	v_cvt_pk_bf16_f32 v179, v180, v181
	global_store_dwordx4 v[146:147], v[176:179], off
	v_pk_mul_f32 v[150:151], v[68:69], v[148:149] op_sel_hi:[1,0]
	v_pk_mul_f32 v[172:173], v[70:71], v[148:149] op_sel_hi:[1,0]
	v_pk_mul_f32 v[176:177], v[64:65], v[148:149] op_sel_hi:[1,0]
	v_pk_mul_f32 v[178:179], v[66:67], v[148:149] op_sel_hi:[1,0]
	v_pk_mul_f32 v[172:173], v[134:135], v[172:173]
	v_pk_mul_f32 v[180:181], v[130:131], v[178:179]
	v_pk_mul_f32 v[178:179], v[128:129], v[176:177]
	v_pk_mul_f32 v[150:151], v[132:133], v[150:151]
	s_nop 0
	v_cvt_pk_bf16_f32 v176, v150, v151
	v_cvt_pk_bf16_f32 v177, v172, v173
	v_cvt_pk_bf16_f32 v178, v178, v179
	v_cvt_pk_bf16_f32 v179, v180, v181
	global_store_dwordx4 v[146:147], v[176:179], off offset:256
	ds_read2st64_b32 v[146:147], v160 offset0:1 offset1:3
	ds_read2st64_b32 v[150:151], v160 offset0:5 offset1:7
	s_waitcnt lgkmcnt(1)
	v_mov_b32_e32 v172, v146
	s_waitcnt lgkmcnt(0)
	v_mov_b32_e32 v173, v150
	v_mov_b32_e32 v150, v147
	v_pk_add_f32 v[146:147], v[172:173], v[150:151]
	v_lshl_add_u64 v[150:151], v[144:145], 0, s[6:7]
	v_add_f32_e32 v146, v146, v147
	v_fmamk_f32 v146, v146, 0x3b800000, v205
	v_cmp_gt_f32_e32 vcc, s84, v146
	v_mul_f32_e32 v147, 0x4b800000, v146
	s_mov_b32 s6, 0x10000
	v_cndmask_b32_e32 v146, v146, v147, vcc
	v_rsq_f32_e32 v146, v146
	s_nop 0
	v_mul_f32_e32 v147, 0x45800000, v146
	v_cndmask_b32_e32 v146, v146, v147, vcc
	v_pk_mul_f32 v[172:173], v[60:61], v[146:147] op_sel_hi:[1,0]
	v_pk_mul_f32 v[176:177], v[62:63], v[146:147] op_sel_hi:[1,0]
	v_pk_mul_f32 v[172:173], v[140:141], v[172:173]
	v_pk_mul_f32 v[178:179], v[142:143], v[176:177]
	v_pk_mul_f32 v[176:177], v[56:57], v[146:147] op_sel_hi:[1,0]
	v_pk_mul_f32 v[180:181], v[58:59], v[146:147] op_sel_hi:[1,0]
	v_pk_mul_f32 v[182:183], v[136:137], v[176:177]
	v_cvt_pk_bf16_f32 v176, v172, v173
	v_add_co_u32_e32 v172, vcc, s6, v144
	v_cvt_pk_bf16_f32 v177, v178, v179
	v_pk_mul_f32 v[180:181], v[138:139], v[180:181]
	s_nop 0
	v_addc_co_u32_e32 v173, vcc, 0, v145, vcc
	v_cvt_pk_bf16_f32 v178, v182, v183
	v_cvt_pk_bf16_f32 v179, v180, v181
	global_store_dwordx4 v[172:173], v[176:179], off
	v_pk_mul_f32 v[172:173], v[52:53], v[146:147] op_sel_hi:[1,0]
	s_mov_b64 s[6:7], 0x12000
	v_pk_mul_f32 v[176:177], v[54:55], v[146:147] op_sel_hi:[1,0]
	v_pk_mul_f32 v[172:173], v[132:133], v[172:173]
	v_pk_mul_f32 v[178:179], v[134:135], v[176:177]
	v_pk_mul_f32 v[176:177], v[48:49], v[146:147] op_sel_hi:[1,0]
	v_pk_mul_f32 v[146:147], v[50:51], v[146:147] op_sel_hi:[1,0]
	v_pk_mul_f32 v[180:181], v[128:129], v[176:177]
	v_pk_mul_f32 v[146:147], v[130:131], v[146:147]
	v_cvt_pk_bf16_f32 v176, v172, v173
	v_cvt_pk_bf16_f32 v177, v178, v179
	v_cvt_pk_bf16_f32 v178, v180, v181
	v_lshl_add_u64 v[172:173], v[144:145], 0, s[6:7]
	v_cvt_pk_bf16_f32 v179, v146, v147
	global_store_dwordx4 v[150:151], v[176:179], off offset:256
	ds_read2_b32 v[146:147], v160 offset0:80 offset1:208
	ds_read2st64_b32 v[148:149], v149 offset0:5 offset1:7
	s_mov_b32 s6, 0x12000
	s_waitcnt lgkmcnt(1)
	v_mov_b32_e32 v150, v146
	s_waitcnt lgkmcnt(0)
	v_mov_b32_e32 v151, v148
	v_mov_b32_e32 v148, v147
	v_pk_add_f32 v[146:147], v[150:151], v[148:149]
	s_nop 0
	v_add_f32_e32 v146, v146, v147
	v_fmamk_f32 v146, v146, 0x3b800000, v205
	v_cmp_gt_f32_e32 vcc, s84, v146
	v_mul_f32_e32 v147, 0x4b800000, v146
	s_nop 0
	v_cndmask_b32_e32 v146, v146, v147, vcc
	v_rsq_f32_e32 v146, v146
	s_nop 0
	v_mul_f32_e32 v147, 0x45800000, v146
	v_cndmask_b32_e32 v150, v146, v147, vcc
	v_pk_mul_f32 v[146:147], v[44:45], v[150:151] op_sel_hi:[1,0]
	v_pk_mul_f32 v[148:149], v[46:47], v[150:151] op_sel_hi:[1,0]
	v_pk_mul_f32 v[176:177], v[40:41], v[150:151] op_sel_hi:[1,0]
	v_pk_mul_f32 v[148:149], v[142:143], v[148:149]
	v_pk_mul_f32 v[146:147], v[140:141], v[146:147]
	v_pk_mul_f32 v[176:177], v[136:137], v[176:177]
	v_pk_mul_f32 v[178:179], v[42:43], v[150:151] op_sel_hi:[1,0]
	v_cvt_pk_bf16_f32 v146, v146, v147
	v_cvt_pk_bf16_f32 v147, v148, v149
	v_cvt_pk_bf16_f32 v148, v176, v177
	v_add_co_u32_e32 v176, vcc, s6, v144
	v_pk_mul_f32 v[178:179], v[138:139], v[178:179]
	s_nop 0
	v_addc_co_u32_e32 v177, vcc, 0, v145, vcc
	v_cvt_pk_bf16_f32 v149, v178, v179
	global_store_dwordx4 v[176:177], v[146:149], off
	v_pk_mul_f32 v[176:177], v[32:33], v[150:151] op_sel_hi:[1,0]
	s_mov_b64 s[6:7], 0x14000
	v_pk_mul_f32 v[146:147], v[36:37], v[150:151] op_sel_hi:[1,0]
	v_pk_mul_f32 v[148:149], v[38:39], v[150:151] op_sel_hi:[1,0]
	v_pk_mul_f32 v[146:147], v[132:133], v[146:147]
	v_pk_mul_f32 v[148:149], v[134:135], v[148:149]
	v_pk_mul_f32 v[150:151], v[34:35], v[150:151] op_sel_hi:[1,0]
	v_pk_mul_f32 v[176:177], v[128:129], v[176:177]
	v_pk_mul_f32 v[150:151], v[130:131], v[150:151]
	v_cvt_pk_bf16_f32 v146, v146, v147
	v_cvt_pk_bf16_f32 v147, v148, v149
	v_cvt_pk_bf16_f32 v148, v176, v177
	s_nop 0
	v_cvt_pk_bf16_f32 v149, v150, v151
	global_store_dwordx4 v[172:173], v[146:149], off offset:256
	ds_read2_b32 v[146:147], v160 offset0:96 offset1:224
	ds_read2st64_b32 v[148:149], v174 offset0:5 offset1:7
	v_lshl_add_u64 v[172:173], v[144:145], 0, s[6:7]
	s_mov_b32 s6, 0x14000
	s_waitcnt lgkmcnt(1)
	v_mov_b32_e32 v150, v146
	s_waitcnt lgkmcnt(0)
	v_mov_b32_e32 v151, v148
	v_mov_b32_e32 v148, v147
	v_pk_add_f32 v[146:147], v[150:151], v[148:149]
	s_nop 0
	v_add_f32_e32 v146, v146, v147
	v_fmamk_f32 v146, v146, 0x3b800000, v205
	v_cmp_gt_f32_e32 vcc, s84, v146
	v_mul_f32_e32 v147, 0x4b800000, v146
	s_nop 0
	v_cndmask_b32_e32 v146, v146, v147, vcc
	v_rsq_f32_e32 v146, v146
	s_nop 0
	v_mul_f32_e32 v147, 0x45800000, v146
	v_cndmask_b32_e32 v150, v146, v147, vcc
	v_pk_mul_f32 v[146:147], v[28:29], v[150:151] op_sel_hi:[1,0]
	v_pk_mul_f32 v[148:149], v[30:31], v[150:151] op_sel_hi:[1,0]
	v_pk_mul_f32 v[174:175], v[24:25], v[150:151] op_sel_hi:[1,0]
	v_pk_mul_f32 v[148:149], v[142:143], v[148:149]
	v_pk_mul_f32 v[146:147], v[140:141], v[146:147]
	v_pk_mul_f32 v[174:175], v[136:137], v[174:175]
	v_pk_mul_f32 v[176:177], v[26:27], v[150:151] op_sel_hi:[1,0]
	v_cvt_pk_bf16_f32 v146, v146, v147
	v_cvt_pk_bf16_f32 v147, v148, v149
	v_cvt_pk_bf16_f32 v148, v174, v175
	v_add_co_u32_e32 v174, vcc, s6, v144
	v_pk_mul_f32 v[176:177], v[138:139], v[176:177]
	s_nop 0
	v_addc_co_u32_e32 v175, vcc, 0, v145, vcc
	v_cvt_pk_bf16_f32 v149, v176, v177
	global_store_dwordx4 v[174:175], v[146:149], off
	v_pk_mul_f32 v[174:175], v[16:17], v[150:151] op_sel_hi:[1,0]
	s_mov_b64 s[6:7], 0x16000
	v_pk_mul_f32 v[146:147], v[20:21], v[150:151] op_sel_hi:[1,0]
	v_pk_mul_f32 v[148:149], v[22:23], v[150:151] op_sel_hi:[1,0]
	v_pk_mul_f32 v[146:147], v[132:133], v[146:147]
	v_pk_mul_f32 v[148:149], v[134:135], v[148:149]
	v_pk_mul_f32 v[150:151], v[18:19], v[150:151] op_sel_hi:[1,0]
	v_pk_mul_f32 v[174:175], v[128:129], v[174:175]
	v_pk_mul_f32 v[150:151], v[130:131], v[150:151]
	v_cvt_pk_bf16_f32 v146, v146, v147
	v_cvt_pk_bf16_f32 v147, v148, v149
	v_cvt_pk_bf16_f32 v148, v174, v175
	s_nop 0
	v_cvt_pk_bf16_f32 v149, v150, v151
	global_store_dwordx4 v[172:173], v[146:149], off offset:256
	ds_read2_b32 v[146:147], v160 offset0:112 offset1:240
	ds_read2st64_b32 v[148:149], v184 offset0:5 offset1:7
	s_waitcnt lgkmcnt(1)
	v_mov_b32_e32 v150, v146
	s_waitcnt lgkmcnt(0)
	v_mov_b32_e32 v151, v148
	v_mov_b32_e32 v148, v147
	v_pk_add_f32 v[146:147], v[150:151], v[148:149]
	v_lshl_add_u64 v[148:149], v[144:145], 0, s[6:7]
	v_add_f32_e32 v146, v146, v147
	v_fmamk_f32 v146, v146, 0x3b800000, v205
	v_cmp_gt_f32_e32 vcc, s84, v146
	v_mul_f32_e32 v147, 0x4b800000, v146
	s_mov_b32 s6, 0x16000
	v_cndmask_b32_e32 v146, v146, v147, vcc
	v_rsq_f32_e32 v146, v146
	s_nop 0
	v_mul_f32_e32 v147, 0x45800000, v146
	v_cndmask_b32_e32 v146, v146, v147, vcc
	v_pk_mul_f32 v[150:151], v[12:13], v[146:147] op_sel_hi:[1,0]
	v_pk_mul_f32 v[172:173], v[14:15], v[146:147] op_sel_hi:[1,0]
	v_pk_mul_f32 v[140:141], v[140:141], v[150:151]
	v_pk_mul_f32 v[142:143], v[142:143], v[172:173]
	v_pk_mul_f32 v[150:151], v[8:9], v[146:147] op_sel_hi:[1,0]
	v_pk_mul_f32 v[172:173], v[10:11], v[146:147] op_sel_hi:[1,0]
	s_nop 0
	v_pk_mul_f32 v[172:173], v[138:139], v[172:173]
	v_pk_mul_f32 v[138:139], v[136:137], v[150:151]
	v_cvt_pk_bf16_f32 v136, v140, v141
	v_add_co_u32_e32 v140, vcc, s6, v144
	v_cvt_pk_bf16_f32 v137, v142, v143
	v_cvt_pk_bf16_f32 v138, v138, v139
	v_cvt_pk_bf16_f32 v139, v172, v173
	s_nop 1
	v_addc_co_u32_e32 v141, vcc, 0, v145, vcc
	global_store_dwordx4 v[140:141], v[136:139], off
	s_nop 1
	v_pk_mul_f32 v[136:137], v[4:5], v[146:147] op_sel_hi:[1,0]
	v_pk_mul_f32 v[138:139], v[6:7], v[146:147] op_sel_hi:[1,0]
	v_pk_mul_f32 v[132:133], v[132:133], v[136:137]
	v_pk_mul_f32 v[134:135], v[134:135], v[138:139]
	v_pk_mul_f32 v[136:137], v[0:1], v[146:147] op_sel_hi:[1,0]
	v_pk_mul_f32 v[138:139], v[2:3], v[146:147] op_sel_hi:[1,0]
	s_nop 0
	v_pk_mul_f32 v[138:139], v[130:131], v[138:139]
	v_pk_mul_f32 v[130:131], v[128:129], v[136:137]
	v_cvt_pk_bf16_f32 v128, v132, v133
	v_cvt_pk_bf16_f32 v129, v134, v135
	s_nop 0
	v_cvt_pk_bf16_f32 v130, v130, v131
	v_cvt_pk_bf16_f32 v131, v138, v139
	global_store_dwordx4 v[148:149], v[128:131], off offset:256

.LBB0_903:
	s_or_b64 exec, exec, s[6:7]
	s_add_i32 s6, s14, 0xffff8080
	v_add_u32_e32 v216, 0x80, v139
	s_lshr_b32 s8, s6, 8
	s_mul_hi_u32 s87, s8, 0x1100
	s_mulk_i32 s8, 0x1100
	s_movk_i32 s6, 0x7f7f
	v_and_b32_e32 v134, 0xcf, v216
	v_cmp_lt_i32_e64 s[16:17], s6, v139
	v_or_b32_e32 v176, s8, v134
	v_cvt_pk_bf16_f32 v128, v52, v53
	v_cvt_pk_bf16_f32 v129, v54, v55
	v_cvt_pk_bf16_f32 v130, v48, v49
	v_cvt_pk_bf16_f32 v131, v50, v51
	s_and_saveexec_b64 s[6:7], s[16:17]
	s_xor_b64 s[6:7], exec, s[6:7]
	v_mov_b32_e32 v177, s87
	v_mov_b64_e32 v[134:135], v[176:177]
	s_or_saveexec_b64 s[6:7], s[6:7]
	v_ashrrev_i32_e32 v140, 12, v216
	v_and_b32_e32 v143, 0xfcf, v216
	v_mul_hi_i32_i24_e32 v141, 0x1100, v140
	v_mul_i32_i24_e32 v140, 0x1100, v140
	v_add_u32_e32 v180, 0x100, v143
	s_xor_b64 exec, exec, s[6:7]
	v_mov_b32_e32 v181, v161
	v_lshl_add_u64 v[134:135], v[140:141], 0, v[180:181]
	s_or_b64 exec, exec, s[6:7]
	v_lshlrev_b64 v[134:135], 8, v[134:135]
	v_lshl_add_u64 v[134:135], v[132:133], 0, v[134:135]
	global_store_dwordx4 v[134:135], v[128:131], off
	s_nop 1
	v_mul_f32_e32 v128, v45, v45
	v_fmac_f32_e32 v128, v44, v44
	v_fmac_f32_e32 v128, v46, v46
	v_fmac_f32_e32 v128, v47, v47
	v_fmac_f32_e32 v128, v40, v40
	v_fmac_f32_e32 v128, v41, v41
	v_fmac_f32_e32 v128, v42, v42
	v_fmac_f32_e32 v128, v43, v43
	ds_bpermute_b32 v129, v138, v128
	s_waitcnt lgkmcnt(0)
	v_add_f32_e32 v128, v128, v129
	ds_bpermute_b32 v129, v207, v128
	s_waitcnt lgkmcnt(0)
	v_add_f32_e32 v214, v128, v129
	s_and_saveexec_b64 s[6:7], vcc
	ds_write_b32 v142, v214 offset:320
	s_or_b64 exec, exec, s[6:7]
	v_add_u32_e32 v213, 0x90, v139
	s_movk_i32 s6, 0x7f6f
	v_and_b32_e32 v134, 0xdf, v213
	v_cmp_lt_i32_e64 s[12:13], s6, v139
	v_or_b32_e32 v150, s8, v134
	v_cvt_pk_bf16_f32 v128, v36, v37
	v_cvt_pk_bf16_f32 v129, v38, v39
	v_cvt_pk_bf16_f32 v130, v32, v33
	v_cvt_pk_bf16_f32 v131, v34, v35
	s_and_saveexec_b64 s[6:7], s[12:13]
	s_xor_b64 s[6:7], exec, s[6:7]
	v_mov_b32_e32 v151, s87
	v_mov_b64_e32 v[134:135], v[150:151]
	s_or_saveexec_b64 s[6:7], s[6:7]
	v_and_b32_e32 v143, 0xfdf, v213
	v_add_u32_e32 v172, 0x100, v143
	s_xor_b64 exec, exec, s[6:7]
	v_mov_b32_e32 v173, v161
	v_lshl_add_u64 v[134:135], v[140:141], 0, v[172:173]
	s_or_b64 exec, exec, s[6:7]
	v_lshlrev_b64 v[134:135], 8, v[134:135]
	v_lshl_add_u64 v[134:135], v[132:133], 0, v[134:135]
	global_store_dwordx4 v[134:135], v[128:131], off
	s_nop 1
	v_mul_f32_e32 v128, v29, v29
	v_fmac_f32_e32 v128, v28, v28
	v_fmac_f32_e32 v128, v30, v30
	v_fmac_f32_e32 v128, v31, v31
	v_fmac_f32_e32 v128, v24, v24
	v_fmac_f32_e32 v128, v25, v25
	v_fmac_f32_e32 v128, v26, v26
	v_fmac_f32_e32 v128, v27, v27
	ds_bpermute_b32 v129, v138, v128
	s_waitcnt lgkmcnt(0)
	v_add_f32_e32 v128, v128, v129
	ds_bpermute_b32 v129, v207, v128
	s_waitcnt lgkmcnt(0)
	v_add_f32_e32 v212, v128, v129
	s_and_saveexec_b64 s[6:7], vcc
	ds_write_b32 v142, v212 offset:384
	s_or_b64 exec, exec, s[6:7]
	v_add_u32_e32 v211, 0xa0, v139
	s_movk_i32 s6, 0x7f5f
	v_and_b32_e32 v134, 0xef, v211
	v_cmp_lt_i32_e64 s[10:11], s6, v139
	v_or_b32_e32 v146, s8, v134
	v_cvt_pk_bf16_f32 v128, v20, v21
	v_cvt_pk_bf16_f32 v129, v22, v23
	v_cvt_pk_bf16_f32 v130, v16, v17
	v_cvt_pk_bf16_f32 v131, v18, v19
	s_and_saveexec_b64 s[6:7], s[10:11]
	s_xor_b64 s[6:7], exec, s[6:7]
	v_mov_b32_e32 v147, s87
	v_mov_b64_e32 v[134:135], v[146:147]
	s_or_saveexec_b64 s[6:7], s[6:7]
	v_and_b32_e32 v143, 0xfef, v211
	v_add_u32_e32 v148, 0x100, v143
	s_xor_b64 exec, exec, s[6:7]
	v_mov_b32_e32 v149, v161
	v_lshl_add_u64 v[134:135], v[140:141], 0, v[148:149]
	s_or_b64 exec, exec, s[6:7]
	v_lshlrev_b64 v[134:135], 8, v[134:135]
	v_lshl_add_u64 v[134:135], v[132:133], 0, v[134:135]
	global_store_dwordx4 v[134:135], v[128:131], off
	s_nop 1
	v_mul_f32_e32 v128, v13, v13
	v_fmac_f32_e32 v128, v12, v12
	v_fmac_f32_e32 v128, v14, v14
	v_fmac_f32_e32 v128, v15, v15
	v_fmac_f32_e32 v128, v8, v8
	v_fmac_f32_e32 v128, v9, v9
	v_fmac_f32_e32 v128, v10, v10
	v_fmac_f32_e32 v128, v11, v11
	ds_bpermute_b32 v129, v138, v128
	s_waitcnt lgkmcnt(0)
	v_add_f32_e32 v128, v128, v129
	ds_bpermute_b32 v129, v207, v128
	s_waitcnt lgkmcnt(0)
	v_add_f32_e32 v210, v128, v129
	s_and_saveexec_b64 s[6:7], vcc
	ds_write_b32 v142, v210 offset:448
	s_or_b64 exec, exec, s[6:7]
	v_add_u32_e32 v209, 0xb0, v139
	s_movk_i32 s6, 0x7f4f
	v_cmp_lt_i32_e64 s[6:7], s6, v139
	v_or_b32_sdwa v142, s8, v209 dst_sel:DWORD dst_unused:UNUSED_PAD src0_sel:DWORD src1_sel:BYTE_0
	v_cvt_pk_bf16_f32 v128, v4, v5
	v_cvt_pk_bf16_f32 v129, v6, v7
	v_cvt_pk_bf16_f32 v130, v0, v1
	v_cvt_pk_bf16_f32 v131, v2, v3
	s_and_saveexec_b64 s[8:9], s[6:7]
	s_xor_b64 s[8:9], exec, s[8:9]
	v_mov_b32_e32 v143, s87
	v_mov_b64_e32 v[134:135], v[142:143]
	s_or_saveexec_b64 s[8:9], s[8:9]
	v_and_b32_e32 v138, 0xfff, v209
	v_add_u32_e32 v144, 0x100, v138
	s_xor_b64 exec, exec, s[8:9]
	v_mov_b32_e32 v145, v161
	v_lshl_add_u64 v[134:135], v[140:141], 0, v[144:145]
	s_or_b64 exec, exec, s[8:9]
	v_lshlrev_b64 v[134:135], 8, v[134:135]
	v_readlane_b32 s8, v254, 26
	v_lshl_add_u64 v[132:133], v[132:133], 0, v[134:135]
	v_readlane_b32 s9, v254, 27
	global_store_dwordx4 v[132:133], v[128:131], off
	s_waitcnt vmcnt(0) lgkmcnt(0)
	v_lshl_add_u64 v[132:133], v[178:179], 2, s[8:9]
	s_barrier
	global_load_dwordx4 v[128:131], v[132:133], off offset:16
	s_nop 0
	global_load_dwordx4 v[132:135], v[132:133], off
	v_and_b32_e32 v137, 32, v137
	v_cmp_eq_u32_e64 s[8:9], 0, v137
	s_lshr_b32 s27, s14, 6
	v_mov_b32_e32 v137, s59
	s_movk_i32 s14, 0x80
	v_bitop3_b32 v137, v208, s14, v137 bitop3:0x36
	v_lshl_add_u32 v137, v137, 2, 0
	v_add_u32_e32 v137, 0x20000, v137
	ds_read_b32 v137, v137
	v_and_b32_e32 v143, 8, v174
	v_cndmask_b32_e64 v145, 0, 1, s[28:29]
	v_cmp_ne_u32_e64 s[14:15], 1, v145
	s_waitcnt lgkmcnt(0)
	v_add_f32_e32 v136, v136, v137
	v_fmamk_f32 v136, v136, 0x3c800000, v205
	v_cmp_gt_f32_e32 vcc, s84, v136
	v_mul_f32_e32 v137, 0x4b800000, v136
	s_nop 0
	v_cndmask_b32_e32 v136, v136, v137, vcc
	v_rsq_f32_e32 v136, v136
	s_nop 0
	v_mul_f32_e32 v137, 0x45800000, v136
	v_cndmask_b32_e32 v174, v136, v137, vcc
	v_pk_mul_f32 v[136:137], v[124:125], v[174:175] op_sel_hi:[1,0]
	v_pk_mul_f32 v[138:139], v[126:127], v[174:175] op_sel_hi:[1,0]
	v_pk_mul_f32 v[198:199], v[120:121], v[174:175] op_sel_hi:[1,0]
	v_pk_mul_f32 v[174:175], v[122:123], v[174:175] op_sel_hi:[1,0]
	s_andn2_b64 vcc, exec, s[28:29]
	s_waitcnt vmcnt(1)
	v_pk_mul_f32 v[196:197], v[130:131], v[174:175]
	s_waitcnt vmcnt(0)
	v_pk_mul_f32 v[138:139], v[134:135], v[138:139]
	v_pk_mul_f32 v[136:137], v[132:133], v[136:137]
	v_pk_mul_f32 v[198:199], v[128:129], v[198:199]
	v_lshlrev_b32_e32 v174, 2, v143
	s_cbranch_vccnz .LBB0_927
	v_mov_b32_e32 v143, s27
	v_cndmask_b32_e64 v143, v208, v143, s[0:1]
	v_lshlrev_b32_e32 v143, 6, v143
	v_and_b32_e32 v224, 0xfc0, v143
	v_mov_b32_e32 v225, v161
	v_lshl_add_u64 v[224:225], s[46:47], 0, v[224:225]
	v_mov_b32_e32 v175, v161
	v_lshl_add_u64 v[236:237], v[224:225], 0, v[174:175]
	v_add_co_u32_e32 v224, vcc, 0x1000, v236
	v_lshl_add_u64 v[228:229], v[236:237], 0, s[90:91]
	s_nop 0
	v_addc_co_u32_e32 v225, vcc, 0, v237, vcc
	global_load_dwordx4 v[224:227], v[224:225], off
	s_nop 0
	global_load_dwordx4 v[228:231], v[228:229], off offset:16
	s_nop 0
	global_load_dwordx4 v[232:235], v[236:237], off
	s_nop 0
	global_load_dwordx4 v[236:239], v[236:237], off offset:16
	ds_bpermute_b32 v240, v207, v136
	ds_bpermute_b32 v242, v207, v198
	ds_bpermute_b32 v241, v207, v137
	ds_bpermute_b32 v244, v207, v138
	ds_bpermute_b32 v245, v207, v139
	ds_bpermute_b32 v246, v207, v196
	ds_bpermute_b32 v247, v207, v197
	ds_bpermute_b32 v243, v207, v199
	s_waitcnt vmcnt(2) lgkmcnt(1)
	v_pk_mul_f32 v[230:231], v[230:231], v[246:247]
	v_pk_mul_f32 v[226:227], v[226:227], v[244:245]
	v_pk_mul_f32 v[224:225], v[224:225], v[240:241]
	s_waitcnt lgkmcnt(0)
	v_pk_mul_f32 v[228:229], v[228:229], v[242:243]
	v_xor_b32_e32 v143, 0x80000000, v226
	v_xor_b32_e32 v145, 0x80000000, v227
	v_xor_b32_e32 v147, 0x80000000, v224
	v_xor_b32_e32 v149, 0x80000000, v225
	v_xor_b32_e32 v151, 0x80000000, v228
	v_xor_b32_e32 v173, 0x80000000, v229
	v_xor_b32_e32 v175, 0x80000000, v230
	v_xor_b32_e32 v177, 0x80000000, v231
	v_cndmask_b32_e64 v227, v227, v145, s[8:9]
	v_cndmask_b32_e64 v226, v226, v143, s[8:9]
	v_cndmask_b32_e64 v225, v225, v149, s[8:9]
	v_cndmask_b32_e64 v224, v224, v147, s[8:9]
	v_cndmask_b32_e64 v231, v231, v177, s[8:9]
	v_cndmask_b32_e64 v230, v230, v175, s[8:9]
	v_cndmask_b32_e64 v229, v229, v173, s[8:9]
	v_cndmask_b32_e64 v228, v228, v151, s[8:9]
	s_waitcnt vmcnt(1)
	v_pk_fma_f32 v[138:139], v[138:139], v[234:235], v[226:227]
	v_pk_fma_f32 v[136:137], v[136:137], v[232:233], v[224:225]
	s_waitcnt vmcnt(0)
	v_pk_fma_f32 v[198:199], v[198:199], v[236:237], v[228:229]
	v_pk_fma_f32 v[196:197], v[196:197], v[238:239], v[230:231]
.LBB0_927:
	v_cvt_pk_bf16_f32 v136, v136, v137
	v_cvt_pk_bf16_f32 v137, v138, v139
	v_cvt_pk_bf16_f32 v138, v198, v199
	s_nop 0
	v_cvt_pk_bf16_f32 v139, v196, v197
	s_and_saveexec_b64 s[42:43], s[24:25]
	s_xor_b64 s[24:25], exec, s[42:43]
	v_mov_b32_e32 v195, s97
	s_andn2_saveexec_b64 s[24:25], s[24:25]
	v_lshl_add_u64 v[194:195], s[88:89], 0, v[160:161]
	s_or_b64 exec, exec, s[24:25]
	v_or_b32_e32 v143, s59, v208
	v_xor_b32_e32 v145, 0x90, v143
	v_lshl_add_u32 v145, v145, 2, 0
	v_add_u32_e32 v145, 0x20000, v145
	ds_read_b32 v145, v145
	v_readlane_b32 s24, v254, 28
	v_readlane_b32 s25, v254, 29
	v_lshlrev_b64 v[194:195], 8, v[194:195]
	s_waitcnt lgkmcnt(0)
	v_add_f32_e32 v145, v222, v145
	v_fmamk_f32 v145, v145, 0x3c800000, v205
	v_mul_f32_e32 v147, 0x4b800000, v145
	v_cmp_gt_f32_e32 vcc, s84, v145
	v_lshl_add_u64 v[178:179], v[178:179], 1, s[24:25]
	v_lshl_add_u64 v[194:195], v[178:179], 0, v[194:195]
	v_cndmask_b32_e32 v145, v145, v147, vcc
	v_rsq_f32_e32 v145, v145
	global_store_dwordx4 v[194:195], v[136:139], off
	s_nop 1
	v_mul_f32_e32 v136, 0x45800000, v145
	v_cndmask_b32_e32 v160, v145, v136, vcc
	v_pk_mul_f32 v[136:137], v[108:109], v[160:161] op_sel_hi:[1,0]
	v_pk_mul_f32 v[138:139], v[110:111], v[160:161] op_sel_hi:[1,0]
	v_pk_mul_f32 v[196:197], v[104:105], v[160:161] op_sel_hi:[1,0]
	v_pk_mul_f32 v[194:195], v[106:107], v[160:161] op_sel_hi:[1,0]
	v_pk_mul_f32 v[138:139], v[134:135], v[138:139]
	v_pk_mul_f32 v[136:137], v[132:133], v[136:137]
	v_pk_mul_f32 v[194:195], v[130:131], v[194:195]
	s_and_b64 vcc, exec, s[14:15]
	v_pk_mul_f32 v[196:197], v[128:129], v[196:197]
	s_cbranch_vccnz .LBB0_933
	v_mov_b32_e32 v145, s27
	v_cndmask_b32_e64 v145, v221, v145, s[0:1]
	v_lshlrev_b32_e32 v145, 6, v145
	v_and_b32_e32 v160, 0xfc0, v145
	v_lshl_add_u64 v[198:199], s[46:47], 0, v[160:161]
	v_mov_b32_e32 v175, v161
	v_lshl_add_u64 v[198:199], v[198:199], 0, v[174:175]
	v_add_co_u32_e32 v222, vcc, 0x1000, v198
	v_lshl_add_u64 v[226:227], v[198:199], 0, s[90:91]
	s_nop 0
	v_addc_co_u32_e32 v223, vcc, 0, v199, vcc
	global_load_dwordx4 v[222:225], v[222:223], off
	s_nop 0
	global_load_dwordx4 v[226:229], v[226:227], off offset:16
	s_nop 0
	global_load_dwordx4 v[230:233], v[198:199], off
	global_load_dwordx4 v[234:237], v[198:199], off offset:16
	ds_bpermute_b32 v198, v207, v136
	ds_bpermute_b32 v238, v207, v196
	ds_bpermute_b32 v199, v207, v137
	ds_bpermute_b32 v240, v207, v138
	ds_bpermute_b32 v241, v207, v139
	ds_bpermute_b32 v242, v207, v194
	ds_bpermute_b32 v243, v207, v195
	ds_bpermute_b32 v239, v207, v197
	s_waitcnt vmcnt(2) lgkmcnt(0)
	v_pk_mul_f32 v[226:227], v[226:227], v[238:239]
	v_pk_mul_f32 v[224:225], v[224:225], v[240:241]
	v_pk_mul_f32 v[198:199], v[222:223], v[198:199]
	v_pk_mul_f32 v[222:223], v[228:229], v[242:243]
	v_xor_b32_e32 v145, 0x80000000, v224
	v_xor_b32_e32 v147, 0x80000000, v225
	v_xor_b32_e32 v149, 0x80000000, v198
	v_xor_b32_e32 v151, 0x80000000, v199
	v_xor_b32_e32 v160, 0x80000000, v226
	v_xor_b32_e32 v173, 0x80000000, v227
	v_xor_b32_e32 v175, 0x80000000, v222
	v_xor_b32_e32 v177, 0x80000000, v223
	v_cndmask_b32_e64 v225, v225, v147, s[8:9]
	v_cndmask_b32_e64 v224, v224, v145, s[8:9]
	v_cndmask_b32_e64 v199, v199, v151, s[8:9]
	v_cndmask_b32_e64 v198, v198, v149, s[8:9]
	v_cndmask_b32_e64 v223, v223, v177, s[8:9]
	v_cndmask_b32_e64 v222, v222, v175, s[8:9]
	v_cndmask_b32_e64 v227, v227, v173, s[8:9]
	v_cndmask_b32_e64 v226, v226, v160, s[8:9]
	s_waitcnt vmcnt(1)
	v_pk_fma_f32 v[138:139], v[138:139], v[232:233], v[224:225]
	v_pk_fma_f32 v[136:137], v[136:137], v[230:231], v[198:199]
	s_waitcnt vmcnt(0)
	v_pk_fma_f32 v[196:197], v[196:197], v[234:235], v[226:227]
	v_pk_fma_f32 v[194:195], v[194:195], v[236:237], v[222:223]
.LBB0_933:
	v_cvt_pk_bf16_f32 v136, v136, v137
	v_cvt_pk_bf16_f32 v137, v138, v139
	v_cvt_pk_bf16_f32 v138, v196, v197
	s_nop 0
	v_cvt_pk_bf16_f32 v139, v194, v195
	s_and_saveexec_b64 s[24:25], s[22:23]
	s_xor_b64 s[22:23], exec, s[24:25]
	v_mov_b32_e32 v191, s97
	s_andn2_saveexec_b64 s[22:23], s[22:23]
	v_mov_b32_e32 v193, v161
	v_lshl_add_u64 v[190:191], s[88:89], 0, v[192:193]
	s_or_b64 exec, exec, s[22:23]
	v_xor_b32_e32 v145, 0xa0, v143
	v_lshl_add_u32 v145, v145, 2, 0
	v_add_u32_e32 v145, 0x20000, v145
	ds_read_b32 v145, v145
	v_lshlrev_b64 v[190:191], 8, v[190:191]
	v_lshl_add_u64 v[190:191], v[178:179], 0, v[190:191]
	global_store_dwordx4 v[190:191], v[136:139], off
	s_waitcnt lgkmcnt(0)
	v_add_f32_e32 v145, v220, v145
	v_fmamk_f32 v145, v145, 0x3c800000, v205
	v_mul_f32_e32 v147, 0x4b800000, v145
	v_cmp_gt_f32_e32 vcc, s84, v145
	s_nop 1
	v_cndmask_b32_e32 v145, v145, v147, vcc
	v_rsq_f32_e32 v145, v145
	s_nop 0
	v_mul_f32_e32 v136, 0x45800000, v145
	v_cndmask_b32_e32 v160, v145, v136, vcc
	v_pk_mul_f32 v[136:137], v[92:93], v[160:161] op_sel_hi:[1,0]
	v_pk_mul_f32 v[138:139], v[94:95], v[160:161] op_sel_hi:[1,0]
	v_pk_mul_f32 v[192:193], v[88:89], v[160:161] op_sel_hi:[1,0]
	v_pk_mul_f32 v[190:191], v[90:91], v[160:161] op_sel_hi:[1,0]
	v_pk_mul_f32 v[138:139], v[134:135], v[138:139]
	v_pk_mul_f32 v[136:137], v[132:133], v[136:137]
	v_pk_mul_f32 v[190:191], v[130:131], v[190:191]
	s_and_b64 vcc, exec, s[14:15]
	v_pk_mul_f32 v[192:193], v[128:129], v[192:193]
	s_cbranch_vccnz .LBB0_939
	v_mov_b32_e32 v145, s27
	v_cndmask_b32_e64 v145, v219, v145, s[0:1]
	v_lshlrev_b32_e32 v145, 6, v145
	v_and_b32_e32 v160, 0xfc0, v145
	v_lshl_add_u64 v[194:195], s[46:47], 0, v[160:161]
	v_mov_b32_e32 v175, v161
	v_lshl_add_u64 v[198:199], v[194:195], 0, v[174:175]
	v_add_co_u32_e32 v194, vcc, 0x1000, v198
	v_lshl_add_u64 v[220:221], v[198:199], 0, s[90:91]
	s_nop 0
	v_addc_co_u32_e32 v195, vcc, 0, v199, vcc
	global_load_dwordx4 v[194:197], v[194:195], off
	s_nop 0
	global_load_dwordx4 v[220:223], v[220:221], off offset:16
	s_nop 0
	global_load_dwordx4 v[224:227], v[198:199], off
	global_load_dwordx4 v[228:231], v[198:199], off offset:16
	ds_bpermute_b32 v198, v207, v136
	ds_bpermute_b32 v232, v207, v192
	ds_bpermute_b32 v199, v207, v137
	ds_bpermute_b32 v234, v207, v138
	ds_bpermute_b32 v235, v207, v139
	ds_bpermute_b32 v236, v207, v190
	ds_bpermute_b32 v237, v207, v191
	ds_bpermute_b32 v233, v207, v193
	s_waitcnt vmcnt(2) lgkmcnt(0)
	v_pk_mul_f32 v[220:221], v[220:221], v[232:233]
	v_pk_mul_f32 v[196:197], v[196:197], v[234:235]
	v_pk_mul_f32 v[194:195], v[194:195], v[198:199]
	v_pk_mul_f32 v[198:199], v[222:223], v[236:237]
	v_xor_b32_e32 v145, 0x80000000, v196
	v_xor_b32_e32 v147, 0x80000000, v197
	v_xor_b32_e32 v149, 0x80000000, v194
	v_xor_b32_e32 v151, 0x80000000, v195
	v_xor_b32_e32 v160, 0x80000000, v220
	v_xor_b32_e32 v173, 0x80000000, v221
	v_xor_b32_e32 v175, 0x80000000, v198
	v_xor_b32_e32 v177, 0x80000000, v199
	v_cndmask_b32_e64 v197, v197, v147, s[8:9]
	v_cndmask_b32_e64 v196, v196, v145, s[8:9]
	v_cndmask_b32_e64 v195, v195, v151, s[8:9]
	v_cndmask_b32_e64 v194, v194, v149, s[8:9]
	v_cndmask_b32_e64 v199, v199, v177, s[8:9]
	v_cndmask_b32_e64 v198, v198, v175, s[8:9]
	v_cndmask_b32_e64 v221, v221, v173, s[8:9]
	v_cndmask_b32_e64 v220, v220, v160, s[8:9]
	s_waitcnt vmcnt(1)
	v_pk_fma_f32 v[138:139], v[138:139], v[226:227], v[196:197]
	v_pk_fma_f32 v[136:137], v[136:137], v[224:225], v[194:195]
	s_waitcnt vmcnt(0)
	v_pk_fma_f32 v[192:193], v[192:193], v[228:229], v[220:221]
	v_pk_fma_f32 v[190:191], v[190:191], v[230:231], v[198:199]
.LBB0_939:
	v_cvt_pk_bf16_f32 v136, v136, v137
	v_cvt_pk_bf16_f32 v137, v138, v139
	v_cvt_pk_bf16_f32 v138, v192, v193
	s_nop 0
	v_cvt_pk_bf16_f32 v139, v190, v191
	s_and_saveexec_b64 s[22:23], s[20:21]
	s_xor_b64 s[20:21], exec, s[22:23]
	v_mov_b32_e32 v187, s97
	s_andn2_saveexec_b64 s[20:21], s[20:21]
	v_mov_b32_e32 v189, v161
	v_lshl_add_u64 v[186:187], s[88:89], 0, v[188:189]
	s_or_b64 exec, exec, s[20:21]
	v_xor_b32_e32 v145, 0xb0, v143
	v_lshl_add_u32 v145, v145, 2, 0
	v_add_u32_e32 v145, 0x20000, v145
	ds_read_b32 v145, v145
	v_lshlrev_b64 v[186:187], 8, v[186:187]
	v_lshl_add_u64 v[186:187], v[178:179], 0, v[186:187]
	global_store_dwordx4 v[186:187], v[136:139], off
	s_waitcnt lgkmcnt(0)
	v_add_f32_e32 v145, v218, v145
	v_fmamk_f32 v145, v145, 0x3c800000, v205
	v_mul_f32_e32 v147, 0x4b800000, v145
	v_cmp_gt_f32_e32 vcc, s84, v145
	s_nop 1
	v_cndmask_b32_e32 v145, v145, v147, vcc
	v_rsq_f32_e32 v145, v145
	s_nop 0
	v_mul_f32_e32 v136, 0x45800000, v145
	v_cndmask_b32_e32 v160, v145, v136, vcc
	v_pk_mul_f32 v[136:137], v[76:77], v[160:161] op_sel_hi:[1,0]
	v_pk_mul_f32 v[138:139], v[78:79], v[160:161] op_sel_hi:[1,0]
	v_pk_mul_f32 v[188:189], v[72:73], v[160:161] op_sel_hi:[1,0]
	v_pk_mul_f32 v[186:187], v[74:75], v[160:161] op_sel_hi:[1,0]
	v_pk_mul_f32 v[138:139], v[134:135], v[138:139]
	v_pk_mul_f32 v[136:137], v[132:133], v[136:137]
	v_pk_mul_f32 v[186:187], v[130:131], v[186:187]
	s_and_b64 vcc, exec, s[14:15]
	v_pk_mul_f32 v[188:189], v[128:129], v[188:189]
	s_cbranch_vccnz .LBB0_945
	v_mov_b32_e32 v145, s27
	v_cndmask_b32_e64 v145, v217, v145, s[0:1]
	v_lshlrev_b32_e32 v145, 6, v145
	v_and_b32_e32 v160, 0xfc0, v145
	v_lshl_add_u64 v[190:191], s[46:47], 0, v[160:161]
	v_mov_b32_e32 v175, v161
	v_lshl_add_u64 v[198:199], v[190:191], 0, v[174:175]
	v_add_co_u32_e32 v190, vcc, 0x1000, v198
	v_lshl_add_u64 v[194:195], v[198:199], 0, s[90:91]
	s_nop 0
	v_addc_co_u32_e32 v191, vcc, 0, v199, vcc
	global_load_dwordx4 v[190:193], v[190:191], off
	s_nop 0
	global_load_dwordx4 v[194:197], v[194:195], off offset:16
	s_nop 0
	global_load_dwordx4 v[218:221], v[198:199], off
	global_load_dwordx4 v[222:225], v[198:199], off offset:16
	ds_bpermute_b32 v198, v207, v136
	ds_bpermute_b32 v226, v207, v188
	ds_bpermute_b32 v199, v207, v137
	ds_bpermute_b32 v228, v207, v138
	ds_bpermute_b32 v229, v207, v139
	ds_bpermute_b32 v230, v207, v186
	ds_bpermute_b32 v231, v207, v187
	ds_bpermute_b32 v227, v207, v189
	s_waitcnt vmcnt(2) lgkmcnt(1)
	v_pk_mul_f32 v[196:197], v[196:197], v[230:231]
	v_pk_mul_f32 v[192:193], v[192:193], v[228:229]
	v_pk_mul_f32 v[190:191], v[190:191], v[198:199]
	s_waitcnt lgkmcnt(0)
	v_pk_mul_f32 v[194:195], v[194:195], v[226:227]
	v_xor_b32_e32 v145, 0x80000000, v192
	v_xor_b32_e32 v147, 0x80000000, v193
	v_xor_b32_e32 v149, 0x80000000, v190
	v_xor_b32_e32 v151, 0x80000000, v191
	v_xor_b32_e32 v160, 0x80000000, v194
	v_xor_b32_e32 v173, 0x80000000, v195
	v_xor_b32_e32 v175, 0x80000000, v196
	v_xor_b32_e32 v177, 0x80000000, v197
	v_cndmask_b32_e64 v193, v193, v147, s[8:9]
	v_cndmask_b32_e64 v192, v192, v145, s[8:9]
	v_cndmask_b32_e64 v191, v191, v151, s[8:9]
	v_cndmask_b32_e64 v190, v190, v149, s[8:9]
	v_cndmask_b32_e64 v197, v197, v177, s[8:9]
	v_cndmask_b32_e64 v196, v196, v175, s[8:9]
	v_cndmask_b32_e64 v195, v195, v173, s[8:9]
	v_cndmask_b32_e64 v194, v194, v160, s[8:9]
	s_waitcnt vmcnt(1)
	v_pk_fma_f32 v[138:139], v[138:139], v[220:221], v[192:193]
	v_pk_fma_f32 v[136:137], v[136:137], v[218:219], v[190:191]
	s_waitcnt vmcnt(0)
	v_pk_fma_f32 v[188:189], v[188:189], v[222:223], v[194:195]
	v_pk_fma_f32 v[186:187], v[186:187], v[224:225], v[196:197]
.LBB0_945:
	v_cvt_pk_bf16_f32 v136, v136, v137
	v_cvt_pk_bf16_f32 v137, v138, v139
	v_cvt_pk_bf16_f32 v138, v188, v189
	s_nop 0
	v_cvt_pk_bf16_f32 v139, v186, v187
	s_and_saveexec_b64 s[20:21], s[18:19]
	s_xor_b64 s[18:19], exec, s[20:21]
	v_mov_b32_e32 v183, s97
	s_andn2_saveexec_b64 s[18:19], s[18:19]
	v_mov_b32_e32 v185, v161
	v_lshl_add_u64 v[182:183], s[88:89], 0, v[184:185]
	s_or_b64 exec, exec, s[18:19]
	v_readlane_b32 s18, v254, 35
	v_lshlrev_b64 v[182:183], 8, v[182:183]
	v_lshl_add_u64 v[182:183], v[178:179], 0, v[182:183]
	v_mov_b32_e32 v145, s18
	s_movk_i32 s18, 0x80
	v_bitop3_b32 v145, v208, s18, v145 bitop3:0x36
	v_lshl_add_u32 v145, v145, 2, 0
	v_add_u32_e32 v145, 0x20000, v145
	ds_read_b32 v145, v145
	global_store_dwordx4 v[182:183], v[136:139], off
	s_waitcnt lgkmcnt(0)
	v_add_f32_e32 v145, v215, v145
	v_fmamk_f32 v145, v145, 0x3c800000, v205
	v_mul_f32_e32 v147, 0x4b800000, v145
	v_cmp_gt_f32_e32 vcc, s84, v145
	s_nop 1
	v_cndmask_b32_e32 v145, v145, v147, vcc
	v_rsq_f32_e32 v147, v145
	v_lshrrev_b32_e32 v145, 6, v216
	v_mul_f32_e32 v136, 0x45800000, v147
	v_cndmask_b32_e32 v160, v147, v136, vcc
	v_pk_mul_f32 v[136:137], v[60:61], v[160:161] op_sel_hi:[1,0]
	v_pk_mul_f32 v[138:139], v[62:63], v[160:161] op_sel_hi:[1,0]
	v_pk_mul_f32 v[184:185], v[56:57], v[160:161] op_sel_hi:[1,0]
	v_pk_mul_f32 v[182:183], v[58:59], v[160:161] op_sel_hi:[1,0]
	v_pk_mul_f32 v[138:139], v[134:135], v[138:139]
	v_pk_mul_f32 v[136:137], v[132:133], v[136:137]
	v_pk_mul_f32 v[182:183], v[130:131], v[182:183]
	s_and_b64 vcc, exec, s[14:15]
	v_pk_mul_f32 v[184:185], v[128:129], v[184:185]
	s_cbranch_vccnz .LBB0_951
	v_cndmask_b32_e64 v147, v208, v145, s[0:1]
	v_lshlrev_b32_e32 v147, 6, v147
	v_and_b32_e32 v160, 0xfc0, v147
	v_lshl_add_u64 v[186:187], s[46:47], 0, v[160:161]
	v_mov_b32_e32 v175, v161
	v_lshl_add_u64 v[198:199], v[186:187], 0, v[174:175]
	v_add_co_u32_e32 v186, vcc, 0x1000, v198
	v_lshl_add_u64 v[190:191], v[198:199], 0, s[90:91]
	s_nop 0
	v_addc_co_u32_e32 v187, vcc, 0, v199, vcc
	global_load_dwordx4 v[186:189], v[186:187], off
	s_nop 0
	global_load_dwordx4 v[190:193], v[190:191], off offset:16
	s_nop 0
	global_load_dwordx4 v[194:197], v[198:199], off
	global_load_dwordx4 v[216:219], v[198:199], off offset:16
	ds_bpermute_b32 v198, v207, v136
	ds_bpermute_b32 v220, v207, v184
	ds_bpermute_b32 v199, v207, v137
	ds_bpermute_b32 v222, v207, v138
	ds_bpermute_b32 v223, v207, v139
	ds_bpermute_b32 v224, v207, v182
	ds_bpermute_b32 v225, v207, v183
	ds_bpermute_b32 v221, v207, v185
	s_waitcnt vmcnt(2) lgkmcnt(1)
	v_pk_mul_f32 v[192:193], v[192:193], v[224:225]
	v_pk_mul_f32 v[188:189], v[188:189], v[222:223]
	v_pk_mul_f32 v[186:187], v[186:187], v[198:199]
	s_waitcnt lgkmcnt(0)
	v_pk_mul_f32 v[190:191], v[190:191], v[220:221]
	v_xor_b32_e32 v147, 0x80000000, v188
	v_xor_b32_e32 v149, 0x80000000, v189
	v_xor_b32_e32 v151, 0x80000000, v186
	v_xor_b32_e32 v160, 0x80000000, v187
	v_xor_b32_e32 v173, 0x80000000, v190
	v_xor_b32_e32 v175, 0x80000000, v191
	v_xor_b32_e32 v177, 0x80000000, v192
	v_xor_b32_e32 v181, 0x80000000, v193
	v_cndmask_b32_e64 v189, v189, v149, s[8:9]
	v_cndmask_b32_e64 v188, v188, v147, s[8:9]
	v_cndmask_b32_e64 v187, v187, v160, s[8:9]
	v_cndmask_b32_e64 v186, v186, v151, s[8:9]
	v_cndmask_b32_e64 v193, v193, v181, s[8:9]
	v_cndmask_b32_e64 v192, v192, v177, s[8:9]
	v_cndmask_b32_e64 v191, v191, v175, s[8:9]
	v_cndmask_b32_e64 v190, v190, v173, s[8:9]
	s_waitcnt vmcnt(1)
	v_pk_fma_f32 v[138:139], v[138:139], v[196:197], v[188:189]
	v_pk_fma_f32 v[136:137], v[136:137], v[194:195], v[186:187]
	s_waitcnt vmcnt(0)
	v_pk_fma_f32 v[184:185], v[184:185], v[216:217], v[190:191]
	v_pk_fma_f32 v[182:183], v[182:183], v[218:219], v[192:193]
.LBB0_951:
	v_cvt_pk_bf16_f32 v136, v136, v137
	v_cvt_pk_bf16_f32 v137, v138, v139
	v_cvt_pk_bf16_f32 v138, v184, v185
	s_nop 0
	v_cvt_pk_bf16_f32 v139, v182, v183
	s_and_saveexec_b64 s[18:19], s[16:17]
	s_xor_b64 s[16:17], exec, s[18:19]
	v_mov_b32_e32 v177, s87
	s_andn2_saveexec_b64 s[16:17], s[16:17]
	v_mov_b32_e32 v181, v161
	v_lshl_add_u64 v[176:177], v[140:141], 0, v[180:181]
	s_or_b64 exec, exec, s[16:17]
	v_xor_b32_e32 v147, 0xd0, v143
	v_lshl_add_u32 v147, v147, 2, 0
	v_add_u32_e32 v147, 0x20000, v147
	ds_read_b32 v147, v147
	v_lshlrev_b64 v[176:177], 8, v[176:177]
	v_lshl_add_u64 v[176:177], v[178:179], 0, v[176:177]
	global_store_dwordx4 v[176:177], v[136:139], off
	s_waitcnt lgkmcnt(0)
	v_add_f32_e32 v147, v214, v147
	v_fmamk_f32 v147, v147, 0x3c800000, v205
	v_mul_f32_e32 v149, 0x4b800000, v147
	v_cmp_gt_f32_e32 vcc, s84, v147
	s_nop 1
	v_cndmask_b32_e32 v147, v147, v149, vcc
	v_rsq_f32_e32 v147, v147
	s_nop 0
	v_mul_f32_e32 v136, 0x45800000, v147
	v_cndmask_b32_e32 v160, v147, v136, vcc
	v_pk_mul_f32 v[136:137], v[44:45], v[160:161] op_sel_hi:[1,0]
	v_pk_mul_f32 v[138:139], v[46:47], v[160:161] op_sel_hi:[1,0]
	v_pk_mul_f32 v[180:181], v[40:41], v[160:161] op_sel_hi:[1,0]
	v_pk_mul_f32 v[176:177], v[42:43], v[160:161] op_sel_hi:[1,0]
	v_pk_mul_f32 v[138:139], v[134:135], v[138:139]
	v_pk_mul_f32 v[136:137], v[132:133], v[136:137]
	v_pk_mul_f32 v[176:177], v[130:131], v[176:177]
	s_and_b64 vcc, exec, s[14:15]
	v_pk_mul_f32 v[180:181], v[128:129], v[180:181]
	s_cbranch_vccnz .LBB0_957
	v_cndmask_b32_e64 v147, v213, v145, s[0:1]
	v_lshlrev_b32_e32 v147, 6, v147
	v_and_b32_e32 v160, 0xfc0, v147
	v_lshl_add_u64 v[182:183], s[46:47], 0, v[160:161]
	v_mov_b32_e32 v175, v161
	v_lshl_add_u64 v[194:195], v[182:183], 0, v[174:175]
	v_add_co_u32_e32 v182, vcc, 0x1000, v194
	v_lshl_add_u64 v[186:187], v[194:195], 0, s[90:91]
	s_nop 0
	v_addc_co_u32_e32 v183, vcc, 0, v195, vcc
	global_load_dwordx4 v[182:185], v[182:183], off
	s_nop 0
	global_load_dwordx4 v[186:189], v[186:187], off offset:16
	s_nop 0
	global_load_dwordx4 v[190:193], v[194:195], off
	s_nop 0
	global_load_dwordx4 v[194:197], v[194:195], off offset:16
	ds_bpermute_b32 v198, v207, v136
	ds_bpermute_b32 v214, v207, v180
	ds_bpermute_b32 v199, v207, v137
	ds_bpermute_b32 v216, v207, v138
	ds_bpermute_b32 v217, v207, v139
	ds_bpermute_b32 v218, v207, v176
	ds_bpermute_b32 v219, v207, v177
	ds_bpermute_b32 v215, v207, v181
	s_waitcnt vmcnt(2) lgkmcnt(1)
	v_pk_mul_f32 v[188:189], v[188:189], v[218:219]
	v_pk_mul_f32 v[184:185], v[184:185], v[216:217]
	v_pk_mul_f32 v[182:183], v[182:183], v[198:199]
	s_waitcnt lgkmcnt(0)
	v_pk_mul_f32 v[186:187], v[186:187], v[214:215]
	v_xor_b32_e32 v147, 0x80000000, v184
	v_xor_b32_e32 v149, 0x80000000, v185
	v_xor_b32_e32 v151, 0x80000000, v182
	v_xor_b32_e32 v160, 0x80000000, v183
	v_xor_b32_e32 v173, 0x80000000, v186
	v_xor_b32_e32 v175, 0x80000000, v187
	v_xor_b32_e32 v198, 0x80000000, v188
	v_xor_b32_e32 v199, 0x80000000, v189
	v_cndmask_b32_e64 v185, v185, v149, s[8:9]
	v_cndmask_b32_e64 v184, v184, v147, s[8:9]
	v_cndmask_b32_e64 v183, v183, v160, s[8:9]
	v_cndmask_b32_e64 v182, v182, v151, s[8:9]
	v_cndmask_b32_e64 v189, v189, v199, s[8:9]
	v_cndmask_b32_e64 v188, v188, v198, s[8:9]
	v_cndmask_b32_e64 v187, v187, v175, s[8:9]
	v_cndmask_b32_e64 v186, v186, v173, s[8:9]
	s_waitcnt vmcnt(1)
	v_pk_fma_f32 v[138:139], v[138:139], v[192:193], v[184:185]
	v_pk_fma_f32 v[136:137], v[136:137], v[190:191], v[182:183]
	s_waitcnt vmcnt(0)
	v_pk_fma_f32 v[180:181], v[180:181], v[194:195], v[186:187]
	v_pk_fma_f32 v[176:177], v[176:177], v[196:197], v[188:189]
.LBB0_957:
	v_cvt_pk_bf16_f32 v136, v136, v137
	v_cvt_pk_bf16_f32 v137, v138, v139
	v_cvt_pk_bf16_f32 v138, v180, v181
	s_nop 0
	v_cvt_pk_bf16_f32 v139, v176, v177
	s_and_saveexec_b64 s[16:17], s[12:13]
	s_xor_b64 s[12:13], exec, s[16:17]
	v_mov_b32_e32 v151, s87
	s_andn2_saveexec_b64 s[12:13], s[12:13]
	v_mov_b32_e32 v173, v161
	v_lshl_add_u64 v[150:151], v[140:141], 0, v[172:173]
	s_or_b64 exec, exec, s[12:13]
	v_xor_b32_e32 v147, 0xe0, v143
	v_lshl_add_u32 v147, v147, 2, 0
	v_add_u32_e32 v147, 0x20000, v147
	ds_read_b32 v147, v147
	v_lshlrev_b64 v[150:151], 8, v[150:151]
	v_lshl_add_u64 v[150:151], v[178:179], 0, v[150:151]
	global_store_dwordx4 v[150:151], v[136:139], off
	s_waitcnt lgkmcnt(0)
	v_add_f32_e32 v147, v212, v147
	v_fmamk_f32 v147, v147, 0x3c800000, v205
	v_mul_f32_e32 v149, 0x4b800000, v147
	v_cmp_gt_f32_e32 vcc, s84, v147
	s_nop 1
	v_cndmask_b32_e32 v147, v147, v149, vcc
	v_rsq_f32_e32 v147, v147
	s_nop 0
	v_mul_f32_e32 v136, 0x45800000, v147
	v_cndmask_b32_e32 v150, v147, v136, vcc
	v_pk_mul_f32 v[136:137], v[28:29], v[150:151] op_sel_hi:[1,0]
	v_pk_mul_f32 v[138:139], v[30:31], v[150:151] op_sel_hi:[1,0]
	v_pk_mul_f32 v[172:173], v[24:25], v[150:151] op_sel_hi:[1,0]
	v_pk_mul_f32 v[150:151], v[26:27], v[150:151] op_sel_hi:[1,0]
	v_pk_mul_f32 v[138:139], v[134:135], v[138:139]
	v_pk_mul_f32 v[136:137], v[132:133], v[136:137]
	v_pk_mul_f32 v[150:151], v[130:131], v[150:151]
	s_and_b64 vcc, exec, s[14:15]
	v_pk_mul_f32 v[172:173], v[128:129], v[172:173]
	s_cbranch_vccnz .LBB0_963
	v_cndmask_b32_e64 v147, v211, v145, s[0:1]
	v_lshlrev_b32_e32 v147, 6, v147
	v_and_b32_e32 v160, 0xfc0, v147
	v_lshl_add_u64 v[176:177], s[46:47], 0, v[160:161]
	v_mov_b32_e32 v175, v161
	v_lshl_add_u64 v[176:177], v[176:177], 0, v[174:175]
	v_add_co_u32_e32 v180, vcc, 0x1000, v176
	v_lshl_add_u64 v[184:185], v[176:177], 0, s[90:91]
	s_nop 0
	v_addc_co_u32_e32 v181, vcc, 0, v177, vcc
	global_load_dwordx4 v[180:183], v[180:181], off
	s_nop 0
	global_load_dwordx4 v[184:187], v[184:185], off offset:16
	s_nop 0
	global_load_dwordx4 v[188:191], v[176:177], off
	global_load_dwordx4 v[192:195], v[176:177], off offset:16
	ds_bpermute_b32 v176, v207, v136
	ds_bpermute_b32 v196, v207, v172
	ds_bpermute_b32 v177, v207, v137
	ds_bpermute_b32 v198, v207, v138
	ds_bpermute_b32 v199, v207, v139
	ds_bpermute_b32 v212, v207, v150
	ds_bpermute_b32 v213, v207, v151
	ds_bpermute_b32 v197, v207, v173
	s_waitcnt vmcnt(2) lgkmcnt(0)
	v_pk_mul_f32 v[184:185], v[184:185], v[196:197]
	v_pk_mul_f32 v[182:183], v[182:183], v[198:199]
	v_pk_mul_f32 v[176:177], v[180:181], v[176:177]
	v_pk_mul_f32 v[180:181], v[186:187], v[212:213]
	v_xor_b32_e32 v147, 0x80000000, v182
	v_xor_b32_e32 v149, 0x80000000, v183
	v_xor_b32_e32 v160, 0x80000000, v176
	v_xor_b32_e32 v175, 0x80000000, v177
	v_xor_b32_e32 v186, 0x80000000, v184
	v_xor_b32_e32 v187, 0x80000000, v185
	v_xor_b32_e32 v196, 0x80000000, v180
	v_xor_b32_e32 v197, 0x80000000, v181
	v_cndmask_b32_e64 v183, v183, v149, s[8:9]
	v_cndmask_b32_e64 v182, v182, v147, s[8:9]
	v_cndmask_b32_e64 v177, v177, v175, s[8:9]
	v_cndmask_b32_e64 v176, v176, v160, s[8:9]
	v_cndmask_b32_e64 v181, v181, v197, s[8:9]
	v_cndmask_b32_e64 v180, v180, v196, s[8:9]
	v_cndmask_b32_e64 v185, v185, v187, s[8:9]
	v_cndmask_b32_e64 v184, v184, v186, s[8:9]
	s_waitcnt vmcnt(1)
	v_pk_fma_f32 v[138:139], v[138:139], v[190:191], v[182:183]
	v_pk_fma_f32 v[136:137], v[136:137], v[188:189], v[176:177]
	s_waitcnt vmcnt(0)
	v_pk_fma_f32 v[172:173], v[172:173], v[192:193], v[184:185]
	v_pk_fma_f32 v[150:151], v[150:151], v[194:195], v[180:181]
.LBB0_963:
	v_cvt_pk_bf16_f32 v136, v136, v137
	v_cvt_pk_bf16_f32 v137, v138, v139
	v_cvt_pk_bf16_f32 v138, v172, v173
	s_nop 0
	v_cvt_pk_bf16_f32 v139, v150, v151
	s_and_saveexec_b64 s[12:13], s[10:11]
	s_xor_b64 s[10:11], exec, s[12:13]
	v_mov_b32_e32 v147, s87
	s_andn2_saveexec_b64 s[10:11], s[10:11]
	v_mov_b32_e32 v149, v161
	v_lshl_add_u64 v[146:147], v[140:141], 0, v[148:149]
	s_or_b64 exec, exec, s[10:11]
	v_lshlrev_b64 v[146:147], 8, v[146:147]
	v_lshl_add_u64 v[146:147], v[178:179], 0, v[146:147]
	global_store_dwordx4 v[146:147], v[136:139], off
	s_nop 1
	v_xor_b32_e32 v136, 0xf0, v143
	v_lshl_add_u32 v136, v136, 2, 0
	v_add_u32_e32 v136, 0x20000, v136
	ds_read_b32 v136, v136
	s_waitcnt lgkmcnt(0)
	v_add_f32_e32 v136, v210, v136
	v_fmamk_f32 v136, v136, 0x3c800000, v205
	v_cmp_gt_f32_e32 vcc, s84, v136
	v_mul_f32_e32 v137, 0x4b800000, v136
	s_nop 0
	v_cndmask_b32_e32 v136, v136, v137, vcc
	v_rsq_f32_e32 v136, v136
	s_nop 0
	v_mul_f32_e32 v137, 0x45800000, v136
	v_cndmask_b32_e32 v136, v136, v137, vcc
	v_pk_mul_f32 v[138:139], v[12:13], v[136:137] op_sel_hi:[1,0]
	v_pk_mul_f32 v[146:147], v[14:15], v[136:137] op_sel_hi:[1,0]
	v_pk_mul_f32 v[132:133], v[132:133], v[138:139]
	v_pk_mul_f32 v[138:139], v[8:9], v[136:137] op_sel_hi:[1,0]
	v_pk_mul_f32 v[136:137], v[10:11], v[136:137] op_sel_hi:[1,0]
	v_pk_mul_f32 v[134:135], v[134:135], v[146:147]
	v_pk_mul_f32 v[136:137], v[130:131], v[136:137]
	v_pk_mul_f32 v[130:131], v[128:129], v[138:139]
	s_and_b64 vcc, exec, s[14:15]
	s_cbranch_vccnz .LBB0_969
	v_cndmask_b32_e64 v128, v209, v145, s[0:1]
	v_lshlrev_b32_e32 v128, 6, v128
	v_and_b32_e32 v160, 0xfc0, v128
	v_lshl_add_u64 v[128:129], s[46:47], 0, v[160:161]
	v_mov_b32_e32 v175, v161
	v_lshl_add_u64 v[128:129], v[128:129], 0, v[174:175]
	v_add_co_u32_e32 v138, vcc, 0x1000, v128
	ds_bpermute_b32 v150, v207, v134
	s_nop 0
	v_addc_co_u32_e32 v139, vcc, 0, v129, vcc
	global_load_dwordx4 v[146:149], v[138:139], off
	v_lshl_add_u64 v[138:139], v[128:129], 0, s[90:91]
	global_load_dwordx4 v[172:175], v[138:139], off offset:16
	global_load_dwordx4 v[180:183], v[128:129], off
	global_load_dwordx4 v[184:187], v[128:129], off offset:16
	ds_bpermute_b32 v128, v207, v132
	ds_bpermute_b32 v138, v207, v130
	ds_bpermute_b32 v129, v207, v133
	ds_bpermute_b32 v151, v207, v135
	ds_bpermute_b32 v176, v207, v136
	ds_bpermute_b32 v177, v207, v137
	ds_bpermute_b32 v139, v207, v131
	s_waitcnt vmcnt(2) lgkmcnt(0)
	v_pk_mul_f32 v[138:139], v[172:173], v[138:139]
	v_pk_mul_f32 v[148:149], v[148:149], v[150:151]
	v_pk_mul_f32 v[128:129], v[146:147], v[128:129]
	v_pk_mul_f32 v[146:147], v[174:175], v[176:177]
	v_xor_b32_e32 v143, 0x80000000, v148
	v_xor_b32_e32 v145, 0x80000000, v149
	v_xor_b32_e32 v150, 0x80000000, v128
	v_xor_b32_e32 v151, 0x80000000, v129
	v_xor_b32_e32 v160, 0x80000000, v138
	v_xor_b32_e32 v172, 0x80000000, v139
	v_xor_b32_e32 v173, 0x80000000, v146
	v_xor_b32_e32 v174, 0x80000000, v147
	v_cndmask_b32_e64 v149, v149, v145, s[8:9]
	v_cndmask_b32_e64 v148, v148, v143, s[8:9]
	v_cndmask_b32_e64 v129, v129, v151, s[8:9]
	v_cndmask_b32_e64 v128, v128, v150, s[8:9]
	v_cndmask_b32_e64 v147, v147, v174, s[8:9]
	v_cndmask_b32_e64 v146, v146, v173, s[8:9]
	v_cndmask_b32_e64 v139, v139, v172, s[8:9]
	v_cndmask_b32_e64 v138, v138, v160, s[8:9]
	s_waitcnt vmcnt(1)
	v_pk_fma_f32 v[134:135], v[134:135], v[182:183], v[148:149]
	v_pk_fma_f32 v[132:133], v[132:133], v[180:181], v[128:129]
	s_waitcnt vmcnt(0)
	v_pk_fma_f32 v[130:131], v[130:131], v[184:185], v[138:139]
	v_pk_fma_f32 v[136:137], v[136:137], v[186:187], v[146:147]

.LBB0_975:
	s_and_b64 vcc, exec, s[6:7]
	s_cbranch_vccz .LBB0_1010
	s_andn2_b64 vcc, exec, s[28:29]
	s_cbranch_vccnz .LBB0_1010
	v_mul_f32_e32 v130, v125, v125
	v_fmac_f32_e32 v130, v124, v124
	v_fmac_f32_e32 v130, v126, v126
	v_and_b32_e32 v129, 64, v206
	v_fmac_f32_e32 v130, v127, v127
	v_xor_b32_e32 v128, 16, v206
	v_add_u32_e32 v129, 64, v129
	v_fmac_f32_e32 v130, v120, v120
	v_cmp_lt_i32_e32 vcc, v128, v129
	v_fmac_f32_e32 v130, v121, v121
	v_fmac_f32_e32 v130, v122, v122
	v_cndmask_b32_e32 v128, v206, v128, vcc
	v_lshlrev_b32_e32 v128, 2, v128
	v_fmac_f32_e32 v130, v123, v123
	ds_bpermute_b32 v131, v128, v130
	v_xor_b32_e32 v132, 32, v206
	v_cmp_lt_i32_e32 vcc, v132, v129
	v_readlane_b32 s6, v254, 34
	v_mbcnt_lo_u32_b32 v136, -1, 0
	v_mbcnt_hi_u32_b32 v136, -1, v136
	s_nop 0
	v_cndmask_b32_e32 v129, v206, v132, vcc
	v_lshlrev_b32_e32 v176, 2, v129
	s_waitcnt lgkmcnt(0)
	v_add_f32_e32 v129, v130, v131
	ds_bpermute_b32 v130, v176, v129
	v_cmp_gt_u32_e32 vcc, 16, v136
	s_waitcnt lgkmcnt(0)
	v_add_f32_e32 v184, v129, v130
	v_lshl_add_u32 v129, v136, 2, s6
	s_and_saveexec_b64 s[6:7], vcc
	ds_write_b32 v129, v184
	s_or_b64 exec, exec, s[6:7]
	v_mul_f32_e32 v130, v109, v109
	v_fmac_f32_e32 v130, v108, v108
	v_fmac_f32_e32 v130, v110, v110
	v_fmac_f32_e32 v130, v111, v111
	v_fmac_f32_e32 v130, v104, v104
	v_fmac_f32_e32 v130, v105, v105
	v_fmac_f32_e32 v130, v106, v106
	v_fmac_f32_e32 v130, v107, v107
	ds_bpermute_b32 v131, v128, v130
	s_waitcnt lgkmcnt(0)
	v_add_f32_e32 v130, v130, v131
	ds_bpermute_b32 v131, v176, v130
	s_waitcnt lgkmcnt(0)
	v_add_f32_e32 v192, v130, v131
	s_and_saveexec_b64 s[6:7], vcc
	ds_write_b32 v129, v192 offset:64
	s_or_b64 exec, exec, s[6:7]
	v_mul_f32_e32 v130, v93, v93
	v_fmac_f32_e32 v130, v92, v92
	v_fmac_f32_e32 v130, v94, v94
	v_fmac_f32_e32 v130, v95, v95
	v_fmac_f32_e32 v130, v88, v88
	v_fmac_f32_e32 v130, v89, v89
	v_fmac_f32_e32 v130, v90, v90
	v_fmac_f32_e32 v130, v91, v91
	ds_bpermute_b32 v131, v128, v130
	s_waitcnt lgkmcnt(0)
	v_add_f32_e32 v130, v130, v131
	ds_bpermute_b32 v131, v176, v130
	s_waitcnt lgkmcnt(0)
	v_add_f32_e32 v189, v130, v131
	s_and_saveexec_b64 s[6:7], vcc
	ds_write_b32 v129, v189 offset:128
	s_or_b64 exec, exec, s[6:7]
	v_mul_f32_e32 v130, v77, v77
	v_fmac_f32_e32 v130, v76, v76
	v_fmac_f32_e32 v130, v78, v78
	v_fmac_f32_e32 v130, v79, v79
	v_fmac_f32_e32 v130, v72, v72
	v_fmac_f32_e32 v130, v73, v73
	v_fmac_f32_e32 v130, v74, v74
	v_fmac_f32_e32 v130, v75, v75
	ds_bpermute_b32 v131, v128, v130
	s_waitcnt lgkmcnt(0)
	v_add_f32_e32 v130, v130, v131
	ds_bpermute_b32 v131, v176, v130
	s_waitcnt lgkmcnt(0)
	v_add_f32_e32 v187, v130, v131
	s_and_saveexec_b64 s[6:7], vcc
	ds_write_b32 v129, v187 offset:192
	s_or_b64 exec, exec, s[6:7]
	v_mul_f32_e32 v130, v61, v61
	v_fmac_f32_e32 v130, v60, v60
	v_fmac_f32_e32 v130, v62, v62
	v_fmac_f32_e32 v130, v63, v63
	v_fmac_f32_e32 v130, v56, v56
	v_fmac_f32_e32 v130, v57, v57
	v_fmac_f32_e32 v130, v58, v58
	v_fmac_f32_e32 v130, v59, v59
	ds_bpermute_b32 v131, v128, v130
	s_waitcnt lgkmcnt(0)
	v_add_f32_e32 v130, v130, v131
	ds_bpermute_b32 v131, v176, v130
	s_waitcnt lgkmcnt(0)
	v_add_f32_e32 v185, v130, v131
	s_and_saveexec_b64 s[6:7], vcc
	ds_write_b32 v129, v185 offset:256
	s_or_b64 exec, exec, s[6:7]
	v_mul_f32_e32 v130, v45, v45
	v_fmac_f32_e32 v130, v44, v44
	v_fmac_f32_e32 v130, v46, v46
	v_fmac_f32_e32 v130, v47, v47
	v_fmac_f32_e32 v130, v40, v40
	v_fmac_f32_e32 v130, v41, v41
	v_fmac_f32_e32 v130, v42, v42
	v_fmac_f32_e32 v130, v43, v43
	ds_bpermute_b32 v131, v128, v130
	s_waitcnt lgkmcnt(0)
	v_add_f32_e32 v130, v130, v131
	ds_bpermute_b32 v131, v176, v130
	s_waitcnt lgkmcnt(0)
	v_add_f32_e32 v182, v130, v131
	s_and_saveexec_b64 s[6:7], vcc
	ds_write_b32 v129, v182 offset:320
	s_or_b64 exec, exec, s[6:7]
	v_mul_f32_e32 v130, v29, v29
	v_fmac_f32_e32 v130, v28, v28
	v_fmac_f32_e32 v130, v30, v30
	v_fmac_f32_e32 v130, v31, v31
	v_fmac_f32_e32 v130, v24, v24
	v_fmac_f32_e32 v130, v25, v25
	v_fmac_f32_e32 v130, v26, v26
	v_fmac_f32_e32 v130, v27, v27
	ds_bpermute_b32 v131, v128, v130
	s_waitcnt lgkmcnt(0)
	v_add_f32_e32 v130, v130, v131
	ds_bpermute_b32 v131, v176, v130
	s_waitcnt lgkmcnt(0)
	v_add_f32_e32 v180, v130, v131
	s_and_saveexec_b64 s[6:7], vcc
	ds_write_b32 v129, v180 offset:384
	s_or_b64 exec, exec, s[6:7]
	v_mul_f32_e32 v130, v13, v13
	v_fmac_f32_e32 v130, v12, v12
	v_fmac_f32_e32 v130, v14, v14
	v_fmac_f32_e32 v130, v15, v15
	v_fmac_f32_e32 v130, v8, v8
	v_fmac_f32_e32 v130, v9, v9
	v_fmac_f32_e32 v130, v10, v10
	v_fmac_f32_e32 v130, v11, v11
	ds_bpermute_b32 v131, v128, v130
	s_waitcnt lgkmcnt(0)
	v_add_f32_e32 v130, v130, v131
	ds_bpermute_b32 v131, v176, v130
	s_waitcnt lgkmcnt(0)
	v_add_f32_e32 v177, v130, v131
	s_and_saveexec_b64 s[6:7], vcc
	ds_write_b32 v129, v177 offset:448
	s_or_b64 exec, exec, s[6:7]
	v_mul_f32_e32 v129, v117, v117
	v_fmac_f32_e32 v129, v116, v116
	v_fmac_f32_e32 v129, v118, v118
	v_fmac_f32_e32 v129, v119, v119
	v_fmac_f32_e32 v129, v112, v112
	v_fmac_f32_e32 v129, v113, v113
	v_fmac_f32_e32 v129, v114, v114
	v_fmac_f32_e32 v129, v115, v115
	ds_bpermute_b32 v130, v128, v129
	v_readlane_b32 s6, v254, 38
	s_waitcnt lgkmcnt(0)
	v_add_f32_e32 v129, v129, v130
	ds_bpermute_b32 v130, v176, v129
	s_waitcnt lgkmcnt(0)
	v_add_f32_e32 v194, v129, v130
	v_lshl_add_u32 v129, v136, 2, s6
	s_and_saveexec_b64 s[6:7], vcc
	ds_write_b32 v129, v194
	s_or_b64 exec, exec, s[6:7]
	v_mul_f32_e32 v130, v101, v101
	v_fmac_f32_e32 v130, v100, v100
	v_fmac_f32_e32 v130, v102, v102
	v_fmac_f32_e32 v130, v103, v103
	v_fmac_f32_e32 v130, v96, v96
	v_fmac_f32_e32 v130, v97, v97
	v_fmac_f32_e32 v130, v98, v98
	v_fmac_f32_e32 v130, v99, v99
	ds_bpermute_b32 v131, v128, v130
	s_waitcnt lgkmcnt(0)
	v_add_f32_e32 v130, v130, v131
	ds_bpermute_b32 v131, v176, v130
	s_waitcnt lgkmcnt(0)
	v_add_f32_e32 v193, v130, v131
	s_and_saveexec_b64 s[6:7], vcc
	ds_write_b32 v129, v193 offset:64
	s_or_b64 exec, exec, s[6:7]
	v_mul_f32_e32 v130, v85, v85
	v_fmac_f32_e32 v130, v84, v84
	v_fmac_f32_e32 v130, v86, v86
	v_fmac_f32_e32 v130, v87, v87
	v_fmac_f32_e32 v130, v80, v80
	v_fmac_f32_e32 v130, v81, v81
	v_fmac_f32_e32 v130, v82, v82
	v_fmac_f32_e32 v130, v83, v83
	ds_bpermute_b32 v131, v128, v130
	s_waitcnt lgkmcnt(0)
	v_add_f32_e32 v130, v130, v131
	ds_bpermute_b32 v131, v176, v130
	s_waitcnt lgkmcnt(0)
	v_add_f32_e32 v190, v130, v131
	s_and_saveexec_b64 s[6:7], vcc
	ds_write_b32 v129, v190 offset:128
	s_or_b64 exec, exec, s[6:7]
	v_mul_f32_e32 v130, v69, v69
	v_fmac_f32_e32 v130, v68, v68
	v_fmac_f32_e32 v130, v70, v70
	v_fmac_f32_e32 v130, v71, v71
	v_fmac_f32_e32 v130, v64, v64
	v_fmac_f32_e32 v130, v65, v65
	v_fmac_f32_e32 v130, v66, v66
	v_fmac_f32_e32 v130, v67, v67
	ds_bpermute_b32 v131, v128, v130
	s_waitcnt lgkmcnt(0)
	v_add_f32_e32 v130, v130, v131
	ds_bpermute_b32 v131, v176, v130
	s_waitcnt lgkmcnt(0)
	v_add_f32_e32 v188, v130, v131
	s_and_saveexec_b64 s[6:7], vcc
	ds_write_b32 v129, v188 offset:192
	s_or_b64 exec, exec, s[6:7]
	v_mul_f32_e32 v130, v53, v53
	v_fmac_f32_e32 v130, v52, v52
	v_fmac_f32_e32 v130, v54, v54
	v_fmac_f32_e32 v130, v55, v55
	v_fmac_f32_e32 v130, v48, v48
	v_fmac_f32_e32 v130, v49, v49
	v_fmac_f32_e32 v130, v50, v50
	v_fmac_f32_e32 v130, v51, v51
	ds_bpermute_b32 v131, v128, v130
	s_waitcnt lgkmcnt(0)
	v_add_f32_e32 v130, v130, v131
	ds_bpermute_b32 v131, v176, v130
	s_waitcnt lgkmcnt(0)
	v_add_f32_e32 v186, v130, v131
	s_and_saveexec_b64 s[6:7], vcc
	ds_write_b32 v129, v186 offset:256
	s_or_b64 exec, exec, s[6:7]
	v_mul_f32_e32 v130, v37, v37
	v_fmac_f32_e32 v130, v36, v36
	v_fmac_f32_e32 v130, v38, v38
	v_fmac_f32_e32 v130, v39, v39
	v_fmac_f32_e32 v130, v32, v32
	v_fmac_f32_e32 v130, v33, v33
	v_fmac_f32_e32 v130, v34, v34
	v_fmac_f32_e32 v130, v35, v35
	ds_bpermute_b32 v131, v128, v130
	s_waitcnt lgkmcnt(0)
	v_add_f32_e32 v130, v130, v131
	ds_bpermute_b32 v131, v176, v130
	s_waitcnt lgkmcnt(0)
	v_add_f32_e32 v183, v130, v131
	s_and_saveexec_b64 s[6:7], vcc
	ds_write_b32 v129, v183 offset:320
	s_or_b64 exec, exec, s[6:7]
	v_mul_f32_e32 v130, v21, v21
	v_fmac_f32_e32 v130, v20, v20
	v_fmac_f32_e32 v130, v22, v22
	v_fmac_f32_e32 v130, v23, v23
	v_fmac_f32_e32 v130, v16, v16
	v_fmac_f32_e32 v130, v17, v17
	v_fmac_f32_e32 v130, v18, v18
	v_fmac_f32_e32 v130, v19, v19
	ds_bpermute_b32 v131, v128, v130
	s_waitcnt lgkmcnt(0)
	v_add_f32_e32 v130, v130, v131
	ds_bpermute_b32 v131, v176, v130
	s_waitcnt lgkmcnt(0)
	v_add_f32_e32 v181, v130, v131
	s_and_saveexec_b64 s[6:7], vcc
	ds_write_b32 v129, v181 offset:384
	s_or_b64 exec, exec, s[6:7]
	v_mul_f32_e32 v130, v5, v5
	v_fmac_f32_e32 v130, v4, v4
	v_fmac_f32_e32 v130, v6, v6
	v_fmac_f32_e32 v130, v7, v7
	v_fmac_f32_e32 v130, v0, v0
	v_fmac_f32_e32 v130, v1, v1
	v_fmac_f32_e32 v130, v2, v2
	v_fmac_f32_e32 v130, v3, v3
	ds_bpermute_b32 v128, v128, v130
	s_waitcnt lgkmcnt(0)
	v_add_f32_e32 v128, v130, v128
	ds_bpermute_b32 v130, v176, v128
	s_waitcnt lgkmcnt(0)
	v_add_f32_e32 v178, v128, v130
	s_and_saveexec_b64 s[6:7], vcc
	ds_write_b32 v129, v178 offset:448
	s_or_b64 exec, exec, s[6:7]
	v_and_b32_e32 v179, 15, v136
	v_ashrrev_i32_e32 v138, 1, v136
	v_and_b32_e32 v136, 32, v136
	v_and_b32_e32 v174, -8, v138
	v_readlane_b32 s6, v254, 30
	v_cmp_eq_u32_e32 vcc, 0, v136
	v_or_b32_e32 v136, s68, v179
	v_ashrrev_i32_e32 v175, 31, v174
	v_readlane_b32 s7, v254, 31
	v_add_u32_e32 v172, s81, v136
	v_lshrrev_b32_e32 v191, 6, v172
	v_lshl_add_u64 v[132:133], v[174:175], 2, s[6:7]
	s_waitcnt vmcnt(0) lgkmcnt(0)
	s_barrier
	global_load_dwordx4 v[128:131], v[132:133], off offset:16
	s_nop 0
	global_load_dwordx4 v[132:135], v[132:133], off
	v_cndmask_b32_e64 v136, v179, v191, s[0:1]
	v_lshlrev_b32_e32 v136, 6, v136
	v_and_b32_e32 v160, 0xfc0, v136
	v_lshlrev_b32_e32 v138, 2, v138
	v_lshl_add_u64 v[136:137], s[46:47], 0, v[160:161]
	v_and_b32_e32 v160, 32, v138
	v_lshl_add_u64 v[144:145], v[136:137], 0, v[160:161]
	global_load_dwordx4 v[136:139], v[144:145], off offset:16
	global_load_dwordx4 v[140:143], v[144:145], off
	v_lshl_add_u64 v[146:147], v[144:145], 0, s[90:91]
	v_add_co_u32_e64 v144, s[6:7], s85, v144
	v_ashrrev_i32_e32 v173, 31, v172
	s_nop 0
	v_addc_co_u32_e64 v145, s[6:7], 0, v145, s[6:7]
	global_load_dwordx4 v[148:151], v[144:145], off
	s_nop 0
	global_load_dwordx4 v[144:147], v[146:147], off offset:16
	v_readlane_b32 s6, v254, 33
	v_lshlrev_b64 v[196:197], 10, v[172:173]
	s_movk_i32 s10, 0x100
	v_mov_b32_e32 v173, s6
	v_bitop3_b32 v195, v179, s10, v173 bitop3:0x36
	v_lshl_add_u32 v195, v195, 2, s26
	ds_read_b32 v195, v195
	v_lshlrev_b64 v[174:175], 1, v[174:175]
	s_waitcnt lgkmcnt(0)
	v_add_f32_e32 v184, v184, v195
	v_fmamk_f32 v184, v184, 0x3c800000, v205
	v_cmp_gt_f32_e64 s[6:7], s84, v184
	v_mul_f32_e32 v195, 0x4b800000, v184
	s_nop 0
	v_cndmask_b32_e64 v184, v184, v195, s[6:7]
	v_rsq_f32_e32 v184, v184
	s_nop 0
	v_mul_f32_e32 v195, 0x45800000, v184
	v_cndmask_b32_e64 v184, v184, v195, s[6:7]
	v_pk_mul_f32 v[124:125], v[124:125], v[184:185] op_sel_hi:[1,0]
	v_pk_mul_f32 v[126:127], v[126:127], v[184:185] op_sel_hi:[1,0]
	v_pk_mul_f32 v[120:121], v[120:121], v[184:185] op_sel_hi:[1,0]
	v_pk_mul_f32 v[122:123], v[122:123], v[184:185] op_sel_hi:[1,0]
	s_lshl_b32 s6, s94, 8
	v_readlane_b32 s7, v254, 13
	s_or_b32 s6, s6, s7
	s_ashr_i32 s7, s6, 31
	s_lshl_b64 s[8:9], s[6:7], 1
	v_readlane_b32 s6, v254, 37
	s_waitcnt vmcnt(5)
	v_pk_mul_f32 v[122:123], v[130:131], v[122:123]
	s_waitcnt vmcnt(4)
	v_pk_mul_f32 v[124:125], v[132:133], v[124:125]
	v_pk_mul_f32 v[126:127], v[134:135], v[126:127]
	ds_bpermute_b32 v198, v176, v124
	ds_bpermute_b32 v199, v176, v125
	ds_bpermute_b32 v210, v176, v126
	ds_bpermute_b32 v211, v176, v127
	v_pk_mul_f32 v[120:121], v[128:129], v[120:121]
	ds_bpermute_b32 v208, v176, v120
	ds_bpermute_b32 v209, v176, v121
	ds_bpermute_b32 v212, v176, v122
	ds_bpermute_b32 v213, v176, v123
	s_waitcnt vmcnt(1) lgkmcnt(6)
	v_pk_mul_f32 v[198:199], v[148:149], v[198:199]
	s_waitcnt lgkmcnt(4)
	v_pk_mul_f32 v[210:211], v[150:151], v[210:211]
	v_xor_b32_e32 v184, 0x80000000, v198
	v_xor_b32_e32 v195, 0x80000000, v199
	v_xor_b32_e32 v207, 0x80000000, v210
	v_xor_b32_e32 v214, 0x80000000, v211
	v_cndmask_b32_e32 v199, v199, v195, vcc
	v_cndmask_b32_e32 v198, v198, v184, vcc
	v_cndmask_b32_e32 v211, v211, v214, vcc
	v_cndmask_b32_e32 v210, v210, v207, vcc
	v_pk_fma_f32 v[124:125], v[140:141], v[124:125], v[198:199]
	s_waitcnt vmcnt(0) lgkmcnt(0)
	v_pk_mul_f32 v[198:199], v[146:147], v[212:213]
	v_pk_mul_f32 v[208:209], v[144:145], v[208:209]
	v_pk_fma_f32 v[126:127], v[142:143], v[126:127], v[210:211]
	v_xor_b32_e32 v184, 0x80000000, v208
	v_xor_b32_e32 v195, 0x80000000, v209
	v_xor_b32_e32 v207, 0x80000000, v198
	v_xor_b32_e32 v210, 0x80000000, v199
	v_cndmask_b32_e32 v199, v199, v210, vcc
	v_cndmask_b32_e32 v198, v198, v207, vcc
	v_cndmask_b32_e32 v209, v209, v195, vcc
	v_cndmask_b32_e32 v208, v208, v184, vcc
	v_pk_mul_f32 v[124:125], v[124:125], s[92:93] op_sel_hi:[1,0]
	v_pk_fma_f32 v[120:121], v[136:137], v[120:121], v[208:209]
	v_pk_fma_f32 v[122:123], v[138:139], v[122:123], v[198:199]
	v_mov_b32_e32 v184, s6
	v_pk_mul_f32 v[198:199], v[122:123], s[92:93] op_sel_hi:[1,0]
	v_pk_mul_f32 v[122:123], v[120:121], s[92:93] op_sel_hi:[1,0]
	v_cvt_pk_bf16_f32 v120, v124, v125
	v_lshl_add_u64 v[124:125], s[44:45], 0, v[196:197]
	v_lshl_add_u64 v[124:125], v[124:125], 0, s[8:9]
	v_lshl_add_u64 v[124:125], v[124:125], 0, s[40:41]
	v_lshl_add_u64 v[124:125], v[124:125], 0, v[174:175]
	v_pk_mul_f32 v[126:127], v[126:127], s[92:93] op_sel_hi:[1,0]
	s_nop 0
	v_cvt_pk_bf16_f32 v121, v126, v127
	v_cvt_pk_bf16_f32 v122, v122, v123
	v_cvt_pk_bf16_f32 v123, v198, v199
	global_store_dwordx4 v[124:125], v[120:123], off
	s_nop 1
	v_bitop3_b32 v120, v179, s10, v184 bitop3:0x36
	v_lshl_add_u32 v120, v120, 2, s26
	ds_read_b32 v120, v120
	s_movk_i32 s10, 0x110
	s_waitcnt lgkmcnt(0)
	v_add_f32_e32 v120, v194, v120
	v_fmamk_f32 v120, v120, 0x3c800000, v205
	v_cmp_gt_f32_e64 s[6:7], s84, v120
	v_mul_f32_e32 v121, 0x4b800000, v120
	s_nop 0
	v_cndmask_b32_e64 v120, v120, v121, s[6:7]
	v_rsq_f32_e32 v120, v120
	s_nop 0
	v_mul_f32_e32 v121, 0x45800000, v120
	v_cndmask_b32_e64 v120, v120, v121, s[6:7]
	v_pk_mul_f32 v[116:117], v[116:117], v[120:121] op_sel_hi:[1,0]
	v_pk_mul_f32 v[118:119], v[118:119], v[120:121] op_sel_hi:[1,0]
	v_pk_mul_f32 v[116:117], v[132:133], v[116:117]
	v_pk_mul_f32 v[118:119], v[134:135], v[118:119]
	v_pk_mul_f32 v[112:113], v[112:113], v[120:121] op_sel_hi:[1,0]
	v_pk_mul_f32 v[114:115], v[114:115], v[120:121] op_sel_hi:[1,0]
	ds_bpermute_b32 v120, v176, v116
	ds_bpermute_b32 v121, v176, v117
	ds_bpermute_b32 v126, v176, v118
	ds_bpermute_b32 v127, v176, v119
	v_pk_mul_f32 v[114:115], v[130:131], v[114:115]
	v_pk_mul_f32 v[112:113], v[128:129], v[112:113]
	ds_bpermute_b32 v122, v176, v112
	ds_bpermute_b32 v123, v176, v113
	ds_bpermute_b32 v194, v176, v114
	ds_bpermute_b32 v195, v176, v115
	s_waitcnt lgkmcnt(6)
	v_pk_mul_f32 v[120:121], v[148:149], v[120:121]
	s_waitcnt lgkmcnt(4)
	v_pk_mul_f32 v[126:127], v[150:151], v[126:127]
	v_xor_b32_e32 v148, 0x80000000, v120
	v_xor_b32_e32 v149, 0x80000000, v121
	v_xor_b32_e32 v150, 0x80000000, v126
	v_xor_b32_e32 v151, 0x80000000, v127
	v_cndmask_b32_e32 v121, v121, v149, vcc
	v_cndmask_b32_e32 v120, v120, v148, vcc
	v_cndmask_b32_e32 v127, v127, v151, vcc
	v_cndmask_b32_e32 v126, v126, v150, vcc
	v_pk_fma_f32 v[116:117], v[140:141], v[116:117], v[120:121]
	s_waitcnt lgkmcnt(0)
	v_pk_mul_f32 v[120:121], v[146:147], v[194:195]
	v_pk_mul_f32 v[122:123], v[144:145], v[122:123]
	v_pk_fma_f32 v[118:119], v[142:143], v[118:119], v[126:127]
	v_xor_b32_e32 v126, 0x80000000, v122
	v_xor_b32_e32 v127, 0x80000000, v123
	v_xor_b32_e32 v140, 0x80000000, v120
	v_xor_b32_e32 v141, 0x80000000, v121
	v_cndmask_b32_e32 v121, v121, v141, vcc
	v_cndmask_b32_e32 v120, v120, v140, vcc
	v_cndmask_b32_e32 v123, v123, v127, vcc
	v_cndmask_b32_e32 v122, v122, v126, vcc
	v_pk_fma_f32 v[112:113], v[136:137], v[112:113], v[122:123]
	v_pk_fma_f32 v[114:115], v[138:139], v[114:115], v[120:121]
	v_pk_mul_f32 v[116:117], v[116:117], s[92:93] op_sel_hi:[1,0]
	v_pk_mul_f32 v[120:121], v[114:115], s[92:93] op_sel_hi:[1,0]
	v_pk_mul_f32 v[114:115], v[112:113], s[92:93] op_sel_hi:[1,0]
	v_cvt_pk_bf16_f32 v112, v116, v117
	v_or_b32_e32 v136, 16, v172
	v_pk_mul_f32 v[118:119], v[118:119], s[92:93] op_sel_hi:[1,0]
	v_bitop3_b32 v138, v179, s10, v173 bitop3:0x36
	v_cvt_pk_bf16_f32 v113, v118, v119
	v_cvt_pk_bf16_f32 v114, v114, v115
	v_cvt_pk_bf16_f32 v115, v120, v121
	global_store_dwordx4 v[124:125], v[112:115], off offset:256
	v_lshl_add_u32 v138, v138, 2, s26
	v_ashrrev_i32_e32 v137, 31, v136
	v_cndmask_b32_e64 v112, v136, v191, s[0:1]
	v_lshlrev_b32_e32 v112, 6, v112
	v_and_b32_e32 v112, 0xfc0, v112
	v_mov_b32_e32 v113, v161
	v_lshl_add_u64 v[112:113], s[46:47], 0, v[112:113]
	v_lshl_add_u64 v[120:121], v[112:113], 0, v[160:161]
	global_load_dwordx4 v[112:115], v[120:121], off offset:16
	global_load_dwordx4 v[116:119], v[120:121], off
	v_lshl_add_u64 v[122:123], v[120:121], 0, s[90:91]
	v_add_co_u32_e64 v120, s[6:7], s85, v120
	v_lshlrev_b64 v[136:137], 10, v[136:137]
	s_nop 0
	v_addc_co_u32_e64 v121, s[6:7], 0, v121, s[6:7]
	global_load_dwordx4 v[124:127], v[120:121], off
	s_nop 0
	global_load_dwordx4 v[120:123], v[122:123], off offset:16
	ds_read_b32 v138, v138
	s_waitcnt lgkmcnt(0)
	v_add_f32_e32 v138, v192, v138
	v_fmamk_f32 v138, v138, 0x3c800000, v205
	v_cmp_gt_f32_e64 s[6:7], s84, v138
	v_mul_f32_e32 v139, 0x4b800000, v138
	s_nop 0
	v_cndmask_b32_e64 v138, v138, v139, s[6:7]
	v_rsq_f32_e32 v138, v138
	s_nop 0
	v_mul_f32_e32 v139, 0x45800000, v138
	v_cndmask_b32_e64 v138, v138, v139, s[6:7]
	v_pk_mul_f32 v[108:109], v[108:109], v[138:139] op_sel_hi:[1,0]
	v_pk_mul_f32 v[110:111], v[110:111], v[138:139] op_sel_hi:[1,0]
	v_pk_mul_f32 v[108:109], v[132:133], v[108:109]
	v_pk_mul_f32 v[110:111], v[134:135], v[110:111]
	v_pk_mul_f32 v[104:105], v[104:105], v[138:139] op_sel_hi:[1,0]
	v_pk_mul_f32 v[106:107], v[106:107], v[138:139] op_sel_hi:[1,0]
	ds_bpermute_b32 v138, v176, v108
	ds_bpermute_b32 v139, v176, v109
	ds_bpermute_b32 v142, v176, v110
	ds_bpermute_b32 v143, v176, v111
	v_pk_mul_f32 v[106:107], v[130:131], v[106:107]
	v_pk_mul_f32 v[104:105], v[128:129], v[104:105]
	ds_bpermute_b32 v140, v176, v104
	ds_bpermute_b32 v141, v176, v105
	ds_bpermute_b32 v144, v176, v106
	ds_bpermute_b32 v145, v176, v107
	s_waitcnt vmcnt(1) lgkmcnt(6)
	v_pk_mul_f32 v[138:139], v[124:125], v[138:139]
	s_waitcnt lgkmcnt(4)
	v_pk_mul_f32 v[142:143], v[126:127], v[142:143]
	v_xor_b32_e32 v146, 0x80000000, v138
	v_xor_b32_e32 v147, 0x80000000, v139
	v_xor_b32_e32 v148, 0x80000000, v142
	v_xor_b32_e32 v149, 0x80000000, v143
	v_cndmask_b32_e32 v139, v139, v147, vcc
	v_cndmask_b32_e32 v138, v138, v146, vcc
	v_cndmask_b32_e32 v143, v143, v149, vcc
	v_cndmask_b32_e32 v142, v142, v148, vcc
	v_pk_fma_f32 v[108:109], v[116:117], v[108:109], v[138:139]
	s_waitcnt vmcnt(0) lgkmcnt(0)
	v_pk_mul_f32 v[138:139], v[122:123], v[144:145]
	v_pk_mul_f32 v[140:141], v[120:121], v[140:141]
	v_pk_fma_f32 v[110:111], v[118:119], v[110:111], v[142:143]
	v_xor_b32_e32 v142, 0x80000000, v140
	v_xor_b32_e32 v143, 0x80000000, v141
	v_xor_b32_e32 v144, 0x80000000, v138
	v_xor_b32_e32 v145, 0x80000000, v139
	v_cndmask_b32_e32 v139, v139, v145, vcc
	v_cndmask_b32_e32 v138, v138, v144, vcc
	v_cndmask_b32_e32 v141, v141, v143, vcc
	v_cndmask_b32_e32 v140, v140, v142, vcc
	v_pk_mul_f32 v[108:109], v[108:109], s[92:93] op_sel_hi:[1,0]
	v_pk_fma_f32 v[104:105], v[112:113], v[104:105], v[140:141]
	v_pk_fma_f32 v[106:107], v[114:115], v[106:107], v[138:139]
	v_pk_mul_f32 v[110:111], v[110:111], s[92:93] op_sel_hi:[1,0]
	v_pk_mul_f32 v[138:139], v[106:107], s[92:93] op_sel_hi:[1,0]
	v_pk_mul_f32 v[106:107], v[104:105], s[92:93] op_sel_hi:[1,0]
	v_cvt_pk_bf16_f32 v104, v108, v109
	v_lshl_add_u64 v[108:109], s[44:45], 0, v[136:137]
	v_lshl_add_u64 v[108:109], v[108:109], 0, s[8:9]
	v_lshl_add_u64 v[108:109], v[108:109], 0, s[40:41]
	v_lshl_add_u64 v[108:109], v[108:109], 0, v[174:175]
	v_cvt_pk_bf16_f32 v105, v110, v111
	v_cvt_pk_bf16_f32 v106, v106, v107
	v_cvt_pk_bf16_f32 v107, v138, v139
	global_store_dwordx4 v[108:109], v[104:107], off
	s_nop 1
	v_bitop3_b32 v104, v179, s10, v184 bitop3:0x36
	v_lshl_add_u32 v104, v104, 2, s26
	ds_read_b32 v104, v104
	s_movk_i32 s10, 0x120
	s_waitcnt lgkmcnt(0)
	v_add_f32_e32 v104, v193, v104
	v_fmamk_f32 v104, v104, 0x3c800000, v205
	v_cmp_gt_f32_e64 s[6:7], s84, v104
	v_mul_f32_e32 v105, 0x4b800000, v104
	s_nop 0
	v_cndmask_b32_e64 v104, v104, v105, s[6:7]
	v_rsq_f32_e32 v104, v104
	s_nop 0
	v_mul_f32_e32 v105, 0x45800000, v104
	v_cndmask_b32_e64 v104, v104, v105, s[6:7]
	v_pk_mul_f32 v[100:101], v[100:101], v[104:105] op_sel_hi:[1,0]
	v_pk_mul_f32 v[102:103], v[102:103], v[104:105] op_sel_hi:[1,0]
	v_pk_mul_f32 v[100:101], v[132:133], v[100:101]
	v_pk_mul_f32 v[102:103], v[134:135], v[102:103]
	v_pk_mul_f32 v[96:97], v[96:97], v[104:105] op_sel_hi:[1,0]
	v_pk_mul_f32 v[98:99], v[98:99], v[104:105] op_sel_hi:[1,0]
	ds_bpermute_b32 v104, v176, v100
	ds_bpermute_b32 v105, v176, v101
	ds_bpermute_b32 v110, v176, v102
	ds_bpermute_b32 v111, v176, v103
	v_pk_mul_f32 v[98:99], v[130:131], v[98:99]
	v_pk_mul_f32 v[96:97], v[128:129], v[96:97]
	ds_bpermute_b32 v106, v176, v96
	ds_bpermute_b32 v107, v176, v97
	ds_bpermute_b32 v136, v176, v98
	ds_bpermute_b32 v137, v176, v99
	s_waitcnt lgkmcnt(6)
	v_pk_mul_f32 v[104:105], v[124:125], v[104:105]
	s_waitcnt lgkmcnt(4)
	v_pk_mul_f32 v[110:111], v[126:127], v[110:111]
	v_xor_b32_e32 v124, 0x80000000, v104
	v_xor_b32_e32 v125, 0x80000000, v105
	v_xor_b32_e32 v126, 0x80000000, v110
	v_xor_b32_e32 v127, 0x80000000, v111
	v_cndmask_b32_e32 v105, v105, v125, vcc
	v_cndmask_b32_e32 v104, v104, v124, vcc
	v_cndmask_b32_e32 v111, v111, v127, vcc
	v_cndmask_b32_e32 v110, v110, v126, vcc
	v_pk_fma_f32 v[100:101], v[116:117], v[100:101], v[104:105]
	s_waitcnt lgkmcnt(0)
	v_pk_mul_f32 v[104:105], v[122:123], v[136:137]
	v_pk_mul_f32 v[106:107], v[120:121], v[106:107]
	v_pk_fma_f32 v[102:103], v[118:119], v[102:103], v[110:111]
	v_xor_b32_e32 v110, 0x80000000, v106
	v_xor_b32_e32 v111, 0x80000000, v107
	v_xor_b32_e32 v116, 0x80000000, v104
	v_xor_b32_e32 v117, 0x80000000, v105
	v_cndmask_b32_e32 v105, v105, v117, vcc
	v_cndmask_b32_e32 v104, v104, v116, vcc
	v_cndmask_b32_e32 v107, v107, v111, vcc
	v_cndmask_b32_e32 v106, v106, v110, vcc
	v_pk_fma_f32 v[96:97], v[112:113], v[96:97], v[106:107]
	v_pk_fma_f32 v[98:99], v[114:115], v[98:99], v[104:105]
	v_pk_mul_f32 v[100:101], v[100:101], s[92:93] op_sel_hi:[1,0]
	v_pk_mul_f32 v[104:105], v[98:99], s[92:93] op_sel_hi:[1,0]
	v_pk_mul_f32 v[98:99], v[96:97], s[92:93] op_sel_hi:[1,0]
	v_cvt_pk_bf16_f32 v96, v100, v101
	v_or_b32_e32 v112, 32, v172
	v_pk_mul_f32 v[102:103], v[102:103], s[92:93] op_sel_hi:[1,0]
	v_bitop3_b32 v114, v179, s10, v173 bitop3:0x36
	v_cvt_pk_bf16_f32 v97, v102, v103
	v_cvt_pk_bf16_f32 v98, v98, v99
	v_cvt_pk_bf16_f32 v99, v104, v105
	global_store_dwordx4 v[108:109], v[96:99], off offset:256
	v_lshl_add_u32 v114, v114, 2, s26
	v_ashrrev_i32_e32 v113, 31, v112
	v_cndmask_b32_e64 v96, v112, v191, s[0:1]
	v_lshlrev_b32_e32 v96, 6, v96
	v_and_b32_e32 v96, 0xfc0, v96
	v_mov_b32_e32 v97, v161
	v_lshl_add_u64 v[96:97], s[46:47], 0, v[96:97]
	v_lshl_add_u64 v[104:105], v[96:97], 0, v[160:161]
	global_load_dwordx4 v[96:99], v[104:105], off offset:16
	global_load_dwordx4 v[100:103], v[104:105], off
	v_lshl_add_u64 v[106:107], v[104:105], 0, s[90:91]
	v_add_co_u32_e64 v104, s[6:7], s85, v104
	v_lshlrev_b64 v[112:113], 10, v[112:113]
	s_nop 0
	v_addc_co_u32_e64 v105, s[6:7], 0, v105, s[6:7]
	global_load_dwordx4 v[108:111], v[104:105], off
	s_nop 0
	global_load_dwordx4 v[104:107], v[106:107], off offset:16
	ds_read_b32 v114, v114
	s_waitcnt lgkmcnt(0)
	v_add_f32_e32 v114, v189, v114
	v_fmamk_f32 v114, v114, 0x3c800000, v205
	v_cmp_gt_f32_e64 s[6:7], s84, v114
	v_mul_f32_e32 v115, 0x4b800000, v114
	s_nop 0
	v_cndmask_b32_e64 v114, v114, v115, s[6:7]
	v_rsq_f32_e32 v114, v114
	s_nop 0
	v_mul_f32_e32 v115, 0x45800000, v114
	v_cndmask_b32_e64 v114, v114, v115, s[6:7]
	v_pk_mul_f32 v[92:93], v[92:93], v[114:115] op_sel_hi:[1,0]
	v_pk_mul_f32 v[94:95], v[94:95], v[114:115] op_sel_hi:[1,0]
	v_pk_mul_f32 v[92:93], v[132:133], v[92:93]
	v_pk_mul_f32 v[94:95], v[134:135], v[94:95]
	v_pk_mul_f32 v[88:89], v[88:89], v[114:115] op_sel_hi:[1,0]
	v_pk_mul_f32 v[90:91], v[90:91], v[114:115] op_sel_hi:[1,0]
	ds_bpermute_b32 v114, v176, v92
	ds_bpermute_b32 v115, v176, v93
	ds_bpermute_b32 v118, v176, v94
	ds_bpermute_b32 v119, v176, v95
	v_pk_mul_f32 v[90:91], v[130:131], v[90:91]
	v_pk_mul_f32 v[88:89], v[128:129], v[88:89]
	ds_bpermute_b32 v116, v176, v88
	ds_bpermute_b32 v117, v176, v89
	ds_bpermute_b32 v120, v176, v90
	ds_bpermute_b32 v121, v176, v91
	s_waitcnt vmcnt(1) lgkmcnt(6)
	v_pk_mul_f32 v[114:115], v[108:109], v[114:115]
	s_waitcnt lgkmcnt(4)
	v_pk_mul_f32 v[118:119], v[110:111], v[118:119]
	v_xor_b32_e32 v122, 0x80000000, v114
	v_xor_b32_e32 v123, 0x80000000, v115
	v_xor_b32_e32 v124, 0x80000000, v118
	v_xor_b32_e32 v125, 0x80000000, v119
	v_cndmask_b32_e32 v115, v115, v123, vcc
	v_cndmask_b32_e32 v114, v114, v122, vcc
	v_cndmask_b32_e32 v119, v119, v125, vcc
	v_cndmask_b32_e32 v118, v118, v124, vcc
	v_pk_fma_f32 v[92:93], v[100:101], v[92:93], v[114:115]
	s_waitcnt vmcnt(0) lgkmcnt(0)
	v_pk_mul_f32 v[114:115], v[106:107], v[120:121]
	v_pk_mul_f32 v[116:117], v[104:105], v[116:117]
	v_pk_fma_f32 v[94:95], v[102:103], v[94:95], v[118:119]
	v_xor_b32_e32 v118, 0x80000000, v116
	v_xor_b32_e32 v119, 0x80000000, v117
	v_xor_b32_e32 v120, 0x80000000, v114
	v_xor_b32_e32 v121, 0x80000000, v115
	v_cndmask_b32_e32 v115, v115, v121, vcc
	v_cndmask_b32_e32 v114, v114, v120, vcc
	v_cndmask_b32_e32 v117, v117, v119, vcc
	v_cndmask_b32_e32 v116, v116, v118, vcc
	v_pk_mul_f32 v[92:93], v[92:93], s[92:93] op_sel_hi:[1,0]
	v_pk_fma_f32 v[88:89], v[96:97], v[88:89], v[116:117]
	v_pk_fma_f32 v[90:91], v[98:99], v[90:91], v[114:115]
	v_pk_mul_f32 v[94:95], v[94:95], s[92:93] op_sel_hi:[1,0]
	v_pk_mul_f32 v[114:115], v[90:91], s[92:93] op_sel_hi:[1,0]
	v_pk_mul_f32 v[90:91], v[88:89], s[92:93] op_sel_hi:[1,0]
	v_cvt_pk_bf16_f32 v88, v92, v93
	v_lshl_add_u64 v[92:93], s[44:45], 0, v[112:113]
	v_lshl_add_u64 v[92:93], v[92:93], 0, s[8:9]
	v_lshl_add_u64 v[92:93], v[92:93], 0, s[40:41]
	v_lshl_add_u64 v[92:93], v[92:93], 0, v[174:175]
	v_cvt_pk_bf16_f32 v89, v94, v95
	v_cvt_pk_bf16_f32 v90, v90, v91
	v_cvt_pk_bf16_f32 v91, v114, v115
	global_store_dwordx4 v[92:93], v[88:91], off
	s_nop 1
	v_bitop3_b32 v88, v179, s10, v184 bitop3:0x36
	v_lshl_add_u32 v88, v88, 2, s26
	ds_read_b32 v88, v88
	s_movk_i32 s10, 0x130
	s_waitcnt lgkmcnt(0)
	v_add_f32_e32 v88, v190, v88
	v_fmamk_f32 v88, v88, 0x3c800000, v205
	v_cmp_gt_f32_e64 s[6:7], s84, v88
	v_mul_f32_e32 v89, 0x4b800000, v88
	s_nop 0
	v_cndmask_b32_e64 v88, v88, v89, s[6:7]
	v_rsq_f32_e32 v88, v88
	s_nop 0
	v_mul_f32_e32 v89, 0x45800000, v88
	v_cndmask_b32_e64 v88, v88, v89, s[6:7]
	v_pk_mul_f32 v[84:85], v[84:85], v[88:89] op_sel_hi:[1,0]
	v_pk_mul_f32 v[86:87], v[86:87], v[88:89] op_sel_hi:[1,0]
	v_pk_mul_f32 v[84:85], v[132:133], v[84:85]
	v_pk_mul_f32 v[86:87], v[134:135], v[86:87]
	v_pk_mul_f32 v[80:81], v[80:81], v[88:89] op_sel_hi:[1,0]
	v_pk_mul_f32 v[82:83], v[82:83], v[88:89] op_sel_hi:[1,0]
	ds_bpermute_b32 v88, v176, v84
	ds_bpermute_b32 v89, v176, v85
	ds_bpermute_b32 v94, v176, v86
	ds_bpermute_b32 v95, v176, v87
	v_pk_mul_f32 v[82:83], v[130:131], v[82:83]
	v_pk_mul_f32 v[80:81], v[128:129], v[80:81]
	ds_bpermute_b32 v90, v176, v80
	ds_bpermute_b32 v91, v176, v81
	ds_bpermute_b32 v112, v176, v82
	ds_bpermute_b32 v113, v176, v83
	s_waitcnt lgkmcnt(6)
	v_pk_mul_f32 v[88:89], v[108:109], v[88:89]
	s_waitcnt lgkmcnt(4)
	v_pk_mul_f32 v[94:95], v[110:111], v[94:95]
	v_xor_b32_e32 v108, 0x80000000, v88
	v_xor_b32_e32 v109, 0x80000000, v89
	v_xor_b32_e32 v110, 0x80000000, v94
	v_xor_b32_e32 v111, 0x80000000, v95
	v_cndmask_b32_e32 v89, v89, v109, vcc
	v_cndmask_b32_e32 v88, v88, v108, vcc
	v_cndmask_b32_e32 v95, v95, v111, vcc
	v_cndmask_b32_e32 v94, v94, v110, vcc
	v_pk_fma_f32 v[84:85], v[100:101], v[84:85], v[88:89]
	s_waitcnt lgkmcnt(0)
	v_pk_mul_f32 v[88:89], v[106:107], v[112:113]
	v_pk_mul_f32 v[90:91], v[104:105], v[90:91]
	v_pk_fma_f32 v[86:87], v[102:103], v[86:87], v[94:95]
	v_xor_b32_e32 v94, 0x80000000, v90
	v_xor_b32_e32 v95, 0x80000000, v91
	v_xor_b32_e32 v100, 0x80000000, v88
	v_xor_b32_e32 v101, 0x80000000, v89
	v_cndmask_b32_e32 v89, v89, v101, vcc
	v_cndmask_b32_e32 v88, v88, v100, vcc
	v_cndmask_b32_e32 v91, v91, v95, vcc
	v_cndmask_b32_e32 v90, v90, v94, vcc
	v_pk_fma_f32 v[80:81], v[96:97], v[80:81], v[90:91]
	v_pk_fma_f32 v[82:83], v[98:99], v[82:83], v[88:89]
	v_pk_mul_f32 v[84:85], v[84:85], s[92:93] op_sel_hi:[1,0]
	v_pk_mul_f32 v[88:89], v[82:83], s[92:93] op_sel_hi:[1,0]
	v_pk_mul_f32 v[82:83], v[80:81], s[92:93] op_sel_hi:[1,0]
	v_cvt_pk_bf16_f32 v80, v84, v85
	v_or_b32_e32 v96, 48, v172
	v_pk_mul_f32 v[86:87], v[86:87], s[92:93] op_sel_hi:[1,0]
	v_bitop3_b32 v98, v179, s10, v173 bitop3:0x36
	v_cvt_pk_bf16_f32 v81, v86, v87
	v_cvt_pk_bf16_f32 v82, v82, v83
	v_cvt_pk_bf16_f32 v83, v88, v89
	global_store_dwordx4 v[92:93], v[80:83], off offset:256
	v_lshl_add_u32 v98, v98, 2, s26
	v_ashrrev_i32_e32 v97, 31, v96
	v_cndmask_b32_e64 v80, v96, v191, s[0:1]
	v_lshlrev_b32_e32 v80, 6, v80
	v_and_b32_e32 v80, 0xfc0, v80
	v_mov_b32_e32 v81, v161
	v_lshl_add_u64 v[80:81], s[46:47], 0, v[80:81]
	v_lshl_add_u64 v[88:89], v[80:81], 0, v[160:161]
	global_load_dwordx4 v[80:83], v[88:89], off offset:16
	global_load_dwordx4 v[84:87], v[88:89], off
	v_lshl_add_u64 v[90:91], v[88:89], 0, s[90:91]
	v_add_co_u32_e64 v88, s[6:7], s85, v88
	v_lshlrev_b64 v[96:97], 10, v[96:97]
	s_nop 0
	v_addc_co_u32_e64 v89, s[6:7], 0, v89, s[6:7]
	global_load_dwordx4 v[92:95], v[88:89], off
	s_nop 0
	global_load_dwordx4 v[88:91], v[90:91], off offset:16
	ds_read_b32 v98, v98
	s_waitcnt lgkmcnt(0)
	v_add_f32_e32 v98, v187, v98
	v_fmamk_f32 v98, v98, 0x3c800000, v205
	v_cmp_gt_f32_e64 s[6:7], s84, v98
	v_mul_f32_e32 v99, 0x4b800000, v98
	s_nop 0
	v_cndmask_b32_e64 v98, v98, v99, s[6:7]
	v_rsq_f32_e32 v98, v98
	s_nop 0
	v_mul_f32_e32 v99, 0x45800000, v98
	v_cndmask_b32_e64 v98, v98, v99, s[6:7]
	v_pk_mul_f32 v[76:77], v[76:77], v[98:99] op_sel_hi:[1,0]
	v_pk_mul_f32 v[78:79], v[78:79], v[98:99] op_sel_hi:[1,0]
	v_pk_mul_f32 v[76:77], v[132:133], v[76:77]
	v_pk_mul_f32 v[78:79], v[134:135], v[78:79]
	v_pk_mul_f32 v[72:73], v[72:73], v[98:99] op_sel_hi:[1,0]
	v_pk_mul_f32 v[74:75], v[74:75], v[98:99] op_sel_hi:[1,0]
	ds_bpermute_b32 v98, v176, v76
	ds_bpermute_b32 v99, v176, v77
	ds_bpermute_b32 v102, v176, v78
	ds_bpermute_b32 v103, v176, v79
	v_pk_mul_f32 v[74:75], v[130:131], v[74:75]
	v_pk_mul_f32 v[72:73], v[128:129], v[72:73]
	ds_bpermute_b32 v100, v176, v72
	ds_bpermute_b32 v101, v176, v73
	ds_bpermute_b32 v104, v176, v74
	ds_bpermute_b32 v105, v176, v75
	s_waitcnt vmcnt(1) lgkmcnt(6)
	v_pk_mul_f32 v[98:99], v[92:93], v[98:99]
	s_waitcnt lgkmcnt(4)
	v_pk_mul_f32 v[102:103], v[94:95], v[102:103]
	v_xor_b32_e32 v106, 0x80000000, v98
	v_xor_b32_e32 v107, 0x80000000, v99
	v_xor_b32_e32 v108, 0x80000000, v102
	v_xor_b32_e32 v109, 0x80000000, v103
	v_cndmask_b32_e32 v99, v99, v107, vcc
	v_cndmask_b32_e32 v98, v98, v106, vcc
	v_cndmask_b32_e32 v103, v103, v109, vcc
	v_cndmask_b32_e32 v102, v102, v108, vcc
	v_pk_fma_f32 v[76:77], v[84:85], v[76:77], v[98:99]
	s_waitcnt vmcnt(0) lgkmcnt(0)
	v_pk_mul_f32 v[98:99], v[90:91], v[104:105]
	v_pk_mul_f32 v[100:101], v[88:89], v[100:101]
	v_pk_fma_f32 v[78:79], v[86:87], v[78:79], v[102:103]
	v_xor_b32_e32 v102, 0x80000000, v100
	v_xor_b32_e32 v103, 0x80000000, v101
	v_xor_b32_e32 v104, 0x80000000, v98
	v_xor_b32_e32 v105, 0x80000000, v99
	v_cndmask_b32_e32 v99, v99, v105, vcc
	v_cndmask_b32_e32 v98, v98, v104, vcc
	v_cndmask_b32_e32 v101, v101, v103, vcc
	v_cndmask_b32_e32 v100, v100, v102, vcc
	v_pk_mul_f32 v[76:77], v[76:77], s[92:93] op_sel_hi:[1,0]
	v_pk_fma_f32 v[72:73], v[80:81], v[72:73], v[100:101]
	v_pk_fma_f32 v[74:75], v[82:83], v[74:75], v[98:99]
	v_pk_mul_f32 v[78:79], v[78:79], s[92:93] op_sel_hi:[1,0]
	v_pk_mul_f32 v[98:99], v[74:75], s[92:93] op_sel_hi:[1,0]
	v_pk_mul_f32 v[74:75], v[72:73], s[92:93] op_sel_hi:[1,0]
	v_cvt_pk_bf16_f32 v72, v76, v77
	v_lshl_add_u64 v[76:77], s[44:45], 0, v[96:97]
	v_lshl_add_u64 v[76:77], v[76:77], 0, s[8:9]
	v_lshl_add_u64 v[76:77], v[76:77], 0, s[40:41]
	v_lshl_add_u64 v[76:77], v[76:77], 0, v[174:175]
	v_cvt_pk_bf16_f32 v73, v78, v79
	v_cvt_pk_bf16_f32 v74, v74, v75
	v_cvt_pk_bf16_f32 v75, v98, v99
	global_store_dwordx4 v[76:77], v[72:75], off
	s_nop 1
	v_bitop3_b32 v72, v179, s10, v184 bitop3:0x36
	v_lshl_add_u32 v72, v72, 2, s26
	ds_read_b32 v72, v72
	s_movk_i32 s10, 0x140
	s_waitcnt lgkmcnt(0)
	v_add_f32_e32 v72, v188, v72
	v_fmamk_f32 v72, v72, 0x3c800000, v205
	v_cmp_gt_f32_e64 s[6:7], s84, v72
	v_mul_f32_e32 v73, 0x4b800000, v72
	s_nop 0
	v_cndmask_b32_e64 v72, v72, v73, s[6:7]
	v_rsq_f32_e32 v72, v72
	s_nop 0
	v_mul_f32_e32 v73, 0x45800000, v72
	v_cndmask_b32_e64 v72, v72, v73, s[6:7]
	v_pk_mul_f32 v[68:69], v[68:69], v[72:73] op_sel_hi:[1,0]
	v_pk_mul_f32 v[70:71], v[70:71], v[72:73] op_sel_hi:[1,0]
	v_pk_mul_f32 v[68:69], v[132:133], v[68:69]
	v_pk_mul_f32 v[70:71], v[134:135], v[70:71]
	v_pk_mul_f32 v[64:65], v[64:65], v[72:73] op_sel_hi:[1,0]
	v_pk_mul_f32 v[66:67], v[66:67], v[72:73] op_sel_hi:[1,0]
	ds_bpermute_b32 v72, v176, v68
	ds_bpermute_b32 v73, v176, v69
	ds_bpermute_b32 v78, v176, v70
	ds_bpermute_b32 v79, v176, v71
	v_pk_mul_f32 v[66:67], v[130:131], v[66:67]
	v_pk_mul_f32 v[64:65], v[128:129], v[64:65]
	ds_bpermute_b32 v74, v176, v64
	ds_bpermute_b32 v75, v176, v65
	ds_bpermute_b32 v96, v176, v66
	ds_bpermute_b32 v97, v176, v67
	s_waitcnt lgkmcnt(6)
	v_pk_mul_f32 v[72:73], v[92:93], v[72:73]
	s_waitcnt lgkmcnt(4)
	v_pk_mul_f32 v[78:79], v[94:95], v[78:79]
	v_xor_b32_e32 v92, 0x80000000, v72
	v_xor_b32_e32 v93, 0x80000000, v73
	v_xor_b32_e32 v94, 0x80000000, v78
	v_xor_b32_e32 v95, 0x80000000, v79
	v_cndmask_b32_e32 v73, v73, v93, vcc
	v_cndmask_b32_e32 v72, v72, v92, vcc
	v_cndmask_b32_e32 v79, v79, v95, vcc
	v_cndmask_b32_e32 v78, v78, v94, vcc
	v_pk_fma_f32 v[68:69], v[84:85], v[68:69], v[72:73]
	s_waitcnt lgkmcnt(0)
	v_pk_mul_f32 v[72:73], v[90:91], v[96:97]
	v_pk_mul_f32 v[74:75], v[88:89], v[74:75]
	v_pk_fma_f32 v[70:71], v[86:87], v[70:71], v[78:79]
	v_xor_b32_e32 v78, 0x80000000, v74
	v_xor_b32_e32 v79, 0x80000000, v75
	v_xor_b32_e32 v84, 0x80000000, v72
	v_xor_b32_e32 v85, 0x80000000, v73
	v_cndmask_b32_e32 v73, v73, v85, vcc
	v_cndmask_b32_e32 v72, v72, v84, vcc
	v_cndmask_b32_e32 v75, v75, v79, vcc
	v_cndmask_b32_e32 v74, v74, v78, vcc
	v_pk_fma_f32 v[64:65], v[80:81], v[64:65], v[74:75]
	v_pk_fma_f32 v[66:67], v[82:83], v[66:67], v[72:73]
	v_add_u32_e32 v82, 0x80, v172
	v_pk_mul_f32 v[68:69], v[68:69], s[92:93] op_sel_hi:[1,0]
	v_pk_mul_f32 v[72:73], v[66:67], s[92:93] op_sel_hi:[1,0]
	v_pk_mul_f32 v[66:67], v[64:65], s[92:93] op_sel_hi:[1,0]
	v_cvt_pk_bf16_f32 v64, v68, v69
	v_lshrrev_b32_e32 v80, 6, v82
	v_pk_mul_f32 v[70:71], v[70:71], s[92:93] op_sel_hi:[1,0]
	v_bitop3_b32 v81, v179, s10, v173 bitop3:0x36
	v_cvt_pk_bf16_f32 v65, v70, v71
	v_cvt_pk_bf16_f32 v66, v66, v67
	v_cvt_pk_bf16_f32 v67, v72, v73
	global_store_dwordx4 v[76:77], v[64:67], off offset:256
	v_lshl_add_u32 v81, v81, 2, s26
	v_ashrrev_i32_e32 v83, 31, v82
	v_cndmask_b32_e64 v64, v179, v80, s[0:1]
	v_lshlrev_b32_e32 v64, 6, v64
	v_and_b32_e32 v64, 0xfc0, v64
	v_mov_b32_e32 v65, v161
	v_lshl_add_u64 v[64:65], s[46:47], 0, v[64:65]
	v_lshl_add_u64 v[72:73], v[64:65], 0, v[160:161]
	global_load_dwordx4 v[64:67], v[72:73], off offset:16
	global_load_dwordx4 v[68:71], v[72:73], off
	v_lshl_add_u64 v[74:75], v[72:73], 0, s[90:91]
	v_add_co_u32_e64 v72, s[6:7], s85, v72
	v_lshlrev_b64 v[82:83], 10, v[82:83]
	s_nop 0
	v_addc_co_u32_e64 v73, s[6:7], 0, v73, s[6:7]
	global_load_dwordx4 v[76:79], v[72:73], off
	s_nop 0
	global_load_dwordx4 v[72:75], v[74:75], off offset:16
	ds_read_b32 v81, v81
	s_waitcnt lgkmcnt(0)
	v_add_f32_e32 v81, v185, v81
	v_fmamk_f32 v81, v81, 0x3c800000, v205
	v_cmp_gt_f32_e64 s[6:7], s84, v81
	v_mul_f32_e32 v84, 0x4b800000, v81
	s_nop 0
	v_cndmask_b32_e64 v81, v81, v84, s[6:7]
	v_rsq_f32_e32 v81, v81
	s_nop 0
	v_mul_f32_e32 v84, 0x45800000, v81
	v_cndmask_b32_e64 v84, v81, v84, s[6:7]
	v_pk_mul_f32 v[60:61], v[60:61], v[84:85] op_sel_hi:[1,0]
	v_pk_mul_f32 v[62:63], v[62:63], v[84:85] op_sel_hi:[1,0]
	v_pk_mul_f32 v[60:61], v[132:133], v[60:61]
	v_pk_mul_f32 v[62:63], v[134:135], v[62:63]
	v_pk_mul_f32 v[56:57], v[56:57], v[84:85] op_sel_hi:[1,0]
	v_pk_mul_f32 v[58:59], v[58:59], v[84:85] op_sel_hi:[1,0]
	ds_bpermute_b32 v84, v176, v60
	ds_bpermute_b32 v85, v176, v61
	ds_bpermute_b32 v88, v176, v62
	ds_bpermute_b32 v89, v176, v63
	v_pk_mul_f32 v[58:59], v[130:131], v[58:59]
	v_pk_mul_f32 v[56:57], v[128:129], v[56:57]
	ds_bpermute_b32 v86, v176, v56
	ds_bpermute_b32 v87, v176, v57
	ds_bpermute_b32 v90, v176, v58
	ds_bpermute_b32 v91, v176, v59
	s_waitcnt vmcnt(1) lgkmcnt(6)
	v_pk_mul_f32 v[84:85], v[76:77], v[84:85]
	s_waitcnt lgkmcnt(4)
	v_pk_mul_f32 v[88:89], v[78:79], v[88:89]
	v_xor_b32_e32 v81, 0x80000000, v84
	v_xor_b32_e32 v92, 0x80000000, v85
	v_xor_b32_e32 v93, 0x80000000, v88
	v_xor_b32_e32 v94, 0x80000000, v89
	v_cndmask_b32_e32 v85, v85, v92, vcc
	v_cndmask_b32_e32 v84, v84, v81, vcc
	v_cndmask_b32_e32 v89, v89, v94, vcc
	v_cndmask_b32_e32 v88, v88, v93, vcc
	v_pk_fma_f32 v[60:61], v[68:69], v[60:61], v[84:85]
	s_waitcnt vmcnt(0) lgkmcnt(0)
	v_pk_mul_f32 v[84:85], v[74:75], v[90:91]
	v_pk_mul_f32 v[86:87], v[72:73], v[86:87]
	v_pk_fma_f32 v[62:63], v[70:71], v[62:63], v[88:89]
	v_xor_b32_e32 v81, 0x80000000, v86
	v_xor_b32_e32 v88, 0x80000000, v87
	v_xor_b32_e32 v89, 0x80000000, v84
	v_xor_b32_e32 v90, 0x80000000, v85
	v_cndmask_b32_e32 v85, v85, v90, vcc
	v_cndmask_b32_e32 v84, v84, v89, vcc
	v_cndmask_b32_e32 v87, v87, v88, vcc
	v_cndmask_b32_e32 v86, v86, v81, vcc
	v_pk_mul_f32 v[60:61], v[60:61], s[92:93] op_sel_hi:[1,0]
	v_pk_fma_f32 v[56:57], v[64:65], v[56:57], v[86:87]
	v_pk_fma_f32 v[58:59], v[66:67], v[58:59], v[84:85]
	v_pk_mul_f32 v[62:63], v[62:63], s[92:93] op_sel_hi:[1,0]
	v_pk_mul_f32 v[84:85], v[58:59], s[92:93] op_sel_hi:[1,0]
	v_pk_mul_f32 v[58:59], v[56:57], s[92:93] op_sel_hi:[1,0]
	v_cvt_pk_bf16_f32 v56, v60, v61
	v_lshl_add_u64 v[60:61], s[44:45], 0, v[82:83]
	v_lshl_add_u64 v[60:61], v[60:61], 0, s[8:9]
	v_lshl_add_u64 v[60:61], v[60:61], 0, s[40:41]
	v_lshl_add_u64 v[60:61], v[60:61], 0, v[174:175]
	v_cvt_pk_bf16_f32 v57, v62, v63
	v_cvt_pk_bf16_f32 v58, v58, v59
	v_cvt_pk_bf16_f32 v59, v84, v85
	global_store_dwordx4 v[60:61], v[56:59], off
	s_nop 1
	v_bitop3_b32 v56, v179, s10, v184 bitop3:0x36
	v_lshl_add_u32 v56, v56, 2, s26
	ds_read_b32 v56, v56
	s_movk_i32 s10, 0x150
	s_waitcnt lgkmcnt(0)
	v_add_f32_e32 v56, v186, v56
	v_fmamk_f32 v56, v56, 0x3c800000, v205
	v_cmp_gt_f32_e64 s[6:7], s84, v56
	v_mul_f32_e32 v57, 0x4b800000, v56
	s_nop 0
	v_cndmask_b32_e64 v56, v56, v57, s[6:7]
	v_rsq_f32_e32 v56, v56
	s_nop 0
	v_mul_f32_e32 v57, 0x45800000, v56
	v_cndmask_b32_e64 v56, v56, v57, s[6:7]
	v_pk_mul_f32 v[52:53], v[52:53], v[56:57] op_sel_hi:[1,0]
	v_pk_mul_f32 v[54:55], v[54:55], v[56:57] op_sel_hi:[1,0]
	v_pk_mul_f32 v[52:53], v[132:133], v[52:53]
	v_pk_mul_f32 v[54:55], v[134:135], v[54:55]
	v_pk_mul_f32 v[48:49], v[48:49], v[56:57] op_sel_hi:[1,0]
	v_pk_mul_f32 v[50:51], v[50:51], v[56:57] op_sel_hi:[1,0]
	ds_bpermute_b32 v56, v176, v52
	ds_bpermute_b32 v57, v176, v53
	ds_bpermute_b32 v62, v176, v54
	ds_bpermute_b32 v63, v176, v55
	v_pk_mul_f32 v[50:51], v[130:131], v[50:51]
	v_pk_mul_f32 v[48:49], v[128:129], v[48:49]
	ds_bpermute_b32 v58, v176, v48
	ds_bpermute_b32 v59, v176, v49
	ds_bpermute_b32 v82, v176, v50
	ds_bpermute_b32 v83, v176, v51
	s_waitcnt lgkmcnt(6)
	v_pk_mul_f32 v[56:57], v[76:77], v[56:57]
	s_waitcnt lgkmcnt(4)
	v_pk_mul_f32 v[62:63], v[78:79], v[62:63]
	v_xor_b32_e32 v76, 0x80000000, v56
	v_xor_b32_e32 v77, 0x80000000, v57
	v_xor_b32_e32 v78, 0x80000000, v62
	v_xor_b32_e32 v79, 0x80000000, v63
	v_cndmask_b32_e32 v57, v57, v77, vcc
	v_cndmask_b32_e32 v56, v56, v76, vcc
	v_cndmask_b32_e32 v63, v63, v79, vcc
	v_cndmask_b32_e32 v62, v62, v78, vcc
	v_pk_fma_f32 v[52:53], v[68:69], v[52:53], v[56:57]
	s_waitcnt lgkmcnt(0)
	v_pk_mul_f32 v[56:57], v[74:75], v[82:83]
	v_pk_mul_f32 v[58:59], v[72:73], v[58:59]
	v_pk_fma_f32 v[54:55], v[70:71], v[54:55], v[62:63]
	v_xor_b32_e32 v62, 0x80000000, v58
	v_xor_b32_e32 v63, 0x80000000, v59
	v_xor_b32_e32 v68, 0x80000000, v56
	v_xor_b32_e32 v69, 0x80000000, v57
	v_cndmask_b32_e32 v57, v57, v69, vcc
	v_cndmask_b32_e32 v56, v56, v68, vcc
	v_cndmask_b32_e32 v59, v59, v63, vcc
	v_cndmask_b32_e32 v58, v58, v62, vcc
	v_pk_fma_f32 v[48:49], v[64:65], v[48:49], v[58:59]
	v_pk_fma_f32 v[50:51], v[66:67], v[50:51], v[56:57]
	v_pk_mul_f32 v[52:53], v[52:53], s[92:93] op_sel_hi:[1,0]
	v_pk_mul_f32 v[56:57], v[50:51], s[92:93] op_sel_hi:[1,0]
	v_pk_mul_f32 v[50:51], v[48:49], s[92:93] op_sel_hi:[1,0]
	v_cvt_pk_bf16_f32 v48, v52, v53
	v_add_u32_e32 v64, 0x90, v172
	v_pk_mul_f32 v[54:55], v[54:55], s[92:93] op_sel_hi:[1,0]
	v_bitop3_b32 v66, v179, s10, v173 bitop3:0x36
	v_cvt_pk_bf16_f32 v49, v54, v55
	v_cvt_pk_bf16_f32 v50, v50, v51
	v_cvt_pk_bf16_f32 v51, v56, v57
	global_store_dwordx4 v[60:61], v[48:51], off offset:256
	v_lshl_add_u32 v66, v66, 2, s26
	v_ashrrev_i32_e32 v65, 31, v64
	v_cndmask_b32_e64 v48, v64, v80, s[0:1]
	v_lshlrev_b32_e32 v48, 6, v48
	v_and_b32_e32 v48, 0xfc0, v48
	v_mov_b32_e32 v49, v161
	v_lshl_add_u64 v[48:49], s[46:47], 0, v[48:49]
	v_lshl_add_u64 v[56:57], v[48:49], 0, v[160:161]
	global_load_dwordx4 v[48:51], v[56:57], off offset:16
	global_load_dwordx4 v[52:55], v[56:57], off
	v_lshl_add_u64 v[58:59], v[56:57], 0, s[90:91]
	v_add_co_u32_e64 v56, s[6:7], s85, v56
	v_lshlrev_b64 v[64:65], 10, v[64:65]
	s_nop 0
	v_addc_co_u32_e64 v57, s[6:7], 0, v57, s[6:7]
	global_load_dwordx4 v[60:63], v[56:57], off
	s_nop 0
	global_load_dwordx4 v[56:59], v[58:59], off offset:16
	ds_read_b32 v66, v66
	s_waitcnt lgkmcnt(0)
	v_add_f32_e32 v66, v182, v66
	v_fmamk_f32 v66, v66, 0x3c800000, v205
	v_cmp_gt_f32_e64 s[6:7], s84, v66
	v_mul_f32_e32 v67, 0x4b800000, v66
	s_nop 0
	v_cndmask_b32_e64 v66, v66, v67, s[6:7]
	v_rsq_f32_e32 v66, v66
	s_nop 0
	v_mul_f32_e32 v67, 0x45800000, v66
	v_cndmask_b32_e64 v66, v66, v67, s[6:7]
	v_pk_mul_f32 v[44:45], v[44:45], v[66:67] op_sel_hi:[1,0]
	v_pk_mul_f32 v[46:47], v[46:47], v[66:67] op_sel_hi:[1,0]
	v_pk_mul_f32 v[44:45], v[132:133], v[44:45]
	v_pk_mul_f32 v[46:47], v[134:135], v[46:47]
	v_pk_mul_f32 v[40:41], v[40:41], v[66:67] op_sel_hi:[1,0]
	v_pk_mul_f32 v[42:43], v[42:43], v[66:67] op_sel_hi:[1,0]
	ds_bpermute_b32 v66, v176, v44
	ds_bpermute_b32 v67, v176, v45
	ds_bpermute_b32 v70, v176, v46
	ds_bpermute_b32 v71, v176, v47
	v_pk_mul_f32 v[42:43], v[130:131], v[42:43]
	v_pk_mul_f32 v[40:41], v[128:129], v[40:41]
	ds_bpermute_b32 v68, v176, v40
	ds_bpermute_b32 v69, v176, v41
	ds_bpermute_b32 v72, v176, v42
	ds_bpermute_b32 v73, v176, v43
	s_waitcnt vmcnt(1) lgkmcnt(6)
	v_pk_mul_f32 v[66:67], v[60:61], v[66:67]
	s_waitcnt lgkmcnt(4)
	v_pk_mul_f32 v[70:71], v[62:63], v[70:71]
	v_xor_b32_e32 v74, 0x80000000, v66
	v_xor_b32_e32 v75, 0x80000000, v67
	v_xor_b32_e32 v76, 0x80000000, v70
	v_xor_b32_e32 v77, 0x80000000, v71
	v_cndmask_b32_e32 v67, v67, v75, vcc
	v_cndmask_b32_e32 v66, v66, v74, vcc
	v_cndmask_b32_e32 v71, v71, v77, vcc
	v_cndmask_b32_e32 v70, v70, v76, vcc
	v_pk_fma_f32 v[44:45], v[52:53], v[44:45], v[66:67]
	s_waitcnt vmcnt(0) lgkmcnt(0)
	v_pk_mul_f32 v[66:67], v[58:59], v[72:73]
	v_pk_mul_f32 v[68:69], v[56:57], v[68:69]
	v_pk_fma_f32 v[46:47], v[54:55], v[46:47], v[70:71]
	v_xor_b32_e32 v70, 0x80000000, v68
	v_xor_b32_e32 v71, 0x80000000, v69
	v_xor_b32_e32 v72, 0x80000000, v66
	v_xor_b32_e32 v73, 0x80000000, v67
	v_cndmask_b32_e32 v67, v67, v73, vcc
	v_cndmask_b32_e32 v66, v66, v72, vcc
	v_cndmask_b32_e32 v69, v69, v71, vcc
	v_cndmask_b32_e32 v68, v68, v70, vcc
	v_pk_mul_f32 v[44:45], v[44:45], s[92:93] op_sel_hi:[1,0]
	v_pk_fma_f32 v[40:41], v[48:49], v[40:41], v[68:69]
	v_pk_fma_f32 v[42:43], v[50:51], v[42:43], v[66:67]
	v_pk_mul_f32 v[46:47], v[46:47], s[92:93] op_sel_hi:[1,0]
	v_pk_mul_f32 v[66:67], v[42:43], s[92:93] op_sel_hi:[1,0]
	v_pk_mul_f32 v[42:43], v[40:41], s[92:93] op_sel_hi:[1,0]
	v_cvt_pk_bf16_f32 v40, v44, v45
	v_lshl_add_u64 v[44:45], s[44:45], 0, v[64:65]
	v_lshl_add_u64 v[44:45], v[44:45], 0, s[8:9]
	v_lshl_add_u64 v[44:45], v[44:45], 0, s[40:41]
	v_lshl_add_u64 v[44:45], v[44:45], 0, v[174:175]
	v_cvt_pk_bf16_f32 v41, v46, v47
	v_cvt_pk_bf16_f32 v42, v42, v43
	v_cvt_pk_bf16_f32 v43, v66, v67
	global_store_dwordx4 v[44:45], v[40:43], off
	s_nop 1
	v_bitop3_b32 v40, v179, s10, v184 bitop3:0x36
	v_lshl_add_u32 v40, v40, 2, s26
	ds_read_b32 v40, v40
	s_movk_i32 s10, 0x160
	s_waitcnt lgkmcnt(0)
	v_add_f32_e32 v40, v183, v40
	v_fmamk_f32 v40, v40, 0x3c800000, v205
	v_cmp_gt_f32_e64 s[6:7], s84, v40
	v_mul_f32_e32 v41, 0x4b800000, v40
	s_nop 0
	v_cndmask_b32_e64 v40, v40, v41, s[6:7]
	v_rsq_f32_e32 v40, v40
	s_nop 0
	v_mul_f32_e32 v41, 0x45800000, v40
	v_cndmask_b32_e64 v40, v40, v41, s[6:7]
	v_pk_mul_f32 v[36:37], v[36:37], v[40:41] op_sel_hi:[1,0]
	v_pk_mul_f32 v[38:39], v[38:39], v[40:41] op_sel_hi:[1,0]
	v_pk_mul_f32 v[36:37], v[132:133], v[36:37]
	v_pk_mul_f32 v[38:39], v[134:135], v[38:39]
	v_pk_mul_f32 v[32:33], v[32:33], v[40:41] op_sel_hi:[1,0]
	v_pk_mul_f32 v[34:35], v[34:35], v[40:41] op_sel_hi:[1,0]
	ds_bpermute_b32 v40, v176, v36
	ds_bpermute_b32 v41, v176, v37
	ds_bpermute_b32 v46, v176, v38
	ds_bpermute_b32 v47, v176, v39
	v_pk_mul_f32 v[34:35], v[130:131], v[34:35]
	v_pk_mul_f32 v[32:33], v[128:129], v[32:33]
	ds_bpermute_b32 v42, v176, v32
	ds_bpermute_b32 v43, v176, v33
	ds_bpermute_b32 v64, v176, v34
	ds_bpermute_b32 v65, v176, v35
	s_waitcnt lgkmcnt(6)
	v_pk_mul_f32 v[40:41], v[60:61], v[40:41]
	s_waitcnt lgkmcnt(4)
	v_pk_mul_f32 v[46:47], v[62:63], v[46:47]
	v_xor_b32_e32 v60, 0x80000000, v40
	v_xor_b32_e32 v61, 0x80000000, v41
	v_xor_b32_e32 v62, 0x80000000, v46
	v_xor_b32_e32 v63, 0x80000000, v47
	v_cndmask_b32_e32 v41, v41, v61, vcc
	v_cndmask_b32_e32 v40, v40, v60, vcc
	v_cndmask_b32_e32 v47, v47, v63, vcc
	v_cndmask_b32_e32 v46, v46, v62, vcc
	v_pk_fma_f32 v[36:37], v[52:53], v[36:37], v[40:41]
	s_waitcnt lgkmcnt(0)
	v_pk_mul_f32 v[40:41], v[58:59], v[64:65]
	v_pk_mul_f32 v[42:43], v[56:57], v[42:43]
	v_pk_fma_f32 v[38:39], v[54:55], v[38:39], v[46:47]
	v_xor_b32_e32 v46, 0x80000000, v42
	v_xor_b32_e32 v47, 0x80000000, v43
	v_xor_b32_e32 v52, 0x80000000, v40
	v_xor_b32_e32 v53, 0x80000000, v41
	v_cndmask_b32_e32 v41, v41, v53, vcc
	v_cndmask_b32_e32 v40, v40, v52, vcc
	v_cndmask_b32_e32 v43, v43, v47, vcc
	v_cndmask_b32_e32 v42, v42, v46, vcc
	v_pk_fma_f32 v[32:33], v[48:49], v[32:33], v[42:43]
	v_pk_fma_f32 v[34:35], v[50:51], v[34:35], v[40:41]
	v_pk_mul_f32 v[36:37], v[36:37], s[92:93] op_sel_hi:[1,0]
	v_pk_mul_f32 v[40:41], v[34:35], s[92:93] op_sel_hi:[1,0]
	v_pk_mul_f32 v[34:35], v[32:33], s[92:93] op_sel_hi:[1,0]
	v_cvt_pk_bf16_f32 v32, v36, v37
	v_add_u32_e32 v48, 0xa0, v172
	v_pk_mul_f32 v[38:39], v[38:39], s[92:93] op_sel_hi:[1,0]
	v_bitop3_b32 v50, v179, s10, v173 bitop3:0x36
	v_cvt_pk_bf16_f32 v33, v38, v39
	v_cvt_pk_bf16_f32 v34, v34, v35
	v_cvt_pk_bf16_f32 v35, v40, v41
	global_store_dwordx4 v[44:45], v[32:35], off offset:256
	v_lshl_add_u32 v50, v50, 2, s26
	v_ashrrev_i32_e32 v49, 31, v48
	v_cndmask_b32_e64 v32, v48, v80, s[0:1]
	v_lshlrev_b32_e32 v32, 6, v32
	v_and_b32_e32 v32, 0xfc0, v32
	v_mov_b32_e32 v33, v161
	v_lshl_add_u64 v[32:33], s[46:47], 0, v[32:33]
	v_lshl_add_u64 v[40:41], v[32:33], 0, v[160:161]
	global_load_dwordx4 v[32:35], v[40:41], off offset:16
	global_load_dwordx4 v[36:39], v[40:41], off
	v_lshl_add_u64 v[42:43], v[40:41], 0, s[90:91]
	v_add_co_u32_e64 v40, s[6:7], s85, v40
	v_lshlrev_b64 v[48:49], 10, v[48:49]
	s_nop 0
	v_addc_co_u32_e64 v41, s[6:7], 0, v41, s[6:7]
	global_load_dwordx4 v[44:47], v[40:41], off
	s_nop 0
	global_load_dwordx4 v[40:43], v[42:43], off offset:16
	ds_read_b32 v50, v50
	s_waitcnt lgkmcnt(0)
	v_add_f32_e32 v50, v180, v50
	v_fmamk_f32 v50, v50, 0x3c800000, v205
	v_cmp_gt_f32_e64 s[6:7], s84, v50
	v_mul_f32_e32 v51, 0x4b800000, v50
	s_nop 0
	v_cndmask_b32_e64 v50, v50, v51, s[6:7]
	v_rsq_f32_e32 v50, v50
	s_nop 0
	v_mul_f32_e32 v51, 0x45800000, v50
	v_cndmask_b32_e64 v50, v50, v51, s[6:7]
	v_pk_mul_f32 v[28:29], v[28:29], v[50:51] op_sel_hi:[1,0]
	v_pk_mul_f32 v[30:31], v[30:31], v[50:51] op_sel_hi:[1,0]
	v_pk_mul_f32 v[28:29], v[132:133], v[28:29]
	v_pk_mul_f32 v[30:31], v[134:135], v[30:31]
	v_pk_mul_f32 v[24:25], v[24:25], v[50:51] op_sel_hi:[1,0]
	v_pk_mul_f32 v[26:27], v[26:27], v[50:51] op_sel_hi:[1,0]
	ds_bpermute_b32 v50, v176, v28
	ds_bpermute_b32 v51, v176, v29
	ds_bpermute_b32 v54, v176, v30
	ds_bpermute_b32 v55, v176, v31
	v_pk_mul_f32 v[26:27], v[130:131], v[26:27]
	v_pk_mul_f32 v[24:25], v[128:129], v[24:25]
	ds_bpermute_b32 v52, v176, v24
	ds_bpermute_b32 v53, v176, v25
	ds_bpermute_b32 v56, v176, v26
	ds_bpermute_b32 v57, v176, v27
	s_waitcnt vmcnt(1) lgkmcnt(6)
	v_pk_mul_f32 v[50:51], v[44:45], v[50:51]
	s_waitcnt lgkmcnt(4)
	v_pk_mul_f32 v[54:55], v[46:47], v[54:55]
	v_xor_b32_e32 v58, 0x80000000, v50
	v_xor_b32_e32 v59, 0x80000000, v51
	v_xor_b32_e32 v60, 0x80000000, v54
	v_xor_b32_e32 v61, 0x80000000, v55
	v_cndmask_b32_e32 v51, v51, v59, vcc
	v_cndmask_b32_e32 v50, v50, v58, vcc
	v_cndmask_b32_e32 v55, v55, v61, vcc
	v_cndmask_b32_e32 v54, v54, v60, vcc
	v_pk_fma_f32 v[28:29], v[36:37], v[28:29], v[50:51]
	s_waitcnt vmcnt(0) lgkmcnt(0)
	v_pk_mul_f32 v[50:51], v[42:43], v[56:57]
	v_pk_mul_f32 v[52:53], v[40:41], v[52:53]
	v_pk_fma_f32 v[30:31], v[38:39], v[30:31], v[54:55]
	v_xor_b32_e32 v54, 0x80000000, v52
	v_xor_b32_e32 v55, 0x80000000, v53
	v_xor_b32_e32 v56, 0x80000000, v50
	v_xor_b32_e32 v57, 0x80000000, v51
	v_cndmask_b32_e32 v51, v51, v57, vcc
	v_cndmask_b32_e32 v50, v50, v56, vcc
	v_cndmask_b32_e32 v53, v53, v55, vcc
	v_cndmask_b32_e32 v52, v52, v54, vcc
	v_pk_mul_f32 v[28:29], v[28:29], s[92:93] op_sel_hi:[1,0]
	v_pk_fma_f32 v[24:25], v[32:33], v[24:25], v[52:53]
	v_pk_fma_f32 v[26:27], v[34:35], v[26:27], v[50:51]
	v_pk_mul_f32 v[30:31], v[30:31], s[92:93] op_sel_hi:[1,0]
	v_pk_mul_f32 v[50:51], v[26:27], s[92:93] op_sel_hi:[1,0]
	v_pk_mul_f32 v[26:27], v[24:25], s[92:93] op_sel_hi:[1,0]
	v_cvt_pk_bf16_f32 v24, v28, v29
	v_lshl_add_u64 v[28:29], s[44:45], 0, v[48:49]
	v_lshl_add_u64 v[28:29], v[28:29], 0, s[8:9]
	v_lshl_add_u64 v[28:29], v[28:29], 0, s[40:41]
	v_lshl_add_u64 v[28:29], v[28:29], 0, v[174:175]
	v_cvt_pk_bf16_f32 v25, v30, v31
	v_cvt_pk_bf16_f32 v26, v26, v27
	v_cvt_pk_bf16_f32 v27, v50, v51
	global_store_dwordx4 v[28:29], v[24:27], off
	s_nop 1
	v_bitop3_b32 v24, v179, s10, v184 bitop3:0x36
	v_lshl_add_u32 v24, v24, 2, s26
	ds_read_b32 v24, v24
	s_movk_i32 s10, 0x170
	s_waitcnt lgkmcnt(0)
	v_add_f32_e32 v24, v181, v24
	v_fmamk_f32 v24, v24, 0x3c800000, v205
	v_cmp_gt_f32_e64 s[6:7], s84, v24
	v_mul_f32_e32 v25, 0x4b800000, v24
	s_nop 0
	v_cndmask_b32_e64 v24, v24, v25, s[6:7]
	v_rsq_f32_e32 v24, v24
	s_nop 0
	v_mul_f32_e32 v25, 0x45800000, v24
	v_cndmask_b32_e64 v24, v24, v25, s[6:7]
	v_pk_mul_f32 v[20:21], v[20:21], v[24:25] op_sel_hi:[1,0]
	v_pk_mul_f32 v[22:23], v[22:23], v[24:25] op_sel_hi:[1,0]
	v_pk_mul_f32 v[20:21], v[132:133], v[20:21]
	v_pk_mul_f32 v[22:23], v[134:135], v[22:23]
	v_pk_mul_f32 v[16:17], v[16:17], v[24:25] op_sel_hi:[1,0]
	v_pk_mul_f32 v[18:19], v[18:19], v[24:25] op_sel_hi:[1,0]
	ds_bpermute_b32 v24, v176, v20
	ds_bpermute_b32 v25, v176, v21
	ds_bpermute_b32 v30, v176, v22
	ds_bpermute_b32 v31, v176, v23
	v_pk_mul_f32 v[18:19], v[130:131], v[18:19]
	v_pk_mul_f32 v[16:17], v[128:129], v[16:17]
	ds_bpermute_b32 v26, v176, v16
	ds_bpermute_b32 v27, v176, v17
	ds_bpermute_b32 v48, v176, v18
	ds_bpermute_b32 v49, v176, v19
	s_waitcnt lgkmcnt(6)
	v_pk_mul_f32 v[24:25], v[44:45], v[24:25]
	s_waitcnt lgkmcnt(4)
	v_pk_mul_f32 v[30:31], v[46:47], v[30:31]
	v_xor_b32_e32 v44, 0x80000000, v24
	v_xor_b32_e32 v45, 0x80000000, v25
	v_xor_b32_e32 v46, 0x80000000, v30
	v_xor_b32_e32 v47, 0x80000000, v31
	v_cndmask_b32_e32 v25, v25, v45, vcc
	v_cndmask_b32_e32 v24, v24, v44, vcc
	v_cndmask_b32_e32 v31, v31, v47, vcc
	v_cndmask_b32_e32 v30, v30, v46, vcc
	v_pk_fma_f32 v[20:21], v[36:37], v[20:21], v[24:25]
	s_waitcnt lgkmcnt(0)
	v_pk_mul_f32 v[24:25], v[42:43], v[48:49]
	v_pk_mul_f32 v[26:27], v[40:41], v[26:27]
	v_pk_fma_f32 v[22:23], v[38:39], v[22:23], v[30:31]
	v_xor_b32_e32 v30, 0x80000000, v26
	v_xor_b32_e32 v31, 0x80000000, v27
	v_xor_b32_e32 v36, 0x80000000, v24
	v_xor_b32_e32 v37, 0x80000000, v25
	v_cndmask_b32_e32 v25, v25, v37, vcc
	v_cndmask_b32_e32 v24, v24, v36, vcc
	v_cndmask_b32_e32 v27, v27, v31, vcc
	v_cndmask_b32_e32 v26, v26, v30, vcc
	v_pk_fma_f32 v[16:17], v[32:33], v[16:17], v[26:27]
	v_pk_fma_f32 v[18:19], v[34:35], v[18:19], v[24:25]
	v_pk_mul_f32 v[20:21], v[20:21], s[92:93] op_sel_hi:[1,0]
	v_pk_mul_f32 v[24:25], v[18:19], s[92:93] op_sel_hi:[1,0]
	v_pk_mul_f32 v[18:19], v[16:17], s[92:93] op_sel_hi:[1,0]
	v_cvt_pk_bf16_f32 v16, v20, v21
	v_add_u32_e32 v32, 0xb0, v172
	v_pk_mul_f32 v[22:23], v[22:23], s[92:93] op_sel_hi:[1,0]
	v_bitop3_b32 v34, v179, s10, v173 bitop3:0x36
	v_cvt_pk_bf16_f32 v17, v22, v23
	v_cvt_pk_bf16_f32 v18, v18, v19
	v_cvt_pk_bf16_f32 v19, v24, v25
	global_store_dwordx4 v[28:29], v[16:19], off offset:256
	v_lshl_add_u32 v34, v34, 2, s26
	v_ashrrev_i32_e32 v33, 31, v32
	v_cndmask_b32_e64 v16, v32, v80, s[0:1]
	v_lshlrev_b32_e32 v16, 6, v16
	v_and_b32_e32 v16, 0xfc0, v16
	v_mov_b32_e32 v17, v161
	v_lshl_add_u64 v[16:17], s[46:47], 0, v[16:17]
	v_lshl_add_u64 v[24:25], v[16:17], 0, v[160:161]
	global_load_dwordx4 v[16:19], v[24:25], off offset:16
	global_load_dwordx4 v[20:23], v[24:25], off
	v_lshl_add_u64 v[26:27], v[24:25], 0, s[90:91]
	v_add_co_u32_e64 v24, s[6:7], s85, v24
	v_lshlrev_b64 v[32:33], 10, v[32:33]
	s_nop 0
	v_addc_co_u32_e64 v25, s[6:7], 0, v25, s[6:7]
	global_load_dwordx4 v[28:31], v[24:25], off
	s_nop 0
	global_load_dwordx4 v[24:27], v[26:27], off offset:16
	ds_read_b32 v34, v34
	s_waitcnt lgkmcnt(0)
	v_add_f32_e32 v34, v177, v34
	v_fmamk_f32 v34, v34, 0x3c800000, v205
	v_cmp_gt_f32_e64 s[6:7], s84, v34
	v_mul_f32_e32 v35, 0x4b800000, v34
	s_nop 0
	v_cndmask_b32_e64 v34, v34, v35, s[6:7]
	v_rsq_f32_e32 v34, v34
	s_nop 0
	v_mul_f32_e32 v35, 0x45800000, v34
	v_cndmask_b32_e64 v34, v34, v35, s[6:7]
	v_pk_mul_f32 v[12:13], v[12:13], v[34:35] op_sel_hi:[1,0]
	v_pk_mul_f32 v[14:15], v[14:15], v[34:35] op_sel_hi:[1,0]
	v_pk_mul_f32 v[12:13], v[132:133], v[12:13]
	v_pk_mul_f32 v[14:15], v[134:135], v[14:15]
	v_pk_mul_f32 v[8:9], v[8:9], v[34:35] op_sel_hi:[1,0]
	v_pk_mul_f32 v[10:11], v[10:11], v[34:35] op_sel_hi:[1,0]
	ds_bpermute_b32 v34, v176, v12
	ds_bpermute_b32 v35, v176, v13
	ds_bpermute_b32 v38, v176, v14
	ds_bpermute_b32 v39, v176, v15
	v_pk_mul_f32 v[10:11], v[130:131], v[10:11]
	v_pk_mul_f32 v[8:9], v[128:129], v[8:9]
	ds_bpermute_b32 v36, v176, v8
	ds_bpermute_b32 v37, v176, v9
	ds_bpermute_b32 v40, v176, v10
	ds_bpermute_b32 v41, v176, v11
	s_waitcnt vmcnt(1) lgkmcnt(6)
	v_pk_mul_f32 v[34:35], v[28:29], v[34:35]
	s_waitcnt lgkmcnt(4)
	v_pk_mul_f32 v[38:39], v[30:31], v[38:39]
	v_xor_b32_e32 v42, 0x80000000, v34
	v_xor_b32_e32 v43, 0x80000000, v35
	v_xor_b32_e32 v44, 0x80000000, v38
	v_xor_b32_e32 v45, 0x80000000, v39
	v_cndmask_b32_e32 v35, v35, v43, vcc
	v_cndmask_b32_e32 v34, v34, v42, vcc
	v_cndmask_b32_e32 v39, v39, v45, vcc
	v_cndmask_b32_e32 v38, v38, v44, vcc
	v_pk_fma_f32 v[12:13], v[20:21], v[12:13], v[34:35]
	s_waitcnt vmcnt(0) lgkmcnt(0)
	v_pk_mul_f32 v[34:35], v[26:27], v[40:41]
	v_pk_mul_f32 v[36:37], v[24:25], v[36:37]
	v_pk_fma_f32 v[14:15], v[22:23], v[14:15], v[38:39]
	v_xor_b32_e32 v38, 0x80000000, v36
	v_xor_b32_e32 v39, 0x80000000, v37
	v_xor_b32_e32 v40, 0x80000000, v34
	v_xor_b32_e32 v41, 0x80000000, v35
	v_cndmask_b32_e32 v35, v35, v41, vcc
	v_cndmask_b32_e32 v34, v34, v40, vcc
	v_cndmask_b32_e32 v37, v37, v39, vcc
	v_cndmask_b32_e32 v36, v36, v38, vcc
	v_pk_mul_f32 v[12:13], v[12:13], s[92:93] op_sel_hi:[1,0]
	v_pk_fma_f32 v[8:9], v[16:17], v[8:9], v[36:37]
	v_pk_fma_f32 v[10:11], v[18:19], v[10:11], v[34:35]
	v_pk_mul_f32 v[14:15], v[14:15], s[92:93] op_sel_hi:[1,0]
	v_pk_mul_f32 v[34:35], v[10:11], s[92:93] op_sel_hi:[1,0]
	v_pk_mul_f32 v[10:11], v[8:9], s[92:93] op_sel_hi:[1,0]
	v_cvt_pk_bf16_f32 v8, v12, v13
	v_lshl_add_u64 v[12:13], s[44:45], 0, v[32:33]
	v_lshl_add_u64 v[12:13], v[12:13], 0, s[8:9]
	v_lshl_add_u64 v[12:13], v[12:13], 0, s[40:41]
	v_lshl_add_u64 v[12:13], v[12:13], 0, v[174:175]
	v_cvt_pk_bf16_f32 v9, v14, v15
	v_cvt_pk_bf16_f32 v10, v10, v11
	v_cvt_pk_bf16_f32 v11, v34, v35
	global_store_dwordx4 v[12:13], v[8:11], off
	s_nop 1
	v_bitop3_b32 v8, v179, s10, v184 bitop3:0x36
	v_lshl_add_u32 v8, v8, 2, s26
	ds_read_b32 v8, v8
	s_waitcnt lgkmcnt(0)
	v_add_f32_e32 v8, v178, v8
	v_fmamk_f32 v8, v8, 0x3c800000, v205
	v_cmp_gt_f32_e64 s[6:7], s84, v8
	v_mul_f32_e32 v9, 0x4b800000, v8
	s_nop 0
	v_cndmask_b32_e64 v8, v8, v9, s[6:7]
	v_rsq_f32_e32 v8, v8
	s_nop 0
	v_mul_f32_e32 v9, 0x45800000, v8
	v_cndmask_b32_e64 v8, v8, v9, s[6:7]
	v_pk_mul_f32 v[4:5], v[4:5], v[8:9] op_sel_hi:[1,0]
	v_pk_mul_f32 v[6:7], v[6:7], v[8:9] op_sel_hi:[1,0]
	v_pk_mul_f32 v[4:5], v[132:133], v[4:5]
	v_pk_mul_f32 v[6:7], v[134:135], v[6:7]
	v_pk_mul_f32 v[0:1], v[0:1], v[8:9] op_sel_hi:[1,0]
	v_pk_mul_f32 v[2:3], v[2:3], v[8:9] op_sel_hi:[1,0]
	ds_bpermute_b32 v8, v176, v4
	ds_bpermute_b32 v9, v176, v5
	ds_bpermute_b32 v14, v176, v6
	ds_bpermute_b32 v15, v176, v7
	v_pk_mul_f32 v[2:3], v[130:131], v[2:3]
	v_pk_mul_f32 v[0:1], v[128:129], v[0:1]
	ds_bpermute_b32 v10, v176, v0
	ds_bpermute_b32 v11, v176, v1
	ds_bpermute_b32 v32, v176, v2
	ds_bpermute_b32 v33, v176, v3
	s_waitcnt lgkmcnt(6)
	v_pk_mul_f32 v[8:9], v[28:29], v[8:9]
	s_waitcnt lgkmcnt(4)
	v_pk_mul_f32 v[14:15], v[30:31], v[14:15]
	v_xor_b32_e32 v28, 0x80000000, v8
	v_xor_b32_e32 v29, 0x80000000, v9
	v_xor_b32_e32 v30, 0x80000000, v14
	v_xor_b32_e32 v31, 0x80000000, v15
	v_cndmask_b32_e32 v9, v9, v29, vcc
	v_cndmask_b32_e32 v8, v8, v28, vcc
	v_cndmask_b32_e32 v15, v15, v31, vcc
	v_cndmask_b32_e32 v14, v14, v30, vcc
	v_pk_fma_f32 v[4:5], v[20:21], v[4:5], v[8:9]
	s_waitcnt lgkmcnt(0)
	v_pk_mul_f32 v[8:9], v[26:27], v[32:33]
	v_pk_mul_f32 v[10:11], v[24:25], v[10:11]
	v_pk_fma_f32 v[6:7], v[22:23], v[6:7], v[14:15]
	v_xor_b32_e32 v14, 0x80000000, v10
	v_xor_b32_e32 v15, 0x80000000, v11
	v_xor_b32_e32 v20, 0x80000000, v8
	v_xor_b32_e32 v21, 0x80000000, v9
	v_cndmask_b32_e32 v9, v9, v21, vcc
	v_cndmask_b32_e32 v8, v8, v20, vcc
	v_cndmask_b32_e32 v11, v11, v15, vcc
	v_cndmask_b32_e32 v10, v10, v14, vcc
	v_pk_fma_f32 v[0:1], v[16:17], v[0:1], v[10:11]
	v_pk_fma_f32 v[2:3], v[18:19], v[2:3], v[8:9]
	v_pk_mul_f32 v[6:7], v[6:7], s[92:93] op_sel_hi:[1,0]
	v_pk_mul_f32 v[8:9], v[2:3], s[92:93] op_sel_hi:[1,0]
	v_pk_mul_f32 v[2:3], v[0:1], s[92:93] op_sel_hi:[1,0]
	v_pk_mul_f32 v[4:5], v[4:5], s[92:93] op_sel_hi:[1,0]
	s_nop 0
	v_cvt_pk_bf16_f32 v0, v4, v5
	v_cvt_pk_bf16_f32 v1, v6, v7
	v_cvt_pk_bf16_f32 v2, v2, v3
	v_cvt_pk_bf16_f32 v3, v8, v9
	global_store_dwordx4 v[12:13], v[0:3], off offset:256

.LBB0_1087:
	s_lshl_b32 s6, s50, 3
	s_or_b32 s43, s6, s63
	s_mul_hi_i32 s6, s43, 0x55555556
	s_lshr_b32 s7, s6, 31
	s_add_i32 s6, s6, s7
	s_lshl_b32 s45, s4, 8
	s_mul_i32 s6, s6, 3
	s_add_i32 s45, s45, s66
	s_sub_i32 s6, s43, s6
	v_mbcnt_lo_u32_b32 v136, -1, 0
	v_mbcnt_hi_u32_b32 v136, -1, v136
	s_cmp_eq_u32 s6, 2
	v_and_b32_e32 v149, 15, v136
	v_ashrrev_i32_e32 v140, 4, v136
	v_and_b32_e32 v136, 16, v136
	s_cselect_b64 s[54:55], -1, 0
	s_lshr_b32 s56, s45, 6
	v_cmp_eq_u32_e64 s[4:5], 0, v136
	s_cmp_lg_u32 s6, 2
	v_mov_b32_e32 v136, s56
	v_cmp_gt_i32_e64 s[6:7], 2, v140
	s_nop 1
	v_cndmask_b32_e64 v136, v149, v136, s[6:7]
	v_lshlrev_b32_e32 v136, 3, v136
	v_and_b32_e32 v136, 0x1f8, v136
	v_lshlrev_b32_e32 v147, 2, v136
	s_cbranch_scc1 .LBB0_1089
	global_load_dwordx4 v[150:153], v147, s[18:19]
	global_load_dwordx4 v[154:157], v147, s[16:17]
	v_and_b32_e32 v137, 64, v146
	v_xor_b32_e32 v136, 16, v146
	v_add_u32_e32 v137, 64, v137
	v_cmp_lt_i32_e32 vcc, v136, v137
	s_nop 1
	v_cndmask_b32_e32 v136, v146, v136, vcc
	v_lshlrev_b32_e32 v139, 2, v136
	ds_bpermute_b32 v136, v139, v124
	ds_bpermute_b32 v137, v139, v125
	ds_bpermute_b32 v138, v139, v126
	ds_bpermute_b32 v139, v139, v127
	s_waitcnt vmcnt(0) lgkmcnt(0)
	v_pk_mul_f32 v[136:137], v[150:151], v[136:137]
	v_pk_mul_f32 v[138:139], v[152:153], v[138:139]
	v_xor_b32_e32 v150, 0x80000000, v136
	v_xor_b32_e32 v141, 0x80000000, v138
	v_xor_b32_e32 v148, 0x80000000, v139
	v_xor_b32_e32 v151, 0x80000000, v137
	v_cndmask_b32_e64 v137, v137, v151, s[4:5]
	v_cndmask_b32_e64 v136, v136, v150, s[4:5]
	v_cndmask_b32_e64 v139, v139, v148, s[4:5]
	v_cndmask_b32_e64 v138, v138, v141, s[4:5]
	v_pk_fma_f32 v[126:127], v[126:127], v[156:157], v[138:139]
	v_pk_fma_f32 v[124:125], v[124:125], v[154:155], v[136:137]
.LBB0_1089:
	s_nop 0
	v_pk_mul_f32 v[124:125], v[124:125], s[40:41] op_sel_hi:[1,0]
	s_andn2_b64 vcc, exec, s[54:55]
	v_cvt_pk_bf16_f32 v124, v124, v125
	v_cndmask_b32_e64 v125, 0, 1, s[54:55]
	v_cmp_ne_u32_e64 s[8:9], 1, v125
	v_pk_mul_f32 v[126:127], v[126:127], s[40:41] op_sel_hi:[1,0]
	s_nop 0
	v_cvt_pk_bf16_f32 v125, v126, v127
	s_cbranch_vccnz .LBB0_1091
	global_load_dwordx4 v[150:153], v147, s[18:19] offset:16
	global_load_dwordx4 v[154:157], v147, s[16:17] offset:16
	v_and_b32_e32 v127, 64, v146
	v_xor_b32_e32 v126, 16, v146
	v_add_u32_e32 v127, 64, v127
	v_cmp_lt_i32_e32 vcc, v126, v127
	s_nop 1
	v_cndmask_b32_e32 v126, v146, v126, vcc
	v_lshlrev_b32_e32 v137, 2, v126
	ds_bpermute_b32 v126, v137, v120
	ds_bpermute_b32 v127, v137, v121
	ds_bpermute_b32 v136, v137, v122
	ds_bpermute_b32 v137, v137, v123
	s_waitcnt vmcnt(0) lgkmcnt(0)
	v_pk_mul_f32 v[126:127], v[150:151], v[126:127]
	v_pk_mul_f32 v[136:137], v[152:153], v[136:137]
	v_xor_b32_e32 v141, 0x80000000, v126
	v_xor_b32_e32 v138, 0x80000000, v136
	v_xor_b32_e32 v139, 0x80000000, v137
	v_xor_b32_e32 v148, 0x80000000, v127
	v_cndmask_b32_e64 v127, v127, v148, s[4:5]
	v_cndmask_b32_e64 v126, v126, v141, s[4:5]
	v_cndmask_b32_e64 v137, v137, v139, s[4:5]
	v_cndmask_b32_e64 v136, v136, v138, s[4:5]
	v_pk_fma_f32 v[122:123], v[122:123], v[156:157], v[136:137]
	v_pk_fma_f32 v[120:121], v[120:121], v[154:155], v[126:127]
.LBB0_1091:
	v_or_b32_e32 v148, s45, v149
	v_mov_b64_e32 v[126:127], s[14:15]
	v_mad_i64_i32 v[126:127], s[54:55], v148, s73, v[126:127]
	s_lshl_b32 s54, s50, 8
	s_ashr_i32 s55, s54, 31
	v_lshl_add_u64 v[126:127], s[54:55], 1, v[126:127]
	v_lshlrev_b32_e32 v136, 3, v140
	v_lshl_add_u64 v[126:127], v[126:127], 0, s[10:11]
	v_ashrrev_i32_e32 v137, 31, v136
	v_pk_mul_f32 v[120:121], v[120:121], s[40:41] op_sel_hi:[1,0]
	v_lshl_add_u64 v[140:141], v[136:137], 1, v[126:127]
	v_cvt_pk_bf16_f32 v126, v120, v121
	v_or_b32_e32 v120, 16, v148
	v_mov_b32_e32 v121, s56
	v_pk_mul_f32 v[122:123], v[122:123], s[40:41] op_sel_hi:[1,0]
	v_cndmask_b32_e64 v120, v120, v121, s[6:7]
	v_cvt_pk_bf16_f32 v127, v122, v123
	global_store_dwordx4 v[140:141], v[124:127], off
	v_lshlrev_b32_e32 v120, 3, v120
	v_and_b32_e32 v120, 0x1f8, v120
	s_and_b64 vcc, exec, s[8:9]
	v_lshlrev_b32_e32 v120, 2, v120
	s_cbranch_vccnz .LBB0_1093
	global_load_dwordx4 v[122:125], v120, s[18:19]
	global_load_dwordx4 v[150:153], v120, s[16:17]
	v_and_b32_e32 v126, 64, v146
	v_xor_b32_e32 v121, 16, v146
	v_add_u32_e32 v126, 64, v126
	v_cmp_lt_i32_e32 vcc, v121, v126
	s_nop 1
	v_cndmask_b32_e32 v121, v146, v121, vcc
	v_lshlrev_b32_e32 v121, 2, v121
	ds_bpermute_b32 v126, v121, v116
	ds_bpermute_b32 v127, v121, v117
	ds_bpermute_b32 v136, v121, v118
	ds_bpermute_b32 v137, v121, v119
	s_waitcnt vmcnt(0) lgkmcnt(0)
	v_pk_mul_f32 v[122:123], v[122:123], v[126:127]
	v_pk_mul_f32 v[124:125], v[124:125], v[136:137]
	v_xor_b32_e32 v127, 0x80000000, v122
	v_xor_b32_e32 v121, 0x80000000, v124
	v_xor_b32_e32 v126, 0x80000000, v125
	v_xor_b32_e32 v136, 0x80000000, v123
	v_cndmask_b32_e64 v123, v123, v136, s[4:5]
	v_cndmask_b32_e64 v122, v122, v127, s[4:5]
	v_cndmask_b32_e64 v125, v125, v126, s[4:5]
	v_cndmask_b32_e64 v124, v124, v121, s[4:5]
	v_pk_fma_f32 v[118:119], v[118:119], v[152:153], v[124:125]
	v_pk_fma_f32 v[116:117], v[116:117], v[150:151], v[122:123]
.LBB0_1093:
	s_nop 0
	v_pk_mul_f32 v[116:117], v[116:117], s[40:41] op_sel_hi:[1,0]
	s_and_b64 vcc, exec, s[8:9]
	v_pk_mul_f32 v[118:119], v[118:119], s[40:41] op_sel_hi:[1,0]
	v_cvt_pk_bf16_f32 v116, v116, v117
	s_nop 0
	v_cvt_pk_bf16_f32 v117, v118, v119
	s_cbranch_vccnz .LBB0_1095
	global_load_dwordx4 v[122:125], v120, s[18:19] offset:16
	global_load_dwordx4 v[150:153], v120, s[16:17] offset:16
	v_and_b32_e32 v119, 64, v146
	v_xor_b32_e32 v118, 16, v146
	v_add_u32_e32 v119, 64, v119
	v_cmp_lt_i32_e32 vcc, v118, v119
	s_nop 1
	v_cndmask_b32_e32 v118, v146, v118, vcc
	v_lshlrev_b32_e32 v121, 2, v118
	ds_bpermute_b32 v118, v121, v112
	ds_bpermute_b32 v119, v121, v113
	ds_bpermute_b32 v126, v121, v114
	ds_bpermute_b32 v127, v121, v115
	s_waitcnt vmcnt(0) lgkmcnt(0)
	v_pk_mul_f32 v[118:119], v[122:123], v[118:119]
	v_pk_mul_f32 v[122:123], v[124:125], v[126:127]
	v_xor_b32_e32 v125, 0x80000000, v118
	v_xor_b32_e32 v121, 0x80000000, v122
	v_xor_b32_e32 v124, 0x80000000, v123
	v_xor_b32_e32 v126, 0x80000000, v119
	v_cndmask_b32_e64 v119, v119, v126, s[4:5]
	v_cndmask_b32_e64 v118, v118, v125, s[4:5]
	v_cndmask_b32_e64 v123, v123, v124, s[4:5]
	v_cndmask_b32_e64 v122, v122, v121, s[4:5]
	v_pk_fma_f32 v[114:115], v[114:115], v[152:153], v[122:123]
	v_pk_fma_f32 v[112:113], v[112:113], v[150:151], v[118:119]
.LBB0_1095:
	s_nop 0
	v_pk_mul_f32 v[112:113], v[112:113], s[40:41] op_sel_hi:[1,0]
	v_pk_mul_f32 v[114:115], v[114:115], s[40:41] op_sel_hi:[1,0]
	v_cvt_pk_bf16_f32 v118, v112, v113
	v_add_co_u32_e32 v112, vcc, 0x6000, v140
	v_cvt_pk_bf16_f32 v119, v114, v115
	s_nop 1
	v_addc_co_u32_e32 v113, vcc, 0, v141, vcc
	global_store_dwordx4 v[112:113], v[116:119], off
	v_or_b32_e32 v112, 32, v148
	v_mov_b32_e32 v113, s56
	v_cndmask_b32_e64 v112, v112, v113, s[6:7]
	v_lshlrev_b32_e32 v112, 3, v112
	v_and_b32_e32 v112, 0x1f8, v112
	s_and_b64 vcc, exec, s[8:9]
	v_lshlrev_b32_e32 v112, 2, v112
	s_cbranch_vccnz .LBB0_1097
	global_load_dwordx4 v[114:117], v112, s[18:19]
	global_load_dwordx4 v[122:125], v112, s[16:17]
	v_and_b32_e32 v118, 64, v146
	v_xor_b32_e32 v113, 16, v146
	v_add_u32_e32 v118, 64, v118
	v_cmp_lt_i32_e32 vcc, v113, v118
	s_nop 1
	v_cndmask_b32_e32 v113, v146, v113, vcc
	v_lshlrev_b32_e32 v113, 2, v113
	ds_bpermute_b32 v118, v113, v108
	ds_bpermute_b32 v119, v113, v109
	ds_bpermute_b32 v126, v113, v110
	ds_bpermute_b32 v127, v113, v111
	s_waitcnt vmcnt(0) lgkmcnt(0)
	v_pk_mul_f32 v[114:115], v[114:115], v[118:119]
	v_pk_mul_f32 v[116:117], v[116:117], v[126:127]
	v_xor_b32_e32 v119, 0x80000000, v114
	v_xor_b32_e32 v113, 0x80000000, v116
	v_xor_b32_e32 v118, 0x80000000, v117
	v_xor_b32_e32 v121, 0x80000000, v115
	v_cndmask_b32_e64 v115, v115, v121, s[4:5]
	v_cndmask_b32_e64 v114, v114, v119, s[4:5]
	v_cndmask_b32_e64 v117, v117, v118, s[4:5]
	v_cndmask_b32_e64 v116, v116, v113, s[4:5]
	v_pk_fma_f32 v[110:111], v[110:111], v[124:125], v[116:117]
	v_pk_fma_f32 v[108:109], v[108:109], v[122:123], v[114:115]
.LBB0_1097:
	s_nop 0
	v_pk_mul_f32 v[108:109], v[108:109], s[40:41] op_sel_hi:[1,0]
	s_and_b64 vcc, exec, s[8:9]
	v_pk_mul_f32 v[110:111], v[110:111], s[40:41] op_sel_hi:[1,0]
	v_cvt_pk_bf16_f32 v108, v108, v109
	s_nop 0
	v_cvt_pk_bf16_f32 v109, v110, v111
	s_cbranch_vccnz .LBB0_1099
	global_load_dwordx4 v[114:117], v112, s[18:19] offset:16
	global_load_dwordx4 v[122:125], v112, s[16:17] offset:16
	v_and_b32_e32 v111, 64, v146
	v_xor_b32_e32 v110, 16, v146
	v_add_u32_e32 v111, 64, v111
	v_cmp_lt_i32_e32 vcc, v110, v111
	s_nop 1
	v_cndmask_b32_e32 v110, v146, v110, vcc
	v_lshlrev_b32_e32 v113, 2, v110
	ds_bpermute_b32 v110, v113, v104
	ds_bpermute_b32 v111, v113, v105
	ds_bpermute_b32 v118, v113, v106
	ds_bpermute_b32 v119, v113, v107
	s_waitcnt vmcnt(0) lgkmcnt(0)
	v_pk_mul_f32 v[110:111], v[114:115], v[110:111]
	v_pk_mul_f32 v[114:115], v[116:117], v[118:119]
	v_xor_b32_e32 v117, 0x80000000, v110
	v_xor_b32_e32 v113, 0x80000000, v114
	v_xor_b32_e32 v116, 0x80000000, v115
	v_xor_b32_e32 v118, 0x80000000, v111
	v_cndmask_b32_e64 v111, v111, v118, s[4:5]
	v_cndmask_b32_e64 v110, v110, v117, s[4:5]
	v_cndmask_b32_e64 v115, v115, v116, s[4:5]
	v_cndmask_b32_e64 v114, v114, v113, s[4:5]
	v_pk_fma_f32 v[106:107], v[106:107], v[124:125], v[114:115]
	v_pk_fma_f32 v[104:105], v[104:105], v[122:123], v[110:111]
.LBB0_1099:
	s_nop 0
	v_pk_mul_f32 v[104:105], v[104:105], s[40:41] op_sel_hi:[1,0]
	v_pk_mul_f32 v[106:107], v[106:107], s[40:41] op_sel_hi:[1,0]
	v_cvt_pk_bf16_f32 v110, v104, v105
	v_add_co_u32_e32 v104, vcc, 0xc000, v140
	v_cvt_pk_bf16_f32 v111, v106, v107
	s_nop 1
	v_addc_co_u32_e32 v105, vcc, 0, v141, vcc
	global_store_dwordx4 v[104:105], v[108:111], off
	v_or_b32_e32 v104, 48, v148
	v_mov_b32_e32 v105, s56
	v_cndmask_b32_e64 v104, v104, v105, s[6:7]
	v_lshlrev_b32_e32 v104, 3, v104
	v_and_b32_e32 v104, 0x1f8, v104
	s_and_b64 vcc, exec, s[8:9]
	v_lshlrev_b32_e32 v104, 2, v104
	s_cbranch_vccnz .LBB0_1101
	global_load_dwordx4 v[106:109], v104, s[18:19]
	global_load_dwordx4 v[114:117], v104, s[16:17]
	v_and_b32_e32 v110, 64, v146
	v_xor_b32_e32 v105, 16, v146
	v_add_u32_e32 v110, 64, v110
	v_cmp_lt_i32_e32 vcc, v105, v110
	s_nop 1
	v_cndmask_b32_e32 v105, v146, v105, vcc
	v_lshlrev_b32_e32 v105, 2, v105
	ds_bpermute_b32 v110, v105, v100
	ds_bpermute_b32 v111, v105, v101
	ds_bpermute_b32 v118, v105, v102
	ds_bpermute_b32 v119, v105, v103
	s_waitcnt vmcnt(0) lgkmcnt(0)
	v_pk_mul_f32 v[106:107], v[106:107], v[110:111]
	v_pk_mul_f32 v[108:109], v[108:109], v[118:119]
	v_xor_b32_e32 v111, 0x80000000, v106
	v_xor_b32_e32 v105, 0x80000000, v108
	v_xor_b32_e32 v110, 0x80000000, v109
	v_xor_b32_e32 v113, 0x80000000, v107
	v_cndmask_b32_e64 v107, v107, v113, s[4:5]
	v_cndmask_b32_e64 v106, v106, v111, s[4:5]
	v_cndmask_b32_e64 v109, v109, v110, s[4:5]
	v_cndmask_b32_e64 v108, v108, v105, s[4:5]
	v_pk_fma_f32 v[102:103], v[102:103], v[116:117], v[108:109]
	v_pk_fma_f32 v[100:101], v[100:101], v[114:115], v[106:107]
.LBB0_1101:
	s_nop 0
	v_pk_mul_f32 v[100:101], v[100:101], s[40:41] op_sel_hi:[1,0]
	s_and_b64 vcc, exec, s[8:9]
	v_pk_mul_f32 v[102:103], v[102:103], s[40:41] op_sel_hi:[1,0]
	v_cvt_pk_bf16_f32 v100, v100, v101
	s_nop 0
	v_cvt_pk_bf16_f32 v101, v102, v103
	s_cbranch_vccnz .LBB0_1103
	global_load_dwordx4 v[106:109], v104, s[18:19] offset:16
	global_load_dwordx4 v[114:117], v104, s[16:17] offset:16
	v_and_b32_e32 v103, 64, v146
	v_xor_b32_e32 v102, 16, v146
	v_add_u32_e32 v103, 64, v103
	v_cmp_lt_i32_e32 vcc, v102, v103
	s_nop 1
	v_cndmask_b32_e32 v102, v146, v102, vcc
	v_lshlrev_b32_e32 v105, 2, v102
	ds_bpermute_b32 v102, v105, v96
	ds_bpermute_b32 v103, v105, v97
	ds_bpermute_b32 v110, v105, v98
	ds_bpermute_b32 v111, v105, v99
	s_waitcnt vmcnt(0) lgkmcnt(0)
	v_pk_mul_f32 v[102:103], v[106:107], v[102:103]
	v_pk_mul_f32 v[106:107], v[108:109], v[110:111]
	v_xor_b32_e32 v109, 0x80000000, v102
	v_xor_b32_e32 v105, 0x80000000, v106
	v_xor_b32_e32 v108, 0x80000000, v107
	v_xor_b32_e32 v110, 0x80000000, v103
	v_cndmask_b32_e64 v103, v103, v110, s[4:5]
	v_cndmask_b32_e64 v102, v102, v109, s[4:5]
	v_cndmask_b32_e64 v107, v107, v108, s[4:5]
	v_cndmask_b32_e64 v106, v106, v105, s[4:5]
	v_pk_fma_f32 v[98:99], v[98:99], v[116:117], v[106:107]
	v_pk_fma_f32 v[96:97], v[96:97], v[114:115], v[102:103]
.LBB0_1103:
	s_nop 0
	v_pk_mul_f32 v[96:97], v[96:97], s[40:41] op_sel_hi:[1,0]
	s_addk_i32 s45, 0x80
	v_cvt_pk_bf16_f32 v102, v96, v97
	v_add_co_u32_e32 v96, vcc, 0x12000, v140
	s_lshr_b32 s45, s45, 6
	s_nop 0
	v_addc_co_u32_e32 v97, vcc, 0, v141, vcc
	v_pk_mul_f32 v[98:99], v[98:99], s[40:41] op_sel_hi:[1,0]
	s_and_b64 vcc, exec, s[8:9]
	v_cvt_pk_bf16_f32 v103, v98, v99
	global_store_dwordx4 v[96:97], v[100:103], off
	v_mov_b32_e32 v96, s45
	v_cndmask_b32_e64 v96, v149, v96, s[6:7]
	v_lshlrev_b32_e32 v96, 3, v96
	v_and_b32_e32 v96, 0x1f8, v96
	v_lshlrev_b32_e32 v96, 2, v96
	s_cbranch_vccnz .LBB0_1105
	global_load_dwordx4 v[98:101], v96, s[18:19]
	global_load_dwordx4 v[106:109], v96, s[16:17]
	v_and_b32_e32 v102, 64, v146
	v_xor_b32_e32 v97, 16, v146
	v_add_u32_e32 v102, 64, v102
	v_cmp_lt_i32_e32 vcc, v97, v102
	s_nop 1
	v_cndmask_b32_e32 v97, v146, v97, vcc
	v_lshlrev_b32_e32 v97, 2, v97
	ds_bpermute_b32 v102, v97, v92
	ds_bpermute_b32 v103, v97, v93
	ds_bpermute_b32 v110, v97, v94
	ds_bpermute_b32 v111, v97, v95
	s_waitcnt vmcnt(0) lgkmcnt(0)
	v_pk_mul_f32 v[98:99], v[98:99], v[102:103]
	v_pk_mul_f32 v[100:101], v[100:101], v[110:111]
	v_xor_b32_e32 v103, 0x80000000, v98
	v_xor_b32_e32 v97, 0x80000000, v100
	v_xor_b32_e32 v102, 0x80000000, v101
	v_xor_b32_e32 v105, 0x80000000, v99
	v_cndmask_b32_e64 v99, v99, v105, s[4:5]
	v_cndmask_b32_e64 v98, v98, v103, s[4:5]
	v_cndmask_b32_e64 v101, v101, v102, s[4:5]
	v_cndmask_b32_e64 v100, v100, v97, s[4:5]
	v_pk_fma_f32 v[94:95], v[94:95], v[108:109], v[100:101]
	v_pk_fma_f32 v[92:93], v[92:93], v[106:107], v[98:99]
.LBB0_1105:
	s_nop 0
	v_pk_mul_f32 v[92:93], v[92:93], s[40:41] op_sel_hi:[1,0]
	s_and_b64 vcc, exec, s[8:9]
	v_pk_mul_f32 v[94:95], v[94:95], s[40:41] op_sel_hi:[1,0]
	v_cvt_pk_bf16_f32 v92, v92, v93
	s_nop 0
	v_cvt_pk_bf16_f32 v93, v94, v95
	s_cbranch_vccnz .LBB0_1107
	global_load_dwordx4 v[98:101], v96, s[18:19] offset:16
	global_load_dwordx4 v[106:109], v96, s[16:17] offset:16
	v_and_b32_e32 v95, 64, v146
	v_xor_b32_e32 v94, 16, v146
	v_add_u32_e32 v95, 64, v95
	v_cmp_lt_i32_e32 vcc, v94, v95
	s_nop 1
	v_cndmask_b32_e32 v94, v146, v94, vcc
	v_lshlrev_b32_e32 v97, 2, v94
	ds_bpermute_b32 v94, v97, v88
	ds_bpermute_b32 v95, v97, v89
	ds_bpermute_b32 v102, v97, v90
	ds_bpermute_b32 v103, v97, v91
	s_waitcnt vmcnt(0) lgkmcnt(0)
	v_pk_mul_f32 v[94:95], v[98:99], v[94:95]
	v_pk_mul_f32 v[98:99], v[100:101], v[102:103]
	v_xor_b32_e32 v101, 0x80000000, v94
	v_xor_b32_e32 v97, 0x80000000, v98
	v_xor_b32_e32 v100, 0x80000000, v99
	v_xor_b32_e32 v102, 0x80000000, v95
	v_cndmask_b32_e64 v95, v95, v102, s[4:5]
	v_cndmask_b32_e64 v94, v94, v101, s[4:5]
	v_cndmask_b32_e64 v99, v99, v100, s[4:5]
	v_cndmask_b32_e64 v98, v98, v97, s[4:5]
	v_pk_fma_f32 v[90:91], v[90:91], v[108:109], v[98:99]
	v_pk_fma_f32 v[88:89], v[88:89], v[106:107], v[94:95]
.LBB0_1107:
	s_nop 0
	v_pk_mul_f32 v[88:89], v[88:89], s[40:41] op_sel_hi:[1,0]
	v_pk_mul_f32 v[90:91], v[90:91], s[40:41] op_sel_hi:[1,0]
	v_cvt_pk_bf16_f32 v94, v88, v89
	v_add_co_u32_e32 v88, vcc, 0x30000, v140
	v_cvt_pk_bf16_f32 v95, v90, v91
	s_nop 1
	v_addc_co_u32_e32 v89, vcc, 0, v141, vcc
	global_store_dwordx4 v[88:89], v[92:95], off
	v_add_u32_e32 v88, 0x90, v148
	v_lshrrev_b32_e32 v89, 6, v88
	v_cndmask_b32_e64 v88, v88, v89, s[6:7]
	v_lshlrev_b32_e32 v88, 3, v88
	v_and_b32_e32 v88, 0x1f8, v88
	s_and_b64 vcc, exec, s[8:9]
	v_lshlrev_b32_e32 v88, 2, v88
	s_cbranch_vccnz .LBB0_1109
	global_load_dwordx4 v[90:93], v88, s[18:19]
	global_load_dwordx4 v[98:101], v88, s[16:17]
	v_and_b32_e32 v94, 64, v146
	v_xor_b32_e32 v89, 16, v146
	v_add_u32_e32 v94, 64, v94
	v_cmp_lt_i32_e32 vcc, v89, v94
	s_nop 1
	v_cndmask_b32_e32 v89, v146, v89, vcc
	v_lshlrev_b32_e32 v89, 2, v89
	ds_bpermute_b32 v94, v89, v84
	ds_bpermute_b32 v95, v89, v85
	ds_bpermute_b32 v102, v89, v86
	ds_bpermute_b32 v103, v89, v87
	s_waitcnt vmcnt(0) lgkmcnt(0)
	v_pk_mul_f32 v[90:91], v[90:91], v[94:95]
	v_pk_mul_f32 v[92:93], v[92:93], v[102:103]
	v_xor_b32_e32 v95, 0x80000000, v90
	v_xor_b32_e32 v89, 0x80000000, v92
	v_xor_b32_e32 v94, 0x80000000, v93
	v_xor_b32_e32 v97, 0x80000000, v91
	v_cndmask_b32_e64 v91, v91, v97, s[4:5]
	v_cndmask_b32_e64 v90, v90, v95, s[4:5]
	v_cndmask_b32_e64 v93, v93, v94, s[4:5]
	v_cndmask_b32_e64 v92, v92, v89, s[4:5]
	v_pk_fma_f32 v[86:87], v[86:87], v[100:101], v[92:93]
	v_pk_fma_f32 v[84:85], v[84:85], v[98:99], v[90:91]
.LBB0_1109:
	s_nop 0
	v_pk_mul_f32 v[84:85], v[84:85], s[40:41] op_sel_hi:[1,0]
	s_and_b64 vcc, exec, s[8:9]
	v_pk_mul_f32 v[86:87], v[86:87], s[40:41] op_sel_hi:[1,0]
	v_cvt_pk_bf16_f32 v84, v84, v85
	s_nop 0
	v_cvt_pk_bf16_f32 v85, v86, v87
	s_cbranch_vccnz .LBB0_1111
	global_load_dwordx4 v[90:93], v88, s[18:19] offset:16
	global_load_dwordx4 v[98:101], v88, s[16:17] offset:16
	v_and_b32_e32 v87, 64, v146
	v_xor_b32_e32 v86, 16, v146
	v_add_u32_e32 v87, 64, v87
	v_cmp_lt_i32_e32 vcc, v86, v87
	s_nop 1
	v_cndmask_b32_e32 v86, v146, v86, vcc
	v_lshlrev_b32_e32 v89, 2, v86
	ds_bpermute_b32 v86, v89, v80
	ds_bpermute_b32 v87, v89, v81
	ds_bpermute_b32 v94, v89, v82
	ds_bpermute_b32 v95, v89, v83
	s_waitcnt vmcnt(0) lgkmcnt(0)
	v_pk_mul_f32 v[86:87], v[90:91], v[86:87]
	v_pk_mul_f32 v[90:91], v[92:93], v[94:95]
	v_xor_b32_e32 v93, 0x80000000, v86
	v_xor_b32_e32 v89, 0x80000000, v90
	v_xor_b32_e32 v92, 0x80000000, v91
	v_xor_b32_e32 v94, 0x80000000, v87
	v_cndmask_b32_e64 v87, v87, v94, s[4:5]
	v_cndmask_b32_e64 v86, v86, v93, s[4:5]
	v_cndmask_b32_e64 v91, v91, v92, s[4:5]
	v_cndmask_b32_e64 v90, v90, v89, s[4:5]
	v_pk_fma_f32 v[82:83], v[82:83], v[100:101], v[90:91]
	v_pk_fma_f32 v[80:81], v[80:81], v[98:99], v[86:87]
.LBB0_1111:
	s_nop 0
	v_pk_mul_f32 v[80:81], v[80:81], s[40:41] op_sel_hi:[1,0]
	v_pk_mul_f32 v[82:83], v[82:83], s[40:41] op_sel_hi:[1,0]
	v_cvt_pk_bf16_f32 v86, v80, v81
	v_add_co_u32_e32 v80, vcc, 0x36000, v140
	v_cvt_pk_bf16_f32 v87, v82, v83
	s_nop 1
	v_addc_co_u32_e32 v81, vcc, 0, v141, vcc
	global_store_dwordx4 v[80:81], v[84:87], off
	v_add_u32_e32 v80, 0xa0, v148
	v_lshrrev_b32_e32 v81, 6, v80
	v_cndmask_b32_e64 v80, v80, v81, s[6:7]
	v_lshlrev_b32_e32 v80, 3, v80
	v_and_b32_e32 v80, 0x1f8, v80
	s_and_b64 vcc, exec, s[8:9]
	v_lshlrev_b32_e32 v80, 2, v80
	s_cbranch_vccnz .LBB0_1113
	global_load_dwordx4 v[82:85], v80, s[18:19]
	global_load_dwordx4 v[90:93], v80, s[16:17]
	v_and_b32_e32 v86, 64, v146
	v_xor_b32_e32 v81, 16, v146
	v_add_u32_e32 v86, 64, v86
	v_cmp_lt_i32_e32 vcc, v81, v86
	s_nop 1
	v_cndmask_b32_e32 v81, v146, v81, vcc
	v_lshlrev_b32_e32 v81, 2, v81
	ds_bpermute_b32 v86, v81, v76
	ds_bpermute_b32 v87, v81, v77
	ds_bpermute_b32 v94, v81, v78
	ds_bpermute_b32 v95, v81, v79
	s_waitcnt vmcnt(0) lgkmcnt(0)
	v_pk_mul_f32 v[82:83], v[82:83], v[86:87]
	v_pk_mul_f32 v[84:85], v[84:85], v[94:95]
	v_xor_b32_e32 v87, 0x80000000, v82
	v_xor_b32_e32 v81, 0x80000000, v84
	v_xor_b32_e32 v86, 0x80000000, v85
	v_xor_b32_e32 v89, 0x80000000, v83
	v_cndmask_b32_e64 v83, v83, v89, s[4:5]
	v_cndmask_b32_e64 v82, v82, v87, s[4:5]
	v_cndmask_b32_e64 v85, v85, v86, s[4:5]
	v_cndmask_b32_e64 v84, v84, v81, s[4:5]
	v_pk_fma_f32 v[78:79], v[78:79], v[92:93], v[84:85]
	v_pk_fma_f32 v[76:77], v[76:77], v[90:91], v[82:83]
.LBB0_1113:
	s_nop 0
	v_pk_mul_f32 v[76:77], v[76:77], s[40:41] op_sel_hi:[1,0]
	s_and_b64 vcc, exec, s[8:9]
	v_pk_mul_f32 v[78:79], v[78:79], s[40:41] op_sel_hi:[1,0]
	v_cvt_pk_bf16_f32 v76, v76, v77
	s_nop 0
	v_cvt_pk_bf16_f32 v77, v78, v79
	s_cbranch_vccnz .LBB0_1115
	global_load_dwordx4 v[82:85], v80, s[18:19] offset:16
	global_load_dwordx4 v[90:93], v80, s[16:17] offset:16
	v_and_b32_e32 v79, 64, v146
	v_xor_b32_e32 v78, 16, v146
	v_add_u32_e32 v79, 64, v79
	v_cmp_lt_i32_e32 vcc, v78, v79
	s_nop 1
	v_cndmask_b32_e32 v78, v146, v78, vcc
	v_lshlrev_b32_e32 v81, 2, v78
	ds_bpermute_b32 v78, v81, v72
	ds_bpermute_b32 v79, v81, v73
	ds_bpermute_b32 v86, v81, v74
	ds_bpermute_b32 v87, v81, v75
	s_waitcnt vmcnt(0) lgkmcnt(0)
	v_pk_mul_f32 v[78:79], v[82:83], v[78:79]
	v_pk_mul_f32 v[82:83], v[84:85], v[86:87]
	v_xor_b32_e32 v85, 0x80000000, v78
	v_xor_b32_e32 v81, 0x80000000, v82
	v_xor_b32_e32 v84, 0x80000000, v83
	v_xor_b32_e32 v86, 0x80000000, v79
	v_cndmask_b32_e64 v79, v79, v86, s[4:5]
	v_cndmask_b32_e64 v78, v78, v85, s[4:5]
	v_cndmask_b32_e64 v83, v83, v84, s[4:5]
	v_cndmask_b32_e64 v82, v82, v81, s[4:5]
	v_pk_fma_f32 v[74:75], v[74:75], v[92:93], v[82:83]
	v_pk_fma_f32 v[72:73], v[72:73], v[90:91], v[78:79]
.LBB0_1115:
	s_nop 0
	v_pk_mul_f32 v[72:73], v[72:73], s[40:41] op_sel_hi:[1,0]
	v_pk_mul_f32 v[74:75], v[74:75], s[40:41] op_sel_hi:[1,0]
	v_cvt_pk_bf16_f32 v78, v72, v73
	v_add_co_u32_e32 v72, vcc, 0x3c000, v140
	v_cvt_pk_bf16_f32 v79, v74, v75
	s_nop 1
	v_addc_co_u32_e32 v73, vcc, 0, v141, vcc
	global_store_dwordx4 v[72:73], v[76:79], off
	v_add_u32_e32 v72, 0xb0, v148
	v_lshrrev_b32_e32 v73, 6, v72
	v_cndmask_b32_e64 v72, v72, v73, s[6:7]
	v_lshlrev_b32_e32 v72, 3, v72
	v_and_b32_e32 v72, 0x1f8, v72
	s_and_b64 vcc, exec, s[8:9]
	v_lshlrev_b32_e32 v72, 2, v72
	s_cbranch_vccnz .LBB0_1117
	global_load_dwordx4 v[74:77], v72, s[18:19]
	global_load_dwordx4 v[82:85], v72, s[16:17]
	v_and_b32_e32 v78, 64, v146
	v_xor_b32_e32 v73, 16, v146
	v_add_u32_e32 v78, 64, v78
	v_cmp_lt_i32_e32 vcc, v73, v78
	s_nop 1
	v_cndmask_b32_e32 v73, v146, v73, vcc
	v_lshlrev_b32_e32 v73, 2, v73
	ds_bpermute_b32 v78, v73, v68
	ds_bpermute_b32 v79, v73, v69
	ds_bpermute_b32 v86, v73, v70
	ds_bpermute_b32 v87, v73, v71
	s_waitcnt vmcnt(0) lgkmcnt(0)
	v_pk_mul_f32 v[74:75], v[74:75], v[78:79]
	v_pk_mul_f32 v[76:77], v[76:77], v[86:87]
	v_xor_b32_e32 v79, 0x80000000, v74
	v_xor_b32_e32 v73, 0x80000000, v76
	v_xor_b32_e32 v78, 0x80000000, v77
	v_xor_b32_e32 v81, 0x80000000, v75
	v_cndmask_b32_e64 v75, v75, v81, s[4:5]
	v_cndmask_b32_e64 v74, v74, v79, s[4:5]
	v_cndmask_b32_e64 v77, v77, v78, s[4:5]
	v_cndmask_b32_e64 v76, v76, v73, s[4:5]
	v_pk_fma_f32 v[70:71], v[70:71], v[84:85], v[76:77]
	v_pk_fma_f32 v[68:69], v[68:69], v[82:83], v[74:75]
.LBB0_1117:
	s_nop 0
	v_pk_mul_f32 v[68:69], v[68:69], s[40:41] op_sel_hi:[1,0]
	s_and_b64 vcc, exec, s[8:9]
	v_pk_mul_f32 v[70:71], v[70:71], s[40:41] op_sel_hi:[1,0]
	v_cvt_pk_bf16_f32 v68, v68, v69
	s_nop 0
	v_cvt_pk_bf16_f32 v69, v70, v71
	s_cbranch_vccnz .LBB0_1119
	global_load_dwordx4 v[74:77], v72, s[18:19] offset:16
	global_load_dwordx4 v[82:85], v72, s[16:17] offset:16
	v_and_b32_e32 v71, 64, v146
	v_xor_b32_e32 v70, 16, v146
	v_add_u32_e32 v71, 64, v71
	v_cmp_lt_i32_e32 vcc, v70, v71
	s_nop 1
	v_cndmask_b32_e32 v70, v146, v70, vcc
	v_lshlrev_b32_e32 v73, 2, v70
	ds_bpermute_b32 v70, v73, v64
	ds_bpermute_b32 v71, v73, v65
	ds_bpermute_b32 v78, v73, v66
	ds_bpermute_b32 v79, v73, v67
	s_waitcnt vmcnt(0) lgkmcnt(0)
	v_pk_mul_f32 v[70:71], v[74:75], v[70:71]
	v_pk_mul_f32 v[74:75], v[76:77], v[78:79]
	v_xor_b32_e32 v77, 0x80000000, v70
	v_xor_b32_e32 v73, 0x80000000, v74
	v_xor_b32_e32 v76, 0x80000000, v75
	v_xor_b32_e32 v78, 0x80000000, v71
	v_cndmask_b32_e64 v71, v71, v78, s[4:5]
	v_cndmask_b32_e64 v70, v70, v77, s[4:5]
	v_cndmask_b32_e64 v75, v75, v76, s[4:5]
	v_cndmask_b32_e64 v74, v74, v73, s[4:5]
	v_pk_fma_f32 v[66:67], v[66:67], v[84:85], v[74:75]
	v_pk_fma_f32 v[64:65], v[64:65], v[82:83], v[70:71]
.LBB0_1119:
	s_or_b32 s6, s43, 4
	v_pk_mul_f32 v[64:65], v[64:65], s[40:41] op_sel_hi:[1,0]
	s_mul_hi_i32 s7, s6, 0x55555556
	v_cvt_pk_bf16_f32 v70, v64, v65
	v_add_co_u32_e32 v64, vcc, 0x42000, v140
	s_lshr_b32 s8, s7, 31
	s_nop 0
	v_addc_co_u32_e32 v65, vcc, 0, v141, vcc
	s_add_i32 s7, s7, s8
	v_pk_mul_f32 v[66:67], v[66:67], s[40:41] op_sel_hi:[1,0]
	s_mul_i32 s7, s7, 3
	v_cvt_pk_bf16_f32 v71, v66, v67
	global_store_dwordx4 v[64:65], v[68:71], off
	s_sub_i32 s6, s6, s7
	s_cmp_eq_u32 s6, 2
	s_cselect_b64 s[8:9], -1, 0
	s_cmp_lg_u32 s6, 2
	s_cbranch_scc1 .LBB0_1121
	global_load_dwordx4 v[64:67], v147, s[18:19]
	global_load_dwordx4 v[68:71], v147, s[16:17]
	v_and_b32_e32 v74, 64, v146
	v_xor_b32_e32 v73, 16, v146
	v_add_u32_e32 v74, 64, v74
	v_cmp_lt_i32_e32 vcc, v73, v74
	s_nop 1
	v_cndmask_b32_e32 v73, v146, v73, vcc
	v_lshlrev_b32_e32 v73, 2, v73
	ds_bpermute_b32 v74, v73, v60
	ds_bpermute_b32 v75, v73, v61
	ds_bpermute_b32 v76, v73, v62
	ds_bpermute_b32 v77, v73, v63
	s_waitcnt vmcnt(0) lgkmcnt(0)
	v_pk_mul_f32 v[64:65], v[64:65], v[74:75]
	v_pk_mul_f32 v[66:67], v[66:67], v[76:77]
	v_xor_b32_e32 v75, 0x80000000, v64
	v_xor_b32_e32 v73, 0x80000000, v66
	v_xor_b32_e32 v74, 0x80000000, v67
	v_xor_b32_e32 v76, 0x80000000, v65
	v_cndmask_b32_e64 v65, v65, v76, s[4:5]
	v_cndmask_b32_e64 v64, v64, v75, s[4:5]
	v_cndmask_b32_e64 v67, v67, v74, s[4:5]
	v_cndmask_b32_e64 v66, v66, v73, s[4:5]
	v_pk_fma_f32 v[62:63], v[62:63], v[70:71], v[66:67]
	v_pk_fma_f32 v[60:61], v[60:61], v[68:69], v[64:65]
.LBB0_1121:
	s_nop 0
	v_pk_mul_f32 v[60:61], v[60:61], s[40:41] op_sel_hi:[1,0]
	s_andn2_b64 vcc, exec, s[8:9]
	v_cvt_pk_bf16_f32 v60, v60, v61
	v_cndmask_b32_e64 v61, 0, 1, s[8:9]
	v_cmp_ne_u32_e64 s[6:7], 1, v61
	v_pk_mul_f32 v[62:63], v[62:63], s[40:41] op_sel_hi:[1,0]
	s_nop 0
	v_cvt_pk_bf16_f32 v61, v62, v63
	s_cbranch_vccnz .LBB0_1123
	global_load_dwordx4 v[62:65], v147, s[18:19] offset:16
	global_load_dwordx4 v[66:69], v147, s[16:17] offset:16
	v_and_b32_e32 v71, 64, v146
	v_xor_b32_e32 v70, 16, v146
	v_add_u32_e32 v71, 64, v71
	v_cmp_lt_i32_e32 vcc, v70, v71
	s_nop 1
	v_cndmask_b32_e32 v70, v146, v70, vcc
	v_lshlrev_b32_e32 v73, 2, v70
	ds_bpermute_b32 v70, v73, v56
	ds_bpermute_b32 v71, v73, v57
	ds_bpermute_b32 v74, v73, v58
	ds_bpermute_b32 v75, v73, v59
	s_waitcnt vmcnt(0) lgkmcnt(0)
	v_pk_mul_f32 v[62:63], v[62:63], v[70:71]
	v_pk_mul_f32 v[64:65], v[64:65], v[74:75]
	v_xor_b32_e32 v73, 0x80000000, v62
	v_xor_b32_e32 v70, 0x80000000, v64
	v_xor_b32_e32 v71, 0x80000000, v65
	v_xor_b32_e32 v74, 0x80000000, v63
	v_cndmask_b32_e64 v63, v63, v74, s[4:5]
	v_cndmask_b32_e64 v62, v62, v73, s[4:5]
	v_cndmask_b32_e64 v65, v65, v71, s[4:5]
	v_cndmask_b32_e64 v64, v64, v70, s[4:5]
	v_pk_fma_f32 v[58:59], v[58:59], v[68:69], v[64:65]
	v_pk_fma_f32 v[56:57], v[56:57], v[66:67], v[62:63]
.LBB0_1123:
	v_pk_mul_f32 v[58:59], v[58:59], s[40:41] op_sel_hi:[1,0]
	v_pk_mul_f32 v[56:57], v[56:57], s[40:41] op_sel_hi:[1,0]
	s_and_b64 vcc, exec, s[6:7]
	v_cvt_pk_bf16_f32 v62, v56, v57
	v_cvt_pk_bf16_f32 v63, v58, v59
	global_store_dwordx4 v[140:141], v[60:63], off offset:256
	s_cbranch_vccnz .LBB0_1125
	global_load_dwordx4 v[56:59], v120, s[18:19]
	global_load_dwordx4 v[60:63], v120, s[16:17]
	v_and_b32_e32 v65, 64, v146
	v_xor_b32_e32 v64, 16, v146
	v_add_u32_e32 v65, 64, v65
	v_cmp_lt_i32_e32 vcc, v64, v65
	s_nop 1
	v_cndmask_b32_e32 v64, v146, v64, vcc
	v_lshlrev_b32_e32 v67, 2, v64
	ds_bpermute_b32 v64, v67, v52
	ds_bpermute_b32 v65, v67, v53
	ds_bpermute_b32 v66, v67, v54
	ds_bpermute_b32 v67, v67, v55
	s_waitcnt vmcnt(0) lgkmcnt(0)
	v_pk_mul_f32 v[56:57], v[56:57], v[64:65]
	v_pk_mul_f32 v[58:59], v[58:59], v[66:67]
	v_xor_b32_e32 v66, 0x80000000, v56
	v_xor_b32_e32 v64, 0x80000000, v58
	v_xor_b32_e32 v65, 0x80000000, v59
	v_xor_b32_e32 v67, 0x80000000, v57
	v_cndmask_b32_e64 v57, v57, v67, s[4:5]
	v_cndmask_b32_e64 v56, v56, v66, s[4:5]
	v_cndmask_b32_e64 v59, v59, v65, s[4:5]
	v_cndmask_b32_e64 v58, v58, v64, s[4:5]
	v_pk_fma_f32 v[54:55], v[54:55], v[62:63], v[58:59]
	v_pk_fma_f32 v[52:53], v[52:53], v[60:61], v[56:57]
.LBB0_1125:
	s_nop 0
	v_pk_mul_f32 v[52:53], v[52:53], s[40:41] op_sel_hi:[1,0]
	s_and_b64 vcc, exec, s[6:7]
	v_pk_mul_f32 v[54:55], v[54:55], s[40:41] op_sel_hi:[1,0]
	v_cvt_pk_bf16_f32 v52, v52, v53
	s_nop 0
	v_cvt_pk_bf16_f32 v53, v54, v55
	s_cbranch_vccnz .LBB0_1127
	global_load_dwordx4 v[54:57], v120, s[18:19] offset:16
	global_load_dwordx4 v[58:61], v120, s[16:17] offset:16
	v_and_b32_e32 v63, 64, v146
	v_xor_b32_e32 v62, 16, v146
	v_add_u32_e32 v63, 64, v63
	v_cmp_lt_i32_e32 vcc, v62, v63
	s_nop 1
	v_cndmask_b32_e32 v62, v146, v62, vcc
	v_lshlrev_b32_e32 v65, 2, v62
	ds_bpermute_b32 v62, v65, v48
	ds_bpermute_b32 v63, v65, v49
	ds_bpermute_b32 v64, v65, v50
	ds_bpermute_b32 v65, v65, v51
	s_waitcnt vmcnt(0) lgkmcnt(0)
	v_pk_mul_f32 v[54:55], v[54:55], v[62:63]
	v_pk_mul_f32 v[56:57], v[56:57], v[64:65]
	v_xor_b32_e32 v64, 0x80000000, v54
	v_xor_b32_e32 v62, 0x80000000, v56
	v_xor_b32_e32 v63, 0x80000000, v57
	v_xor_b32_e32 v65, 0x80000000, v55
	v_cndmask_b32_e64 v55, v55, v65, s[4:5]
	v_cndmask_b32_e64 v54, v54, v64, s[4:5]
	v_cndmask_b32_e64 v57, v57, v63, s[4:5]
	v_cndmask_b32_e64 v56, v56, v62, s[4:5]
	v_pk_fma_f32 v[50:51], v[50:51], v[60:61], v[56:57]
	v_pk_fma_f32 v[48:49], v[48:49], v[58:59], v[54:55]
.LBB0_1127:
	s_nop 0
	v_pk_mul_f32 v[48:49], v[48:49], s[40:41] op_sel_hi:[1,0]
	v_pk_mul_f32 v[50:51], v[50:51], s[40:41] op_sel_hi:[1,0]
	v_cvt_pk_bf16_f32 v54, v48, v49
	v_add_co_u32_e32 v48, vcc, 0x6000, v140
	v_cvt_pk_bf16_f32 v55, v50, v51
	s_nop 1
	v_addc_co_u32_e32 v49, vcc, 0, v141, vcc
	global_store_dwordx4 v[48:49], v[52:55], off offset:256
	s_and_b64 vcc, exec, s[6:7]
	s_cbranch_vccnz .LBB0_1129
	global_load_dwordx4 v[48:51], v112, s[18:19]
	global_load_dwordx4 v[52:55], v112, s[16:17]
	v_and_b32_e32 v57, 64, v146
	v_xor_b32_e32 v56, 16, v146
	v_add_u32_e32 v57, 64, v57
	v_cmp_lt_i32_e32 vcc, v56, v57
	s_nop 1
	v_cndmask_b32_e32 v56, v146, v56, vcc
	v_lshlrev_b32_e32 v59, 2, v56
	ds_bpermute_b32 v56, v59, v44
	ds_bpermute_b32 v57, v59, v45
	ds_bpermute_b32 v58, v59, v46
	ds_bpermute_b32 v59, v59, v47
	s_waitcnt vmcnt(0) lgkmcnt(0)
	v_pk_mul_f32 v[48:49], v[48:49], v[56:57]
	v_pk_mul_f32 v[50:51], v[50:51], v[58:59]
	v_xor_b32_e32 v58, 0x80000000, v48
	v_xor_b32_e32 v56, 0x80000000, v50
	v_xor_b32_e32 v57, 0x80000000, v51
	v_xor_b32_e32 v59, 0x80000000, v49
	v_cndmask_b32_e64 v49, v49, v59, s[4:5]
	v_cndmask_b32_e64 v48, v48, v58, s[4:5]
	v_cndmask_b32_e64 v51, v51, v57, s[4:5]
	v_cndmask_b32_e64 v50, v50, v56, s[4:5]
	v_pk_fma_f32 v[46:47], v[46:47], v[54:55], v[50:51]
	v_pk_fma_f32 v[44:45], v[44:45], v[52:53], v[48:49]
.LBB0_1129:
	s_nop 0
	v_pk_mul_f32 v[44:45], v[44:45], s[40:41] op_sel_hi:[1,0]
	s_and_b64 vcc, exec, s[6:7]
	v_pk_mul_f32 v[46:47], v[46:47], s[40:41] op_sel_hi:[1,0]
	v_cvt_pk_bf16_f32 v44, v44, v45
	s_nop 0
	v_cvt_pk_bf16_f32 v45, v46, v47
	s_cbranch_vccnz .LBB0_1131
	global_load_dwordx4 v[46:49], v112, s[18:19] offset:16
	global_load_dwordx4 v[50:53], v112, s[16:17] offset:16
	v_and_b32_e32 v55, 64, v146
	v_xor_b32_e32 v54, 16, v146
	v_add_u32_e32 v55, 64, v55
	v_cmp_lt_i32_e32 vcc, v54, v55
	s_nop 1
	v_cndmask_b32_e32 v54, v146, v54, vcc
	v_lshlrev_b32_e32 v57, 2, v54
	ds_bpermute_b32 v54, v57, v40
	ds_bpermute_b32 v55, v57, v41
	ds_bpermute_b32 v56, v57, v42
	ds_bpermute_b32 v57, v57, v43
	s_waitcnt vmcnt(0) lgkmcnt(0)
	v_pk_mul_f32 v[46:47], v[46:47], v[54:55]
	v_pk_mul_f32 v[48:49], v[48:49], v[56:57]
	v_xor_b32_e32 v56, 0x80000000, v46
	v_xor_b32_e32 v54, 0x80000000, v48
	v_xor_b32_e32 v55, 0x80000000, v49
	v_xor_b32_e32 v57, 0x80000000, v47
	v_cndmask_b32_e64 v47, v47, v57, s[4:5]
	v_cndmask_b32_e64 v46, v46, v56, s[4:5]
	v_cndmask_b32_e64 v49, v49, v55, s[4:5]
	v_cndmask_b32_e64 v48, v48, v54, s[4:5]
	v_pk_fma_f32 v[42:43], v[42:43], v[52:53], v[48:49]
	v_pk_fma_f32 v[40:41], v[40:41], v[50:51], v[46:47]
.LBB0_1131:
	s_nop 0
	v_pk_mul_f32 v[40:41], v[40:41], s[40:41] op_sel_hi:[1,0]
	v_pk_mul_f32 v[42:43], v[42:43], s[40:41] op_sel_hi:[1,0]
	v_cvt_pk_bf16_f32 v46, v40, v41
	v_add_co_u32_e32 v40, vcc, 0xc000, v140
	v_cvt_pk_bf16_f32 v47, v42, v43
	s_nop 1
	v_addc_co_u32_e32 v41, vcc, 0, v141, vcc
	global_store_dwordx4 v[40:41], v[44:47], off offset:256
	s_and_b64 vcc, exec, s[6:7]
	s_cbranch_vccnz .LBB0_1133
	global_load_dwordx4 v[40:43], v104, s[18:19]
	global_load_dwordx4 v[44:47], v104, s[16:17]
	v_and_b32_e32 v49, 64, v146
	v_xor_b32_e32 v48, 16, v146
	v_add_u32_e32 v49, 64, v49
	v_cmp_lt_i32_e32 vcc, v48, v49
	s_nop 1
	v_cndmask_b32_e32 v48, v146, v48, vcc
	v_lshlrev_b32_e32 v51, 2, v48
	ds_bpermute_b32 v48, v51, v36
	ds_bpermute_b32 v49, v51, v37
	ds_bpermute_b32 v50, v51, v38
	ds_bpermute_b32 v51, v51, v39
	s_waitcnt vmcnt(0) lgkmcnt(0)
	v_pk_mul_f32 v[40:41], v[40:41], v[48:49]
	v_pk_mul_f32 v[42:43], v[42:43], v[50:51]
	v_xor_b32_e32 v50, 0x80000000, v40
	v_xor_b32_e32 v48, 0x80000000, v42
	v_xor_b32_e32 v49, 0x80000000, v43
	v_xor_b32_e32 v51, 0x80000000, v41
	v_cndmask_b32_e64 v41, v41, v51, s[4:5]
	v_cndmask_b32_e64 v40, v40, v50, s[4:5]
	v_cndmask_b32_e64 v43, v43, v49, s[4:5]
	v_cndmask_b32_e64 v42, v42, v48, s[4:5]
	v_pk_fma_f32 v[38:39], v[38:39], v[46:47], v[42:43]
	v_pk_fma_f32 v[36:37], v[36:37], v[44:45], v[40:41]
.LBB0_1133:
	s_nop 0
	v_pk_mul_f32 v[36:37], v[36:37], s[40:41] op_sel_hi:[1,0]
	s_and_b64 vcc, exec, s[6:7]
	v_pk_mul_f32 v[38:39], v[38:39], s[40:41] op_sel_hi:[1,0]
	v_cvt_pk_bf16_f32 v36, v36, v37
	s_nop 0
	v_cvt_pk_bf16_f32 v37, v38, v39
	s_cbranch_vccnz .LBB0_1135
	global_load_dwordx4 v[38:41], v104, s[18:19] offset:16
	global_load_dwordx4 v[42:45], v104, s[16:17] offset:16
	v_and_b32_e32 v47, 64, v146
	v_xor_b32_e32 v46, 16, v146
	v_add_u32_e32 v47, 64, v47
	v_cmp_lt_i32_e32 vcc, v46, v47
	s_nop 1
	v_cndmask_b32_e32 v46, v146, v46, vcc
	v_lshlrev_b32_e32 v49, 2, v46
	ds_bpermute_b32 v46, v49, v32
	ds_bpermute_b32 v47, v49, v33
	ds_bpermute_b32 v48, v49, v34
	ds_bpermute_b32 v49, v49, v35
	s_waitcnt vmcnt(0) lgkmcnt(0)
	v_pk_mul_f32 v[38:39], v[38:39], v[46:47]
	v_pk_mul_f32 v[40:41], v[40:41], v[48:49]
	v_xor_b32_e32 v48, 0x80000000, v38
	v_xor_b32_e32 v46, 0x80000000, v40
	v_xor_b32_e32 v47, 0x80000000, v41
	v_xor_b32_e32 v49, 0x80000000, v39
	v_cndmask_b32_e64 v39, v39, v49, s[4:5]
	v_cndmask_b32_e64 v38, v38, v48, s[4:5]
	v_cndmask_b32_e64 v41, v41, v47, s[4:5]
	v_cndmask_b32_e64 v40, v40, v46, s[4:5]
	v_pk_fma_f32 v[34:35], v[34:35], v[44:45], v[40:41]
	v_pk_fma_f32 v[32:33], v[32:33], v[42:43], v[38:39]
.LBB0_1135:
	s_nop 0
	v_pk_mul_f32 v[32:33], v[32:33], s[40:41] op_sel_hi:[1,0]
	v_pk_mul_f32 v[34:35], v[34:35], s[40:41] op_sel_hi:[1,0]
	v_cvt_pk_bf16_f32 v38, v32, v33
	v_add_co_u32_e32 v32, vcc, 0x12000, v140
	v_cvt_pk_bf16_f32 v39, v34, v35
	s_nop 1
	v_addc_co_u32_e32 v33, vcc, 0, v141, vcc
	global_store_dwordx4 v[32:33], v[36:39], off offset:256
	s_and_b64 vcc, exec, s[6:7]
	s_cbranch_vccnz .LBB0_1137
	global_load_dwordx4 v[32:35], v96, s[18:19]
	global_load_dwordx4 v[36:39], v96, s[16:17]
	v_and_b32_e32 v41, 64, v146
	v_xor_b32_e32 v40, 16, v146
	v_add_u32_e32 v41, 64, v41
	v_cmp_lt_i32_e32 vcc, v40, v41
	s_nop 1
	v_cndmask_b32_e32 v40, v146, v40, vcc
	v_lshlrev_b32_e32 v43, 2, v40
	ds_bpermute_b32 v40, v43, v28
	ds_bpermute_b32 v41, v43, v29
	ds_bpermute_b32 v42, v43, v30
	ds_bpermute_b32 v43, v43, v31
	s_waitcnt vmcnt(0) lgkmcnt(0)
	v_pk_mul_f32 v[32:33], v[32:33], v[40:41]
	v_pk_mul_f32 v[34:35], v[34:35], v[42:43]
	v_xor_b32_e32 v42, 0x80000000, v32
	v_xor_b32_e32 v40, 0x80000000, v34
	v_xor_b32_e32 v41, 0x80000000, v35
	v_xor_b32_e32 v43, 0x80000000, v33
	v_cndmask_b32_e64 v33, v33, v43, s[4:5]
	v_cndmask_b32_e64 v32, v32, v42, s[4:5]
	v_cndmask_b32_e64 v35, v35, v41, s[4:5]
	v_cndmask_b32_e64 v34, v34, v40, s[4:5]
	v_pk_fma_f32 v[30:31], v[30:31], v[38:39], v[34:35]
	v_pk_fma_f32 v[28:29], v[28:29], v[36:37], v[32:33]
.LBB0_1137:
	s_nop 0
	v_pk_mul_f32 v[28:29], v[28:29], s[40:41] op_sel_hi:[1,0]
	s_and_b64 vcc, exec, s[6:7]
	v_pk_mul_f32 v[30:31], v[30:31], s[40:41] op_sel_hi:[1,0]
	v_cvt_pk_bf16_f32 v28, v28, v29
	s_nop 0
	v_cvt_pk_bf16_f32 v29, v30, v31
	s_cbranch_vccnz .LBB0_1139
	global_load_dwordx4 v[30:33], v96, s[18:19] offset:16
	global_load_dwordx4 v[34:37], v96, s[16:17] offset:16
	v_and_b32_e32 v39, 64, v146
	v_xor_b32_e32 v38, 16, v146
	v_add_u32_e32 v39, 64, v39
	v_cmp_lt_i32_e32 vcc, v38, v39
	s_nop 1
	v_cndmask_b32_e32 v38, v146, v38, vcc
	v_lshlrev_b32_e32 v41, 2, v38
	ds_bpermute_b32 v38, v41, v24
	ds_bpermute_b32 v39, v41, v25
	ds_bpermute_b32 v40, v41, v26
	ds_bpermute_b32 v41, v41, v27
	s_waitcnt vmcnt(0) lgkmcnt(0)
	v_pk_mul_f32 v[30:31], v[30:31], v[38:39]
	v_pk_mul_f32 v[32:33], v[32:33], v[40:41]
	v_xor_b32_e32 v40, 0x80000000, v30
	v_xor_b32_e32 v38, 0x80000000, v32
	v_xor_b32_e32 v39, 0x80000000, v33
	v_xor_b32_e32 v41, 0x80000000, v31
	v_cndmask_b32_e64 v31, v31, v41, s[4:5]
	v_cndmask_b32_e64 v30, v30, v40, s[4:5]
	v_cndmask_b32_e64 v33, v33, v39, s[4:5]
	v_cndmask_b32_e64 v32, v32, v38, s[4:5]
	v_pk_fma_f32 v[26:27], v[26:27], v[36:37], v[32:33]
	v_pk_fma_f32 v[24:25], v[24:25], v[34:35], v[30:31]
.LBB0_1139:
	s_nop 0
	v_pk_mul_f32 v[24:25], v[24:25], s[40:41] op_sel_hi:[1,0]
	v_pk_mul_f32 v[26:27], v[26:27], s[40:41] op_sel_hi:[1,0]
	v_cvt_pk_bf16_f32 v30, v24, v25
	v_add_co_u32_e32 v24, vcc, 0x30000, v140
	v_cvt_pk_bf16_f32 v31, v26, v27
	s_nop 1
	v_addc_co_u32_e32 v25, vcc, 0, v141, vcc
	global_store_dwordx4 v[24:25], v[28:31], off offset:256
	s_and_b64 vcc, exec, s[6:7]
	s_cbranch_vccnz .LBB0_1141
	global_load_dwordx4 v[24:27], v88, s[18:19]
	global_load_dwordx4 v[28:31], v88, s[16:17]
	v_and_b32_e32 v33, 64, v146
	v_xor_b32_e32 v32, 16, v146
	v_add_u32_e32 v33, 64, v33
	v_cmp_lt_i32_e32 vcc, v32, v33
	s_nop 1
	v_cndmask_b32_e32 v32, v146, v32, vcc
	v_lshlrev_b32_e32 v35, 2, v32
	ds_bpermute_b32 v32, v35, v20
	ds_bpermute_b32 v33, v35, v21
	ds_bpermute_b32 v34, v35, v22
	ds_bpermute_b32 v35, v35, v23
	s_waitcnt vmcnt(0) lgkmcnt(0)
	v_pk_mul_f32 v[24:25], v[24:25], v[32:33]
	v_pk_mul_f32 v[26:27], v[26:27], v[34:35]
	v_xor_b32_e32 v34, 0x80000000, v24
	v_xor_b32_e32 v32, 0x80000000, v26
	v_xor_b32_e32 v33, 0x80000000, v27
	v_xor_b32_e32 v35, 0x80000000, v25
	v_cndmask_b32_e64 v25, v25, v35, s[4:5]
	v_cndmask_b32_e64 v24, v24, v34, s[4:5]
	v_cndmask_b32_e64 v27, v27, v33, s[4:5]
	v_cndmask_b32_e64 v26, v26, v32, s[4:5]
	v_pk_fma_f32 v[22:23], v[22:23], v[30:31], v[26:27]
	v_pk_fma_f32 v[20:21], v[20:21], v[28:29], v[24:25]
.LBB0_1141:
	s_nop 0
	v_pk_mul_f32 v[20:21], v[20:21], s[40:41] op_sel_hi:[1,0]
	s_and_b64 vcc, exec, s[6:7]
	v_pk_mul_f32 v[22:23], v[22:23], s[40:41] op_sel_hi:[1,0]
	v_cvt_pk_bf16_f32 v20, v20, v21
	s_nop 0
	v_cvt_pk_bf16_f32 v21, v22, v23
	s_cbranch_vccnz .LBB0_1143
	global_load_dwordx4 v[22:25], v88, s[18:19] offset:16
	global_load_dwordx4 v[26:29], v88, s[16:17] offset:16
	v_and_b32_e32 v31, 64, v146
	v_xor_b32_e32 v30, 16, v146
	v_add_u32_e32 v31, 64, v31
	v_cmp_lt_i32_e32 vcc, v30, v31
	s_nop 1
	v_cndmask_b32_e32 v30, v146, v30, vcc
	v_lshlrev_b32_e32 v33, 2, v30
	ds_bpermute_b32 v30, v33, v16
	ds_bpermute_b32 v31, v33, v17
	ds_bpermute_b32 v32, v33, v18
	ds_bpermute_b32 v33, v33, v19
	s_waitcnt vmcnt(0) lgkmcnt(0)
	v_pk_mul_f32 v[22:23], v[22:23], v[30:31]
	v_pk_mul_f32 v[24:25], v[24:25], v[32:33]
	v_xor_b32_e32 v32, 0x80000000, v22
	v_xor_b32_e32 v30, 0x80000000, v24
	v_xor_b32_e32 v31, 0x80000000, v25
	v_xor_b32_e32 v33, 0x80000000, v23
	v_cndmask_b32_e64 v23, v23, v33, s[4:5]
	v_cndmask_b32_e64 v22, v22, v32, s[4:5]
	v_cndmask_b32_e64 v25, v25, v31, s[4:5]
	v_cndmask_b32_e64 v24, v24, v30, s[4:5]
	v_pk_fma_f32 v[18:19], v[18:19], v[28:29], v[24:25]
	v_pk_fma_f32 v[16:17], v[16:17], v[26:27], v[22:23]
.LBB0_1143:
	s_nop 0
	v_pk_mul_f32 v[16:17], v[16:17], s[40:41] op_sel_hi:[1,0]
	v_pk_mul_f32 v[18:19], v[18:19], s[40:41] op_sel_hi:[1,0]
	v_cvt_pk_bf16_f32 v22, v16, v17
	v_add_co_u32_e32 v16, vcc, 0x36000, v140
	v_cvt_pk_bf16_f32 v23, v18, v19
	s_nop 1
	v_addc_co_u32_e32 v17, vcc, 0, v141, vcc
	global_store_dwordx4 v[16:17], v[20:23], off offset:256
	s_and_b64 vcc, exec, s[6:7]
	s_cbranch_vccnz .LBB0_1145
	global_load_dwordx4 v[16:19], v80, s[18:19]
	global_load_dwordx4 v[20:23], v80, s[16:17]
	v_and_b32_e32 v25, 64, v146
	v_xor_b32_e32 v24, 16, v146
	v_add_u32_e32 v25, 64, v25
	v_cmp_lt_i32_e32 vcc, v24, v25
	s_nop 1
	v_cndmask_b32_e32 v24, v146, v24, vcc
	v_lshlrev_b32_e32 v27, 2, v24
	ds_bpermute_b32 v24, v27, v12
	ds_bpermute_b32 v25, v27, v13
	ds_bpermute_b32 v26, v27, v14
	ds_bpermute_b32 v27, v27, v15
	s_waitcnt vmcnt(0) lgkmcnt(0)
	v_pk_mul_f32 v[16:17], v[16:17], v[24:25]
	v_pk_mul_f32 v[18:19], v[18:19], v[26:27]
	v_xor_b32_e32 v26, 0x80000000, v16
	v_xor_b32_e32 v24, 0x80000000, v18
	v_xor_b32_e32 v25, 0x80000000, v19
	v_xor_b32_e32 v27, 0x80000000, v17
	v_cndmask_b32_e64 v17, v17, v27, s[4:5]
	v_cndmask_b32_e64 v16, v16, v26, s[4:5]
	v_cndmask_b32_e64 v19, v19, v25, s[4:5]
	v_cndmask_b32_e64 v18, v18, v24, s[4:5]
	v_pk_fma_f32 v[14:15], v[14:15], v[22:23], v[18:19]
	v_pk_fma_f32 v[12:13], v[12:13], v[20:21], v[16:17]
.LBB0_1145:
	s_nop 0
	v_pk_mul_f32 v[12:13], v[12:13], s[40:41] op_sel_hi:[1,0]
	s_and_b64 vcc, exec, s[6:7]
	v_pk_mul_f32 v[14:15], v[14:15], s[40:41] op_sel_hi:[1,0]
	v_cvt_pk_bf16_f32 v12, v12, v13
	s_nop 0
	v_cvt_pk_bf16_f32 v13, v14, v15
	s_cbranch_vccnz .LBB0_1147
	global_load_dwordx4 v[14:17], v80, s[18:19] offset:16
	global_load_dwordx4 v[18:21], v80, s[16:17] offset:16
	v_and_b32_e32 v23, 64, v146
	v_xor_b32_e32 v22, 16, v146
	v_add_u32_e32 v23, 64, v23
	v_cmp_lt_i32_e32 vcc, v22, v23
	s_nop 1
	v_cndmask_b32_e32 v22, v146, v22, vcc
	v_lshlrev_b32_e32 v25, 2, v22
	ds_bpermute_b32 v22, v25, v8
	ds_bpermute_b32 v23, v25, v9
	ds_bpermute_b32 v24, v25, v10
	ds_bpermute_b32 v25, v25, v11
	s_waitcnt vmcnt(0) lgkmcnt(0)
	v_pk_mul_f32 v[14:15], v[14:15], v[22:23]
	v_pk_mul_f32 v[16:17], v[16:17], v[24:25]
	v_xor_b32_e32 v24, 0x80000000, v14
	v_xor_b32_e32 v22, 0x80000000, v16
	v_xor_b32_e32 v23, 0x80000000, v17
	v_xor_b32_e32 v25, 0x80000000, v15
	v_cndmask_b32_e64 v15, v15, v25, s[4:5]
	v_cndmask_b32_e64 v14, v14, v24, s[4:5]
	v_cndmask_b32_e64 v17, v17, v23, s[4:5]
	v_cndmask_b32_e64 v16, v16, v22, s[4:5]
	v_pk_fma_f32 v[10:11], v[10:11], v[20:21], v[16:17]
	v_pk_fma_f32 v[8:9], v[8:9], v[18:19], v[14:15]
.LBB0_1147:
	s_nop 0
	v_pk_mul_f32 v[8:9], v[8:9], s[40:41] op_sel_hi:[1,0]
	v_pk_mul_f32 v[10:11], v[10:11], s[40:41] op_sel_hi:[1,0]
	v_cvt_pk_bf16_f32 v14, v8, v9
	v_add_co_u32_e32 v8, vcc, 0x3c000, v140
	v_cvt_pk_bf16_f32 v15, v10, v11
	s_nop 1
	v_addc_co_u32_e32 v9, vcc, 0, v141, vcc
	global_store_dwordx4 v[8:9], v[12:15], off offset:256
	s_and_b64 vcc, exec, s[6:7]
	s_cbranch_vccnz .LBB0_1149
	global_load_dwordx4 v[8:11], v72, s[18:19]
	global_load_dwordx4 v[12:15], v72, s[16:17]
	v_and_b32_e32 v17, 64, v146
	v_xor_b32_e32 v16, 16, v146
	v_add_u32_e32 v17, 64, v17
	v_cmp_lt_i32_e32 vcc, v16, v17
	s_nop 1
	v_cndmask_b32_e32 v16, v146, v16, vcc
	v_lshlrev_b32_e32 v19, 2, v16
	ds_bpermute_b32 v16, v19, v4
	ds_bpermute_b32 v17, v19, v5
	ds_bpermute_b32 v18, v19, v6
	ds_bpermute_b32 v19, v19, v7
	s_waitcnt vmcnt(0) lgkmcnt(0)
	v_pk_mul_f32 v[8:9], v[8:9], v[16:17]
	v_pk_mul_f32 v[10:11], v[10:11], v[18:19]
	v_xor_b32_e32 v18, 0x80000000, v8
	v_xor_b32_e32 v16, 0x80000000, v10
	v_xor_b32_e32 v17, 0x80000000, v11
	v_xor_b32_e32 v19, 0x80000000, v9
	v_cndmask_b32_e64 v9, v9, v19, s[4:5]
	v_cndmask_b32_e64 v8, v8, v18, s[4:5]
	v_cndmask_b32_e64 v11, v11, v17, s[4:5]
	v_cndmask_b32_e64 v10, v10, v16, s[4:5]
	v_pk_fma_f32 v[6:7], v[6:7], v[14:15], v[10:11]
	v_pk_fma_f32 v[4:5], v[4:5], v[12:13], v[8:9]
.LBB0_1149:
	s_nop 0
	v_pk_mul_f32 v[4:5], v[4:5], s[40:41] op_sel_hi:[1,0]
	s_and_b64 vcc, exec, s[6:7]
	v_pk_mul_f32 v[6:7], v[6:7], s[40:41] op_sel_hi:[1,0]
	v_cvt_pk_bf16_f32 v4, v4, v5
	s_nop 0
	v_cvt_pk_bf16_f32 v5, v6, v7
	s_cbranch_vccnz .LBB0_1151
	global_load_dwordx4 v[6:9], v72, s[18:19] offset:16
	global_load_dwordx4 v[10:13], v72, s[16:17] offset:16
	v_and_b32_e32 v15, 64, v146
	v_xor_b32_e32 v14, 16, v146
	v_add_u32_e32 v15, 64, v15
	v_cmp_lt_i32_e32 vcc, v14, v15
	s_nop 1
	v_cndmask_b32_e32 v14, v146, v14, vcc
	v_lshlrev_b32_e32 v17, 2, v14
	ds_bpermute_b32 v14, v17, v0
	ds_bpermute_b32 v15, v17, v1
	ds_bpermute_b32 v16, v17, v2
	ds_bpermute_b32 v17, v17, v3
	s_waitcnt vmcnt(0) lgkmcnt(0)
	v_pk_mul_f32 v[6:7], v[6:7], v[14:15]
	v_pk_mul_f32 v[8:9], v[8:9], v[16:17]
	v_xor_b32_e32 v16, 0x80000000, v6
	v_xor_b32_e32 v14, 0x80000000, v8
	v_xor_b32_e32 v15, 0x80000000, v9
	v_xor_b32_e32 v17, 0x80000000, v7
	v_cndmask_b32_e64 v7, v7, v17, s[4:5]
	v_cndmask_b32_e64 v6, v6, v16, s[4:5]
	v_cndmask_b32_e64 v9, v9, v15, s[4:5]
	v_cndmask_b32_e64 v8, v8, v14, s[4:5]
	v_pk_fma_f32 v[2:3], v[2:3], v[12:13], v[8:9]
	v_pk_fma_f32 v[0:1], v[0:1], v[10:11], v[6:7]
.LBB0_1151:
	s_nop 0
	v_pk_mul_f32 v[0:1], v[0:1], s[40:41] op_sel_hi:[1,0]
	v_pk_mul_f32 v[2:3], v[2:3], s[40:41] op_sel_hi:[1,0]
	v_cvt_pk_bf16_f32 v6, v0, v1
	v_add_co_u32_e32 v0, vcc, 0x42000, v140
	v_cvt_pk_bf16_f32 v7, v2, v3
	s_nop 1
	v_addc_co_u32_e32 v1, vcc, 0, v141, vcc
	global_store_dwordx4 v[0:1], v[4:7], off offset:256
	s_andn2_b64 vcc, exec, s[0:1]
	s_mov_b64 s[0:1], -1
	s_cbranch_vccnz .LBB0_1082
	s_andn2_b64 vcc, exec, s[12:13]
	s_cbranch_vccnz .LBB0_1081
	s_barrier
	s_branch .LBB0_1081

.LBB0_1229:
	s_cmp_lt_i32 s34, 6
	s_cselect_b64 s[0:1], -1, 0
	s_cmp_gt_i32 s35, 5
	s_cselect_b64 s[4:5], -1, 0
	s_and_b64 s[0:1], s[0:1], s[4:5]
	s_andn2_b64 vcc, exec, s[0:1]
	s_cbranch_vccnz .LBB0_1440
	s_getreg_b32 s98, hwreg(HW_REG_HW_ID, 0, 6)
	s_lshl_b32 s98, s98, 2
	s_and_b32 s98, s98, 0xfc
	s_add_i32 s98, s98, 0x256c0
	v_mov_b32_e32 v250, s98
	ds_read_b32 v250, v250
	s_waitcnt lgkmcnt(0)
	v_readfirstlane_b32 s98, v250
	s_nop 3
	s_cmp_ge_u32 s98, 4
	s_cbranch_scc1 .Lp5_prio_skip
	s_setprio 1
.Lp5_prio_skip:
	s_and_b32 s1, s2, 7
	s_lshr_b32 s3, s33, 3
	s_mul_i32 s1, s3, s1
	s_lshr_b32 s3, s2, 3
	s_and_b32 s0, s33, 7
	s_add_i32 s1, s1, s3
	s_cmp_eq_u32 s0, 0
	s_cselect_b32 s3, s1, s2
	v_writelane_b32 v254, s92, 6
	s_cmpk_gt_i32 s3, 0x7ff
	s_mov_b32 s9, 0
	v_writelane_b32 v254, s93, 7
	s_cbranch_scc1 .LBB0_1386
	v_mov_b32_e32 v0, 0x1538000
	global_load_dword v0, v0, s[78:79]
	s_add_u32 s0, s78, 0x12900000
	v_writelane_b32 v254, s0, 8
	s_addc_u32 s1, s79, 0
	v_writelane_b32 v254, s1, 35
	s_add_u32 s1, s78, 0x14900000
	s_addc_u32 s82, s79, 0
	s_add_u32 s83, s78, 0x15200000
	s_addc_u32 s84, s79, 0
	s_add_u32 s85, s78, 0x4000000
	s_addc_u32 s86, s79, 0
	s_add_u32 s87, s78, 0x1b400000
	s_addc_u32 s88, s79, 0
	s_add_u32 s89, s78, 0xbe00000
	s_addc_u32 s90, s79, 0
	s_add_u32 s48, s78, 0x17400000
	s_addc_u32 s49, s79, 0
	s_add_u32 s50, s78, 0xe200000
	s_addc_u32 s51, s79, 0
	s_add_u32 s91, s78, 0xbe10000
	s_addc_u32 s92, s79, 0
	s_add_u32 s54, s78, 0x1b478000
	s_addc_u32 s55, s79, 0
	s_add_u32 s56, s78, 0x14904000
	s_addc_u32 s57, s79, 0
	s_mov_b32 s0, 0x41c00000
	s_add_u32 s58, s78, 0x15204000
	s_waitcnt lgkmcnt(0)
	v_mov_b32_e32 v1, 0
	s_mov_b64 s[10:11], 0x80
	s_mov_b32 s63, 0xc000
	s_mov_b64 s[12:13], 0x18000
	s_mov_b64 s[14:15], 0x10000
	s_mov_b64 s[16:17], 0x30000
	s_mov_b32 s66, 0x8000
	s_mov_b64 s[18:19], 0x20000
	s_mov_b32 s69, 0xff800000
	s_mov_b32 s72, 0x41000000
	s_movk_i32 s67, 0x4000
	s_mov_b64 s[22:23], 0x8000
	s_mov_b64 s[24:25], 0xc000
	s_mov_b64 s[40:41], 0x14000
	s_mov_b64 s[80:81], 0x10c000
	v_writelane_b32 v254, s1, 33
	s_addc_u32 s59, s79, 0
	v_mov_b32_e32 v236, 0xc0
	s_waitcnt vmcnt(0)
	v_xor_b32_e32 v16, 0x80000000, v0
	v_cmp_ge_f32_e64 s[0:1], s0, v0
	v_mov_b32_e32 v17, v16
	v_mov_b32_e32 v18, v16
	v_mov_b32_e32 v19, v16
	v_mov_b32_e32 v20, v16
	v_mov_b32_e32 v21, v16
	v_mov_b32_e32 v22, v16
	v_mov_b32_e32 v23, v16
	v_mov_b32_e32 v24, v16
	v_mov_b32_e32 v25, v16
	v_mov_b32_e32 v26, v16
	v_mov_b32_e32 v27, v16
	v_mov_b32_e32 v28, v16
	v_mov_b32_e32 v29, v16
	v_mov_b32_e32 v30, v16
	v_mov_b32_e32 v31, v16
	s_branch .LBB0_1234
.LBB0_1232:
	s_or_b64 exec, exec, s[28:29]
	s_waitcnt lgkmcnt(0)
	ds_read_b128 v[2:5], v212 offset:128
	ds_read_b128 v[6:9], v212 offset:160
	s_lshl_b32 s4, s27, 12
	s_add_i32 s4, s4, 0
	s_add_i32 s4, s4, 0x10800
	s_waitcnt lgkmcnt(1)
	v_rcp_f32_e32 v10, v2
	v_rcp_f32_e32 v11, v3
	v_lshlrev_b32_e32 v68, 9, v215
	v_lshlrev_b32_e32 v69, 1, v214
	v_mul_f32_e32 v32, v32, v10
	v_mul_f32_e32 v10, v48, v10
	v_add3_u32 v68, s4, v68, v69
	v_cvt_pk_bf16_f32 v10, v10, s0
	v_rcp_f32_e32 v12, v4
	ds_write_b16 v68, v10 offset:64
	v_mul_f32_e32 v10, v33, v11
	v_cvt_pk_bf16_f32 v10, v10, s0
	ds_write_b16 v68, v10 offset:128
	v_mul_f32_e32 v10, v49, v11
	v_cvt_pk_bf16_f32 v10, v10, s0
	v_rcp_f32_e32 v13, v5
	ds_write_b16 v68, v10 offset:192
	v_mul_f32_e32 v10, v34, v12
	v_cvt_pk_bf16_f32 v10, v10, s0
	ds_write_b16 v68, v10 offset:256
	v_mul_f32_e32 v10, v50, v12
	v_cvt_pk_bf16_f32 v10, v10, s0
	s_waitcnt lgkmcnt(4)
	v_rcp_f32_e32 v64, v6
	ds_write_b16 v68, v10 offset:320
	v_mul_f32_e32 v10, v35, v13
	v_cvt_pk_bf16_f32 v10, v10, s0
	ds_write_b16 v68, v10 offset:384
	v_mul_f32_e32 v10, v51, v13
	v_cvt_pk_bf16_f32 v10, v10, s0
	v_rcp_f32_e32 v65, v7
	ds_write_b16 v68, v10 offset:448
	v_mul_f32_e32 v10, v36, v64
	v_cvt_pk_bf16_f32 v10, v10, s0
	ds_write_b16 v68, v10 offset:1024
	v_mul_f32_e32 v10, v52, v64
	v_cvt_pk_bf16_f32 v10, v10, s0
	v_rcp_f32_e32 v66, v8
	ds_write_b16 v68, v10 offset:1088
	v_mul_f32_e32 v10, v37, v65
	v_cvt_pk_bf16_f32 v10, v10, s0
	ds_write_b16 v68, v10 offset:1152
	v_mul_f32_e32 v10, v53, v65
	ds_read_b128 v[2:5], v212 offset:192
	v_cvt_pk_bf16_f32 v10, v10, s0
	v_rcp_f32_e32 v67, v9
	ds_write_b16 v68, v10 offset:1216
	v_mul_f32_e32 v10, v38, v66
	v_cvt_pk_bf16_f32 v10, v10, s0
	ds_write_b16 v68, v10 offset:1280
	v_mul_f32_e32 v10, v54, v66
	v_cvt_pk_bf16_f32 v10, v10, s0
	ds_read_b128 v[6:9], v212 offset:224
	s_waitcnt lgkmcnt(3)
	v_rcp_f32_e32 v2, v2
	ds_write_b16 v68, v10 offset:1344
	v_mul_f32_e32 v10, v39, v67
	v_cvt_pk_bf16_f32 v10, v10, s0
	v_rcp_f32_e32 v3, v3
	ds_write_b16 v68, v10 offset:1408
	v_mul_f32_e32 v10, v55, v67
	v_cvt_pk_bf16_f32 v10, v10, s0
	ds_write_b16 v68, v10 offset:1472
	v_mul_f32_e32 v10, v40, v2
	v_mul_f32_e32 v2, v56, v2
	v_cvt_pk_bf16_f32 v2, v2, s0
	v_rcp_f32_e32 v4, v4
	ds_write_b16 v68, v2 offset:2112
	v_mul_f32_e32 v2, v41, v3
	v_cvt_pk_bf16_f32 v2, v2, s0
	ds_write_b16 v68, v2 offset:2176
	v_mul_f32_e32 v2, v57, v3
	v_cvt_pk_bf16_f32 v2, v2, s0
	v_rcp_f32_e32 v5, v5
	ds_write_b16 v68, v2 offset:2240
	v_mul_f32_e32 v2, v42, v4
	v_cvt_pk_bf16_f32 v2, v2, s0
	ds_write_b16 v68, v2 offset:2304
	v_mul_f32_e32 v2, v58, v4
	v_cvt_pk_bf16_f32 v2, v2, s0
	s_waitcnt lgkmcnt(7)
	v_rcp_f32_e32 v6, v6
	ds_write_b16 v68, v2 offset:2368
	v_mul_f32_e32 v2, v43, v5
	v_cvt_pk_bf16_f32 v2, v2, s0
	ds_write_b16 v68, v2 offset:2432
	v_mul_f32_e32 v2, v59, v5
	v_cvt_pk_bf16_f32 v2, v2, s0
	v_rcp_f32_e32 v7, v7
	ds_write_b16 v68, v2 offset:2496
	v_mul_f32_e32 v2, v44, v6
	v_cvt_pk_bf16_f32 v2, v2, s0
	ds_write_b16 v68, v2 offset:3072
	v_mul_f32_e32 v2, v60, v6
	v_cvt_pk_bf16_f32 v2, v2, s0
	v_rcp_f32_e32 v8, v8
	ds_write_b16 v68, v2 offset:3136
	v_mul_f32_e32 v2, v45, v7
	v_cvt_pk_bf16_f32 v2, v2, s0
	ds_write_b16 v68, v2 offset:3200
	v_mul_f32_e32 v2, v61, v7
	v_cvt_pk_bf16_f32 v2, v2, s0
	v_rcp_f32_e32 v9, v9
	ds_write_b16 v68, v2 offset:3264
	v_mul_f32_e32 v2, v46, v8
	v_cvt_pk_bf16_f32 v2, v2, s0
	ds_write_b16 v68, v2 offset:3328
	v_mul_f32_e32 v2, v62, v8
	v_cvt_pk_bf16_f32 v2, v2, s0
	ds_write_b16 v68, v2 offset:3392
	v_mul_f32_e32 v2, v47, v9
	s_waitcnt vmcnt(3)
	v_lshlrev_b32_e32 v12, 16, v140
	v_cvt_pk_bf16_f32 v2, v2, s0
	v_and_b32_e32 v13, 0xffff0000, v140
	v_mul_f32_e32 v4, 0xbfb8aa3b, v12
	ds_write_b16 v68, v2 offset:3456
	v_mul_f32_e32 v2, v63, v9
	v_exp_f32_e32 v8, v4
	v_mul_f32_e32 v4, 0xbfb8aa3b, v13
	v_cvt_pk_bf16_f32 v32, v32, s0
	v_cvt_pk_bf16_f32 v10, v10, s0
	v_cvt_pk_bf16_f32 v2, v2, s0
	v_add_u32_e32 v36, s4, v0
	s_add_u32 s4, s50, s8
	v_exp_f32_e32 v9, v4
	ds_write_b16 v68, v32
	ds_write_b16 v68, v10 offset:2048
	ds_write_b16 v68, v2 offset:3520
	s_addc_u32 s5, s51, 0
	s_waitcnt lgkmcnt(0)
	v_lshl_add_u64 v[2:3], s[4:5], 0, v[0:1]
	v_lshl_add_u32 v0, v200, 7, v36
	ds_read_b128 v[4:7], v0
	v_add_f32_e32 v0, 1.0, v8
	v_rcp_f32_e32 v32, v0
	v_add_f32_e32 v0, 1.0, v9
	v_rcp_f32_e32 v33, v0
	s_waitcnt lgkmcnt(0)
	v_lshlrev_b32_e32 v34, 16, v4
	v_and_b32_e32 v35, 0xffff0000, v4
	v_or_b32_e32 v0, 8, v200
	v_pk_mul_f32 v[12:13], v[32:33], v[12:13]
	v_lshlrev_b32_e32 v32, 16, v141
	v_and_b32_e32 v33, 0xffff0000, v141
	v_mul_f32_e32 v4, 0xbfb8aa3b, v32
	v_exp_f32_e32 v4, v4
	v_mul_f32_e32 v37, 0xbfb8aa3b, v33
	v_exp_f32_e32 v37, v37
	v_pk_mul_f32 v[12:13], v[12:13], v[34:35]
	v_add_f32_e32 v4, 1.0, v4
	v_rcp_f32_e32 v34, v4
	v_add_f32_e32 v4, 1.0, v37
	v_rcp_f32_e32 v35, v4
	v_cvt_pk_bf16_f32 v4, v12, v13
	v_lshlrev_b32_e32 v12, 16, v5
	v_and_b32_e32 v13, 0xffff0000, v5
	v_pk_mul_f32 v[32:33], v[34:35], v[32:33]
	v_lshlrev_b32_e32 v34, 16, v142
	v_and_b32_e32 v35, 0xffff0000, v142
	v_mul_f32_e32 v5, 0xbfb8aa3b, v34
	v_exp_f32_e32 v5, v5
	v_mul_f32_e32 v37, 0xbfb8aa3b, v35
	v_exp_f32_e32 v37, v37
	v_pk_mul_f32 v[12:13], v[32:33], v[12:13]
	v_add_f32_e32 v5, 1.0, v5
	v_rcp_f32_e32 v32, v5
	v_add_f32_e32 v5, 1.0, v37
	v_rcp_f32_e32 v33, v5
	v_cvt_pk_bf16_f32 v5, v12, v13
	v_lshlrev_b32_e32 v12, 16, v6
	v_and_b32_e32 v13, 0xffff0000, v6
	v_pk_mul_f32 v[32:33], v[32:33], v[34:35]
	v_lshlrev_b32_e32 v34, 16, v143
	v_and_b32_e32 v35, 0xffff0000, v143
	v_mul_f32_e32 v6, 0xbfb8aa3b, v34
	v_exp_f32_e32 v6, v6
	v_mul_f32_e32 v37, 0xbfb8aa3b, v35
	v_exp_f32_e32 v37, v37
	v_pk_mul_f32 v[12:13], v[32:33], v[12:13]
	v_add_f32_e32 v6, 1.0, v6
	v_rcp_f32_e32 v32, v6
	v_add_f32_e32 v6, 1.0, v37
	v_rcp_f32_e32 v33, v6
	v_cvt_pk_bf16_f32 v6, v12, v13
	v_lshlrev_b32_e32 v12, 16, v7
	v_and_b32_e32 v13, 0xffff0000, v7
	v_pk_mul_f32 v[32:33], v[32:33], v[34:35]
	v_lshl_add_u32 v8, v0, 7, v36
	v_pk_mul_f32 v[12:13], v[32:33], v[12:13]
	ds_read_b128 v[8:11], v8
	v_cvt_pk_bf16_f32 v7, v12, v13
	v_lshl_add_u64 v[12:13], v[2:3], 0, v[14:15]
	global_store_dwordx4 v[12:13], v[4:7], off
	s_waitcnt lgkmcnt(0)
	v_lshlrev_b32_e32 v14, 16, v8
	s_waitcnt vmcnt(3)
	v_lshlrev_b32_e32 v6, 16, v136
	v_and_b32_e32 v7, 0xffff0000, v136
	v_mul_f32_e32 v4, 0xbfb8aa3b, v6
	v_exp_f32_e32 v5, v4
	v_mul_f32_e32 v4, 0xbfb8aa3b, v7
	v_exp_f32_e32 v13, v4
	v_or_b32_e32 v4, s6, v0
	v_add_f32_e32 v0, 1.0, v5
	v_rcp_f32_e32 v12, v0
	v_add_f32_e32 v0, 1.0, v13
	v_rcp_f32_e32 v13, v0
	v_and_b32_e32 v15, 0xffff0000, v8
	v_mov_b32_e32 v5, s7
	v_pk_mul_f32 v[6:7], v[12:13], v[6:7]
	v_lshlrev_b32_e32 v12, 16, v137
	v_and_b32_e32 v13, 0xffff0000, v137
	v_mul_f32_e32 v0, 0xbfb8aa3b, v12
	v_exp_f32_e32 v0, v0
	v_mul_f32_e32 v8, 0xbfb8aa3b, v13
	v_exp_f32_e32 v8, v8
	v_pk_mul_f32 v[6:7], v[6:7], v[14:15]
	v_add_f32_e32 v0, 1.0, v0
	v_rcp_f32_e32 v14, v0
	v_add_f32_e32 v0, 1.0, v8
	v_rcp_f32_e32 v15, v0
	v_cvt_pk_bf16_f32 v6, v6, v7
	v_lshlrev_b32_e32 v8, 16, v9
	v_and_b32_e32 v9, 0xffff0000, v9
	v_pk_mul_f32 v[12:13], v[14:15], v[12:13]
	v_lshlrev_b32_e32 v14, 16, v138
	v_and_b32_e32 v15, 0xffff0000, v138
	v_mul_f32_e32 v0, 0xbfb8aa3b, v14
	v_exp_f32_e32 v0, v0
	v_mul_f32_e32 v7, 0xbfb8aa3b, v15
	v_exp_f32_e32 v7, v7
	v_pk_mul_f32 v[8:9], v[12:13], v[8:9]
	v_add_f32_e32 v0, 1.0, v0
	v_rcp_f32_e32 v12, v0
	v_add_f32_e32 v0, 1.0, v7
	v_rcp_f32_e32 v13, v0
	v_cvt_pk_bf16_f32 v7, v8, v9
	v_lshlrev_b32_e32 v8, 16, v10
	v_and_b32_e32 v9, 0xffff0000, v10
	v_pk_mul_f32 v[12:13], v[12:13], v[14:15]
	v_lshlrev_b32_e32 v14, 16, v139
	v_and_b32_e32 v15, 0xffff0000, v139
	v_mul_f32_e32 v0, 0xbfb8aa3b, v14
	v_exp_f32_e32 v0, v0
	v_mul_f32_e32 v10, 0xbfb8aa3b, v15
	v_exp_f32_e32 v10, v10
	v_pk_mul_f32 v[8:9], v[12:13], v[8:9]
	v_add_f32_e32 v0, 1.0, v0
	v_rcp_f32_e32 v12, v0
	v_add_f32_e32 v0, 1.0, v10
	v_rcp_f32_e32 v13, v0
	v_lshlrev_b32_e32 v10, 16, v11
	v_and_b32_e32 v11, 0xffff0000, v11
	v_cvt_pk_bf16_f32 v8, v8, v9
	v_pk_mul_f32 v[12:13], v[12:13], v[14:15]
	v_or_b32_e32 v0, 16, v200
	v_pk_mul_f32 v[10:11], v[12:13], v[10:11]
	s_waitcnt vmcnt(2)
	v_lshlrev_b32_e32 v14, 16, v132
	v_cvt_pk_bf16_f32 v9, v10, v11
	v_lshlrev_b64 v[10:11], 11, v[4:5]
	v_lshl_add_u64 v[10:11], v[2:3], 0, v[10:11]
	v_lshl_add_u32 v4, v0, 7, v36
	global_store_dwordx4 v[10:11], v[6:9], off
	ds_read_b128 v[6:9], v4
	v_and_b32_e32 v15, 0xffff0000, v132
	v_mul_f32_e32 v4, 0xbfb8aa3b, v14
	v_exp_f32_e32 v10, v4
	v_mul_f32_e32 v4, 0xbfb8aa3b, v15
	v_exp_f32_e32 v11, v4
	v_or_b32_e32 v4, s6, v0
	v_add_f32_e32 v0, 1.0, v10
	v_rcp_f32_e32 v32, v0
	v_add_f32_e32 v0, 1.0, v11
	v_rcp_f32_e32 v33, v0
	v_or_b32_e32 v0, 24, v200
	s_waitcnt lgkmcnt(0)
	v_lshlrev_b32_e32 v34, 16, v6
	v_and_b32_e32 v35, 0xffff0000, v6
	v_pk_mul_f32 v[14:15], v[32:33], v[14:15]
	v_lshlrev_b32_e32 v32, 16, v133
	v_and_b32_e32 v33, 0xffff0000, v133
	v_mul_f32_e32 v6, 0xbfb8aa3b, v32
	v_lshl_add_u32 v10, v0, 7, v36
	v_exp_f32_e32 v6, v6
	v_mul_f32_e32 v36, 0xbfb8aa3b, v33
	v_exp_f32_e32 v36, v36
	v_pk_mul_f32 v[14:15], v[14:15], v[34:35]
	v_add_f32_e32 v6, 1.0, v6
	v_rcp_f32_e32 v34, v6
	v_add_f32_e32 v6, 1.0, v36
	v_rcp_f32_e32 v35, v6
	v_cvt_pk_bf16_f32 v6, v14, v15
	v_lshlrev_b32_e32 v14, 16, v7
	v_and_b32_e32 v15, 0xffff0000, v7
	v_pk_mul_f32 v[32:33], v[34:35], v[32:33]
	v_lshlrev_b32_e32 v34, 16, v134
	v_and_b32_e32 v35, 0xffff0000, v134
	v_mul_f32_e32 v7, 0xbfb8aa3b, v34
	v_exp_f32_e32 v7, v7
	v_mul_f32_e32 v36, 0xbfb8aa3b, v35
	v_exp_f32_e32 v36, v36
	v_pk_mul_f32 v[14:15], v[32:33], v[14:15]
	v_add_f32_e32 v7, 1.0, v7
	v_rcp_f32_e32 v32, v7
	v_add_f32_e32 v7, 1.0, v36
	v_rcp_f32_e32 v33, v7
	v_cvt_pk_bf16_f32 v7, v14, v15
	v_lshlrev_b32_e32 v14, 16, v8
	v_and_b32_e32 v15, 0xffff0000, v8
	v_pk_mul_f32 v[32:33], v[32:33], v[34:35]
	v_lshlrev_b32_e32 v34, 16, v135
	v_and_b32_e32 v35, 0xffff0000, v135
	v_mul_f32_e32 v8, 0xbfb8aa3b, v34
	v_exp_f32_e32 v8, v8
	v_mul_f32_e32 v36, 0xbfb8aa3b, v35
	v_exp_f32_e32 v36, v36
	v_pk_mul_f32 v[14:15], v[32:33], v[14:15]
	v_add_f32_e32 v8, 1.0, v8
	v_rcp_f32_e32 v32, v8
	v_add_f32_e32 v8, 1.0, v36
	v_rcp_f32_e32 v33, v8
	v_cvt_pk_bf16_f32 v8, v14, v15
	v_lshlrev_b32_e32 v14, 16, v9
	v_and_b32_e32 v15, 0xffff0000, v9
	v_pk_mul_f32 v[32:33], v[32:33], v[34:35]
	ds_read_b128 v[10:13], v10
	v_pk_mul_f32 v[14:15], v[32:33], v[14:15]
	s_waitcnt vmcnt(2)
	v_lshlrev_b32_e32 v32, 16, v128
	v_cvt_pk_bf16_f32 v9, v14, v15
	v_lshlrev_b64 v[14:15], 11, v[4:5]
	v_and_b32_e32 v33, 0xffff0000, v128
	v_mul_f32_e32 v4, 0xbfb8aa3b, v32
	v_exp_f32_e32 v4, v4
	v_mul_f32_e32 v34, 0xbfb8aa3b, v33
	v_exp_f32_e32 v34, v34
	v_lshl_add_u64 v[14:15], v[2:3], 0, v[14:15]
	v_add_f32_e32 v4, 1.0, v4
	global_store_dwordx4 v[14:15], v[6:9], off
	v_lshlrev_b32_e32 v14, 16, v129
	v_and_b32_e32 v15, 0xffff0000, v129
	v_rcp_f32_e32 v6, v4
	v_add_f32_e32 v4, 1.0, v34
	v_rcp_f32_e32 v7, v4
	v_or_b32_e32 v4, s6, v0
	v_mul_f32_e32 v0, 0xbfb8aa3b, v14
	s_waitcnt lgkmcnt(0)
	v_lshlrev_b32_e32 v8, 16, v10
	v_and_b32_e32 v9, 0xffff0000, v10
	v_exp_f32_e32 v0, v0
	v_mul_f32_e32 v10, 0xbfb8aa3b, v15
	v_exp_f32_e32 v10, v10
	v_pk_mul_f32 v[6:7], v[6:7], v[32:33]
	v_add_f32_e32 v0, 1.0, v0
	v_pk_mul_f32 v[6:7], v[6:7], v[8:9]
	v_rcp_f32_e32 v8, v0
	v_add_f32_e32 v0, 1.0, v10
	v_rcp_f32_e32 v9, v0
	v_cvt_pk_bf16_f32 v6, v6, v7
	v_lshlrev_b32_e32 v10, 16, v11
	v_and_b32_e32 v11, 0xffff0000, v11
	v_pk_mul_f32 v[8:9], v[8:9], v[14:15]
	v_lshlrev_b32_e32 v14, 16, v130
	v_and_b32_e32 v15, 0xffff0000, v130
	v_mul_f32_e32 v0, 0xbfb8aa3b, v14
	v_exp_f32_e32 v0, v0
	v_mul_f32_e32 v7, 0xbfb8aa3b, v15
	v_exp_f32_e32 v7, v7
	v_pk_mul_f32 v[8:9], v[8:9], v[10:11]
	v_add_f32_e32 v0, 1.0, v0
	v_rcp_f32_e32 v10, v0
	v_add_f32_e32 v0, 1.0, v7
	v_rcp_f32_e32 v11, v0
	v_cvt_pk_bf16_f32 v7, v8, v9
	v_lshlrev_b32_e32 v8, 16, v12
	v_and_b32_e32 v9, 0xffff0000, v12
	v_pk_mul_f32 v[10:11], v[10:11], v[14:15]
	v_lshlrev_b32_e32 v14, 16, v131
	v_and_b32_e32 v15, 0xffff0000, v131
	v_mul_f32_e32 v0, 0xbfb8aa3b, v14
	v_exp_f32_e32 v0, v0
	v_mul_f32_e32 v12, 0xbfb8aa3b, v15
	v_exp_f32_e32 v12, v12
	v_pk_mul_f32 v[8:9], v[10:11], v[8:9]
	v_add_f32_e32 v0, 1.0, v0
	v_rcp_f32_e32 v10, v0
	v_add_f32_e32 v0, 1.0, v12
	v_rcp_f32_e32 v11, v0
	v_lshlrev_b32_e32 v12, 16, v13
	v_and_b32_e32 v13, 0xffff0000, v13
	v_lshlrev_b64 v[4:5], 11, v[4:5]
	v_pk_mul_f32 v[10:11], v[10:11], v[14:15]
	v_cvt_pk_bf16_f32 v8, v8, v9
	v_pk_mul_f32 v[10:11], v[10:11], v[12:13]
	v_lshl_add_u64 v[2:3], v[2:3], 0, v[4:5]
	v_cvt_pk_bf16_f32 v9, v10, v11
	global_store_dwordx4 v[2:3], v[6:9], off
	s_waitcnt lgkmcnt(0)
	s_barrier

.LBB0_1264:
	s_waitcnt lgkmcnt(0)
	v_add_u32_e32 v2, s46, v234
	ds_read_b128 v[80:83], v2 offset:96
	ds_read_b128 v[84:87], v2 offset:64
	ds_read_b128 v[88:91], v2 offset:32
	ds_read_b128 v[96:99], v2
	s_waitcnt lgkmcnt(3)
	v_pk_mul_f32 v[60:61], v[60:61], v[80:81]
	s_waitcnt lgkmcnt(2)
	v_pk_mul_f32 v[56:57], v[56:57], v[84:85]
	s_waitcnt lgkmcnt(1)
	v_pk_mul_f32 v[52:53], v[52:53], v[88:89]
	v_pk_mul_f32 v[62:63], v[62:63], v[82:83]
	v_pk_mul_f32 v[58:59], v[58:59], v[86:87]
	v_pk_mul_f32 v[54:55], v[54:55], v[90:91]
	s_waitcnt lgkmcnt(0)
	v_pk_mul_f32 v[50:51], v[50:51], v[98:99]
	v_pk_mul_f32 v[48:49], v[48:49], v[96:97]
	v_pk_mul_f32 v[44:45], v[44:45], v[80:81]
	v_pk_mul_f32 v[40:41], v[40:41], v[84:85]
	v_pk_mul_f32 v[36:37], v[36:37], v[88:89]
	v_pk_mul_f32 v[46:47], v[46:47], v[82:83]
	v_pk_mul_f32 v[42:43], v[42:43], v[86:87]
	v_pk_mul_f32 v[38:39], v[38:39], v[90:91]
	v_pk_mul_f32 v[34:35], v[34:35], v[98:99]
	v_pk_mul_f32 v[32:33], v[32:33], v[96:97]

.LBB0_1271:
	s_waitcnt lgkmcnt(0)
	v_add_u32_e32 v0, s46, v234
	ds_read_b128 v[116:119], v0 offset:96
	ds_read_b128 v[120:123], v0 offset:64
	ds_read_b128 v[124:127], v0 offset:32
	ds_read_b128 v[128:131], v0
	s_waitcnt lgkmcnt(3)
	v_pk_mul_f32 v[60:61], v[60:61], v[116:117]
	s_waitcnt lgkmcnt(2)
	v_pk_mul_f32 v[56:57], v[56:57], v[120:121]
	s_waitcnt lgkmcnt(1)
	v_pk_mul_f32 v[52:53], v[52:53], v[124:125]
	v_pk_mul_f32 v[62:63], v[62:63], v[118:119]
	v_pk_mul_f32 v[58:59], v[58:59], v[122:123]
	v_pk_mul_f32 v[54:55], v[54:55], v[126:127]
	s_waitcnt lgkmcnt(0)
	v_pk_mul_f32 v[50:51], v[50:51], v[130:131]
	v_pk_mul_f32 v[48:49], v[48:49], v[128:129]
	v_pk_mul_f32 v[44:45], v[44:45], v[116:117]
	v_pk_mul_f32 v[40:41], v[40:41], v[120:121]
	v_pk_mul_f32 v[36:37], v[36:37], v[124:125]
	v_pk_mul_f32 v[46:47], v[46:47], v[118:119]
	v_pk_mul_f32 v[42:43], v[42:43], v[122:123]
	v_pk_mul_f32 v[38:39], v[38:39], v[126:127]
	v_pk_mul_f32 v[34:35], v[34:35], v[130:131]
	v_pk_mul_f32 v[32:33], v[32:33], v[128:129]

.LBB0_1290:
	s_waitcnt lgkmcnt(0)
	ds_read_b128 v[80:83], v234 offset:96
	ds_read_b128 v[84:87], v234 offset:64
	ds_read_b128 v[88:91], v234 offset:32
	ds_read_b128 v[96:99], v234
	s_waitcnt lgkmcnt(3)
	v_pk_mul_f32 v[60:61], v[60:61], v[80:81]
	s_waitcnt lgkmcnt(2)
	v_pk_mul_f32 v[56:57], v[56:57], v[84:85]
	s_waitcnt lgkmcnt(1)
	v_pk_mul_f32 v[52:53], v[52:53], v[88:89]
	v_pk_mul_f32 v[62:63], v[62:63], v[82:83]
	v_pk_mul_f32 v[58:59], v[58:59], v[86:87]
	v_pk_mul_f32 v[54:55], v[54:55], v[90:91]
	s_waitcnt lgkmcnt(0)
	v_pk_mul_f32 v[50:51], v[50:51], v[98:99]
	v_pk_mul_f32 v[48:49], v[48:49], v[96:97]
	v_pk_mul_f32 v[44:45], v[44:45], v[80:81]
	v_pk_mul_f32 v[40:41], v[40:41], v[84:85]
	v_pk_mul_f32 v[36:37], v[36:37], v[88:89]
	v_pk_mul_f32 v[46:47], v[46:47], v[82:83]
	v_pk_mul_f32 v[42:43], v[42:43], v[86:87]
	v_pk_mul_f32 v[38:39], v[38:39], v[90:91]
	v_pk_mul_f32 v[34:35], v[34:35], v[98:99]
	v_pk_mul_f32 v[32:33], v[32:33], v[96:97]

.LBB0_1295:
	s_waitcnt lgkmcnt(0)
	ds_read_b128 v[96:99], v234 offset:96
	ds_read_b128 v[100:103], v234 offset:64
	ds_read_b128 v[108:111], v234 offset:32
	ds_read_b128 v[112:115], v234
	s_waitcnt lgkmcnt(3)
	v_pk_mul_f32 v[60:61], v[60:61], v[96:97]
	s_waitcnt lgkmcnt(2)
	v_pk_mul_f32 v[56:57], v[56:57], v[100:101]
	s_waitcnt lgkmcnt(1)
	v_pk_mul_f32 v[52:53], v[52:53], v[108:109]
	v_pk_mul_f32 v[62:63], v[62:63], v[98:99]
	v_pk_mul_f32 v[58:59], v[58:59], v[102:103]
	v_pk_mul_f32 v[54:55], v[54:55], v[110:111]
	s_waitcnt lgkmcnt(0)
	v_pk_mul_f32 v[50:51], v[50:51], v[114:115]
	v_pk_mul_f32 v[48:49], v[48:49], v[112:113]
	v_pk_mul_f32 v[44:45], v[44:45], v[96:97]
	v_pk_mul_f32 v[40:41], v[40:41], v[100:101]
	v_pk_mul_f32 v[36:37], v[36:37], v[108:109]
	v_pk_mul_f32 v[46:47], v[46:47], v[98:99]
	v_pk_mul_f32 v[42:43], v[42:43], v[102:103]
	v_pk_mul_f32 v[38:39], v[38:39], v[110:111]
	v_pk_mul_f32 v[34:35], v[34:35], v[114:115]
	v_pk_mul_f32 v[32:33], v[32:33], v[112:113]

.LBB0_1300:
	s_waitcnt lgkmcnt(0)
	ds_read_b128 v[80:83], v234 offset:96
	ds_read_b128 v[84:87], v234 offset:64
	ds_read_b128 v[88:91], v234 offset:32
	ds_read_b128 v[112:115], v234
	s_waitcnt lgkmcnt(3)
	v_pk_mul_f32 v[60:61], v[60:61], v[80:81]
	s_waitcnt lgkmcnt(2)
	v_pk_mul_f32 v[56:57], v[56:57], v[84:85]
	s_waitcnt lgkmcnt(1)
	v_pk_mul_f32 v[52:53], v[52:53], v[88:89]
	v_pk_mul_f32 v[62:63], v[62:63], v[82:83]
	v_pk_mul_f32 v[58:59], v[58:59], v[86:87]
	v_pk_mul_f32 v[54:55], v[54:55], v[90:91]
	s_waitcnt lgkmcnt(0)
	v_pk_mul_f32 v[50:51], v[50:51], v[114:115]
	v_pk_mul_f32 v[48:49], v[48:49], v[112:113]
	v_pk_mul_f32 v[44:45], v[44:45], v[80:81]
	v_pk_mul_f32 v[40:41], v[40:41], v[84:85]
	v_pk_mul_f32 v[36:37], v[36:37], v[88:89]
	v_pk_mul_f32 v[46:47], v[46:47], v[82:83]
	v_pk_mul_f32 v[42:43], v[42:43], v[86:87]
	v_pk_mul_f32 v[38:39], v[38:39], v[90:91]
	v_pk_mul_f32 v[34:35], v[34:35], v[114:115]
	v_pk_mul_f32 v[32:33], v[32:33], v[112:113]

.LBB0_1302:
	v_mfma_f32_32x32x16_bf16 v[48:63], v[184:187], v[188:191], v[48:63]
	v_exp_f32_e32 v112, v112
	v_exp_f32_e32 v113, v113
	v_exp_f32_e32 v114, v114
	v_exp_f32_e32 v115, v115
	s_waitcnt lgkmcnt(12)
	v_mfma_f32_32x32x16_bf16 v[32:47], v[184:187], v[156:159], v[32:47]
	v_exp_f32_e32 v116, v116
	v_exp_f32_e32 v117, v117
	v_exp_f32_e32 v118, v118
	v_exp_f32_e32 v119, v119
	ds_read_b128 v[220:223], v245 offset:36864
	ds_read_b128 v[216:219], v245 offset:38912
	s_waitcnt lgkmcnt(12)
	v_mfma_f32_32x32x16_bf16 v[48:63], v[10:13], v[128:131], v[48:63]
	v_exp_f32_e32 v120, v120
	v_exp_f32_e32 v121, v121
	v_exp_f32_e32 v122, v122
	v_exp_f32_e32 v123, v123
	ds_read_b128 v[212:215], v244 offset:36864
	ds_read_b128 v[208:211], v244 offset:38912
	s_waitcnt lgkmcnt(12)
	v_mfma_f32_32x32x16_bf16 v[32:47], v[10:13], v[132:135], v[32:47]
	v_exp_f32_e32 v124, v124
	v_exp_f32_e32 v125, v125
	v_exp_f32_e32 v126, v126
	v_exp_f32_e32 v127, v127
	ds_read_b128 v[204:207], v245 offset:40960
	ds_read_b128 v[192:195], v245 offset:43008
	s_waitcnt lgkmcnt(12)
	v_mfma_f32_32x32x16_bf16 v[48:63], v[6:9], v[136:139], v[48:63]
	v_exp_f32_e32 v80, v80
	v_exp_f32_e32 v81, v81
	v_exp_f32_e32 v82, v82
	v_exp_f32_e32 v83, v83
	ds_read_b128 v[188:191], v244 offset:40960
	ds_read_b128 v[144:147], v244 offset:43008
	s_waitcnt lgkmcnt(12)
	v_mfma_f32_32x32x16_bf16 v[32:47], v[6:9], v[96:99], v[32:47]
	v_exp_f32_e32 v84, v84
	v_exp_f32_e32 v85, v85
	v_exp_f32_e32 v86, v86
	v_exp_f32_e32 v87, v87
	ds_read_b128 v[152:155], v245 offset:45056
	ds_read_b128 v[148:151], v245 offset:47104
	s_waitcnt lgkmcnt(12)
	v_mfma_f32_32x32x16_bf16 v[48:63], v[2:5], v[100:103], v[48:63]
	v_exp_f32_e32 v88, v88
	v_exp_f32_e32 v89, v89
	v_exp_f32_e32 v90, v90
	v_exp_f32_e32 v91, v91
	ds_read_b128 v[200:203], v244 offset:45056
	ds_read_b128 v[196:199], v244 offset:47104
	s_waitcnt lgkmcnt(12)
	v_mfma_f32_32x32x16_bf16 v[32:47], v[2:5], v[104:107], v[32:47]
	v_exp_f32_e32 v92, v92
	v_exp_f32_e32 v93, v93
	v_exp_f32_e32 v94, v94
	v_exp_f32_e32 v95, v95
	s_waitcnt vmcnt(0) lgkmcnt(0)
	s_barrier
	s_andn2_b64 vcc, exec, s[6:7]
	s_cbranch_vccnz .LBB0_1304
	s_waitcnt lgkmcnt(0)
	ds_read_b128 v[96:99], v234 offset:96
	ds_read_b128 v[100:103], v234 offset:64
	ds_read_b128 v[104:107], v234 offset:32
	ds_read_b128 v[108:111], v234
	s_waitcnt lgkmcnt(3)
	v_pk_mul_f32 v[60:61], v[60:61], v[96:97]
	s_waitcnt lgkmcnt(2)
	v_pk_mul_f32 v[56:57], v[56:57], v[100:101]
	s_waitcnt lgkmcnt(1)
	v_pk_mul_f32 v[52:53], v[52:53], v[104:105]
	v_pk_mul_f32 v[62:63], v[62:63], v[98:99]
	v_pk_mul_f32 v[58:59], v[58:59], v[102:103]
	v_pk_mul_f32 v[54:55], v[54:55], v[106:107]
	s_waitcnt lgkmcnt(0)
	v_pk_mul_f32 v[50:51], v[50:51], v[110:111]
	v_pk_mul_f32 v[48:49], v[48:49], v[108:109]
	v_pk_mul_f32 v[44:45], v[44:45], v[96:97]
	v_pk_mul_f32 v[40:41], v[40:41], v[100:101]
	v_pk_mul_f32 v[36:37], v[36:37], v[104:105]
	v_pk_mul_f32 v[46:47], v[46:47], v[98:99]
	v_pk_mul_f32 v[42:43], v[42:43], v[102:103]
	v_pk_mul_f32 v[38:39], v[38:39], v[106:107]
	v_pk_mul_f32 v[34:35], v[34:35], v[110:111]
	v_pk_mul_f32 v[32:33], v[32:33], v[108:109]

.LBB0_1305:
	v_mfma_f32_32x32x16_bf16 v[48:63], v[184:187], v[156:159], v[48:63]
	v_exp_f32_e32 v96, v96
	v_exp_f32_e32 v97, v97
	v_exp_f32_e32 v98, v98
	v_exp_f32_e32 v99, v99
	s_waitcnt lgkmcnt(12)
	v_mfma_f32_32x32x16_bf16 v[32:47], v[184:187], v[112:115], v[32:47]
	v_exp_f32_e32 v100, v100
	v_exp_f32_e32 v101, v101
	v_exp_f32_e32 v102, v102
	v_exp_f32_e32 v103, v103
	s_waitcnt lgkmcnt(10)
	v_mfma_f32_32x32x16_bf16 v[48:63], v[10:13], v[116:119], v[48:63]
	v_exp_f32_e32 v104, v104
	v_exp_f32_e32 v105, v105
	v_exp_f32_e32 v106, v106
	v_exp_f32_e32 v107, v107
	s_waitcnt lgkmcnt(8)
	v_mfma_f32_32x32x16_bf16 v[32:47], v[10:13], v[120:123], v[32:47]
	v_exp_f32_e32 v108, v108
	v_exp_f32_e32 v109, v109
	v_exp_f32_e32 v110, v110
	v_exp_f32_e32 v111, v111
	s_waitcnt lgkmcnt(6)
	v_mfma_f32_32x32x16_bf16 v[48:63], v[6:9], v[124:127], v[48:63]
	v_exp_f32_e32 v64, v64
	v_exp_f32_e32 v65, v65
	v_exp_f32_e32 v66, v66
	v_exp_f32_e32 v67, v67
	s_waitcnt lgkmcnt(4)
	v_mfma_f32_32x32x16_bf16 v[32:47], v[6:9], v[176:179], v[32:47]
	v_exp_f32_e32 v68, v68
	v_exp_f32_e32 v69, v69
	v_exp_f32_e32 v70, v70
	v_exp_f32_e32 v71, v71
	s_waitcnt lgkmcnt(2)
	v_mfma_f32_32x32x16_bf16 v[48:63], v[2:5], v[172:175], v[48:63]
	v_exp_f32_e32 v72, v72
	v_exp_f32_e32 v73, v73
	v_exp_f32_e32 v74, v74
	v_exp_f32_e32 v75, v75
	s_waitcnt lgkmcnt(0)
	v_mfma_f32_32x32x16_bf16 v[32:47], v[2:5], v[180:183], v[32:47]
	v_exp_f32_e32 v76, v76
	v_exp_f32_e32 v77, v77
	v_exp_f32_e32 v78, v78
	v_exp_f32_e32 v79, v79
	s_andn2_b64 vcc, exec, s[6:7]
	s_cbranch_vccnz .LBB0_1307
	s_waitcnt lgkmcnt(0)
	ds_read_b128 v[2:5], v234 offset:96
	ds_read_b128 v[6:9], v234 offset:64
	ds_read_b128 v[10:13], v234 offset:32
	ds_read_b128 v[80:83], v234
	s_waitcnt lgkmcnt(3)
	v_pk_mul_f32 v[60:61], v[60:61], v[2:3]
	s_waitcnt lgkmcnt(2)
	v_pk_mul_f32 v[56:57], v[56:57], v[6:7]
	s_waitcnt lgkmcnt(1)
	v_pk_mul_f32 v[52:53], v[52:53], v[10:11]
	v_pk_mul_f32 v[62:63], v[62:63], v[4:5]
	v_pk_mul_f32 v[58:59], v[58:59], v[8:9]
	v_pk_mul_f32 v[54:55], v[54:55], v[12:13]
	s_waitcnt lgkmcnt(0)
	v_pk_mul_f32 v[50:51], v[50:51], v[82:83]
	v_pk_mul_f32 v[48:49], v[48:49], v[80:81]
	v_pk_mul_f32 v[44:45], v[44:45], v[2:3]
	v_pk_mul_f32 v[40:41], v[40:41], v[6:7]
	v_pk_mul_f32 v[36:37], v[36:37], v[10:11]
	v_pk_mul_f32 v[46:47], v[46:47], v[4:5]
	v_pk_mul_f32 v[42:43], v[42:43], v[8:9]
	v_pk_mul_f32 v[38:39], v[38:39], v[12:13]
	v_pk_mul_f32 v[34:35], v[34:35], v[82:83]
	v_pk_mul_f32 v[32:33], v[32:33], v[80:81]
.LBB0_1307:
	v_add_f32_e32 v2, v96, v97
	v_add_f32_e32 v2, v98, v2
	v_add_f32_e32 v2, v99, v2
	v_add_f32_e32 v2, v100, v2
	v_add_f32_e32 v2, v101, v2
	v_add_f32_e32 v2, v102, v2
	v_add_f32_e32 v2, v103, v2
	v_add_f32_e32 v2, v104, v2
	v_add_f32_e32 v2, v105, v2
	v_add_f32_e32 v2, v106, v2
	v_add_f32_e32 v2, v107, v2
	v_add_f32_e32 v2, v108, v2
	v_add_f32_e32 v2, v109, v2
	v_add_f32_e32 v2, v110, v2
	v_add_f32_e32 v2, v111, v2
	v_add_f32_e32 v2, v64, v2
	v_add_f32_e32 v2, v65, v2
	v_add_f32_e32 v2, v66, v2
	v_add_f32_e32 v2, v67, v2
	v_add_f32_e32 v2, v68, v2
	v_add_f32_e32 v2, v69, v2
	v_add_f32_e32 v2, v70, v2
	v_add_f32_e32 v2, v71, v2
	v_add_f32_e32 v2, v72, v2
	v_add_f32_e32 v2, v73, v2
	v_add_f32_e32 v2, v74, v2
	v_add_f32_e32 v2, v75, v2
	v_add_f32_e32 v2, v76, v2
	v_add_f32_e32 v2, v77, v2
	v_add_f32_e32 v2, v78, v2
	v_add_f32_e32 v2, v79, v2
	v_add_f32_e32 v2, v144, v2
	v_cvt_pk_bf16_f32 v4, v96, v97
	v_cvt_pk_bf16_f32 v5, v98, v99
	v_cvt_pk_bf16_f32 v6, v100, v101
	v_cvt_pk_bf16_f32 v7, v102, v103
	v_cvt_pk_bf16_f32 v8, v104, v105
	v_cvt_pk_bf16_f32 v9, v106, v107
	v_cvt_pk_bf16_f32 v10, v108, v109
	v_cvt_pk_bf16_f32 v11, v110, v111
	v_cvt_pk_bf16_f32 v64, v64, v65
	v_cvt_pk_bf16_f32 v65, v66, v67
	v_cvt_pk_bf16_f32 v66, v68, v69
	v_cvt_pk_bf16_f32 v67, v70, v71
	v_cvt_pk_bf16_f32 v68, v72, v73
	v_cvt_pk_bf16_f32 v69, v74, v75
	v_cvt_pk_bf16_f32 v70, v76, v77
	v_cvt_pk_bf16_f32 v71, v78, v79
	s_cmp_lg_u32 0, -1
	s_cselect_b32 s6, 0, 0
	s_add_i32 s6, s6, 0x12000
	v_add_u32_e32 v3, s6, v240
	v_add3_u32 v3, v3, v235, v241
	ds_read_b64_tr_b16 v[72:73],v3 offset:0
	ds_read_b64_tr_b16 v[74:75],v3 offset:512
	ds_read_b64_tr_b16 v[76:77],v3 offset:1024
	ds_read_b64_tr_b16 v[78:79],v3 offset:1536
	ds_read_b64_tr_b16 v[80:81],v3 offset:2048
	ds_read_b64_tr_b16 v[82:83],v3 offset:2560
	ds_read_b64_tr_b16 v[84:85],v3 offset:3072
	ds_read_b64_tr_b16 v[86:87],v3 offset:3584
	s_waitcnt lgkmcnt(0)
	s_nop 0
	v_mfma_f32_32x32x16_bf16 v[48:63], v[4:7], v[72:75], v[48:63]
	ds_read_b64_tr_b16 v[72:73],v3 offset:4096
	ds_read_b64_tr_b16 v[74:75],v3 offset:4608
	v_mfma_f32_32x32x16_bf16 v[48:63], v[8:11], v[76:79], v[48:63]
	ds_read_b64_tr_b16 v[76:77],v3 offset:5120
	ds_read_b64_tr_b16 v[78:79],v3 offset:5632
	v_mfma_f32_32x32x16_bf16 v[48:63], v[64:67], v[80:83], v[48:63]
	ds_read_b64_tr_b16 v[80:81],v3 offset:6144
	ds_read_b64_tr_b16 v[82:83],v3 offset:6656
	ds_read_b64_tr_b16 v[88:89],v3 offset:7168
	ds_read_b64_tr_b16 v[90:91],v3 offset:7680
	s_waitcnt lgkmcnt(0)
	v_mfma_f32_32x32x16_bf16 v[48:63], v[68:71], v[84:87], v[48:63]
	v_mfma_f32_32x32x16_bf16 v[32:47], v[4:7], v[72:75], v[32:47]
	v_mov_b32_e32 v3, v2
	s_nop 1
	v_permlane32_swap_b32_e32 v2, v3
	v_mfma_f32_32x32x16_bf16 v[32:47], v[8:11], v[76:79], v[32:47]
	v_mfma_f32_32x32x16_bf16 v[32:47], v[64:67], v[80:83], v[32:47]
	v_mfma_f32_32x32x16_bf16 v[32:47], v[68:71], v[88:91], v[32:47]
	s_and_saveexec_b64 s[6:7], s[4:5]
	v_add_f32_e32 v2, v2, v3
	ds_write_b32 v239, v2 offset:128
	s_or_b64 exec, exec, s[6:7]
	s_waitcnt lgkmcnt(0)
	ds_read_b128 v[2:5], v234 offset:128
	ds_read_b128 v[6:9], v234 offset:160
	s_lshl_b32 s4, s95, 12
	s_add_i32 s4, s4, 0
	s_add_i32 s4, s4, 0x14800
	s_waitcnt lgkmcnt(1)
	v_rcp_f32_e32 v10, v2
	v_rcp_f32_e32 v11, v3
	v_lshlrev_b32_e32 v68, 9, v238
	v_lshlrev_b32_e32 v69, 1, v237
	v_mul_f32_e32 v48, v48, v10
	v_mul_f32_e32 v10, v32, v10
	v_add3_u32 v68, s4, v68, v69
	v_cvt_pk_bf16_f32 v10, v10, s0
	v_rcp_f32_e32 v12, v4
	ds_write_b16 v68, v10 offset:64
	v_mul_f32_e32 v10, v49, v11
	v_cvt_pk_bf16_f32 v10, v10, s0
	ds_write_b16 v68, v10 offset:128
	v_mul_f32_e32 v10, v33, v11
	v_cvt_pk_bf16_f32 v10, v10, s0
	v_rcp_f32_e32 v13, v5
	ds_write_b16 v68, v10 offset:192
	v_mul_f32_e32 v10, v50, v12
	v_cvt_pk_bf16_f32 v10, v10, s0
	ds_write_b16 v68, v10 offset:256
	v_mul_f32_e32 v10, v34, v12
	v_cvt_pk_bf16_f32 v10, v10, s0
	s_waitcnt lgkmcnt(4)
	v_rcp_f32_e32 v64, v6
	ds_write_b16 v68, v10 offset:320
	v_mul_f32_e32 v10, v51, v13
	v_cvt_pk_bf16_f32 v10, v10, s0
	ds_write_b16 v68, v10 offset:384
	v_mul_f32_e32 v10, v35, v13
	v_cvt_pk_bf16_f32 v10, v10, s0
	v_rcp_f32_e32 v65, v7
	ds_write_b16 v68, v10 offset:448
	v_mul_f32_e32 v10, v52, v64
	v_cvt_pk_bf16_f32 v10, v10, s0
	ds_write_b16 v68, v10 offset:1024
	v_mul_f32_e32 v10, v36, v64
	v_cvt_pk_bf16_f32 v10, v10, s0
	v_rcp_f32_e32 v66, v8
	ds_write_b16 v68, v10 offset:1088
	v_mul_f32_e32 v10, v53, v65
	v_cvt_pk_bf16_f32 v10, v10, s0
	ds_write_b16 v68, v10 offset:1152
	v_mul_f32_e32 v10, v37, v65
	ds_read_b128 v[2:5], v234 offset:192
	v_cvt_pk_bf16_f32 v10, v10, s0
	v_rcp_f32_e32 v67, v9
	ds_write_b16 v68, v10 offset:1216
	v_mul_f32_e32 v10, v54, v66
	v_cvt_pk_bf16_f32 v10, v10, s0
	ds_write_b16 v68, v10 offset:1280
	v_mul_f32_e32 v10, v38, v66
	v_cvt_pk_bf16_f32 v10, v10, s0
	ds_read_b128 v[6:9], v234 offset:224
	s_waitcnt lgkmcnt(3)
	v_rcp_f32_e32 v2, v2
	ds_write_b16 v68, v10 offset:1344
	v_mul_f32_e32 v10, v55, v67
	v_cvt_pk_bf16_f32 v10, v10, s0
	v_rcp_f32_e32 v3, v3
	ds_write_b16 v68, v10 offset:1408
	v_mul_f32_e32 v10, v39, v67
	v_cvt_pk_bf16_f32 v10, v10, s0
	ds_write_b16 v68, v10 offset:1472
	v_mul_f32_e32 v10, v56, v2
	v_mul_f32_e32 v2, v40, v2
	v_cvt_pk_bf16_f32 v2, v2, s0
	v_rcp_f32_e32 v4, v4
	ds_write_b16 v68, v2 offset:2112
	v_mul_f32_e32 v2, v57, v3
	v_cvt_pk_bf16_f32 v2, v2, s0
	ds_write_b16 v68, v2 offset:2176
	v_mul_f32_e32 v2, v41, v3
	v_cvt_pk_bf16_f32 v2, v2, s0
	v_rcp_f32_e32 v5, v5
	ds_write_b16 v68, v2 offset:2240
	v_mul_f32_e32 v2, v58, v4
	v_cvt_pk_bf16_f32 v2, v2, s0
	ds_write_b16 v68, v2 offset:2304
	v_mul_f32_e32 v2, v42, v4
	v_cvt_pk_bf16_f32 v2, v2, s0
	s_waitcnt lgkmcnt(7)
	v_rcp_f32_e32 v6, v6
	ds_write_b16 v68, v2 offset:2368
	v_mul_f32_e32 v2, v59, v5
	v_cvt_pk_bf16_f32 v2, v2, s0
	ds_write_b16 v68, v2 offset:2432
	v_mul_f32_e32 v2, v43, v5
	v_cvt_pk_bf16_f32 v2, v2, s0
	v_rcp_f32_e32 v7, v7
	ds_write_b16 v68, v2 offset:2496
	v_mul_f32_e32 v2, v60, v6
	v_cvt_pk_bf16_f32 v2, v2, s0
	ds_write_b16 v68, v2 offset:3072
	v_mul_f32_e32 v2, v44, v6
	v_cvt_pk_bf16_f32 v2, v2, s0
	v_rcp_f32_e32 v8, v8
	ds_write_b16 v68, v2 offset:3136
	v_mul_f32_e32 v2, v61, v7
	v_cvt_pk_bf16_f32 v2, v2, s0
	ds_write_b16 v68, v2 offset:3200
	v_mul_f32_e32 v2, v45, v7
	v_cvt_pk_bf16_f32 v2, v2, s0
	v_rcp_f32_e32 v9, v9
	ds_write_b16 v68, v2 offset:3264
	v_mul_f32_e32 v2, v62, v8
	v_cvt_pk_bf16_f32 v2, v2, s0
	ds_write_b16 v68, v2 offset:3328
	v_mul_f32_e32 v2, v46, v8
	v_cvt_pk_bf16_f32 v2, v2, s0
	ds_write_b16 v68, v2 offset:3392
	v_mul_f32_e32 v2, v63, v9
	s_waitcnt vmcnt(3)
	v_lshlrev_b32_e32 v12, 16, v140
	v_cvt_pk_bf16_f32 v2, v2, s0
	v_and_b32_e32 v13, 0xffff0000, v140
	v_mul_f32_e32 v4, 0xbfb8aa3b, v12
	ds_write_b16 v68, v2 offset:3456
	v_mul_f32_e32 v2, v47, v9
	v_exp_f32_e32 v8, v4
	v_mul_f32_e32 v4, 0xbfb8aa3b, v13
	v_cvt_pk_bf16_f32 v48, v48, s0
	v_cvt_pk_bf16_f32 v10, v10, s0
	v_cvt_pk_bf16_f32 v2, v2, s0
	v_exp_f32_e32 v9, v4
	ds_write_b16 v68, v48
	ds_write_b16 v68, v10 offset:2048
	ds_write_b16 v68, v2 offset:3520
	v_add_u32_e32 v36, s4, v0
	s_waitcnt lgkmcnt(0)
	v_lshl_add_u64 v[2:3], s[50:51], 0, v[0:1]
	v_lshl_add_u32 v0, v224, 7, v36
	ds_read_b128 v[4:7], v0
	v_add_f32_e32 v0, 1.0, v8
	v_rcp_f32_e32 v32, v0
	v_add_f32_e32 v0, 1.0, v9
	v_rcp_f32_e32 v33, v0
	s_waitcnt lgkmcnt(0)
	v_lshlrev_b32_e32 v34, 16, v4
	v_and_b32_e32 v35, 0xffff0000, v4
	s_bitset1_b32 s8, 10
	v_pk_mul_f32 v[12:13], v[32:33], v[12:13]
	v_lshlrev_b32_e32 v32, 16, v141
	v_and_b32_e32 v33, 0xffff0000, v141
	v_mul_f32_e32 v4, 0xbfb8aa3b, v32
	v_exp_f32_e32 v4, v4
	v_mul_f32_e32 v37, 0xbfb8aa3b, v33
	v_exp_f32_e32 v37, v37
	v_pk_mul_f32 v[12:13], v[12:13], v[34:35]
	v_add_f32_e32 v4, 1.0, v4
	v_rcp_f32_e32 v34, v4
	v_add_f32_e32 v4, 1.0, v37
	v_rcp_f32_e32 v35, v4
	v_cvt_pk_bf16_f32 v4, v12, v13
	v_lshlrev_b32_e32 v12, 16, v5
	v_and_b32_e32 v13, 0xffff0000, v5
	v_pk_mul_f32 v[32:33], v[34:35], v[32:33]
	v_lshlrev_b32_e32 v34, 16, v142
	v_and_b32_e32 v35, 0xffff0000, v142
	v_mul_f32_e32 v5, 0xbfb8aa3b, v34
	v_exp_f32_e32 v5, v5
	v_mul_f32_e32 v37, 0xbfb8aa3b, v35
	v_exp_f32_e32 v37, v37
	v_pk_mul_f32 v[12:13], v[32:33], v[12:13]
	v_add_f32_e32 v5, 1.0, v5
	v_rcp_f32_e32 v32, v5
	v_add_f32_e32 v5, 1.0, v37
	v_rcp_f32_e32 v33, v5
	v_cvt_pk_bf16_f32 v5, v12, v13
	v_lshlrev_b32_e32 v12, 16, v6
	v_and_b32_e32 v13, 0xffff0000, v6
	v_pk_mul_f32 v[32:33], v[32:33], v[34:35]
	v_lshlrev_b32_e32 v34, 16, v143
	v_and_b32_e32 v35, 0xffff0000, v143
	v_mul_f32_e32 v6, 0xbfb8aa3b, v34
	v_exp_f32_e32 v6, v6
	v_mul_f32_e32 v37, 0xbfb8aa3b, v35
	v_exp_f32_e32 v37, v37
	v_pk_mul_f32 v[12:13], v[32:33], v[12:13]
	v_add_f32_e32 v6, 1.0, v6
	v_rcp_f32_e32 v32, v6
	v_add_f32_e32 v6, 1.0, v37
	v_rcp_f32_e32 v33, v6
	v_cvt_pk_bf16_f32 v6, v12, v13
	v_lshlrev_b32_e32 v12, 16, v7
	v_and_b32_e32 v13, 0xffff0000, v7
	v_pk_mul_f32 v[32:33], v[32:33], v[34:35]
	v_or_b32_e32 v0, 8, v224
	v_pk_mul_f32 v[12:13], v[32:33], v[12:13]
	v_lshl_add_u32 v8, v0, 7, v36
	v_cvt_pk_bf16_f32 v7, v12, v13
	v_lshl_add_u64 v[12:13], v[2:3], 0, v[14:15]
	v_lshl_add_u64 v[12:13], v[12:13], 0, s[8:9]
	global_store_dwordx4 v[12:13], v[4:7], off
	ds_read_b128 v[8:11], v8
	s_mov_b64 s[4:5], 0
	s_waitcnt vmcnt(3)
	v_lshlrev_b32_e32 v6, 16, v136
	v_and_b32_e32 v7, 0xffff0000, v136
	v_mul_f32_e32 v4, 0xbfb8aa3b, v6
	v_exp_f32_e32 v5, v4
	v_mul_f32_e32 v4, 0xbfb8aa3b, v7
	v_exp_f32_e32 v13, v4
	v_or_b32_e32 v4, s94, v0
	v_add_f32_e32 v0, 1.0, v5
	v_rcp_f32_e32 v12, v0
	v_add_f32_e32 v0, 1.0, v13
	v_rcp_f32_e32 v13, v0
	s_waitcnt lgkmcnt(0)
	v_lshlrev_b32_e32 v14, 16, v8
	v_and_b32_e32 v15, 0xffff0000, v8
	v_mov_b32_e32 v5, s96
	v_pk_mul_f32 v[6:7], v[12:13], v[6:7]
	v_lshlrev_b32_e32 v12, 16, v137
	v_and_b32_e32 v13, 0xffff0000, v137
	v_mul_f32_e32 v0, 0xbfb8aa3b, v12
	v_exp_f32_e32 v0, v0
	v_mul_f32_e32 v8, 0xbfb8aa3b, v13
	v_exp_f32_e32 v8, v8
	v_pk_mul_f32 v[6:7], v[6:7], v[14:15]
	v_add_f32_e32 v0, 1.0, v0
	v_rcp_f32_e32 v14, v0
	v_add_f32_e32 v0, 1.0, v8
	v_rcp_f32_e32 v15, v0
	v_cvt_pk_bf16_f32 v6, v6, v7
	v_lshlrev_b32_e32 v8, 16, v9
	v_and_b32_e32 v9, 0xffff0000, v9
	v_pk_mul_f32 v[12:13], v[14:15], v[12:13]
	v_lshlrev_b32_e32 v14, 16, v138
	v_and_b32_e32 v15, 0xffff0000, v138
	v_mul_f32_e32 v0, 0xbfb8aa3b, v14
	v_exp_f32_e32 v0, v0
	v_mul_f32_e32 v7, 0xbfb8aa3b, v15
	v_exp_f32_e32 v7, v7
	v_pk_mul_f32 v[8:9], v[12:13], v[8:9]
	v_add_f32_e32 v0, 1.0, v0
	v_rcp_f32_e32 v12, v0
	v_add_f32_e32 v0, 1.0, v7
	v_rcp_f32_e32 v13, v0
	v_cvt_pk_bf16_f32 v7, v8, v9
	v_lshlrev_b32_e32 v8, 16, v10
	v_and_b32_e32 v9, 0xffff0000, v10
	v_pk_mul_f32 v[12:13], v[12:13], v[14:15]
	v_lshlrev_b32_e32 v14, 16, v139
	v_and_b32_e32 v15, 0xffff0000, v139
	v_mul_f32_e32 v0, 0xbfb8aa3b, v14
	v_exp_f32_e32 v0, v0
	v_mul_f32_e32 v10, 0xbfb8aa3b, v15
	v_exp_f32_e32 v10, v10
	v_pk_mul_f32 v[8:9], v[12:13], v[8:9]
	v_add_f32_e32 v0, 1.0, v0
	v_rcp_f32_e32 v12, v0
	v_add_f32_e32 v0, 1.0, v10
	v_rcp_f32_e32 v13, v0
	v_lshlrev_b32_e32 v10, 16, v11
	v_and_b32_e32 v11, 0xffff0000, v11
	v_cvt_pk_bf16_f32 v8, v8, v9
	v_pk_mul_f32 v[12:13], v[12:13], v[14:15]
	v_or_b32_e32 v0, 16, v224
	v_pk_mul_f32 v[10:11], v[12:13], v[10:11]
	s_waitcnt vmcnt(2)
	v_lshlrev_b32_e32 v14, 16, v132
	v_cvt_pk_bf16_f32 v9, v10, v11
	v_lshlrev_b64 v[10:11], 11, v[4:5]
	v_lshl_add_u64 v[10:11], v[2:3], 0, v[10:11]
	v_lshl_add_u64 v[10:11], v[10:11], 0, s[8:9]
	v_lshl_add_u32 v4, v0, 7, v36
	global_store_dwordx4 v[10:11], v[6:9], off
	ds_read_b128 v[6:9], v4
	v_and_b32_e32 v15, 0xffff0000, v132
	v_mul_f32_e32 v4, 0xbfb8aa3b, v14
	v_exp_f32_e32 v10, v4
	v_mul_f32_e32 v4, 0xbfb8aa3b, v15
	v_exp_f32_e32 v11, v4
	v_or_b32_e32 v4, s94, v0
	v_add_f32_e32 v0, 1.0, v10
	v_rcp_f32_e32 v32, v0
	v_add_f32_e32 v0, 1.0, v11
	v_rcp_f32_e32 v33, v0
	v_or_b32_e32 v0, 24, v224
	s_waitcnt lgkmcnt(0)
	v_lshlrev_b32_e32 v34, 16, v6
	v_and_b32_e32 v35, 0xffff0000, v6
	v_pk_mul_f32 v[14:15], v[32:33], v[14:15]
	v_lshlrev_b32_e32 v32, 16, v133
	v_and_b32_e32 v33, 0xffff0000, v133
	v_mul_f32_e32 v6, 0xbfb8aa3b, v32
	v_lshl_add_u32 v10, v0, 7, v36
	v_exp_f32_e32 v6, v6
	v_mul_f32_e32 v36, 0xbfb8aa3b, v33
	v_exp_f32_e32 v36, v36
	v_pk_mul_f32 v[14:15], v[14:15], v[34:35]
	v_add_f32_e32 v6, 1.0, v6
	v_rcp_f32_e32 v34, v6
	v_add_f32_e32 v6, 1.0, v36
	v_rcp_f32_e32 v35, v6
	v_cvt_pk_bf16_f32 v6, v14, v15
	v_lshlrev_b32_e32 v14, 16, v7
	v_and_b32_e32 v15, 0xffff0000, v7
	v_pk_mul_f32 v[32:33], v[34:35], v[32:33]
	v_lshlrev_b32_e32 v34, 16, v134
	v_and_b32_e32 v35, 0xffff0000, v134
	v_mul_f32_e32 v7, 0xbfb8aa3b, v34
	v_exp_f32_e32 v7, v7
	v_mul_f32_e32 v36, 0xbfb8aa3b, v35
	v_exp_f32_e32 v36, v36
	v_pk_mul_f32 v[14:15], v[32:33], v[14:15]
	v_add_f32_e32 v7, 1.0, v7
	v_rcp_f32_e32 v32, v7
	v_add_f32_e32 v7, 1.0, v36
	v_rcp_f32_e32 v33, v7
	v_cvt_pk_bf16_f32 v7, v14, v15
	v_lshlrev_b32_e32 v14, 16, v8
	v_and_b32_e32 v15, 0xffff0000, v8
	v_pk_mul_f32 v[32:33], v[32:33], v[34:35]
	v_lshlrev_b32_e32 v34, 16, v135
	v_and_b32_e32 v35, 0xffff0000, v135
	v_mul_f32_e32 v8, 0xbfb8aa3b, v34
	v_exp_f32_e32 v8, v8
	v_mul_f32_e32 v36, 0xbfb8aa3b, v35
	v_exp_f32_e32 v36, v36
	v_pk_mul_f32 v[14:15], v[32:33], v[14:15]
	v_add_f32_e32 v8, 1.0, v8
	v_rcp_f32_e32 v32, v8
	v_add_f32_e32 v8, 1.0, v36
	v_rcp_f32_e32 v33, v8
	v_cvt_pk_bf16_f32 v8, v14, v15
	v_lshlrev_b32_e32 v14, 16, v9
	v_and_b32_e32 v15, 0xffff0000, v9
	v_pk_mul_f32 v[32:33], v[32:33], v[34:35]
	ds_read_b128 v[10:13], v10
	v_pk_mul_f32 v[14:15], v[32:33], v[14:15]
	s_waitcnt vmcnt(2)
	v_lshlrev_b32_e32 v32, 16, v128
	v_cvt_pk_bf16_f32 v9, v14, v15
	v_lshlrev_b64 v[14:15], 11, v[4:5]
	v_and_b32_e32 v33, 0xffff0000, v128
	v_mul_f32_e32 v4, 0xbfb8aa3b, v32
	v_exp_f32_e32 v4, v4
	v_mul_f32_e32 v34, 0xbfb8aa3b, v33
	v_exp_f32_e32 v34, v34
	v_lshl_add_u64 v[14:15], v[2:3], 0, v[14:15]
	v_lshl_add_u64 v[14:15], v[14:15], 0, s[8:9]
	v_add_f32_e32 v4, 1.0, v4
	global_store_dwordx4 v[14:15], v[6:9], off
	v_lshlrev_b32_e32 v14, 16, v129
	v_and_b32_e32 v15, 0xffff0000, v129
	v_rcp_f32_e32 v6, v4
	v_add_f32_e32 v4, 1.0, v34
	v_rcp_f32_e32 v7, v4
	v_or_b32_e32 v4, s94, v0
	v_mul_f32_e32 v0, 0xbfb8aa3b, v14
	s_waitcnt lgkmcnt(0)
	v_lshlrev_b32_e32 v8, 16, v10
	v_and_b32_e32 v9, 0xffff0000, v10
	v_exp_f32_e32 v0, v0
	v_mul_f32_e32 v10, 0xbfb8aa3b, v15
	v_exp_f32_e32 v10, v10
	v_pk_mul_f32 v[6:7], v[6:7], v[32:33]
	v_add_f32_e32 v0, 1.0, v0
	v_pk_mul_f32 v[6:7], v[6:7], v[8:9]
	v_rcp_f32_e32 v8, v0
	v_add_f32_e32 v0, 1.0, v10
	v_rcp_f32_e32 v9, v0
	v_cvt_pk_bf16_f32 v6, v6, v7
	v_lshlrev_b32_e32 v10, 16, v11
	v_and_b32_e32 v11, 0xffff0000, v11
	v_pk_mul_f32 v[8:9], v[8:9], v[14:15]
	v_lshlrev_b32_e32 v14, 16, v130
	v_and_b32_e32 v15, 0xffff0000, v130
	v_mul_f32_e32 v0, 0xbfb8aa3b, v14
	v_exp_f32_e32 v0, v0
	v_mul_f32_e32 v7, 0xbfb8aa3b, v15
	v_exp_f32_e32 v7, v7
	v_pk_mul_f32 v[8:9], v[8:9], v[10:11]
	v_add_f32_e32 v0, 1.0, v0
	v_rcp_f32_e32 v10, v0
	v_add_f32_e32 v0, 1.0, v7
	v_rcp_f32_e32 v11, v0
	v_cvt_pk_bf16_f32 v7, v8, v9
	v_lshlrev_b32_e32 v8, 16, v12
	v_and_b32_e32 v9, 0xffff0000, v12
	v_pk_mul_f32 v[10:11], v[10:11], v[14:15]
	v_lshlrev_b32_e32 v14, 16, v131
	v_and_b32_e32 v15, 0xffff0000, v131
	v_mul_f32_e32 v0, 0xbfb8aa3b, v14
	v_exp_f32_e32 v0, v0
	v_mul_f32_e32 v12, 0xbfb8aa3b, v15
	v_exp_f32_e32 v12, v12
	v_pk_mul_f32 v[8:9], v[10:11], v[8:9]
	v_add_f32_e32 v0, 1.0, v0
	v_rcp_f32_e32 v10, v0
	v_add_f32_e32 v0, 1.0, v12
	v_rcp_f32_e32 v11, v0
	v_lshlrev_b32_e32 v12, 16, v13
	v_and_b32_e32 v13, 0xffff0000, v13
	v_lshlrev_b64 v[4:5], 11, v[4:5]
	v_pk_mul_f32 v[10:11], v[10:11], v[14:15]
	v_lshl_add_u64 v[2:3], v[2:3], 0, v[4:5]
	v_pk_mul_f32 v[10:11], v[10:11], v[12:13]
	v_cvt_pk_bf16_f32 v8, v8, v9
	v_cvt_pk_bf16_f32 v9, v10, v11
	v_lshl_add_u64 v[2:3], v[2:3], 0, s[8:9]
	global_store_dwordx4 v[2:3], v[6:9], off
	s_waitcnt lgkmcnt(0)
	s_barrier

.LBB0_1313:
	s_mov_b32 s6, s47
	s_mov_b32 s7, s46
	v_add_u32_e32 v214, s7, v206
	ds_read_b64_tr_b16 v[210:211], v214 offset:32768
	ds_read_b64_tr_b16 v[212:213], v214 offset:33280
	v_add_f32_e32 v2, v96, v97
	v_add_f32_e32 v2, v98, v2
	v_add_f32_e32 v2, v99, v2
	v_add_f32_e32 v2, v100, v2
	v_add_f32_e32 v2, v101, v2
	v_cvt_pk_bf16_f32 v160, v96, v97
	v_cvt_pk_bf16_f32 v161, v98, v99
	s_waitcnt lgkmcnt(9)
	v_mfma_f32_32x32x16_bf16 v[128:143], v[112:115], v[172:175], v[32:47]
	ds_read_b64_tr_b16 v[96:97], v214 offset:36864
	ds_read_b64_tr_b16 v[98:99], v214 offset:37376
	s_waitcnt lgkmcnt(10)
	v_mfma_f32_32x32x16_bf16 v[112:127], v[188:191], v[172:175], v[32:47]
	v_add_f32_e32 v2, v102, v2
	v_add_f32_e32 v2, v103, v2
	v_add_f32_e32 v2, v104, v2
	v_add_f32_e32 v2, v105, v2
	v_cvt_pk_bf16_f32 v162, v100, v101
	v_cvt_pk_bf16_f32 v163, v102, v103
	ds_read_b64_tr_b16 v[100:101], v214 offset:33792
	ds_read_b64_tr_b16 v[102:103], v214 offset:34304
	v_add_f32_e32 v2, v106, v2
	v_add_f32_e32 v2, v107, v2
	v_add_f32_e32 v2, v108, v2
	v_add_f32_e32 v2, v109, v2
	v_cvt_pk_bf16_f32 v10, v104, v105
	v_cvt_pk_bf16_f32 v11, v106, v107
	s_waitcnt lgkmcnt(11)
	v_mfma_f32_32x32x16_bf16 v[128:143], v[184:187], v[176:179], v[128:143]
	ds_read_b64_tr_b16 v[104:105], v214 offset:37888
	ds_read_b64_tr_b16 v[106:107], v214 offset:38400
	s_waitcnt lgkmcnt(12)
	v_mfma_f32_32x32x16_bf16 v[112:127], v[180:183], v[176:179], v[112:127]
	v_add_f32_e32 v2, v110, v2
	v_add_f32_e32 v2, v111, v2
	v_add_f32_e32 v2, v80, v2
	v_add_f32_e32 v2, v81, v2
	v_cvt_pk_bf16_f32 v12, v108, v109
	v_cvt_pk_bf16_f32 v13, v110, v111
	ds_read_b64_tr_b16 v[108:109], v214 offset:34816
	ds_read_b64_tr_b16 v[110:111], v214 offset:35328
	v_add_f32_e32 v2, v82, v2
	v_add_f32_e32 v2, v83, v2
	v_add_f32_e32 v2, v84, v2
	v_add_f32_e32 v2, v85, v2
	v_cvt_pk_bf16_f32 v6, v80, v81
	v_cvt_pk_bf16_f32 v7, v82, v83
	s_waitcnt lgkmcnt(13)
	v_mfma_f32_32x32x16_bf16 v[128:143], v[156:159], v[168:171], v[128:143]
	ds_read_b64_tr_b16 v[80:81], v214 offset:38912
	ds_read_b64_tr_b16 v[82:83], v214 offset:39424
	s_waitcnt lgkmcnt(14)
	v_mfma_f32_32x32x16_bf16 v[112:127], v[152:155], v[168:171], v[112:127]
	v_add_f32_e32 v2, v86, v2
	v_add_f32_e32 v2, v87, v2
	v_add_f32_e32 v2, v88, v2
	v_add_f32_e32 v2, v89, v2
	v_cvt_pk_bf16_f32 v8, v84, v85
	v_cvt_pk_bf16_f32 v9, v86, v87
	ds_read_b64_tr_b16 v[84:85], v214 offset:35840
	ds_read_b64_tr_b16 v[86:87], v214 offset:36352
	v_add_f32_e32 v2, v90, v2
	v_add_f32_e32 v2, v91, v2
	v_add_f32_e32 v2, v92, v2
	s_waitcnt lgkmcnt(14)
	v_mfma_f32_32x32x16_bf16 v[128:143], v[148:151], v[164:167], v[128:143]
	v_add_f32_e32 v148, v93, v2
	v_cvt_pk_bf16_f32 v2, v88, v89
	v_cvt_pk_bf16_f32 v3, v90, v91
	ds_read_b64_tr_b16 v[88:89], v214 offset:39936
	ds_read_b64_tr_b16 v[90:91], v214 offset:40448
	v_mfma_f32_32x32x16_bf16 v[112:127], v[144:147], v[164:167], v[112:127]
	v_add_f32_e32 v4, v94, v148
	v_add_f32_e32 v144, v95, v4
	v_cvt_pk_bf16_f32 v4, v92, v93
	v_cvt_pk_bf16_f32 v5, v94, v95
	v_lshl_add_u64 v[92:93], v[196:197], 0, s[14:15]
	s_add_i32 s46, s47, s31
	s_mov_b32 s47, m0
	s_mov_b32 m0, s46
	s_nop 0
	global_load_lds_dwordx4 v[92:93], off
	s_mov_b32 m0, s47
	s_add_i32 s46, s45, s42
	s_mov_b32 s47, m0
	s_mov_b32 m0, s46
	s_nop 0
	global_load_lds_dwordx4 v[194:195], off
	s_mov_b32 m0, s47
	v_add_f32_e32 v0, v0, v144
	s_waitcnt lgkmcnt(14)
	v_mfma_f32_32x32x16_bf16 v[48:63], v[160:163], v[210:213], v[48:63]
	v_exp_f32_e32 v128, v128
	v_exp_f32_e32 v129, v129
	v_exp_f32_e32 v130, v130
	v_exp_f32_e32 v131, v131
	s_waitcnt lgkmcnt(12)
	v_mfma_f32_32x32x16_bf16 v[64:79], v[160:163], v[96:99], v[64:79]
	v_exp_f32_e32 v132, v132
	v_exp_f32_e32 v133, v133
	v_exp_f32_e32 v134, v134
	v_exp_f32_e32 v135, v135
	v_add_u32_e32 v96, s44, v208
	ds_read_b128 v[92:95], v96
	ds_read_b128 v[148:151], v96 offset:2048
	v_add_u32_e32 v97, s44, v209
	s_waitcnt lgkmcnt(12)
	v_mfma_f32_32x32x16_bf16 v[48:63], v[10:13], v[100:103], v[48:63]
	v_exp_f32_e32 v136, v136
	v_exp_f32_e32 v137, v137
	v_exp_f32_e32 v138, v138
	v_exp_f32_e32 v139, v139
	ds_read_b128 v[152:155], v97
	ds_read_b128 v[156:159], v97 offset:2048
	s_waitcnt lgkmcnt(12)
	v_mfma_f32_32x32x16_bf16 v[64:79], v[10:13], v[104:107], v[64:79]
	v_exp_f32_e32 v140, v140
	v_exp_f32_e32 v141, v141
	v_exp_f32_e32 v142, v142
	v_exp_f32_e32 v143, v143
	ds_read_b128 v[180:183], v96 offset:4096
	ds_read_b128 v[184:187], v96 offset:6144
	s_waitcnt lgkmcnt(12)
	v_mfma_f32_32x32x16_bf16 v[48:63], v[6:9], v[108:111], v[48:63]
	v_exp_f32_e32 v112, v112
	v_exp_f32_e32 v113, v113
	v_exp_f32_e32 v114, v114
	v_exp_f32_e32 v115, v115
	ds_read_b128 v[188:191], v97 offset:4096
	ds_read_b128 v[144:147], v97 offset:6144
	s_waitcnt lgkmcnt(12)
	v_mfma_f32_32x32x16_bf16 v[64:79], v[6:9], v[80:83], v[64:79]
	v_exp_f32_e32 v116, v116
	v_exp_f32_e32 v117, v117
	v_exp_f32_e32 v118, v118
	v_exp_f32_e32 v119, v119
	s_waitcnt lgkmcnt(10)
	v_mfma_f32_32x32x16_bf16 v[48:63], v[2:5], v[84:87], v[48:63]
	v_exp_f32_e32 v120, v120
	v_exp_f32_e32 v121, v121
	v_exp_f32_e32 v122, v122
	v_exp_f32_e32 v123, v123
	s_waitcnt lgkmcnt(8)
	v_mfma_f32_32x32x16_bf16 v[64:79], v[2:5], v[88:91], v[64:79]
	v_exp_f32_e32 v124, v124
	v_exp_f32_e32 v125, v125
	v_exp_f32_e32 v126, v126
	v_exp_f32_e32 v127, v127
	s_waitcnt vmcnt(4) lgkmcnt(0)
	s_barrier
	v_add_u32_e32 v218, s6, v206
	ds_read_b64_tr_b16 v[210:211], v218 offset:32768
	ds_read_b64_tr_b16 v[212:213], v218 offset:33280
	s_waitcnt lgkmcnt(9)
	v_mfma_f32_32x32x16_bf16 v[96:111], v[92:95], v[172:175], v[32:47]
	v_add_f32_e32 v2, v128, v129
	v_add_f32_e32 v2, v130, v2
	v_add_f32_e32 v2, v131, v2
	v_add_f32_e32 v2, v132, v2
	v_add_f32_e32 v2, v133, v2
	v_cvt_pk_bf16_f32 v160, v128, v129
	v_cvt_pk_bf16_f32 v161, v130, v131
	ds_read_b64_tr_b16 v[128:129], v218 offset:36864
	ds_read_b64_tr_b16 v[130:131], v218 offset:37376
	s_waitcnt lgkmcnt(10)
	v_mfma_f32_32x32x16_bf16 v[80:95], v[148:151], v[172:175], v[32:47]
	v_add_f32_e32 v2, v134, v2
	v_add_f32_e32 v2, v135, v2
	v_add_f32_e32 v2, v136, v2
	v_add_f32_e32 v2, v137, v2
	v_cvt_pk_bf16_f32 v162, v132, v133
	v_cvt_pk_bf16_f32 v163, v134, v135
	ds_read_b64_tr_b16 v[132:133], v218 offset:33792
	ds_read_b64_tr_b16 v[134:135], v218 offset:34304
	s_waitcnt lgkmcnt(11)
	v_mfma_f32_32x32x16_bf16 v[96:111], v[152:155], v[176:179], v[96:111]
	v_add_f32_e32 v2, v138, v2
	v_add_f32_e32 v2, v139, v2
	v_add_f32_e32 v2, v140, v2
	v_add_f32_e32 v2, v141, v2
	v_cvt_pk_bf16_f32 v10, v136, v137
	v_cvt_pk_bf16_f32 v11, v138, v139
	ds_read_b64_tr_b16 v[136:137], v218 offset:37888
	ds_read_b64_tr_b16 v[138:139], v218 offset:38400
	s_waitcnt lgkmcnt(12)
	v_mfma_f32_32x32x16_bf16 v[80:95], v[156:159], v[176:179], v[80:95]
	v_add_f32_e32 v2, v142, v2
	v_add_f32_e32 v2, v143, v2
	v_add_f32_e32 v2, v112, v2
	v_add_f32_e32 v2, v113, v2
	v_cvt_pk_bf16_f32 v12, v140, v141
	v_cvt_pk_bf16_f32 v13, v142, v143
	ds_read_b64_tr_b16 v[140:141], v218 offset:34816
	ds_read_b64_tr_b16 v[142:143], v218 offset:35328
	s_waitcnt lgkmcnt(13)
	v_mfma_f32_32x32x16_bf16 v[96:111], v[180:183], v[168:171], v[96:111]
	v_add_f32_e32 v2, v114, v2
	v_add_f32_e32 v2, v115, v2
	v_add_f32_e32 v2, v116, v2
	v_add_f32_e32 v2, v117, v2
	v_cvt_pk_bf16_f32 v6, v112, v113
	v_cvt_pk_bf16_f32 v7, v114, v115
	ds_read_b64_tr_b16 v[214:215], v218 offset:38912
	ds_read_b64_tr_b16 v[216:217], v218 offset:39424
	s_waitcnt lgkmcnt(14)
	v_mfma_f32_32x32x16_bf16 v[80:95], v[184:187], v[168:171], v[80:95]
	v_add_f32_e32 v2, v118, v2
	v_add_f32_e32 v2, v119, v2
	v_add_f32_e32 v2, v120, v2
	v_add_f32_e32 v2, v121, v2
	v_cvt_pk_bf16_f32 v8, v116, v117
	v_cvt_pk_bf16_f32 v9, v118, v119
	ds_read_b64_tr_b16 v[116:117], v218 offset:35840
	ds_read_b64_tr_b16 v[118:119], v218 offset:36352
	s_waitcnt lgkmcnt(14)
	v_mfma_f32_32x32x16_bf16 v[96:111], v[188:191], v[164:167], v[96:111]
	v_add_f32_e32 v2, v122, v2
	v_add_f32_e32 v2, v123, v2
	v_add_f32_e32 v2, v124, v2
	v_add_f32_e32 v112, v125, v2
	v_cvt_pk_bf16_f32 v2, v120, v121
	v_cvt_pk_bf16_f32 v3, v122, v123
	ds_read_b64_tr_b16 v[120:121], v218 offset:39936
	ds_read_b64_tr_b16 v[122:123], v218 offset:40448
	v_mfma_f32_32x32x16_bf16 v[80:95], v[144:147], v[164:167], v[80:95]
	v_add_f32_e32 v4, v126, v112
	v_add_f32_e32 v112, v127, v4
	v_cvt_pk_bf16_f32 v4, v124, v125
	v_cvt_pk_bf16_f32 v5, v126, v127
	s_nop 0
	v_add_f32_e32 v0, v0, v112
	v_lshl_add_u64 v[112:113], v[196:197], 0, s[40:41]
	s_add_i32 s46, s44, s31
	s_mov_b32 s47, m0
	s_mov_b32 m0, s46
	s_nop 0
	global_load_lds_dwordx4 v[112:113], off
	s_mov_b32 m0, s47
	v_lshl_add_u64 v[112:113], v[198:199], 0, s[24:25]
	s_add_i32 s46, s7, s42
	s_mov_b32 s47, m0
	s_mov_b32 m0, s46
	s_nop 0
	global_load_lds_dwordx4 v[112:113], off
	s_mov_b32 m0, s47
	s_waitcnt lgkmcnt(14)
	v_mfma_f32_32x32x16_bf16 v[48:63], v[160:163], v[210:213], v[48:63]
	v_exp_f32_e32 v96, v96
	v_exp_f32_e32 v97, v97
	v_exp_f32_e32 v98, v98
	v_exp_f32_e32 v99, v99
	s_waitcnt lgkmcnt(12)
	v_mfma_f32_32x32x16_bf16 v[64:79], v[160:163], v[128:131], v[64:79]
	v_exp_f32_e32 v100, v100
	v_exp_f32_e32 v101, v101
	v_exp_f32_e32 v102, v102
	v_exp_f32_e32 v103, v103
	v_add_u32_e32 v124, s45, v208
	ds_read_b128 v[112:115], v124
	ds_read_b128 v[188:191], v124 offset:2048
	v_add_u32_e32 v125, s45, v209
	s_waitcnt lgkmcnt(12)
	v_mfma_f32_32x32x16_bf16 v[48:63], v[10:13], v[132:135], v[48:63]
	v_exp_f32_e32 v104, v104
	v_exp_f32_e32 v105, v105
	v_exp_f32_e32 v106, v106
	v_exp_f32_e32 v107, v107
	ds_read_b128 v[184:187], v125
	ds_read_b128 v[180:183], v125 offset:2048
	s_waitcnt lgkmcnt(12)
	v_mfma_f32_32x32x16_bf16 v[64:79], v[10:13], v[136:139], v[64:79]
	v_exp_f32_e32 v108, v108
	v_exp_f32_e32 v109, v109
	v_exp_f32_e32 v110, v110
	v_exp_f32_e32 v111, v111
	ds_read_b128 v[156:159], v124 offset:4096
	ds_read_b128 v[152:155], v124 offset:6144
	s_waitcnt lgkmcnt(12)
	v_mfma_f32_32x32x16_bf16 v[48:63], v[6:9], v[140:143], v[48:63]
	v_exp_f32_e32 v80, v80
	v_exp_f32_e32 v81, v81
	v_exp_f32_e32 v82, v82
	v_exp_f32_e32 v83, v83
	ds_read_b128 v[148:151], v125 offset:4096
	ds_read_b128 v[144:147], v125 offset:6144
	s_waitcnt lgkmcnt(12)
	v_mfma_f32_32x32x16_bf16 v[64:79], v[6:9], v[214:217], v[64:79]
	v_exp_f32_e32 v84, v84
	v_exp_f32_e32 v85, v85
	v_exp_f32_e32 v86, v86
	v_exp_f32_e32 v87, v87
	s_waitcnt lgkmcnt(10)
	v_mfma_f32_32x32x16_bf16 v[48:63], v[2:5], v[116:119], v[48:63]
	v_exp_f32_e32 v88, v88
	v_exp_f32_e32 v89, v89
	v_exp_f32_e32 v90, v90
	v_exp_f32_e32 v91, v91
	s_waitcnt lgkmcnt(8)
	v_mfma_f32_32x32x16_bf16 v[64:79], v[2:5], v[120:123], v[64:79]
	v_exp_f32_e32 v92, v92
	v_exp_f32_e32 v93, v93
	v_exp_f32_e32 v94, v94
	v_exp_f32_e32 v95, v95
	s_waitcnt vmcnt(4) lgkmcnt(0)
	s_barrier
	s_add_i32 s43, s43, 2
	v_lshl_add_u64 v[194:195], v[194:195], 0, s[22:23]
	v_lshl_add_u64 v[196:197], v[196:197], 0, s[22:23]
	v_lshl_add_u64 v[198:199], v[198:199], 0, s[22:23]
	s_mov_b32 s46, s44
	s_mov_b32 s47, s45
	s_mov_b32 s44, s7
	s_cmp_gt_u32 s43, 60
	s_mov_b32 s45, s6
	s_cbranch_scc0 .LBB0_1313
	s_and_b32 s6, s21, 0x3fffffc0
	s_lshl_b32 s6, s6, 2
	s_add_i32 s31, s6, 0
	s_add_i32 s31, s31, 0x10000
	ds_read_b64_tr_b16 v[194:195], v206 offset:49152
	ds_read_b64_tr_b16 v[196:197], v206 offset:49664
	s_waitcnt lgkmcnt(9)
	v_mfma_f32_32x32x16_bf16 v[128:143], v[112:115], v[172:175], v[32:47]
	v_add_f32_e32 v2, v96, v97
	v_add_f32_e32 v2, v98, v2
	v_add_f32_e32 v2, v99, v2
	v_add_f32_e32 v2, v100, v2
	v_add_f32_e32 v2, v101, v2
	v_cvt_pk_bf16_f32 v160, v96, v97
	v_cvt_pk_bf16_f32 v161, v98, v99
	ds_read_b64_tr_b16 v[96:97], v206 offset:53248
	ds_read_b64_tr_b16 v[98:99], v206 offset:53760
	v_add_f32_e32 v2, v102, v2
	v_add_f32_e32 v2, v103, v2
	v_add_f32_e32 v2, v104, v2
	v_add_f32_e32 v2, v105, v2
	v_cvt_pk_bf16_f32 v162, v100, v101
	v_cvt_pk_bf16_f32 v163, v102, v103
	s_waitcnt lgkmcnt(10)
	v_mfma_f32_32x32x16_bf16 v[112:127], v[188:191], v[172:175], v[32:47]
	ds_read_b64_tr_b16 v[100:101], v206 offset:50176
	ds_read_b64_tr_b16 v[102:103], v206 offset:50688
	s_waitcnt lgkmcnt(11)
	v_mfma_f32_32x32x16_bf16 v[128:143], v[184:187], v[176:179], v[128:143]
	v_add_f32_e32 v2, v106, v2
	v_add_f32_e32 v2, v107, v2
	v_add_f32_e32 v2, v108, v2
	v_add_f32_e32 v2, v109, v2
	v_cvt_pk_bf16_f32 v10, v104, v105
	v_cvt_pk_bf16_f32 v11, v106, v107
	ds_read_b64_tr_b16 v[104:105], v206 offset:54272
	ds_read_b64_tr_b16 v[106:107], v206 offset:54784
	v_add_f32_e32 v2, v110, v2
	v_add_f32_e32 v2, v111, v2
	v_add_f32_e32 v2, v80, v2
	v_add_f32_e32 v2, v81, v2
	v_cvt_pk_bf16_f32 v12, v108, v109
	v_cvt_pk_bf16_f32 v13, v110, v111
	s_waitcnt lgkmcnt(12)
	v_mfma_f32_32x32x16_bf16 v[112:127], v[180:183], v[176:179], v[112:127]
	ds_read_b64_tr_b16 v[108:109], v206 offset:51200
	ds_read_b64_tr_b16 v[110:111], v206 offset:51712
	s_waitcnt lgkmcnt(13)
	v_mfma_f32_32x32x16_bf16 v[128:143], v[156:159], v[168:171], v[128:143]
	v_add_f32_e32 v2, v82, v2
	v_add_f32_e32 v2, v83, v2
	v_add_f32_e32 v2, v84, v2
	v_add_f32_e32 v2, v85, v2
	v_cvt_pk_bf16_f32 v6, v80, v81
	v_cvt_pk_bf16_f32 v7, v82, v83
	ds_read_b64_tr_b16 v[80:81], v206 offset:55296
	ds_read_b64_tr_b16 v[82:83], v206 offset:55808
	v_add_f32_e32 v2, v86, v2
	v_add_f32_e32 v2, v87, v2
	v_add_f32_e32 v2, v88, v2
	v_add_f32_e32 v2, v89, v2
	v_cvt_pk_bf16_f32 v8, v84, v85
	v_cvt_pk_bf16_f32 v9, v86, v87
	s_waitcnt lgkmcnt(14)
	v_mfma_f32_32x32x16_bf16 v[112:127], v[152:155], v[168:171], v[112:127]
	ds_read_b64_tr_b16 v[84:85], v206 offset:52224
	ds_read_b64_tr_b16 v[86:87], v206 offset:52736
	s_waitcnt lgkmcnt(14)
	v_mfma_f32_32x32x16_bf16 v[128:143], v[148:151], v[164:167], v[128:143]
	v_add_f32_e32 v2, v90, v2
	v_add_f32_e32 v2, v91, v2
	v_add_f32_e32 v2, v92, v2
	v_add_f32_e32 v152, v93, v2
	v_cvt_pk_bf16_f32 v2, v88, v89
	v_cvt_pk_bf16_f32 v3, v90, v91
	ds_read_b64_tr_b16 v[88:89], v206 offset:56320
	ds_read_b64_tr_b16 v[90:91], v206 offset:56832
	v_add_f32_e32 v4, v94, v152
	v_add_f32_e32 v148, v95, v4
	v_cvt_pk_bf16_f32 v4, v92, v93
	v_cvt_pk_bf16_f32 v5, v94, v95
	v_mfma_f32_32x32x16_bf16 v[112:127], v[144:147], v[164:167], v[112:127]
	s_mov_b64 s[42:43], 0x10c000
	v_lshl_add_u64 v[92:93], v[192:193], 0, s[42:43]
	s_mov_b32 s6, m0
	s_mov_b32 m0, s20
	s_nop 0
	global_load_lds_dwordx4 v[92:93], off
	s_mov_b32 m0, s6
	s_mov_b64 s[6:7], 0x104000
	s_cmp_lg_u32 0, -1
	v_lshl_add_u64 v[92:93], v[14:15], 0, s[6:7]
	s_cselect_b32 s6, 0, 0
	s_add_i32 s7, s6, s8
	s_add_i32 s20, s7, 0xa000
	s_mov_b32 s21, m0
	s_mov_b32 m0, s20
	s_nop 0
	global_load_lds_dwordx4 v[92:93], off
	s_mov_b32 m0, s21
	v_add_f32_e32 v0, v0, v148
	s_waitcnt lgkmcnt(14)
	v_mfma_f32_32x32x16_bf16 v[48:63], v[160:163], v[194:197], v[48:63]
	v_exp_f32_e32 v128, v128
	v_exp_f32_e32 v129, v129
	v_exp_f32_e32 v130, v130
	v_exp_f32_e32 v131, v131
	s_waitcnt lgkmcnt(12)
	v_mfma_f32_32x32x16_bf16 v[64:79], v[160:163], v[96:99], v[64:79]
	v_exp_f32_e32 v132, v132
	v_exp_f32_e32 v133, v133
	v_exp_f32_e32 v134, v134
	v_exp_f32_e32 v135, v135
	ds_read_b128 v[92:95], v208
	ds_read_b128 v[180:183], v208 offset:2048
	s_waitcnt lgkmcnt(12)
	v_mfma_f32_32x32x16_bf16 v[48:63], v[10:13], v[100:103], v[48:63]
	v_exp_f32_e32 v136, v136
	v_exp_f32_e32 v137, v137
	v_exp_f32_e32 v138, v138
	v_exp_f32_e32 v139, v139
	ds_read_b128 v[100:103], v209
	ds_read_b128 v[184:187], v209 offset:2048
	s_waitcnt lgkmcnt(12)
	v_mfma_f32_32x32x16_bf16 v[64:79], v[10:13], v[104:107], v[64:79]
	v_exp_f32_e32 v140, v140
	v_exp_f32_e32 v141, v141
	v_exp_f32_e32 v142, v142
	v_exp_f32_e32 v143, v143
	ds_read_b128 v[104:107], v208 offset:4096
	ds_read_b128 v[188:191], v208 offset:6144
	s_waitcnt lgkmcnt(12)
	v_mfma_f32_32x32x16_bf16 v[48:63], v[6:9], v[108:111], v[48:63]
	v_exp_f32_e32 v112, v112
	v_exp_f32_e32 v113, v113
	v_exp_f32_e32 v114, v114
	v_exp_f32_e32 v115, v115
	ds_read_b128 v[108:111], v209 offset:4096
	ds_read_b128 v[96:99], v209 offset:6144
	s_waitcnt lgkmcnt(12)
	v_mfma_f32_32x32x16_bf16 v[64:79], v[6:9], v[80:83], v[64:79]
	v_exp_f32_e32 v116, v116
	v_exp_f32_e32 v117, v117
	v_exp_f32_e32 v118, v118
	v_exp_f32_e32 v119, v119
	s_waitcnt lgkmcnt(10)
	v_mfma_f32_32x32x16_bf16 v[48:63], v[2:5], v[84:87], v[48:63]
	v_exp_f32_e32 v120, v120
	v_exp_f32_e32 v121, v121
	v_exp_f32_e32 v122, v122
	v_exp_f32_e32 v123, v123
	s_waitcnt lgkmcnt(8)
	v_mfma_f32_32x32x16_bf16 v[64:79], v[2:5], v[88:91], v[64:79]
	v_exp_f32_e32 v124, v124
	v_exp_f32_e32 v125, v125
	v_exp_f32_e32 v126, v126
	v_exp_f32_e32 v127, v127
	s_waitcnt vmcnt(4) lgkmcnt(0)
	s_barrier
	ds_read_b64_tr_b16 v[192:193], v206 offset:57344
	ds_read_b64_tr_b16 v[194:195], v206 offset:57856
	v_add_f32_e32 v2, v128, v129
	v_add_f32_e32 v2, v130, v2
	v_add_f32_e32 v2, v131, v2
	v_add_f32_e32 v2, v132, v2
	v_add_f32_e32 v2, v133, v2
	v_cvt_pk_bf16_f32 v160, v128, v129
	v_cvt_pk_bf16_f32 v161, v130, v131
	s_waitcnt lgkmcnt(9)
	v_mfma_f32_32x32x16_bf16 v[144:159], v[92:95], v[172:175], v[32:47]
	ds_read_b64_tr_b16 v[128:129], v206 offset:61440
	ds_read_b64_tr_b16 v[130:131], v206 offset:61952
	s_waitcnt lgkmcnt(10)
	v_mfma_f32_32x32x16_bf16 v[80:95], v[180:183], v[172:175], v[32:47]
	v_add_f32_e32 v2, v134, v2
	v_add_f32_e32 v2, v135, v2
	v_add_f32_e32 v2, v136, v2
	v_add_f32_e32 v2, v137, v2
	v_cvt_pk_bf16_f32 v162, v132, v133
	v_cvt_pk_bf16_f32 v163, v134, v135
	ds_read_b64_tr_b16 v[132:133], v206 offset:58368
	ds_read_b64_tr_b16 v[134:135], v206 offset:58880
	v_add_f32_e32 v2, v138, v2
	v_add_f32_e32 v2, v139, v2
	v_add_f32_e32 v2, v140, v2
	v_add_f32_e32 v2, v141, v2
	v_cvt_pk_bf16_f32 v10, v136, v137
	v_cvt_pk_bf16_f32 v11, v138, v139
	s_waitcnt lgkmcnt(11)
	v_mfma_f32_32x32x16_bf16 v[144:159], v[100:103], v[176:179], v[144:159]
	ds_read_b64_tr_b16 v[100:101], v206 offset:62464
	ds_read_b64_tr_b16 v[102:103], v206 offset:62976
	s_waitcnt lgkmcnt(12)
	v_mfma_f32_32x32x16_bf16 v[80:95], v[184:187], v[176:179], v[80:95]
	v_add_f32_e32 v2, v142, v2
	v_add_f32_e32 v2, v143, v2
	v_add_f32_e32 v2, v112, v2
	v_add_f32_e32 v2, v113, v2
	v_cvt_pk_bf16_f32 v12, v140, v141
	v_cvt_pk_bf16_f32 v13, v142, v143
	ds_read_b64_tr_b16 v[136:137], v206 offset:59392
	ds_read_b64_tr_b16 v[138:139], v206 offset:59904
	v_add_f32_e32 v2, v114, v2
	v_add_f32_e32 v2, v115, v2
	v_add_f32_e32 v2, v116, v2
	v_add_f32_e32 v2, v117, v2
	v_cvt_pk_bf16_f32 v6, v112, v113
	v_cvt_pk_bf16_f32 v7, v114, v115
	s_waitcnt lgkmcnt(13)
	v_mfma_f32_32x32x16_bf16 v[144:159], v[104:107], v[168:171], v[144:159]
	ds_read_b64_tr_b16 v[104:105], v206 offset:63488
	ds_read_b64_tr_b16 v[106:107], v206 offset:64000
	s_waitcnt lgkmcnt(14)
	v_mfma_f32_32x32x16_bf16 v[80:95], v[188:191], v[168:171], v[80:95]
	v_add_f32_e32 v2, v118, v2
	v_add_f32_e32 v2, v119, v2
	v_add_f32_e32 v2, v120, v2
	v_add_f32_e32 v2, v121, v2
	v_cvt_pk_bf16_f32 v8, v116, v117
	v_cvt_pk_bf16_f32 v9, v118, v119
	ds_read_b64_tr_b16 v[116:117], v206 offset:60416
	ds_read_b64_tr_b16 v[118:119], v206 offset:60928
	v_add_f32_e32 v2, v122, v2
	v_add_f32_e32 v2, v123, v2
	v_add_f32_e32 v2, v124, v2
	v_add_f32_e32 v112, v125, v2
	v_cvt_pk_bf16_f32 v2, v120, v121
	v_cvt_pk_bf16_f32 v3, v122, v123
	s_waitcnt lgkmcnt(14)
	v_mfma_f32_32x32x16_bf16 v[144:159], v[108:111], v[164:167], v[144:159]
	ds_read_b64_tr_b16 v[108:109], v206 offset:64512
	ds_read_b64_tr_b16 v[110:111], v206 offset:65024
	v_mfma_f32_32x32x16_bf16 v[80:95], v[96:99], v[164:167], v[80:95]
	v_add_f32_e32 v4, v126, v112
	v_add_f32_e32 v96, v127, v4
	v_cvt_pk_bf16_f32 v4, v124, v125
	v_cvt_pk_bf16_f32 v5, v126, v127
	s_mov_b64 s[20:21], 0x108000
	v_add_f32_e32 v0, v0, v96
	v_lshl_add_u64 v[96:97], v[14:15], 0, s[20:21]
	s_add_i32 s7, s7, 0xc000
	s_mov_b32 s20, m0
	s_mov_b32 m0, s7
	s_nop 0
	global_load_lds_dwordx4 v[96:97], off
	s_mov_b32 m0, s20
	s_waitcnt lgkmcnt(14)
	v_mfma_f32_32x32x16_bf16 v[48:63], v[160:163], v[192:195], v[48:63]
	v_exp_f32_e32 v144, v144
	v_exp_f32_e32 v145, v145
	v_exp_f32_e32 v146, v146
	v_exp_f32_e32 v147, v147
	s_waitcnt lgkmcnt(12)
	v_mfma_f32_32x32x16_bf16 v[64:79], v[160:163], v[128:131], v[64:79]
	v_exp_f32_e32 v148, v148
	v_exp_f32_e32 v149, v149
	v_exp_f32_e32 v150, v150
	v_exp_f32_e32 v151, v151
	ds_read_b128 v[96:99], v208 offset:8192
	ds_read_b128 v[120:123], v208 offset:10240
	s_waitcnt lgkmcnt(12)
	v_mfma_f32_32x32x16_bf16 v[48:63], v[10:13], v[132:135], v[48:63]
	v_exp_f32_e32 v152, v152
	v_exp_f32_e32 v153, v153
	v_exp_f32_e32 v154, v154
	v_exp_f32_e32 v155, v155
	ds_read_b128 v[124:127], v209 offset:8192
	ds_read_b128 v[180:183], v209 offset:10240
	s_waitcnt lgkmcnt(12)
	v_mfma_f32_32x32x16_bf16 v[64:79], v[10:13], v[100:103], v[64:79]
	v_exp_f32_e32 v156, v156
	v_exp_f32_e32 v157, v157
	v_exp_f32_e32 v158, v158
	v_exp_f32_e32 v159, v159
	ds_read_b128 v[184:187], v208 offset:12288
	ds_read_b128 v[188:191], v208 offset:14336
	s_waitcnt lgkmcnt(12)
	v_mfma_f32_32x32x16_bf16 v[48:63], v[6:9], v[136:139], v[48:63]
	v_exp_f32_e32 v80, v80
	v_exp_f32_e32 v81, v81
	v_exp_f32_e32 v82, v82
	v_exp_f32_e32 v83, v83
	ds_read_b128 v[192:195], v209 offset:12288
	ds_read_b128 v[112:115], v209 offset:14336
	s_waitcnt lgkmcnt(12)
	v_mfma_f32_32x32x16_bf16 v[64:79], v[6:9], v[104:107], v[64:79]
	v_exp_f32_e32 v84, v84
	v_exp_f32_e32 v85, v85
	v_exp_f32_e32 v86, v86
	v_exp_f32_e32 v87, v87
	s_waitcnt lgkmcnt(10)
	v_mfma_f32_32x32x16_bf16 v[48:63], v[2:5], v[116:119], v[48:63]
	v_exp_f32_e32 v88, v88
	v_exp_f32_e32 v89, v89
	v_exp_f32_e32 v90, v90
	v_exp_f32_e32 v91, v91
	s_waitcnt lgkmcnt(8)
	v_mfma_f32_32x32x16_bf16 v[64:79], v[2:5], v[108:111], v[64:79]
	v_exp_f32_e32 v92, v92
	v_exp_f32_e32 v93, v93
	v_exp_f32_e32 v94, v94
	v_exp_f32_e32 v95, v95
	s_waitcnt vmcnt(3) lgkmcnt(0)
	s_barrier
	ds_read_b64_tr_b16 v[116:117], v206 offset:32768
	ds_read_b64_tr_b16 v[118:119], v206 offset:33280
	s_waitcnt lgkmcnt(9)
	v_mfma_f32_32x32x16_bf16 v[128:143], v[96:99], v[172:175], v[32:47]
	v_add_f32_e32 v2, v144, v145
	v_add_f32_e32 v2, v146, v2
	v_add_f32_e32 v2, v147, v2
	v_add_f32_e32 v2, v148, v2
	v_add_f32_e32 v2, v149, v2
	v_cvt_pk_bf16_f32 v160, v144, v145
	v_cvt_pk_bf16_f32 v161, v146, v147
	ds_read_b64_tr_b16 v[144:145], v206 offset:36864
	ds_read_b64_tr_b16 v[146:147], v206 offset:37376
	v_add_f32_e32 v2, v150, v2
	v_add_f32_e32 v2, v151, v2
	v_add_f32_e32 v2, v152, v2
	v_add_f32_e32 v2, v153, v2
	v_cvt_pk_bf16_f32 v162, v148, v149
	v_cvt_pk_bf16_f32 v163, v150, v151
	s_waitcnt lgkmcnt(10)
	v_mfma_f32_32x32x16_bf16 v[96:111], v[120:123], v[172:175], v[32:47]
	ds_read_b64_tr_b16 v[120:121], v206 offset:33792
	ds_read_b64_tr_b16 v[122:123], v206 offset:34304
	s_waitcnt lgkmcnt(11)
	v_mfma_f32_32x32x16_bf16 v[128:143], v[124:127], v[176:179], v[128:143]
	v_add_f32_e32 v2, v154, v2
	v_add_f32_e32 v2, v155, v2
	v_add_f32_e32 v2, v156, v2
	v_add_f32_e32 v2, v157, v2
	v_cvt_pk_bf16_f32 v10, v152, v153
	v_cvt_pk_bf16_f32 v11, v154, v155
	ds_read_b64_tr_b16 v[124:125], v206 offset:37888
	ds_read_b64_tr_b16 v[126:127], v206 offset:38400
	v_add_f32_e32 v2, v158, v2
	v_add_f32_e32 v2, v159, v2
	v_add_f32_e32 v2, v80, v2
	v_add_f32_e32 v2, v81, v2
	v_cvt_pk_bf16_f32 v12, v156, v157
	v_cvt_pk_bf16_f32 v13, v158, v159
	s_waitcnt lgkmcnt(12)
	v_mfma_f32_32x32x16_bf16 v[96:111], v[180:183], v[176:179], v[96:111]
	ds_read_b64_tr_b16 v[148:149], v206 offset:34816
	ds_read_b64_tr_b16 v[150:151], v206 offset:35328
	s_waitcnt lgkmcnt(13)
	v_mfma_f32_32x32x16_bf16 v[128:143], v[184:187], v[168:171], v[128:143]
	v_add_f32_e32 v2, v82, v2
	v_add_f32_e32 v2, v83, v2
	v_add_f32_e32 v2, v84, v2
	v_add_f32_e32 v2, v85, v2
	v_cvt_pk_bf16_f32 v6, v80, v81
	v_cvt_pk_bf16_f32 v7, v82, v83
	ds_read_b64_tr_b16 v[80:81], v206 offset:38912
	ds_read_b64_tr_b16 v[82:83], v206 offset:39424
	v_add_f32_e32 v2, v86, v2
	v_add_f32_e32 v2, v87, v2
	v_add_f32_e32 v2, v88, v2
	v_add_f32_e32 v2, v89, v2
	v_cvt_pk_bf16_f32 v8, v84, v85
	v_cvt_pk_bf16_f32 v9, v86, v87
	s_waitcnt lgkmcnt(14)
	v_mfma_f32_32x32x16_bf16 v[96:111], v[188:191], v[168:171], v[96:111]
	ds_read_b64_tr_b16 v[84:85], v206 offset:35840
	ds_read_b64_tr_b16 v[86:87], v206 offset:36352
	s_waitcnt lgkmcnt(14)
	v_mfma_f32_32x32x16_bf16 v[128:143], v[192:195], v[164:167], v[128:143]
	v_add_f32_e32 v2, v90, v2
	v_add_f32_e32 v2, v91, v2
	v_add_f32_e32 v2, v92, v2
	v_add_f32_e32 v152, v93, v2
	v_cvt_pk_bf16_f32 v2, v88, v89
	v_cvt_pk_bf16_f32 v3, v90, v91
	ds_read_b64_tr_b16 v[88:89], v206 offset:39936
	ds_read_b64_tr_b16 v[90:91], v206 offset:40448
	v_add_f32_e32 v4, v94, v152
	v_add_f32_e32 v152, v95, v4
	v_cvt_pk_bf16_f32 v4, v92, v93
	v_cvt_pk_bf16_f32 v5, v94, v95
	v_mfma_f32_32x32x16_bf16 v[96:111], v[112:115], v[164:167], v[96:111]
	s_add_i32 s6, s6, 0xe000
	v_lshl_add_u64 v[14:15], v[14:15], 0, s[42:43]
	s_add_i32 s8, s8, s6
	s_mov_b32 s7, m0
	s_mov_b32 m0, s8
	s_nop 0
	global_load_lds_dwordx4 v[14:15], off
	s_mov_b32 m0, s7
	v_add_f32_e32 v0, v0, v152
	s_mov_b64 s[80:81], 0x10c000
	s_waitcnt lgkmcnt(14)
	v_mfma_f32_32x32x16_bf16 v[48:63], v[160:163], v[116:119], v[48:63]
	v_exp_f32_e32 v128, v128
	v_exp_f32_e32 v129, v129
	v_exp_f32_e32 v130, v130
	v_exp_f32_e32 v131, v131
	s_waitcnt lgkmcnt(12)
	v_mfma_f32_32x32x16_bf16 v[64:79], v[160:163], v[144:147], v[64:79]
	v_exp_f32_e32 v132, v132
	v_exp_f32_e32 v133, v133
	v_exp_f32_e32 v134, v134
	v_exp_f32_e32 v135, v135
	ds_read_b128 v[92:95], v208 offset:16384
	ds_read_b128 v[152:155], v208 offset:18432
	s_waitcnt lgkmcnt(12)
	v_mfma_f32_32x32x16_bf16 v[48:63], v[10:13], v[120:123], v[48:63]
	v_exp_f32_e32 v136, v136
	v_exp_f32_e32 v137, v137
	v_exp_f32_e32 v138, v138
	v_exp_f32_e32 v139, v139
	ds_read_b128 v[156:159], v209 offset:16384
	ds_read_b128 v[180:183], v209 offset:18432
	s_waitcnt lgkmcnt(12)
	v_mfma_f32_32x32x16_bf16 v[64:79], v[10:13], v[124:127], v[64:79]
	v_exp_f32_e32 v140, v140
	v_exp_f32_e32 v141, v141
	v_exp_f32_e32 v142, v142
	v_exp_f32_e32 v143, v143
	ds_read_b128 v[184:187], v208 offset:20480
	ds_read_b128 v[188:191], v208 offset:22528
	s_waitcnt lgkmcnt(12)
	v_mfma_f32_32x32x16_bf16 v[48:63], v[6:9], v[148:151], v[48:63]
	v_exp_f32_e32 v96, v96
	v_exp_f32_e32 v97, v97
	v_exp_f32_e32 v98, v98
	v_exp_f32_e32 v99, v99
	ds_read_b128 v[148:151], v209 offset:20480
	ds_read_b128 v[144:147], v209 offset:22528
	s_waitcnt lgkmcnt(12)
	v_mfma_f32_32x32x16_bf16 v[64:79], v[6:9], v[80:83], v[64:79]
	v_exp_f32_e32 v100, v100
	v_exp_f32_e32 v101, v101
	v_exp_f32_e32 v102, v102
	v_exp_f32_e32 v103, v103
	s_waitcnt lgkmcnt(10)
	v_mfma_f32_32x32x16_bf16 v[48:63], v[2:5], v[84:87], v[48:63]
	v_exp_f32_e32 v104, v104
	v_exp_f32_e32 v105, v105
	v_exp_f32_e32 v106, v106
	v_exp_f32_e32 v107, v107
	s_waitcnt lgkmcnt(8)
	v_mfma_f32_32x32x16_bf16 v[64:79], v[2:5], v[88:91], v[64:79]
	v_exp_f32_e32 v108, v108
	v_exp_f32_e32 v109, v109
	v_exp_f32_e32 v110, v110
	v_exp_f32_e32 v111, v111
	s_waitcnt vmcnt(2) lgkmcnt(0)
	s_barrier
	ds_read_b64_tr_b16 v[192:193], v206 offset:40960
	ds_read_b64_tr_b16 v[194:195], v206 offset:41472
	v_add_f32_e32 v2, v128, v129
	v_add_f32_e32 v2, v130, v2
	v_add_f32_e32 v2, v131, v2
	v_add_f32_e32 v2, v132, v2
	v_add_f32_e32 v2, v133, v2
	v_cvt_pk_bf16_f32 v160, v128, v129
	v_cvt_pk_bf16_f32 v161, v130, v131
	s_waitcnt lgkmcnt(9)
	v_mfma_f32_32x32x16_bf16 v[112:127], v[92:95], v[172:175], v[32:47]
	ds_read_b64_tr_b16 v[128:129], v206 offset:45056
	ds_read_b64_tr_b16 v[130:131], v206 offset:45568
	s_waitcnt lgkmcnt(10)
	v_mfma_f32_32x32x16_bf16 v[80:95], v[152:155], v[172:175], v[32:47]
	v_add_f32_e32 v2, v134, v2
	v_add_f32_e32 v2, v135, v2
	v_add_f32_e32 v2, v136, v2
	v_add_f32_e32 v2, v137, v2
	v_cvt_pk_bf16_f32 v162, v132, v133
	v_cvt_pk_bf16_f32 v163, v134, v135
	ds_read_b64_tr_b16 v[132:133], v206 offset:41984
	ds_read_b64_tr_b16 v[134:135], v206 offset:42496
	v_add_f32_e32 v2, v138, v2
	v_add_f32_e32 v2, v139, v2
	v_add_f32_e32 v2, v140, v2
	v_add_f32_e32 v2, v141, v2
	v_cvt_pk_bf16_f32 v10, v136, v137
	v_cvt_pk_bf16_f32 v11, v138, v139
	s_waitcnt lgkmcnt(11)
	v_mfma_f32_32x32x16_bf16 v[112:127], v[156:159], v[176:179], v[112:127]
	ds_read_b64_tr_b16 v[136:137], v206 offset:46080
	ds_read_b64_tr_b16 v[138:139], v206 offset:46592
	s_waitcnt lgkmcnt(12)
	v_mfma_f32_32x32x16_bf16 v[80:95], v[180:183], v[176:179], v[80:95]
	v_add_f32_e32 v2, v142, v2
	v_add_f32_e32 v2, v143, v2
	v_add_f32_e32 v2, v96, v2
	v_add_f32_e32 v2, v97, v2
	v_cvt_pk_bf16_f32 v12, v140, v141
	v_cvt_pk_bf16_f32 v13, v142, v143
	ds_read_b64_tr_b16 v[140:141], v206 offset:43008
	ds_read_b64_tr_b16 v[142:143], v206 offset:43520
	v_add_f32_e32 v2, v98, v2
	v_add_f32_e32 v2, v99, v2
	v_add_f32_e32 v2, v100, v2
	v_add_f32_e32 v2, v101, v2
	v_cvt_pk_bf16_f32 v6, v96, v97
	v_cvt_pk_bf16_f32 v7, v98, v99
	s_waitcnt lgkmcnt(13)
	v_mfma_f32_32x32x16_bf16 v[112:127], v[184:187], v[168:171], v[112:127]
	ds_read_b64_tr_b16 v[96:97], v206 offset:47104
	ds_read_b64_tr_b16 v[98:99], v206 offset:47616
	s_waitcnt lgkmcnt(14)
	v_mfma_f32_32x32x16_bf16 v[80:95], v[188:191], v[168:171], v[80:95]
	v_add_f32_e32 v2, v102, v2
	v_add_f32_e32 v2, v103, v2
	v_add_f32_e32 v2, v104, v2
	v_add_f32_e32 v2, v105, v2
	v_cvt_pk_bf16_f32 v8, v100, v101
	v_cvt_pk_bf16_f32 v9, v102, v103
	ds_read_b64_tr_b16 v[100:101], v206 offset:44032
	ds_read_b64_tr_b16 v[102:103], v206 offset:44544
	v_add_f32_e32 v2, v106, v2
	v_add_f32_e32 v2, v107, v2
	v_add_f32_e32 v2, v108, v2
	v_add_f32_e32 v14, v109, v2
	v_cvt_pk_bf16_f32 v2, v104, v105
	v_cvt_pk_bf16_f32 v3, v106, v107
	s_waitcnt lgkmcnt(14)
	v_mfma_f32_32x32x16_bf16 v[112:127], v[148:151], v[164:167], v[112:127]
	ds_read_b64_tr_b16 v[104:105], v206 offset:48128
	ds_read_b64_tr_b16 v[106:107], v206 offset:48640
	v_mfma_f32_32x32x16_bf16 v[80:95], v[144:147], v[164:167], v[80:95]
	v_add_f32_e32 v4, v110, v14
	v_add_f32_e32 v14, v111, v4
	v_cvt_pk_bf16_f32 v4, v108, v109
	v_cvt_pk_bf16_f32 v5, v110, v111
	s_nop 0
	v_add_f32_e32 v185, v0, v14
	s_waitcnt lgkmcnt(14)
	v_mfma_f32_32x32x16_bf16 v[48:63], v[160:163], v[192:195], v[48:63]
	s_nop 0
	v_exp_f32_e32 v112, v112
	v_exp_f32_e32 v113, v113
	v_exp_f32_e32 v114, v114
	v_exp_f32_e32 v115, v115
	s_waitcnt lgkmcnt(12)
	v_mfma_f32_32x32x16_bf16 v[64:79], v[160:163], v[128:131], v[64:79]
	v_exp_f32_e32 v116, v116
	v_exp_f32_e32 v117, v117
	v_exp_f32_e32 v118, v118
	v_exp_f32_e32 v119, v119
	ds_read_b128 v[148:151], v208 offset:24576
	ds_read_b128 v[186:189], v208 offset:26624
	s_waitcnt lgkmcnt(12)
	v_mfma_f32_32x32x16_bf16 v[48:63], v[10:13], v[132:135], v[48:63]
	v_exp_f32_e32 v120, v120
	v_exp_f32_e32 v121, v121
	v_exp_f32_e32 v122, v122
	v_exp_f32_e32 v123, v123
	ds_read_b128 v[190:193], v209 offset:24576
	ds_read_b128 v[194:197], v209 offset:26624
	s_waitcnt lgkmcnt(12)
	v_mfma_f32_32x32x16_bf16 v[64:79], v[10:13], v[136:139], v[64:79]
	v_exp_f32_e32 v124, v124
	v_exp_f32_e32 v125, v125
	v_exp_f32_e32 v126, v126
	v_exp_f32_e32 v127, v127
	ds_read_b128 v[210:213], v208 offset:28672
	ds_read_b128 v[180:183], v208 offset:30720
	s_waitcnt lgkmcnt(12)
	v_mfma_f32_32x32x16_bf16 v[48:63], v[6:9], v[140:143], v[48:63]
	v_exp_f32_e32 v80, v80
	v_exp_f32_e32 v81, v81
	v_exp_f32_e32 v82, v82
	v_exp_f32_e32 v83, v83
	ds_read_b128 v[156:159], v209 offset:28672
	ds_read_b128 v[152:155], v209 offset:30720
	s_waitcnt lgkmcnt(12)
	v_mfma_f32_32x32x16_bf16 v[64:79], v[6:9], v[96:99], v[64:79]
	v_exp_f32_e32 v84, v84
	v_exp_f32_e32 v85, v85
	v_exp_f32_e32 v86, v86
	v_exp_f32_e32 v87, v87
	s_waitcnt lgkmcnt(10)
	v_mfma_f32_32x32x16_bf16 v[48:63], v[2:5], v[100:103], v[48:63]
	v_exp_f32_e32 v88, v88
	v_exp_f32_e32 v89, v89
	v_exp_f32_e32 v90, v90
	v_exp_f32_e32 v91, v91
	s_waitcnt lgkmcnt(8)
	v_mfma_f32_32x32x16_bf16 v[64:79], v[2:5], v[104:107], v[64:79]
	v_exp_f32_e32 v92, v92
	v_exp_f32_e32 v93, v93
	v_exp_f32_e32 v94, v94
	v_exp_f32_e32 v95, v95
	v_lshrrev_b32_e32 v184, 3, v203
	v_or_b32_e32 v2, s4, v184
	v_mov_b32_e32 v3, s5
	v_lshlrev_b64 v[14:15], 11, v[2:3]
	v_lshl_add_u64 v[2:3], s[48:49], 0, v[14:15]
	s_lshl_b32 s8, s26, 1
	v_and_b32_e32 v0, 56, v207
	v_lshl_add_u64 v[2:3], v[2:3], 0, s[8:9]
	v_lshlrev_b32_e32 v0, 1, v0
	v_lshl_add_u64 v[2:3], v[2:3], 0, v[0:1]
	v_add_co_u32_e32 v6, vcc, s67, v2
	s_waitcnt vmcnt(0) lgkmcnt(0)
	s_barrier
	s_nop 1
	v_addc_co_u32_e32 v7, vcc, 0, v3, vcc
	global_load_dwordx4 v[140:143], v[2:3], off
	global_load_dwordx4 v[136:139], v[6:7], off
	v_add_co_u32_e32 v6, vcc, s66, v2
	s_nop 1
	v_addc_co_u32_e32 v7, vcc, 0, v3, vcc
	v_add_co_u32_e32 v2, vcc, s63, v2
	s_nop 1
	v_addc_co_u32_e32 v3, vcc, 0, v3, vcc
	global_load_dwordx4 v[132:135], v[6:7], off
	global_load_dwordx4 v[128:131], v[2:3], off
	ds_read_b64_tr_b16 v[144:145], v206 offset:49152
	ds_read_b64_tr_b16 v[146:147], v206 offset:49664
	v_add_f32_e32 v2, v112, v113
	v_add_f32_e32 v2, v114, v2
	v_add_f32_e32 v2, v115, v2
	v_add_f32_e32 v2, v116, v2
	v_add_f32_e32 v2, v117, v2
	v_cvt_pk_bf16_f32 v160, v112, v113
	v_cvt_pk_bf16_f32 v161, v114, v115
	s_waitcnt lgkmcnt(9)
	v_mfma_f32_32x32x16_bf16 v[96:111], v[148:151], v[172:175], v[32:47]
	ds_read_b64_tr_b16 v[112:113], v206 offset:53248
	ds_read_b64_tr_b16 v[114:115], v206 offset:53760
	v_add_f32_e32 v2, v118, v2
	v_add_f32_e32 v2, v119, v2
	v_add_f32_e32 v2, v120, v2
	v_add_f32_e32 v2, v121, v2
	v_cvt_pk_bf16_f32 v162, v116, v117
	v_cvt_pk_bf16_f32 v163, v118, v119
	s_waitcnt lgkmcnt(10)
	v_mfma_f32_32x32x16_bf16 v[32:47], v[186:189], v[172:175], v[32:47]
	ds_read_b64_tr_b16 v[148:149], v206 offset:50176
	ds_read_b64_tr_b16 v[150:151], v206 offset:50688
	v_add_f32_e32 v2, v122, v2
	v_add_f32_e32 v2, v123, v2
	v_add_f32_e32 v2, v124, v2
	v_add_f32_e32 v2, v125, v2
	v_cvt_pk_bf16_f32 v10, v120, v121
	v_cvt_pk_bf16_f32 v11, v122, v123
	s_waitcnt lgkmcnt(11)
	v_mfma_f32_32x32x16_bf16 v[96:111], v[190:193], v[176:179], v[96:111]
	ds_read_b64_tr_b16 v[116:117], v206 offset:54272
	ds_read_b64_tr_b16 v[118:119], v206 offset:54784
	v_add_f32_e32 v2, v126, v2
	v_add_f32_e32 v2, v127, v2
	v_add_f32_e32 v2, v80, v2
	v_add_f32_e32 v2, v81, v2
	v_cvt_pk_bf16_f32 v12, v124, v125
	v_cvt_pk_bf16_f32 v13, v126, v127
	s_waitcnt lgkmcnt(12)
	v_mfma_f32_32x32x16_bf16 v[32:47], v[194:197], v[176:179], v[32:47]
	ds_read_b64_tr_b16 v[120:121], v206 offset:51200
	ds_read_b64_tr_b16 v[122:123], v206 offset:51712
	v_add_f32_e32 v2, v82, v2
	v_add_f32_e32 v2, v83, v2
	v_add_f32_e32 v2, v84, v2
	v_add_f32_e32 v2, v85, v2
	v_cvt_pk_bf16_f32 v6, v80, v81
	v_cvt_pk_bf16_f32 v7, v82, v83
	s_waitcnt lgkmcnt(13)
	v_mfma_f32_32x32x16_bf16 v[96:111], v[210:213], v[168:171], v[96:111]
	ds_read_b64_tr_b16 v[80:81], v206 offset:55296
	ds_read_b64_tr_b16 v[82:83], v206 offset:55808
	v_add_f32_e32 v2, v86, v2
	v_add_f32_e32 v2, v87, v2
	v_add_f32_e32 v2, v88, v2
	v_add_f32_e32 v2, v89, v2
	v_cvt_pk_bf16_f32 v8, v84, v85
	v_cvt_pk_bf16_f32 v9, v86, v87
	s_waitcnt lgkmcnt(14)
	v_mfma_f32_32x32x16_bf16 v[32:47], v[180:183], v[168:171], v[32:47]
	ds_read_b64_tr_b16 v[124:125], v206 offset:52224
	ds_read_b64_tr_b16 v[126:127], v206 offset:52736
	v_add_f32_e32 v2, v90, v2
	v_add_f32_e32 v2, v91, v2
	v_add_f32_e32 v2, v92, v2
	v_add_f32_e32 v168, v93, v2
	v_cvt_pk_bf16_f32 v2, v88, v89
	v_cvt_pk_bf16_f32 v3, v90, v91
	s_waitcnt lgkmcnt(14)
	v_mfma_f32_32x32x16_bf16 v[96:111], v[156:159], v[164:167], v[96:111]
	ds_read_b64_tr_b16 v[84:85], v206 offset:56320
	ds_read_b64_tr_b16 v[86:87], v206 offset:56832
	v_add_f32_e32 v4, v94, v168
	v_add_f32_e32 v88, v95, v4
	v_cvt_pk_bf16_f32 v4, v92, v93
	v_cvt_pk_bf16_f32 v5, v94, v95
	v_mfma_f32_32x32x16_bf16 v[32:47], v[152:155], v[164:167], v[32:47]
	s_nop 4
	v_exp_f32_e32 v96, v96
	v_exp_f32_e32 v97, v97
	v_exp_f32_e32 v98, v98
	v_exp_f32_e32 v99, v99
	s_nop 0
	v_exp_f32_e32 v100, v100
	v_exp_f32_e32 v101, v101
	v_exp_f32_e32 v102, v102
	v_exp_f32_e32 v103, v103
	s_nop 0
	v_exp_f32_e32 v104, v104
	v_exp_f32_e32 v105, v105
	v_exp_f32_e32 v106, v106
	v_exp_f32_e32 v107, v107
	s_nop 0
	v_exp_f32_e32 v108, v108
	v_exp_f32_e32 v109, v109
	v_exp_f32_e32 v110, v110
	v_exp_f32_e32 v111, v111
	v_exp_f32_e32 v32, v32
	v_exp_f32_e32 v33, v33
	v_exp_f32_e32 v34, v34
	v_exp_f32_e32 v35, v35
	s_nop 0
	v_exp_f32_e32 v36, v36
	v_exp_f32_e32 v37, v37
	v_exp_f32_e32 v38, v38
	v_exp_f32_e32 v39, v39
	s_nop 0
	v_exp_f32_e32 v40, v40
	v_exp_f32_e32 v41, v41
	v_exp_f32_e32 v42, v42
	v_exp_f32_e32 v43, v43
	s_nop 0
	v_exp_f32_e32 v44, v44
	v_exp_f32_e32 v45, v45
	v_exp_f32_e32 v46, v46
	v_exp_f32_e32 v47, v47
	s_waitcnt lgkmcnt(14)
	v_mfma_f32_32x32x16_bf16 v[48:63], v[160:163], v[144:147], v[48:63]
	v_add_f32_e32 v89, v96, v97
	v_add_f32_e32 v89, v98, v89
	v_add_f32_e32 v89, v99, v89
	v_add_f32_e32 v89, v100, v89
	v_add_f32_e32 v89, v101, v89
	v_add_f32_e32 v89, v102, v89
	v_add_f32_e32 v89, v103, v89
	s_waitcnt lgkmcnt(12)
	v_mfma_f32_32x32x16_bf16 v[64:79], v[160:163], v[112:115], v[64:79]
	v_add_f32_e32 v89, v104, v89
	v_add_f32_e32 v89, v105, v89
	v_add_f32_e32 v89, v106, v89
	v_add_f32_e32 v89, v107, v89
	v_add_f32_e32 v89, v108, v89
	v_add_f32_e32 v89, v109, v89
	v_add_f32_e32 v89, v110, v89
	s_waitcnt lgkmcnt(10)
	v_mfma_f32_32x32x16_bf16 v[48:63], v[10:13], v[148:151], v[48:63]
	v_add_f32_e32 v89, v111, v89
	v_add_f32_e32 v89, v32, v89
	v_add_f32_e32 v89, v33, v89
	v_add_f32_e32 v89, v34, v89
	v_add_f32_e32 v89, v35, v89
	v_add_f32_e32 v89, v36, v89
	v_add_f32_e32 v89, v37, v89
	s_waitcnt lgkmcnt(8)
	v_mfma_f32_32x32x16_bf16 v[64:79], v[10:13], v[116:119], v[64:79]
	v_add_f32_e32 v89, v38, v89
	v_add_f32_e32 v89, v39, v89
	v_add_f32_e32 v89, v40, v89
	v_add_f32_e32 v89, v41, v89
	v_add_f32_e32 v89, v42, v89
	v_add_f32_e32 v89, v43, v89
	v_add_f32_e32 v89, v44, v89
	s_waitcnt lgkmcnt(6)
	v_mfma_f32_32x32x16_bf16 v[48:63], v[6:9], v[120:123], v[48:63]
	v_add_f32_e32 v89, v45, v89
	v_add_f32_e32 v89, v46, v89
	v_add_f32_e32 v89, v47, v89
	v_add_f32_e32 v88, v185, v88
	v_add_f32_e32 v88, v88, v89
	v_cvt_pk_bf16_f32 v90, v96, v97
	v_cvt_pk_bf16_f32 v91, v98, v99
	s_waitcnt lgkmcnt(4)
	v_mfma_f32_32x32x16_bf16 v[64:79], v[6:9], v[80:83], v[64:79]
	v_cvt_pk_bf16_f32 v92, v100, v101
	v_cvt_pk_bf16_f32 v93, v102, v103
	v_cvt_pk_bf16_f32 v10, v104, v105
	v_cvt_pk_bf16_f32 v11, v106, v107
	v_cvt_pk_bf16_f32 v12, v108, v109
	v_cvt_pk_bf16_f32 v13, v110, v111
	v_cvt_pk_bf16_f32 v6, v32, v33
	s_waitcnt lgkmcnt(2)
	v_mfma_f32_32x32x16_bf16 v[48:63], v[2:5], v[124:127], v[48:63]
	v_cvt_pk_bf16_f32 v7, v34, v35
	v_cvt_pk_bf16_f32 v8, v36, v37
	v_cvt_pk_bf16_f32 v9, v38, v39
	v_cvt_pk_bf16_f32 v32, v40, v41
	v_cvt_pk_bf16_f32 v33, v42, v43
	v_cvt_pk_bf16_f32 v34, v44, v45
	v_cvt_pk_bf16_f32 v35, v46, v47
	s_waitcnt lgkmcnt(0)
	v_mfma_f32_32x32x16_bf16 v[64:79], v[2:5], v[84:87], v[64:79]
	v_add_u32_e32 v2, s6, v204
	v_add3_u32 v84, v2, v202, v205
	ds_read_b64_tr_b16 v[2:3],v84 offset:0
	ds_read_b64_tr_b16 v[4:5],v84 offset:512
	ds_read_b64_tr_b16 v[36:37],v84 offset:1024
	ds_read_b64_tr_b16 v[38:39],v84 offset:1536
	ds_read_b64_tr_b16 v[40:41],v84 offset:2048
	ds_read_b64_tr_b16 v[42:43],v84 offset:2560
	ds_read_b64_tr_b16 v[44:45],v84 offset:3072
	ds_read_b64_tr_b16 v[46:47],v84 offset:3584
	s_waitcnt lgkmcnt(0)
	s_nop 0
	v_mfma_f32_32x32x16_bf16 v[48:63], v[90:93], v[2:5], v[48:63]
	ds_read_b64_tr_b16 v[2:3],v84 offset:4096
	ds_read_b64_tr_b16 v[4:5],v84 offset:4608
	v_mfma_f32_32x32x16_bf16 v[48:63], v[10:13], v[36:39], v[48:63]
	ds_read_b64_tr_b16 v[36:37],v84 offset:5120
	ds_read_b64_tr_b16 v[38:39],v84 offset:5632
	v_mfma_f32_32x32x16_bf16 v[48:63], v[6:9], v[40:43], v[48:63]
	ds_read_b64_tr_b16 v[40:41],v84 offset:6144
	ds_read_b64_tr_b16 v[42:43],v84 offset:6656
	ds_read_b64_tr_b16 v[80:81],v84 offset:7168
	ds_read_b64_tr_b16 v[82:83],v84 offset:7680
	s_waitcnt lgkmcnt(0)
	v_mfma_f32_32x32x16_bf16 v[48:63], v[32:35], v[44:47], v[48:63]
	v_mfma_f32_32x32x16_bf16 v[64:79], v[90:93], v[2:5], v[64:79]
	v_mov_b32_e32 v2, v88
	s_nop 1
	v_permlane32_swap_b32_e32 v88, v2
	v_cmp_gt_u32_e32 vcc, 32, v203
	v_mfma_f32_32x32x16_bf16 v[64:79], v[10:13], v[36:39], v[64:79]
	v_mfma_f32_32x32x16_bf16 v[64:79], v[6:9], v[40:43], v[64:79]
	v_mfma_f32_32x32x16_bf16 v[64:79], v[32:35], v[80:83], v[64:79]
	s_and_saveexec_b64 s[6:7], vcc
	v_lshl_add_u32 v3, v200, 2, s31
	v_add_f32_e32 v2, v88, v2
	ds_write_b32 v3, v2 offset:128
	s_or_b64 exec, exec, s[6:7]
	s_waitcnt lgkmcnt(0)
	v_lshl_add_u32 v10, v201, 4, s31
	ds_read_b128 v[2:5], v10 offset:128
	ds_read_b128 v[6:9], v10 offset:160
	s_lshl_b32 s6, s27, 12
	s_add_i32 s6, s6, 0
	s_add_i32 s6, s6, 0x10800
	s_waitcnt lgkmcnt(1)
	v_rcp_f32_e32 v11, v2
	v_rcp_f32_e32 v12, v3
	v_rcp_f32_e32 v13, v4
	v_rcp_f32_e32 v32, v5
	s_waitcnt lgkmcnt(0)
	v_rcp_f32_e32 v33, v6
	ds_read_b128 v[2:5], v10 offset:192
	v_rcp_f32_e32 v34, v7
	v_rcp_f32_e32 v35, v8
	v_rcp_f32_e32 v36, v9
	ds_read_b128 v[6:9], v10 offset:224
	v_lshlrev_b32_e32 v10, 9, v201
	v_lshlrev_b32_e32 v37, 1, v200
	v_add3_u32 v10, s6, v10, v37
	v_mul_f32_e32 v37, v48, v11
	v_mul_f32_e32 v11, v64, v11
	v_cvt_pk_bf16_f32 v11, v11, s0
	ds_write_b16 v10, v11 offset:64
	v_mul_f32_e32 v11, v49, v12
	v_cvt_pk_bf16_f32 v11, v11, s0
	ds_write_b16 v10, v11 offset:128
	v_mul_f32_e32 v11, v65, v12
	v_cvt_pk_bf16_f32 v11, v11, s0
	ds_write_b16 v10, v11 offset:192
	v_mul_f32_e32 v11, v50, v13
	v_cvt_pk_bf16_f32 v11, v11, s0
	ds_write_b16 v10, v11 offset:256
	v_mul_f32_e32 v11, v66, v13
	v_cvt_pk_bf16_f32 v11, v11, s0
	ds_write_b16 v10, v11 offset:320
	v_mul_f32_e32 v11, v51, v32
	v_cvt_pk_bf16_f32 v11, v11, s0
	ds_write_b16 v10, v11 offset:384
	v_mul_f32_e32 v11, v67, v32
	v_cvt_pk_bf16_f32 v11, v11, s0
	ds_write_b16 v10, v11 offset:448
	v_mul_f32_e32 v11, v52, v33
	v_cvt_pk_bf16_f32 v11, v11, s0
	ds_write_b16 v10, v11 offset:1024
	v_mul_f32_e32 v11, v68, v33
	v_cvt_pk_bf16_f32 v11, v11, s0
	ds_write_b16 v10, v11 offset:1088
	v_mul_f32_e32 v11, v53, v34
	v_cvt_pk_bf16_f32 v11, v11, s0
	ds_write_b16 v10, v11 offset:1152
	v_mul_f32_e32 v11, v69, v34
	v_cvt_pk_bf16_f32 v11, v11, s0
	ds_write_b16 v10, v11 offset:1216
	v_mul_f32_e32 v11, v54, v35
	v_cvt_pk_bf16_f32 v11, v11, s0
	ds_write_b16 v10, v11 offset:1280
	v_mul_f32_e32 v11, v70, v35
	v_cvt_pk_bf16_f32 v11, v11, s0
	s_waitcnt lgkmcnt(13)
	v_rcp_f32_e32 v2, v2
	ds_write_b16 v10, v11 offset:1344
	v_mul_f32_e32 v11, v55, v36
	v_cvt_pk_bf16_f32 v11, v11, s0
	v_rcp_f32_e32 v3, v3
	ds_write_b16 v10, v11 offset:1408
	v_mul_f32_e32 v11, v71, v36
	v_cvt_pk_bf16_f32 v11, v11, s0
	ds_write_b16 v10, v11 offset:1472
	v_mul_f32_e32 v11, v56, v2
	v_mul_f32_e32 v2, v72, v2
	v_cvt_pk_bf16_f32 v2, v2, s0
	v_rcp_f32_e32 v4, v4
	ds_write_b16 v10, v2 offset:2112
	v_mul_f32_e32 v2, v57, v3
	v_cvt_pk_bf16_f32 v2, v2, s0
	ds_write_b16 v10, v2 offset:2176
	v_mul_f32_e32 v2, v73, v3
	v_cvt_pk_bf16_f32 v2, v2, s0
	v_rcp_f32_e32 v5, v5
	ds_write_b16 v10, v2 offset:2240
	v_mul_f32_e32 v2, v58, v4
	v_cvt_pk_bf16_f32 v2, v2, s0
	ds_write_b16 v10, v2 offset:2304
	v_mul_f32_e32 v2, v74, v4
	v_cvt_pk_bf16_f32 v2, v2, s0
	s_waitcnt lgkmcnt(14)
	v_rcp_f32_e32 v6, v6
	ds_write_b16 v10, v2 offset:2368
	v_mul_f32_e32 v2, v59, v5
	v_cvt_pk_bf16_f32 v2, v2, s0
	ds_write_b16 v10, v2 offset:2432
	v_mul_f32_e32 v2, v75, v5
	v_cvt_pk_bf16_f32 v2, v2, s0
	v_rcp_f32_e32 v7, v7
	ds_write_b16 v10, v2 offset:2496
	v_mul_f32_e32 v2, v60, v6
	v_cvt_pk_bf16_f32 v2, v2, s0
	ds_write_b16 v10, v2 offset:3072
	v_mul_f32_e32 v2, v76, v6
	v_cvt_pk_bf16_f32 v2, v2, s0
	v_rcp_f32_e32 v8, v8
	ds_write_b16 v10, v2 offset:3136
	v_mul_f32_e32 v2, v61, v7
	v_cvt_pk_bf16_f32 v2, v2, s0
	ds_write_b16 v10, v2 offset:3200
	v_mul_f32_e32 v2, v77, v7
	v_cvt_pk_bf16_f32 v2, v2, s0
	v_rcp_f32_e32 v9, v9
	ds_write_b16 v10, v2 offset:3264
	v_mul_f32_e32 v2, v62, v8
	v_cvt_pk_bf16_f32 v2, v2, s0
	ds_write_b16 v10, v2 offset:3328
	v_mul_f32_e32 v2, v78, v8
	v_cvt_pk_bf16_f32 v2, v2, s0
	ds_write_b16 v10, v2 offset:3392
	v_mul_f32_e32 v2, v63, v9
	s_waitcnt vmcnt(3)
	v_lshlrev_b32_e32 v12, 16, v140
	v_cvt_pk_bf16_f32 v2, v2, s0
	v_and_b32_e32 v13, 0xffff0000, v140
	v_mul_f32_e32 v4, 0xbfb8aa3b, v12
	ds_write_b16 v10, v2 offset:3456
	v_mul_f32_e32 v2, v79, v9
	v_exp_f32_e32 v8, v4
	v_mul_f32_e32 v4, 0xbfb8aa3b, v13
	v_cvt_pk_bf16_f32 v37, v37, s0
	v_cvt_pk_bf16_f32 v11, v11, s0
	v_cvt_pk_bf16_f32 v2, v2, s0
	v_add_u32_e32 v36, s6, v0
	s_add_u32 s6, s50, s8
	v_exp_f32_e32 v9, v4
	ds_write_b16 v10, v37
	ds_write_b16 v10, v11 offset:2048
	ds_write_b16 v10, v2 offset:3520
	s_addc_u32 s7, s51, 0
	s_waitcnt lgkmcnt(0)
	v_lshl_add_u64 v[2:3], s[6:7], 0, v[0:1]
	v_lshl_add_u32 v0, v184, 7, v36
	ds_read_b128 v[4:7], v0
	v_add_f32_e32 v0, 1.0, v8
	v_rcp_f32_e32 v32, v0
	v_add_f32_e32 v0, 1.0, v9
	v_rcp_f32_e32 v33, v0
	s_waitcnt lgkmcnt(0)
	v_lshlrev_b32_e32 v34, 16, v4
	v_and_b32_e32 v35, 0xffff0000, v4
	v_or_b32_e32 v0, 8, v184
	v_pk_mul_f32 v[12:13], v[32:33], v[12:13]
	v_lshlrev_b32_e32 v32, 16, v141
	v_and_b32_e32 v33, 0xffff0000, v141
	v_mul_f32_e32 v4, 0xbfb8aa3b, v32
	v_exp_f32_e32 v4, v4
	v_mul_f32_e32 v37, 0xbfb8aa3b, v33
	v_exp_f32_e32 v37, v37
	v_pk_mul_f32 v[12:13], v[12:13], v[34:35]
	v_add_f32_e32 v4, 1.0, v4
	v_rcp_f32_e32 v34, v4
	v_add_f32_e32 v4, 1.0, v37
	v_rcp_f32_e32 v35, v4
	v_cvt_pk_bf16_f32 v4, v12, v13
	v_lshlrev_b32_e32 v12, 16, v5
	v_and_b32_e32 v13, 0xffff0000, v5
	v_pk_mul_f32 v[32:33], v[34:35], v[32:33]
	v_lshlrev_b32_e32 v34, 16, v142
	v_and_b32_e32 v35, 0xffff0000, v142
	v_mul_f32_e32 v5, 0xbfb8aa3b, v34
	v_exp_f32_e32 v5, v5
	v_mul_f32_e32 v37, 0xbfb8aa3b, v35
	v_exp_f32_e32 v37, v37
	v_pk_mul_f32 v[12:13], v[32:33], v[12:13]
	v_add_f32_e32 v5, 1.0, v5
	v_rcp_f32_e32 v32, v5
	v_add_f32_e32 v5, 1.0, v37
	v_rcp_f32_e32 v33, v5
	v_cvt_pk_bf16_f32 v5, v12, v13
	v_lshlrev_b32_e32 v12, 16, v6
	v_and_b32_e32 v13, 0xffff0000, v6
	v_pk_mul_f32 v[32:33], v[32:33], v[34:35]
	v_lshlrev_b32_e32 v34, 16, v143
	v_and_b32_e32 v35, 0xffff0000, v143
	v_mul_f32_e32 v6, 0xbfb8aa3b, v34
	v_exp_f32_e32 v6, v6
	v_mul_f32_e32 v37, 0xbfb8aa3b, v35
	v_exp_f32_e32 v37, v37
	v_pk_mul_f32 v[12:13], v[32:33], v[12:13]
	v_add_f32_e32 v6, 1.0, v6
	v_rcp_f32_e32 v32, v6
	v_add_f32_e32 v6, 1.0, v37
	v_rcp_f32_e32 v33, v6
	v_cvt_pk_bf16_f32 v6, v12, v13
	v_lshlrev_b32_e32 v12, 16, v7
	v_and_b32_e32 v13, 0xffff0000, v7
	v_pk_mul_f32 v[32:33], v[32:33], v[34:35]
	v_lshl_add_u32 v8, v0, 7, v36
	v_pk_mul_f32 v[12:13], v[32:33], v[12:13]
	ds_read_b128 v[8:11], v8
	v_cvt_pk_bf16_f32 v7, v12, v13
	v_lshl_add_u64 v[12:13], v[2:3], 0, v[14:15]
	global_store_dwordx4 v[12:13], v[4:7], off
	s_waitcnt lgkmcnt(0)
	v_lshlrev_b32_e32 v14, 16, v8
	s_waitcnt vmcnt(3)
	v_lshlrev_b32_e32 v6, 16, v136
	v_and_b32_e32 v7, 0xffff0000, v136
	v_mul_f32_e32 v4, 0xbfb8aa3b, v6
	v_exp_f32_e32 v5, v4
	v_mul_f32_e32 v4, 0xbfb8aa3b, v7
	v_exp_f32_e32 v13, v4
	v_or_b32_e32 v4, s4, v0
	v_add_f32_e32 v0, 1.0, v5
	v_rcp_f32_e32 v12, v0
	v_add_f32_e32 v0, 1.0, v13
	v_rcp_f32_e32 v13, v0
	v_and_b32_e32 v15, 0xffff0000, v8
	v_mov_b32_e32 v5, s5
	v_pk_mul_f32 v[6:7], v[12:13], v[6:7]
	v_lshlrev_b32_e32 v12, 16, v137
	v_and_b32_e32 v13, 0xffff0000, v137
	v_mul_f32_e32 v0, 0xbfb8aa3b, v12
	v_exp_f32_e32 v0, v0
	v_mul_f32_e32 v8, 0xbfb8aa3b, v13
	v_exp_f32_e32 v8, v8
	v_pk_mul_f32 v[6:7], v[6:7], v[14:15]
	v_add_f32_e32 v0, 1.0, v0
	v_rcp_f32_e32 v14, v0
	v_add_f32_e32 v0, 1.0, v8
	v_rcp_f32_e32 v15, v0
	v_cvt_pk_bf16_f32 v6, v6, v7
	v_lshlrev_b32_e32 v8, 16, v9
	v_and_b32_e32 v9, 0xffff0000, v9
	v_pk_mul_f32 v[12:13], v[14:15], v[12:13]
	v_lshlrev_b32_e32 v14, 16, v138
	v_and_b32_e32 v15, 0xffff0000, v138
	v_mul_f32_e32 v0, 0xbfb8aa3b, v14
	v_exp_f32_e32 v0, v0
	v_mul_f32_e32 v7, 0xbfb8aa3b, v15
	v_exp_f32_e32 v7, v7
	v_pk_mul_f32 v[8:9], v[12:13], v[8:9]
	v_add_f32_e32 v0, 1.0, v0
	v_rcp_f32_e32 v12, v0
	v_add_f32_e32 v0, 1.0, v7
	v_rcp_f32_e32 v13, v0
	v_cvt_pk_bf16_f32 v7, v8, v9
	v_lshlrev_b32_e32 v8, 16, v10
	v_and_b32_e32 v9, 0xffff0000, v10
	v_pk_mul_f32 v[12:13], v[12:13], v[14:15]
	v_lshlrev_b32_e32 v14, 16, v139
	v_and_b32_e32 v15, 0xffff0000, v139
	v_mul_f32_e32 v0, 0xbfb8aa3b, v14
	v_exp_f32_e32 v0, v0
	v_mul_f32_e32 v10, 0xbfb8aa3b, v15
	v_exp_f32_e32 v10, v10
	v_pk_mul_f32 v[8:9], v[12:13], v[8:9]
	v_add_f32_e32 v0, 1.0, v0
	v_rcp_f32_e32 v12, v0
	v_add_f32_e32 v0, 1.0, v10
	v_rcp_f32_e32 v13, v0
	v_lshlrev_b32_e32 v10, 16, v11
	v_and_b32_e32 v11, 0xffff0000, v11
	v_cvt_pk_bf16_f32 v8, v8, v9
	v_pk_mul_f32 v[12:13], v[12:13], v[14:15]
	v_or_b32_e32 v0, 16, v184
	v_pk_mul_f32 v[10:11], v[12:13], v[10:11]
	s_waitcnt vmcnt(2)
	v_lshlrev_b32_e32 v14, 16, v132
	v_cvt_pk_bf16_f32 v9, v10, v11
	v_lshlrev_b64 v[10:11], 11, v[4:5]
	v_lshl_add_u64 v[10:11], v[2:3], 0, v[10:11]
	v_lshl_add_u32 v4, v0, 7, v36
	global_store_dwordx4 v[10:11], v[6:9], off
	ds_read_b128 v[6:9], v4
	v_and_b32_e32 v15, 0xffff0000, v132
	v_mul_f32_e32 v4, 0xbfb8aa3b, v14
	v_exp_f32_e32 v10, v4
	v_mul_f32_e32 v4, 0xbfb8aa3b, v15
	v_exp_f32_e32 v11, v4
	v_or_b32_e32 v4, s4, v0
	v_add_f32_e32 v0, 1.0, v10
	v_rcp_f32_e32 v32, v0
	v_add_f32_e32 v0, 1.0, v11
	v_rcp_f32_e32 v33, v0
	v_or_b32_e32 v0, 24, v184
	s_waitcnt lgkmcnt(0)
	v_lshlrev_b32_e32 v34, 16, v6
	v_and_b32_e32 v35, 0xffff0000, v6
	v_pk_mul_f32 v[14:15], v[32:33], v[14:15]
	v_lshlrev_b32_e32 v32, 16, v133
	v_and_b32_e32 v33, 0xffff0000, v133
	v_mul_f32_e32 v6, 0xbfb8aa3b, v32
	v_lshl_add_u32 v10, v0, 7, v36
	v_exp_f32_e32 v6, v6
	v_mul_f32_e32 v36, 0xbfb8aa3b, v33
	v_exp_f32_e32 v36, v36
	v_pk_mul_f32 v[14:15], v[14:15], v[34:35]
	v_add_f32_e32 v6, 1.0, v6
	v_rcp_f32_e32 v34, v6
	v_add_f32_e32 v6, 1.0, v36
	v_rcp_f32_e32 v35, v6
	v_cvt_pk_bf16_f32 v6, v14, v15
	v_lshlrev_b32_e32 v14, 16, v7
	v_and_b32_e32 v15, 0xffff0000, v7
	v_pk_mul_f32 v[32:33], v[34:35], v[32:33]
	v_lshlrev_b32_e32 v34, 16, v134
	v_and_b32_e32 v35, 0xffff0000, v134
	v_mul_f32_e32 v7, 0xbfb8aa3b, v34
	v_exp_f32_e32 v7, v7
	v_mul_f32_e32 v36, 0xbfb8aa3b, v35
	v_exp_f32_e32 v36, v36
	v_pk_mul_f32 v[14:15], v[32:33], v[14:15]
	v_add_f32_e32 v7, 1.0, v7
	v_rcp_f32_e32 v32, v7
	v_add_f32_e32 v7, 1.0, v36
	v_rcp_f32_e32 v33, v7
	v_cvt_pk_bf16_f32 v7, v14, v15
	v_lshlrev_b32_e32 v14, 16, v8
	v_and_b32_e32 v15, 0xffff0000, v8
	v_pk_mul_f32 v[32:33], v[32:33], v[34:35]
	v_lshlrev_b32_e32 v34, 16, v135
	v_and_b32_e32 v35, 0xffff0000, v135
	v_mul_f32_e32 v8, 0xbfb8aa3b, v34
	v_exp_f32_e32 v8, v8
	v_mul_f32_e32 v36, 0xbfb8aa3b, v35
	v_exp_f32_e32 v36, v36
	v_pk_mul_f32 v[14:15], v[32:33], v[14:15]
	v_add_f32_e32 v8, 1.0, v8
	v_rcp_f32_e32 v32, v8
	v_add_f32_e32 v8, 1.0, v36
	v_rcp_f32_e32 v33, v8
	v_cvt_pk_bf16_f32 v8, v14, v15
	v_lshlrev_b32_e32 v14, 16, v9
	v_and_b32_e32 v15, 0xffff0000, v9
	v_pk_mul_f32 v[32:33], v[32:33], v[34:35]
	ds_read_b128 v[10:13], v10
	v_pk_mul_f32 v[14:15], v[32:33], v[14:15]
	s_waitcnt vmcnt(2)
	v_lshlrev_b32_e32 v32, 16, v128
	v_cvt_pk_bf16_f32 v9, v14, v15
	v_lshlrev_b64 v[14:15], 11, v[4:5]
	v_and_b32_e32 v33, 0xffff0000, v128
	v_mul_f32_e32 v4, 0xbfb8aa3b, v32
	v_exp_f32_e32 v4, v4
	v_mul_f32_e32 v34, 0xbfb8aa3b, v33
	v_exp_f32_e32 v34, v34
	v_lshl_add_u64 v[14:15], v[2:3], 0, v[14:15]
	v_add_f32_e32 v4, 1.0, v4
	global_store_dwordx4 v[14:15], v[6:9], off
	v_lshlrev_b32_e32 v14, 16, v129
	v_and_b32_e32 v15, 0xffff0000, v129
	v_rcp_f32_e32 v6, v4
	v_add_f32_e32 v4, 1.0, v34
	v_rcp_f32_e32 v7, v4
	v_or_b32_e32 v4, s4, v0
	v_mul_f32_e32 v0, 0xbfb8aa3b, v14
	s_waitcnt lgkmcnt(0)
	v_lshlrev_b32_e32 v8, 16, v10
	v_and_b32_e32 v9, 0xffff0000, v10
	v_exp_f32_e32 v0, v0
	v_mul_f32_e32 v10, 0xbfb8aa3b, v15
	v_exp_f32_e32 v10, v10
	v_pk_mul_f32 v[6:7], v[6:7], v[32:33]
	v_add_f32_e32 v0, 1.0, v0
	v_pk_mul_f32 v[6:7], v[6:7], v[8:9]
	v_rcp_f32_e32 v8, v0
	v_add_f32_e32 v0, 1.0, v10
	v_rcp_f32_e32 v9, v0
	v_cvt_pk_bf16_f32 v6, v6, v7
	v_lshlrev_b32_e32 v10, 16, v11
	v_and_b32_e32 v11, 0xffff0000, v11
	v_pk_mul_f32 v[8:9], v[8:9], v[14:15]
	v_lshlrev_b32_e32 v14, 16, v130
	v_and_b32_e32 v15, 0xffff0000, v130
	v_mul_f32_e32 v0, 0xbfb8aa3b, v14
	v_exp_f32_e32 v0, v0
	v_mul_f32_e32 v7, 0xbfb8aa3b, v15
	v_exp_f32_e32 v7, v7
	v_pk_mul_f32 v[8:9], v[8:9], v[10:11]
	v_add_f32_e32 v0, 1.0, v0
	v_rcp_f32_e32 v10, v0
	v_add_f32_e32 v0, 1.0, v7
	v_rcp_f32_e32 v11, v0
	v_cvt_pk_bf16_f32 v7, v8, v9
	v_lshlrev_b32_e32 v8, 16, v12
	v_and_b32_e32 v9, 0xffff0000, v12
	v_pk_mul_f32 v[10:11], v[10:11], v[14:15]
	v_lshlrev_b32_e32 v14, 16, v131
	v_and_b32_e32 v15, 0xffff0000, v131
	v_mul_f32_e32 v0, 0xbfb8aa3b, v14
	v_exp_f32_e32 v0, v0
	v_mul_f32_e32 v12, 0xbfb8aa3b, v15
	v_exp_f32_e32 v12, v12
	v_pk_mul_f32 v[8:9], v[10:11], v[8:9]
	v_add_f32_e32 v0, 1.0, v0
	v_rcp_f32_e32 v10, v0
	v_add_f32_e32 v0, 1.0, v12
	v_rcp_f32_e32 v11, v0
	v_lshlrev_b32_e32 v12, 16, v13
	v_and_b32_e32 v13, 0xffff0000, v13
	v_lshlrev_b64 v[4:5], 11, v[4:5]
	v_pk_mul_f32 v[10:11], v[10:11], v[14:15]
	v_cvt_pk_bf16_f32 v8, v8, v9
	v_pk_mul_f32 v[10:11], v[10:11], v[12:13]
	v_lshl_add_u64 v[2:3], v[2:3], 0, v[4:5]
	v_cvt_pk_bf16_f32 v9, v10, v11
	global_store_dwordx4 v[2:3], v[6:9], off
	s_waitcnt lgkmcnt(0)
	s_barrier
	s_mov_b64 s[4:5], 0

.LBB0_1320:
	s_waitcnt lgkmcnt(14)
	v_mfma_f32_32x32x16_bf16 v[32:47], v[176:179], v[196:199], v[32:47]
	v_exp_f32_e32 v128, v128
	v_exp_f32_e32 v129, v129
	v_exp_f32_e32 v130, v130
	v_exp_f32_e32 v131, v131
	s_waitcnt lgkmcnt(12)
	v_mfma_f32_32x32x16_bf16 v[48:63], v[176:179], v[192:195], v[48:63]
	v_exp_f32_e32 v132, v132
	v_exp_f32_e32 v133, v133
	v_exp_f32_e32 v134, v134
	v_exp_f32_e32 v135, v135
	v_add_u32_e32 v108, s61, v223
	ds_read_b128 v[92:95], v108
	ds_read_b128 v[192:195], v108 offset:2048
	v_add_u32_e32 v109, s61, v224
	s_waitcnt lgkmcnt(12)
	v_mfma_f32_32x32x16_bf16 v[32:47], v[164:167], v[96:99], v[32:47]
	v_exp_f32_e32 v136, v136
	v_exp_f32_e32 v137, v137
	v_exp_f32_e32 v138, v138
	v_exp_f32_e32 v139, v139
	ds_read_b128 v[196:199], v109
	ds_read_b128 v[188:191], v109 offset:2048
	s_waitcnt lgkmcnt(12)
	v_mfma_f32_32x32x16_bf16 v[48:63], v[164:167], v[100:103], v[48:63]
	v_exp_f32_e32 v140, v140
	v_exp_f32_e32 v141, v141
	v_exp_f32_e32 v142, v142
	v_exp_f32_e32 v143, v143
	ds_read_b128 v[184:187], v108 offset:4096
	ds_read_b128 v[180:183], v108 offset:6144
	s_waitcnt lgkmcnt(12)
	v_mfma_f32_32x32x16_bf16 v[32:47], v[160:163], v[104:107], v[32:47]
	v_exp_f32_e32 v112, v112
	v_exp_f32_e32 v113, v113
	v_exp_f32_e32 v114, v114
	v_exp_f32_e32 v115, v115
	ds_read_b128 v[156:159], v109 offset:4096
	ds_read_b128 v[152:155], v109 offset:6144
	s_waitcnt lgkmcnt(12)
	v_mfma_f32_32x32x16_bf16 v[48:63], v[160:163], v[80:83], v[48:63]
	v_exp_f32_e32 v116, v116
	v_exp_f32_e32 v117, v117
	v_exp_f32_e32 v118, v118
	v_exp_f32_e32 v119, v119
	s_waitcnt lgkmcnt(10)
	v_mfma_f32_32x32x16_bf16 v[32:47], v[6:9], v[84:87], v[32:47]
	v_exp_f32_e32 v120, v120
	v_exp_f32_e32 v121, v121
	v_exp_f32_e32 v122, v122
	v_exp_f32_e32 v123, v123
	s_waitcnt lgkmcnt(8)
	v_mfma_f32_32x32x16_bf16 v[48:63], v[6:9], v[88:91], v[48:63]
	v_exp_f32_e32 v124, v124
	v_exp_f32_e32 v125, v125
	v_exp_f32_e32 v126, v126
	v_exp_f32_e32 v127, v127
	s_waitcnt vmcnt(4) lgkmcnt(0)
	s_barrier
	s_andn2_b64 vcc, exec, s[28:29]
	s_cbranch_vccnz .LBB0_1322
	s_waitcnt lgkmcnt(0)
	v_add_u32_e32 v6, s44, v212
	ds_read_b128 v[80:83], v6 offset:96
	ds_read_b128 v[84:87], v6 offset:64
	ds_read_b128 v[88:91], v6 offset:32
	ds_read_b128 v[96:99], v6
	s_waitcnt lgkmcnt(3)
	v_pk_mul_f32 v[44:45], v[44:45], v[80:81]
	s_waitcnt lgkmcnt(2)
	v_pk_mul_f32 v[40:41], v[40:41], v[84:85]
	s_waitcnt lgkmcnt(1)
	v_pk_mul_f32 v[36:37], v[36:37], v[88:89]
	v_pk_mul_f32 v[46:47], v[46:47], v[82:83]
	v_pk_mul_f32 v[42:43], v[42:43], v[86:87]
	v_pk_mul_f32 v[38:39], v[38:39], v[90:91]
	s_waitcnt lgkmcnt(0)
	v_pk_mul_f32 v[34:35], v[34:35], v[98:99]
	v_pk_mul_f32 v[32:33], v[32:33], v[96:97]
	v_pk_mul_f32 v[60:61], v[60:61], v[80:81]
	v_pk_mul_f32 v[56:57], v[56:57], v[84:85]
	v_pk_mul_f32 v[52:53], v[52:53], v[88:89]
	v_pk_mul_f32 v[62:63], v[62:63], v[82:83]
	v_pk_mul_f32 v[58:59], v[58:59], v[86:87]
	v_pk_mul_f32 v[54:55], v[54:55], v[90:91]
	v_pk_mul_f32 v[50:51], v[50:51], v[98:99]
	v_pk_mul_f32 v[48:49], v[48:49], v[96:97]

.LBB0_1323:
	s_waitcnt lgkmcnt(14)
	v_mfma_f32_32x32x16_bf16 v[32:47], v[176:179], v[148:151], v[32:47]
	v_exp_f32_e32 v96, v96
	v_exp_f32_e32 v97, v97
	v_exp_f32_e32 v98, v98
	v_exp_f32_e32 v99, v99
	s_waitcnt lgkmcnt(12)
	v_mfma_f32_32x32x16_bf16 v[48:63], v[176:179], v[144:147], v[48:63]
	v_exp_f32_e32 v100, v100
	v_exp_f32_e32 v101, v101
	v_exp_f32_e32 v102, v102
	v_exp_f32_e32 v103, v103
	v_add_u32_e32 v124, s62, v223
	ds_read_b128 v[112:115], v124
	ds_read_b128 v[188:191], v124 offset:2048
	v_add_u32_e32 v125, s62, v224
	s_waitcnt lgkmcnt(12)
	v_mfma_f32_32x32x16_bf16 v[32:47], v[164:167], v[128:131], v[32:47]
	v_exp_f32_e32 v104, v104
	v_exp_f32_e32 v105, v105
	v_exp_f32_e32 v106, v106
	v_exp_f32_e32 v107, v107
	ds_read_b128 v[184:187], v125
	ds_read_b128 v[180:183], v125 offset:2048
	s_waitcnt lgkmcnt(12)
	v_mfma_f32_32x32x16_bf16 v[48:63], v[164:167], v[132:135], v[48:63]
	v_exp_f32_e32 v108, v108
	v_exp_f32_e32 v109, v109
	v_exp_f32_e32 v110, v110
	v_exp_f32_e32 v111, v111
	ds_read_b128 v[156:159], v124 offset:4096
	ds_read_b128 v[152:155], v124 offset:6144
	s_waitcnt lgkmcnt(12)
	v_mfma_f32_32x32x16_bf16 v[32:47], v[160:163], v[136:139], v[32:47]
	v_exp_f32_e32 v80, v80
	v_exp_f32_e32 v81, v81
	v_exp_f32_e32 v82, v82
	v_exp_f32_e32 v83, v83
	ds_read_b128 v[148:151], v125 offset:4096
	ds_read_b128 v[144:147], v125 offset:6144
	s_waitcnt lgkmcnt(12)
	v_mfma_f32_32x32x16_bf16 v[48:63], v[160:163], v[140:143], v[48:63]
	v_exp_f32_e32 v84, v84
	v_exp_f32_e32 v85, v85
	v_exp_f32_e32 v86, v86
	v_exp_f32_e32 v87, v87
	s_waitcnt lgkmcnt(10)
	v_mfma_f32_32x32x16_bf16 v[32:47], v[6:9], v[116:119], v[32:47]
	v_exp_f32_e32 v88, v88
	v_exp_f32_e32 v89, v89
	v_exp_f32_e32 v90, v90
	v_exp_f32_e32 v91, v91
	s_waitcnt lgkmcnt(8)
	v_mfma_f32_32x32x16_bf16 v[48:63], v[6:9], v[120:123], v[48:63]
	v_exp_f32_e32 v92, v92
	v_exp_f32_e32 v93, v93
	v_exp_f32_e32 v94, v94
	v_exp_f32_e32 v95, v95
	s_waitcnt vmcnt(4) lgkmcnt(0)
	s_barrier
	s_andn2_b64 vcc, exec, s[28:29]
	s_cbranch_vccnz .LBB0_1325
	s_waitcnt lgkmcnt(0)
	v_add_u32_e32 v6, s44, v212
	ds_read_b128 v[116:119], v6 offset:96
	ds_read_b128 v[120:123], v6 offset:64
	ds_read_b128 v[124:127], v6
	ds_read_b128 v[128:131], v6 offset:32
	s_waitcnt lgkmcnt(3)
	v_pk_mul_f32 v[46:47], v[46:47], v[118:119]
	v_pk_mul_f32 v[44:45], v[44:45], v[116:117]
	s_waitcnt lgkmcnt(2)
	v_pk_mul_f32 v[42:43], v[42:43], v[122:123]
	v_pk_mul_f32 v[40:41], v[40:41], v[120:121]
	s_waitcnt lgkmcnt(0)
	v_pk_mul_f32 v[38:39], v[38:39], v[130:131]
	v_pk_mul_f32 v[36:37], v[36:37], v[128:129]
	v_pk_mul_f32 v[34:35], v[34:35], v[126:127]
	v_pk_mul_f32 v[32:33], v[32:33], v[124:125]
	v_pk_mul_f32 v[62:63], v[62:63], v[118:119]
	v_pk_mul_f32 v[60:61], v[60:61], v[116:117]
	v_pk_mul_f32 v[58:59], v[58:59], v[122:123]
	v_pk_mul_f32 v[56:57], v[56:57], v[120:121]
	v_pk_mul_f32 v[54:55], v[54:55], v[130:131]
	v_pk_mul_f32 v[52:53], v[52:53], v[128:129]
	v_pk_mul_f32 v[50:51], v[50:51], v[126:127]
	v_pk_mul_f32 v[48:49], v[48:49], v[124:125]

.LBB0_1340:
	s_waitcnt lgkmcnt(14)
	v_mfma_f32_32x32x16_bf16 v[32:47], v[176:179], v[196:199], v[32:47]
	v_exp_f32_e32 v128, v128
	v_exp_f32_e32 v129, v129
	v_exp_f32_e32 v130, v130
	v_exp_f32_e32 v131, v131
	s_waitcnt lgkmcnt(12)
	v_mfma_f32_32x32x16_bf16 v[48:63], v[176:179], v[192:195], v[48:63]
	v_exp_f32_e32 v132, v132
	v_exp_f32_e32 v133, v133
	v_exp_f32_e32 v134, v134
	v_exp_f32_e32 v135, v135
	ds_read_b128 v[92:95], v223
	ds_read_b128 v[204:207], v223 offset:2048
	s_waitcnt lgkmcnt(12)
	v_mfma_f32_32x32x16_bf16 v[32:47], v[164:167], v[96:99], v[32:47]
	v_exp_f32_e32 v136, v136
	v_exp_f32_e32 v137, v137
	v_exp_f32_e32 v138, v138
	v_exp_f32_e32 v139, v139
	ds_read_b128 v[208:211], v224
	ds_read_b128 v[200:203], v224 offset:2048
	s_waitcnt lgkmcnt(12)
	v_mfma_f32_32x32x16_bf16 v[48:63], v[164:167], v[100:103], v[48:63]
	v_exp_f32_e32 v140, v140
	v_exp_f32_e32 v141, v141
	v_exp_f32_e32 v142, v142
	v_exp_f32_e32 v143, v143
	ds_read_b128 v[196:199], v223 offset:4096
	ds_read_b128 v[192:195], v223 offset:6144
	s_waitcnt lgkmcnt(12)
	v_mfma_f32_32x32x16_bf16 v[32:47], v[160:163], v[104:107], v[32:47]
	v_exp_f32_e32 v112, v112
	v_exp_f32_e32 v113, v113
	v_exp_f32_e32 v114, v114
	v_exp_f32_e32 v115, v115
	ds_read_b128 v[188:191], v224 offset:4096
	ds_read_b128 v[184:187], v224 offset:6144
	s_waitcnt lgkmcnt(12)
	v_mfma_f32_32x32x16_bf16 v[48:63], v[160:163], v[80:83], v[48:63]
	v_exp_f32_e32 v116, v116
	v_exp_f32_e32 v117, v117
	v_exp_f32_e32 v118, v118
	v_exp_f32_e32 v119, v119
	s_waitcnt lgkmcnt(10)
	v_mfma_f32_32x32x16_bf16 v[32:47], v[6:9], v[84:87], v[32:47]
	v_exp_f32_e32 v120, v120
	v_exp_f32_e32 v121, v121
	v_exp_f32_e32 v122, v122
	v_exp_f32_e32 v123, v123
	s_waitcnt lgkmcnt(8)
	v_mfma_f32_32x32x16_bf16 v[48:63], v[6:9], v[88:91], v[48:63]
	v_exp_f32_e32 v124, v124
	v_exp_f32_e32 v125, v125
	v_exp_f32_e32 v126, v126
	v_exp_f32_e32 v127, v127
	s_waitcnt vmcnt(4) lgkmcnt(0)
	s_barrier
	s_andn2_b64 vcc, exec, s[28:29]
	v_add_u32_e32 v212, s44, v212
	s_cbranch_vccnz .LBB0_1342
	s_waitcnt lgkmcnt(0)
	ds_read_b128 v[80:83], v212 offset:96
	ds_read_b128 v[84:87], v212 offset:64
	ds_read_b128 v[88:91], v212 offset:32
	ds_read_b128 v[96:99], v212
	s_waitcnt lgkmcnt(3)
	v_pk_mul_f32 v[44:45], v[44:45], v[80:81]
	s_waitcnt lgkmcnt(2)
	v_pk_mul_f32 v[40:41], v[40:41], v[84:85]
	s_waitcnt lgkmcnt(1)
	v_pk_mul_f32 v[36:37], v[36:37], v[88:89]
	v_pk_mul_f32 v[46:47], v[46:47], v[82:83]
	v_pk_mul_f32 v[42:43], v[42:43], v[86:87]
	v_pk_mul_f32 v[38:39], v[38:39], v[90:91]
	s_waitcnt lgkmcnt(0)
	v_pk_mul_f32 v[34:35], v[34:35], v[98:99]
	v_pk_mul_f32 v[32:33], v[32:33], v[96:97]
	v_pk_mul_f32 v[60:61], v[60:61], v[80:81]
	v_pk_mul_f32 v[56:57], v[56:57], v[84:85]
	v_pk_mul_f32 v[52:53], v[52:53], v[88:89]
	v_pk_mul_f32 v[62:63], v[62:63], v[82:83]
	v_pk_mul_f32 v[58:59], v[58:59], v[86:87]
	v_pk_mul_f32 v[54:55], v[54:55], v[90:91]
	v_pk_mul_f32 v[50:51], v[50:51], v[98:99]
	v_pk_mul_f32 v[48:49], v[48:49], v[96:97]

.LBB0_1343:
	s_waitcnt lgkmcnt(14)
	v_mfma_f32_32x32x16_bf16 v[32:47], v[176:179], v[180:183], v[32:47]
	v_exp_f32_e32 v144, v144
	v_exp_f32_e32 v145, v145
	v_exp_f32_e32 v146, v146
	v_exp_f32_e32 v147, v147
	s_waitcnt lgkmcnt(12)
	v_mfma_f32_32x32x16_bf16 v[48:63], v[176:179], v[108:111], v[48:63]
	v_exp_f32_e32 v148, v148
	v_exp_f32_e32 v149, v149
	v_exp_f32_e32 v150, v150
	v_exp_f32_e32 v151, v151
	ds_read_b128 v[108:111], v223 offset:8192
	ds_read_b128 v[204:207], v223 offset:10240
	s_waitcnt lgkmcnt(12)
	v_mfma_f32_32x32x16_bf16 v[32:47], v[164:167], v[96:99], v[32:47]
	v_exp_f32_e32 v152, v152
	v_exp_f32_e32 v153, v153
	v_exp_f32_e32 v154, v154
	v_exp_f32_e32 v155, v155
	ds_read_b128 v[208:211], v224 offset:8192
	ds_read_b128 v[200:203], v224 offset:10240
	s_waitcnt lgkmcnt(12)
	v_mfma_f32_32x32x16_bf16 v[48:63], v[164:167], v[100:103], v[48:63]
	v_exp_f32_e32 v156, v156
	v_exp_f32_e32 v157, v157
	v_exp_f32_e32 v158, v158
	v_exp_f32_e32 v159, v159
	ds_read_b128 v[196:199], v223 offset:12288
	ds_read_b128 v[192:195], v223 offset:14336
	s_waitcnt lgkmcnt(12)
	v_mfma_f32_32x32x16_bf16 v[32:47], v[160:163], v[104:107], v[32:47]
	v_exp_f32_e32 v80, v80
	v_exp_f32_e32 v81, v81
	v_exp_f32_e32 v82, v82
	v_exp_f32_e32 v83, v83
	ds_read_b128 v[188:191], v224 offset:12288
	ds_read_b128 v[184:187], v224 offset:14336
	s_waitcnt lgkmcnt(12)
	v_mfma_f32_32x32x16_bf16 v[48:63], v[160:163], v[112:115], v[48:63]
	v_exp_f32_e32 v84, v84
	v_exp_f32_e32 v85, v85
	v_exp_f32_e32 v86, v86
	v_exp_f32_e32 v87, v87
	s_waitcnt lgkmcnt(10)
	v_mfma_f32_32x32x16_bf16 v[32:47], v[6:9], v[116:119], v[32:47]
	v_exp_f32_e32 v88, v88
	v_exp_f32_e32 v89, v89
	v_exp_f32_e32 v90, v90
	v_exp_f32_e32 v91, v91
	s_waitcnt lgkmcnt(8)
	v_mfma_f32_32x32x16_bf16 v[48:63], v[6:9], v[120:123], v[48:63]
	v_exp_f32_e32 v92, v92
	v_exp_f32_e32 v93, v93
	v_exp_f32_e32 v94, v94
	v_exp_f32_e32 v95, v95
	s_waitcnt vmcnt(3) lgkmcnt(0)
	s_barrier
	s_andn2_b64 vcc, exec, s[28:29]
	s_cbranch_vccnz .LBB0_1345
	s_waitcnt lgkmcnt(0)
	ds_read_b128 v[96:99], v212 offset:96
	ds_read_b128 v[100:103], v212 offset:64
	ds_read_b128 v[104:107], v212 offset:32
	ds_read_b128 v[112:115], v212
	s_waitcnt lgkmcnt(3)
	v_pk_mul_f32 v[44:45], v[44:45], v[96:97]
	s_waitcnt lgkmcnt(2)
	v_pk_mul_f32 v[40:41], v[40:41], v[100:101]
	s_waitcnt lgkmcnt(1)
	v_pk_mul_f32 v[36:37], v[36:37], v[104:105]
	v_pk_mul_f32 v[46:47], v[46:47], v[98:99]
	v_pk_mul_f32 v[42:43], v[42:43], v[102:103]
	v_pk_mul_f32 v[38:39], v[38:39], v[106:107]
	s_waitcnt lgkmcnt(0)
	v_pk_mul_f32 v[34:35], v[34:35], v[114:115]
	v_pk_mul_f32 v[32:33], v[32:33], v[112:113]
	v_pk_mul_f32 v[60:61], v[60:61], v[96:97]
	v_pk_mul_f32 v[56:57], v[56:57], v[100:101]
	v_pk_mul_f32 v[52:53], v[52:53], v[104:105]
	v_pk_mul_f32 v[62:63], v[62:63], v[98:99]
	v_pk_mul_f32 v[58:59], v[58:59], v[102:103]
	v_pk_mul_f32 v[54:55], v[54:55], v[106:107]
	v_pk_mul_f32 v[50:51], v[50:51], v[114:115]
	v_pk_mul_f32 v[48:49], v[48:49], v[112:113]

.LBB0_1346:
	s_waitcnt lgkmcnt(14)
	v_mfma_f32_32x32x16_bf16 v[32:47], v[176:179], v[180:183], v[32:47]
	v_exp_f32_e32 v128, v128
	v_exp_f32_e32 v129, v129
	v_exp_f32_e32 v130, v130
	v_exp_f32_e32 v131, v131
	s_waitcnt lgkmcnt(12)
	v_mfma_f32_32x32x16_bf16 v[48:63], v[176:179], v[124:127], v[48:63]
	v_exp_f32_e32 v132, v132
	v_exp_f32_e32 v133, v133
	v_exp_f32_e32 v134, v134
	v_exp_f32_e32 v135, v135
	ds_read_b128 v[92:95], v223 offset:16384
	ds_read_b128 v[192:195], v223 offset:18432
	s_waitcnt lgkmcnt(12)
	v_mfma_f32_32x32x16_bf16 v[32:47], v[164:167], v[112:115], v[32:47]
	v_exp_f32_e32 v136, v136
	v_exp_f32_e32 v137, v137
	v_exp_f32_e32 v138, v138
	v_exp_f32_e32 v139, v139
	ds_read_b128 v[196:199], v224 offset:16384
	ds_read_b128 v[188:191], v224 offset:18432
	s_waitcnt lgkmcnt(12)
	v_mfma_f32_32x32x16_bf16 v[48:63], v[164:167], v[116:119], v[48:63]
	v_exp_f32_e32 v140, v140
	v_exp_f32_e32 v141, v141
	v_exp_f32_e32 v142, v142
	v_exp_f32_e32 v143, v143
	ds_read_b128 v[184:187], v223 offset:20480
	ds_read_b128 v[180:183], v223 offset:22528
	s_waitcnt lgkmcnt(12)
	v_mfma_f32_32x32x16_bf16 v[32:47], v[160:163], v[120:123], v[32:47]
	v_exp_f32_e32 v96, v96
	v_exp_f32_e32 v97, v97
	v_exp_f32_e32 v98, v98
	v_exp_f32_e32 v99, v99
	ds_read_b128 v[156:159], v224 offset:20480
	ds_read_b128 v[144:147], v224 offset:22528
	s_waitcnt lgkmcnt(12)
	v_mfma_f32_32x32x16_bf16 v[48:63], v[160:163], v[80:83], v[48:63]
	v_exp_f32_e32 v100, v100
	v_exp_f32_e32 v101, v101
	v_exp_f32_e32 v102, v102
	v_exp_f32_e32 v103, v103
	s_waitcnt lgkmcnt(10)
	v_mfma_f32_32x32x16_bf16 v[32:47], v[6:9], v[84:87], v[32:47]
	v_exp_f32_e32 v104, v104
	v_exp_f32_e32 v105, v105
	v_exp_f32_e32 v106, v106
	v_exp_f32_e32 v107, v107
	s_waitcnt lgkmcnt(8)
	v_mfma_f32_32x32x16_bf16 v[48:63], v[6:9], v[88:91], v[48:63]
	v_exp_f32_e32 v108, v108
	v_exp_f32_e32 v109, v109
	v_exp_f32_e32 v110, v110
	v_exp_f32_e32 v111, v111
	s_waitcnt vmcnt(2) lgkmcnt(0)
	s_barrier
	s_andn2_b64 vcc, exec, s[28:29]
	s_cbranch_vccnz .LBB0_1348
	s_waitcnt lgkmcnt(0)
	ds_read_b128 v[80:83], v212 offset:96
	ds_read_b128 v[84:87], v212 offset:64
	ds_read_b128 v[88:91], v212 offset:32
	ds_read_b128 v[112:115], v212
	s_waitcnt lgkmcnt(3)
	v_pk_mul_f32 v[44:45], v[44:45], v[80:81]
	s_waitcnt lgkmcnt(2)
	v_pk_mul_f32 v[40:41], v[40:41], v[84:85]
	s_waitcnt lgkmcnt(1)
	v_pk_mul_f32 v[36:37], v[36:37], v[88:89]
	v_pk_mul_f32 v[46:47], v[46:47], v[82:83]
	v_pk_mul_f32 v[42:43], v[42:43], v[86:87]
	v_pk_mul_f32 v[38:39], v[38:39], v[90:91]
	s_waitcnt lgkmcnt(0)
	v_pk_mul_f32 v[34:35], v[34:35], v[114:115]
	v_pk_mul_f32 v[32:33], v[32:33], v[112:113]
	v_pk_mul_f32 v[60:61], v[60:61], v[80:81]
	v_pk_mul_f32 v[56:57], v[56:57], v[84:85]
	v_pk_mul_f32 v[52:53], v[52:53], v[88:89]
	v_pk_mul_f32 v[62:63], v[62:63], v[82:83]
	v_pk_mul_f32 v[58:59], v[58:59], v[86:87]
	v_pk_mul_f32 v[54:55], v[54:55], v[90:91]
	v_pk_mul_f32 v[50:51], v[50:51], v[114:115]
	v_pk_mul_f32 v[48:49], v[48:49], v[112:113]

.LBB0_1349:
	s_waitcnt lgkmcnt(14)
	v_mfma_f32_32x32x16_bf16 v[32:47], v[176:179], v[152:155], v[32:47]
	v_exp_f32_e32 v112, v112
	v_exp_f32_e32 v113, v113
	v_exp_f32_e32 v114, v114
	v_exp_f32_e32 v115, v115
	s_waitcnt lgkmcnt(12)
	v_mfma_f32_32x32x16_bf16 v[48:63], v[176:179], v[148:151], v[48:63]
	v_exp_f32_e32 v116, v116
	v_exp_f32_e32 v117, v117
	v_exp_f32_e32 v118, v118
	v_exp_f32_e32 v119, v119
	ds_read_b128 v[196:199], v223 offset:24576
	ds_read_b128 v[192:195], v223 offset:26624
	s_waitcnt lgkmcnt(12)
	v_mfma_f32_32x32x16_bf16 v[32:47], v[164:167], v[128:131], v[32:47]
	v_exp_f32_e32 v120, v120
	v_exp_f32_e32 v121, v121
	v_exp_f32_e32 v122, v122
	v_exp_f32_e32 v123, v123
	ds_read_b128 v[188:191], v224 offset:24576
	ds_read_b128 v[184:187], v224 offset:26624
	s_waitcnt lgkmcnt(12)
	v_mfma_f32_32x32x16_bf16 v[48:63], v[164:167], v[132:135], v[48:63]
	v_exp_f32_e32 v124, v124
	v_exp_f32_e32 v125, v125
	v_exp_f32_e32 v126, v126
	v_exp_f32_e32 v127, v127
	ds_read_b128 v[180:183], v223 offset:28672
	ds_read_b128 v[156:159], v223 offset:30720
	s_waitcnt lgkmcnt(12)
	v_mfma_f32_32x32x16_bf16 v[32:47], v[160:163], v[136:139], v[32:47]
	v_exp_f32_e32 v80, v80
	v_exp_f32_e32 v81, v81
	v_exp_f32_e32 v82, v82
	v_exp_f32_e32 v83, v83
	ds_read_b128 v[152:155], v224 offset:28672
	ds_read_b128 v[144:147], v224 offset:30720
	s_waitcnt lgkmcnt(12)
	v_mfma_f32_32x32x16_bf16 v[48:63], v[160:163], v[96:99], v[48:63]
	v_exp_f32_e32 v84, v84
	v_exp_f32_e32 v85, v85
	v_exp_f32_e32 v86, v86
	v_exp_f32_e32 v87, v87
	s_waitcnt lgkmcnt(10)
	v_mfma_f32_32x32x16_bf16 v[32:47], v[6:9], v[100:103], v[32:47]
	v_exp_f32_e32 v88, v88
	v_exp_f32_e32 v89, v89
	v_exp_f32_e32 v90, v90
	v_exp_f32_e32 v91, v91
	s_waitcnt lgkmcnt(8)
	v_mfma_f32_32x32x16_bf16 v[48:63], v[6:9], v[104:107], v[48:63]
	v_exp_f32_e32 v92, v92
	v_exp_f32_e32 v93, v93
	v_exp_f32_e32 v94, v94
	v_exp_f32_e32 v95, v95
	s_waitcnt vmcnt(0) lgkmcnt(0)
	s_barrier
	s_andn2_b64 vcc, exec, s[28:29]
	s_cbranch_vccnz .LBB0_1351
	s_waitcnt lgkmcnt(0)
	ds_read_b128 v[96:99], v212 offset:96
	ds_read_b128 v[100:103], v212 offset:64
	ds_read_b128 v[104:107], v212 offset:32
	ds_read_b128 v[108:111], v212
	s_waitcnt lgkmcnt(3)
	v_pk_mul_f32 v[44:45], v[44:45], v[96:97]
	s_waitcnt lgkmcnt(2)
	v_pk_mul_f32 v[40:41], v[40:41], v[100:101]
	s_waitcnt lgkmcnt(1)
	v_pk_mul_f32 v[36:37], v[36:37], v[104:105]
	v_pk_mul_f32 v[46:47], v[46:47], v[98:99]
	v_pk_mul_f32 v[42:43], v[42:43], v[102:103]
	v_pk_mul_f32 v[38:39], v[38:39], v[106:107]
	s_waitcnt lgkmcnt(0)
	v_pk_mul_f32 v[34:35], v[34:35], v[110:111]
	v_pk_mul_f32 v[32:33], v[32:33], v[108:109]
	v_pk_mul_f32 v[60:61], v[60:61], v[96:97]
	v_pk_mul_f32 v[56:57], v[56:57], v[100:101]
	v_pk_mul_f32 v[52:53], v[52:53], v[104:105]
	v_pk_mul_f32 v[62:63], v[62:63], v[98:99]
	v_pk_mul_f32 v[58:59], v[58:59], v[102:103]
	v_pk_mul_f32 v[54:55], v[54:55], v[106:107]
	v_pk_mul_f32 v[50:51], v[50:51], v[110:111]
	v_pk_mul_f32 v[48:49], v[48:49], v[108:109]

.LBB0_1352:
	s_waitcnt lgkmcnt(14)
	v_mfma_f32_32x32x16_bf16 v[32:47], v[176:179], v[148:151], v[32:47]
	v_exp_f32_e32 v96, v96
	v_exp_f32_e32 v97, v97
	v_exp_f32_e32 v98, v98
	v_exp_f32_e32 v99, v99
	s_waitcnt lgkmcnt(12)
	v_mfma_f32_32x32x16_bf16 v[48:63], v[176:179], v[112:115], v[48:63]
	v_exp_f32_e32 v100, v100
	v_exp_f32_e32 v101, v101
	v_exp_f32_e32 v102, v102
	v_exp_f32_e32 v103, v103
	s_waitcnt lgkmcnt(10)
	v_mfma_f32_32x32x16_bf16 v[32:47], v[164:167], v[116:119], v[32:47]
	v_exp_f32_e32 v104, v104
	v_exp_f32_e32 v105, v105
	v_exp_f32_e32 v106, v106
	v_exp_f32_e32 v107, v107
	s_waitcnt lgkmcnt(8)
	v_mfma_f32_32x32x16_bf16 v[48:63], v[164:167], v[120:123], v[48:63]
	v_exp_f32_e32 v108, v108
	v_exp_f32_e32 v109, v109
	v_exp_f32_e32 v110, v110
	v_exp_f32_e32 v111, v111
	s_waitcnt lgkmcnt(6)
	v_mfma_f32_32x32x16_bf16 v[32:47], v[160:163], v[124:127], v[32:47]
	v_exp_f32_e32 v64, v64
	v_exp_f32_e32 v65, v65
	v_exp_f32_e32 v66, v66
	v_exp_f32_e32 v67, v67
	s_waitcnt lgkmcnt(4)
	v_mfma_f32_32x32x16_bf16 v[48:63], v[160:163], v[168:171], v[48:63]
	v_exp_f32_e32 v68, v68
	v_exp_f32_e32 v69, v69
	v_exp_f32_e32 v70, v70
	v_exp_f32_e32 v71, v71
	s_waitcnt lgkmcnt(2)
	v_mfma_f32_32x32x16_bf16 v[32:47], v[6:9], v[10:13], v[32:47]
	v_exp_f32_e32 v72, v72
	v_exp_f32_e32 v73, v73
	v_exp_f32_e32 v74, v74
	v_exp_f32_e32 v75, v75
	s_waitcnt lgkmcnt(0)
	v_mfma_f32_32x32x16_bf16 v[48:63], v[6:9], v[152:155], v[48:63]
	v_exp_f32_e32 v76, v76
	v_exp_f32_e32 v77, v77
	v_exp_f32_e32 v78, v78
	v_exp_f32_e32 v79, v79
	s_andn2_b64 vcc, exec, s[28:29]
	s_cbranch_vccnz .LBB0_1354
	s_waitcnt lgkmcnt(0)
	ds_read_b128 v[4:7], v212 offset:96
	ds_read_b128 v[8:11], v212 offset:64
	ds_read_b128 v[80:83], v212 offset:32
	ds_read_b128 v[84:87], v212
	s_waitcnt lgkmcnt(3)
	v_pk_mul_f32 v[44:45], v[44:45], v[4:5]
	s_waitcnt lgkmcnt(2)
	v_pk_mul_f32 v[40:41], v[40:41], v[8:9]
	s_waitcnt lgkmcnt(1)
	v_pk_mul_f32 v[36:37], v[36:37], v[80:81]
	v_pk_mul_f32 v[46:47], v[46:47], v[6:7]
	v_pk_mul_f32 v[42:43], v[42:43], v[10:11]
	v_pk_mul_f32 v[38:39], v[38:39], v[82:83]
	s_waitcnt lgkmcnt(0)
	v_pk_mul_f32 v[34:35], v[34:35], v[86:87]
	v_pk_mul_f32 v[32:33], v[32:33], v[84:85]
	v_pk_mul_f32 v[60:61], v[60:61], v[4:5]
	v_pk_mul_f32 v[56:57], v[56:57], v[8:9]
	v_pk_mul_f32 v[52:53], v[52:53], v[80:81]
	v_pk_mul_f32 v[62:63], v[62:63], v[6:7]
	v_pk_mul_f32 v[58:59], v[58:59], v[10:11]
	v_pk_mul_f32 v[54:55], v[54:55], v[82:83]
	v_pk_mul_f32 v[50:51], v[50:51], v[86:87]
	v_pk_mul_f32 v[48:49], v[48:49], v[84:85]

.LBB0_1386:
	s_setprio 0
	v_readlane_b32 s90, v254, 4
	v_readlane_b32 s92, v254, 6
	s_cmp_lt_i32 s35, 7
	v_readlane_b32 s91, v254, 5
	v_readlane_b32 s93, v254, 7
	s_cbranch_scc1 .LBB0_1440
	s_getreg_b32 s3, hwreg(HW_REG_XCC_ID, 0, 4)
	s_waitcnt vmcnt(0)
	s_waitcnt vmcnt(0) lgkmcnt(0)
	s_barrier
	s_getreg_b32 s0, hwreg(HW_REG_HW_ID, 0, 6)
	s_lshl_b32 s0, s0, 2
	s_and_b32 s0, s0, 0xfc
	s_add_i32 s0, s0, 0
	s_add_i32 s0, s0, 0x256c0
	v_mov_b32_e32 v0, s0
	ds_read_b32 v0, v0
	s_waitcnt lgkmcnt(0)
	v_readfirstlane_b32 s0, v0
	v_mbcnt_lo_u32_b32 v0, -1, 0
	v_mbcnt_hi_u32_b32 v0, -1, v0
	s_lshl_b32 s0, s0, 6
	v_sub_u32_e32 v0, 0, v0
	v_cmp_eq_u32_e32 vcc, s0, v0
	s_and_saveexec_b64 s[0:1], vcc
	s_cbranch_execz .LBB0_1439
	s_add_i32 s4, 0, 0x257c0
	v_mov_b32_e32 v0, s4
	s_waitcnt vmcnt(0) expcnt(0) lgkmcnt(0)
	ds_read_b32 v2, v0
	s_add_i32 s4, 0, 0x257c4
	v_mov_b32_e32 v0, s4
	ds_read_b32 v0, v0
	s_and_b32 s3, s3, 15
	s_waitcnt lgkmcnt(1)
	v_cmp_ne_u32_e32 vcc, 0, v2
	s_cbranch_vccnz .LBB0_1403
	s_load_dwordx2 s[8:9], s[90:91], 0x4
	s_add_u32 s4, s78, 0x1f400200
	s_addc_u32 s5, s79, 0
	s_add_u32 s6, s78, 0x1f400400
	s_addc_u32 s7, s79, 0
	s_waitcnt lgkmcnt(0)
	s_mul_i32 s26, s8, s33
	s_add_u32 s8, s78, 0x1f400500
	s_mul_i32 s26, s26, s9
	s_addc_u32 s9, s79, 0
	s_add_u32 s10, s78, 0x1f400600
	s_addc_u32 s11, s79, 0
	s_add_u32 s12, s78, 0x1f400700
	s_addc_u32 s13, s79, 0
	s_add_u32 s14, s78, 0x1f400800
	s_addc_u32 s15, s79, 0
	s_add_u32 s16, s78, 0x1f400900
	s_addc_u32 s17, s79, 0
	s_add_u32 s18, s78, 0x1f400a00
	s_addc_u32 s19, s79, 0
	s_add_u32 s20, s78, 0x1f400b00
	s_addc_u32 s21, s79, 0
	s_add_u32 s22, s78, 0x1f400c00
	s_addc_u32 s23, s79, 0
	s_add_u32 s24, s78, 0x1f400d00
	s_addc_u32 s25, s79, 0
	s_add_u32 s28, s78, 0x1f400e00
	s_addc_u32 s29, s79, 0
	s_add_u32 s30, s78, 0x1f400f00
	s_addc_u32 s31, s79, 0
	s_add_u32 s40, s78, 0x1f401000
	s_addc_u32 s41, s79, 0
	s_add_u32 s42, s78, 0x1f401100
	s_addc_u32 s43, s79, 0
	s_add_u32 s44, s78, 0x1f401200
	s_addc_u32 s45, s79, 0
	s_add_u32 s46, s78, 0x1f401300
	s_addc_u32 s47, s79, 0
	s_mov_b32 s27, 1
	v_mov_b32_e32 v16, 0
	s_branch .LBB0_1391

.LBB0_1458:
	s_lshr_b32 s19, s28, 4
	s_mul_i32 s30, s19, 0xc00
	s_ashr_i32 s31, s30, 31
	v_lshl_or_b32 v168, s60, 8, v177
	s_lshl_b64 s[30:31], s[30:31], 2
	s_add_u32 s30, s78, s30
	v_ashrrev_i32_e32 v169, 31, v168
	v_lshl_add_u32 v172, s28, 8, v175
	s_addc_u32 s31, s79, s31
	v_lshlrev_b64 v[132:133], 2, v[168:169]
	v_or_b32_e32 v238, 16, v172
	v_lshl_add_u64 v[134:135], s[30:31], 0, v[132:133]
	v_ashrrev_i32_e32 v173, 31, v172
	v_ashrrev_i32_e32 v239, 31, v238
	v_lshl_add_u64 v[144:145], v[134:135], 0, s[16:17]
	v_add_co_u32_e32 v134, vcc, s59, v134
	v_lshl_add_u64 v[170:171], s[52:53], 0, v[132:133]
	v_lshlrev_b64 v[132:133], 12, v[172:173]
	v_lshlrev_b64 v[140:141], 12, v[238:239]
	v_lshl_add_u64 v[132:133], v[170:171], 0, v[132:133]
	v_lshl_add_u64 v[146:147], v[170:171], 0, v[140:141]
	v_addc_co_u32_e32 v135, vcc, 0, v135, vcc
	global_load_dwordx4 v[136:139], v[144:145], off offset:16
	global_load_dwordx4 v[128:131], v[144:145], off offset:512
	global_load_dwordx4 v[182:185], v[132:133], off offset:16
	global_load_dwordx4 v[186:189], v[132:133], off offset:512
	global_load_dwordx4 v[190:193], v[146:147], off offset:16
	global_load_dwordx4 v[194:197], v[146:147], off offset:512
	global_load_dwordx4 v[140:143], v[134:135], off
	global_load_dwordx4 v[198:201], v[132:133], off
	global_load_dwordx4 v[202:205], v[132:133], off offset:528
	s_nop 0
	global_load_dwordx4 v[132:135], v[144:145], off offset:528
	global_load_dwordx4 v[206:209], v[146:147], off
	global_load_dwordx4 v[210:213], v[146:147], off offset:528
	v_or_b32_e32 v240, 32, v172
	v_ashrrev_i32_e32 v241, 31, v240
	v_lshlrev_b64 v[144:145], 12, v[240:241]
	v_lshl_add_u64 v[144:145], v[170:171], 0, v[144:145]
	global_load_dwordx4 v[214:217], v[144:145], off
	global_load_dwordx4 v[218:221], v[144:145], off offset:16
	global_load_dwordx4 v[222:225], v[144:145], off offset:512
	global_load_dwordx4 v[226:229], v[144:145], off offset:528
	v_or_b32_e32 v242, 48, v172
	v_ashrrev_i32_e32 v243, 31, v242
	v_lshlrev_b64 v[144:145], 12, v[242:243]
	v_lshl_add_u64 v[144:145], v[170:171], 0, v[144:145]
	global_load_dwordx4 v[230:233], v[144:145], off
	global_load_dwordx4 v[234:237], v[144:145], off offset:16
	global_load_dwordx4 v[148:151], v[144:145], off offset:512
	s_nop 0
	global_load_dwordx4 v[144:147], v[144:145], off offset:528
	v_lshlrev_b64 v[244:245], 11, v[172:173]
	v_lshlrev_b64 v[168:169], 1, v[168:169]
	v_lshl_add_u64 v[244:245], s[6:7], 0, v[244:245]
	v_lshlrev_b64 v[238:239], 11, v[238:239]
	v_lshl_add_u64 v[244:245], v[244:245], 0, v[168:169]
	v_lshl_add_u64 v[238:239], s[6:7], 0, v[238:239]
	v_lshl_add_u64 v[238:239], v[238:239], 0, v[168:169]
	s_andn2_b64 vcc, exec, s[4:5]
	s_mov_b64 s[4:5], -1
	s_waitcnt vmcnt(0)
	v_pk_fma_f32 v[122:123], v[122:123], v[142:143], v[200:201]
	v_pk_fma_f32 v[126:127], v[126:127], v[138:139], v[184:185]
	v_pk_fma_f32 v[120:121], v[120:121], v[140:141], v[198:199]
	v_pk_fma_f32 v[124:125], v[124:125], v[136:137], v[182:183]
	v_pk_fma_f32 v[184:185], v[96:97], v[132:133], v[210:211]
	v_cvt_pk_bf16_f32 v96, v120, v121
	v_cvt_pk_bf16_f32 v97, v122, v123
	v_pk_fma_f32 v[110:111], v[110:111], v[130:131], v[188:189]
	v_pk_fma_f32 v[108:109], v[108:109], v[128:129], v[186:187]
	v_pk_fma_f32 v[182:183], v[98:99], v[134:135], v[212:213]
	v_cvt_pk_bf16_f32 v98, v124, v125
	v_cvt_pk_bf16_f32 v99, v126, v127
	global_store_dwordx4 v[244:245], v[96:99], off
	v_pk_fma_f32 v[106:107], v[106:107], v[134:135], v[204:205]
	v_pk_fma_f32 v[104:105], v[104:105], v[132:133], v[202:203]
	v_cvt_pk_bf16_f32 v96, v108, v109
	v_cvt_pk_bf16_f32 v97, v110, v111
	v_pk_fma_f32 v[114:115], v[114:115], v[142:143], v[208:209]
	v_pk_fma_f32 v[112:113], v[112:113], v[140:141], v[206:207]
	v_cvt_pk_bf16_f32 v98, v104, v105
	v_cvt_pk_bf16_f32 v99, v106, v107
	global_store_dwordx4 v[244:245], v[96:99], off offset:256
	v_pk_fma_f32 v[118:119], v[118:119], v[138:139], v[192:193]
	v_pk_fma_f32 v[116:117], v[116:117], v[136:137], v[190:191]
	v_cvt_pk_bf16_f32 v96, v112, v113
	v_cvt_pk_bf16_f32 v97, v114, v115
	v_pk_fma_f32 v[102:103], v[102:103], v[130:131], v[196:197]
	v_pk_fma_f32 v[100:101], v[100:101], v[128:129], v[194:195]
	v_cvt_pk_bf16_f32 v98, v116, v117
	v_cvt_pk_bf16_f32 v99, v118, v119
	global_store_dwordx4 v[238:239], v[96:99], off
	v_pk_fma_f32 v[92:93], v[92:93], v[140:141], v[214:215]
	v_pk_fma_f32 v[94:95], v[94:95], v[142:143], v[216:217]
	v_cvt_pk_bf16_f32 v96, v100, v101
	v_cvt_pk_bf16_f32 v97, v102, v103
	v_cvt_pk_bf16_f32 v98, v184, v185
	v_cvt_pk_bf16_f32 v99, v182, v183
	global_store_dwordx4 v[238:239], v[96:99], off offset:256
	v_pk_fma_f32 v[86:87], v[86:87], v[130:131], v[224:225]
	v_pk_fma_f32 v[84:85], v[84:85], v[128:129], v[222:223]
	v_lshlrev_b64 v[96:97], 11, v[240:241]
	v_pk_fma_f32 v[98:99], v[90:91], v[138:139], v[220:221]
	v_pk_fma_f32 v[90:91], v[88:89], v[136:137], v[218:219]
	v_cvt_pk_bf16_f32 v88, v92, v93
	v_lshl_add_u64 v[92:93], s[6:7], 0, v[96:97]
	v_cvt_pk_bf16_f32 v89, v94, v95
	v_lshl_add_u64 v[92:93], v[92:93], 0, v[168:169]
	v_cvt_pk_bf16_f32 v90, v90, v91
	v_cvt_pk_bf16_f32 v91, v98, v99
	global_store_dwordx4 v[92:93], v[88:91], off
	v_pk_fma_f32 v[80:81], v[80:81], v[140:141], v[230:231]
	v_pk_fma_f32 v[70:71], v[70:71], v[130:131], v[150:151]
	v_pk_fma_f32 v[88:89], v[78:79], v[134:135], v[228:229]
	v_pk_fma_f32 v[78:79], v[76:77], v[132:133], v[226:227]
	v_cvt_pk_bf16_f32 v76, v84, v85
	v_cvt_pk_bf16_f32 v77, v86, v87
	v_pk_fma_f32 v[68:69], v[68:69], v[128:129], v[148:149]
	v_cvt_pk_bf16_f32 v78, v78, v79
	v_cvt_pk_bf16_f32 v79, v88, v89
	global_store_dwordx4 v[92:93], v[76:79], off offset:256
	v_add_u32_e32 v148, 0xa0, v172
	v_ashrrev_i32_e32 v149, 31, v148
	v_lshlrev_b64 v[76:77], 11, v[242:243]
	v_lshl_add_u64 v[76:77], s[6:7], 0, v[76:77]
	v_pk_fma_f32 v[78:79], v[82:83], v[142:143], v[232:233]
	v_pk_fma_f32 v[82:83], v[74:75], v[138:139], v[236:237]
	v_pk_fma_f32 v[74:75], v[72:73], v[136:137], v[234:235]
	v_cvt_pk_bf16_f32 v72, v80, v81
	v_cvt_pk_bf16_f32 v73, v78, v79
	v_lshl_add_u64 v[76:77], v[76:77], 0, v[168:169]
	v_cvt_pk_bf16_f32 v74, v74, v75
	v_cvt_pk_bf16_f32 v75, v82, v83
	global_store_dwordx4 v[76:77], v[72:75], off
	v_lshlrev_b64 v[96:97], 12, v[148:149]
	v_lshl_add_u64 v[108:109], v[170:171], 0, v[96:97]
	v_pk_fma_f32 v[72:73], v[66:67], v[134:135], v[146:147]
	v_pk_fma_f32 v[66:67], v[64:65], v[132:133], v[144:145]
	v_add_u32_e32 v144, 0x80, v172
	v_cvt_pk_bf16_f32 v64, v68, v69
	v_cvt_pk_bf16_f32 v65, v70, v71
	v_ashrrev_i32_e32 v145, 31, v144
	v_cvt_pk_bf16_f32 v66, v66, v67
	v_cvt_pk_bf16_f32 v67, v72, v73
	global_store_dwordx4 v[76:77], v[64:67], off offset:256
	v_add_u32_e32 v146, 0x90, v172
	v_ashrrev_i32_e32 v147, 31, v146
	v_lshlrev_b64 v[64:65], 12, v[144:145]
	v_lshl_add_u64 v[76:77], v[170:171], 0, v[64:65]
	global_load_dwordx4 v[64:67], v[76:77], off
	global_load_dwordx4 v[68:71], v[76:77], off offset:16
	global_load_dwordx4 v[72:75], v[76:77], off offset:512
	s_nop 0
	global_load_dwordx4 v[76:79], v[76:77], off offset:528
	v_lshlrev_b64 v[80:81], 12, v[146:147]
	v_lshl_add_u64 v[92:93], v[170:171], 0, v[80:81]
	global_load_dwordx4 v[80:83], v[92:93], off
	global_load_dwordx4 v[84:87], v[92:93], off offset:16
	global_load_dwordx4 v[88:91], v[92:93], off offset:512
	s_nop 0
	global_load_dwordx4 v[92:95], v[92:93], off offset:528
	s_nop 0
	global_load_dwordx4 v[96:99], v[108:109], off
	global_load_dwordx4 v[100:103], v[108:109], off offset:16
	global_load_dwordx4 v[104:107], v[108:109], off offset:512
	s_nop 0
	global_load_dwordx4 v[108:111], v[108:109], off offset:528
	v_add_u32_e32 v150, 0xb0, v172
	v_ashrrev_i32_e32 v151, 31, v150
	v_lshlrev_b64 v[112:113], 12, v[150:151]
	v_lshl_add_u64 v[124:125], v[170:171], 0, v[112:113]
	global_load_dwordx4 v[112:115], v[124:125], off
	global_load_dwordx4 v[116:119], v[124:125], off offset:16
	global_load_dwordx4 v[120:123], v[124:125], off offset:512
	s_nop 0
	global_load_dwordx4 v[124:127], v[124:125], off offset:528
	v_lshlrev_b64 v[144:145], 11, v[144:145]
	v_lshl_add_u64 v[144:145], s[6:7], 0, v[144:145]
	v_lshl_add_u64 v[144:145], v[144:145], 0, v[168:169]
	s_waitcnt vmcnt(15)
	v_pk_fma_f32 v[62:63], v[62:63], v[142:143], v[66:67]
	v_pk_fma_f32 v[60:61], v[60:61], v[140:141], v[64:65]
	s_waitcnt vmcnt(14)
	v_pk_fma_f32 v[64:65], v[58:59], v[138:139], v[70:71]
	v_pk_fma_f32 v[58:59], v[56:57], v[136:137], v[68:69]
	v_cvt_pk_bf16_f32 v56, v60, v61
	v_cvt_pk_bf16_f32 v57, v62, v63
	s_waitcnt vmcnt(13)
	v_pk_fma_f32 v[54:55], v[54:55], v[130:131], v[74:75]
	v_cvt_pk_bf16_f32 v58, v58, v59
	v_cvt_pk_bf16_f32 v59, v64, v65
	global_store_dwordx4 v[144:145], v[56:59], off
	v_pk_fma_f32 v[52:53], v[52:53], v[128:129], v[72:73]
	s_waitcnt vmcnt(12)
	v_pk_fma_f32 v[48:49], v[48:49], v[140:141], v[80:81]
	v_pk_fma_f32 v[56:57], v[46:47], v[134:135], v[78:79]
	v_pk_fma_f32 v[46:47], v[44:45], v[132:133], v[76:77]
	v_cvt_pk_bf16_f32 v44, v52, v53
	v_cvt_pk_bf16_f32 v45, v54, v55
	s_waitcnt vmcnt(10)
	v_pk_fma_f32 v[38:39], v[38:39], v[130:131], v[90:91]
	v_cvt_pk_bf16_f32 v46, v46, v47
	v_cvt_pk_bf16_f32 v47, v56, v57
	global_store_dwordx4 v[144:145], v[44:47], off offset:256
	v_pk_fma_f32 v[36:37], v[36:37], v[128:129], v[88:89]
	s_waitcnt vmcnt(9)
	v_pk_fma_f32 v[32:33], v[32:33], v[140:141], v[96:97]
	v_lshlrev_b64 v[44:45], 11, v[146:147]
	v_lshl_add_u64 v[44:45], s[6:7], 0, v[44:45]
	v_pk_fma_f32 v[46:47], v[50:51], v[142:143], v[82:83]
	v_pk_fma_f32 v[50:51], v[42:43], v[138:139], v[86:87]
	v_pk_fma_f32 v[42:43], v[40:41], v[136:137], v[84:85]
	v_cvt_pk_bf16_f32 v40, v48, v49
	v_cvt_pk_bf16_f32 v41, v46, v47
	v_lshl_add_u64 v[44:45], v[44:45], 0, v[168:169]
	v_cvt_pk_bf16_f32 v42, v42, v43
	v_cvt_pk_bf16_f32 v43, v50, v51
	global_store_dwordx4 v[44:45], v[40:43], off
	s_waitcnt vmcnt(8)
	v_pk_fma_f32 v[22:23], v[22:23], v[130:131], v[106:107]
	v_pk_fma_f32 v[20:21], v[20:21], v[128:129], v[104:105]
	v_pk_fma_f32 v[40:41], v[30:31], v[134:135], v[94:95]
	v_pk_fma_f32 v[30:31], v[28:29], v[132:133], v[92:93]
	v_cvt_pk_bf16_f32 v28, v36, v37
	v_cvt_pk_bf16_f32 v29, v38, v39
	s_waitcnt vmcnt(6)
	v_pk_fma_f32 v[16:17], v[16:17], v[140:141], v[112:113]
	v_cvt_pk_bf16_f32 v30, v30, v31
	v_cvt_pk_bf16_f32 v31, v40, v41
	global_store_dwordx4 v[44:45], v[28:31], off offset:256
	s_waitcnt vmcnt(5)
	v_pk_fma_f32 v[6:7], v[6:7], v[130:131], v[122:123]
	v_pk_fma_f32 v[4:5], v[4:5], v[128:129], v[120:121]
	v_lshlrev_b64 v[28:29], 11, v[148:149]
	v_lshl_add_u64 v[28:29], s[6:7], 0, v[28:29]
	v_pk_fma_f32 v[30:31], v[34:35], v[142:143], v[98:99]
	v_pk_fma_f32 v[34:35], v[26:27], v[138:139], v[102:103]
	v_pk_fma_f32 v[26:27], v[24:25], v[136:137], v[100:101]
	v_cvt_pk_bf16_f32 v24, v32, v33
	v_cvt_pk_bf16_f32 v25, v30, v31
	v_lshl_add_u64 v[28:29], v[28:29], 0, v[168:169]
	v_cvt_pk_bf16_f32 v26, v26, v27
	v_cvt_pk_bf16_f32 v27, v34, v35
	global_store_dwordx4 v[28:29], v[24:27], off
	s_nop 1
	v_pk_fma_f32 v[24:25], v[14:15], v[134:135], v[110:111]
	v_pk_fma_f32 v[14:15], v[12:13], v[132:133], v[108:109]
	v_cvt_pk_bf16_f32 v12, v20, v21
	v_cvt_pk_bf16_f32 v13, v22, v23
	s_nop 0
	v_cvt_pk_bf16_f32 v14, v14, v15
	v_cvt_pk_bf16_f32 v15, v24, v25
	global_store_dwordx4 v[28:29], v[12:15], off offset:256
	s_nop 1
	v_lshlrev_b64 v[12:13], 11, v[150:151]
	v_lshl_add_u64 v[12:13], s[6:7], 0, v[12:13]
	v_pk_fma_f32 v[14:15], v[18:19], v[142:143], v[114:115]
	v_pk_fma_f32 v[18:19], v[10:11], v[138:139], v[118:119]
	v_pk_fma_f32 v[10:11], v[8:9], v[136:137], v[116:117]
	v_cvt_pk_bf16_f32 v8, v16, v17
	v_cvt_pk_bf16_f32 v9, v14, v15
	v_lshl_add_u64 v[12:13], v[12:13], 0, v[168:169]
	v_cvt_pk_bf16_f32 v10, v10, v11
	v_cvt_pk_bf16_f32 v11, v18, v19
	global_store_dwordx4 v[12:13], v[8:11], off
	s_waitcnt vmcnt(7)
	s_nop 0
	v_pk_fma_f32 v[8:9], v[2:3], v[134:135], v[126:127]
	v_pk_fma_f32 v[2:3], v[0:1], v[132:133], v[124:125]
	v_cvt_pk_bf16_f32 v0, v4, v5
	v_cvt_pk_bf16_f32 v1, v6, v7
	s_nop 0
	v_cvt_pk_bf16_f32 v2, v2, v3
	v_cvt_pk_bf16_f32 v3, v8, v9
	global_store_dwordx4 v[12:13], v[0:3], off offset:256
	s_cbranch_vccnz .LBB0_1447
	s_andn2_b64 vcc, exec, s[10:11]
	s_cbranch_vccnz .LBB0_1446
	s_barrier
	s_branch .LBB0_1446

.LBB0_1482:
	s_lshr_b32 s17, s46, 4
	s_mul_i32 s48, s17, 0xc00
	s_ashr_i32 s49, s48, 31
	v_lshl_or_b32 v208, s44, 8, v230
	s_lshl_b64 s[48:49], s[48:49], 2
	s_add_u32 s50, s78, s48
	v_ashrrev_i32_e32 v209, 31, v208
	s_addc_u32 s51, s79, s49
	v_lshlrev_b64 v[216:217], 2, v[208:209]
	v_lshl_add_u32 v218, s46, 8, v228
	v_lshl_add_u64 v[112:113], s[50:51], 0, v[216:217]
	s_mov_b64 s[50:51], 0x1502000
	s_mov_b32 s17, 0x1502000
	v_ashrrev_i32_e32 v219, 31, v218
	v_lshl_add_u64 v[114:115], v[112:113], 0, s[50:51]
	v_add_co_u32_e32 v112, vcc, s17, v112
	v_lshl_add_u64 v[220:221], s[52:53], 0, v[216:217]
	v_lshlrev_b64 v[116:117], 12, v[218:219]
	v_addc_co_u32_e32 v113, vcc, 0, v113, vcc
	v_lshl_add_u64 v[144:145], v[220:221], 0, v[116:117]
	global_load_dwordx4 v[224:227], v[144:145], off offset:16
	global_load_dwordx4 v[124:127], v[114:115], off offset:16
	global_load_dwordx4 v[116:119], v[114:115], off offset:512
	global_load_dwordx4 v[240:243], v[144:145], off offset:512
	global_load_dwordx4 v[128:131], v[112:113], off
	global_load_dwordx4 v[244:247], v[144:145], off
	global_load_dwordx4 v[248:251], v[144:145], off offset:528
	s_nop 0
	global_load_dwordx4 v[112:115], v[114:115], off offset:528
	v_or_b32_e32 v210, 16, v218
	v_ashrrev_i32_e32 v211, 31, v210
	v_lshlrev_b64 v[144:145], 12, v[210:211]
	v_or_b32_e32 v214, 32, v218
	v_lshl_add_u64 v[144:145], v[220:221], 0, v[144:145]
	v_ashrrev_i32_e32 v215, 31, v214
	global_load_dwordx4 v[184:187], v[144:145], off offset:16
	global_load_dwordx4 v[188:191], v[144:145], off
	global_load_dwordx4 v[172:175], v[144:145], off offset:528
	global_load_dwordx4 v[176:179], v[144:145], off offset:512
	v_lshlrev_b64 v[144:145], 12, v[214:215]
	v_or_b32_e32 v222, 48, v218
	v_lshl_add_u64 v[144:145], v[220:221], 0, v[144:145]
	v_ashrrev_i32_e32 v223, 31, v222
	global_load_dwordx4 v[168:171], v[144:145], off offset:16
	global_load_dwordx4 v[180:183], v[144:145], off
	global_load_dwordx4 v[160:163], v[144:145], off offset:528
	global_load_dwordx4 v[164:167], v[144:145], off offset:512
	v_lshlrev_b64 v[144:145], 12, v[222:223]
	v_lshl_add_u64 v[148:149], v[220:221], 0, v[144:145]
	global_load_dwordx4 v[152:155], v[148:149], off offset:16
	global_load_dwordx4 v[156:159], v[148:149], off
	global_load_dwordx4 v[144:147], v[148:149], off offset:528
	s_nop 0
	global_load_dwordx4 v[148:151], v[148:149], off offset:512
	v_and_b32_e32 v212, 64, v236
	v_xor_b32_e32 v238, 16, v236
	v_add_u32_e32 v252, 64, v212
	v_cmp_lt_i32_e32 vcc, v238, v252
	v_xor_b32_e32 v239, 32, v236
	v_lshlrev_b64 v[212:213], 11, v[218:219]
	v_cndmask_b32_e32 v238, v236, v238, vcc
	v_lshlrev_b32_e32 v238, 2, v238
	v_cmp_lt_i32_e32 vcc, v239, v252
	v_lshl_add_u64 v[252:253], s[6:7], 0, v[212:213]
	v_lshl_add_u64 v[252:253], v[208:209], 1, v[252:253]
	v_cndmask_b32_e32 v239, v236, v239, vcc
	v_lshlrev_b32_e32 v239, 2, v239
	s_waitcnt vmcnt(0)
	v_pk_fma_f32 v[138:139], v[138:139], v[126:127], v[226:227]
	v_pk_fma_f32 v[136:137], v[136:137], v[124:125], v[224:225]
	v_pk_fma_f32 v[226:227], v[8:9], v[116:117], v[240:241]
	v_pk_fma_f32 v[224:225], v[10:11], v[118:119], v[242:243]
	v_pk_fma_f32 v[140:141], v[140:141], v[128:129], v[244:245]
	v_pk_fma_f32 v[10:11], v[142:143], v[130:131], v[246:247]
	v_pk_fma_f32 v[142:143], v[6:7], v[114:115], v[250:251]
	v_pk_fma_f32 v[6:7], v[4:5], v[112:113], v[248:249]
	v_mul_f32_e32 v4, v227, v227
	v_mul_f32_e32 v5, v141, v141
	v_fmac_f32_e32 v4, v226, v226
	v_fmac_f32_e32 v5, v140, v140
	v_fmac_f32_e32 v4, v224, v224
	v_fmac_f32_e32 v5, v10, v10
	v_fmac_f32_e32 v4, v225, v225
	v_fmac_f32_e32 v5, v11, v11
	v_fmac_f32_e32 v4, v6, v6
	v_fmac_f32_e32 v5, v136, v136
	v_fmac_f32_e32 v4, v7, v7
	v_fmac_f32_e32 v5, v137, v137
	v_fmac_f32_e32 v4, v142, v142
	v_fmac_f32_e32 v5, v138, v138
	v_fmac_f32_e32 v4, v143, v143
	v_fmac_f32_e32 v5, v139, v139
	v_add_f32_e32 v5, v5, v4
	v_cvt_pk_bf16_f32 v8, v140, v141
	ds_bpermute_b32 v140, v238, v5
	v_cvt_pk_bf16_f32 v9, v10, v11
	v_cvt_pk_bf16_f32 v10, v136, v137
	v_cvt_pk_bf16_f32 v11, v138, v139
	global_store_dwordx4 v[252:253], v[8:11], off
	s_waitcnt lgkmcnt(0)
	v_add_f32_e32 v136, v5, v140
	ds_bpermute_b32 v137, v239, v136
	v_cvt_pk_bf16_f32 v4, v226, v227
	v_cvt_pk_bf16_f32 v5, v224, v225
	v_cvt_pk_bf16_f32 v6, v6, v7
	v_cvt_pk_bf16_f32 v7, v142, v143
	global_store_dwordx4 v[252:253], v[4:7], off offset:256
	s_and_saveexec_b64 s[50:51], s[0:1]
	s_cbranch_execz .LBB0_1484
	s_waitcnt lgkmcnt(0)
	v_add_f32_e32 v136, v136, v137
	ds_write_b32 v231, v136
.LBB0_1484:
	s_or_b64 exec, exec, s[50:51]
	v_pk_fma_f32 v[132:133], v[132:133], v[128:129], v[188:189]
	v_pk_fma_f32 v[120:121], v[120:121], v[116:117], v[176:177]
	v_mul_f32_e32 v140, v133, v133
	v_pk_fma_f32 v[138:139], v[0:1], v[124:125], v[184:185]
	v_cvt_pk_bf16_f32 v0, v132, v133
	v_fmac_f32_e32 v140, v132, v132
	v_pk_fma_f32 v[132:133], v[14:15], v[114:115], v[174:175]
	v_pk_fma_f32 v[14:15], v[12:13], v[112:113], v[172:173]
	v_mul_f32_e32 v12, v121, v121
	v_pk_fma_f32 v[134:135], v[134:135], v[130:131], v[190:191]
	v_pk_fma_f32 v[122:123], v[122:123], v[118:119], v[178:179]
	v_fmac_f32_e32 v12, v120, v120
	v_fmac_f32_e32 v140, v134, v134
	v_fmac_f32_e32 v12, v122, v122
	v_fmac_f32_e32 v140, v135, v135
	v_fmac_f32_e32 v12, v123, v123
	v_fmac_f32_e32 v140, v138, v138
	v_fmac_f32_e32 v12, v14, v14
	s_waitcnt lgkmcnt(0)
	v_pk_fma_f32 v[136:137], v[2:3], v[126:127], v[186:187]
	v_fmac_f32_e32 v140, v139, v139
	v_fmac_f32_e32 v12, v15, v15
	v_fmac_f32_e32 v140, v136, v136
	v_fmac_f32_e32 v12, v132, v132
	v_fmac_f32_e32 v140, v137, v137
	v_fmac_f32_e32 v12, v133, v133
	v_cvt_pk_bf16_f32 v1, v134, v135
	v_cvt_pk_bf16_f32 v2, v138, v139
	v_cvt_pk_bf16_f32 v3, v136, v137
	v_add_f32_e32 v136, v140, v12
	ds_bpermute_b32 v137, v238, v136
	v_lshlrev_b64 v[210:211], 11, v[210:211]
	v_lshl_add_u64 v[12:13], s[6:7], 0, v[210:211]
	v_lshl_add_u64 v[134:135], v[208:209], 1, v[12:13]
	global_store_dwordx4 v[134:135], v[0:3], off
	v_cvt_pk_bf16_f32 v12, v120, v121
	s_waitcnt lgkmcnt(0)
	v_add_f32_e32 v120, v136, v137
	ds_bpermute_b32 v121, v239, v120
	v_cvt_pk_bf16_f32 v13, v122, v123
	v_cvt_pk_bf16_f32 v14, v14, v15
	v_cvt_pk_bf16_f32 v15, v132, v133
	global_store_dwordx4 v[134:135], v[12:15], off offset:256
	s_and_saveexec_b64 s[50:51], s[0:1]
	s_cbranch_execz .LBB0_1486
	s_waitcnt lgkmcnt(0)
	v_add_f32_e32 v120, v120, v121
	ds_write_b32 v231, v120 offset:64
.LBB0_1486:
	s_or_b64 exec, exec, s[50:51]
	v_add_u32_e32 v226, 0x80, v218
	v_ashrrev_i32_e32 v227, 31, v226
	s_waitcnt lgkmcnt(0)
	v_lshlrev_b64 v[120:121], 12, v[226:227]
	v_add_u32_e32 v224, 0x90, v218
	v_lshl_add_u64 v[120:121], v[220:221], 0, v[120:121]
	v_ashrrev_i32_e32 v225, 31, v224
	global_load_dwordx4 v[184:187], v[120:121], off offset:16
	global_load_dwordx4 v[188:191], v[120:121], off
	global_load_dwordx4 v[172:175], v[120:121], off offset:528
	global_load_dwordx4 v[176:179], v[120:121], off offset:512
	v_lshlrev_b64 v[120:121], 12, v[224:225]
	v_lshl_add_u64 v[132:133], v[220:221], 0, v[120:121]
	global_load_dwordx4 v[136:139], v[132:133], off offset:16
	global_load_dwordx4 v[140:143], v[132:133], off
	global_load_dwordx4 v[120:123], v[132:133], off offset:528
	s_nop 0
	global_load_dwordx4 v[132:135], v[132:133], off offset:512
	v_pk_fma_f32 v[108:109], v[108:109], v[128:129], v[180:181]
	v_pk_fma_f32 v[104:105], v[104:105], v[116:117], v[164:165]
	v_mul_f32_e32 v180, v109, v109
	v_pk_fma_f32 v[168:169], v[16:17], v[124:125], v[168:169]
	v_cvt_pk_bf16_f32 v16, v108, v109
	v_fmac_f32_e32 v180, v108, v108
	v_pk_fma_f32 v[108:109], v[26:27], v[114:115], v[162:163]
	v_pk_fma_f32 v[26:27], v[24:25], v[112:113], v[160:161]
	v_mul_f32_e32 v24, v105, v105
	v_pk_fma_f32 v[110:111], v[110:111], v[130:131], v[182:183]
	v_pk_fma_f32 v[106:107], v[106:107], v[118:119], v[166:167]
	v_fmac_f32_e32 v24, v104, v104
	v_fmac_f32_e32 v180, v110, v110
	v_fmac_f32_e32 v24, v106, v106
	v_fmac_f32_e32 v180, v111, v111
	v_fmac_f32_e32 v24, v107, v107
	v_fmac_f32_e32 v180, v168, v168
	v_fmac_f32_e32 v24, v26, v26
	v_pk_fma_f32 v[170:171], v[18:19], v[126:127], v[170:171]
	v_fmac_f32_e32 v180, v169, v169
	v_fmac_f32_e32 v24, v27, v27
	v_fmac_f32_e32 v180, v170, v170
	v_fmac_f32_e32 v24, v108, v108
	v_fmac_f32_e32 v180, v171, v171
	v_fmac_f32_e32 v24, v109, v109
	v_add_f32_e32 v160, v180, v24
	ds_bpermute_b32 v161, v238, v160
	v_lshlrev_b64 v[214:215], 11, v[214:215]
	v_lshl_add_u64 v[24:25], s[6:7], 0, v[214:215]
	v_cvt_pk_bf16_f32 v17, v110, v111
	v_lshl_add_u64 v[110:111], v[208:209], 1, v[24:25]
	v_cvt_pk_bf16_f32 v18, v168, v169
	v_cvt_pk_bf16_f32 v19, v170, v171
	global_store_dwordx4 v[110:111], v[16:19], off
	v_cvt_pk_bf16_f32 v24, v104, v105
	s_waitcnt lgkmcnt(0)
	v_add_f32_e32 v104, v160, v161
	ds_bpermute_b32 v105, v239, v104
	v_cvt_pk_bf16_f32 v25, v106, v107
	v_cvt_pk_bf16_f32 v26, v26, v27
	v_cvt_pk_bf16_f32 v27, v108, v109
	global_store_dwordx4 v[110:111], v[24:27], off offset:256
	s_and_saveexec_b64 s[50:51], s[0:1]
	s_cbranch_execz .LBB0_1488
	s_waitcnt lgkmcnt(0)
	v_add_f32_e32 v104, v104, v105
	ds_write_b32 v231, v104 offset:128
.LBB0_1488:
	s_or_b64 exec, exec, s[50:51]
	v_pk_fma_f32 v[100:101], v[100:101], v[128:129], v[156:157]
	v_pk_fma_f32 v[96:97], v[96:97], v[116:117], v[148:149]
	v_mul_f32_e32 v108, v101, v101
	v_pk_fma_f32 v[106:107], v[20:21], v[124:125], v[152:153]
	v_cvt_pk_bf16_f32 v20, v100, v101
	v_fmac_f32_e32 v108, v100, v100
	v_pk_fma_f32 v[100:101], v[30:31], v[114:115], v[146:147]
	v_pk_fma_f32 v[30:31], v[28:29], v[112:113], v[144:145]
	v_mul_f32_e32 v28, v97, v97
	v_pk_fma_f32 v[102:103], v[102:103], v[130:131], v[158:159]
	v_pk_fma_f32 v[98:99], v[98:99], v[118:119], v[150:151]
	v_fmac_f32_e32 v28, v96, v96
	v_fmac_f32_e32 v108, v102, v102
	v_fmac_f32_e32 v28, v98, v98
	v_fmac_f32_e32 v108, v103, v103
	v_fmac_f32_e32 v28, v99, v99
	v_fmac_f32_e32 v108, v106, v106
	v_fmac_f32_e32 v28, v30, v30
	s_waitcnt lgkmcnt(0)
	v_pk_fma_f32 v[104:105], v[22:23], v[126:127], v[154:155]
	v_fmac_f32_e32 v108, v107, v107
	v_fmac_f32_e32 v28, v31, v31
	v_fmac_f32_e32 v108, v104, v104
	v_fmac_f32_e32 v28, v100, v100
	v_fmac_f32_e32 v108, v105, v105
	v_fmac_f32_e32 v28, v101, v101
	v_cvt_pk_bf16_f32 v21, v102, v103
	v_cvt_pk_bf16_f32 v22, v106, v107
	v_cvt_pk_bf16_f32 v23, v104, v105
	v_add_f32_e32 v104, v108, v28
	ds_bpermute_b32 v105, v238, v104
	v_lshlrev_b64 v[160:161], 11, v[222:223]
	v_lshl_add_u64 v[28:29], s[6:7], 0, v[160:161]
	v_lshl_add_u64 v[102:103], v[208:209], 1, v[28:29]
	global_store_dwordx4 v[102:103], v[20:23], off
	v_cvt_pk_bf16_f32 v28, v96, v97
	s_waitcnt lgkmcnt(0)
	v_add_f32_e32 v96, v104, v105
	ds_bpermute_b32 v97, v239, v96
	v_cvt_pk_bf16_f32 v29, v98, v99
	v_cvt_pk_bf16_f32 v30, v30, v31
	v_cvt_pk_bf16_f32 v31, v100, v101
	global_store_dwordx4 v[102:103], v[28:31], off offset:256
	s_and_saveexec_b64 s[50:51], s[0:1]
	s_cbranch_execz .LBB0_1490
	s_waitcnt lgkmcnt(0)
	v_add_f32_e32 v96, v96, v97
	ds_write_b32 v231, v96 offset:192
.LBB0_1490:
	s_or_b64 exec, exec, s[50:51]
	v_or_b32_e32 v96, 32, v226
	s_waitcnt lgkmcnt(0)
	v_ashrrev_i32_e32 v97, 31, v96
	v_lshlrev_b64 v[96:97], 12, v[96:97]
	v_add_u32_e32 v166, 0xb0, v218
	v_lshl_add_u64 v[96:97], v[220:221], 0, v[96:97]
	v_ashrrev_i32_e32 v167, 31, v166
	global_load_dwordx4 v[152:155], v[96:97], off offset:16
	global_load_dwordx4 v[156:159], v[96:97], off
	global_load_dwordx4 v[144:147], v[96:97], off offset:528
	global_load_dwordx4 v[148:151], v[96:97], off offset:512
	v_lshlrev_b64 v[96:97], 12, v[166:167]
	v_lshl_add_u64 v[100:101], v[220:221], 0, v[96:97]
	global_load_dwordx4 v[104:107], v[100:101], off offset:16
	global_load_dwordx4 v[108:111], v[100:101], off
	global_load_dwordx4 v[96:99], v[100:101], off offset:528
	s_nop 0
	global_load_dwordx4 v[100:103], v[100:101], off offset:512
	s_waitcnt vmcnt(18)
	v_pk_fma_f32 v[92:93], v[92:93], v[128:129], v[188:189]
	s_waitcnt vmcnt(16)
	v_pk_fma_f32 v[88:89], v[88:89], v[116:117], v[176:177]
	v_mul_f32_e32 v170, v93, v93
	v_pk_fma_f32 v[168:169], v[32:33], v[124:125], v[184:185]
	v_cvt_pk_bf16_f32 v32, v92, v93
	v_fmac_f32_e32 v170, v92, v92
	v_pk_fma_f32 v[92:93], v[50:51], v[114:115], v[174:175]
	v_pk_fma_f32 v[50:51], v[48:49], v[112:113], v[172:173]
	v_mul_f32_e32 v48, v89, v89
	v_pk_fma_f32 v[94:95], v[94:95], v[130:131], v[190:191]
	v_pk_fma_f32 v[90:91], v[90:91], v[118:119], v[178:179]
	v_fmac_f32_e32 v48, v88, v88
	v_fmac_f32_e32 v170, v94, v94
	v_fmac_f32_e32 v48, v90, v90
	v_fmac_f32_e32 v170, v95, v95
	v_fmac_f32_e32 v48, v91, v91
	v_fmac_f32_e32 v170, v168, v168
	v_fmac_f32_e32 v48, v50, v50
	v_pk_fma_f32 v[164:165], v[34:35], v[126:127], v[186:187]
	v_fmac_f32_e32 v170, v169, v169
	v_fmac_f32_e32 v48, v51, v51
	v_fmac_f32_e32 v170, v164, v164
	v_fmac_f32_e32 v48, v92, v92
	v_fmac_f32_e32 v170, v165, v165
	v_fmac_f32_e32 v48, v93, v93
	v_cvt_pk_bf16_f32 v33, v94, v95
	v_cvt_pk_bf16_f32 v34, v168, v169
	v_cvt_pk_bf16_f32 v35, v164, v165
	v_add_f32_e32 v164, v170, v48
	ds_bpermute_b32 v165, v238, v164
	v_lshlrev_b64 v[162:163], 11, v[226:227]
	v_lshl_add_u64 v[48:49], s[6:7], 0, v[162:163]
	v_lshl_add_u64 v[94:95], v[208:209], 1, v[48:49]
	global_store_dwordx4 v[94:95], v[32:35], off
	v_cvt_pk_bf16_f32 v48, v88, v89
	s_waitcnt lgkmcnt(0)
	v_add_f32_e32 v88, v164, v165
	ds_bpermute_b32 v89, v239, v88
	v_cvt_pk_bf16_f32 v49, v90, v91
	v_cvt_pk_bf16_f32 v50, v50, v51
	v_cvt_pk_bf16_f32 v51, v92, v93
	global_store_dwordx4 v[94:95], v[48:51], off offset:256
	s_and_saveexec_b64 s[50:51], s[0:1]
	s_cbranch_execz .LBB0_1492
	s_waitcnt lgkmcnt(0)
	v_add_f32_e32 v88, v88, v89
	ds_write_b32 v231, v88 offset:256
.LBB0_1492:
	s_or_b64 exec, exec, s[50:51]
	s_waitcnt vmcnt(16)
	v_pk_fma_f32 v[84:85], v[84:85], v[128:129], v[140:141]
	s_waitcnt vmcnt(14)
	v_pk_fma_f32 v[80:81], v[80:81], v[116:117], v[132:133]
	v_mul_f32_e32 v92, v85, v85
	v_pk_fma_f32 v[90:91], v[44:45], v[124:125], v[136:137]
	v_cvt_pk_bf16_f32 v44, v84, v85
	v_fmac_f32_e32 v92, v84, v84
	v_pk_fma_f32 v[84:85], v[54:55], v[114:115], v[122:123]
	v_pk_fma_f32 v[54:55], v[52:53], v[112:113], v[120:121]
	v_mul_f32_e32 v52, v81, v81
	v_pk_fma_f32 v[86:87], v[86:87], v[130:131], v[142:143]
	v_pk_fma_f32 v[82:83], v[82:83], v[118:119], v[134:135]
	v_fmac_f32_e32 v52, v80, v80
	v_fmac_f32_e32 v92, v86, v86
	v_fmac_f32_e32 v52, v82, v82
	v_fmac_f32_e32 v92, v87, v87
	v_fmac_f32_e32 v52, v83, v83
	v_fmac_f32_e32 v92, v90, v90
	v_fmac_f32_e32 v52, v54, v54
	s_waitcnt lgkmcnt(0)
	v_pk_fma_f32 v[88:89], v[46:47], v[126:127], v[138:139]
	v_fmac_f32_e32 v92, v91, v91
	v_fmac_f32_e32 v52, v55, v55
	v_fmac_f32_e32 v92, v88, v88
	v_fmac_f32_e32 v52, v84, v84
	v_fmac_f32_e32 v92, v89, v89
	v_fmac_f32_e32 v52, v85, v85
	v_cvt_pk_bf16_f32 v45, v86, v87
	v_cvt_pk_bf16_f32 v46, v90, v91
	v_cvt_pk_bf16_f32 v47, v88, v89
	v_add_f32_e32 v88, v92, v52
	ds_bpermute_b32 v89, v238, v88
	v_lshlrev_b64 v[164:165], 11, v[224:225]
	v_lshl_add_u64 v[52:53], s[6:7], 0, v[164:165]
	v_lshl_add_u64 v[86:87], v[208:209], 1, v[52:53]
	global_store_dwordx4 v[86:87], v[44:47], off
	v_cvt_pk_bf16_f32 v52, v80, v81
	s_waitcnt lgkmcnt(0)
	v_add_f32_e32 v80, v88, v89
	ds_bpermute_b32 v81, v239, v80
	v_cvt_pk_bf16_f32 v53, v82, v83
	v_cvt_pk_bf16_f32 v54, v54, v55
	v_cvt_pk_bf16_f32 v55, v84, v85
	global_store_dwordx4 v[86:87], v[52:55], off offset:256
	s_and_saveexec_b64 s[50:51], s[0:1]
	s_cbranch_execz .LBB0_1494
	s_waitcnt lgkmcnt(0)
	v_add_f32_e32 v80, v80, v81
	ds_write_b32 v231, v80 offset:320
.LBB0_1494:
	s_or_b64 exec, exec, s[50:51]
	s_waitcnt vmcnt(10)
	v_pk_fma_f32 v[76:77], v[76:77], v[128:129], v[156:157]
	s_waitcnt vmcnt(8)
	v_pk_fma_f32 v[72:73], v[72:73], v[116:117], v[148:149]
	v_mul_f32_e32 v84, v77, v77
	v_pk_fma_f32 v[82:83], v[56:57], v[124:125], v[152:153]
	v_cvt_pk_bf16_f32 v56, v76, v77
	v_fmac_f32_e32 v84, v76, v76
	v_pk_fma_f32 v[76:77], v[70:71], v[114:115], v[146:147]
	v_pk_fma_f32 v[70:71], v[68:69], v[112:113], v[144:145]
	v_mul_f32_e32 v68, v73, v73
	v_pk_fma_f32 v[78:79], v[78:79], v[130:131], v[158:159]
	v_pk_fma_f32 v[74:75], v[74:75], v[118:119], v[150:151]
	v_fmac_f32_e32 v68, v72, v72
	v_fmac_f32_e32 v84, v78, v78
	v_fmac_f32_e32 v68, v74, v74
	v_fmac_f32_e32 v84, v79, v79
	v_fmac_f32_e32 v68, v75, v75
	s_waitcnt lgkmcnt(0)
	v_lshlrev_b64 v[80:81], 11, v[218:219]
	s_mov_b64 s[50:51], 0x50000
	v_fmac_f32_e32 v84, v82, v82
	v_fmac_f32_e32 v68, v70, v70
	v_lshl_add_u64 v[120:121], v[80:81], 0, s[50:51]
	v_pk_fma_f32 v[80:81], v[58:59], v[126:127], v[154:155]
	v_fmac_f32_e32 v84, v83, v83
	v_fmac_f32_e32 v68, v71, v71
	v_fmac_f32_e32 v84, v80, v80
	v_fmac_f32_e32 v68, v76, v76
	v_fmac_f32_e32 v84, v81, v81
	v_fmac_f32_e32 v68, v77, v77
	v_cvt_pk_bf16_f32 v57, v78, v79
	v_cvt_pk_bf16_f32 v58, v82, v83
	v_cvt_pk_bf16_f32 v59, v80, v81
	v_add_f32_e32 v80, v84, v68
	ds_bpermute_b32 v81, v238, v80
	v_lshl_add_u64 v[68:69], s[6:7], 0, v[120:121]
	v_lshl_add_u64 v[78:79], v[208:209], 1, v[68:69]
	global_store_dwordx4 v[78:79], v[56:59], off
	v_cvt_pk_bf16_f32 v68, v72, v73
	s_waitcnt lgkmcnt(0)
	v_add_f32_e32 v72, v80, v81
	ds_bpermute_b32 v73, v239, v72
	v_cvt_pk_bf16_f32 v69, v74, v75
	v_cvt_pk_bf16_f32 v70, v70, v71
	v_cvt_pk_bf16_f32 v71, v76, v77
	global_store_dwordx4 v[78:79], v[68:71], off offset:256
	s_and_saveexec_b64 s[50:51], s[0:1]
	s_cbranch_execz .LBB0_1496
	s_waitcnt lgkmcnt(0)
	v_add_f32_e32 v72, v72, v73
	ds_write_b32 v231, v72 offset:384
.LBB0_1496:
	s_or_b64 exec, exec, s[50:51]
	s_waitcnt vmcnt(8)
	v_pk_fma_f32 v[64:65], v[64:65], v[128:129], v[108:109]
	s_waitcnt vmcnt(6)
	v_pk_fma_f32 v[40:41], v[40:41], v[116:117], v[100:101]
	v_mul_f32_e32 v76, v65, v65
	v_pk_fma_f32 v[74:75], v[60:61], v[124:125], v[104:105]
	v_cvt_pk_bf16_f32 v60, v64, v65
	v_fmac_f32_e32 v76, v64, v64
	v_pk_fma_f32 v[64:65], v[38:39], v[114:115], v[98:99]
	v_pk_fma_f32 v[38:39], v[36:37], v[112:113], v[96:97]
	v_mul_f32_e32 v36, v41, v41
	v_pk_fma_f32 v[66:67], v[66:67], v[130:131], v[110:111]
	v_pk_fma_f32 v[42:43], v[42:43], v[118:119], v[102:103]
	v_fmac_f32_e32 v36, v40, v40
	v_fmac_f32_e32 v76, v66, v66
	v_fmac_f32_e32 v36, v42, v42
	v_fmac_f32_e32 v76, v67, v67
	v_fmac_f32_e32 v36, v43, v43
	v_fmac_f32_e32 v76, v74, v74
	v_fmac_f32_e32 v36, v38, v38
	s_waitcnt lgkmcnt(0)
	v_pk_fma_f32 v[72:73], v[62:63], v[126:127], v[106:107]
	v_fmac_f32_e32 v76, v75, v75
	v_fmac_f32_e32 v36, v39, v39
	v_fmac_f32_e32 v76, v72, v72
	v_fmac_f32_e32 v36, v64, v64
	v_fmac_f32_e32 v76, v73, v73
	v_fmac_f32_e32 v36, v65, v65
	v_cvt_pk_bf16_f32 v61, v66, v67
	v_cvt_pk_bf16_f32 v62, v74, v75
	v_cvt_pk_bf16_f32 v63, v72, v73
	v_add_f32_e32 v72, v76, v36
	ds_bpermute_b32 v73, v238, v72
	v_lshlrev_b64 v[122:123], 11, v[166:167]
	v_lshl_add_u64 v[36:37], s[6:7], 0, v[122:123]
	v_lshl_add_u64 v[66:67], v[208:209], 1, v[36:37]
	global_store_dwordx4 v[66:67], v[60:63], off
	v_cvt_pk_bf16_f32 v36, v40, v41
	s_waitcnt lgkmcnt(0)
	v_add_f32_e32 v40, v72, v73
	ds_bpermute_b32 v41, v239, v40
	v_cvt_pk_bf16_f32 v37, v42, v43
	v_cvt_pk_bf16_f32 v38, v38, v39
	v_cvt_pk_bf16_f32 v39, v64, v65
	global_store_dwordx4 v[66:67], v[36:39], off offset:256
	s_and_saveexec_b64 s[50:51], s[0:1]
	s_cbranch_execz .LBB0_1498
	s_waitcnt lgkmcnt(0)
	v_add_f32_e32 v40, v40, v41
	ds_write_b32 v231, v40 offset:448
.LBB0_1498:
	s_or_b64 exec, exec, s[50:51]
	s_add_u32 s48, s91, s48
	s_addc_u32 s49, s92, s49
	s_add_u32 s50, s48, 0x1000
	s_addc_u32 s51, s49, 0
	s_waitcnt lgkmcnt(0)
	v_lshl_add_u64 v[40:41], s[12:13], 0, v[216:217]
	global_load_dwordx4 v[84:87], v[40:41], off offset:16
	global_load_dwordx4 v[80:83], v[40:41], off
	v_lshl_add_u64 v[40:41], s[50:51], 0, v[216:217]
	global_load_dwordx4 v[92:95], v[40:41], off offset:16
	global_load_dwordx4 v[88:91], v[40:41], off
	v_or_b32_e32 v40, 0x80, v208
	v_ashrrev_i32_e32 v41, 31, v40
	v_lshlrev_b64 v[40:41], 2, v[40:41]
	v_lshl_add_u64 v[64:65], s[48:49], 0, v[216:217]
	v_lshl_add_u64 v[42:43], s[12:13], 0, v[40:41]
	v_lshl_add_u64 v[40:41], s[50:51], 0, v[40:41]
	global_load_dwordx4 v[72:75], v[64:65], off offset:16
	global_load_dwordx4 v[76:79], v[64:65], off
	global_load_dwordx4 v[100:103], v[42:43], off offset:16
	global_load_dwordx4 v[96:99], v[42:43], off
	global_load_dwordx4 v[108:111], v[40:41], off offset:16
	global_load_dwordx4 v[104:107], v[40:41], off
	s_nop 0
	global_load_dwordx4 v[40:43], v[64:65], off offset:528
	s_nop 0
	global_load_dwordx4 v[64:67], v[64:65], off offset:512
	s_barrier
	v_mbcnt_lo_u32_b32 v112, -1, 0
	v_mbcnt_hi_u32_b32 v112, -1, v112
	s_nop 0
	v_cmp_gt_i32_e32 vcc, 32, v112
	s_and_saveexec_b64 s[48:49], vcc
	s_cbranch_execz .LBB0_1592
	v_ashrrev_i32_e32 v113, 4, v112
	v_add_u32_e32 v113, s95, v113
	v_lshlrev_b32_e32 v115, 5, v113
	v_and_b32_e32 v114, 15, v112
	v_lshlrev_b32_e32 v112, 4, v113
	v_and_b32_e32 v115, 0xffffff80, v115
	v_add_u32_e32 v115, s90, v115
	v_and_b32_e32 v112, 48, v112
	v_or3_b32 v112, v115, v112, v114
	v_lshlrev_b32_e32 v113, 6, v113
	v_lshlrev_b32_e32 v114, 2, v114
	v_add3_u32 v113, s96, v113, v114
	ds_read2st64_b32 v[114:115], v113 offset1:2
	ds_read2st64_b32 v[116:117], v113 offset0:4 offset1:6
	s_ashr_i32 s47, s46, 31
	s_lshl_b64 s[46:47], s[46:47], 8
	v_ashrrev_i32_e32 v113, 31, v112
	s_ashr_i32 s45, s44, 31
	v_lshl_add_u64 v[118:119], s[46:47], 0, v[112:113]
	s_waitcnt lgkmcnt(1)
	v_mov_b32_e32 v124, v114
	s_waitcnt lgkmcnt(0)
	v_mov_b32_e32 v125, v116
	v_mov_b32_e32 v116, v115
	s_lshl_b64 s[46:47], s[44:45], 17
	v_pk_add_f32 v[114:115], v[124:125], v[116:117]
	s_add_u32 s46, s14, s46
	v_add_f32_e32 v113, v114, v115
	s_addc_u32 s47, s15, s47
	v_add_f32_e32 v115, 0xda24260, v113
	v_lshl_add_u64 v[116:117], v[118:119], 2, s[46:47]
	global_store_dword v[116:117], v115, off sc1
	s_cmp_eq_u32 s44, 0
	v_mov_b32_e32 v116, v115
	s_cbranch_scc1 .LBB0_1522
	v_lshl_add_u64 v[124:125], v[118:119], 2, s[14:15]
	s_mov_b32 s17, 0x100000
	s_mov_b64 s[46:47], 0
	s_branch .LBB0_1510

.LBB0_1591:
	v_pk_add_f32 v[114:115], v[116:117], v[114:115]
	s_mov_b32 s17, 0x800000
	v_add_f32_e32 v113, v114, v115
	v_fmamk_f32 v113, v113, 0x3a800000, v237
	v_mul_f32_e32 v114, 0x4b800000, v113
	v_cmp_gt_f32_e32 vcc, s17, v113
	v_lshl_add_u32 v112, v112, 2, 0
	v_add_u32_e32 v112, 0x22000, v112
	v_cndmask_b32_e32 v113, v113, v114, vcc
	v_rsq_f32_e32 v113, v113
	s_nop 0
	v_mul_f32_e32 v114, 0x45800000, v113
	v_cndmask_b32_e32 v113, v113, v114, vcc
	ds_write_b32 v112, v113
.LBB0_1592:
	s_or_b64 exec, exec, s[48:49]
	s_waitcnt vmcnt(9)
	v_pk_add_f32 v[92:93], v[92:93], 1.0 op_sel_hi:[1,0]
	s_waitcnt lgkmcnt(0)
	v_pk_mul_f32 v[84:85], v[84:85], v[92:93]
	s_barrier
	ds_read_b32 v92, v232
	s_waitcnt vmcnt(8)
	v_pk_add_f32 v[90:91], v[90:91], 1.0 op_sel_hi:[1,0]
	v_pk_add_f32 v[88:89], v[88:89], 1.0 op_sel_hi:[1,0]
	v_pk_add_f32 v[94:95], v[94:95], 1.0 op_sel_hi:[1,0]
	v_pk_mul_f32 v[82:83], v[82:83], v[90:91]
	v_pk_mul_f32 v[80:81], v[80:81], v[88:89]
	v_lshlrev_b32_e32 v88, 16, v8
	v_and_b32_e32 v89, 0xffff0000, v8
	v_lshlrev_b32_e32 v8, 16, v9
	v_and_b32_e32 v9, 0xffff0000, v9
	v_lshlrev_b32_e32 v90, 16, v10
	v_and_b32_e32 v91, 0xffff0000, v10
	v_lshlrev_b32_e32 v10, 16, v11
	v_and_b32_e32 v11, 0xffff0000, v11
	v_pk_mul_f32 v[86:87], v[86:87], v[94:95]
	s_waitcnt lgkmcnt(0)
	v_pk_mul_f32 v[88:89], v[92:93], v[88:89] op_sel_hi:[0,1]
	v_pk_mul_f32 v[8:9], v[92:93], v[8:9] op_sel_hi:[0,1]
	v_pk_mul_f32 v[90:91], v[92:93], v[90:91] op_sel_hi:[0,1]
	v_pk_mul_f32 v[10:11], v[92:93], v[10:11] op_sel_hi:[0,1]
	s_waitcnt vmcnt(6)
	v_pk_fma_f32 v[8:9], v[82:83], v[8:9], v[78:79]
	v_pk_fma_f32 v[88:89], v[80:81], v[88:89], v[76:77]
	v_pk_fma_f32 v[10:11], v[86:87], v[10:11], v[74:75]
	v_pk_fma_f32 v[90:91], v[84:85], v[90:91], v[72:73]
	v_cvt_pk_bf16_f32 v88, v88, v89
	v_cvt_pk_bf16_f32 v89, v8, v9
	v_lshlrev_b64 v[8:9], 1, v[208:209]
	v_cvt_pk_bf16_f32 v90, v90, v91
	v_cvt_pk_bf16_f32 v91, v10, v11
	v_lshl_add_u64 v[10:11], s[10:11], 0, v[212:213]
	v_lshl_add_u64 v[10:11], v[10:11], 0, v[8:9]
	s_waitcnt vmcnt(2)
	v_pk_add_f32 v[106:107], v[106:107], 1.0 op_sel_hi:[1,0]
	v_pk_add_f32 v[104:105], v[104:105], 1.0 op_sel_hi:[1,0]
	global_store_dwordx4 v[10:11], v[88:91], off
	v_pk_add_f32 v[110:111], v[110:111], 1.0 op_sel_hi:[1,0]
	v_pk_add_f32 v[108:109], v[108:109], 1.0 op_sel_hi:[1,0]
	v_lshlrev_b32_e32 v88, 16, v4
	v_and_b32_e32 v89, 0xffff0000, v4
	v_lshlrev_b32_e32 v4, 16, v5
	v_and_b32_e32 v5, 0xffff0000, v5
	v_pk_mul_f32 v[98:99], v[98:99], v[106:107]
	v_pk_mul_f32 v[96:97], v[96:97], v[104:105]
	v_lshlrev_b32_e32 v90, 16, v6
	v_and_b32_e32 v91, 0xffff0000, v6
	v_lshlrev_b32_e32 v6, 16, v7
	v_and_b32_e32 v7, 0xffff0000, v7
	v_pk_mul_f32 v[88:89], v[92:93], v[88:89] op_sel_hi:[0,1]
	v_pk_mul_f32 v[4:5], v[92:93], v[4:5] op_sel_hi:[0,1]
	v_pk_mul_f32 v[100:101], v[100:101], v[108:109]
	v_pk_mul_f32 v[102:103], v[102:103], v[110:111]
	s_waitcnt vmcnt(1)
	v_pk_fma_f32 v[94:95], v[98:99], v[4:5], v[66:67]
	v_pk_fma_f32 v[4:5], v[96:97], v[88:89], v[64:65]
	v_pk_mul_f32 v[88:89], v[92:93], v[90:91] op_sel_hi:[0,1]
	v_pk_mul_f32 v[6:7], v[92:93], v[6:7] op_sel_hi:[0,1]
	v_pk_fma_f32 v[90:91], v[102:103], v[6:7], v[42:43]
	v_pk_fma_f32 v[6:7], v[100:101], v[88:89], v[40:41]
	v_cvt_pk_bf16_f32 v4, v4, v5
	v_cvt_pk_bf16_f32 v5, v94, v95
	s_andn2_b64 vcc, exec, s[4:5]
	v_cvt_pk_bf16_f32 v6, v6, v7
	v_cvt_pk_bf16_f32 v7, v90, v91
	global_store_dwordx4 v[10:11], v[4:7], off offset:256
	ds_read_b32 v4, v232 offset:64
	v_lshlrev_b32_e32 v10, 16, v2
	v_lshlrev_b32_e32 v6, 16, v0
	v_and_b32_e32 v7, 0xffff0000, v0
	v_lshlrev_b32_e32 v0, 16, v1
	v_and_b32_e32 v1, 0xffff0000, v1
	v_and_b32_e32 v11, 0xffff0000, v2
	v_lshlrev_b32_e32 v2, 16, v3
	v_and_b32_e32 v3, 0xffff0000, v3
	s_waitcnt lgkmcnt(0)
	v_pk_mul_f32 v[6:7], v[4:5], v[6:7] op_sel_hi:[0,1]
	v_pk_mul_f32 v[0:1], v[4:5], v[0:1] op_sel_hi:[0,1]
	v_pk_fma_f32 v[88:89], v[82:83], v[0:1], v[78:79]
	v_pk_fma_f32 v[0:1], v[80:81], v[6:7], v[76:77]
	v_pk_mul_f32 v[6:7], v[4:5], v[10:11] op_sel_hi:[0,1]
	v_pk_mul_f32 v[2:3], v[4:5], v[2:3] op_sel_hi:[0,1]
	v_pk_fma_f32 v[10:11], v[86:87], v[2:3], v[74:75]
	v_pk_fma_f32 v[2:3], v[84:85], v[6:7], v[72:73]
	v_lshl_add_u64 v[6:7], s[10:11], 0, v[210:211]
	v_cvt_pk_bf16_f32 v0, v0, v1
	v_cvt_pk_bf16_f32 v1, v88, v89
	v_cvt_pk_bf16_f32 v2, v2, v3
	v_cvt_pk_bf16_f32 v3, v10, v11
	v_lshl_add_u64 v[6:7], v[6:7], 0, v[8:9]
	global_store_dwordx4 v[6:7], v[0:3], off
	v_lshlrev_b32_e32 v10, 16, v14
	v_and_b32_e32 v11, 0xffff0000, v14
	v_lshlrev_b32_e32 v0, 16, v12
	v_and_b32_e32 v1, 0xffff0000, v12
	v_lshlrev_b32_e32 v2, 16, v13
	v_and_b32_e32 v3, 0xffff0000, v13
	v_lshlrev_b32_e32 v12, 16, v15
	v_and_b32_e32 v13, 0xffff0000, v15
	v_pk_mul_f32 v[0:1], v[4:5], v[0:1] op_sel_hi:[0,1]
	v_pk_mul_f32 v[2:3], v[4:5], v[2:3] op_sel_hi:[0,1]
	v_pk_mul_f32 v[10:11], v[4:5], v[10:11] op_sel_hi:[0,1]
	v_pk_mul_f32 v[4:5], v[4:5], v[12:13] op_sel_hi:[0,1]
	v_pk_fma_f32 v[2:3], v[98:99], v[2:3], v[66:67]
	v_pk_fma_f32 v[0:1], v[96:97], v[0:1], v[64:65]
	v_pk_fma_f32 v[4:5], v[102:103], v[4:5], v[42:43]
	v_pk_fma_f32 v[10:11], v[100:101], v[10:11], v[40:41]
	v_cvt_pk_bf16_f32 v0, v0, v1
	v_cvt_pk_bf16_f32 v1, v2, v3
	v_lshlrev_b32_e32 v12, 16, v27
	v_cvt_pk_bf16_f32 v2, v10, v11
	v_cvt_pk_bf16_f32 v3, v4, v5
	ds_read_b32 v4, v232 offset:128
	global_store_dwordx4 v[6:7], v[0:3], off offset:256
	v_lshlrev_b32_e32 v6, 16, v18
	v_and_b32_e32 v7, 0xffff0000, v18
	v_lshlrev_b32_e32 v0, 16, v16
	v_and_b32_e32 v1, 0xffff0000, v16
	v_lshlrev_b32_e32 v2, 16, v17
	v_and_b32_e32 v3, 0xffff0000, v17
	s_waitcnt lgkmcnt(0)
	v_pk_mul_f32 v[0:1], v[4:5], v[0:1] op_sel_hi:[0,1]
	v_pk_mul_f32 v[2:3], v[4:5], v[2:3] op_sel_hi:[0,1]
	v_pk_mul_f32 v[6:7], v[4:5], v[6:7] op_sel_hi:[0,1]
	v_lshlrev_b32_e32 v10, 16, v19
	v_and_b32_e32 v11, 0xffff0000, v19
	v_pk_fma_f32 v[2:3], v[82:83], v[2:3], v[78:79]
	v_pk_fma_f32 v[0:1], v[80:81], v[0:1], v[76:77]
	v_pk_fma_f32 v[6:7], v[84:85], v[6:7], v[72:73]
	v_pk_mul_f32 v[10:11], v[4:5], v[10:11] op_sel_hi:[0,1]
	v_cvt_pk_bf16_f32 v0, v0, v1
	v_cvt_pk_bf16_f32 v1, v2, v3
	v_cvt_pk_bf16_f32 v2, v6, v7
	v_lshl_add_u64 v[6:7], s[10:11], 0, v[214:215]
	v_pk_fma_f32 v[10:11], v[86:87], v[10:11], v[74:75]
	v_lshl_add_u64 v[6:7], v[6:7], 0, v[8:9]
	v_cvt_pk_bf16_f32 v3, v10, v11
	global_store_dwordx4 v[6:7], v[0:3], off
	v_lshlrev_b32_e32 v10, 16, v26
	v_and_b32_e32 v11, 0xffff0000, v26
	v_lshlrev_b32_e32 v0, 16, v24
	v_and_b32_e32 v1, 0xffff0000, v24
	v_lshlrev_b32_e32 v2, 16, v25
	v_and_b32_e32 v3, 0xffff0000, v25
	v_and_b32_e32 v13, 0xffff0000, v27
	v_pk_mul_f32 v[0:1], v[4:5], v[0:1] op_sel_hi:[0,1]
	v_pk_mul_f32 v[2:3], v[4:5], v[2:3] op_sel_hi:[0,1]
	v_pk_mul_f32 v[10:11], v[4:5], v[10:11] op_sel_hi:[0,1]
	v_pk_mul_f32 v[4:5], v[4:5], v[12:13] op_sel_hi:[0,1]
	v_pk_fma_f32 v[2:3], v[98:99], v[2:3], v[66:67]
	v_pk_fma_f32 v[0:1], v[96:97], v[0:1], v[64:65]
	v_pk_fma_f32 v[4:5], v[102:103], v[4:5], v[42:43]
	v_pk_fma_f32 v[10:11], v[100:101], v[10:11], v[40:41]
	v_cvt_pk_bf16_f32 v0, v0, v1
	v_cvt_pk_bf16_f32 v1, v2, v3
	v_lshlrev_b32_e32 v12, 16, v31
	v_cvt_pk_bf16_f32 v2, v10, v11
	v_cvt_pk_bf16_f32 v3, v4, v5
	ds_read_b32 v4, v232 offset:192
	global_store_dwordx4 v[6:7], v[0:3], off offset:256
	v_lshlrev_b32_e32 v6, 16, v22
	v_and_b32_e32 v7, 0xffff0000, v22
	v_lshlrev_b32_e32 v0, 16, v20
	v_and_b32_e32 v1, 0xffff0000, v20
	v_lshlrev_b32_e32 v2, 16, v21
	v_and_b32_e32 v3, 0xffff0000, v21
	s_waitcnt lgkmcnt(0)
	v_pk_mul_f32 v[0:1], v[4:5], v[0:1] op_sel_hi:[0,1]
	v_pk_mul_f32 v[2:3], v[4:5], v[2:3] op_sel_hi:[0,1]
	v_pk_mul_f32 v[6:7], v[4:5], v[6:7] op_sel_hi:[0,1]
	v_lshlrev_b32_e32 v10, 16, v23
	v_and_b32_e32 v11, 0xffff0000, v23
	v_pk_fma_f32 v[2:3], v[82:83], v[2:3], v[78:79]
	v_pk_fma_f32 v[0:1], v[80:81], v[0:1], v[76:77]
	v_pk_fma_f32 v[6:7], v[84:85], v[6:7], v[72:73]
	v_pk_mul_f32 v[10:11], v[4:5], v[10:11] op_sel_hi:[0,1]
	v_cvt_pk_bf16_f32 v0, v0, v1
	v_cvt_pk_bf16_f32 v1, v2, v3
	v_cvt_pk_bf16_f32 v2, v6, v7
	v_lshl_add_u64 v[6:7], s[10:11], 0, v[160:161]
	v_pk_fma_f32 v[10:11], v[86:87], v[10:11], v[74:75]
	v_lshl_add_u64 v[6:7], v[6:7], 0, v[8:9]
	v_cvt_pk_bf16_f32 v3, v10, v11
	global_store_dwordx4 v[6:7], v[0:3], off
	v_lshlrev_b32_e32 v10, 16, v30
	v_and_b32_e32 v11, 0xffff0000, v30
	v_lshlrev_b32_e32 v0, 16, v28
	v_and_b32_e32 v1, 0xffff0000, v28
	v_lshlrev_b32_e32 v2, 16, v29
	v_and_b32_e32 v3, 0xffff0000, v29
	v_and_b32_e32 v13, 0xffff0000, v31
	v_pk_mul_f32 v[0:1], v[4:5], v[0:1] op_sel_hi:[0,1]
	v_pk_mul_f32 v[2:3], v[4:5], v[2:3] op_sel_hi:[0,1]
	v_pk_mul_f32 v[10:11], v[4:5], v[10:11] op_sel_hi:[0,1]
	v_pk_mul_f32 v[4:5], v[4:5], v[12:13] op_sel_hi:[0,1]
	v_pk_fma_f32 v[2:3], v[98:99], v[2:3], v[66:67]
	v_pk_fma_f32 v[0:1], v[96:97], v[0:1], v[64:65]
	v_pk_fma_f32 v[4:5], v[102:103], v[4:5], v[42:43]
	v_pk_fma_f32 v[10:11], v[100:101], v[10:11], v[40:41]
	v_cvt_pk_bf16_f32 v0, v0, v1
	v_cvt_pk_bf16_f32 v1, v2, v3
	v_lshlrev_b32_e32 v12, 16, v51
	v_cvt_pk_bf16_f32 v2, v10, v11
	v_cvt_pk_bf16_f32 v3, v4, v5
	ds_read_b32 v4, v232 offset:512
	global_store_dwordx4 v[6:7], v[0:3], off offset:256
	v_lshlrev_b32_e32 v6, 16, v34
	v_and_b32_e32 v7, 0xffff0000, v34
	v_lshlrev_b32_e32 v0, 16, v32
	v_and_b32_e32 v1, 0xffff0000, v32
	v_lshlrev_b32_e32 v2, 16, v33
	v_and_b32_e32 v3, 0xffff0000, v33
	s_waitcnt lgkmcnt(0)
	v_pk_mul_f32 v[0:1], v[4:5], v[0:1] op_sel_hi:[0,1]
	v_pk_mul_f32 v[2:3], v[4:5], v[2:3] op_sel_hi:[0,1]
	v_pk_mul_f32 v[6:7], v[4:5], v[6:7] op_sel_hi:[0,1]
	v_lshlrev_b32_e32 v10, 16, v35
	v_and_b32_e32 v11, 0xffff0000, v35
	v_pk_fma_f32 v[2:3], v[82:83], v[2:3], v[78:79]
	v_pk_fma_f32 v[0:1], v[80:81], v[0:1], v[76:77]
	v_pk_fma_f32 v[6:7], v[84:85], v[6:7], v[72:73]
	v_pk_mul_f32 v[10:11], v[4:5], v[10:11] op_sel_hi:[0,1]
	v_cvt_pk_bf16_f32 v0, v0, v1
	v_cvt_pk_bf16_f32 v1, v2, v3
	v_cvt_pk_bf16_f32 v2, v6, v7
	v_lshl_add_u64 v[6:7], s[10:11], 0, v[162:163]
	v_pk_fma_f32 v[10:11], v[86:87], v[10:11], v[74:75]
	v_lshl_add_u64 v[6:7], v[6:7], 0, v[8:9]
	v_cvt_pk_bf16_f32 v3, v10, v11
	global_store_dwordx4 v[6:7], v[0:3], off
	v_lshlrev_b32_e32 v10, 16, v50
	v_and_b32_e32 v11, 0xffff0000, v50
	v_lshlrev_b32_e32 v0, 16, v48
	v_and_b32_e32 v1, 0xffff0000, v48
	v_lshlrev_b32_e32 v2, 16, v49
	v_and_b32_e32 v3, 0xffff0000, v49
	v_and_b32_e32 v13, 0xffff0000, v51
	v_pk_mul_f32 v[0:1], v[4:5], v[0:1] op_sel_hi:[0,1]
	v_pk_mul_f32 v[2:3], v[4:5], v[2:3] op_sel_hi:[0,1]
	v_pk_mul_f32 v[10:11], v[4:5], v[10:11] op_sel_hi:[0,1]
	v_pk_mul_f32 v[4:5], v[4:5], v[12:13] op_sel_hi:[0,1]
	v_pk_fma_f32 v[2:3], v[98:99], v[2:3], v[66:67]
	v_pk_fma_f32 v[0:1], v[96:97], v[0:1], v[64:65]
	v_pk_fma_f32 v[4:5], v[102:103], v[4:5], v[42:43]
	v_pk_fma_f32 v[10:11], v[100:101], v[10:11], v[40:41]
	v_cvt_pk_bf16_f32 v0, v0, v1
	v_cvt_pk_bf16_f32 v1, v2, v3
	v_lshlrev_b32_e32 v12, 16, v55
	v_cvt_pk_bf16_f32 v2, v10, v11
	v_cvt_pk_bf16_f32 v3, v4, v5
	ds_read_b32 v4, v232 offset:576
	global_store_dwordx4 v[6:7], v[0:3], off offset:256
	v_lshlrev_b32_e32 v6, 16, v46
	v_and_b32_e32 v7, 0xffff0000, v46
	v_lshlrev_b32_e32 v0, 16, v44
	v_and_b32_e32 v1, 0xffff0000, v44
	v_lshlrev_b32_e32 v2, 16, v45
	v_and_b32_e32 v3, 0xffff0000, v45
	s_waitcnt lgkmcnt(0)
	v_pk_mul_f32 v[0:1], v[4:5], v[0:1] op_sel_hi:[0,1]
	v_pk_mul_f32 v[2:3], v[4:5], v[2:3] op_sel_hi:[0,1]
	v_pk_mul_f32 v[6:7], v[4:5], v[6:7] op_sel_hi:[0,1]
	v_lshlrev_b32_e32 v10, 16, v47
	v_and_b32_e32 v11, 0xffff0000, v47
	v_pk_fma_f32 v[2:3], v[82:83], v[2:3], v[78:79]
	v_pk_fma_f32 v[0:1], v[80:81], v[0:1], v[76:77]
	v_pk_fma_f32 v[6:7], v[84:85], v[6:7], v[72:73]
	v_pk_mul_f32 v[10:11], v[4:5], v[10:11] op_sel_hi:[0,1]
	v_cvt_pk_bf16_f32 v0, v0, v1
	v_cvt_pk_bf16_f32 v1, v2, v3
	v_cvt_pk_bf16_f32 v2, v6, v7
	v_lshl_add_u64 v[6:7], s[10:11], 0, v[164:165]
	v_pk_fma_f32 v[10:11], v[86:87], v[10:11], v[74:75]
	v_lshl_add_u64 v[6:7], v[6:7], 0, v[8:9]
	v_cvt_pk_bf16_f32 v3, v10, v11
	global_store_dwordx4 v[6:7], v[0:3], off
	v_lshlrev_b32_e32 v10, 16, v54
	v_and_b32_e32 v11, 0xffff0000, v54
	v_lshlrev_b32_e32 v0, 16, v52
	v_and_b32_e32 v1, 0xffff0000, v52
	v_lshlrev_b32_e32 v2, 16, v53
	v_and_b32_e32 v3, 0xffff0000, v53
	v_and_b32_e32 v13, 0xffff0000, v55
	v_pk_mul_f32 v[0:1], v[4:5], v[0:1] op_sel_hi:[0,1]
	v_pk_mul_f32 v[2:3], v[4:5], v[2:3] op_sel_hi:[0,1]
	v_pk_mul_f32 v[10:11], v[4:5], v[10:11] op_sel_hi:[0,1]
	v_pk_mul_f32 v[4:5], v[4:5], v[12:13] op_sel_hi:[0,1]
	v_pk_fma_f32 v[2:3], v[98:99], v[2:3], v[66:67]
	v_pk_fma_f32 v[0:1], v[96:97], v[0:1], v[64:65]
	v_pk_fma_f32 v[4:5], v[102:103], v[4:5], v[42:43]
	v_pk_fma_f32 v[10:11], v[100:101], v[10:11], v[40:41]
	v_cvt_pk_bf16_f32 v0, v0, v1
	v_cvt_pk_bf16_f32 v1, v2, v3
	v_lshlrev_b32_e32 v12, 16, v71
	v_cvt_pk_bf16_f32 v2, v10, v11
	v_cvt_pk_bf16_f32 v3, v4, v5
	ds_read_b32 v4, v232 offset:640
	global_store_dwordx4 v[6:7], v[0:3], off offset:256
	v_lshlrev_b32_e32 v6, 16, v58
	v_and_b32_e32 v7, 0xffff0000, v58
	v_lshlrev_b32_e32 v0, 16, v56
	v_and_b32_e32 v1, 0xffff0000, v56
	v_lshlrev_b32_e32 v2, 16, v57
	v_and_b32_e32 v3, 0xffff0000, v57
	s_waitcnt lgkmcnt(0)
	v_pk_mul_f32 v[0:1], v[4:5], v[0:1] op_sel_hi:[0,1]
	v_pk_mul_f32 v[2:3], v[4:5], v[2:3] op_sel_hi:[0,1]
	v_pk_mul_f32 v[6:7], v[4:5], v[6:7] op_sel_hi:[0,1]
	v_lshlrev_b32_e32 v10, 16, v59
	v_and_b32_e32 v11, 0xffff0000, v59
	v_pk_fma_f32 v[2:3], v[82:83], v[2:3], v[78:79]
	v_pk_fma_f32 v[0:1], v[80:81], v[0:1], v[76:77]
	v_pk_fma_f32 v[6:7], v[84:85], v[6:7], v[72:73]
	v_pk_mul_f32 v[10:11], v[4:5], v[10:11] op_sel_hi:[0,1]
	v_cvt_pk_bf16_f32 v0, v0, v1
	v_cvt_pk_bf16_f32 v1, v2, v3
	v_cvt_pk_bf16_f32 v2, v6, v7
	v_lshl_add_u64 v[6:7], s[10:11], 0, v[120:121]
	v_pk_fma_f32 v[10:11], v[86:87], v[10:11], v[74:75]
	v_lshl_add_u64 v[6:7], v[6:7], 0, v[8:9]
	v_cvt_pk_bf16_f32 v3, v10, v11
	global_store_dwordx4 v[6:7], v[0:3], off
	v_lshlrev_b32_e32 v10, 16, v70
	v_and_b32_e32 v11, 0xffff0000, v70
	v_lshlrev_b32_e32 v0, 16, v68
	v_and_b32_e32 v1, 0xffff0000, v68
	v_lshlrev_b32_e32 v2, 16, v69
	v_and_b32_e32 v3, 0xffff0000, v69
	v_and_b32_e32 v13, 0xffff0000, v71
	v_pk_mul_f32 v[0:1], v[4:5], v[0:1] op_sel_hi:[0,1]
	v_pk_mul_f32 v[2:3], v[4:5], v[2:3] op_sel_hi:[0,1]
	v_pk_mul_f32 v[10:11], v[4:5], v[10:11] op_sel_hi:[0,1]
	v_pk_mul_f32 v[4:5], v[4:5], v[12:13] op_sel_hi:[0,1]
	v_pk_fma_f32 v[2:3], v[98:99], v[2:3], v[66:67]
	v_pk_fma_f32 v[0:1], v[96:97], v[0:1], v[64:65]
	v_pk_fma_f32 v[4:5], v[102:103], v[4:5], v[42:43]
	v_pk_fma_f32 v[10:11], v[100:101], v[10:11], v[40:41]
	v_cvt_pk_bf16_f32 v0, v0, v1
	v_cvt_pk_bf16_f32 v1, v2, v3
	s_mov_b64 s[4:5], -1
	v_cvt_pk_bf16_f32 v2, v10, v11
	v_cvt_pk_bf16_f32 v3, v4, v5
	ds_read_b32 v4, v232 offset:704
	global_store_dwordx4 v[6:7], v[0:3], off offset:256
	v_lshlrev_b32_e32 v6, 16, v62
	v_and_b32_e32 v7, 0xffff0000, v62
	v_lshlrev_b32_e32 v0, 16, v60
	v_and_b32_e32 v1, 0xffff0000, v60
	v_lshlrev_b32_e32 v2, 16, v61
	v_and_b32_e32 v3, 0xffff0000, v61
	s_waitcnt lgkmcnt(0)
	v_pk_mul_f32 v[0:1], v[4:5], v[0:1] op_sel_hi:[0,1]
	v_pk_mul_f32 v[2:3], v[4:5], v[2:3] op_sel_hi:[0,1]
	v_pk_mul_f32 v[6:7], v[4:5], v[6:7] op_sel_hi:[0,1]
	v_lshlrev_b32_e32 v10, 16, v63
	v_and_b32_e32 v11, 0xffff0000, v63
	v_pk_fma_f32 v[2:3], v[82:83], v[2:3], v[78:79]
	v_pk_fma_f32 v[0:1], v[80:81], v[0:1], v[76:77]
	v_pk_fma_f32 v[6:7], v[84:85], v[6:7], v[72:73]
	v_pk_mul_f32 v[10:11], v[4:5], v[10:11] op_sel_hi:[0,1]
	v_cvt_pk_bf16_f32 v0, v0, v1
	v_cvt_pk_bf16_f32 v1, v2, v3
	v_cvt_pk_bf16_f32 v2, v6, v7
	v_lshl_add_u64 v[6:7], s[10:11], 0, v[122:123]
	v_pk_fma_f32 v[10:11], v[86:87], v[10:11], v[74:75]
	v_lshl_add_u64 v[6:7], v[6:7], 0, v[8:9]
	v_cvt_pk_bf16_f32 v3, v10, v11
	global_store_dwordx4 v[6:7], v[0:3], off
	v_lshlrev_b32_e32 v8, 16, v38
	v_and_b32_e32 v9, 0xffff0000, v38
	v_lshlrev_b32_e32 v0, 16, v36
	v_and_b32_e32 v1, 0xffff0000, v36
	v_lshlrev_b32_e32 v2, 16, v37
	v_and_b32_e32 v3, 0xffff0000, v37
	v_lshlrev_b32_e32 v10, 16, v39
	v_and_b32_e32 v11, 0xffff0000, v39
	v_pk_mul_f32 v[0:1], v[4:5], v[0:1] op_sel_hi:[0,1]
	v_pk_mul_f32 v[2:3], v[4:5], v[2:3] op_sel_hi:[0,1]
	v_pk_fma_f32 v[2:3], v[98:99], v[2:3], v[66:67]
	v_pk_fma_f32 v[0:1], v[96:97], v[0:1], v[64:65]
	v_pk_mul_f32 v[8:9], v[4:5], v[8:9] op_sel_hi:[0,1]
	v_pk_mul_f32 v[4:5], v[4:5], v[10:11] op_sel_hi:[0,1]
	v_pk_fma_f32 v[4:5], v[102:103], v[4:5], v[42:43]
	v_pk_fma_f32 v[8:9], v[100:101], v[8:9], v[40:41]
	v_cvt_pk_bf16_f32 v0, v0, v1
	v_cvt_pk_bf16_f32 v1, v2, v3
	s_nop 0
	v_cvt_pk_bf16_f32 v2, v8, v9
	v_cvt_pk_bf16_f32 v3, v4, v5
	global_store_dwordx4 v[6:7], v[0:3], off offset:256
	s_cbranch_vccnz .LBB0_1471
	s_andn2_b64 vcc, exec, s[8:9]
	s_cbranch_vccnz .LBB0_1470
	s_barrier
	s_branch .LBB0_1470

.LBB0_1653:
	v_add_u32_e32 v74, s6, v14
	v_ashrrev_i32_e32 v19, 12, v14
	v_pk_mul_f32 v[60:61], v[34:35], v[34:35]
	v_pk_mul_f32 v[62:63], v[30:31], v[30:31]
	v_cmp_gt_i32_e32 vcc, s3, v74
	v_mul_i32_i24_e32 v66, 0xc00, v19
	v_pk_mul_f32 v[48:49], v[24:25], v[24:25]
	v_pk_mul_f32 v[56:57], v[28:29], v[28:29]
	v_pk_mul_f32 v[50:51], v[22:23], v[22:23]
	v_pk_mul_f32 v[52:53], v[26:27], v[26:27]
	v_pk_mul_f32 v[54:55], v[36:37], v[36:37]
	v_pk_mul_f32 v[58:59], v[32:33], v[32:33]
	v_cndmask_b32_e32 v64, v14, v74, vcc
	v_mov_b32_e32 v68, v60
	v_mov_b32_e32 v69, v62
	v_mov_b32_e32 v62, v61
	v_ashrrev_i32_e32 v67, 31, v66
	v_mov_b32_e32 v60, v54
	v_mov_b32_e32 v61, v58
	v_mov_b32_e32 v58, v55
	v_mov_b32_e32 v54, v50
	v_mov_b32_e32 v55, v52
	v_mov_b32_e32 v52, v51
	v_mov_b32_e32 v50, v48
	v_mov_b32_e32 v51, v56
	v_mov_b32_e32 v56, v49
	v_ashrrev_i32_e32 v65, 31, v64
	v_pk_add_f32 v[48:49], v[68:69], v[62:63]
	v_lshl_add_u64 v[62:63], v[66:67], 2, s[4:5]
	v_pk_add_f32 v[52:53], v[54:55], v[52:53]
	v_lshlrev_b64 v[54:55], 11, v[64:65]
	v_lshl_add_u64 v[68:69], v[62:63], 0, s[8:9]
	v_lshl_add_u64 v[62:63], v[62:63], 0, v[0:1]
	global_load_dwordx4 v[44:47], v[4:5], off
	v_pk_add_f32 v[60:61], v[60:61], v[48:49]
	v_pk_add_f32 v[64:65], v[50:51], v[52:53]
	v_lshl_add_u64 v[66:67], v[2:3], 0, v[54:55]
	v_lshl_add_u64 v[70:71], v[68:69], 0, v[0:1]
	global_load_dwordx4 v[48:51], v[62:63], off
	global_load_dwordx4 v[52:55], v[70:71], off
	v_pk_add_f32 v[58:59], v[58:59], v[60:61]
	v_pk_add_f32 v[56:57], v[56:57], v[64:65]
	v_add_f32_e32 v14, v58, v59
	v_add_f32_e32 v14, v57, v14
	v_mov_b32_e32 v17, v1
	v_add_f32_e32 v14, v56, v14
	v_lshl_add_u64 v[58:59], v[68:69], 0, v[16:17]
	ds_bpermute_b32 v17, v38, v14
	global_load_dwordx2 v[60:61], v[66:67], off
	global_load_dwordx2 v[64:65], v[66:67], off offset:512
	global_load_dwordx2 v[70:71], v[66:67], off offset:1024
	global_load_dwordx2 v[72:73], v[66:67], off offset:1536
	v_mov_b32_e32 v19, v1
	v_mov_b32_e32 v21, v1
	s_waitcnt lgkmcnt(0)
	v_add_f32_e32 v14, v14, v17
	ds_bpermute_b32 v17, v39, v14
	s_waitcnt lgkmcnt(0)
	v_add_f32_e32 v14, v14, v17
	ds_bpermute_b32 v17, v40, v14
	s_waitcnt lgkmcnt(0)
	v_add_f32_e32 v14, v14, v17
	ds_bpermute_b32 v17, v41, v14
	s_waitcnt lgkmcnt(0)
	v_add_f32_e32 v14, v14, v17
	ds_bpermute_b32 v17, v42, v14
	s_waitcnt lgkmcnt(0)
	v_add_f32_e32 v14, v14, v17
	ds_bpermute_b32 v17, v43, v14
	s_waitcnt lgkmcnt(0)
	v_add_f32_e32 v14, v14, v17
	v_fmamk_f32 v14, v14, 0x3a800000, v15
	v_mul_f32_e32 v17, 0x4b800000, v14
	v_cmp_gt_f32_e32 vcc, s17, v14
	s_nop 1
	v_cndmask_b32_e32 v14, v14, v17, vcc
	v_rsq_f32_e32 v14, v14
	s_nop 0
	v_mul_f32_e32 v17, 0x45800000, v14
	v_cndmask_b32_e32 v56, v14, v17, vcc
	v_pk_mul_f32 v[34:35], v[34:35], v[56:57] op_sel_hi:[1,0]
	v_pk_mul_f32 v[36:37], v[36:37], v[56:57] op_sel_hi:[1,0]
	v_pk_mul_f32 v[30:31], v[30:31], v[56:57] op_sel_hi:[1,0]
	v_pk_mul_f32 v[32:33], v[32:33], v[56:57] op_sel_hi:[1,0]
	v_pk_mul_f32 v[26:27], v[26:27], v[56:57] op_sel_hi:[1,0]
	v_pk_mul_f32 v[28:29], v[28:29], v[56:57] op_sel_hi:[1,0]
	v_cmp_lt_i32_e32 vcc, s16, v74
	v_mov_b32_e32 v14, v74
	s_or_b64 s[10:11], vcc, s[10:11]
	s_waitcnt vmcnt(6)
	v_pk_mul_f32 v[34:35], v[44:45], v[34:35]
	v_pk_mul_f32 v[36:37], v[46:47], v[36:37]
	s_waitcnt vmcnt(4)
	v_pk_add_f32 v[44:45], v[52:53], 1.0 op_sel_hi:[1,0]
	v_pk_add_f32 v[46:47], v[54:55], 1.0 op_sel_hi:[1,0]
	v_pk_fma_f32 v[34:35], v[44:45], v[34:35], v[48:49]
	v_pk_fma_f32 v[36:37], v[46:47], v[36:37], v[50:51]
	v_cvt_pk_bf16_f32 v34, v34, v35
	v_cvt_pk_bf16_f32 v35, v36, v37
	global_store_dwordx2 v[6:7], v[34:35], off
	global_load_dwordx4 v[34:37], v[8:9], off
	s_nop 0
	global_load_dwordx4 v[44:47], v[58:59], off
	global_load_dwordx4 v[48:51], v[62:63], off offset:1024
	v_lshl_add_u64 v[52:53], v[68:69], 0, v[18:19]
	v_lshl_add_u64 v[58:59], v[68:69], 0, v[20:21]
	s_waitcnt vmcnt(2)
	v_pk_mul_f32 v[30:31], v[34:35], v[30:31]
	s_waitcnt vmcnt(1)
	v_pk_add_f32 v[34:35], v[44:45], 1.0 op_sel_hi:[1,0]
	v_pk_mul_f32 v[32:33], v[36:37], v[32:33]
	v_pk_add_f32 v[36:37], v[46:47], 1.0 op_sel_hi:[1,0]
	s_waitcnt vmcnt(0)
	v_pk_fma_f32 v[30:31], v[34:35], v[30:31], v[48:49]
	v_pk_fma_f32 v[32:33], v[36:37], v[32:33], v[50:51]
	v_cvt_pk_bf16_f32 v30, v30, v31
	v_cvt_pk_bf16_f32 v31, v32, v33
	global_store_dwordx2 v[6:7], v[30:31], off offset:512
	global_load_dwordx4 v[30:33], v[10:11], off
	s_nop 0
	global_load_dwordx4 v[34:37], v[52:53], off
	global_load_dwordx4 v[44:47], v[62:63], off offset:2048
	s_waitcnt vmcnt(2)
	v_pk_mul_f32 v[26:27], v[30:31], v[26:27]
	s_waitcnt vmcnt(1)
	v_pk_add_f32 v[30:31], v[34:35], 1.0 op_sel_hi:[1,0]
	v_pk_mul_f32 v[28:29], v[32:33], v[28:29]
	v_pk_add_f32 v[32:33], v[36:37], 1.0 op_sel_hi:[1,0]
	s_waitcnt vmcnt(0)
	v_pk_fma_f32 v[26:27], v[26:27], v[30:31], v[44:45]
	v_pk_fma_f32 v[28:29], v[28:29], v[32:33], v[46:47]
	v_cvt_pk_bf16_f32 v26, v26, v27
	v_cvt_pk_bf16_f32 v27, v28, v29
	global_store_dwordx2 v[6:7], v[26:27], off offset:1024
	global_load_dwordx4 v[44:47], v[12:13], off
	global_load_dwordx4 v[48:51], v[58:59], off
	global_load_dwordx4 v[52:55], v[62:63], off offset:3072
	v_pk_mul_f32 v[58:59], v[22:23], v[56:57] op_sel_hi:[1,0]
	v_pk_mul_f32 v[56:57], v[24:25], v[56:57] op_sel_hi:[1,0]
	v_lshlrev_b32_e32 v34, 16, v60
	v_and_b32_e32 v35, 0xffff0000, v60
	v_lshlrev_b32_e32 v36, 16, v61
	v_and_b32_e32 v37, 0xffff0000, v61
	v_lshlrev_b32_e32 v30, 16, v64
	v_and_b32_e32 v31, 0xffff0000, v64
	v_lshlrev_b32_e32 v27, 16, v70
	v_and_b32_e32 v28, 0xffff0000, v70
	v_lshlrev_b32_e32 v29, 16, v71
	v_and_b32_e32 v60, 0xffff0000, v71
	v_lshlrev_b32_e32 v61, 16, v72
	v_and_b32_e32 v62, 0xffff0000, v72
	v_lshlrev_b32_e32 v63, 16, v73
	v_and_b32_e32 v64, 0xffff0000, v73
	v_lshlrev_b32_e32 v32, 16, v65
	v_and_b32_e32 v33, 0xffff0000, v65
	v_mov_b32_e32 v26, v27
	v_mov_b32_e32 v27, v28
	v_mov_b32_e32 v28, v29
	v_mov_b32_e32 v29, v60
	v_mov_b32_e32 v22, v61
	v_mov_b32_e32 v23, v62
	v_mov_b32_e32 v24, v63
	v_mov_b32_e32 v25, v64
	s_waitcnt vmcnt(2)
	v_pk_mul_f32 v[44:45], v[58:59], v[44:45]
	s_waitcnt vmcnt(1)
	v_pk_add_f32 v[48:49], v[48:49], 1.0 op_sel_hi:[1,0]
	v_pk_mul_f32 v[46:47], v[56:57], v[46:47]
	v_pk_add_f32 v[50:51], v[50:51], 1.0 op_sel_hi:[1,0]
	s_waitcnt vmcnt(0)
	v_pk_fma_f32 v[44:45], v[44:45], v[48:49], v[52:53]
	v_pk_fma_f32 v[46:47], v[46:47], v[50:51], v[54:55]
	v_cvt_pk_bf16_f32 v44, v44, v45
	v_cvt_pk_bf16_f32 v45, v46, v47
	global_store_dwordx2 v[6:7], v[44:45], off offset:1536
	v_lshl_add_u64 v[6:7], v[6:7], 0, s[12:13]
	s_andn2_b64 exec, exec, s[10:11]
	s_cbranch_execnz .LBB0_1653

.LBB0_1791:
	s_getreg_b32 s0, hwreg(HW_REG_HW_ID, 0, 6)
	s_lshl_b32 s0, s0, 2
	s_and_b32 s0, s0, 0xfc
	s_add_i32 s0, s0, 0
	s_add_i32 s0, s0, 0x256c0
	v_mov_b32_e32 v0, s0
	ds_read_b32 v0, v0
	s_ashr_i32 s45, s44, 31
	s_lshl_b64 s[0:1], s[44:45], 2
	s_add_u32 s46, s36, s0
	s_addc_u32 s47, s37, s1
	s_waitcnt lgkmcnt(0)
	v_readfirstlane_b32 s4, v0
	v_mbcnt_lo_u32_b32 v1, -1, 0
	v_mbcnt_hi_u32_b32 v1, -1, v1
	s_add_u32 s48, s38, s0
	s_addc_u32 s49, s39, s1
	v_lshl_add_u32 v209, s4, 6, v1
	s_lshl_b64 s[0:1], s[44:45], 13
	v_lshlrev_b32_e32 v0, 3, v209
	v_ashrrev_i32_e32 v1, 31, v0
	s_add_u32 s0, s12, s0
	s_addc_u32 s1, s13, s1
	v_lshlrev_b64 v[2:3], 1, v[0:1]
	s_waitcnt vmcnt(0)
	v_lshl_add_u64 v[22:23], s[0:1], 0, v[2:3]
	v_add_co_u32_e32 v8, vcc, s64, v22
	v_lshl_add_u64 v[16:17], v[22:23], 0, s[22:23]
	s_nop 0
	v_addc_co_u32_e32 v9, vcc, 0, v23, vcc
	s_add_i32 s50, s44, 0x2000
	global_load_dwordx4 v[4:7], v[22:23], off
	global_load_dwordx4 v[18:21], v[8:9], off
	s_nop 0
	global_load_ushort v9, v[16:17], off offset:-2
	global_load_ushort v11, v[22:23], off offset:16
	global_load_ushort v13, v[22:23], off offset:-2
	s_ashr_i32 s51, s50, 31
	v_mov_b32_e32 v8, 0x3000
	s_lshl_b64 s[0:1], s[50:51], 13
	global_load_dword v8, v8, s[46:47]
	s_nop 0
	global_load_dword v10, v172, s[46:47]
	s_add_u32 s0, s12, s0
	s_addc_u32 s1, s13, s1
	v_mov_b32_e32 v12, 0x6000
	v_lshl_add_u64 v[34:35], s[0:1], 0, v[2:3]
	global_load_dword v14, v12, s[46:47]
	s_nop 0
	global_load_dword v12, v172, s[48:49]
	global_load_ushort v15, v[34:35], off offset:-2
	global_load_ushort v62, v[16:17], off offset:16
	v_lshl_add_u64 v[16:17], v[0:1], 2, s[16:17]
	v_add_co_u32_e32 v0, vcc, s65, v22
	v_cmp_lt_i32_e64 s[0:1], 0, v209
	s_nop 0
	v_addc_co_u32_e32 v1, vcc, 0, v23, vcc
	v_add_co_u32_e32 v40, vcc, s66, v22
	v_lshl_add_u64 v[36:37], v[22:23], 0, s[24:25]
	s_nop 0
	v_addc_co_u32_e32 v41, vcc, 0, v23, vcc
	v_add_co_u32_e32 v2, vcc, s67, v22
	v_lshl_add_u64 v[38:39], v[22:23], 0, s[28:29]
	s_nop 0
	v_addc_co_u32_e32 v3, vcc, 0, v23, vcc
	v_add_co_u32_e32 v46, vcc, s68, v22
	v_lshl_add_u64 v[42:43], v[22:23], 0, s[30:31]
	s_nop 0
	v_addc_co_u32_e32 v47, vcc, 0, v23, vcc
	v_add_co_u32_e32 v30, vcc, s69, v22
	v_lshl_add_u64 v[44:45], v[22:23], 0, s[40:41]
	s_nop 0
	v_addc_co_u32_e32 v31, vcc, 0, v23, vcc
	v_lshl_add_u64 v[48:49], v[22:23], 0, s[42:43]
	global_load_dwordx4 v[22:25], v[0:1], off
	global_load_dwordx4 v[26:29], v[2:3], off
	s_nop 0
	global_load_dwordx4 v[0:3], v[30:31], off
	s_nop 0
	global_load_dwordx4 v[30:33], v[34:35], off
	global_load_ushort v63, v[36:37], off offset:-2
	v_cmp_gt_i32_e32 vcc, s63, v209
	s_mov_b32 s6, 0
	s_add_i32 s45, s44, 0xc00
	s_add_i32 s51, s44, 0x2c00
	s_mov_b64 s[52:53], 0
	s_mov_b64 s[54:55], -1
	s_waitcnt vmcnt(0)
	v_lshlrev_b32_e32 v9, 16, v9
	v_lshlrev_b32_e32 v50, 16, v5
	v_lshlrev_b32_e32 v13, 16, v13
	v_and_b32_e32 v52, 0xffff0000, v5
	v_and_b32_e32 v56, 0xffff0000, v4
	v_lshlrev_b32_e32 v51, 16, v19
	v_and_b32_e32 v53, 0xffff0000, v19
	v_and_b32_e32 v57, 0xffff0000, v18
	v_lshlrev_b32_e32 v5, 16, v18
	v_cndmask_b32_e64 v18, 0, v13, s[0:1]
	v_cndmask_b32_e64 v19, 0, v9, s[0:1]
	v_lshlrev_b32_e32 v4, 16, v4
	v_pk_mul_f32 v[58:59], v[8:9], v[56:57] op_sel_hi:[0,1]
	v_pk_mul_f32 v[60:61], v[8:9], v[50:51] op_sel_hi:[0,1]
	v_pk_mul_f32 v[18:19], v[10:11], v[18:19] op_sel_hi:[0,1]
	v_pk_fma_f32 v[58:59], v[10:11], v[4:5], v[58:59] op_sel_hi:[0,1,1]
	v_pk_fma_f32 v[60:61], v[10:11], v[56:57], v[60:61] op_sel_hi:[0,1,1]
	v_pk_fma_f32 v[4:5], v[8:9], v[4:5], v[18:19] op_sel_hi:[0,1,1]
	v_pk_fma_f32 v[18:19], v[14:15], v[50:51], v[58:59] op_sel_hi:[0,1,1]
	v_pk_fma_f32 v[58:59], v[14:15], v[52:53], v[60:61] op_sel_hi:[0,1,1]
	v_pk_fma_f32 v[4:5], v[14:15], v[56:57], v[4:5] op_sel_hi:[0,1,1]
	v_pk_add_f32 v[56:57], v[12:13], v[18:19] op_sel_hi:[0,1]
	v_pk_add_f32 v[58:59], v[12:13], v[58:59] op_sel_hi:[0,1]
	v_pk_add_f32 v[4:5], v[12:13], v[4:5] op_sel_hi:[0,1]
	v_pk_mul_f32 v[18:19], v[8:9], v[52:53] op_sel_hi:[0,1]
	global_load_ushort v9, v[36:37], off offset:16
	global_load_ushort v13, v[34:35], off offset:16
	v_lshlrev_b32_e32 v54, 16, v6
	v_lshlrev_b32_e32 v55, 16, v20
	v_pk_fma_f32 v[18:19], v[10:11], v[50:51], v[18:19] op_sel_hi:[0,1,1]
	v_pk_fma_f32 v[18:19], v[14:15], v[54:55], v[18:19] op_sel_hi:[0,1,1]
	v_lshlrev_b32_e32 v11, 16, v11
	v_and_b32_e32 v37, 0xffff0000, v21
	v_and_b32_e32 v36, 0xffff0000, v7
	v_and_b32_e32 v6, 0xffff0000, v6
	v_lshlrev_b32_e32 v51, 16, v62
	v_cndmask_b32_e32 v50, 0, v11, vcc
	v_cndmask_b32_e32 v51, 0, v51, vcc
	s_waitcnt vmcnt(0)
	v_pk_add_f32 v[34:35], v[12:13], v[18:19] op_sel_hi:[0,1]
	v_lshlrev_b32_e32 v19, 16, v21
	v_lshlrev_b32_e32 v18, 16, v7
	v_and_b32_e32 v7, 0xffff0000, v20
	v_pk_mul_f32 v[20:21], v[8:9], v[54:55] op_sel_hi:[0,1]
	v_pk_fma_f32 v[20:21], v[10:11], v[52:53], v[20:21] op_sel_hi:[0,1,1]
	v_pk_fma_f32 v[20:21], v[14:15], v[6:7], v[20:21] op_sel_hi:[0,1,1]
	v_pk_add_f32 v[52:53], v[12:13], v[20:21] op_sel_hi:[0,1]
	v_pk_mul_f32 v[20:21], v[8:9], v[6:7] op_sel_hi:[0,1]
	v_pk_fma_f32 v[20:21], v[10:11], v[54:55], v[20:21] op_sel_hi:[0,1,1]
	v_pk_fma_f32 v[20:21], v[14:15], v[18:19], v[20:21] op_sel_hi:[0,1,1]
	v_pk_add_f32 v[54:55], v[12:13], v[20:21] op_sel_hi:[0,1]
	v_pk_mul_f32 v[20:21], v[8:9], v[18:19] op_sel_hi:[0,1]
	v_pk_fma_f32 v[6:7], v[10:11], v[6:7], v[20:21] op_sel_hi:[0,1,1]
	v_pk_fma_f32 v[6:7], v[14:15], v[36:37], v[6:7] op_sel_hi:[0,1,1]
	v_pk_add_f32 v[60:61], v[12:13], v[6:7] op_sel_hi:[0,1]
	v_pk_mul_f32 v[6:7], v[8:9], v[36:37] op_sel_hi:[0,1]
	v_pk_fma_f32 v[6:7], v[10:11], v[18:19], v[6:7] op_sel_hi:[0,1,1]
	v_pk_fma_f32 v[6:7], v[14:15], v[50:51], v[6:7] op_sel_hi:[0,1,1]
	v_pk_add_f32 v[50:51], v[12:13], v[6:7] op_sel_hi:[0,1]
	v_cvt_pk_f16_f32 v18, v4, v5
	v_cvt_pk_f16_f32 v19, v56, v57
	v_cvt_pk_f16_f32 v20, v58, v59
	v_cvt_pk_f16_f32 v21, v34, v35
	global_load_dwordx4 v[34:37], v[40:41], off
	global_load_ushort v11, v[42:43], off offset:-2
	global_load_ushort v56, v[42:43], off offset:16
	global_load_ushort v57, v[38:39], off offset:-2
	global_load_ushort v58, v[38:39], off offset:16
	global_load_dwordx4 v[4:7], v[46:47], off
	global_load_ushort v59, v[48:49], off offset:-2
	s_nop 0
	global_load_ushort v48, v[48:49], off offset:16
	s_nop 0
	global_load_ushort v49, v[44:45], off offset:-2
	global_load_ushort v62, v[44:45], off offset:16
	v_lshlrev_b32_e32 v15, 16, v15
	global_store_dwordx4 v[16:17], v[18:21], off
	v_and_b32_e32 v41, 0xffff0000, v22
	v_and_b32_e32 v40, 0xffff0000, v30
	v_cvt_pk_f16_f32 v18, v52, v53
	v_cvt_pk_f16_f32 v19, v54, v55
	v_cvt_pk_f16_f32 v20, v60, v61
	v_cvt_pk_f16_f32 v21, v50, v51
	global_store_dwordx4 v[16:17], v[18:21], off offset:16
	v_lshlrev_b32_e32 v30, 16, v30
	v_pk_mul_f32 v[42:43], v[8:9], v[40:41] op_sel_hi:[0,1]
	v_lshlrev_b32_e32 v19, 16, v23
	v_and_b32_e32 v21, 0xffff0000, v23
	v_lshlrev_b32_e32 v23, 16, v63
	v_lshlrev_b32_e32 v18, 16, v31
	v_and_b32_e32 v20, 0xffff0000, v31
	v_lshlrev_b32_e32 v31, 16, v22
	v_cndmask_b32_e64 v22, 0, v15, s[0:1]
	v_cndmask_b32_e64 v23, 0, v23, s[0:1]
	v_lshlrev_b32_e32 v38, 16, v32
	v_lshlrev_b32_e32 v39, 16, v24
	v_and_b32_e32 v45, 0xffff0000, v25
	v_and_b32_e32 v44, 0xffff0000, v33
	s_waitcnt vmcnt(10)
	v_pk_mul_f32 v[22:23], v[10:11], v[22:23] op_sel_hi:[0,1]
	v_pk_fma_f32 v[22:23], v[8:9], v[30:31], v[22:23] op_sel_hi:[0,1,1]
	v_pk_fma_f32 v[30:31], v[10:11], v[30:31], v[42:43] op_sel_hi:[0,1,1]
	v_pk_mul_f32 v[42:43], v[8:9], v[18:19] op_sel_hi:[0,1]
	v_pk_fma_f32 v[22:23], v[14:15], v[40:41], v[22:23] op_sel_hi:[0,1,1]
	v_pk_fma_f32 v[40:41], v[10:11], v[40:41], v[42:43] op_sel_hi:[0,1,1]
	v_pk_mul_f32 v[42:43], v[8:9], v[20:21] op_sel_hi:[0,1]
	v_pk_fma_f32 v[30:31], v[14:15], v[18:19], v[30:31] op_sel_hi:[0,1,1]
	v_pk_fma_f32 v[18:19], v[10:11], v[18:19], v[42:43] op_sel_hi:[0,1,1]
	v_pk_fma_f32 v[18:19], v[14:15], v[38:39], v[18:19] op_sel_hi:[0,1,1]
	v_lshlrev_b32_e32 v9, 16, v9
	v_pk_add_f32 v[42:43], v[12:13], v[18:19] op_sel_hi:[0,1]
	v_lshlrev_b32_e32 v18, 16, v33
	v_lshlrev_b32_e32 v19, 16, v25
	v_and_b32_e32 v25, 0xffff0000, v24
	v_and_b32_e32 v24, 0xffff0000, v32
	v_pk_mul_f32 v[32:33], v[8:9], v[38:39] op_sel_hi:[0,1]
	v_pk_fma_f32 v[40:41], v[14:15], v[20:21], v[40:41] op_sel_hi:[0,1,1]
	v_pk_fma_f32 v[20:21], v[10:11], v[20:21], v[32:33] op_sel_hi:[0,1,1]
	v_pk_add_f32 v[22:23], v[12:13], v[22:23] op_sel_hi:[0,1]
	v_pk_add_f32 v[30:31], v[12:13], v[30:31] op_sel_hi:[0,1]
	v_pk_add_f32 v[40:41], v[12:13], v[40:41] op_sel_hi:[0,1]
	v_lshlrev_b32_e32 v13, 16, v13
	v_pk_fma_f32 v[20:21], v[14:15], v[24:25], v[20:21] op_sel_hi:[0,1,1]
	v_pk_add_f32 v[32:33], v[12:13], v[20:21] op_sel_hi:[0,1]
	v_pk_mul_f32 v[20:21], v[8:9], v[24:25] op_sel_hi:[0,1]
	v_pk_fma_f32 v[20:21], v[10:11], v[38:39], v[20:21] op_sel_hi:[0,1,1]
	v_pk_fma_f32 v[20:21], v[14:15], v[18:19], v[20:21] op_sel_hi:[0,1,1]
	v_pk_add_f32 v[38:39], v[12:13], v[20:21] op_sel_hi:[0,1]
	v_pk_mul_f32 v[20:21], v[8:9], v[18:19] op_sel_hi:[0,1]
	v_pk_fma_f32 v[20:21], v[10:11], v[24:25], v[20:21] op_sel_hi:[0,1,1]
	v_pk_fma_f32 v[20:21], v[14:15], v[44:45], v[20:21] op_sel_hi:[0,1,1]
	v_pk_add_f32 v[24:25], v[12:13], v[20:21] op_sel_hi:[0,1]
	v_pk_mul_f32 v[20:21], v[8:9], v[44:45] op_sel_hi:[0,1]
	v_cndmask_b32_e32 v46, 0, v13, vcc
	v_cndmask_b32_e32 v47, 0, v9, vcc
	v_pk_fma_f32 v[18:19], v[10:11], v[18:19], v[20:21] op_sel_hi:[0,1,1]
	v_pk_fma_f32 v[18:19], v[14:15], v[46:47], v[18:19] op_sel_hi:[0,1,1]
	v_pk_add_f32 v[44:45], v[12:13], v[18:19] op_sel_hi:[0,1]
	v_cvt_pk_f16_f32 v18, v22, v23
	v_add_co_u32_e64 v22, s[4:5], s72, v16
	v_cvt_pk_f16_f32 v19, v30, v31
	v_cvt_pk_f16_f32 v20, v40, v41
	v_cvt_pk_f16_f32 v21, v42, v43
	v_addc_co_u32_e64 v23, s[4:5], 0, v17, s[4:5]
	s_waitcnt vmcnt(8)
	v_lshlrev_b32_e32 v9, 16, v57
	v_lshlrev_b32_e32 v11, 16, v11
	global_store_dwordx4 v[22:23], v[18:21], off
	v_cndmask_b32_e64 v31, 0, v11, s[0:1]
	v_cndmask_b32_e64 v30, 0, v9, s[0:1]
	v_cvt_pk_f16_f32 v18, v32, v33
	v_cvt_pk_f16_f32 v19, v38, v39
	v_cvt_pk_f16_f32 v20, v24, v25
	v_cvt_pk_f16_f32 v21, v44, v45
	v_and_b32_e32 v25, 0xffff0000, v26
	v_and_b32_e32 v24, 0xffff0000, v34
	global_store_dwordx4 v[22:23], v[18:21], off offset:16
	v_pk_mul_f32 v[30:31], v[10:11], v[30:31] op_sel_hi:[0,1]
	v_pk_mul_f32 v[32:33], v[8:9], v[24:25] op_sel_hi:[0,1]
	v_lshlrev_b32_e32 v19, 16, v27
	v_lshlrev_b32_e32 v18, 16, v35
	v_and_b32_e32 v21, 0xffff0000, v27
	v_lshlrev_b32_e32 v27, 16, v26
	v_lshlrev_b32_e32 v26, 16, v34
	v_and_b32_e32 v20, 0xffff0000, v35
	v_pk_fma_f32 v[30:31], v[8:9], v[26:27], v[30:31] op_sel_hi:[0,1,1]
	v_pk_fma_f32 v[26:27], v[10:11], v[26:27], v[32:33] op_sel_hi:[0,1,1]
	v_pk_mul_f32 v[32:33], v[8:9], v[18:19] op_sel_hi:[0,1]
	v_pk_fma_f32 v[30:31], v[14:15], v[24:25], v[30:31] op_sel_hi:[0,1,1]
	v_pk_fma_f32 v[24:25], v[10:11], v[24:25], v[32:33] op_sel_hi:[0,1,1]
	v_pk_mul_f32 v[32:33], v[8:9], v[20:21] op_sel_hi:[0,1]
	v_lshlrev_b32_e32 v23, 16, v28
	v_lshlrev_b32_e32 v22, 16, v36
	v_pk_fma_f32 v[26:27], v[14:15], v[18:19], v[26:27] op_sel_hi:[0,1,1]
	v_pk_fma_f32 v[18:19], v[10:11], v[18:19], v[32:33] op_sel_hi:[0,1,1]
	v_pk_fma_f32 v[18:19], v[14:15], v[22:23], v[18:19] op_sel_hi:[0,1,1]
	s_waitcnt vmcnt(9)
	v_lshlrev_b32_e32 v9, 16, v58
	v_pk_add_f32 v[32:33], v[12:13], v[18:19] op_sel_hi:[0,1]
	v_lshlrev_b32_e32 v11, 16, v56
	v_lshlrev_b32_e32 v19, 16, v29
	v_lshlrev_b32_e32 v18, 16, v37
	v_and_b32_e32 v35, 0xffff0000, v29
	v_and_b32_e32 v34, 0xffff0000, v37
	v_and_b32_e32 v29, 0xffff0000, v28
	v_and_b32_e32 v28, 0xffff0000, v36
	v_pk_mul_f32 v[36:37], v[8:9], v[22:23] op_sel_hi:[0,1]
	v_pk_fma_f32 v[24:25], v[14:15], v[20:21], v[24:25] op_sel_hi:[0,1,1]
	v_pk_fma_f32 v[20:21], v[10:11], v[20:21], v[36:37] op_sel_hi:[0,1,1]
	v_pk_fma_f32 v[20:21], v[14:15], v[28:29], v[20:21] op_sel_hi:[0,1,1]
	v_pk_add_f32 v[36:37], v[12:13], v[20:21] op_sel_hi:[0,1]
	v_pk_mul_f32 v[20:21], v[8:9], v[28:29] op_sel_hi:[0,1]
	v_pk_fma_f32 v[20:21], v[10:11], v[22:23], v[20:21] op_sel_hi:[0,1,1]
	v_pk_fma_f32 v[20:21], v[14:15], v[18:19], v[20:21] op_sel_hi:[0,1,1]
	v_pk_add_f32 v[22:23], v[12:13], v[20:21] op_sel_hi:[0,1]
	v_pk_mul_f32 v[20:21], v[8:9], v[18:19] op_sel_hi:[0,1]
	v_pk_fma_f32 v[20:21], v[10:11], v[28:29], v[20:21] op_sel_hi:[0,1,1]
	v_pk_fma_f32 v[20:21], v[14:15], v[34:35], v[20:21] op_sel_hi:[0,1,1]
	v_pk_add_f32 v[28:29], v[12:13], v[20:21] op_sel_hi:[0,1]
	v_pk_mul_f32 v[20:21], v[8:9], v[34:35] op_sel_hi:[0,1]
	v_pk_add_f32 v[24:25], v[12:13], v[24:25] op_sel_hi:[0,1]
	v_cndmask_b32_e32 v39, 0, v11, vcc
	v_cndmask_b32_e32 v38, 0, v9, vcc
	v_pk_fma_f32 v[18:19], v[10:11], v[18:19], v[20:21] op_sel_hi:[0,1,1]
	v_pk_add_f32 v[30:31], v[12:13], v[30:31] op_sel_hi:[0,1]
	v_pk_add_f32 v[26:27], v[12:13], v[26:27] op_sel_hi:[0,1]
	v_pk_fma_f32 v[18:19], v[14:15], v[38:39], v[18:19] op_sel_hi:[0,1,1]
	v_cvt_pk_f16_f32 v20, v24, v25
	v_add_co_u32_e64 v24, s[4:5], s73, v16
	v_pk_add_f32 v[34:35], v[12:13], v[18:19] op_sel_hi:[0,1]
	v_cvt_pk_f16_f32 v18, v30, v31
	v_cvt_pk_f16_f32 v19, v26, v27
	v_cvt_pk_f16_f32 v21, v32, v33
	v_addc_co_u32_e64 v25, s[4:5], 0, v17, s[4:5]
	global_store_dwordx4 v[24:25], v[18:21], off
	s_nop 1
	v_cvt_pk_f16_f32 v18, v36, v37
	v_cvt_pk_f16_f32 v19, v22, v23
	v_cvt_pk_f16_f32 v20, v28, v29
	v_cvt_pk_f16_f32 v21, v34, v35
	global_store_dwordx4 v[24:25], v[18:21], off offset:16
	v_and_b32_e32 v25, 0xffff0000, v0
	s_waitcnt vmcnt(10)
	v_and_b32_e32 v24, 0xffff0000, v4
	v_lshlrev_b32_e32 v19, 16, v1
	v_lshlrev_b32_e32 v18, 16, v5
	v_and_b32_e32 v21, 0xffff0000, v1
	v_and_b32_e32 v20, 0xffff0000, v5
	v_lshlrev_b32_e32 v1, 16, v0
	v_lshlrev_b32_e32 v0, 16, v4
	s_waitcnt vmcnt(7)
	v_lshlrev_b32_e32 v4, 16, v49
	v_lshlrev_b32_e32 v5, 16, v59
	v_cndmask_b32_e64 v5, 0, v5, s[0:1]
	v_cndmask_b32_e64 v4, 0, v4, s[0:1]
	v_pk_mul_f32 v[4:5], v[10:11], v[4:5] op_sel_hi:[0,1]
	v_pk_mul_f32 v[26:27], v[8:9], v[24:25] op_sel_hi:[0,1]
	v_pk_fma_f32 v[4:5], v[8:9], v[0:1], v[4:5] op_sel_hi:[0,1,1]
	v_pk_fma_f32 v[0:1], v[10:11], v[0:1], v[26:27] op_sel_hi:[0,1,1]
	v_pk_fma_f32 v[0:1], v[14:15], v[18:19], v[0:1] op_sel_hi:[0,1,1]
	v_pk_add_f32 v[26:27], v[12:13], v[0:1] op_sel_hi:[0,1]
	v_pk_mul_f32 v[0:1], v[8:9], v[18:19] op_sel_hi:[0,1]
	v_pk_fma_f32 v[0:1], v[10:11], v[24:25], v[0:1] op_sel_hi:[0,1,1]
	v_pk_fma_f32 v[0:1], v[14:15], v[20:21], v[0:1] op_sel_hi:[0,1,1]
	v_pk_fma_f32 v[4:5], v[14:15], v[24:25], v[4:5] op_sel_hi:[0,1,1]
	v_pk_add_f32 v[24:25], v[12:13], v[0:1] op_sel_hi:[0,1]
	v_pk_mul_f32 v[0:1], v[8:9], v[20:21] op_sel_hi:[0,1]
	v_lshlrev_b32_e32 v23, 16, v2
	v_lshlrev_b32_e32 v22, 16, v6
	v_pk_fma_f32 v[0:1], v[10:11], v[18:19], v[0:1] op_sel_hi:[0,1,1]
	v_pk_fma_f32 v[0:1], v[14:15], v[22:23], v[0:1] op_sel_hi:[0,1,1]
	s_waitcnt vmcnt(6)
	v_lshlrev_b32_e32 v9, 16, v62
	v_pk_add_f32 v[18:19], v[12:13], v[0:1] op_sel_hi:[0,1]
	v_lshlrev_b32_e32 v11, 16, v48
	v_lshlrev_b32_e32 v1, 16, v3
	v_lshlrev_b32_e32 v0, 16, v7
	v_and_b32_e32 v29, 0xffff0000, v3
	v_and_b32_e32 v28, 0xffff0000, v7
	v_and_b32_e32 v3, 0xffff0000, v2
	v_and_b32_e32 v2, 0xffff0000, v6
	v_pk_mul_f32 v[6:7], v[8:9], v[22:23] op_sel_hi:[0,1]
	v_pk_fma_f32 v[6:7], v[10:11], v[20:21], v[6:7] op_sel_hi:[0,1,1]
	v_pk_mul_f32 v[20:21], v[8:9], v[2:3] op_sel_hi:[0,1]
	v_pk_fma_f32 v[20:21], v[10:11], v[22:23], v[20:21] op_sel_hi:[0,1,1]
	v_pk_mul_f32 v[22:23], v[8:9], v[0:1] op_sel_hi:[0,1]
	v_pk_fma_f32 v[6:7], v[14:15], v[2:3], v[6:7] op_sel_hi:[0,1,1]
	v_pk_fma_f32 v[2:3], v[10:11], v[2:3], v[22:23] op_sel_hi:[0,1,1]
	v_pk_fma_f32 v[2:3], v[14:15], v[28:29], v[2:3] op_sel_hi:[0,1,1]
	v_pk_add_f32 v[22:23], v[12:13], v[2:3] op_sel_hi:[0,1]
	v_pk_mul_f32 v[2:3], v[8:9], v[28:29] op_sel_hi:[0,1]
	v_cndmask_b32_e32 v31, 0, v11, vcc
	v_cndmask_b32_e32 v30, 0, v9, vcc
	v_pk_fma_f32 v[20:21], v[14:15], v[0:1], v[20:21] op_sel_hi:[0,1,1]
	v_pk_fma_f32 v[0:1], v[10:11], v[0:1], v[2:3] op_sel_hi:[0,1,1]
	v_pk_add_f32 v[4:5], v[12:13], v[4:5] op_sel_hi:[0,1]
	v_pk_fma_f32 v[0:1], v[14:15], v[30:31], v[0:1] op_sel_hi:[0,1,1]
	v_pk_add_f32 v[8:9], v[12:13], v[0:1] op_sel_hi:[0,1]
	v_cvt_pk_f16_f32 v0, v4, v5
	v_add_co_u32_e32 v4, vcc, s80, v16
	v_pk_add_f32 v[6:7], v[12:13], v[6:7] op_sel_hi:[0,1]
	v_pk_add_f32 v[20:21], v[12:13], v[20:21] op_sel_hi:[0,1]
	v_cvt_pk_f16_f32 v1, v26, v27
	v_cvt_pk_f16_f32 v2, v24, v25
	v_cvt_pk_f16_f32 v3, v18, v19
	v_addc_co_u32_e32 v5, vcc, 0, v17, vcc
	global_store_dwordx4 v[4:5], v[0:3], off
	s_nop 1
	v_cvt_pk_f16_f32 v0, v6, v7
	v_cvt_pk_f16_f32 v1, v20, v21
	v_cvt_pk_f16_f32 v2, v22, v23
	v_cvt_pk_f16_f32 v3, v8, v9
	global_store_dwordx4 v[4:5], v[0:3], off offset:16
	s_barrier
	s_branch .LBB0_1793

.LBB0_1804:
	v_lshlrev_b32_e32 v16, 1, v209
	v_and_b32_e32 v16, -4, v16
	v_add_u32_e32 v26, v242, v16
	ds_read_b128 v[16:19], v26 offset:34816
	ds_read_b128 v[20:23], v26 offset:52224
	s_waitcnt vmcnt(11)
	v_and_b32_e32 v56, 0xffff0000, v124
	ds_read_b128 v[38:41], v26 offset:34832
	ds_read_b128 v[42:45], v26 offset:52240
	v_cvt_f32_f16_e32 v55, v109
	v_cvt_f32_f16_e32 v54, v108
	s_waitcnt lgkmcnt(2)
	v_pk_add_f16 v36, v17, v21
	s_waitcnt vmcnt(9)
	v_lshlrev_b32_e32 v17, 16, v245
	v_pk_add_f16 v34, v16, v20
	v_pk_add_f16 v32, v18, v22
	v_pk_add_f16 v35, v19, v23
	v_cndmask_b32_e64 v18, 0, v17, s[0:1]
	v_mov_b32_e32 v19, v56
	v_lshlrev_b32_e32 v16, 16, v124
	v_cvt_f32_f16_e32 v23, v36
	v_cvt_f32_f16_e32 v22, v34
	v_pk_mul_f32 v[18:19], v[170:171], v[18:19]
	v_cvt_f32_f16_e32 v53, v35
	v_cvt_f32_f16_e32 v52, v32
	v_pk_fma_f32 v[16:17], v[168:169], v[16:17], v[18:19] op_sel_hi:[1,0,1]
	v_cvt_f32_f16_e32 v19, v111
	v_cvt_f32_f16_e32 v18, v110
	v_lshlrev_b32_e32 v57, 16, v125
	v_pk_fma_f32 v[16:17], v[158:159], v[56:57], v[16:17]
	v_and_b32_e32 v51, 16, v126
	v_and_b32_e32 v50, 0xffff0000, v125
	v_pk_fma_f32 v[22:23], v[154:155], v[54:55], v[22:23]
	v_pk_add_f32 v[16:17], v[152:153], v[16:17]
	v_lshlrev_b32_e32 v27, 16, v246
	s_waitcnt lgkmcnt(0)
	v_pk_add_f16 v31, v38, v42
	v_pk_add_f16 v33, v39, v43
	v_and_b32_e32 v43, 16, v127
	v_and_b32_e32 v42, 0xffff0000, v126
	v_lshlrev_b32_e32 v49, 16, v126
	v_mov_b32_e32 v48, v50
	v_pk_mul_f32 v[22:23], v[16:17], v[22:23]
	v_pk_fma_f32 v[16:17], v[154:155], v[18:19], v[52:53]
	v_pk_mov_b32 v[18:19], v[56:57], v[50:51] op_sel:[1,0]
	v_cndmask_b32_e64 v46, 0, v27, s[4:5]
	v_pk_add_f16 v27, v40, v44
	v_pk_add_f16 v30, v41, v45
	v_mov_b32_e32 v40, v42
	v_cvt_f32_f16_e32 v45, v33
	v_cvt_f32_f16_e32 v44, v31
	v_pk_mul_f32 v[18:19], v[156:157], v[18:19]
	v_cvt_f32_f16_e32 v51, v101
	v_cvt_f32_f16_e32 v50, v100
	v_pk_mov_b32 v[42:43], v[48:49], v[42:43] op_sel:[1,0]
	v_pk_fma_f32 v[18:19], v[150:151], v[56:57], v[18:19]
	v_pk_mul_f32 v[42:43], v[156:157], v[42:43]
	v_lshlrev_b32_e32 v41, 16, v127
	v_pk_fma_f32 v[18:19], v[158:159], v[48:49], v[18:19]
	v_pk_fma_f32 v[42:43], v[150:151], v[48:49], v[42:43]
	v_pk_add_f32 v[18:19], v[152:153], v[18:19]
	v_pk_fma_f32 v[42:43], v[158:159], v[40:41], v[42:43]
	v_pk_mul_f32 v[16:17], v[18:19], v[16:17]
	v_pk_fma_f32 v[18:19], v[154:155], v[50:51], v[44:45]
	v_pk_add_f32 v[42:43], v[152:153], v[42:43]
	v_cvt_f32_f16_e32 v39, v27
	v_cvt_f32_f16_e32 v38, v30
	v_pk_mul_f32 v[18:19], v[42:43], v[18:19]
	v_cvt_f32_f16_e32 v43, v102
	v_cvt_f32_f16_e32 v42, v103
	v_and_b32_e32 v20, 0xffff0000, v127
	v_mov_b32_e32 v21, v41
	v_pk_mul_f32 v[40:41], v[150:151], v[40:41]
	v_mov_b32_e32 v47, v20
	v_pk_fma_f32 v[20:21], v[156:157], v[20:21], v[40:41] op_sel:[0,0,1] op_sel_hi:[1,1,0]
	s_lshl_b32 s6, s60, 12
	v_pk_fma_f32 v[20:21], v[158:159], v[46:47], v[20:21]
	v_pk_fma_f32 v[38:39], v[154:155], v[42:43], v[38:39]
	v_pk_add_f32 v[20:21], v[152:153], v[20:21]
	v_cndmask_b32_e64 v37, 0, 1, s[56:57]
	s_add_i32 s8, s6, s44
	v_cmp_ne_u32_e64 s[6:7], 1, v37
	s_andn2_b64 vcc, exec, s[56:57]
	v_pk_mul_f32 v[20:21], v[20:21], v[38:39]
	s_cbranch_vccnz .LBB0_1806
	v_lshlrev_b32_e32 v38, 16, v120
	v_and_b32_e32 v39, 0xffff0000, v120
	v_mul_f32_e32 v37, 0xbfb8aa3b, v38
	v_exp_f32_e32 v37, v37
	v_mul_f32_e32 v40, 0xbfb8aa3b, v39
	v_exp_f32_e32 v41, v40
	v_lshlrev_b32_e32 v42, 16, v121
	v_add_f32_e32 v37, 1.0, v37
	v_rcp_f32_e32 v40, v37
	v_add_f32_e32 v37, 1.0, v41
	v_rcp_f32_e32 v41, v37
	v_and_b32_e32 v43, 0xffff0000, v121
	v_mul_f32_e32 v37, 0xbfb8aa3b, v42
	v_exp_f32_e32 v37, v37
	v_pk_mul_f32 v[38:39], v[40:41], v[38:39]
	v_mul_f32_e32 v40, 0xbfb8aa3b, v43
	v_exp_f32_e32 v40, v40
	v_add_f32_e32 v37, 1.0, v37
	v_pk_mul_f32 v[22:23], v[38:39], v[22:23]
	v_rcp_f32_e32 v38, v37
	v_add_f32_e32 v37, 1.0, v40
	v_lshlrev_b32_e32 v40, 16, v122
	v_rcp_f32_e32 v39, v37
	v_and_b32_e32 v41, 0xffff0000, v122
	v_mul_f32_e32 v37, 0xbfb8aa3b, v40
	v_exp_f32_e32 v37, v37
	v_mul_f32_e32 v44, 0xbfb8aa3b, v41
	v_exp_f32_e32 v44, v44
	v_pk_mul_f32 v[38:39], v[38:39], v[42:43]
	v_add_f32_e32 v37, 1.0, v37
	v_rcp_f32_e32 v42, v37
	v_add_f32_e32 v37, 1.0, v44
	v_lshlrev_b32_e32 v44, 16, v123
	v_and_b32_e32 v45, 0xffff0000, v123
	v_mul_f32_e32 v43, 0xbfb8aa3b, v44
	v_exp_f32_e32 v46, v43
	v_mul_f32_e32 v43, 0xbfb8aa3b, v45
	v_exp_f32_e32 v47, v43
	v_rcp_f32_e32 v43, v37
	v_add_f32_e32 v37, 1.0, v46
	v_rcp_f32_e32 v46, v37
	v_add_f32_e32 v37, 1.0, v47
	v_rcp_f32_e32 v47, v37
	v_pk_mul_f32 v[38:39], v[38:39], v[16:17]
	v_pk_mul_f32 v[16:17], v[42:43], v[40:41]
	s_ashr_i32 s9, s8, 31
	v_pk_mul_f32 v[18:19], v[16:17], v[18:19]
	v_pk_mul_f32 v[16:17], v[46:47], v[44:45]
	s_lshl_b64 s[92:93], s[8:9], 13
	v_pk_mul_f32 v[20:21], v[16:17], v[20:21] op_sel:[0,1] op_sel_hi:[1,0]
	v_cvt_pk_bf16_f32 v16, v22, v23
	v_cvt_pk_bf16_f32 v17, v38, v39
	v_cvt_pk_bf16_f32 v18, v18, v19
	v_cvt_pk_bf16_f32 v19, v20, v21
	v_lshl_add_u64 v[20:21], v[162:163], 0, s[92:93]
	global_store_dwordx4 v[20:21], v[16:19], off
	s_branch .LBB0_1807

.LBB0_1807:
	s_waitcnt vmcnt(6)
	v_lshlrev_b32_e32 v23, 16, v243
	v_and_b32_e32 v48, 0xffff0000, v116
	v_cvt_f32_f16_sdwa v17, v36 dst_sel:DWORD dst_unused:UNUSED_PAD src0_sel:WORD_1
	v_lshlrev_b32_e32 v22, 16, v244
	v_cndmask_b32_e64 v36, 0, v23, s[0:1]
	v_mov_b32_e32 v37, v48
	v_cvt_f32_f16_sdwa v16, v34 dst_sel:DWORD dst_unused:UNUSED_PAD src0_sel:WORD_1
	v_cvt_f32_f16_sdwa v18, v32 dst_sel:DWORD dst_unused:UNUSED_PAD src0_sel:WORD_1
	v_cndmask_b32_e64 v32, 0, v22, s[4:5]
	v_lshlrev_b32_e32 v22, 16, v116
	v_cvt_f32_f16_sdwa v47, v109 dst_sel:DWORD dst_unused:UNUSED_PAD src0_sel:WORD_1
	v_cvt_f32_f16_sdwa v46, v108 dst_sel:DWORD dst_unused:UNUSED_PAD src0_sel:WORD_1
	v_pk_mul_f32 v[36:37], v[170:171], v[36:37]
	v_cvt_f32_f16_sdwa v19, v35 dst_sel:DWORD dst_unused:UNUSED_PAD src0_sel:WORD_1
	v_pk_fma_f32 v[22:23], v[168:169], v[22:23], v[36:37] op_sel_hi:[1,0,1]
	v_cvt_f32_f16_sdwa v37, v111 dst_sel:DWORD dst_unused:UNUSED_PAD src0_sel:WORD_1
	v_cvt_f32_f16_sdwa v36, v110 dst_sel:DWORD dst_unused:UNUSED_PAD src0_sel:WORD_1
	v_lshlrev_b32_e32 v49, 16, v117
	v_pk_fma_f32 v[22:23], v[158:159], v[48:49], v[22:23]
	v_and_b32_e32 v45, 16, v118
	v_and_b32_e32 v44, 0xffff0000, v117
	v_pk_fma_f32 v[16:17], v[154:155], v[46:47], v[16:17] neg_lo:[0,0,1] neg_hi:[0,0,1]
	v_pk_add_f32 v[22:23], v[152:153], v[22:23]
	v_cvt_f32_f16_sdwa v21, v33 dst_sel:DWORD dst_unused:UNUSED_PAD src0_sel:WORD_1
	v_pk_mul_f32 v[22:23], v[22:23], v[16:17]
	v_pk_fma_f32 v[16:17], v[154:155], v[36:37], v[18:19] neg_lo:[0,0,1] neg_hi:[0,0,1]
	v_pk_mov_b32 v[18:19], v[48:49], v[44:45] op_sel:[1,0]
	v_cvt_f32_f16_sdwa v20, v31 dst_sel:DWORD dst_unused:UNUSED_PAD src0_sel:WORD_1
	v_pk_mul_f32 v[18:19], v[156:157], v[18:19]
	v_cvt_f32_f16_sdwa v37, v101 dst_sel:DWORD dst_unused:UNUSED_PAD src0_sel:WORD_1
	v_cvt_f32_f16_sdwa v36, v100 dst_sel:DWORD dst_unused:UNUSED_PAD src0_sel:WORD_1
	v_lshlrev_b32_e32 v43, 16, v118
	v_mov_b32_e32 v42, v44
	v_pk_fma_f32 v[18:19], v[150:151], v[48:49], v[18:19]
	v_and_b32_e32 v41, 16, v119
	v_pk_fma_f32 v[18:19], v[158:159], v[42:43], v[18:19]
	v_and_b32_e32 v40, 0xffff0000, v118
	v_pk_add_f32 v[18:19], v[152:153], v[18:19]
	v_lshlrev_b32_e32 v39, 16, v119
	v_pk_mul_f32 v[16:17], v[18:19], v[16:17]
	v_pk_fma_f32 v[18:19], v[154:155], v[36:37], v[20:21] neg_lo:[0,0,1] neg_hi:[0,0,1]
	v_pk_mov_b32 v[20:21], v[42:43], v[40:41] op_sel:[1,0]
	v_mov_b32_e32 v38, v40
	v_pk_mul_f32 v[20:21], v[156:157], v[20:21]
	v_cvt_f32_f16_sdwa v31, v27 dst_sel:DWORD dst_unused:UNUSED_PAD src0_sel:WORD_1
	v_pk_fma_f32 v[20:21], v[150:151], v[42:43], v[20:21]
	v_cvt_f32_f16_sdwa v30, v30 dst_sel:DWORD dst_unused:UNUSED_PAD src0_sel:WORD_1
	v_pk_fma_f32 v[20:21], v[158:159], v[38:39], v[20:21]
	v_cvt_f32_f16_sdwa v37, v102 dst_sel:DWORD dst_unused:UNUSED_PAD src0_sel:WORD_1
	v_pk_add_f32 v[20:21], v[152:153], v[20:21]
	v_cvt_f32_f16_sdwa v36, v103 dst_sel:DWORD dst_unused:UNUSED_PAD src0_sel:WORD_1
	v_and_b32_e32 v34, 0xffff0000, v119
	v_mov_b32_e32 v35, v39
	v_pk_mul_f32 v[18:19], v[20:21], v[18:19]
	v_pk_mul_f32 v[20:21], v[150:151], v[38:39]
	v_mov_b32_e32 v33, v34
	v_pk_fma_f32 v[20:21], v[156:157], v[34:35], v[20:21] op_sel:[0,0,1] op_sel_hi:[1,1,0]
	v_pk_fma_f32 v[30:31], v[154:155], v[36:37], v[30:31] neg_lo:[0,0,1] neg_hi:[0,0,1]
	v_pk_fma_f32 v[20:21], v[158:159], v[32:33], v[20:21]
	s_and_b64 vcc, exec, s[6:7]
	v_pk_add_f32 v[20:21], v[152:153], v[20:21]
	s_nop 0
	v_pk_mul_f32 v[20:21], v[20:21], v[30:31]
	s_cbranch_vccnz .LBB0_1809
	v_lshlrev_b32_e32 v30, 16, v112
	v_and_b32_e32 v31, 0xffff0000, v112
	v_mul_f32_e32 v27, 0xbfb8aa3b, v30
	v_exp_f32_e32 v27, v27
	v_mul_f32_e32 v32, 0xbfb8aa3b, v31
	v_exp_f32_e32 v33, v32
	v_lshlrev_b32_e32 v34, 16, v113
	v_add_f32_e32 v27, 1.0, v27
	v_rcp_f32_e32 v32, v27
	v_add_f32_e32 v27, 1.0, v33
	v_rcp_f32_e32 v33, v27
	v_and_b32_e32 v35, 0xffff0000, v113
	v_mul_f32_e32 v27, 0xbfb8aa3b, v34
	v_exp_f32_e32 v27, v27
	v_pk_mul_f32 v[30:31], v[32:33], v[30:31]
	v_mul_f32_e32 v32, 0xbfb8aa3b, v35
	v_exp_f32_e32 v32, v32
	v_add_f32_e32 v27, 1.0, v27
	v_pk_mul_f32 v[22:23], v[30:31], v[22:23]
	v_rcp_f32_e32 v30, v27
	v_add_f32_e32 v27, 1.0, v32
	v_lshlrev_b32_e32 v32, 16, v114
	v_rcp_f32_e32 v31, v27
	v_and_b32_e32 v33, 0xffff0000, v114
	v_mul_f32_e32 v27, 0xbfb8aa3b, v32
	v_exp_f32_e32 v27, v27
	v_mul_f32_e32 v36, 0xbfb8aa3b, v33
	v_exp_f32_e32 v36, v36
	v_pk_mul_f32 v[30:31], v[30:31], v[34:35]
	v_add_f32_e32 v27, 1.0, v27
	v_rcp_f32_e32 v34, v27
	v_add_f32_e32 v27, 1.0, v36
	v_lshlrev_b32_e32 v36, 16, v115
	v_and_b32_e32 v37, 0xffff0000, v115
	v_mul_f32_e32 v35, 0xbfb8aa3b, v36
	v_exp_f32_e32 v38, v35
	v_mul_f32_e32 v35, 0xbfb8aa3b, v37
	v_exp_f32_e32 v39, v35
	v_rcp_f32_e32 v35, v27
	v_add_f32_e32 v27, 1.0, v38
	v_rcp_f32_e32 v38, v27
	v_add_f32_e32 v27, 1.0, v39
	v_rcp_f32_e32 v39, v27
	v_pk_mul_f32 v[30:31], v[30:31], v[16:17]
	v_pk_mul_f32 v[16:17], v[34:35], v[32:33]
	s_ashr_i32 s9, s8, 31
	v_pk_mul_f32 v[18:19], v[16:17], v[18:19]
	v_pk_mul_f32 v[16:17], v[38:39], v[36:37]
	s_lshl_b64 s[8:9], s[8:9], 13
	v_pk_mul_f32 v[20:21], v[16:17], v[20:21] op_sel:[0,1] op_sel_hi:[1,0]
	v_cvt_pk_bf16_f32 v18, v18, v19
	v_cvt_pk_bf16_f32 v19, v20, v21
	v_lshl_add_u64 v[20:21], v[162:163], 0, s[8:9]
	v_add_co_u32_e32 v20, vcc, 0x800000, v20
	v_cvt_pk_bf16_f32 v16, v22, v23
	v_cvt_pk_bf16_f32 v17, v30, v31
	v_addc_co_u32_e32 v21, vcc, 0, v21, vcc
	global_store_dwordx4 v[20:21], v[16:19], off
	s_nop 1
	v_cndmask_b32_e64 v16, 0, 1, s[54:55]
	v_cmp_ne_u32_e64 s[8:9], 1, v16
	s_andn2_b64 vcc, exec, s[54:55]
	s_cbranch_vccz .LBB0_1810
	s_branch .LBB0_1811

.LBB0_1811:
	s_waitcnt vmcnt(3)
	s_nop 0
	v_lshlrev_b32_e32 v16, 16, v25
	v_cndmask_b32_e64 v52, 0, v16, s[4:5]
	global_load_dwordx4 v[108:111], v[164:165], off
	global_load_dwordx4 v[100:103], v[164:165], off offset:16
	global_load_dwordx4 v[16:19], v[166:167], off
	global_load_dwordx4 v[20:23], v[166:167], off offset:16
	v_add_u32_e32 v26, 0x8800, v26
	v_add_u32_e32 v25, 0x11000, v26
	ds_read_b128 v[36:39], v25
	v_add_u32_e32 v25, 0x15400, v26
	ds_read_b128 v[40:43], v25
	v_add_u32_e32 v25, 0x11010, v26
	ds_read_b128 v[44:47], v25
	v_add_u32_e32 v25, 0x15410, v26
	ds_read_b128 v[48:51], v25
	s_waitcnt lgkmcnt(2)
	v_pk_add_f16 v35, v36, v40
	v_pk_add_f16 v37, v37, v41
	v_cvt_f32_f16_e32 v54, v35
	v_cvt_f32_f16_e32 v55, v37
	v_cvt_f32_f16_e32 v57, v105
	v_cvt_f32_f16_e32 v56, v104
	v_lshlrev_b32_e32 v26, 16, v12
	v_lshlrev_b32_e32 v24, 16, v24
	v_and_b32_e32 v12, 0xffff0000, v12
	s_waitcnt lgkmcnt(0)
	v_pk_add_f16 v32, v44, v48
	v_pk_add_f16 v34, v45, v49
	v_cndmask_b32_e64 v24, 0, v24, s[0:1]
	v_and_b32_e32 v49, 16, v14
	v_and_b32_e32 v48, 0xffff0000, v13
	v_lshlrev_b32_e32 v13, 16, v13
	v_mov_b32_e32 v25, v12
	v_pk_add_f16 v33, v38, v42
	v_pk_add_f16 v36, v39, v43
	v_and_b32_e32 v38, 0xffff0000, v15
	v_lshlrev_b32_e32 v43, 16, v15
	v_and_b32_e32 v45, 16, v15
	v_and_b32_e32 v44, 0xffff0000, v14
	v_lshlrev_b32_e32 v15, 16, v14
	v_mov_b32_e32 v14, v48
	v_pk_mul_f32 v[24:25], v[170:171], v[24:25]
	v_pk_mov_b32 v[48:49], v[12:13], v[48:49] op_sel:[1,0]
	v_pk_add_f16 v30, v46, v50
	v_pk_add_f16 v31, v47, v51
	v_cvt_f32_f16_e32 v51, v36
	v_cvt_f32_f16_e32 v50, v33
	v_pk_fma_f32 v[54:55], v[154:155], v[56:57], v[54:55]
	v_pk_fma_f32 v[24:25], v[168:169], v[26:27], v[24:25] op_sel_hi:[1,0,1]
	v_cvt_f32_f16_e32 v57, v107
	v_cvt_f32_f16_e32 v56, v106
	v_pk_mul_f32 v[48:49], v[156:157], v[48:49]
	v_mov_b32_e32 v42, v44
	v_cvt_f32_f16_e32 v47, v34
	v_cvt_f32_f16_e32 v46, v32
	v_pk_fma_f32 v[24:25], v[158:159], v[12:13], v[24:25]
	v_pk_fma_f32 v[12:13], v[150:151], v[12:13], v[48:49]
	v_cvt_f32_f16_e32 v49, v97
	v_cvt_f32_f16_e32 v48, v96
	v_pk_mov_b32 v[44:45], v[14:15], v[44:45] op_sel:[1,0]
	v_pk_add_f32 v[24:25], v[152:153], v[24:25]
	v_pk_mul_f32 v[44:45], v[156:157], v[44:45]
	v_pk_fma_f32 v[12:13], v[158:159], v[14:15], v[12:13]
	v_pk_fma_f32 v[14:15], v[150:151], v[14:15], v[44:45]
	v_pk_mul_f32 v[26:27], v[24:25], v[54:55]
	v_pk_fma_f32 v[24:25], v[154:155], v[56:57], v[50:51]
	v_pk_add_f32 v[12:13], v[152:153], v[12:13]
	v_pk_fma_f32 v[14:15], v[158:159], v[42:43], v[14:15]
	v_pk_mul_f32 v[12:13], v[12:13], v[24:25]
	v_pk_fma_f32 v[24:25], v[154:155], v[48:49], v[46:47]
	v_pk_add_f32 v[14:15], v[152:153], v[14:15]
	v_cvt_f32_f16_e32 v41, v30
	v_cvt_f32_f16_e32 v40, v31
	v_mov_b32_e32 v39, v43
	v_pk_mul_f32 v[14:15], v[14:15], v[24:25]
	v_pk_mul_f32 v[24:25], v[150:151], v[42:43]
	v_cvt_f32_f16_e32 v43, v98
	v_cvt_f32_f16_e32 v42, v99
	s_lshl_b32 s10, s60, 1
	v_mov_b32_e32 v53, v38
	v_pk_fma_f32 v[24:25], v[156:157], v[38:39], v[24:25] op_sel:[0,0,1] op_sel_hi:[1,1,0]
	s_or_b32 s10, s10, 1
	v_pk_fma_f32 v[24:25], v[158:159], v[52:53], v[24:25]
	s_lshl_b32 s60, s10, 11
	v_pk_add_f32 v[24:25], v[152:153], v[24:25]
	v_pk_fma_f32 v[38:39], v[154:155], v[42:43], v[40:41]
	s_add_i32 s60, s60, s44
	s_and_b64 vcc, exec, s[6:7]
	v_pk_mul_f32 v[24:25], v[24:25], v[38:39]
	s_cbranch_vccnz .LBB0_1813
	v_lshlrev_b32_e32 v38, 16, v8
	v_and_b32_e32 v39, 0xffff0000, v8
	v_mul_f32_e32 v8, 0xbfb8aa3b, v38
	v_exp_f32_e32 v8, v8
	v_mul_f32_e32 v40, 0xbfb8aa3b, v39
	v_exp_f32_e32 v41, v40
	s_ashr_i32 s61, s60, 31
	v_add_f32_e32 v8, 1.0, v8
	v_rcp_f32_e32 v40, v8
	v_add_f32_e32 v8, 1.0, v41
	v_rcp_f32_e32 v41, v8
	v_lshlrev_b32_e32 v8, 16, v9
	v_and_b32_e32 v9, 0xffff0000, v9
	s_lshl_b64 s[92:93], s[60:61], 13
	v_pk_mul_f32 v[38:39], v[40:41], v[38:39]
	v_mul_f32_e32 v40, 0xbfb8aa3b, v8
	v_mul_f32_e32 v41, 0xbfb8aa3b, v9
	v_exp_f32_e32 v40, v40
	v_exp_f32_e32 v41, v41
	v_pk_mul_f32 v[26:27], v[38:39], v[26:27]
	v_add_f32_e32 v38, 1.0, v40
	v_add_f32_e32 v39, 1.0, v41
	v_rcp_f32_e32 v38, v38
	v_rcp_f32_e32 v39, v39
	v_lshlrev_b32_e32 v40, 16, v10
	v_and_b32_e32 v41, 0xffff0000, v10
	v_mul_f32_e32 v10, 0xbfb8aa3b, v40
	v_pk_mul_f32 v[8:9], v[38:39], v[8:9]
	v_lshlrev_b32_e32 v38, 16, v11
	v_mul_f32_e32 v42, 0xbfb8aa3b, v41
	v_and_b32_e32 v39, 0xffff0000, v11
	v_mul_f32_e32 v11, 0xbfb8aa3b, v38
	v_exp_f32_e32 v10, v10
	v_exp_f32_e32 v42, v42
	v_exp_f32_e32 v43, v11
	v_mul_f32_e32 v11, 0xbfb8aa3b, v39
	v_exp_f32_e32 v44, v11
	v_add_f32_e32 v10, 1.0, v10
	v_add_f32_e32 v42, 1.0, v42
	v_rcp_f32_e32 v10, v10
	v_rcp_f32_e32 v11, v42
	v_add_f32_e32 v42, 1.0, v43
	v_add_f32_e32 v43, 1.0, v44
	v_rcp_f32_e32 v42, v42
	v_rcp_f32_e32 v43, v43
	v_pk_mul_f32 v[12:13], v[8:9], v[12:13]
	v_pk_mul_f32 v[8:9], v[10:11], v[40:41]
	s_nop 0
	v_pk_mul_f32 v[10:11], v[8:9], v[14:15]
	v_pk_mul_f32 v[8:9], v[42:43], v[38:39]
	v_cvt_pk_bf16_f32 v10, v10, v11
	v_pk_mul_f32 v[14:15], v[8:9], v[24:25] op_sel:[0,1] op_sel_hi:[1,0]
	v_cvt_pk_bf16_f32 v8, v26, v27
	v_cvt_pk_bf16_f32 v9, v12, v13
	v_cvt_pk_bf16_f32 v11, v14, v15
	v_lshl_add_u64 v[12:13], v[162:163], 0, s[92:93]
	global_store_dwordx4 v[12:13], v[8:11], off
	s_branch .LBB0_1814

.LBB0_1814:
	s_waitcnt vmcnt(5)
	v_lshlrev_b32_e32 v10, 16, v29
	v_cndmask_b32_e64 v26, 0, v10, s[4:5]
	v_lshlrev_b32_e32 v10, 16, v4
	s_waitcnt vmcnt(4)
	v_lshlrev_b32_e32 v11, 16, v28
	v_and_b32_e32 v4, 0xffff0000, v4
	v_cndmask_b32_e64 v28, 0, v11, s[0:1]
	v_mov_b32_e32 v29, v4
	v_cvt_f32_f16_sdwa v9, v37 dst_sel:DWORD dst_unused:UNUSED_PAD src0_sel:WORD_1
	v_cvt_f32_f16_sdwa v8, v35 dst_sel:DWORD dst_unused:UNUSED_PAD src0_sel:WORD_1
	v_cvt_f32_f16_sdwa v39, v105 dst_sel:DWORD dst_unused:UNUSED_PAD src0_sel:WORD_1
	v_cvt_f32_f16_sdwa v38, v104 dst_sel:DWORD dst_unused:UNUSED_PAD src0_sel:WORD_1
	v_pk_mul_f32 v[28:29], v[170:171], v[28:29]
	v_cvt_f32_f16_sdwa v13, v36 dst_sel:DWORD dst_unused:UNUSED_PAD src0_sel:WORD_1
	v_cvt_f32_f16_sdwa v12, v33 dst_sel:DWORD dst_unused:UNUSED_PAD src0_sel:WORD_1
	v_pk_fma_f32 v[10:11], v[168:169], v[10:11], v[28:29] op_sel_hi:[1,0,1]
	v_cvt_f32_f16_sdwa v29, v107 dst_sel:DWORD dst_unused:UNUSED_PAD src0_sel:WORD_1
	v_cvt_f32_f16_sdwa v28, v106 dst_sel:DWORD dst_unused:UNUSED_PAD src0_sel:WORD_1
	v_and_b32_e32 v36, 0xffff0000, v5
	v_lshlrev_b32_e32 v5, 16, v5
	v_pk_fma_f32 v[10:11], v[158:159], v[4:5], v[10:11]
	v_and_b32_e32 v37, 16, v6
	v_pk_fma_f32 v[8:9], v[154:155], v[38:39], v[8:9] neg_lo:[0,0,1] neg_hi:[0,0,1]
	v_pk_add_f32 v[10:11], v[152:153], v[10:11]
	v_cvt_f32_f16_sdwa v15, v34 dst_sel:DWORD dst_unused:UNUSED_PAD src0_sel:WORD_1
	v_pk_mul_f32 v[10:11], v[10:11], v[8:9]
	v_pk_fma_f32 v[8:9], v[154:155], v[28:29], v[12:13] neg_lo:[0,0,1] neg_hi:[0,0,1]
	v_pk_mov_b32 v[12:13], v[4:5], v[36:37] op_sel:[1,0]
	v_cvt_f32_f16_sdwa v14, v32 dst_sel:DWORD dst_unused:UNUSED_PAD src0_sel:WORD_1
	v_pk_mul_f32 v[12:13], v[156:157], v[12:13]
	v_cvt_f32_f16_sdwa v25, v30 dst_sel:DWORD dst_unused:UNUSED_PAD src0_sel:WORD_1
	v_pk_fma_f32 v[4:5], v[150:151], v[4:5], v[12:13]
	v_cvt_f32_f16_sdwa v13, v97 dst_sel:DWORD dst_unused:UNUSED_PAD src0_sel:WORD_1
	v_cvt_f32_f16_sdwa v12, v96 dst_sel:DWORD dst_unused:UNUSED_PAD src0_sel:WORD_1
	v_and_b32_e32 v30, 0xffff0000, v7
	v_lshlrev_b32_e32 v33, 16, v7
	v_and_b32_e32 v35, 16, v7
	v_and_b32_e32 v34, 0xffff0000, v6
	v_lshlrev_b32_e32 v7, 16, v6
	v_mov_b32_e32 v6, v36
	v_pk_fma_f32 v[4:5], v[158:159], v[6:7], v[4:5]
	v_mov_b32_e32 v32, v34
	v_pk_add_f32 v[4:5], v[152:153], v[4:5]
	v_cvt_f32_f16_sdwa v24, v31 dst_sel:DWORD dst_unused:UNUSED_PAD src0_sel:WORD_1
	v_pk_mul_f32 v[4:5], v[4:5], v[8:9]
	v_pk_fma_f32 v[8:9], v[154:155], v[12:13], v[14:15] neg_lo:[0,0,1] neg_hi:[0,0,1]
	v_pk_mov_b32 v[12:13], v[6:7], v[34:35] op_sel:[1,0]
	v_mov_b32_e32 v31, v33
	v_pk_mul_f32 v[12:13], v[156:157], v[12:13]
	v_mov_b32_e32 v27, v30
	v_pk_fma_f32 v[6:7], v[150:151], v[6:7], v[12:13]
	v_cvt_f32_f16_sdwa v13, v98 dst_sel:DWORD dst_unused:UNUSED_PAD src0_sel:WORD_1
	v_pk_fma_f32 v[6:7], v[158:159], v[32:33], v[6:7]
	v_cvt_f32_f16_sdwa v12, v99 dst_sel:DWORD dst_unused:UNUSED_PAD src0_sel:WORD_1
	v_pk_add_f32 v[6:7], v[152:153], v[6:7]
	s_and_b64 vcc, exec, s[6:7]
	v_pk_mul_f32 v[6:7], v[6:7], v[8:9]
	v_pk_mul_f32 v[8:9], v[150:151], v[32:33]
	v_pk_fma_f32 v[12:13], v[154:155], v[12:13], v[24:25] neg_lo:[0,0,1] neg_hi:[0,0,1]
	v_pk_fma_f32 v[8:9], v[156:157], v[30:31], v[8:9] op_sel:[0,0,1] op_sel_hi:[1,1,0]
	s_nop 0
	v_pk_fma_f32 v[8:9], v[158:159], v[26:27], v[8:9]
	s_nop 0
	v_pk_add_f32 v[8:9], v[152:153], v[8:9]
	s_nop 0
	v_pk_mul_f32 v[8:9], v[8:9], v[12:13]
	s_cbranch_vccnz .LBB0_1816
	v_lshlrev_b32_e32 v12, 16, v0
	v_and_b32_e32 v13, 0xffff0000, v0
	v_mul_f32_e32 v0, 0xbfb8aa3b, v12
	v_exp_f32_e32 v0, v0
	v_mul_f32_e32 v14, 0xbfb8aa3b, v13
	v_exp_f32_e32 v15, v14
	s_ashr_i32 s61, s60, 31
	v_add_f32_e32 v0, 1.0, v0
	v_rcp_f32_e32 v14, v0
	v_add_f32_e32 v0, 1.0, v15
	v_rcp_f32_e32 v15, v0
	v_lshlrev_b32_e32 v0, 16, v1
	v_and_b32_e32 v1, 0xffff0000, v1
	s_lshl_b64 s[6:7], s[60:61], 13
	v_pk_mul_f32 v[12:13], v[14:15], v[12:13]
	v_mul_f32_e32 v14, 0xbfb8aa3b, v0
	v_mul_f32_e32 v15, 0xbfb8aa3b, v1
	v_exp_f32_e32 v14, v14
	v_exp_f32_e32 v15, v15
	v_pk_mul_f32 v[10:11], v[12:13], v[10:11]
	v_add_f32_e32 v12, 1.0, v14
	v_add_f32_e32 v13, 1.0, v15
	v_rcp_f32_e32 v12, v12
	v_rcp_f32_e32 v13, v13
	v_lshlrev_b32_e32 v14, 16, v2
	v_and_b32_e32 v15, 0xffff0000, v2
	v_mul_f32_e32 v2, 0xbfb8aa3b, v14
	v_pk_mul_f32 v[0:1], v[12:13], v[0:1]
	v_lshlrev_b32_e32 v12, 16, v3
	v_mul_f32_e32 v24, 0xbfb8aa3b, v15
	v_and_b32_e32 v13, 0xffff0000, v3
	v_mul_f32_e32 v3, 0xbfb8aa3b, v12
	v_exp_f32_e32 v2, v2
	v_exp_f32_e32 v24, v24
	v_exp_f32_e32 v25, v3
	v_mul_f32_e32 v3, 0xbfb8aa3b, v13
	v_exp_f32_e32 v26, v3
	v_add_f32_e32 v2, 1.0, v2
	v_add_f32_e32 v24, 1.0, v24
	v_rcp_f32_e32 v2, v2
	v_rcp_f32_e32 v3, v24
	v_add_f32_e32 v24, 1.0, v25
	v_add_f32_e32 v25, 1.0, v26
	v_rcp_f32_e32 v24, v24
	v_rcp_f32_e32 v25, v25
	v_pk_mul_f32 v[4:5], v[0:1], v[4:5]
	v_pk_mul_f32 v[0:1], v[2:3], v[14:15]
	s_nop 0
	v_pk_mul_f32 v[2:3], v[0:1], v[6:7]
	v_pk_mul_f32 v[0:1], v[24:25], v[12:13]
	v_cvt_pk_bf16_f32 v2, v2, v3
	v_pk_mul_f32 v[6:7], v[0:1], v[8:9] op_sel:[0,1] op_sel_hi:[1,0]
	v_cvt_pk_bf16_f32 v1, v4, v5
	v_lshl_add_u64 v[4:5], v[162:163], 0, s[6:7]
	v_add_co_u32_e32 v4, vcc, 0x800000, v4
	v_cvt_pk_bf16_f32 v0, v10, v11
	v_cvt_pk_bf16_f32 v3, v6, v7
	v_addc_co_u32_e32 v5, vcc, 0, v5, vcc
	global_store_dwordx4 v[4:5], v[0:3], off
	s_and_b64 vcc, exec, s[8:9]
	s_cbranch_vccz .LBB0_1817
	s_branch .LBB0_1818

.LBB0_1879:
	v_lshl_add_u64 v[136:137], s[78:79], 0, v[176:177]
	v_add_co_u32_e32 v128, vcc, s29, v136
	v_lshl_add_u64 v[152:153], s[78:79], 0, v[174:175]
	s_nop 0
	v_addc_co_u32_e32 v129, vcc, 0, v137, vcc
	v_add_co_u32_e32 v132, vcc, s30, v136
	s_add_i32 s19, s18, 1
	s_nop 0
	v_addc_co_u32_e32 v133, vcc, 0, v137, vcc
	v_add_co_u32_e32 v138, vcc, s31, v136
	global_load_dwordx4 v[128:131], v[128:129], off
	s_nop 0
	global_load_dwordx4 v[132:135], v[132:133], off
	v_addc_co_u32_e32 v139, vcc, 0, v137, vcc
	v_add_co_u32_e32 v140, vcc, s36, v136
	s_nop 1
	v_addc_co_u32_e32 v141, vcc, 0, v137, vcc
	v_add_co_u32_e32 v144, vcc, s37, v152
	global_load_dwordx4 v[136:139], v[138:139], off
	s_nop 0
	global_load_dwordx4 v[140:143], v[140:141], off
	v_addc_co_u32_e32 v145, vcc, 0, v153, vcc
	v_add_co_u32_e32 v148, vcc, s38, v152
	s_nop 1
	v_addc_co_u32_e32 v149, vcc, 0, v153, vcc
	v_add_co_u32_e32 v154, vcc, s39, v152
	global_load_dwordx4 v[144:147], v[144:145], off offset:128
	s_nop 0
	global_load_dwordx4 v[148:151], v[148:149], off offset:128
	v_addc_co_u32_e32 v155, vcc, 0, v153, vcc
	v_add_co_u32_e32 v156, vcc, s40, v152
	s_nop 1
	v_addc_co_u32_e32 v157, vcc, 0, v153, vcc
	global_load_dwordx4 v[152:155], v[154:155], off offset:128
	s_nop 0
	global_load_dwordx4 v[156:159], v[156:157], off offset:128
	s_bitcmp1_b32 s18, 0
	s_cselect_b32 s18, 0x12000, 0
	s_add_i32 s18, s18, 0
	v_add_u32_e32 v179, s18, v173
	v_add_u32_e32 v188, s18, v196
	v_add_u32_e32 v183, s18, v178
	ds_read_b64_tr_b16 v[186:187], v179 offset:2304
	ds_read_b64_tr_b16 v[184:185], v179
	ds_read_b64_tr_b16 v[198:199], v179 offset:64
	ds_read_b64_tr_b16 v[202:203], v179 offset:128
	ds_read_b64_tr_b16 v[206:207], v179 offset:192
	ds_read_b128 v[210:213], v183 offset:36864
	ds_read_b64_tr_b16 v[200:201], v179 offset:2368
	ds_read_b64_tr_b16 v[204:205], v179 offset:2432
	ds_read_b64_tr_b16 v[208:209], v179 offset:2496
	ds_read_b128 v[214:217], v183 offset:36896
	ds_read_b128 v[218:221], v188 offset:4608
	ds_read_b128 v[222:225], v188 offset:4640
	s_waitcnt lgkmcnt(6)
	v_mfma_f32_32x32x16_bf16 v[112:127], v[184:187], v[210:213], v[112:127]
	s_bitcmp1_b32 s19, 0
	s_cselect_b32 s20, 0x12000, 0
	s_add_i32 s20, s20, 0
	v_lshl_add_u64 v[174:175], v[174:175], 0, s[10:11]
	v_lshl_add_u64 v[176:177], v[176:177], 0, s[12:13]
	s_mov_b32 s18, s19
	s_cmp_lg_u32 s19, 15
	s_waitcnt lgkmcnt(1)
	v_mfma_f32_32x32x16_bf16 v[96:111], v[184:187], v[218:221], v[96:111]
	ds_read_b64_tr_b16 v[186:187], v179 offset:11520
	v_mfma_f32_32x32x16_bf16 v[64:79], v[198:201], v[210:213], v[64:79]
	v_mfma_f32_32x32x16_bf16 v[80:95], v[198:201], v[218:221], v[80:95]
	v_mfma_f32_32x32x16_bf16 v[32:47], v[202:205], v[210:213], v[32:47]
	v_mfma_f32_32x32x16_bf16 v[48:63], v[202:205], v[218:221], v[48:63]
	v_mfma_f32_32x32x16_bf16 v[0:15], v[206:209], v[210:213], v[0:15]
	v_mfma_f32_32x32x16_bf16 v[16:31], v[206:209], v[218:221], v[16:31]
	ds_read_b64_tr_b16 v[184:185], v179 offset:9216
	ds_read_b64_tr_b16 v[198:199], v179 offset:9280
	ds_read_b64_tr_b16 v[202:203], v179 offset:9344
	ds_read_b64_tr_b16 v[206:207], v179 offset:9408
	ds_read_b64_tr_b16 v[200:201], v179 offset:11584
	ds_read_b64_tr_b16 v[204:205], v179 offset:11648
	ds_read_b64_tr_b16 v[208:209], v179 offset:11712
	s_waitcnt lgkmcnt(6)
	v_mfma_f32_32x32x16_bf16 v[112:127], v[184:187], v[214:217], v[112:127]
	v_mfma_f32_32x32x16_bf16 v[96:111], v[184:187], v[222:225], v[96:111]
	s_waitcnt lgkmcnt(2)
	v_mfma_f32_32x32x16_bf16 v[64:79], v[198:201], v[214:217], v[64:79]
	v_mfma_f32_32x32x16_bf16 v[80:95], v[198:201], v[222:225], v[80:95]
	ds_read_b64_tr_b16 v[186:187], v179 offset:20736
	ds_read_b64_tr_b16 v[184:185], v179 offset:18432
	ds_read_b64_tr_b16 v[198:199], v179 offset:18496
	s_waitcnt lgkmcnt(4)
	v_mfma_f32_32x32x16_bf16 v[32:47], v[202:205], v[214:217], v[32:47]
	v_mfma_f32_32x32x16_bf16 v[48:63], v[202:205], v[222:225], v[48:63]
	s_waitcnt lgkmcnt(3)
	v_mfma_f32_32x32x16_bf16 v[0:15], v[206:209], v[214:217], v[0:15]
	v_mfma_f32_32x32x16_bf16 v[16:31], v[206:209], v[222:225], v[16:31]
	ds_read_b64_tr_b16 v[202:203], v179 offset:18560
	ds_read_b64_tr_b16 v[206:207], v179 offset:18624
	ds_read_b128 v[210:213], v183 offset:36928
	ds_read_b64_tr_b16 v[200:201], v179 offset:20800
	ds_read_b64_tr_b16 v[204:205], v179 offset:20864
	ds_read_b64_tr_b16 v[208:209], v179 offset:20928
	ds_read_b128 v[214:217], v183 offset:36960
	ds_read_b128 v[218:221], v188 offset:4672
	ds_read_b128 v[222:225], v188 offset:4704
	v_add_u32_e32 v183, s20, v172
	s_waitcnt lgkmcnt(6)
	v_mfma_f32_32x32x16_bf16 v[112:127], v[184:187], v[210:213], v[112:127]
	s_waitcnt lgkmcnt(1)
	v_mfma_f32_32x32x16_bf16 v[96:111], v[184:187], v[218:221], v[96:111]
	ds_read_b64_tr_b16 v[186:187], v179 offset:29952
	v_mfma_f32_32x32x16_bf16 v[64:79], v[198:201], v[210:213], v[64:79]
	v_mfma_f32_32x32x16_bf16 v[80:95], v[198:201], v[218:221], v[80:95]
	v_mfma_f32_32x32x16_bf16 v[32:47], v[202:205], v[210:213], v[32:47]
	v_mfma_f32_32x32x16_bf16 v[48:63], v[202:205], v[218:221], v[48:63]
	v_mfma_f32_32x32x16_bf16 v[0:15], v[206:209], v[210:213], v[0:15]
	v_mfma_f32_32x32x16_bf16 v[16:31], v[206:209], v[218:221], v[16:31]
	ds_read_b64_tr_b16 v[184:185], v179 offset:27648
	ds_read_b64_tr_b16 v[198:199], v179 offset:27712
	ds_read_b64_tr_b16 v[202:203], v179 offset:27776
	ds_read_b64_tr_b16 v[206:207], v179 offset:27840
	ds_read_b64_tr_b16 v[200:201], v179 offset:30016
	ds_read_b64_tr_b16 v[204:205], v179 offset:30080
	ds_read_b64_tr_b16 v[208:209], v179 offset:30144
	v_add_u32_e32 v179, s20, v170
	s_waitcnt vmcnt(7)
	ds_write_b128 v179, v[128:131]
	s_waitcnt vmcnt(6)
	ds_write_b128 v179, v[132:135] offset:9216
	s_waitcnt vmcnt(5)
	ds_write_b128 v179, v[136:139] offset:18432
	s_waitcnt vmcnt(4)
	ds_write_b128 v179, v[140:143] offset:27648
	s_waitcnt vmcnt(3)
	ds_write_b128 v183, v[144:147] offset:36864
	s_waitcnt vmcnt(2)
	ds_write_b128 v183, v[148:151] offset:46080
	s_waitcnt vmcnt(1)
	ds_write_b128 v183, v[152:155] offset:55296
	s_waitcnt vmcnt(0)
	ds_write_b128 v183, v[156:159] offset:64512
	s_waitcnt lgkmcnt(0)
	s_barrier
	v_mfma_f32_32x32x16_bf16 v[112:127], v[184:187], v[214:217], v[112:127]
	v_mfma_f32_32x32x16_bf16 v[96:111], v[184:187], v[222:225], v[96:111]
	v_mfma_f32_32x32x16_bf16 v[64:79], v[198:201], v[214:217], v[64:79]
	v_mfma_f32_32x32x16_bf16 v[80:95], v[198:201], v[222:225], v[80:95]
	v_mfma_f32_32x32x16_bf16 v[32:47], v[202:205], v[214:217], v[32:47]
	v_mfma_f32_32x32x16_bf16 v[48:63], v[202:205], v[222:225], v[48:63]
	v_mfma_f32_32x32x16_bf16 v[0:15], v[206:209], v[214:217], v[0:15]
	v_mfma_f32_32x32x16_bf16 v[16:31], v[206:209], v[222:225], v[16:31]
	s_cbranch_scc1 .LBB0_1879
	v_add_co_u32_e32 v128, vcc, 0x780000, v160
	s_lshl_b32 s16, s16, 8
	s_nop 0
	v_addc_co_u32_e32 v129, vcc, 0, v161, vcc
	v_add_co_u32_e32 v130, vcc, 0x7a0000, v160
	s_lshr_b32 s18, s54, 6
	s_nop 0
	v_addc_co_u32_e32 v131, vcc, 0, v161, vcc
	v_add_co_u32_e32 v132, vcc, 0x7c0000, v160
	s_nop 1
	v_addc_co_u32_e32 v133, vcc, 0, v161, vcc
	global_load_dwordx4 v[176:179], v[130:131], off
	global_load_dwordx4 v[184:187], v[132:133], off
	v_add_co_u32_e32 v130, vcc, 0x7e0000, v160
	v_add3_u32 v160, v171, v180, s41
	s_nop 0
	v_addc_co_u32_e32 v131, vcc, 0, v161, vcc
	global_load_dwordx4 v[198:201], v[128:129], off
	global_load_dwordx4 v[202:205], v[162:163], off offset:1920
	global_load_dwordx4 v[206:209], v[130:131], off
	global_load_dwordx4 v[210:213], v[164:165], off offset:1920
	global_load_dwordx4 v[214:217], v[166:167], off offset:1920
	global_load_dwordx4 v[218:221], v[168:169], off offset:1920
	v_add_u32_e32 v128, v181, v182
	v_add_u32_e32 v152, 64, v128
	v_add_u32_e32 v153, 0x80, v128
	v_add_u32_e32 v154, 0xc0, v128
	s_add_i32 s19, 0, 0x12000
	v_add_u32_e32 v130, s19, v173
	v_add_u32_e32 v134, s19, v152
	v_add_u32_e32 v132, s19, v196
	ds_read_b64_tr_b16 v[128:129], v130
	ds_read_b64_tr_b16 v[130:131], v130 offset:2304
	ds_read_b128 v[144:147], v132
	v_add_u32_e32 v136, s19, v160
	ds_read_b64_tr_b16 v[132:133], v134
	ds_read_b64_tr_b16 v[134:135], v134 offset:2304
	ds_read_b128 v[222:225], v136
	s_waitcnt lgkmcnt(3)
	v_mfma_f32_32x32x16_bf16 v[112:127], v[128:131], v[144:147], v[112:127]
	v_add_u32_e32 v148, s44, v173
	v_add_u32_e32 v149, s44, v152
	v_add_u32_e32 v155, s45, v160
	v_add_u32_e32 v161, s47, v196
	s_mulk_i32 s18, 0x2200
	s_add_i32 s53, s53, s52
	s_or_b32 s16, s17, s16
	s_waitcnt lgkmcnt(0)
	v_mfma_f32_32x32x16_bf16 v[96:111], v[128:131], v[222:225], v[96:111]
	v_add_u32_e32 v128, s19, v153
	v_add_u32_e32 v129, s19, v154
	ds_read_b64_tr_b16 v[140:141], v128
	ds_read_b64_tr_b16 v[142:143], v128 offset:2304
	ds_read_b64_tr_b16 v[226:227], v129
	ds_read_b64_tr_b16 v[228:229], v129 offset:2304
	v_add_u32_e32 v128, s42, v173
	v_add_u32_e32 v129, s42, v152
	ds_read_b64_tr_b16 v[156:157], v128
	ds_read_b64_tr_b16 v[158:159], v128 offset:2304
	ds_read_b64_tr_b16 v[180:181], v129
	ds_read_b64_tr_b16 v[182:183], v129 offset:2304
	v_add_u32_e32 v128, s42, v153
	v_mfma_f32_32x32x16_bf16 v[64:79], v[132:135], v[144:147], v[64:79]
	v_add_u32_e32 v130, s42, v154
	ds_read_b64_tr_b16 v[164:165], v128
	ds_read_b64_tr_b16 v[166:167], v128 offset:2304
	ds_read_b64_tr_b16 v[128:129], v130
	ds_read_b64_tr_b16 v[130:131], v130 offset:2304
	v_add_u32_e32 v152, s46, v152
	s_add_i32 s19, s19, s18
	s_ashr_i32 s18, s53, 12
	s_mulk_i32 s18, 0xc00
	s_ashr_i32 s17, s16, 31
	v_mfma_f32_32x32x16_bf16 v[80:95], v[132:135], v[222:225], v[80:95]
	v_add_u32_e32 v132, s43, v196
	v_add_u32_e32 v133, s43, v160
	ds_read_b128 v[136:139], v132
	ds_read_b128 v[132:135], v133
	ds_read_b64_tr_b16 v[230:231], v148
	ds_read_b64_tr_b16 v[232:233], v148 offset:2304
	ds_read_b64_tr_b16 v[234:235], v149
	ds_read_b64_tr_b16 v[236:237], v149 offset:2304
	v_add_u32_e32 v148, s44, v153
	s_waitcnt lgkmcnt(5)
	v_mfma_f32_32x32x16_bf16 v[112:127], v[156:159], v[136:139], v[112:127]
	s_waitcnt lgkmcnt(4)
	v_mfma_f32_32x32x16_bf16 v[96:111], v[156:159], v[132:135], v[96:111]
	v_add_u32_e32 v156, s47, v160
	v_mfma_f32_32x32x16_bf16 v[32:47], v[140:143], v[144:147], v[32:47]
	v_mfma_f32_32x32x16_bf16 v[48:63], v[140:143], v[222:225], v[48:63]
	v_add_u32_e32 v142, s44, v154
	ds_read_b64_tr_b16 v[168:169], v148
	ds_read_b64_tr_b16 v[170:171], v148 offset:2304
	ds_read_b64_tr_b16 v[140:141], v142
	ds_read_b64_tr_b16 v[142:143], v142 offset:2304
	v_add_u32_e32 v148, s45, v196
	v_add_u32_e32 v154, s46, v154
	v_mfma_f32_32x32x16_bf16 v[0:15], v[226:229], v[144:147], v[0:15]
	ds_read_b128 v[148:151], v148
	ds_read_b128 v[144:147], v155
	v_add_u32_e32 v155, s46, v173
	ds_read_b64_tr_b16 v[238:239], v155
	ds_read_b64_tr_b16 v[240:241], v155 offset:2304
	ds_read_b64_tr_b16 v[242:243], v152
	ds_read_b64_tr_b16 v[244:245], v152 offset:2304
	v_add_u32_e32 v152, s46, v153
	ds_read_b64_tr_b16 v[172:173], v152
	ds_read_b64_tr_b16 v[174:175], v152 offset:2304
	ds_read_b64_tr_b16 v[152:153], v154
	ds_read_b64_tr_b16 v[154:155], v154 offset:2304
	ds_read_b128 v[160:163], v161
	ds_read_b128 v[156:159], v156
	s_waitcnt vmcnt(5)
	ds_write_b128 v195, v[198:201]
	ds_write_b128 v195, v[176:179] offset:9216
	ds_write_b128 v195, v[184:187] offset:18432
	s_waitcnt vmcnt(3)
	ds_write_b128 v195, v[206:209] offset:27648
	s_waitcnt lgkmcnt(14)
	v_mfma_f32_32x32x16_bf16 v[112:127], v[230:233], v[148:151], v[112:127]
	v_lshlrev_b32_e32 v176, 3, v190
	v_lshrrev_b32_e32 v178, 3, v193
	v_and_b32_e32 v179, 56, v176
	v_lshlrev_b32_e32 v177, 2, v191
	v_lshlrev_b32_e32 v188, 2, v179
	v_mul_u32_u24_e32 v176, 0x110, v178
	v_mul_u32_u24_e32 v184, 0x440, v192
	v_mfma_f32_32x32x16_bf16 v[96:111], v[230:233], v[144:147], v[96:111]
	v_add3_u32 v176, s19, v188, v176
	v_add3_u32 v177, s19, v177, v184
	s_ashr_i32 s19, s18, 31
	s_lshl_b64 s[18:19], s[18:19], 2
	s_add_u32 s20, s78, s18
	s_addc_u32 s21, s79, s19
	s_lshl_b64 s[18:19], s[16:17], 2
	s_waitcnt lgkmcnt(5)
	v_mfma_f32_32x32x16_bf16 v[112:127], v[238:241], v[160:163], v[112:127]
	ds_write_b128 v194, v[202:205] offset:36864
	s_waitcnt vmcnt(2)
	ds_write_b128 v194, v[210:213] offset:46080
	s_waitcnt vmcnt(1)
	ds_write_b128 v194, v[214:217] offset:55296
	s_waitcnt vmcnt(0)
	ds_write_b128 v194, v[218:221] offset:64512
	s_waitcnt lgkmcnt(0)
	s_barrier
	s_add_u32 s18, s20, s18
	s_addc_u32 s19, s21, s19
	s_lshl_b64 s[16:17], s[16:17], 1
	v_mfma_f32_32x32x16_bf16 v[96:111], v[238:241], v[156:159], v[96:111]
	s_nop 11
	ds_write2_b32 v177, v112, v96 offset1:32
	ds_write2_b32 v177, v113, v97 offset0:68 offset1:100
	ds_write2_b32 v177, v114, v98 offset0:136 offset1:168
	ds_write2_b32 v177, v115, v99 offset0:204 offset1:236
	v_add_u32_e32 v112, 0x800, v177
	v_add_u32_e32 v114, 0xa00, v177
	v_add_u32_e32 v113, 0x1000, v177
	ds_write2_b32 v112, v116, v100 offset0:32 offset1:64
	ds_write2_b32 v112, v117, v101 offset0:100 offset1:132
	ds_write2_b32 v112, v118, v102 offset0:168 offset1:200
	ds_write2_b32 v114, v119, v103 offset0:108 offset1:140
	ds_write2_b32 v113, v120, v104 offset0:64 offset1:96
	ds_write2_b32 v113, v121, v105 offset0:132 offset1:164
	ds_write2_b32 v113, v122, v106 offset0:200 offset1:232
	v_add_u32_e32 v104, 0x1400, v177
	v_add_u32_e32 v105, 0x1800, v177
	v_or_b32_e32 v96, s53, v178
	ds_write2_b32 v104, v123, v107 offset0:12 offset1:44
	ds_write2_b32 v105, v124, v108 offset0:96 offset1:128
	ds_write2_b32 v105, v125, v109 offset0:164 offset1:196
	v_lshl_add_u64 v[102:103], s[18:19], 0, v[188:189]
	s_add_u32 s18, s6, s16
	v_or_b32_e32 v124, 8, v96
	v_add_u32_e32 v106, 0x1a00, v177
	v_add_u32_e32 v107, 0x1c00, v177
	s_addc_u32 s19, s7, s17
	v_lshlrev_b32_e32 v188, 1, v179
	v_ashrrev_i32_e32 v97, 31, v96
	v_ashrrev_i32_e32 v125, 31, v124
	ds_write2_b32 v106, v126, v110 offset0:104 offset1:136
	ds_write2_b32 v107, v127, v111 offset0:44 offset1:76
	v_lshl_add_u64 v[98:99], s[18:19], 0, v[188:189]
	v_lshlrev_b64 v[186:187], 11, v[96:97]
	v_lshlrev_b64 v[198:199], 11, v[124:125]
	s_waitcnt lgkmcnt(0)
	v_lshl_add_u64 v[100:101], v[98:99], 0, v[186:187]
	v_lshl_add_u64 v[124:125], v[98:99], 0, v[198:199]
	global_load_dwordx4 v[108:111], v[100:101], off
	v_or_b32_e32 v178, 16, v96
	global_load_dwordx4 v[124:127], v[124:125], off
	v_add_co_u32_e32 v100, vcc, s50, v102
	v_ashrrev_i32_e32 v179, 31, v178
	s_nop 0
	v_addc_co_u32_e32 v101, vcc, 0, v103, vcc
	global_load_dwordx4 v[116:119], v[100:101], off
	v_lshl_add_u64 v[102:103], v[102:103], 0, s[14:15]
	global_load_dwordx4 v[120:123], v[102:103], off offset:16
	v_lshlrev_b64 v[200:201], 11, v[178:179]
	v_lshl_add_u64 v[178:179], v[98:99], 0, v[200:201]
	v_mfma_f32_32x32x16_bf16 v[64:79], v[180:183], v[136:139], v[64:79]
	ds_read_b128 v[190:193], v176
	ds_read_b128 v[194:197], v176 offset:16
	v_lshl_add_u64 v[186:187], s[8:9], 0, v[186:187]
	v_lshl_add_u64 v[186:187], v[186:187], 0, s[16:17]
	v_lshl_add_u64 v[186:187], v[186:187], 0, v[188:189]
	s_add_i32 s51, s51, s33
	s_cmpk_lt_i32 s51, 0x200
	v_mfma_f32_32x32x16_bf16 v[80:95], v[180:183], v[132:135], v[80:95]
	global_load_dwordx4 v[178:181], v[178:179], off
	v_or_b32_e32 v182, 24, v96
	v_ashrrev_i32_e32 v183, 31, v182
	v_lshlrev_b64 v[202:203], 11, v[182:183]
	v_lshl_add_u64 v[182:183], v[98:99], 0, v[202:203]
	global_load_dwordx4 v[182:185], v[182:183], off
	s_waitcnt vmcnt(5)
	v_lshlrev_b32_e32 v204, 16, v108
	v_and_b32_e32 v205, 0xffff0000, v108
	v_mfma_f32_32x32x16_bf16 v[64:79], v[234:237], v[148:151], v[64:79]
	s_waitcnt vmcnt(3) lgkmcnt(1)
	v_fma_f32 v190, v116, v190, v204
	v_fma_f32 v191, v117, v191, v205
	v_cvt_pk_bf16_f32 v108, v190, v191
	v_lshlrev_b32_e32 v190, 16, v109
	v_and_b32_e32 v191, 0xffff0000, v109
	v_pk_fma_f32 v[190:191], v[118:119], v[192:193], v[190:191]
	v_mfma_f32_32x32x16_bf16 v[80:95], v[234:237], v[144:147], v[80:95]
	v_cvt_pk_bf16_f32 v109, v190, v191
	v_lshlrev_b32_e32 v190, 16, v110
	v_and_b32_e32 v191, 0xffff0000, v110
	s_waitcnt vmcnt(2) lgkmcnt(0)
	v_fma_f32 v190, v120, v194, v190
	v_fma_f32 v191, v121, v195, v191
	v_cvt_pk_bf16_f32 v110, v190, v191
	v_lshlrev_b32_e32 v190, 16, v111
	v_and_b32_e32 v191, 0xffff0000, v111
	v_pk_fma_f32 v[190:191], v[122:123], v[196:197], v[190:191]
	v_mfma_f32_32x32x16_bf16 v[64:79], v[242:245], v[160:163], v[64:79]
	v_cvt_pk_bf16_f32 v111, v190, v191
	ds_read_b128 v[190:193], v176 offset:2176
	global_store_dwordx4 v[186:187], v[108:111], off
	ds_read_b128 v[108:111], v176 offset:2192
	v_lshlrev_b32_e32 v186, 16, v124
	v_and_b32_e32 v187, 0xffff0000, v124
	s_waitcnt lgkmcnt(1)
	v_pk_fma_f32 v[186:187], v[116:117], v[190:191], v[186:187]
	v_mfma_f32_32x32x16_bf16 v[80:95], v[242:245], v[156:159], v[80:95]
	v_cvt_pk_bf16_f32 v124, v186, v187
	v_lshlrev_b32_e32 v186, 16, v125
	v_and_b32_e32 v187, 0xffff0000, v125
	v_fma_f32 v186, v118, v192, v186
	v_fma_f32 v187, v119, v193, v187
	v_cvt_pk_bf16_f32 v125, v186, v187
	v_lshlrev_b32_e32 v186, 16, v126
	v_and_b32_e32 v187, 0xffff0000, v126
	s_waitcnt lgkmcnt(0)
	v_pk_fma_f32 v[108:109], v[120:121], v[108:109], v[186:187]
	v_mfma_f32_32x32x16_bf16 v[32:47], v[164:167], v[136:139], v[32:47]
	v_cvt_pk_bf16_f32 v126, v108, v109
	v_lshlrev_b32_e32 v108, 16, v127
	v_and_b32_e32 v109, 0xffff0000, v127
	v_fma_f32 v108, v122, v110, v108
	v_fma_f32 v109, v123, v111, v109
	v_cvt_pk_bf16_f32 v127, v108, v109
	v_lshl_add_u64 v[108:109], s[8:9], 0, v[198:199]
	v_lshl_add_u64 v[108:109], v[108:109], 0, s[16:17]
	v_lshl_add_u64 v[186:187], v[108:109], 0, v[188:189]
	ds_read_b128 v[108:111], v176 offset:4352
	global_store_dwordx4 v[186:187], v[124:127], off
	ds_read_b128 v[124:127], v176 offset:4368
	s_waitcnt vmcnt(3)
	v_lshlrev_b32_e32 v186, 16, v178
	v_and_b32_e32 v187, 0xffff0000, v178
	v_lshlrev_b32_e32 v178, 16, v179
	v_and_b32_e32 v179, 0xffff0000, v179
	s_waitcnt lgkmcnt(1)
	v_pk_fma_f32 v[108:109], v[116:117], v[108:109], v[186:187]
	v_pk_fma_f32 v[110:111], v[118:119], v[110:111], v[178:179]
	v_cvt_pk_bf16_f32 v108, v108, v109
	v_cvt_pk_bf16_f32 v109, v110, v111
	v_lshlrev_b32_e32 v110, 16, v180
	v_and_b32_e32 v111, 0xffff0000, v180
	s_waitcnt lgkmcnt(0)
	v_pk_fma_f32 v[110:111], v[120:121], v[124:125], v[110:111]
	v_lshlrev_b32_e32 v124, 16, v181
	v_and_b32_e32 v125, 0xffff0000, v181
	v_pk_fma_f32 v[124:125], v[122:123], v[126:127], v[124:125]
	v_cvt_pk_bf16_f32 v110, v110, v111
	v_cvt_pk_bf16_f32 v111, v124, v125
	v_lshl_add_u64 v[124:125], s[8:9], 0, v[200:201]
	v_lshl_add_u64 v[124:125], v[124:125], 0, s[16:17]
	v_lshl_add_u64 v[178:179], v[124:125], 0, v[188:189]
	ds_read_b128 v[124:127], v176 offset:6528
	global_store_dwordx4 v[178:179], v[108:111], off
	ds_read_b128 v[108:111], v176 offset:6544
	s_waitcnt vmcnt(3)
	v_lshlrev_b32_e32 v178, 16, v182
	v_and_b32_e32 v179, 0xffff0000, v182
	s_waitcnt lgkmcnt(1)
	v_pk_fma_f32 v[116:117], v[116:117], v[124:125], v[178:179]
	v_lshlrev_b32_e32 v124, 16, v183
	v_and_b32_e32 v125, 0xffff0000, v183
	v_pk_fma_f32 v[118:119], v[118:119], v[126:127], v[124:125]
	v_cvt_pk_bf16_f32 v116, v116, v117
	v_cvt_pk_bf16_f32 v117, v118, v119
	v_lshlrev_b32_e32 v118, 16, v184
	v_and_b32_e32 v119, 0xffff0000, v184
	s_waitcnt lgkmcnt(0)
	v_pk_fma_f32 v[108:109], v[120:121], v[108:109], v[118:119]
	v_mfma_f32_32x32x16_bf16 v[48:63], v[164:167], v[132:135], v[48:63]
	v_cvt_pk_bf16_f32 v118, v108, v109
	v_lshlrev_b32_e32 v108, 16, v185
	v_and_b32_e32 v109, 0xffff0000, v185
	v_fma_f32 v108, v122, v110, v108
	v_fma_f32 v109, v123, v111, v109
	v_cvt_pk_bf16_f32 v119, v108, v109
	v_lshl_add_u64 v[108:109], s[8:9], 0, v[202:203]
	v_lshl_add_u64 v[108:109], v[108:109], 0, s[16:17]
	v_lshl_add_u64 v[108:109], v[108:109], 0, v[188:189]
	global_store_dwordx4 v[108:109], v[116:119], off
	s_waitcnt lgkmcnt(0)
	ds_write2_b32 v177, v64, v80 offset1:32
	ds_write2_b32 v177, v65, v81 offset0:68 offset1:100
	ds_write2_b32 v177, v66, v82 offset0:136 offset1:168
	ds_write2_b32 v177, v67, v83 offset0:204 offset1:236
	ds_write2_b32 v112, v68, v84 offset0:32 offset1:64
	ds_write2_b32 v112, v69, v85 offset0:100 offset1:132
	ds_write2_b32 v112, v70, v86 offset0:168 offset1:200
	ds_write2_b32 v114, v71, v87 offset0:108 offset1:140
	ds_write2_b32 v113, v72, v88 offset0:64 offset1:96
	ds_write2_b32 v113, v73, v89 offset0:132 offset1:164
	ds_write2_b32 v113, v74, v90 offset0:200 offset1:232
	ds_write2_b32 v104, v75, v91 offset0:12 offset1:44
	ds_write2_b32 v105, v76, v92 offset0:96 offset1:128
	ds_write2_b32 v105, v77, v93 offset0:164 offset1:196
	ds_write2_b32 v106, v78, v94 offset0:104 offset1:136
	ds_write2_b32 v107, v79, v95 offset0:44 offset1:76
	v_or_b32_e32 v64, 32, v96
	v_ashrrev_i32_e32 v65, 31, v64
	v_lshlrev_b64 v[108:109], 11, v[64:65]
	s_waitcnt lgkmcnt(0)
	v_lshl_add_u64 v[64:65], v[98:99], 0, v[108:109]
	global_load_dwordx4 v[64:67], v[64:65], off
	v_or_b32_e32 v76, 40, v96
	global_load_dwordx4 v[68:71], v[100:101], off
	global_load_dwordx4 v[72:75], v[102:103], off offset:16
	v_ashrrev_i32_e32 v77, 31, v76
	v_lshlrev_b64 v[110:111], 11, v[76:77]
	v_lshl_add_u64 v[76:77], v[98:99], 0, v[110:111]
	global_load_dwordx4 v[76:79], v[76:77], off
	v_or_b32_e32 v80, 48, v96
	v_ashrrev_i32_e32 v81, 31, v80
	v_lshlrev_b64 v[116:117], 11, v[80:81]
	v_lshl_add_u64 v[80:81], v[98:99], 0, v[116:117]
	global_load_dwordx4 v[80:83], v[80:81], off
	v_or_b32_e32 v84, 56, v96
	v_ashrrev_i32_e32 v85, 31, v84
	v_lshlrev_b64 v[118:119], 11, v[84:85]
	v_lshl_add_u64 v[84:85], v[98:99], 0, v[118:119]
	global_load_dwordx4 v[84:87], v[84:85], off
	ds_read_b128 v[88:91], v176
	ds_read_b128 v[92:95], v176 offset:16
	v_mfma_f32_32x32x16_bf16 v[32:47], v[168:171], v[148:151], v[32:47]
	s_waitcnt vmcnt(5)
	v_lshlrev_b32_e32 v120, 16, v64
	v_and_b32_e32 v121, 0xffff0000, v64
	s_waitcnt vmcnt(4) lgkmcnt(1)
	v_fma_f32 v88, v68, v88, v120
	v_fma_f32 v89, v69, v89, v121
	v_mfma_f32_32x32x16_bf16 v[48:63], v[168:171], v[144:147], v[48:63]
	v_cvt_pk_bf16_f32 v64, v88, v89
	v_lshlrev_b32_e32 v88, 16, v65
	v_and_b32_e32 v89, 0xffff0000, v65
	v_fma_f32 v88, v70, v90, v88
	v_fma_f32 v89, v71, v91, v89
	v_cvt_pk_bf16_f32 v65, v88, v89
	v_lshlrev_b32_e32 v88, 16, v66
	v_and_b32_e32 v89, 0xffff0000, v66
	s_waitcnt vmcnt(3) lgkmcnt(0)
	v_pk_fma_f32 v[88:89], v[72:73], v[92:93], v[88:89]
	v_mfma_f32_32x32x16_bf16 v[32:47], v[172:175], v[160:163], v[32:47]
	v_cvt_pk_bf16_f32 v66, v88, v89
	v_lshlrev_b32_e32 v88, 16, v67
	v_and_b32_e32 v89, 0xffff0000, v67
	v_fma_f32 v88, v74, v94, v88
	v_fma_f32 v89, v75, v95, v89
	v_cvt_pk_bf16_f32 v67, v88, v89
	v_lshl_add_u64 v[88:89], s[8:9], 0, v[108:109]
	v_lshl_add_u64 v[88:89], v[88:89], 0, s[16:17]
	v_lshl_add_u64 v[92:93], v[88:89], 0, v[188:189]
	ds_read_b128 v[88:91], v176 offset:2176
	global_store_dwordx4 v[92:93], v[64:67], off
	ds_read_b128 v[64:67], v176 offset:2192
	s_waitcnt vmcnt(3)
	v_lshlrev_b32_e32 v92, 16, v76
	v_and_b32_e32 v93, 0xffff0000, v76
	s_waitcnt lgkmcnt(1)
	v_pk_fma_f32 v[88:89], v[68:69], v[88:89], v[92:93]
	v_mfma_f32_32x32x16_bf16 v[48:63], v[172:175], v[156:159], v[48:63]
	v_cvt_pk_bf16_f32 v76, v88, v89
	v_lshlrev_b32_e32 v88, 16, v77
	v_and_b32_e32 v89, 0xffff0000, v77
	v_fma_f32 v88, v70, v90, v88
	v_fma_f32 v89, v71, v91, v89
	v_cvt_pk_bf16_f32 v77, v88, v89
	v_lshlrev_b32_e32 v88, 16, v78
	v_and_b32_e32 v89, 0xffff0000, v78
	s_waitcnt lgkmcnt(0)
	v_pk_fma_f32 v[64:65], v[72:73], v[64:65], v[88:89]
	v_mfma_f32_32x32x16_bf16 v[16:31], v[226:229], v[222:225], v[16:31]
	v_cvt_pk_bf16_f32 v78, v64, v65
	v_lshlrev_b32_e32 v64, 16, v79
	v_and_b32_e32 v65, 0xffff0000, v79
	v_fma_f32 v64, v74, v66, v64
	v_fma_f32 v65, v75, v67, v65
	v_cvt_pk_bf16_f32 v79, v64, v65
	v_lshl_add_u64 v[64:65], s[8:9], 0, v[110:111]
	v_lshl_add_u64 v[64:65], v[64:65], 0, s[16:17]
	v_lshl_add_u64 v[88:89], v[64:65], 0, v[188:189]
	ds_read_b128 v[64:67], v176 offset:4352
	global_store_dwordx4 v[88:89], v[76:79], off
	ds_read_b128 v[76:79], v176 offset:4368
	s_waitcnt vmcnt(3)
	v_lshlrev_b32_e32 v88, 16, v80
	v_and_b32_e32 v89, 0xffff0000, v80
	v_lshlrev_b32_e32 v80, 16, v81
	v_and_b32_e32 v81, 0xffff0000, v81
	s_waitcnt lgkmcnt(1)
	v_pk_fma_f32 v[64:65], v[68:69], v[64:65], v[88:89]
	v_pk_fma_f32 v[66:67], v[70:71], v[66:67], v[80:81]
	v_cvt_pk_bf16_f32 v64, v64, v65
	v_cvt_pk_bf16_f32 v65, v66, v67
	v_lshlrev_b32_e32 v66, 16, v82
	v_and_b32_e32 v67, 0xffff0000, v82
	s_waitcnt lgkmcnt(0)
	v_pk_fma_f32 v[66:67], v[72:73], v[76:77], v[66:67]
	v_lshlrev_b32_e32 v76, 16, v83
	v_and_b32_e32 v77, 0xffff0000, v83
	v_pk_fma_f32 v[76:77], v[74:75], v[78:79], v[76:77]
	v_cvt_pk_bf16_f32 v66, v66, v67
	v_cvt_pk_bf16_f32 v67, v76, v77
	v_lshl_add_u64 v[76:77], s[8:9], 0, v[116:117]
	v_lshl_add_u64 v[76:77], v[76:77], 0, s[16:17]
	v_lshl_add_u64 v[80:81], v[76:77], 0, v[188:189]
	ds_read_b128 v[76:79], v176 offset:6528
	global_store_dwordx4 v[80:81], v[64:67], off
	ds_read_b128 v[64:67], v176 offset:6544
	s_waitcnt vmcnt(3)
	v_lshlrev_b32_e32 v80, 16, v84
	v_and_b32_e32 v81, 0xffff0000, v84
	s_waitcnt lgkmcnt(1)
	v_pk_fma_f32 v[68:69], v[68:69], v[76:77], v[80:81]
	v_lshlrev_b32_e32 v76, 16, v85
	v_and_b32_e32 v77, 0xffff0000, v85
	v_pk_fma_f32 v[70:71], v[70:71], v[78:79], v[76:77]
	v_cvt_pk_bf16_f32 v68, v68, v69
	v_cvt_pk_bf16_f32 v69, v70, v71
	v_lshlrev_b32_e32 v70, 16, v86
	v_and_b32_e32 v71, 0xffff0000, v86
	s_waitcnt lgkmcnt(0)
	v_pk_fma_f32 v[64:65], v[72:73], v[64:65], v[70:71]
	v_mfma_f32_32x32x16_bf16 v[0:15], v[128:131], v[136:139], v[0:15]
	v_cvt_pk_bf16_f32 v70, v64, v65
	v_lshlrev_b32_e32 v64, 16, v87
	v_and_b32_e32 v65, 0xffff0000, v87
	v_fma_f32 v64, v74, v66, v64
	v_fma_f32 v65, v75, v67, v65
	v_cvt_pk_bf16_f32 v71, v64, v65
	v_lshl_add_u64 v[64:65], s[8:9], 0, v[118:119]
	v_lshl_add_u64 v[64:65], v[64:65], 0, s[16:17]
	v_lshl_add_u64 v[64:65], v[64:65], 0, v[188:189]
	global_store_dwordx4 v[64:65], v[68:71], off
	s_waitcnt lgkmcnt(0)
	ds_write2_b32 v177, v32, v48 offset1:32
	ds_write2_b32 v177, v33, v49 offset0:68 offset1:100
	ds_write2_b32 v177, v34, v50 offset0:136 offset1:168
	ds_write2_b32 v177, v35, v51 offset0:204 offset1:236
	ds_write2_b32 v112, v36, v52 offset0:32 offset1:64
	ds_write2_b32 v112, v37, v53 offset0:100 offset1:132
	ds_write2_b32 v112, v38, v54 offset0:168 offset1:200
	ds_write2_b32 v114, v39, v55 offset0:108 offset1:140
	ds_write2_b32 v113, v40, v56 offset0:64 offset1:96
	ds_write2_b32 v113, v41, v57 offset0:132 offset1:164
	ds_write2_b32 v113, v42, v58 offset0:200 offset1:232
	ds_write2_b32 v104, v43, v59 offset0:12 offset1:44
	ds_write2_b32 v105, v44, v60 offset0:96 offset1:128
	ds_write2_b32 v105, v45, v61 offset0:164 offset1:196
	ds_write2_b32 v106, v46, v62 offset0:104 offset1:136
	ds_write2_b32 v107, v47, v63 offset0:44 offset1:76
	v_or_b32_e32 v32, 64, v96
	v_ashrrev_i32_e32 v33, 31, v32
	v_lshlrev_b64 v[64:65], 11, v[32:33]
	s_waitcnt lgkmcnt(0)
	v_lshl_add_u64 v[32:33], v[98:99], 0, v[64:65]
	global_load_dwordx4 v[32:35], v[32:33], off
	v_or_b32_e32 v44, 0x48, v96
	global_load_dwordx4 v[36:39], v[100:101], off
	global_load_dwordx4 v[40:43], v[102:103], off offset:16
	v_ashrrev_i32_e32 v45, 31, v44
	v_lshlrev_b64 v[66:67], 11, v[44:45]
	v_lshl_add_u64 v[44:45], v[98:99], 0, v[66:67]
	global_load_dwordx4 v[44:47], v[44:45], off
	v_or_b32_e32 v48, 0x50, v96
	v_ashrrev_i32_e32 v49, 31, v48
	v_lshlrev_b64 v[68:69], 11, v[48:49]
	v_lshl_add_u64 v[48:49], v[98:99], 0, v[68:69]
	global_load_dwordx4 v[48:51], v[48:49], off
	v_or_b32_e32 v52, 0x58, v96
	v_ashrrev_i32_e32 v53, 31, v52
	v_lshlrev_b64 v[70:71], 11, v[52:53]
	v_lshl_add_u64 v[52:53], v[98:99], 0, v[70:71]
	global_load_dwordx4 v[52:55], v[52:53], off
	ds_read_b128 v[56:59], v176
	ds_read_b128 v[60:63], v176 offset:16
	v_mfma_f32_32x32x16_bf16 v[16:31], v[128:131], v[132:135], v[16:31]
	s_waitcnt vmcnt(5)
	v_lshlrev_b32_e32 v72, 16, v32
	v_and_b32_e32 v73, 0xffff0000, v32
	s_waitcnt vmcnt(4) lgkmcnt(1)
	v_fma_f32 v56, v36, v56, v72
	v_fma_f32 v57, v37, v57, v73
	v_mfma_f32_32x32x16_bf16 v[0:15], v[140:143], v[148:151], v[0:15]
	v_cvt_pk_bf16_f32 v32, v56, v57
	v_lshlrev_b32_e32 v56, 16, v33
	v_and_b32_e32 v57, 0xffff0000, v33
	v_fma_f32 v56, v38, v58, v56
	v_fma_f32 v57, v39, v59, v57
	v_cvt_pk_bf16_f32 v33, v56, v57
	v_lshlrev_b32_e32 v56, 16, v34
	v_and_b32_e32 v57, 0xffff0000, v34
	s_waitcnt vmcnt(3) lgkmcnt(0)
	v_pk_fma_f32 v[56:57], v[40:41], v[60:61], v[56:57]
	v_mfma_f32_32x32x16_bf16 v[16:31], v[140:143], v[144:147], v[16:31]
	v_cvt_pk_bf16_f32 v34, v56, v57
	v_lshlrev_b32_e32 v56, 16, v35
	v_and_b32_e32 v57, 0xffff0000, v35
	v_fma_f32 v56, v42, v62, v56
	v_fma_f32 v57, v43, v63, v57
	v_cvt_pk_bf16_f32 v35, v56, v57
	v_lshl_add_u64 v[56:57], s[8:9], 0, v[64:65]
	v_lshl_add_u64 v[56:57], v[56:57], 0, s[16:17]
	v_lshl_add_u64 v[60:61], v[56:57], 0, v[188:189]
	ds_read_b128 v[56:59], v176 offset:2176
	global_store_dwordx4 v[60:61], v[32:35], off
	ds_read_b128 v[32:35], v176 offset:2192
	s_waitcnt vmcnt(3)
	v_lshlrev_b32_e32 v60, 16, v44
	v_and_b32_e32 v61, 0xffff0000, v44
	s_waitcnt lgkmcnt(1)
	v_pk_fma_f32 v[56:57], v[36:37], v[56:57], v[60:61]
	v_mfma_f32_32x32x16_bf16 v[0:15], v[152:155], v[160:163], v[0:15]
	v_cvt_pk_bf16_f32 v44, v56, v57
	v_lshlrev_b32_e32 v56, 16, v45
	v_and_b32_e32 v57, 0xffff0000, v45
	v_fma_f32 v56, v38, v58, v56
	v_fma_f32 v57, v39, v59, v57
	v_cvt_pk_bf16_f32 v45, v56, v57
	v_lshlrev_b32_e32 v56, 16, v46
	v_and_b32_e32 v57, 0xffff0000, v46
	s_waitcnt lgkmcnt(0)
	v_pk_fma_f32 v[32:33], v[40:41], v[32:33], v[56:57]
	v_mfma_f32_32x32x16_bf16 v[16:31], v[152:155], v[156:159], v[16:31]
	v_cvt_pk_bf16_f32 v46, v32, v33
	v_lshlrev_b32_e32 v32, 16, v47
	v_and_b32_e32 v33, 0xffff0000, v47
	v_fma_f32 v32, v42, v34, v32
	v_fma_f32 v33, v43, v35, v33
	v_cvt_pk_bf16_f32 v47, v32, v33
	v_lshl_add_u64 v[32:33], s[8:9], 0, v[66:67]
	v_lshl_add_u64 v[32:33], v[32:33], 0, s[16:17]
	v_lshl_add_u64 v[56:57], v[32:33], 0, v[188:189]
	ds_read_b128 v[32:35], v176 offset:4352
	global_store_dwordx4 v[56:57], v[44:47], off
	ds_read_b128 v[44:47], v176 offset:4368
	s_waitcnt vmcnt(3)
	v_lshlrev_b32_e32 v56, 16, v48
	v_and_b32_e32 v57, 0xffff0000, v48
	v_lshlrev_b32_e32 v48, 16, v49
	v_and_b32_e32 v49, 0xffff0000, v49
	s_waitcnt lgkmcnt(1)
	v_pk_fma_f32 v[32:33], v[36:37], v[32:33], v[56:57]
	v_pk_fma_f32 v[34:35], v[38:39], v[34:35], v[48:49]
	v_cvt_pk_bf16_f32 v32, v32, v33
	v_cvt_pk_bf16_f32 v33, v34, v35
	v_lshlrev_b32_e32 v34, 16, v50
	v_and_b32_e32 v35, 0xffff0000, v50
	s_waitcnt lgkmcnt(0)
	v_pk_fma_f32 v[34:35], v[40:41], v[44:45], v[34:35]
	v_lshlrev_b32_e32 v44, 16, v51
	v_and_b32_e32 v45, 0xffff0000, v51
	v_pk_fma_f32 v[44:45], v[42:43], v[46:47], v[44:45]
	v_cvt_pk_bf16_f32 v34, v34, v35
	v_cvt_pk_bf16_f32 v35, v44, v45
	v_lshl_add_u64 v[44:45], s[8:9], 0, v[68:69]
	v_lshl_add_u64 v[44:45], v[44:45], 0, s[16:17]
	v_lshl_add_u64 v[48:49], v[44:45], 0, v[188:189]
	ds_read_b128 v[44:47], v176 offset:6528
	global_store_dwordx4 v[48:49], v[32:35], off
	ds_read_b128 v[32:35], v176 offset:6544
	s_waitcnt vmcnt(3)
	v_lshlrev_b32_e32 v48, 16, v52
	v_and_b32_e32 v49, 0xffff0000, v52
	s_waitcnt lgkmcnt(1)
	v_pk_fma_f32 v[36:37], v[36:37], v[44:45], v[48:49]
	v_lshlrev_b32_e32 v44, 16, v53
	v_and_b32_e32 v45, 0xffff0000, v53
	v_pk_fma_f32 v[38:39], v[38:39], v[46:47], v[44:45]
	v_cvt_pk_bf16_f32 v36, v36, v37
	v_cvt_pk_bf16_f32 v37, v38, v39
	v_lshlrev_b32_e32 v38, 16, v54
	v_and_b32_e32 v39, 0xffff0000, v54
	s_waitcnt lgkmcnt(0)
	v_pk_fma_f32 v[32:33], v[40:41], v[32:33], v[38:39]
	s_nop 0
	v_cvt_pk_bf16_f32 v38, v32, v33
	v_lshlrev_b32_e32 v32, 16, v55
	v_and_b32_e32 v33, 0xffff0000, v55
	v_pk_fma_f32 v[32:33], v[42:43], v[34:35], v[32:33]
	s_nop 0
	v_cvt_pk_bf16_f32 v39, v32, v33
	v_lshl_add_u64 v[32:33], s[8:9], 0, v[70:71]
	v_lshl_add_u64 v[32:33], v[32:33], 0, s[16:17]
	v_lshl_add_u64 v[32:33], v[32:33], 0, v[188:189]
	global_store_dwordx4 v[32:33], v[36:39], off
	s_waitcnt lgkmcnt(0)
	ds_write2_b32 v177, v0, v16 offset1:32
	ds_write2_b32 v177, v1, v17 offset0:68 offset1:100
	ds_write2_b32 v177, v2, v18 offset0:136 offset1:168
	ds_write2_b32 v177, v3, v19 offset0:204 offset1:236
	ds_write2_b32 v112, v4, v20 offset0:32 offset1:64
	ds_write2_b32 v112, v5, v21 offset0:100 offset1:132
	ds_write2_b32 v112, v6, v22 offset0:168 offset1:200
	ds_write2_b32 v114, v7, v23 offset0:108 offset1:140
	ds_write2_b32 v113, v8, v24 offset0:64 offset1:96
	ds_write2_b32 v113, v9, v25 offset0:132 offset1:164
	ds_write2_b32 v113, v10, v26 offset0:200 offset1:232
	ds_write2_b32 v104, v11, v27 offset0:12 offset1:44
	ds_write2_b32 v105, v12, v28 offset0:96 offset1:128
	ds_write2_b32 v105, v13, v29 offset0:164 offset1:196
	ds_write2_b32 v106, v14, v30 offset0:104 offset1:136
	ds_write2_b32 v107, v15, v31 offset0:44 offset1:76
	v_or_b32_e32 v0, 0x60, v96
	v_ashrrev_i32_e32 v1, 31, v0
	v_lshlrev_b64 v[32:33], 11, v[0:1]
	s_waitcnt lgkmcnt(0)
	v_lshl_add_u64 v[0:1], v[98:99], 0, v[32:33]
	global_load_dwordx4 v[0:3], v[0:1], off
	s_nop 0
	global_load_dwordx4 v[4:7], v[100:101], off
	global_load_dwordx4 v[8:11], v[102:103], off offset:16
	v_or_b32_e32 v12, 0x68, v96
	v_ashrrev_i32_e32 v13, 31, v12
	v_lshlrev_b64 v[34:35], 11, v[12:13]
	v_lshl_add_u64 v[12:13], v[98:99], 0, v[34:35]
	global_load_dwordx4 v[12:15], v[12:13], off
	v_or_b32_e32 v16, 0x70, v96
	v_ashrrev_i32_e32 v17, 31, v16
	v_lshlrev_b64 v[36:37], 11, v[16:17]
	v_lshl_add_u64 v[16:17], v[98:99], 0, v[36:37]
	global_load_dwordx4 v[16:19], v[16:17], off
	v_or_b32_e32 v20, 0x78, v96
	v_ashrrev_i32_e32 v21, 31, v20
	v_lshlrev_b64 v[38:39], 11, v[20:21]
	v_lshl_add_u64 v[20:21], v[98:99], 0, v[38:39]
	global_load_dwordx4 v[20:23], v[20:21], off
	ds_read_b128 v[24:27], v176
	ds_read_b128 v[28:31], v176 offset:16
	s_waitcnt vmcnt(5)
	v_lshlrev_b32_e32 v40, 16, v0
	v_and_b32_e32 v41, 0xffff0000, v0
	s_waitcnt vmcnt(4) lgkmcnt(1)
	v_pk_fma_f32 v[24:25], v[4:5], v[24:25], v[40:41]
	s_nop 0
	v_cvt_pk_bf16_f32 v0, v24, v25
	v_lshlrev_b32_e32 v24, 16, v1
	v_and_b32_e32 v25, 0xffff0000, v1
	v_pk_fma_f32 v[24:25], v[6:7], v[26:27], v[24:25]
	s_nop 0
	v_cvt_pk_bf16_f32 v1, v24, v25
	v_lshlrev_b32_e32 v24, 16, v2
	v_and_b32_e32 v25, 0xffff0000, v2
	s_waitcnt vmcnt(3) lgkmcnt(0)
	v_pk_fma_f32 v[24:25], v[8:9], v[28:29], v[24:25]
	s_nop 0
	v_cvt_pk_bf16_f32 v2, v24, v25
	v_lshlrev_b32_e32 v24, 16, v3
	v_and_b32_e32 v25, 0xffff0000, v3
	v_pk_fma_f32 v[24:25], v[10:11], v[30:31], v[24:25]
	s_nop 0
	v_cvt_pk_bf16_f32 v3, v24, v25
	v_lshl_add_u64 v[24:25], s[8:9], 0, v[32:33]
	v_lshl_add_u64 v[24:25], v[24:25], 0, s[16:17]
	v_lshl_add_u64 v[28:29], v[24:25], 0, v[188:189]
	ds_read_b128 v[24:27], v176 offset:2176
	global_store_dwordx4 v[28:29], v[0:3], off
	ds_read_b128 v[0:3], v176 offset:2192
	s_waitcnt vmcnt(3)
	v_lshlrev_b32_e32 v28, 16, v12
	v_and_b32_e32 v29, 0xffff0000, v12
	s_waitcnt lgkmcnt(1)
	v_pk_fma_f32 v[24:25], v[4:5], v[24:25], v[28:29]
	s_nop 0
	v_cvt_pk_bf16_f32 v12, v24, v25
	v_lshlrev_b32_e32 v24, 16, v13
	v_and_b32_e32 v25, 0xffff0000, v13
	v_pk_fma_f32 v[24:25], v[6:7], v[26:27], v[24:25]
	s_nop 0
	v_cvt_pk_bf16_f32 v13, v24, v25
	v_lshlrev_b32_e32 v24, 16, v14
	v_and_b32_e32 v25, 0xffff0000, v14
	s_waitcnt lgkmcnt(0)
	v_pk_fma_f32 v[0:1], v[8:9], v[0:1], v[24:25]
	s_nop 0
	v_cvt_pk_bf16_f32 v14, v0, v1
	v_lshlrev_b32_e32 v0, 16, v15
	v_and_b32_e32 v1, 0xffff0000, v15
	v_pk_fma_f32 v[0:1], v[10:11], v[2:3], v[0:1]
	s_nop 0
	v_cvt_pk_bf16_f32 v15, v0, v1
	v_lshl_add_u64 v[0:1], s[8:9], 0, v[34:35]
	v_lshl_add_u64 v[0:1], v[0:1], 0, s[16:17]
	v_lshl_add_u64 v[24:25], v[0:1], 0, v[188:189]
	ds_read_b128 v[0:3], v176 offset:4352
	global_store_dwordx4 v[24:25], v[12:15], off
	ds_read_b128 v[12:15], v176 offset:4368
	s_waitcnt vmcnt(3)
	v_lshlrev_b32_e32 v24, 16, v16
	v_and_b32_e32 v25, 0xffff0000, v16
	v_lshlrev_b32_e32 v16, 16, v17
	v_and_b32_e32 v17, 0xffff0000, v17
	s_waitcnt lgkmcnt(1)
	v_pk_fma_f32 v[0:1], v[4:5], v[0:1], v[24:25]
	v_pk_fma_f32 v[2:3], v[6:7], v[2:3], v[16:17]
	v_cvt_pk_bf16_f32 v0, v0, v1
	v_cvt_pk_bf16_f32 v1, v2, v3
	v_lshlrev_b32_e32 v2, 16, v18
	v_and_b32_e32 v3, 0xffff0000, v18
	s_waitcnt lgkmcnt(0)
	v_pk_fma_f32 v[2:3], v[8:9], v[12:13], v[2:3]
	v_lshlrev_b32_e32 v12, 16, v19
	v_and_b32_e32 v13, 0xffff0000, v19
	v_pk_fma_f32 v[12:13], v[10:11], v[14:15], v[12:13]
	v_cvt_pk_bf16_f32 v2, v2, v3
	v_cvt_pk_bf16_f32 v3, v12, v13
	v_lshl_add_u64 v[12:13], s[8:9], 0, v[36:37]
	v_lshl_add_u64 v[12:13], v[12:13], 0, s[16:17]
	v_lshl_add_u64 v[16:17], v[12:13], 0, v[188:189]
	ds_read_b128 v[12:15], v176 offset:6528
	global_store_dwordx4 v[16:17], v[0:3], off
	ds_read_b128 v[0:3], v176 offset:6544
	s_waitcnt vmcnt(3)
	v_lshlrev_b32_e32 v16, 16, v20
	v_and_b32_e32 v17, 0xffff0000, v20
	s_waitcnt lgkmcnt(1)
	v_pk_fma_f32 v[4:5], v[4:5], v[12:13], v[16:17]
	v_lshlrev_b32_e32 v12, 16, v21
	v_and_b32_e32 v13, 0xffff0000, v21
	v_pk_fma_f32 v[6:7], v[6:7], v[14:15], v[12:13]
	v_cvt_pk_bf16_f32 v4, v4, v5
	v_cvt_pk_bf16_f32 v5, v6, v7
	v_lshlrev_b32_e32 v6, 16, v22
	v_and_b32_e32 v7, 0xffff0000, v22
	s_waitcnt lgkmcnt(0)
	v_pk_fma_f32 v[0:1], v[8:9], v[0:1], v[6:7]
	s_nop 0
	v_cvt_pk_bf16_f32 v6, v0, v1
	v_lshlrev_b32_e32 v0, 16, v23
	v_and_b32_e32 v1, 0xffff0000, v23
	v_pk_fma_f32 v[0:1], v[10:11], v[2:3], v[0:1]
	s_nop 0
	v_cvt_pk_bf16_f32 v7, v0, v1
	v_lshl_add_u64 v[0:1], s[8:9], 0, v[38:39]
	v_lshl_add_u64 v[0:1], v[0:1], 0, s[16:17]
	v_lshl_add_u64 v[0:1], v[0:1], 0, v[188:189]
	global_store_dwordx4 v[0:1], v[4:7], off
	s_waitcnt lgkmcnt(0)
	s_cbranch_scc1 .LBB0_1878

.LBB0_1886:
	v_pk_add_f32 v[0:1], v[2:3], v[0:1]
	s_nop 0
	v_add_f32_e32 v0, v0, v1
	v_fmamk_f32 v0, v0, 0x3a800000, v179
	v_mul_f32_e32 v1, 0x4b800000, v0
	v_cmp_gt_f32_e32 vcc, s86, v0
	s_nop 1
	v_cndmask_b32_e32 v0, v0, v1, vcc
	v_rsq_f32_e32 v0, v0
	v_lshl_add_u32 v1, v174, 2, 0
	v_add_u32_e32 v1, 0x25000, v1
	v_mul_f32_e32 v2, 0x45800000, v0
	v_cndmask_b32_e32 v0, v0, v2, vcc
	ds_write_b32 v1, v0
.LBB0_1887:
	s_or_b64 exec, exec, s[0:1]
	v_lshlrev_b64 v[72:73], 2, v[176:177]
	v_lshl_add_u64 v[0:1], s[74:75], 0, v[72:73]
	s_waitcnt lgkmcnt(0)
	s_barrier
	global_load_dwordx4 v[4:7], v[0:1], off
	s_nop 0
	global_load_dwordx4 v[0:3], v[0:1], off offset:16
	v_or_b32_e32 v79, 16, v181
	s_add_i32 s0, 0, 0x25000
	v_or_b32_e32 v97, 24, v181
	v_add_u32_e32 v96, s14, v79
	v_add_u32_e32 v74, s14, v181
	v_or_b32_e32 v77, 8, v181
	v_lshl_add_u32 v101, v97, 2, s0
	v_add_u32_e32 v130, s14, v97
	v_ashrrev_i32_e32 v97, 31, v96
	v_or_b32_e32 v133, 48, v181
	v_or_b32_e32 v135, 56, v181
	v_ashrrev_i32_e32 v75, 31, v74
	v_add_u32_e32 v78, s14, v77
	v_lshlrev_b64 v[96:97], 12, v[96:97]
	v_or_b32_e32 v109, 40, v181
	v_lshl_add_u32 v98, v181, 2, s0
	v_lshl_add_u32 v99, v77, 2, s0
	v_lshl_add_u32 v77, v79, 2, s0
	v_lshl_add_u32 v106, v133, 2, s0
	v_lshl_add_u32 v107, v135, 2, s0
	v_lshlrev_b64 v[74:75], 12, v[74:75]
	v_ashrrev_i32_e32 v79, 31, v78
	v_lshl_add_u64 v[96:97], s[76:77], 0, v[96:97]
	v_lshl_add_u32 v103, v168, 2, s0
	v_lshl_add_u32 v105, v109, 2, s0
	ds_read_b32 v98, v98
	ds_read_b32 v100, v99
	ds_read_b32 v102, v77
	ds_read_b32 v104, v101
	ds_read_b32 v132, v103
	ds_read_b32 v134, v105
	ds_read_b32 v170, v106
	ds_read_b32 v172, v107
	v_lshl_add_u64 v[74:75], s[76:77], 0, v[74:75]
	v_lshlrev_b64 v[78:79], 12, v[78:79]
	v_lshl_add_u64 v[174:175], v[96:97], 0, v[72:73]
	s_waitcnt lgkmcnt(7)
	v_pk_mul_f32 v[96:97], v[112:113], v[98:99] op_sel_hi:[1,0]
	v_pk_mul_f32 v[106:107], v[114:115], v[98:99] op_sel_hi:[1,0]
	v_lshl_add_u64 v[74:75], v[74:75], 0, v[72:73]
	v_lshl_add_u64 v[78:79], s[76:77], 0, v[78:79]
	v_pk_mul_f32 v[110:111], v[116:117], v[98:99] op_sel_hi:[1,0]
	v_pk_mul_f32 v[112:113], v[118:119], v[98:99] op_sel_hi:[1,0]
	s_waitcnt lgkmcnt(6)
	v_pk_mul_f32 v[114:115], v[120:121], v[100:101] op_sel_hi:[1,0]
	v_pk_mul_f32 v[116:117], v[122:123], v[100:101] op_sel_hi:[1,0]
	v_pk_mul_f32 v[118:119], v[124:125], v[100:101] op_sel_hi:[1,0]
	v_pk_mul_f32 v[120:121], v[126:127], v[100:101] op_sel_hi:[1,0]
	s_waitcnt lgkmcnt(5)
	v_pk_mul_f32 v[122:123], v[160:161], v[102:103] op_sel_hi:[1,0]
	v_pk_mul_f32 v[124:125], v[156:157], v[102:103] op_sel_hi:[1,0]
	v_pk_mul_f32 v[126:127], v[162:163], v[102:103] op_sel_hi:[1,0]
	v_pk_mul_f32 v[128:129], v[158:159], v[102:103] op_sel_hi:[1,0]
	v_ashrrev_i32_e32 v131, 31, v130
	v_lshl_add_u64 v[78:79], v[78:79], 0, v[72:73]
	s_waitcnt lgkmcnt(4)
	v_pk_mul_f32 v[156:157], v[164:165], v[104:105] op_sel_hi:[1,0]
	v_pk_mul_f32 v[152:153], v[152:153], v[104:105] op_sel_hi:[1,0]
	v_pk_mul_f32 v[158:159], v[166:167], v[104:105] op_sel_hi:[1,0]
	v_pk_mul_f32 v[154:155], v[154:155], v[104:105] op_sel_hi:[1,0]
	v_or_b32_e32 v77, 0x48, v181
	s_add_i32 s49, s49, s33
	s_cmpk_gt_i32 s49, 0x1ff
	s_waitcnt vmcnt(1)
	v_pk_mul_f32 v[98:99], v[6:7], v[106:107]
	v_pk_mul_f32 v[96:97], v[4:5], v[96:97]
	s_waitcnt vmcnt(0)
	v_pk_mul_f32 v[102:103], v[2:3], v[112:113]
	v_pk_mul_f32 v[100:101], v[0:1], v[110:111]
	v_pk_mul_f32 v[106:107], v[6:7], v[116:117]
	v_pk_mul_f32 v[104:105], v[4:5], v[114:115]
	v_pk_mul_f32 v[112:113], v[2:3], v[120:121]
	v_pk_mul_f32 v[110:111], v[0:1], v[118:119]
	v_pk_mul_f32 v[116:117], v[6:7], v[124:125]
	v_pk_mul_f32 v[114:115], v[4:5], v[122:123]
	v_pk_mul_f32 v[120:121], v[2:3], v[128:129]
	v_pk_mul_f32 v[118:119], v[0:1], v[126:127]
	global_store_dwordx4 v[74:75], v[96:99], off
	global_store_dwordx4 v[74:75], v[100:103], off offset:16
	global_store_dwordx4 v[78:79], v[104:107], off
	global_store_dwordx4 v[78:79], v[110:113], off offset:16
	global_store_dwordx4 v[174:175], v[114:117], off
	global_store_dwordx4 v[174:175], v[118:121], off offset:16
	v_lshlrev_b64 v[74:75], 12, v[130:131]
	v_lshl_add_u64 v[74:75], s[76:77], 0, v[74:75]
	v_pk_mul_f32 v[124:125], v[6:7], v[152:153]
	v_pk_mul_f32 v[122:123], v[4:5], v[156:157]
	v_lshl_add_u64 v[74:75], v[74:75], 0, v[72:73]
	v_pk_mul_f32 v[128:129], v[2:3], v[154:155]
	v_pk_mul_f32 v[126:127], v[0:1], v[158:159]
	global_store_dwordx4 v[74:75], v[122:125], off
	global_store_dwordx4 v[74:75], v[126:129], off offset:16
	v_add_u32_e32 v74, s14, v168
	v_ashrrev_i32_e32 v75, 31, v74
	v_lshlrev_b64 v[74:75], 12, v[74:75]
	s_waitcnt lgkmcnt(3)
	v_pk_mul_f32 v[78:79], v[80:81], v[132:133] op_sel_hi:[1,0]
	v_pk_mul_f32 v[80:81], v[82:83], v[132:133] op_sel_hi:[1,0]
	v_lshl_add_u64 v[74:75], s[76:77], 0, v[74:75]
	v_pk_mul_f32 v[80:81], v[6:7], v[80:81]
	v_pk_mul_f32 v[78:79], v[4:5], v[78:79]
	v_pk_mul_f32 v[82:83], v[84:85], v[132:133] op_sel_hi:[1,0]
	v_pk_mul_f32 v[84:85], v[86:87], v[132:133] op_sel_hi:[1,0]
	v_lshl_add_u64 v[74:75], v[74:75], 0, v[72:73]
	v_pk_mul_f32 v[84:85], v[2:3], v[84:85]
	v_pk_mul_f32 v[82:83], v[0:1], v[82:83]
	global_store_dwordx4 v[74:75], v[78:81], off
	global_store_dwordx4 v[74:75], v[82:85], off offset:16
	v_add_u32_e32 v74, s14, v109
	v_ashrrev_i32_e32 v75, 31, v74
	v_lshlrev_b64 v[74:75], 12, v[74:75]
	s_waitcnt lgkmcnt(2)
	v_pk_mul_f32 v[78:79], v[88:89], v[134:135] op_sel_hi:[1,0]
	v_pk_mul_f32 v[80:81], v[90:91], v[134:135] op_sel_hi:[1,0]
	v_lshl_add_u64 v[74:75], s[76:77], 0, v[74:75]
	v_pk_mul_f32 v[80:81], v[6:7], v[80:81]
	v_pk_mul_f32 v[78:79], v[4:5], v[78:79]
	v_pk_mul_f32 v[82:83], v[92:93], v[134:135] op_sel_hi:[1,0]
	v_pk_mul_f32 v[84:85], v[94:95], v[134:135] op_sel_hi:[1,0]
	v_lshl_add_u64 v[74:75], v[74:75], 0, v[72:73]
	v_pk_mul_f32 v[84:85], v[2:3], v[84:85]
	v_pk_mul_f32 v[82:83], v[0:1], v[82:83]
	global_store_dwordx4 v[74:75], v[78:81], off
	global_store_dwordx4 v[74:75], v[82:85], off offset:16
	v_add_u32_e32 v74, s14, v133
	v_ashrrev_i32_e32 v75, 31, v74
	v_lshlrev_b64 v[74:75], 12, v[74:75]
	s_waitcnt lgkmcnt(1)
	v_pk_mul_f32 v[78:79], v[144:145], v[170:171] op_sel_hi:[1,0]
	v_pk_mul_f32 v[80:81], v[140:141], v[170:171] op_sel_hi:[1,0]
	v_lshl_add_u64 v[74:75], s[76:77], 0, v[74:75]
	v_pk_mul_f32 v[80:81], v[6:7], v[80:81]
	v_pk_mul_f32 v[78:79], v[4:5], v[78:79]
	v_pk_mul_f32 v[82:83], v[146:147], v[170:171] op_sel_hi:[1,0]
	v_pk_mul_f32 v[84:85], v[142:143], v[170:171] op_sel_hi:[1,0]
	v_lshl_add_u64 v[74:75], v[74:75], 0, v[72:73]
	v_pk_mul_f32 v[84:85], v[2:3], v[84:85]
	v_pk_mul_f32 v[82:83], v[0:1], v[82:83]
	global_store_dwordx4 v[74:75], v[78:81], off
	global_store_dwordx4 v[74:75], v[82:85], off offset:16
	v_add_u32_e32 v74, s14, v135
	v_ashrrev_i32_e32 v75, 31, v74
	v_lshlrev_b64 v[74:75], 12, v[74:75]
	s_waitcnt lgkmcnt(0)
	v_pk_mul_f32 v[78:79], v[148:149], v[172:173] op_sel_hi:[1,0]
	v_pk_mul_f32 v[80:81], v[136:137], v[172:173] op_sel_hi:[1,0]
	v_pk_mul_f32 v[82:83], v[150:151], v[172:173] op_sel_hi:[1,0]
	v_lshl_add_u64 v[74:75], s[76:77], 0, v[74:75]
	v_pk_mul_f32 v[80:81], v[6:7], v[80:81]
	v_pk_mul_f32 v[78:79], v[4:5], v[78:79]
	v_pk_mul_f32 v[84:85], v[138:139], v[172:173] op_sel_hi:[1,0]
	v_pk_mul_f32 v[82:83], v[0:1], v[82:83]
	v_lshl_add_u64 v[74:75], v[74:75], 0, v[72:73]
	v_pk_mul_f32 v[84:85], v[2:3], v[84:85]
	global_store_dwordx4 v[74:75], v[78:81], off
	global_store_dwordx4 v[74:75], v[82:85], off offset:16
	v_or_b32_e32 v87, 0x68, v181
	v_or_b32_e32 v81, 0x50, v181
	v_or_b32_e32 v83, 0x58, v181
	v_or_b32_e32 v89, 0x70, v181
	v_or_b32_e32 v91, 0x78, v181
	v_lshl_add_u32 v75, v108, 2, s0
	v_add_u32_e32 v74, s14, v108
	v_lshl_add_u32 v82, v81, 2, s0
	v_lshl_add_u32 v84, v83, 2, s0
	v_lshl_add_u32 v88, v87, 2, s0
	v_lshl_add_u32 v90, v89, 2, s0
	v_lshl_add_u32 v92, v91, 2, s0
	v_lshl_add_u32 v79, v77, 2, s0
	v_lshl_add_u32 v85, v76, 2, s0
	ds_read_b32 v78, v75
	ds_read_b32 v80, v79
	ds_read_b32 v82, v82
	ds_read_b32 v84, v84
	ds_read_b32 v86, v85
	ds_read_b32 v88, v88
	ds_read_b32 v90, v90
	ds_read_b32 v92, v92
	v_ashrrev_i32_e32 v75, 31, v74
	v_lshlrev_b64 v[74:75], 12, v[74:75]
	s_waitcnt lgkmcnt(7)
	v_pk_mul_f32 v[32:33], v[32:33], v[78:79] op_sel_hi:[1,0]
	v_pk_mul_f32 v[34:35], v[34:35], v[78:79] op_sel_hi:[1,0]
	v_lshl_add_u64 v[74:75], s[76:77], 0, v[74:75]
	v_pk_mul_f32 v[34:35], v[6:7], v[34:35]
	v_pk_mul_f32 v[32:33], v[4:5], v[32:33]
	v_pk_mul_f32 v[36:37], v[36:37], v[78:79] op_sel_hi:[1,0]
	v_pk_mul_f32 v[38:39], v[38:39], v[78:79] op_sel_hi:[1,0]
	v_lshl_add_u64 v[74:75], v[74:75], 0, v[72:73]
	v_pk_mul_f32 v[38:39], v[2:3], v[38:39]
	v_pk_mul_f32 v[36:37], v[0:1], v[36:37]
	global_store_dwordx4 v[74:75], v[32:35], off
	global_store_dwordx4 v[74:75], v[36:39], off offset:16
	v_add_u32_e32 v74, s14, v77
	v_ashrrev_i32_e32 v75, 31, v74
	s_waitcnt lgkmcnt(6)
	v_pk_mul_f32 v[32:33], v[40:41], v[80:81] op_sel_hi:[1,0]
	v_lshlrev_b64 v[40:41], 12, v[74:75]
	v_pk_mul_f32 v[34:35], v[42:43], v[80:81] op_sel_hi:[1,0]
	v_lshl_add_u64 v[40:41], s[76:77], 0, v[40:41]
	v_pk_mul_f32 v[34:35], v[6:7], v[34:35]
	v_pk_mul_f32 v[32:33], v[4:5], v[32:33]
	v_pk_mul_f32 v[36:37], v[44:45], v[80:81] op_sel_hi:[1,0]
	v_pk_mul_f32 v[38:39], v[46:47], v[80:81] op_sel_hi:[1,0]
	v_lshl_add_u64 v[40:41], v[40:41], 0, v[72:73]
	v_pk_mul_f32 v[38:39], v[2:3], v[38:39]
	v_pk_mul_f32 v[36:37], v[0:1], v[36:37]
	global_store_dwordx4 v[40:41], v[32:35], off
	global_store_dwordx4 v[40:41], v[36:39], off offset:16
	v_add_u32_e32 v40, s14, v81
	v_ashrrev_i32_e32 v41, 31, v40
	v_lshlrev_b64 v[40:41], 12, v[40:41]
	s_waitcnt lgkmcnt(5)
	v_pk_mul_f32 v[32:33], v[48:49], v[82:83] op_sel_hi:[1,0]
	v_pk_mul_f32 v[34:35], v[50:51], v[82:83] op_sel_hi:[1,0]
	v_lshl_add_u64 v[40:41], s[76:77], 0, v[40:41]
	v_pk_mul_f32 v[34:35], v[6:7], v[34:35]
	v_pk_mul_f32 v[32:33], v[4:5], v[32:33]
	v_pk_mul_f32 v[36:37], v[52:53], v[82:83] op_sel_hi:[1,0]
	v_pk_mul_f32 v[38:39], v[54:55], v[82:83] op_sel_hi:[1,0]
	v_lshl_add_u64 v[40:41], v[40:41], 0, v[72:73]
	v_pk_mul_f32 v[38:39], v[2:3], v[38:39]
	v_pk_mul_f32 v[36:37], v[0:1], v[36:37]
	global_store_dwordx4 v[40:41], v[32:35], off
	global_store_dwordx4 v[40:41], v[36:39], off offset:16
	v_add_u32_e32 v40, s14, v83
	v_ashrrev_i32_e32 v41, 31, v40
	v_lshlrev_b64 v[40:41], 12, v[40:41]
	s_waitcnt lgkmcnt(4)
	v_pk_mul_f32 v[32:33], v[56:57], v[84:85] op_sel_hi:[1,0]
	v_pk_mul_f32 v[34:35], v[58:59], v[84:85] op_sel_hi:[1,0]
	v_lshl_add_u64 v[40:41], s[76:77], 0, v[40:41]
	v_pk_mul_f32 v[34:35], v[6:7], v[34:35]
	v_pk_mul_f32 v[32:33], v[4:5], v[32:33]
	v_pk_mul_f32 v[36:37], v[60:61], v[84:85] op_sel_hi:[1,0]
	v_pk_mul_f32 v[38:39], v[62:63], v[84:85] op_sel_hi:[1,0]
	v_lshl_add_u64 v[40:41], v[40:41], 0, v[72:73]
	v_pk_mul_f32 v[38:39], v[2:3], v[38:39]
	v_pk_mul_f32 v[36:37], v[0:1], v[36:37]
	global_store_dwordx4 v[40:41], v[32:35], off
	global_store_dwordx4 v[40:41], v[36:39], off offset:16
	s_waitcnt lgkmcnt(3)
	v_pk_mul_f32 v[8:9], v[8:9], v[86:87] op_sel_hi:[1,0]
	v_add_u32_e32 v32, s14, v76
	v_ashrrev_i32_e32 v33, 31, v32
	v_lshlrev_b64 v[32:33], 12, v[32:33]
	v_pk_mul_f32 v[10:11], v[10:11], v[86:87] op_sel_hi:[1,0]
	v_lshl_add_u64 v[32:33], s[76:77], 0, v[32:33]
	v_pk_mul_f32 v[10:11], v[6:7], v[10:11]
	v_pk_mul_f32 v[8:9], v[4:5], v[8:9]
	v_pk_mul_f32 v[12:13], v[12:13], v[86:87] op_sel_hi:[1,0]
	v_pk_mul_f32 v[14:15], v[14:15], v[86:87] op_sel_hi:[1,0]
	v_lshl_add_u64 v[32:33], v[32:33], 0, v[72:73]
	v_pk_mul_f32 v[14:15], v[2:3], v[14:15]
	v_pk_mul_f32 v[12:13], v[0:1], v[12:13]
	global_store_dwordx4 v[32:33], v[8:11], off
	global_store_dwordx4 v[32:33], v[12:15], off offset:16
	v_add_u32_e32 v32, s14, v87
	v_ashrrev_i32_e32 v33, 31, v32
	s_waitcnt lgkmcnt(2)
	v_pk_mul_f32 v[8:9], v[16:17], v[88:89] op_sel_hi:[1,0]
	v_lshlrev_b64 v[16:17], 12, v[32:33]
	v_pk_mul_f32 v[10:11], v[18:19], v[88:89] op_sel_hi:[1,0]
	v_lshl_add_u64 v[16:17], s[76:77], 0, v[16:17]
	v_pk_mul_f32 v[10:11], v[6:7], v[10:11]
	v_pk_mul_f32 v[8:9], v[4:5], v[8:9]
	v_pk_mul_f32 v[12:13], v[20:21], v[88:89] op_sel_hi:[1,0]
	v_pk_mul_f32 v[14:15], v[22:23], v[88:89] op_sel_hi:[1,0]
	v_lshl_add_u64 v[16:17], v[16:17], 0, v[72:73]
	v_pk_mul_f32 v[14:15], v[2:3], v[14:15]
	v_pk_mul_f32 v[12:13], v[0:1], v[12:13]
	global_store_dwordx4 v[16:17], v[8:11], off
	global_store_dwordx4 v[16:17], v[12:15], off offset:16
	v_add_u32_e32 v16, s14, v89
	v_ashrrev_i32_e32 v17, 31, v16
	v_lshlrev_b64 v[16:17], 12, v[16:17]
	s_waitcnt lgkmcnt(1)
	v_pk_mul_f32 v[8:9], v[24:25], v[90:91] op_sel_hi:[1,0]
	v_pk_mul_f32 v[10:11], v[26:27], v[90:91] op_sel_hi:[1,0]
	v_lshl_add_u64 v[16:17], s[76:77], 0, v[16:17]
	v_pk_mul_f32 v[10:11], v[6:7], v[10:11]
	v_pk_mul_f32 v[8:9], v[4:5], v[8:9]
	v_pk_mul_f32 v[12:13], v[28:29], v[90:91] op_sel_hi:[1,0]
	v_pk_mul_f32 v[14:15], v[30:31], v[90:91] op_sel_hi:[1,0]
	v_lshl_add_u64 v[16:17], v[16:17], 0, v[72:73]
	v_pk_mul_f32 v[14:15], v[2:3], v[14:15]
	v_pk_mul_f32 v[12:13], v[0:1], v[12:13]
	global_store_dwordx4 v[16:17], v[8:11], off
	global_store_dwordx4 v[16:17], v[12:15], off offset:16
	s_nop 0
	v_add_u32_e32 v8, s14, v91
	v_ashrrev_i32_e32 v9, 31, v8
	s_waitcnt lgkmcnt(0)
	v_pk_mul_f32 v[10:11], v[68:69], v[92:93] op_sel_hi:[1,0]
	v_pk_mul_f32 v[12:13], v[64:65], v[92:93] op_sel_hi:[1,0]
	v_lshlrev_b64 v[8:9], 12, v[8:9]
	v_pk_mul_f32 v[6:7], v[6:7], v[12:13]
	v_pk_mul_f32 v[4:5], v[4:5], v[10:11]
	v_pk_mul_f32 v[10:11], v[70:71], v[92:93] op_sel_hi:[1,0]
	v_pk_mul_f32 v[12:13], v[66:67], v[92:93] op_sel_hi:[1,0]
	v_lshl_add_u64 v[8:9], s[76:77], 0, v[8:9]
	v_pk_mul_f32 v[2:3], v[2:3], v[12:13]
	v_pk_mul_f32 v[0:1], v[0:1], v[10:11]
	v_lshl_add_u64 v[8:9], v[8:9], 0, v[72:73]
	global_store_dwordx4 v[8:9], v[4:7], off
	global_store_dwordx4 v[8:9], v[0:3], off offset:16
	s_cbranch_scc1 .LBB0_2014

.LBB0_1889:
	v_lshl_add_u64 v[136:137], s[78:79], 0, v[182:183]
	v_add_co_u32_e32 v128, vcc, s63, v136
	v_lshl_add_u64 v[152:153], s[78:79], 0, v[180:181]
	s_nop 0
	v_addc_co_u32_e32 v129, vcc, 0, v137, vcc
	v_add_co_u32_e32 v132, vcc, s64, v136
	s_add_i32 s1, s0, 1
	s_nop 0
	v_addc_co_u32_e32 v133, vcc, 0, v137, vcc
	v_add_co_u32_e32 v138, vcc, s65, v136
	global_load_dwordx4 v[128:131], v[128:129], off
	s_nop 0
	global_load_dwordx4 v[132:135], v[132:133], off
	v_addc_co_u32_e32 v139, vcc, 0, v137, vcc
	v_add_co_u32_e32 v140, vcc, s66, v136
	s_nop 1
	v_addc_co_u32_e32 v141, vcc, 0, v137, vcc
	v_add_co_u32_e32 v144, vcc, s67, v152
	global_load_dwordx4 v[136:139], v[138:139], off
	s_nop 0
	global_load_dwordx4 v[140:143], v[140:141], off
	v_addc_co_u32_e32 v145, vcc, 0, v153, vcc
	v_add_co_u32_e32 v148, vcc, s68, v152
	s_nop 1
	v_addc_co_u32_e32 v149, vcc, 0, v153, vcc
	v_add_co_u32_e32 v154, vcc, s69, v152
	global_load_dwordx4 v[144:147], v[144:145], off offset:128
	s_nop 0
	global_load_dwordx4 v[148:151], v[148:149], off offset:128
	v_addc_co_u32_e32 v155, vcc, 0, v153, vcc
	v_add_co_u32_e32 v156, vcc, s70, v152
	s_nop 1
	v_addc_co_u32_e32 v157, vcc, 0, v153, vcc
	global_load_dwordx4 v[152:155], v[154:155], off offset:128
	s_nop 0
	global_load_dwordx4 v[156:159], v[156:157], off offset:128
	s_bitcmp1_b32 s0, 0
	s_cselect_b32 s0, 0x12000, 0
	s_add_i32 s0, s0, 0
	v_add_u32_e32 v172, s0, v188
	v_add_u32_e32 v226, s0, v193
	ds_read_b64_tr_b16 v[196:197], v172 offset:2304
	ds_read_b64_tr_b16 v[194:195], v172
	ds_read_b64_tr_b16 v[198:199], v172 offset:64
	ds_read_b64_tr_b16 v[202:203], v172 offset:128
	ds_read_b64_tr_b16 v[206:207], v172 offset:192
	ds_read_b128 v[210:213], v226 offset:36864
	ds_read_b64_tr_b16 v[200:201], v172 offset:2368
	ds_read_b64_tr_b16 v[204:205], v172 offset:2432
	ds_read_b64_tr_b16 v[208:209], v172 offset:2496
	ds_read_b128 v[214:217], v226 offset:36896
	ds_read_b128 v[218:221], v226 offset:41472
	ds_read_b128 v[222:225], v226 offset:41504
	s_waitcnt lgkmcnt(6)
	v_mfma_f32_32x32x16_bf16 v[96:111], v[194:197], v[210:213], v[96:111]
	s_bitcmp1_b32 s1, 0
	s_cselect_b32 s18, 0x12000, 0
	s_add_i32 s18, s18, 0
	v_lshl_add_u64 v[180:181], v[180:181], 0, s[8:9]
	v_lshl_add_u64 v[182:183], v[182:183], 0, s[10:11]
	s_mov_b32 s0, s1
	s_cmp_eq_u32 s1, 15
	s_waitcnt lgkmcnt(1)
	v_mfma_f32_32x32x16_bf16 v[112:127], v[194:197], v[218:221], v[112:127]
	ds_read_b64_tr_b16 v[196:197], v172 offset:11520
	v_mfma_f32_32x32x16_bf16 v[64:79], v[198:201], v[210:213], v[64:79]
	v_mfma_f32_32x32x16_bf16 v[80:95], v[198:201], v[218:221], v[80:95]
	v_mfma_f32_32x32x16_bf16 v[32:47], v[202:205], v[210:213], v[32:47]
	v_mfma_f32_32x32x16_bf16 v[48:63], v[202:205], v[218:221], v[48:63]
	v_mfma_f32_32x32x16_bf16 v[0:15], v[206:209], v[210:213], v[0:15]
	v_mfma_f32_32x32x16_bf16 v[16:31], v[206:209], v[218:221], v[16:31]
	ds_read_b64_tr_b16 v[194:195], v172 offset:9216
	ds_read_b64_tr_b16 v[198:199], v172 offset:9280
	ds_read_b64_tr_b16 v[202:203], v172 offset:9344
	ds_read_b64_tr_b16 v[206:207], v172 offset:9408
	ds_read_b64_tr_b16 v[200:201], v172 offset:11584
	ds_read_b64_tr_b16 v[204:205], v172 offset:11648
	ds_read_b64_tr_b16 v[208:209], v172 offset:11712
	s_waitcnt lgkmcnt(6)
	v_mfma_f32_32x32x16_bf16 v[96:111], v[194:197], v[214:217], v[96:111]
	v_mfma_f32_32x32x16_bf16 v[112:127], v[194:197], v[222:225], v[112:127]
	s_waitcnt lgkmcnt(2)
	v_mfma_f32_32x32x16_bf16 v[64:79], v[198:201], v[214:217], v[64:79]
	v_mfma_f32_32x32x16_bf16 v[80:95], v[198:201], v[222:225], v[80:95]
	ds_read_b64_tr_b16 v[196:197], v172 offset:20736
	ds_read_b64_tr_b16 v[194:195], v172 offset:18432
	ds_read_b64_tr_b16 v[198:199], v172 offset:18496
	s_waitcnt lgkmcnt(4)
	v_mfma_f32_32x32x16_bf16 v[32:47], v[202:205], v[214:217], v[32:47]
	v_mfma_f32_32x32x16_bf16 v[48:63], v[202:205], v[222:225], v[48:63]
	s_waitcnt lgkmcnt(3)
	v_mfma_f32_32x32x16_bf16 v[0:15], v[206:209], v[214:217], v[0:15]
	v_mfma_f32_32x32x16_bf16 v[16:31], v[206:209], v[222:225], v[16:31]
	ds_read_b64_tr_b16 v[202:203], v172 offset:18560
	ds_read_b64_tr_b16 v[206:207], v172 offset:18624
	ds_read_b128 v[210:213], v226 offset:36928
	ds_read_b64_tr_b16 v[200:201], v172 offset:20800
	ds_read_b64_tr_b16 v[204:205], v172 offset:20864
	ds_read_b64_tr_b16 v[208:209], v172 offset:20928
	ds_read_b128 v[214:217], v226 offset:36960
	ds_read_b128 v[218:221], v226 offset:41536
	ds_read_b128 v[222:225], v226 offset:41568
	s_waitcnt lgkmcnt(6)
	v_mfma_f32_32x32x16_bf16 v[96:111], v[194:197], v[210:213], v[96:111]
	s_waitcnt lgkmcnt(1)
	v_mfma_f32_32x32x16_bf16 v[112:127], v[194:197], v[218:221], v[112:127]
	ds_read_b64_tr_b16 v[196:197], v172 offset:29952
	v_mfma_f32_32x32x16_bf16 v[64:79], v[198:201], v[210:213], v[64:79]
	v_mfma_f32_32x32x16_bf16 v[80:95], v[198:201], v[218:221], v[80:95]
	v_mfma_f32_32x32x16_bf16 v[32:47], v[202:205], v[210:213], v[32:47]
	v_mfma_f32_32x32x16_bf16 v[48:63], v[202:205], v[218:221], v[48:63]
	v_mfma_f32_32x32x16_bf16 v[0:15], v[206:209], v[210:213], v[0:15]
	v_mfma_f32_32x32x16_bf16 v[16:31], v[206:209], v[218:221], v[16:31]
	ds_read_b64_tr_b16 v[194:195], v172 offset:27648
	ds_read_b64_tr_b16 v[198:199], v172 offset:27712
	ds_read_b64_tr_b16 v[202:203], v172 offset:27776
	ds_read_b64_tr_b16 v[206:207], v172 offset:27840
	ds_read_b64_tr_b16 v[200:201], v172 offset:30016
	ds_read_b64_tr_b16 v[204:205], v172 offset:30080
	ds_read_b64_tr_b16 v[208:209], v172 offset:30144
	v_add_u32_e32 v172, s18, v170
	s_waitcnt vmcnt(7)
	ds_write_b128 v172, v[128:131]
	s_waitcnt vmcnt(6)
	ds_write_b128 v172, v[132:135] offset:9216
	s_waitcnt vmcnt(5)
	ds_write_b128 v172, v[136:139] offset:18432
	s_waitcnt vmcnt(4)
	ds_write_b128 v172, v[140:143] offset:27648
	s_waitcnt lgkmcnt(10)
	v_mfma_f32_32x32x16_bf16 v[96:111], v[194:197], v[214:217], v[96:111]
	v_mfma_f32_32x32x16_bf16 v[112:127], v[194:197], v[222:225], v[112:127]
	v_add_u32_e32 v194, s18, v176
	s_waitcnt vmcnt(3)
	ds_write_b128 v194, v[144:147] offset:36864
	s_waitcnt vmcnt(2)
	ds_write_b128 v194, v[148:151] offset:46080
	s_waitcnt vmcnt(1)
	ds_write_b128 v194, v[152:155] offset:55296
	s_waitcnt vmcnt(0)
	ds_write_b128 v194, v[156:159] offset:64512
	s_waitcnt lgkmcnt(0)
	s_barrier
	v_mfma_f32_32x32x16_bf16 v[64:79], v[198:201], v[214:217], v[64:79]
	v_mfma_f32_32x32x16_bf16 v[80:95], v[198:201], v[222:225], v[80:95]
	v_mfma_f32_32x32x16_bf16 v[32:47], v[202:205], v[214:217], v[32:47]
	v_mfma_f32_32x32x16_bf16 v[48:63], v[202:205], v[222:225], v[48:63]
	v_mfma_f32_32x32x16_bf16 v[0:15], v[206:209], v[214:217], v[0:15]
	v_mfma_f32_32x32x16_bf16 v[16:31], v[206:209], v[222:225], v[16:31]
	s_cbranch_scc0 .LBB0_1889
	v_add_co_u32_e32 v136, vcc, 0x780000, v160
	s_lshl_b32 s0, s16, 8
	s_nop 0
	v_addc_co_u32_e32 v137, vcc, 0, v161, vcc
	v_add_co_u32_e32 v128, vcc, 0x7a0000, v160
	s_nop 1
	v_addc_co_u32_e32 v129, vcc, 0, v161, vcc
	v_add_co_u32_e32 v132, vcc, 0x7c0000, v160
	s_nop 1
	v_addc_co_u32_e32 v133, vcc, 0, v161, vcc
	v_add_co_u32_e32 v144, vcc, 0x7e0000, v160
	global_load_dwordx4 v[128:131], v[128:129], off
	s_nop 0
	global_load_dwordx4 v[132:135], v[132:133], off
	v_addc_co_u32_e32 v145, vcc, 0, v161, vcc
	global_load_dwordx4 v[136:139], v[136:137], off
	s_nop 0
	global_load_dwordx4 v[140:143], v[162:163], off offset:1920
	s_nop 0
	global_load_dwordx4 v[144:147], v[144:145], off
	s_nop 0
	global_load_dwordx4 v[148:151], v[164:165], off offset:1920
	global_load_dwordx4 v[152:155], v[166:167], off offset:1920
	global_load_dwordx4 v[156:159], v[168:169], off offset:1920
	v_add_u32_e32 v160, v190, v192
	v_add_u32_e32 v168, 64, v160
	v_add_u32_e32 v169, 0x80, v160
	v_add_u32_e32 v170, 0xc0, v160
	v_add_u32_e32 v160, v191, v189
	v_add_u32_e32 v172, 0x9000, v160
	v_add_u32_e32 v176, 0xa200, v160
	s_add_i32 s1, 0, 0x12000
	v_add_u32_e32 v162, s1, v188
	v_add_u32_e32 v182, s1, v168
	v_add_u32_e32 v164, s1, v172
	ds_read_b64_tr_b16 v[160:161], v162
	ds_read_b64_tr_b16 v[162:163], v162 offset:2304
	ds_read_b128 v[164:167], v164
	v_add_u32_e32 v189, s1, v176
	ds_read_b64_tr_b16 v[180:181], v182
	ds_read_b64_tr_b16 v[182:183], v182 offset:2304
	ds_read_b128 v[190:193], v189
	s_waitcnt lgkmcnt(3)
	v_mfma_f32_32x32x16_bf16 v[96:111], v[160:163], v[164:167], v[96:111]
	v_add_u32_e32 v189, s1, v170
	v_add_u32_e32 v200, s71, v168
	v_add_u32_e32 v208, s71, v170
	v_add_u32_e32 v214, s72, v176
	s_mulk_i32 s21, 0x2200
	s_add_i32 s21, s1, s21
	s_or_b32 s0, s22, s0
	s_waitcnt lgkmcnt(0)
	v_mfma_f32_32x32x16_bf16 v[112:127], v[160:163], v[190:193], v[112:127]
	v_add_u32_e32 v162, s1, v169
	ds_read_b64_tr_b16 v[160:161], v162
	ds_read_b64_tr_b16 v[162:163], v162 offset:2304
	ds_read_b64_tr_b16 v[194:195], v189
	ds_read_b64_tr_b16 v[196:197], v189 offset:2304
	v_add_u32_e32 v189, s71, v188
	s_add_i32 s1, s20, s14
	v_lshlrev_b32_e32 v175, 2, v175
	v_mfma_f32_32x32x16_bf16 v[64:79], v[180:183], v[164:167], v[64:79]
	v_mfma_f32_32x32x16_bf16 v[80:95], v[180:183], v[190:193], v[80:95]
	ds_read_b64_tr_b16 v[180:181], v189
	ds_read_b64_tr_b16 v[182:183], v189 offset:2304
	ds_read_b64_tr_b16 v[198:199], v200
	ds_read_b64_tr_b16 v[200:201], v200 offset:2304
	v_add_u32_e32 v189, s71, v169
	ds_read_b64_tr_b16 v[202:203], v189
	ds_read_b64_tr_b16 v[204:205], v189 offset:2304
	ds_read_b64_tr_b16 v[206:207], v208
	ds_read_b64_tr_b16 v[208:209], v208 offset:2304
	v_add_u32_e32 v189, s72, v172
	ds_read_b128 v[210:213], v189
	ds_read_b128 v[214:217], v214
	v_add_u32_e32 v189, s73, v188
	s_waitcnt lgkmcnt(12)
	v_mfma_f32_32x32x16_bf16 v[32:47], v[160:163], v[164:167], v[32:47]
	v_mfma_f32_32x32x16_bf16 v[48:63], v[160:163], v[190:193], v[48:63]
	v_add_u32_e32 v160, s73, v168
	ds_read_b64_tr_b16 v[218:219], v189
	ds_read_b64_tr_b16 v[220:221], v189 offset:2304
	ds_read_b64_tr_b16 v[222:223], v160
	ds_read_b64_tr_b16 v[224:225], v160 offset:2304
	v_add_u32_e32 v160, s73, v169
	v_add_u32_e32 v161, s73, v170
	ds_read_b64_tr_b16 v[226:227], v160
	ds_read_b64_tr_b16 v[228:229], v160 offset:2304
	ds_read_b64_tr_b16 v[230:231], v161
	ds_read_b64_tr_b16 v[232:233], v161 offset:2304
	v_add_u32_e32 v160, s80, v172
	v_add_u32_e32 v161, s80, v176
	s_waitcnt lgkmcnt(14)
	v_mfma_f32_32x32x16_bf16 v[0:15], v[194:197], v[164:167], v[0:15]
	ds_read_b128 v[234:237], v160
	ds_read_b128 v[238:241], v161
	v_add_u32_e32 v160, s81, v188
	v_add_u32_e32 v161, s81, v168
	v_add_u32_e32 v162, s81, v170
	v_add_u32_e32 v164, s82, v172
	v_add_u32_e32 v165, s82, v176
	v_lshlrev_b32_e32 v172, 1, v178
	v_mfma_f32_32x32x16_bf16 v[16:31], v[194:197], v[190:193], v[16:31]
	v_lshrrev_b32_e32 v194, 3, v187
	ds_read_b64_tr_b16 v[188:189], v160
	ds_read_b64_tr_b16 v[190:191], v160 offset:2304
	ds_read_b64_tr_b16 v[242:243], v161
	ds_read_b64_tr_b16 v[244:245], v161 offset:2304
	v_add_u32_e32 v160, s81, v169
	ds_read_b64_tr_b16 v[246:247], v160
	ds_read_b64_tr_b16 v[248:249], v160 offset:2304
	ds_read_b64_tr_b16 v[160:161], v162
	ds_read_b64_tr_b16 v[162:163], v162 offset:2304
	ds_read_b128 v[250:253], v164
	ds_read_b128 v[164:167], v165
	s_waitcnt vmcnt(5)
	ds_write_b128 v177, v[136:139]
	ds_write_b128 v177, v[128:131] offset:9216
	ds_write_b128 v177, v[132:135] offset:18432
	s_waitcnt vmcnt(3)
	ds_write_b128 v177, v[144:147] offset:27648
	ds_write_b128 v171, v[140:143] offset:36864
	s_waitcnt vmcnt(2)
	ds_write_b128 v171, v[148:151] offset:46080
	s_waitcnt vmcnt(1)
	ds_write_b128 v171, v[152:155] offset:55296
	s_waitcnt vmcnt(0)
	ds_write_b128 v171, v[156:159] offset:64512
	s_waitcnt lgkmcnt(14)
	v_mfma_f32_32x32x16_bf16 v[96:111], v[180:183], v[210:213], v[96:111]
	s_waitcnt lgkmcnt(0)
	s_barrier
	v_or_b32_e32 v176, s0, v178
	v_ashrrev_i32_e32 v177, 31, v176
	v_lshl_add_u32 v195, v178, 2, s21
	v_mul_u32_u24_e32 v178, 0x440, v186
	v_mfma_f32_32x32x16_bf16 v[112:127], v[180:183], v[214:217], v[112:127]
	v_or_b32_e32 v180, s1, v194
	v_ashrrev_i32_e32 v181, 31, v180
	v_or_b32_e32 v130, 8, v180
	s_ashr_i32 s1, s0, 31
	v_lshlrev_b64 v[128:129], 11, v[180:181]
	v_ashrrev_i32_e32 v131, 31, v130
	v_lshl_add_u64 v[128:129], s[6:7], 0, v[128:129]
	s_lshl_b64 s[18:19], s[0:1], 1
	v_lshlrev_b64 v[130:131], 11, v[130:131]
	v_lshl_add_u64 v[128:129], v[128:129], 0, s[18:19]
	v_lshl_add_u64 v[130:131], s[6:7], 0, v[130:131]
	v_lshl_add_u64 v[128:129], v[128:129], 0, v[172:173]
	v_lshl_add_u64 v[130:131], v[130:131], 0, s[18:19]
	v_mfma_f32_32x32x16_bf16 v[64:79], v[198:201], v[210:213], v[64:79]
	v_lshl_add_u64 v[130:131], v[130:131], 0, v[172:173]
	s_ashr_i32 s0, s14, 12
	s_mulk_i32 s0, 0xc00
	s_ashr_i32 s1, s0, 31
	s_lshl_b64 s[0:1], s[0:1], 2
	s_add_u32 s0, s78, s0
	s_addc_u32 s1, s79, s1
	v_mfma_f32_32x32x16_bf16 v[80:95], v[198:201], v[214:217], v[80:95]
	global_load_dwordx4 v[196:199], v[128:129], off
	global_load_dwordx4 v[168:171], v[130:131], off
	v_or_b32_e32 v128, 16, v180
	v_ashrrev_i32_e32 v129, 31, v128
	v_or_b32_e32 v130, 24, v180
	v_lshlrev_b64 v[128:129], 11, v[128:129]
	v_ashrrev_i32_e32 v131, 31, v130
	v_lshl_add_u64 v[128:129], s[6:7], 0, v[128:129]
	v_lshlrev_b64 v[130:131], 11, v[130:131]
	v_lshl_add_u64 v[128:129], v[128:129], 0, s[18:19]
	v_lshl_add_u64 v[130:131], s[6:7], 0, v[130:131]
	v_lshl_add_u64 v[128:129], v[128:129], 0, v[172:173]
	v_lshl_add_u64 v[130:131], v[130:131], 0, s[18:19]
	v_lshl_add_u64 v[130:131], v[130:131], 0, v[172:173]
	global_load_dwordx4 v[156:159], v[128:129], off
	global_load_dwordx4 v[152:155], v[130:131], off
	v_lshl_add_u64 v[128:129], v[176:177], 2, s[0:1]
	v_lshl_add_u64 v[130:131], v[128:129], 0, s[12:13]
	v_add_co_u32_e32 v128, vcc, s83, v128
	v_or_b32_e32 v136, 32, v180
	s_nop 0
	v_addc_co_u32_e32 v129, vcc, 0, v129, vcc
	global_load_dwordx4 v[132:135], v[128:129], off
	s_nop 0
	global_load_dwordx4 v[128:131], v[130:131], off offset:16
	v_or_b32_e32 v138, 40, v180
	v_ashrrev_i32_e32 v137, 31, v136
	v_ashrrev_i32_e32 v139, 31, v138
	v_lshlrev_b64 v[136:137], 11, v[136:137]
	v_lshlrev_b64 v[138:139], 11, v[138:139]
	v_lshl_add_u64 v[136:137], s[6:7], 0, v[136:137]
	v_lshl_add_u64 v[138:139], s[6:7], 0, v[138:139]
	v_lshl_add_u64 v[136:137], v[136:137], 0, s[18:19]
	v_lshl_add_u64 v[138:139], v[138:139], 0, s[18:19]
	v_lshl_add_u64 v[136:137], v[136:137], 0, v[172:173]
	v_lshl_add_u64 v[138:139], v[138:139], 0, v[172:173]
	global_load_dwordx4 v[148:151], v[136:137], off
	global_load_dwordx4 v[144:147], v[138:139], off
	v_or_b32_e32 v136, 48, v180
	v_or_b32_e32 v138, 56, v180
	v_ashrrev_i32_e32 v137, 31, v136
	v_ashrrev_i32_e32 v139, 31, v138
	v_lshlrev_b64 v[136:137], 11, v[136:137]
	v_lshlrev_b64 v[138:139], 11, v[138:139]
	v_lshl_add_u64 v[136:137], s[6:7], 0, v[136:137]
	v_lshl_add_u64 v[138:139], s[6:7], 0, v[138:139]
	v_lshl_add_u64 v[136:137], v[136:137], 0, s[18:19]
	v_lshl_add_u64 v[138:139], v[138:139], 0, s[18:19]
	v_lshl_add_u64 v[136:137], v[136:137], 0, v[172:173]
	v_lshl_add_u64 v[138:139], v[138:139], 0, v[172:173]
	global_load_dwordx4 v[140:143], v[136:137], off
	s_nop 0
	global_load_dwordx4 v[136:139], v[138:139], off
	v_mfma_f32_32x32x16_bf16 v[96:111], v[218:221], v[234:237], v[96:111]
	v_add3_u32 v186, s21, v175, v178
	v_add_u32_e32 v187, 0x800, v186
	v_add_u32_e32 v192, 0x1a00, v186
	v_add_u32_e32 v193, 0x1c00, v186
	v_or_b32_e32 v181, s20, v194
	v_cmp_eq_u32_e32 vcc, 0, v185
	v_mfma_f32_32x32x16_bf16 v[112:127], v[218:221], v[238:241], v[112:127]
	v_mfma_f32_32x32x16_bf16 v[96:111], v[188:191], v[250:253], v[96:111]
	v_mfma_f32_32x32x16_bf16 v[112:127], v[188:191], v[164:167], v[112:127]
	s_nop 11
	ds_write2_b32 v186, v96, v112 offset1:32
	ds_write2_b32 v186, v97, v113 offset0:68 offset1:100
	ds_write2_b32 v186, v98, v114 offset0:136 offset1:168
	ds_write2_b32 v186, v99, v115 offset0:204 offset1:236
	v_add_u32_e32 v189, 0xa00, v186
	v_add_u32_e32 v188, 0x1000, v186
	v_and_b32_e32 v97, 64, v184
	ds_write2_b32 v187, v100, v116 offset0:32 offset1:64
	ds_write2_b32 v187, v101, v117 offset0:100 offset1:132
	ds_write2_b32 v187, v102, v118 offset0:168 offset1:200
	ds_write2_b32 v189, v103, v119 offset0:108 offset1:140
	ds_write2_b32 v188, v104, v120 offset0:64 offset1:96
	ds_write2_b32 v188, v105, v121 offset0:132 offset1:164
	ds_write2_b32 v188, v106, v122 offset0:200 offset1:232
	v_add_u32_e32 v190, 0x1400, v186
	v_add_u32_e32 v191, 0x1800, v186
	v_xor_b32_e32 v96, 1, v184
	v_add_u32_e32 v106, 64, v97
	ds_write2_b32 v190, v107, v123 offset0:12 offset1:44
	ds_write2_b32 v191, v108, v124 offset0:96 offset1:128
	ds_write2_b32 v191, v109, v125 offset0:164 offset1:196
	ds_write2_b32 v192, v110, v126 offset0:104 offset1:136
	ds_write2_b32 v193, v111, v127 offset0:44 offset1:76
	v_cmp_lt_i32_e64 s[0:1], v96, v106
	s_waitcnt lgkmcnt(0)
	v_mad_u32_u24 v100, v194, s84, v195
	s_waitcnt vmcnt(9)
	v_lshlrev_b32_e32 v104, 16, v196
	v_cndmask_b32_e64 v96, v184, v96, s[0:1]
	v_lshlrev_b32_e32 v175, 2, v96
	ds_read_b128 v[96:99], v100
	ds_read_b128 v[100:103], v100 offset:16
	v_and_b32_e32 v105, 0xffff0000, v196
	v_mfma_f32_32x32x16_bf16 v[32:47], v[202:205], v[210:213], v[32:47]
	v_xor_b32_e32 v107, 2, v184
	s_waitcnt vmcnt(5) lgkmcnt(1)
	v_fma_f32 v112, v132, v96, v104
	v_fma_f32 v113, v133, v97, v105
	v_lshlrev_b32_e32 v96, 16, v197
	v_and_b32_e32 v97, 0xffff0000, v197
	v_pk_fma_f32 v[114:115], v[134:135], v[98:99], v[96:97]
	v_lshlrev_b32_e32 v96, 16, v198
	v_and_b32_e32 v97, 0xffff0000, v198
	v_mfma_f32_32x32x16_bf16 v[48:63], v[202:205], v[214:217], v[48:63]
	s_waitcnt vmcnt(4) lgkmcnt(0)
	v_fma_f32 v116, v128, v100, v96
	v_fma_f32 v117, v129, v101, v97
	v_lshlrev_b32_e32 v96, 16, v199
	v_and_b32_e32 v97, 0xffff0000, v199
	v_pk_fma_f32 v[118:119], v[130:131], v[102:103], v[96:97]
	v_pk_mul_f32 v[96:97], v[112:113], v[112:113]
	v_pk_mul_f32 v[100:101], v[116:117], v[116:117]
	v_pk_mul_f32 v[98:99], v[114:115], v[114:115]
	v_mfma_f32_32x32x16_bf16 v[0:15], v[206:209], v[210:213], v[0:15]
	v_mul_f32_e64 v102, v118, v118
	v_mul_f32_e64 v103, v119, v119
	v_add_f32_e32 v96, v96, v97
	v_add_f32_e32 v97, v100, v101
	v_add_f32_e32 v96, v98, v96
	v_add_f32_e32 v97, v102, v97
	v_add_f32_e32 v96, v99, v96
	v_add_f32_e32 v97, v103, v97
	v_mfma_f32_32x32x16_bf16 v[16:31], v[206:209], v[214:217], v[16:31]
	v_add_f32_e32 v96, v96, v97
	ds_bpermute_b32 v97, v175, v96
	v_cmp_lt_i32_e64 s[0:1], v107, v106
	s_waitcnt lgkmcnt(0)
	v_add_f32_e32 v96, v96, v97
	v_mfma_f32_32x32x16_bf16 v[64:79], v[222:225], v[234:237], v[64:79]
	v_cndmask_b32_e64 v98, v184, v107, s[0:1]
	v_lshlrev_b32_e32 v178, 2, v98
	ds_bpermute_b32 v97, v178, v96
	v_xor_b32_e32 v98, 4, v184
	v_cmp_lt_i32_e64 s[0:1], v98, v106
	s_waitcnt lgkmcnt(0)
	v_add_f32_e32 v96, v96, v97
	v_mfma_f32_32x32x16_bf16 v[80:95], v[222:225], v[238:241], v[80:95]
	v_cndmask_b32_e64 v98, v184, v98, s[0:1]
	v_lshlrev_b32_e32 v183, 2, v98
	ds_bpermute_b32 v97, v183, v96
	s_lshl_b32 s0, s15, 2
	s_add_i32 s15, s0, 0
	s_add_i32 s15, s15, 0x24000
	v_lshl_add_u32 v182, v181, 4, s15
	v_mfma_f32_32x32x16_bf16 v[32:47], v[226:229], v[234:237], v[32:47]
	v_mfma_f32_32x32x16_bf16 v[48:63], v[226:229], v[238:241], v[48:63]
	v_mfma_f32_32x32x16_bf16 v[0:15], v[230:233], v[234:237], v[0:15]
	v_mfma_f32_32x32x16_bf16 v[16:31], v[230:233], v[238:241], v[16:31]
	v_mfma_f32_32x32x16_bf16 v[64:79], v[242:245], v[250:253], v[64:79]
	v_mfma_f32_32x32x16_bf16 v[80:95], v[242:245], v[164:167], v[80:95]
	v_mfma_f32_32x32x16_bf16 v[32:47], v[246:249], v[250:253], v[32:47]
	v_mfma_f32_32x32x16_bf16 v[48:63], v[246:249], v[164:167], v[48:63]
	v_mfma_f32_32x32x16_bf16 v[0:15], v[160:163], v[250:253], v[0:15]
	v_mfma_f32_32x32x16_bf16 v[16:31], v[160:163], v[164:167], v[16:31]
	s_and_saveexec_b64 s[0:1], vcc
	s_cbranch_execz .LBB0_1892
	s_waitcnt lgkmcnt(0)
	v_add_f32_e32 v96, v96, v97
	ds_write_b32 v182, v96
.LBB0_1892:
	s_or_b64 exec, exec, s[0:1]
	v_mul_u32_u24_e32 v96, 0x110, v194
	v_add_u32_e32 v185, v195, v96
	s_waitcnt lgkmcnt(0)
	ds_read_b128 v[96:99], v185 offset:2176
	ds_read_b128 v[100:103], v185 offset:2192
	v_lshlrev_b32_e32 v104, 16, v168
	v_and_b32_e32 v105, 0xffff0000, v168
	v_lshlrev_b32_e32 v106, 16, v169
	s_waitcnt lgkmcnt(1)
	v_pk_fma_f32 v[120:121], v[132:133], v[96:97], v[104:105]
	v_lshlrev_b32_e32 v96, 16, v170
	v_and_b32_e32 v97, 0xffff0000, v170
	v_and_b32_e32 v107, 0xffff0000, v169
	s_waitcnt lgkmcnt(0)
	v_pk_fma_f32 v[124:125], v[128:129], v[100:101], v[96:97]
	v_lshlrev_b32_e32 v96, 16, v171
	v_and_b32_e32 v97, 0xffff0000, v171
	v_pk_fma_f32 v[122:123], v[134:135], v[98:99], v[106:107]
	v_pk_fma_f32 v[126:127], v[130:131], v[102:103], v[96:97]
	v_pk_mul_f32 v[96:97], v[120:121], v[120:121]
	v_pk_mul_f32 v[100:101], v[124:125], v[124:125]
	v_pk_mul_f32 v[98:99], v[122:123], v[122:123]
	v_pk_mul_f32 v[102:103], v[126:127], v[126:127]
	v_add_f32_e32 v100, v100, v101
	v_add_f32_e32 v96, v96, v97
	v_add_f32_e32 v100, v102, v100
	v_add_f32_e32 v96, v98, v96
	v_add_f32_e32 v100, v103, v100
	v_add_f32_e32 v96, v99, v96
	v_add_f32_e32 v96, v96, v100
	ds_bpermute_b32 v97, v175, v96
	s_waitcnt lgkmcnt(0)
	v_add_f32_e32 v96, v96, v97
	ds_bpermute_b32 v97, v178, v96
	s_waitcnt lgkmcnt(0)
	v_add_f32_e32 v96, v96, v97
	ds_bpermute_b32 v97, v183, v96
	s_and_saveexec_b64 s[0:1], vcc
	s_cbranch_execz .LBB0_1894
	s_waitcnt lgkmcnt(0)
	v_add_f32_e32 v96, v96, v97
	ds_write_b32 v182, v96 offset:128
.LBB0_1894:
	s_or_b64 exec, exec, s[0:1]
	s_waitcnt lgkmcnt(0)
	ds_read_b128 v[96:99], v185 offset:4352
	ds_read_b128 v[100:103], v185 offset:4368
	v_lshlrev_b32_e32 v104, 16, v156
	v_and_b32_e32 v105, 0xffff0000, v156
	v_lshlrev_b32_e32 v106, 16, v157
	s_waitcnt lgkmcnt(1)
	v_pk_fma_f32 v[160:161], v[132:133], v[96:97], v[104:105]
	v_lshlrev_b32_e32 v96, 16, v158
	v_and_b32_e32 v97, 0xffff0000, v158
	v_and_b32_e32 v107, 0xffff0000, v157
	s_waitcnt lgkmcnt(0)
	v_pk_fma_f32 v[162:163], v[128:129], v[100:101], v[96:97]
	v_lshlrev_b32_e32 v96, 16, v159
	v_and_b32_e32 v97, 0xffff0000, v159
	v_pk_fma_f32 v[156:157], v[134:135], v[98:99], v[106:107]
	v_pk_fma_f32 v[158:159], v[130:131], v[102:103], v[96:97]
	v_pk_mul_f32 v[96:97], v[160:161], v[160:161]
	v_pk_mul_f32 v[100:101], v[162:163], v[162:163]
	v_pk_mul_f32 v[98:99], v[156:157], v[156:157]
	v_pk_mul_f32 v[102:103], v[158:159], v[158:159]
	v_add_f32_e32 v100, v100, v101
	v_add_f32_e32 v96, v96, v97
	v_add_f32_e32 v100, v102, v100
	v_add_f32_e32 v96, v98, v96
	v_add_f32_e32 v100, v103, v100
	v_add_f32_e32 v96, v99, v96
	v_add_f32_e32 v96, v96, v100
	ds_bpermute_b32 v97, v175, v96
	s_waitcnt lgkmcnt(0)
	v_add_f32_e32 v96, v96, v97
	ds_bpermute_b32 v97, v178, v96
	s_waitcnt lgkmcnt(0)
	v_add_f32_e32 v96, v96, v97
	ds_bpermute_b32 v97, v183, v96
	s_and_saveexec_b64 s[0:1], vcc
	s_cbranch_execz .LBB0_1896
	s_waitcnt lgkmcnt(0)
	v_add_f32_e32 v96, v96, v97
	ds_write_b32 v182, v96 offset:256
.LBB0_1896:
	s_or_b64 exec, exec, s[0:1]
	s_waitcnt lgkmcnt(0)
	ds_read_b128 v[96:99], v185 offset:6528
	ds_read_b128 v[100:103], v185 offset:6544
	v_lshlrev_b32_e32 v104, 16, v152
	v_and_b32_e32 v105, 0xffff0000, v152
	v_lshlrev_b32_e32 v106, 16, v153
	s_waitcnt lgkmcnt(1)
	v_pk_fma_f32 v[164:165], v[132:133], v[96:97], v[104:105]
	v_lshlrev_b32_e32 v96, 16, v154
	v_and_b32_e32 v97, 0xffff0000, v154
	v_and_b32_e32 v107, 0xffff0000, v153
	s_waitcnt lgkmcnt(0)
	v_pk_fma_f32 v[166:167], v[128:129], v[100:101], v[96:97]
	v_lshlrev_b32_e32 v96, 16, v155
	v_and_b32_e32 v97, 0xffff0000, v155
	v_pk_fma_f32 v[152:153], v[134:135], v[98:99], v[106:107]
	v_pk_fma_f32 v[154:155], v[130:131], v[102:103], v[96:97]
	v_pk_mul_f32 v[96:97], v[164:165], v[164:165]
	v_pk_mul_f32 v[100:101], v[166:167], v[166:167]
	v_pk_mul_f32 v[98:99], v[152:153], v[152:153]
	v_pk_mul_f32 v[102:103], v[154:155], v[154:155]
	v_add_f32_e32 v100, v100, v101
	v_add_f32_e32 v96, v96, v97
	v_add_f32_e32 v100, v102, v100
	v_add_f32_e32 v96, v98, v96
	v_add_f32_e32 v100, v103, v100
	v_add_f32_e32 v96, v99, v96
	v_add_f32_e32 v96, v96, v100
	ds_bpermute_b32 v97, v175, v96
	s_waitcnt lgkmcnt(0)
	v_add_f32_e32 v96, v96, v97
	ds_bpermute_b32 v97, v178, v96
	s_waitcnt lgkmcnt(0)
	v_add_f32_e32 v96, v96, v97
	ds_bpermute_b32 v97, v183, v96
	s_and_saveexec_b64 s[0:1], vcc
	s_cbranch_execz .LBB0_1898
	s_waitcnt lgkmcnt(0)
	v_add_f32_e32 v96, v96, v97
	ds_write_b32 v182, v96 offset:384
.LBB0_1898:
	s_or_b64 exec, exec, s[0:1]
	v_or_b32_e32 v96, 64, v180
	v_or_b32_e32 v98, 0x48, v180
	s_waitcnt lgkmcnt(0)
	v_ashrrev_i32_e32 v97, 31, v96
	v_ashrrev_i32_e32 v99, 31, v98
	v_lshlrev_b64 v[96:97], 11, v[96:97]
	v_lshlrev_b64 v[98:99], 11, v[98:99]
	v_lshl_add_u64 v[96:97], s[6:7], 0, v[96:97]
	v_lshl_add_u64 v[98:99], s[6:7], 0, v[98:99]
	v_lshl_add_u64 v[96:97], v[96:97], 0, s[18:19]
	v_lshl_add_u64 v[98:99], v[98:99], 0, s[18:19]
	s_waitcnt lgkmcnt(0)
	v_lshl_add_u64 v[96:97], v[96:97], 0, v[172:173]
	v_lshl_add_u64 v[98:99], v[98:99], 0, v[172:173]
	global_load_dwordx4 v[108:111], v[96:97], off
	global_load_dwordx4 v[104:107], v[98:99], off
	v_or_b32_e32 v96, 0x50, v180
	v_or_b32_e32 v98, 0x58, v180
	v_ashrrev_i32_e32 v97, 31, v96
	v_ashrrev_i32_e32 v99, 31, v98
	v_lshlrev_b64 v[96:97], 11, v[96:97]
	v_lshlrev_b64 v[98:99], 11, v[98:99]
	v_lshl_add_u64 v[96:97], s[6:7], 0, v[96:97]
	v_lshl_add_u64 v[98:99], s[6:7], 0, v[98:99]
	v_lshl_add_u64 v[96:97], v[96:97], 0, s[18:19]
	v_lshl_add_u64 v[98:99], v[98:99], 0, s[18:19]
	v_lshl_add_u64 v[96:97], v[96:97], 0, v[172:173]
	v_lshl_add_u64 v[98:99], v[98:99], 0, v[172:173]
	global_load_dwordx4 v[100:103], v[96:97], off
	s_nop 0
	global_load_dwordx4 v[96:99], v[98:99], off
	ds_write2_b32 v186, v64, v80 offset1:32
	ds_write2_b32 v186, v65, v81 offset0:68 offset1:100
	ds_write2_b32 v186, v66, v82 offset0:136 offset1:168
	ds_write2_b32 v186, v67, v83 offset0:204 offset1:236
	ds_write2_b32 v187, v68, v84 offset0:32 offset1:64
	ds_write2_b32 v187, v69, v85 offset0:100 offset1:132
	ds_write2_b32 v187, v70, v86 offset0:168 offset1:200
	ds_write2_b32 v189, v71, v87 offset0:108 offset1:140
	ds_write2_b32 v188, v72, v88 offset0:64 offset1:96
	ds_write2_b32 v188, v73, v89 offset0:132 offset1:164
	ds_write2_b32 v188, v74, v90 offset0:200 offset1:232
	ds_write2_b32 v190, v75, v91 offset0:12 offset1:44
	ds_write2_b32 v191, v76, v92 offset0:96 offset1:128
	ds_write2_b32 v191, v77, v93 offset0:164 offset1:196
	ds_write2_b32 v192, v78, v94 offset0:104 offset1:136
	ds_write2_b32 v193, v79, v95 offset0:44 offset1:76
	s_waitcnt lgkmcnt(0)
	ds_read_b128 v[64:67], v185
	ds_read_b128 v[68:71], v185 offset:16
	s_waitcnt vmcnt(7)
	v_lshlrev_b32_e32 v72, 16, v148
	v_and_b32_e32 v73, 0xffff0000, v148
	v_or_b32_e32 v168, 32, v181
	s_waitcnt lgkmcnt(1)
	v_pk_fma_f32 v[80:81], v[132:133], v[64:65], v[72:73]
	v_lshlrev_b32_e32 v64, 16, v149
	v_and_b32_e32 v65, 0xffff0000, v149
	v_pk_fma_f32 v[82:83], v[134:135], v[66:67], v[64:65]
	v_lshlrev_b32_e32 v64, 16, v150
	v_and_b32_e32 v65, 0xffff0000, v150
	s_waitcnt lgkmcnt(0)
	v_pk_fma_f32 v[84:85], v[128:129], v[68:69], v[64:65]
	v_lshlrev_b32_e32 v64, 16, v151
	v_and_b32_e32 v65, 0xffff0000, v151
	v_pk_fma_f32 v[86:87], v[130:131], v[70:71], v[64:65]
	v_pk_mul_f32 v[64:65], v[80:81], v[80:81]
	v_pk_mul_f32 v[68:69], v[84:85], v[84:85]
	v_pk_mul_f32 v[66:67], v[82:83], v[82:83]
	v_pk_mul_f32 v[70:71], v[86:87], v[86:87]
	v_add_f32_e32 v68, v68, v69
	v_add_f32_e32 v64, v64, v65
	v_add_f32_e32 v68, v70, v68
	v_add_f32_e32 v64, v66, v64
	v_add_f32_e32 v68, v71, v68
	v_add_f32_e32 v64, v67, v64
	v_add_f32_e32 v64, v64, v68
	ds_bpermute_b32 v65, v175, v64
	s_waitcnt lgkmcnt(0)
	v_add_f32_e32 v64, v64, v65
	ds_bpermute_b32 v65, v178, v64
	s_waitcnt lgkmcnt(0)
	v_add_f32_e32 v64, v64, v65
	ds_bpermute_b32 v65, v183, v64
	s_and_saveexec_b64 s[0:1], vcc
	s_cbranch_execz .LBB0_1900
	v_lshl_add_u32 v66, v168, 4, s15
	s_waitcnt lgkmcnt(0)
	v_add_f32_e32 v64, v64, v65
	ds_write_b32 v66, v64
.LBB0_1900:
	s_or_b64 exec, exec, s[0:1]
	s_waitcnt lgkmcnt(0)
	ds_read_b128 v[64:67], v185 offset:2176
	ds_read_b128 v[68:71], v185 offset:2192
	s_waitcnt vmcnt(6)
	v_lshlrev_b32_e32 v72, 16, v144
	v_and_b32_e32 v73, 0xffff0000, v144
	v_lshlrev_b32_e32 v74, 16, v145
	s_waitcnt lgkmcnt(1)
	v_pk_fma_f32 v[88:89], v[132:133], v[64:65], v[72:73]
	v_lshlrev_b32_e32 v64, 16, v146
	v_and_b32_e32 v65, 0xffff0000, v146
	v_and_b32_e32 v75, 0xffff0000, v145
	s_waitcnt lgkmcnt(0)
	v_pk_fma_f32 v[92:93], v[128:129], v[68:69], v[64:65]
	v_lshlrev_b32_e32 v64, 16, v147
	v_and_b32_e32 v65, 0xffff0000, v147
	v_pk_fma_f32 v[90:91], v[134:135], v[66:67], v[74:75]
	v_pk_fma_f32 v[94:95], v[130:131], v[70:71], v[64:65]
	v_pk_mul_f32 v[64:65], v[88:89], v[88:89]
	v_pk_mul_f32 v[68:69], v[92:93], v[92:93]
	v_pk_mul_f32 v[66:67], v[90:91], v[90:91]
	v_pk_mul_f32 v[70:71], v[94:95], v[94:95]
	v_add_f32_e32 v68, v68, v69
	v_add_f32_e32 v64, v64, v65
	v_add_f32_e32 v68, v70, v68
	v_add_f32_e32 v64, v66, v64
	v_add_f32_e32 v68, v71, v68
	v_add_f32_e32 v64, v67, v64
	v_add_f32_e32 v64, v64, v68
	ds_bpermute_b32 v65, v175, v64
	s_waitcnt lgkmcnt(0)
	v_add_f32_e32 v64, v64, v65
	ds_bpermute_b32 v65, v178, v64
	s_waitcnt lgkmcnt(0)
	v_add_f32_e32 v64, v64, v65
	ds_bpermute_b32 v65, v183, v64
	s_and_saveexec_b64 s[0:1], vcc
	s_cbranch_execz .LBB0_1902
	s_waitcnt lgkmcnt(0)
	v_add_f32_e32 v64, v64, v65
	ds_write_b32 v182, v64 offset:640
.LBB0_1902:
	s_or_b64 exec, exec, s[0:1]
	s_waitcnt lgkmcnt(0)
	ds_read_b128 v[64:67], v185 offset:4352
	ds_read_b128 v[68:71], v185 offset:4368
	s_waitcnt vmcnt(5)
	v_lshlrev_b32_e32 v72, 16, v140
	v_and_b32_e32 v73, 0xffff0000, v140
	v_lshlrev_b32_e32 v74, 16, v141
	s_waitcnt lgkmcnt(1)
	v_pk_fma_f32 v[144:145], v[132:133], v[64:65], v[72:73]
	v_lshlrev_b32_e32 v64, 16, v142
	v_and_b32_e32 v65, 0xffff0000, v142
	v_and_b32_e32 v75, 0xffff0000, v141
	s_waitcnt lgkmcnt(0)
	v_pk_fma_f32 v[146:147], v[128:129], v[68:69], v[64:65]
	v_lshlrev_b32_e32 v64, 16, v143
	v_and_b32_e32 v65, 0xffff0000, v143
	v_pk_fma_f32 v[140:141], v[134:135], v[66:67], v[74:75]
	v_pk_fma_f32 v[142:143], v[130:131], v[70:71], v[64:65]
	v_pk_mul_f32 v[64:65], v[144:145], v[144:145]
	v_pk_mul_f32 v[68:69], v[146:147], v[146:147]
	v_pk_mul_f32 v[66:67], v[140:141], v[140:141]
	v_pk_mul_f32 v[70:71], v[142:143], v[142:143]
	v_add_f32_e32 v68, v68, v69
	v_add_f32_e32 v64, v64, v65
	v_add_f32_e32 v68, v70, v68
	v_add_f32_e32 v64, v66, v64
	v_add_f32_e32 v68, v71, v68
	v_add_f32_e32 v64, v67, v64
	v_add_f32_e32 v64, v64, v68
	ds_bpermute_b32 v65, v175, v64
	s_waitcnt lgkmcnt(0)
	v_add_f32_e32 v64, v64, v65
	ds_bpermute_b32 v65, v178, v64
	s_waitcnt lgkmcnt(0)
	v_add_f32_e32 v64, v64, v65
	ds_bpermute_b32 v65, v183, v64
	s_and_saveexec_b64 s[0:1], vcc
	s_cbranch_execz .LBB0_1904
	s_waitcnt lgkmcnt(0)
	v_add_f32_e32 v64, v64, v65
	ds_write_b32 v182, v64 offset:768
.LBB0_1904:
	s_or_b64 exec, exec, s[0:1]
	s_waitcnt lgkmcnt(0)
	ds_read_b128 v[64:67], v185 offset:6528
	ds_read_b128 v[68:71], v185 offset:6544
	s_waitcnt vmcnt(4)
	v_lshlrev_b32_e32 v72, 16, v136
	v_and_b32_e32 v73, 0xffff0000, v136
	v_lshlrev_b32_e32 v74, 16, v137
	s_waitcnt lgkmcnt(1)
	v_pk_fma_f32 v[148:149], v[132:133], v[64:65], v[72:73]
	v_lshlrev_b32_e32 v64, 16, v138
	v_and_b32_e32 v65, 0xffff0000, v138
	v_and_b32_e32 v75, 0xffff0000, v137
	s_waitcnt lgkmcnt(0)
	v_pk_fma_f32 v[150:151], v[128:129], v[68:69], v[64:65]
	v_lshlrev_b32_e32 v64, 16, v139
	v_and_b32_e32 v65, 0xffff0000, v139
	v_pk_fma_f32 v[136:137], v[134:135], v[66:67], v[74:75]
	v_pk_fma_f32 v[138:139], v[130:131], v[70:71], v[64:65]
	v_pk_mul_f32 v[64:65], v[148:149], v[148:149]
	v_pk_mul_f32 v[68:69], v[150:151], v[150:151]
	v_pk_mul_f32 v[66:67], v[136:137], v[136:137]
	v_pk_mul_f32 v[70:71], v[138:139], v[138:139]
	v_add_f32_e32 v68, v68, v69
	v_add_f32_e32 v64, v64, v65
	v_add_f32_e32 v68, v70, v68
	v_add_f32_e32 v64, v66, v64
	v_add_f32_e32 v68, v71, v68
	v_add_f32_e32 v64, v67, v64
	v_add_f32_e32 v64, v64, v68
	ds_bpermute_b32 v65, v175, v64
	s_waitcnt lgkmcnt(0)
	v_add_f32_e32 v64, v64, v65
	ds_bpermute_b32 v65, v178, v64
	s_waitcnt lgkmcnt(0)
	v_add_f32_e32 v64, v64, v65
	ds_bpermute_b32 v65, v183, v64
	s_and_saveexec_b64 s[0:1], vcc
	s_cbranch_execz .LBB0_1906
	s_waitcnt lgkmcnt(0)
	v_add_f32_e32 v64, v64, v65
	ds_write_b32 v182, v64 offset:896
.LBB0_1906:
	s_or_b64 exec, exec, s[0:1]
	v_or_b32_e32 v64, 0x60, v180
	v_or_b32_e32 v66, 0x68, v180
	s_waitcnt lgkmcnt(0)
	v_ashrrev_i32_e32 v65, 31, v64
	v_ashrrev_i32_e32 v67, 31, v66
	v_lshlrev_b64 v[64:65], 11, v[64:65]
	v_lshlrev_b64 v[66:67], 11, v[66:67]
	v_lshl_add_u64 v[64:65], s[6:7], 0, v[64:65]
	v_lshl_add_u64 v[66:67], s[6:7], 0, v[66:67]
	v_lshl_add_u64 v[64:65], v[64:65], 0, s[18:19]
	v_lshl_add_u64 v[66:67], v[66:67], 0, s[18:19]
	s_waitcnt lgkmcnt(0)
	v_lshl_add_u64 v[64:65], v[64:65], 0, v[172:173]
	v_lshl_add_u64 v[66:67], v[66:67], 0, v[172:173]
	global_load_dwordx4 v[76:79], v[64:65], off
	global_load_dwordx4 v[72:75], v[66:67], off
	v_or_b32_e32 v64, 0x70, v180
	v_or_b32_e32 v66, 0x78, v180
	v_ashrrev_i32_e32 v65, 31, v64
	v_ashrrev_i32_e32 v67, 31, v66
	v_lshlrev_b64 v[64:65], 11, v[64:65]
	v_lshlrev_b64 v[66:67], 11, v[66:67]
	v_lshl_add_u64 v[64:65], s[6:7], 0, v[64:65]
	v_lshl_add_u64 v[66:67], s[6:7], 0, v[66:67]
	v_lshl_add_u64 v[64:65], v[64:65], 0, s[18:19]
	v_lshl_add_u64 v[66:67], v[66:67], 0, s[18:19]
	v_lshl_add_u64 v[64:65], v[64:65], 0, v[172:173]
	v_lshl_add_u64 v[66:67], v[66:67], 0, v[172:173]
	global_load_dwordx4 v[68:71], v[64:65], off
	s_nop 0
	global_load_dwordx4 v[64:67], v[66:67], off
	ds_write2_b32 v186, v32, v48 offset1:32
	ds_write2_b32 v186, v33, v49 offset0:68 offset1:100
	ds_write2_b32 v186, v34, v50 offset0:136 offset1:168
	ds_write2_b32 v186, v35, v51 offset0:204 offset1:236
	ds_write2_b32 v187, v36, v52 offset0:32 offset1:64
	ds_write2_b32 v187, v37, v53 offset0:100 offset1:132
	ds_write2_b32 v187, v38, v54 offset0:168 offset1:200
	ds_write2_b32 v189, v39, v55 offset0:108 offset1:140
	ds_write2_b32 v188, v40, v56 offset0:64 offset1:96
	ds_write2_b32 v188, v41, v57 offset0:132 offset1:164
	ds_write2_b32 v188, v42, v58 offset0:200 offset1:232
	ds_write2_b32 v190, v43, v59 offset0:12 offset1:44
	ds_write2_b32 v191, v44, v60 offset0:96 offset1:128
	ds_write2_b32 v191, v45, v61 offset0:164 offset1:196
	ds_write2_b32 v192, v46, v62 offset0:104 offset1:136
	ds_write2_b32 v193, v47, v63 offset0:44 offset1:76
	s_waitcnt lgkmcnt(0)
	ds_read_b128 v[32:35], v185
	ds_read_b128 v[36:39], v185 offset:16
	s_waitcnt vmcnt(7)
	v_lshlrev_b32_e32 v40, 16, v108
	v_and_b32_e32 v41, 0xffff0000, v108
	v_or_b32_e32 v108, 64, v181
	s_waitcnt lgkmcnt(1)
	v_pk_fma_f32 v[32:33], v[132:133], v[32:33], v[40:41]
	v_lshlrev_b32_e32 v40, 16, v109
	v_and_b32_e32 v41, 0xffff0000, v109
	v_pk_fma_f32 v[34:35], v[134:135], v[34:35], v[40:41]
	v_lshlrev_b32_e32 v40, 16, v110
	v_and_b32_e32 v41, 0xffff0000, v110
	s_waitcnt lgkmcnt(0)
	v_pk_fma_f32 v[36:37], v[128:129], v[36:37], v[40:41]
	v_lshlrev_b32_e32 v40, 16, v111
	v_and_b32_e32 v41, 0xffff0000, v111
	v_pk_fma_f32 v[38:39], v[130:131], v[38:39], v[40:41]
	v_pk_mul_f32 v[40:41], v[32:33], v[32:33]
	v_pk_mul_f32 v[44:45], v[36:37], v[36:37]
	v_pk_mul_f32 v[42:43], v[34:35], v[34:35]
	v_pk_mul_f32 v[46:47], v[38:39], v[38:39]
	v_add_f32_e32 v44, v44, v45
	v_add_f32_e32 v40, v40, v41
	v_add_f32_e32 v44, v46, v44
	v_add_f32_e32 v40, v42, v40
	v_add_f32_e32 v44, v47, v44
	v_add_f32_e32 v40, v43, v40
	v_add_f32_e32 v40, v40, v44
	ds_bpermute_b32 v41, v175, v40
	s_waitcnt lgkmcnt(0)
	v_add_f32_e32 v40, v40, v41
	ds_bpermute_b32 v41, v178, v40
	s_waitcnt lgkmcnt(0)
	v_add_f32_e32 v40, v40, v41
	ds_bpermute_b32 v41, v183, v40
	s_and_saveexec_b64 s[0:1], vcc
	s_cbranch_execz .LBB0_1908
	v_lshl_add_u32 v42, v108, 4, s15
	s_waitcnt lgkmcnt(0)
	v_add_f32_e32 v40, v40, v41
	ds_write_b32 v42, v40
.LBB0_1908:
	s_or_b64 exec, exec, s[0:1]
	s_waitcnt lgkmcnt(0)
	ds_read_b128 v[40:43], v185 offset:2176
	ds_read_b128 v[44:47], v185 offset:2192
	s_waitcnt vmcnt(6)
	v_lshlrev_b32_e32 v48, 16, v104
	v_and_b32_e32 v49, 0xffff0000, v104
	v_lshlrev_b32_e32 v50, 16, v105
	s_waitcnt lgkmcnt(1)
	v_pk_fma_f32 v[40:41], v[132:133], v[40:41], v[48:49]
	v_lshlrev_b32_e32 v48, 16, v106
	v_and_b32_e32 v49, 0xffff0000, v106
	v_and_b32_e32 v51, 0xffff0000, v105
	s_waitcnt lgkmcnt(0)
	v_pk_fma_f32 v[44:45], v[128:129], v[44:45], v[48:49]
	v_lshlrev_b32_e32 v48, 16, v107
	v_and_b32_e32 v49, 0xffff0000, v107
	v_pk_fma_f32 v[42:43], v[134:135], v[42:43], v[50:51]
	v_pk_fma_f32 v[46:47], v[130:131], v[46:47], v[48:49]
	v_pk_mul_f32 v[48:49], v[40:41], v[40:41]
	v_pk_mul_f32 v[52:53], v[44:45], v[44:45]
	v_pk_mul_f32 v[50:51], v[42:43], v[42:43]
	v_pk_mul_f32 v[54:55], v[46:47], v[46:47]
	v_add_f32_e32 v52, v52, v53
	v_add_f32_e32 v48, v48, v49
	v_add_f32_e32 v52, v54, v52
	v_add_f32_e32 v48, v50, v48
	v_add_f32_e32 v52, v55, v52
	v_add_f32_e32 v48, v51, v48
	v_add_f32_e32 v48, v48, v52
	ds_bpermute_b32 v49, v175, v48
	s_waitcnt lgkmcnt(0)
	v_add_f32_e32 v48, v48, v49
	ds_bpermute_b32 v49, v178, v48
	s_waitcnt lgkmcnt(0)
	v_add_f32_e32 v48, v48, v49
	ds_bpermute_b32 v49, v183, v48
	s_and_saveexec_b64 s[0:1], vcc
	s_cbranch_execz .LBB0_1910
	s_waitcnt lgkmcnt(0)
	v_add_f32_e32 v48, v48, v49
	ds_write_b32 v182, v48 offset:1152
.LBB0_1910:
	s_or_b64 exec, exec, s[0:1]
	s_waitcnt lgkmcnt(0)
	ds_read_b128 v[48:51], v185 offset:4352
	ds_read_b128 v[52:55], v185 offset:4368
	s_waitcnt vmcnt(5)
	v_lshlrev_b32_e32 v56, 16, v100
	v_and_b32_e32 v57, 0xffff0000, v100
	v_lshlrev_b32_e32 v58, 16, v101
	s_waitcnt lgkmcnt(1)
	v_pk_fma_f32 v[48:49], v[132:133], v[48:49], v[56:57]
	v_lshlrev_b32_e32 v56, 16, v102
	v_and_b32_e32 v57, 0xffff0000, v102
	v_and_b32_e32 v59, 0xffff0000, v101
	s_waitcnt lgkmcnt(0)
	v_pk_fma_f32 v[52:53], v[128:129], v[52:53], v[56:57]
	v_lshlrev_b32_e32 v56, 16, v103
	v_and_b32_e32 v57, 0xffff0000, v103
	v_pk_fma_f32 v[50:51], v[134:135], v[50:51], v[58:59]
	v_pk_fma_f32 v[54:55], v[130:131], v[54:55], v[56:57]
	v_pk_mul_f32 v[56:57], v[48:49], v[48:49]
	v_pk_mul_f32 v[60:61], v[52:53], v[52:53]
	v_pk_mul_f32 v[58:59], v[50:51], v[50:51]
	v_pk_mul_f32 v[62:63], v[54:55], v[54:55]
	v_add_f32_e32 v60, v60, v61
	v_add_f32_e32 v56, v56, v57
	v_add_f32_e32 v60, v62, v60
	v_add_f32_e32 v56, v58, v56
	v_add_f32_e32 v60, v63, v60
	v_add_f32_e32 v56, v59, v56
	v_add_f32_e32 v56, v56, v60
	ds_bpermute_b32 v57, v175, v56
	s_waitcnt lgkmcnt(0)
	v_add_f32_e32 v56, v56, v57
	ds_bpermute_b32 v57, v178, v56
	s_waitcnt lgkmcnt(0)
	v_add_f32_e32 v56, v56, v57
	ds_bpermute_b32 v57, v183, v56
	s_and_saveexec_b64 s[0:1], vcc
	s_cbranch_execz .LBB0_1912
	s_waitcnt lgkmcnt(0)
	v_add_f32_e32 v56, v56, v57
	ds_write_b32 v182, v56 offset:1280
.LBB0_1912:
	s_or_b64 exec, exec, s[0:1]
	s_waitcnt lgkmcnt(0)
	ds_read_b128 v[56:59], v185 offset:6528
	ds_read_b128 v[60:63], v185 offset:6544
	s_waitcnt vmcnt(4)
	v_lshlrev_b32_e32 v100, 16, v96
	v_and_b32_e32 v101, 0xffff0000, v96
	v_lshlrev_b32_e32 v96, 16, v97
	v_and_b32_e32 v97, 0xffff0000, v97
	s_waitcnt lgkmcnt(1)
	v_pk_fma_f32 v[58:59], v[134:135], v[58:59], v[96:97]
	v_lshlrev_b32_e32 v96, 16, v98
	v_and_b32_e32 v97, 0xffff0000, v98
	v_pk_fma_f32 v[56:57], v[132:133], v[56:57], v[100:101]
	s_waitcnt lgkmcnt(0)
	v_pk_fma_f32 v[60:61], v[128:129], v[60:61], v[96:97]
	v_lshlrev_b32_e32 v96, 16, v99
	v_and_b32_e32 v97, 0xffff0000, v99
	v_pk_fma_f32 v[62:63], v[130:131], v[62:63], v[96:97]
	v_pk_mul_f32 v[96:97], v[56:57], v[56:57]
	v_pk_mul_f32 v[100:101], v[60:61], v[60:61]
	v_pk_mul_f32 v[98:99], v[58:59], v[58:59]
	v_pk_mul_f32 v[102:103], v[62:63], v[62:63]
	v_add_f32_e32 v100, v100, v101
	v_add_f32_e32 v96, v96, v97
	v_add_f32_e32 v100, v102, v100
	v_add_f32_e32 v96, v98, v96
	v_add_f32_e32 v100, v103, v100
	v_add_f32_e32 v96, v99, v96
	v_add_f32_e32 v96, v96, v100
	ds_bpermute_b32 v97, v175, v96
	s_waitcnt lgkmcnt(0)
	v_add_f32_e32 v96, v96, v97
	ds_bpermute_b32 v97, v178, v96
	s_waitcnt lgkmcnt(0)
	v_add_f32_e32 v96, v96, v97
	ds_bpermute_b32 v97, v183, v96
	s_and_saveexec_b64 s[0:1], vcc
	s_cbranch_execz .LBB0_1914
	s_waitcnt lgkmcnt(0)
	v_add_f32_e32 v96, v96, v97
	ds_write_b32 v182, v96 offset:1408
.LBB0_1914:
	s_or_b64 exec, exec, s[0:1]
	s_waitcnt lgkmcnt(0)
	ds_write2_b32 v186, v0, v16 offset1:32
	ds_write2_b32 v186, v1, v17 offset0:68 offset1:100
	ds_write2_b32 v186, v2, v18 offset0:136 offset1:168
	ds_write2_b32 v186, v3, v19 offset0:204 offset1:236
	ds_write2_b32 v187, v4, v20 offset0:32 offset1:64
	ds_write2_b32 v187, v5, v21 offset0:100 offset1:132
	ds_write2_b32 v187, v6, v22 offset0:168 offset1:200
	ds_write2_b32 v189, v7, v23 offset0:108 offset1:140
	ds_write2_b32 v188, v8, v24 offset0:64 offset1:96
	ds_write2_b32 v188, v9, v25 offset0:132 offset1:164
	ds_write2_b32 v188, v10, v26 offset0:200 offset1:232
	ds_write2_b32 v190, v11, v27 offset0:12 offset1:44
	ds_write2_b32 v191, v12, v28 offset0:96 offset1:128
	ds_write2_b32 v191, v13, v29 offset0:164 offset1:196
	ds_write2_b32 v192, v14, v30 offset0:104 offset1:136
	ds_write2_b32 v193, v15, v31 offset0:44 offset1:76
	s_waitcnt lgkmcnt(0)
	ds_read_b128 v[0:3], v185
	ds_read_b128 v[4:7], v185 offset:16
	s_waitcnt vmcnt(3)
	v_lshlrev_b32_e32 v8, 16, v76
	v_and_b32_e32 v9, 0xffff0000, v76
	v_or_b32_e32 v76, 0x60, v181
	s_waitcnt lgkmcnt(1)
	v_pk_fma_f32 v[8:9], v[132:133], v[0:1], v[8:9]
	v_lshlrev_b32_e32 v0, 16, v77
	v_and_b32_e32 v1, 0xffff0000, v77
	v_pk_fma_f32 v[10:11], v[134:135], v[2:3], v[0:1]
	v_lshlrev_b32_e32 v0, 16, v78
	v_and_b32_e32 v1, 0xffff0000, v78
	s_waitcnt lgkmcnt(0)
	v_pk_fma_f32 v[12:13], v[128:129], v[4:5], v[0:1]
	v_lshlrev_b32_e32 v0, 16, v79
	v_and_b32_e32 v1, 0xffff0000, v79
	v_pk_fma_f32 v[14:15], v[130:131], v[6:7], v[0:1]
	v_pk_mul_f32 v[0:1], v[8:9], v[8:9]
	v_pk_mul_f32 v[4:5], v[12:13], v[12:13]
	v_pk_mul_f32 v[2:3], v[10:11], v[10:11]
	v_pk_mul_f32 v[6:7], v[14:15], v[14:15]
	v_add_f32_e32 v4, v4, v5
	v_add_f32_e32 v0, v0, v1
	v_add_f32_e32 v4, v6, v4
	v_add_f32_e32 v0, v2, v0
	v_add_f32_e32 v4, v7, v4
	v_add_f32_e32 v0, v3, v0
	v_add_f32_e32 v0, v0, v4
	ds_bpermute_b32 v1, v175, v0
	s_waitcnt lgkmcnt(0)
	v_add_f32_e32 v0, v0, v1
	ds_bpermute_b32 v1, v178, v0
	s_waitcnt lgkmcnt(0)
	v_add_f32_e32 v0, v0, v1
	ds_bpermute_b32 v1, v183, v0
	s_and_saveexec_b64 s[0:1], vcc
	s_cbranch_execz .LBB0_1916
	v_lshl_add_u32 v2, v76, 4, s15
	s_waitcnt lgkmcnt(0)
	v_add_f32_e32 v0, v0, v1
	ds_write_b32 v2, v0
.LBB0_1916:
	s_or_b64 exec, exec, s[0:1]
	s_waitcnt lgkmcnt(0)
	ds_read_b128 v[0:3], v185 offset:2176
	ds_read_b128 v[4:7], v185 offset:2192
	s_waitcnt vmcnt(2)
	v_lshlrev_b32_e32 v16, 16, v72
	v_and_b32_e32 v17, 0xffff0000, v72
	v_lshlrev_b32_e32 v18, 16, v73
	s_waitcnt lgkmcnt(1)
	v_pk_fma_f32 v[16:17], v[132:133], v[0:1], v[16:17]
	v_lshlrev_b32_e32 v0, 16, v74
	v_and_b32_e32 v1, 0xffff0000, v74
	v_and_b32_e32 v19, 0xffff0000, v73
	s_waitcnt lgkmcnt(0)
	v_pk_fma_f32 v[20:21], v[128:129], v[4:5], v[0:1]
	v_lshlrev_b32_e32 v0, 16, v75
	v_and_b32_e32 v1, 0xffff0000, v75
	v_pk_fma_f32 v[18:19], v[134:135], v[2:3], v[18:19]
	v_pk_fma_f32 v[22:23], v[130:131], v[6:7], v[0:1]
	v_pk_mul_f32 v[0:1], v[16:17], v[16:17]
	v_pk_mul_f32 v[4:5], v[20:21], v[20:21]
	v_pk_mul_f32 v[2:3], v[18:19], v[18:19]
	v_pk_mul_f32 v[6:7], v[22:23], v[22:23]
	v_add_f32_e32 v4, v4, v5
	v_add_f32_e32 v0, v0, v1
	v_add_f32_e32 v4, v6, v4
	v_add_f32_e32 v0, v2, v0
	v_add_f32_e32 v4, v7, v4
	v_add_f32_e32 v0, v3, v0
	v_add_f32_e32 v0, v0, v4
	ds_bpermute_b32 v1, v175, v0
	s_waitcnt lgkmcnt(0)
	v_add_f32_e32 v0, v0, v1
	ds_bpermute_b32 v1, v178, v0
	s_waitcnt lgkmcnt(0)
	v_add_f32_e32 v0, v0, v1
	ds_bpermute_b32 v1, v183, v0
	s_and_saveexec_b64 s[0:1], vcc
	s_cbranch_execz .LBB0_1918
	s_waitcnt lgkmcnt(0)
	v_add_f32_e32 v0, v0, v1
	ds_write_b32 v182, v0 offset:1664
.LBB0_1918:
	s_or_b64 exec, exec, s[0:1]
	s_waitcnt lgkmcnt(0)
	ds_read_b128 v[0:3], v185 offset:4352
	ds_read_b128 v[4:7], v185 offset:4368
	s_waitcnt vmcnt(1)
	v_lshlrev_b32_e32 v24, 16, v68
	v_and_b32_e32 v25, 0xffff0000, v68
	v_lshlrev_b32_e32 v26, 16, v69
	s_waitcnt lgkmcnt(1)
	v_pk_fma_f32 v[24:25], v[132:133], v[0:1], v[24:25]
	v_lshlrev_b32_e32 v0, 16, v70
	v_and_b32_e32 v1, 0xffff0000, v70
	v_and_b32_e32 v27, 0xffff0000, v69
	s_waitcnt lgkmcnt(0)
	v_pk_fma_f32 v[28:29], v[128:129], v[4:5], v[0:1]
	v_lshlrev_b32_e32 v0, 16, v71
	v_and_b32_e32 v1, 0xffff0000, v71
	v_pk_fma_f32 v[26:27], v[134:135], v[2:3], v[26:27]
	v_pk_fma_f32 v[30:31], v[130:131], v[6:7], v[0:1]
	v_pk_mul_f32 v[0:1], v[24:25], v[24:25]
	v_pk_mul_f32 v[4:5], v[28:29], v[28:29]
	v_pk_mul_f32 v[2:3], v[26:27], v[26:27]
	v_pk_mul_f32 v[6:7], v[30:31], v[30:31]
	v_add_f32_e32 v4, v4, v5
	v_add_f32_e32 v0, v0, v1
	v_add_f32_e32 v4, v6, v4
	v_add_f32_e32 v0, v2, v0
	v_add_f32_e32 v4, v7, v4
	v_add_f32_e32 v0, v3, v0
	v_add_f32_e32 v0, v0, v4
	ds_bpermute_b32 v1, v175, v0
	s_waitcnt lgkmcnt(0)
	v_add_f32_e32 v0, v0, v1
	ds_bpermute_b32 v1, v178, v0
	s_waitcnt lgkmcnt(0)
	v_add_f32_e32 v0, v0, v1
	ds_bpermute_b32 v1, v183, v0
	s_and_saveexec_b64 s[0:1], vcc
	s_cbranch_execz .LBB0_1920
	s_waitcnt lgkmcnt(0)
	v_add_f32_e32 v0, v0, v1
	ds_write_b32 v182, v0 offset:1792
.LBB0_1920:
	s_or_b64 exec, exec, s[0:1]
	s_waitcnt lgkmcnt(0)
	ds_read_b128 v[0:3], v185 offset:6528
	ds_read_b128 v[4:7], v185 offset:6544
	s_waitcnt vmcnt(0)
	v_lshlrev_b32_e32 v68, 16, v64
	v_and_b32_e32 v69, 0xffff0000, v64
	v_lshlrev_b32_e32 v64, 16, v65
	s_waitcnt lgkmcnt(1)
	v_pk_fma_f32 v[68:69], v[132:133], v[0:1], v[68:69]
	v_lshlrev_b32_e32 v0, 16, v66
	v_and_b32_e32 v1, 0xffff0000, v66
	v_and_b32_e32 v65, 0xffff0000, v65
	s_waitcnt lgkmcnt(0)
	v_pk_fma_f32 v[70:71], v[128:129], v[4:5], v[0:1]
	v_lshlrev_b32_e32 v0, 16, v67
	v_and_b32_e32 v1, 0xffff0000, v67
	v_pk_fma_f32 v[64:65], v[134:135], v[2:3], v[64:65]
	v_pk_fma_f32 v[66:67], v[130:131], v[6:7], v[0:1]
	v_pk_mul_f32 v[0:1], v[68:69], v[68:69]
	v_pk_mul_f32 v[4:5], v[70:71], v[70:71]
	v_pk_mul_f32 v[2:3], v[64:65], v[64:65]
	v_pk_mul_f32 v[6:7], v[66:67], v[66:67]
	v_add_f32_e32 v4, v4, v5
	v_add_f32_e32 v0, v0, v1
	v_add_f32_e32 v4, v6, v4
	v_add_f32_e32 v0, v2, v0
	v_add_f32_e32 v4, v7, v4
	v_add_f32_e32 v0, v3, v0
	v_add_f32_e32 v0, v0, v4
	ds_bpermute_b32 v1, v175, v0
	s_waitcnt lgkmcnt(0)
	v_add_f32_e32 v0, v0, v1
	ds_bpermute_b32 v1, v178, v0
	s_waitcnt lgkmcnt(0)
	v_add_f32_e32 v0, v0, v1
	ds_bpermute_b32 v1, v183, v0
	s_and_saveexec_b64 s[0:1], vcc
	s_cbranch_execz .LBB0_1922
	s_waitcnt lgkmcnt(0)
	v_add_f32_e32 v0, v0, v1
	ds_write_b32 v182, v0 offset:1920
.LBB0_1922:
	s_or_b64 exec, exec, s[0:1]
	s_waitcnt lgkmcnt(0)
	v_cmp_gt_i32_e32 vcc, s85, v174
	s_waitcnt lgkmcnt(0)
	s_barrier
	s_and_saveexec_b64 s[0:1], vcc
	s_xor_b64 s[0:1], exec, s[0:1]
	s_cbranch_execz .LBB0_1887
	v_lshl_add_u32 v0, v174, 4, 0
	v_add_u32_e32 v0, 0x24000, v0
	ds_read_b128 v[0:3], v0
	s_lshl_b64 s[18:19], s[16:17], 17
	s_add_u32 s17, s50, s18
	s_addc_u32 s21, s51, s19
	s_ashr_i32 s15, s14, 31
	s_waitcnt lgkmcnt(0)
	v_mov_b32_e32 v4, v1
	v_mov_b32_e32 v5, v2
	v_mov_b32_e32 v1, v3
	s_lshl_b64 s[18:19], s[14:15], 2
	v_pk_add_f32 v[0:1], v[4:5], v[0:1]
	s_add_u32 s20, s17, s18
	v_add_f32_e32 v0, v0, v1
	s_addc_u32 s21, s21, s19
	v_ashrrev_i32_e32 v175, 31, v174
	v_add_f32_e32 v1, 0xda24260, v0
	v_lshl_add_u64 v[2:3], v[174:175], 2, s[20:21]
	global_store_dword v[2:3], v1, off sc1
	s_cmp_eq_u32 s16, 0
	v_mov_b32_e32 v2, v1
	s_cbranch_scc1 .LBB0_1946
	s_add_u32 s20, s50, s18
	s_addc_u32 s21, s51, s19
	v_lshl_add_u64 v[4:5], v[174:175], 2, s[20:21]
	s_mov_b32 s15, 0x100000
	s_mov_b64 s[20:21], 0
	s_branch .LBB0_1934

.LBB0_2071:
	global_load_dwordx4 v[30:33], v[6:7], off
	v_pk_mul_f32 v[46:47], v[20:21], v[20:21]
	v_pk_mul_f32 v[48:49], v[16:17], v[16:17]
	v_pk_mul_f32 v[34:35], v[10:11], v[10:11]
	v_pk_mul_f32 v[36:37], v[14:15], v[14:15]
	v_pk_mul_f32 v[38:39], v[8:9], v[8:9]
	v_pk_mul_f32 v[40:41], v[12:13], v[12:13]
	v_pk_mul_f32 v[42:43], v[22:23], v[22:23]
	v_pk_mul_f32 v[44:45], v[18:19], v[18:19]
	v_mov_b32_e32 v52, v46
	v_mov_b32_e32 v53, v48
	v_mov_b32_e32 v48, v47
	v_mov_b32_e32 v46, v42
	v_mov_b32_e32 v47, v44
	v_mov_b32_e32 v44, v43
	v_mov_b32_e32 v42, v38
	v_mov_b32_e32 v43, v40
	v_mov_b32_e32 v40, v39
	v_mov_b32_e32 v38, v34
	v_mov_b32_e32 v39, v36
	v_mov_b32_e32 v36, v35
	v_pk_add_f32 v[34:35], v[52:53], v[48:49]
	v_add_u32_e32 v54, s0, v2
	v_pk_add_f32 v[40:41], v[42:43], v[40:41]
	v_pk_add_f32 v[34:35], v[46:47], v[34:35]
	v_cmp_gt_i32_e32 vcc, s6, v54
	v_pk_add_f32 v[38:39], v[38:39], v[40:41]
	v_pk_add_f32 v[34:35], v[44:45], v[34:35]
	v_cndmask_b32_e32 v50, v2, v54, vcc
	v_pk_add_f32 v[36:37], v[36:37], v[38:39]
	v_add_f32_e32 v2, v34, v35
	v_add_f32_e32 v2, v37, v2
	v_add_f32_e32 v2, v36, v2
	ds_bpermute_b32 v34, v3, v2
	v_ashrrev_i32_e32 v51, 31, v50
	v_lshlrev_b64 v[42:43], 11, v[50:51]
	v_lshl_add_u64 v[40:41], v[0:1], 0, v[42:43]
	global_load_dwordx2 v[38:39], v[40:41], off
	global_load_dwordx2 v[42:43], v[40:41], off offset:512
	global_load_dwordx2 v[44:45], v[40:41], off offset:1024
	global_load_dwordx2 v[46:47], v[40:41], off offset:1536
	s_waitcnt lgkmcnt(0)
	v_add_f32_e32 v2, v2, v34
	ds_bpermute_b32 v34, v25, v2
	s_waitcnt lgkmcnt(0)
	v_add_f32_e32 v2, v2, v34
	ds_bpermute_b32 v34, v26, v2
	s_waitcnt lgkmcnt(0)
	v_add_f32_e32 v2, v2, v34
	ds_bpermute_b32 v34, v27, v2
	s_waitcnt lgkmcnt(0)
	v_add_f32_e32 v2, v2, v34
	ds_bpermute_b32 v34, v28, v2
	s_waitcnt lgkmcnt(0)
	v_add_f32_e32 v2, v2, v34
	ds_bpermute_b32 v34, v29, v2
	s_waitcnt lgkmcnt(0)
	v_add_f32_e32 v2, v2, v34
	v_fmamk_f32 v2, v2, 0x3a800000, v24
	v_mul_f32_e32 v34, 0x4b800000, v2
	v_cmp_gt_f32_e32 vcc, s1, v2
	s_waitcnt vmcnt(1)
	v_lshlrev_b32_e32 v40, 16, v45
	v_cndmask_b32_e32 v2, v2, v34, vcc
	v_rsq_f32_e32 v2, v2
	v_and_b32_e32 v41, 0xffff0000, v45
	s_waitcnt vmcnt(0)
	v_and_b32_e32 v45, 0xffff0000, v47
	v_mul_f32_e32 v34, 0x45800000, v2
	v_cndmask_b32_e32 v34, v2, v34, vcc
	v_pk_mul_f32 v[20:21], v[20:21], v[34:35] op_sel_hi:[1,0]
	v_pk_mul_f32 v[22:23], v[22:23], v[34:35] op_sel_hi:[1,0]
	v_pk_mul_f32 v[20:21], v[30:31], v[20:21]
	v_pk_mul_f32 v[22:23], v[32:33], v[22:23]
	global_store_dwordx4 v[4:5], v[20:23], off
	global_load_dwordx4 v[20:23], v[6:7], off offset:1024
	v_pk_mul_f32 v[16:17], v[16:17], v[34:35] op_sel_hi:[1,0]
	v_pk_mul_f32 v[18:19], v[18:19], v[34:35] op_sel_hi:[1,0]
	v_pk_mul_f32 v[12:13], v[12:13], v[34:35] op_sel_hi:[1,0]
	v_pk_mul_f32 v[14:15], v[14:15], v[34:35] op_sel_hi:[1,0]
	v_pk_mul_f32 v[36:37], v[8:9], v[34:35] op_sel_hi:[1,0]
	v_pk_mul_f32 v[34:35], v[10:11], v[34:35] op_sel_hi:[1,0]
	v_cmp_lt_i32_e32 vcc, s7, v54
	v_mov_b32_e32 v2, v54
	s_or_b64 s[2:3], vcc, s[2:3]
	v_mov_b32_e32 v11, v45
	s_waitcnt vmcnt(0)
	v_pk_mul_f32 v[16:17], v[20:21], v[16:17]
	v_pk_mul_f32 v[18:19], v[22:23], v[18:19]
	global_store_dwordx4 v[4:5], v[16:19], off offset:1024
	global_load_dwordx4 v[16:19], v[6:7], off offset:2048
	v_lshlrev_b32_e32 v20, 16, v38
	v_and_b32_e32 v21, 0xffff0000, v38
	v_lshlrev_b32_e32 v22, 16, v39
	v_and_b32_e32 v23, 0xffff0000, v39
	v_lshlrev_b32_e32 v38, 16, v44
	v_and_b32_e32 v39, 0xffff0000, v44
	v_lshlrev_b32_e32 v44, 16, v47
	v_mov_b32_e32 v10, v44
	s_waitcnt vmcnt(0)
	v_pk_mul_f32 v[12:13], v[16:17], v[12:13]
	v_pk_mul_f32 v[14:15], v[18:19], v[14:15]
	global_store_dwordx4 v[4:5], v[12:15], off offset:2048
	global_load_dwordx4 v[30:33], v[6:7], off offset:3072
	v_lshlrev_b32_e32 v16, 16, v42
	v_and_b32_e32 v17, 0xffff0000, v42
	v_lshlrev_b32_e32 v18, 16, v43
	v_and_b32_e32 v19, 0xffff0000, v43
	v_lshlrev_b32_e32 v42, 16, v46
	v_and_b32_e32 v43, 0xffff0000, v46
	v_mov_b32_e32 v12, v38
	v_mov_b32_e32 v13, v39
	v_mov_b32_e32 v14, v40
	v_mov_b32_e32 v15, v41
	v_mov_b32_e32 v8, v42
	v_mov_b32_e32 v9, v43
	s_waitcnt vmcnt(0)
	v_pk_mul_f32 v[30:31], v[30:31], v[36:37]
	v_pk_mul_f32 v[32:33], v[32:33], v[34:35]
	global_store_dwordx4 v[4:5], v[30:33], off offset:3072
	v_lshl_add_u64 v[4:5], v[4:5], 0, s[4:5]
	s_andn2_b64 exec, exec, s[2:3]
	s_cbranch_execnz .LBB0_2071

	.amdhsa_kernel _Z10fwd_kernel6Params
		.amdhsa_group_segment_fixed_size 0
		.amdhsa_private_segment_fixed_size 0
		.amdhsa_kernarg_size 504
		.amdhsa_user_sgpr_count 2
		.amdhsa_user_sgpr_dispatch_ptr 0
		.amdhsa_user_sgpr_queue_ptr 0
		.amdhsa_user_sgpr_kernarg_segment_ptr 1
		.amdhsa_user_sgpr_dispatch_id 0
		.amdhsa_user_sgpr_kernarg_preload_length 0
		.amdhsa_user_sgpr_kernarg_preload_offset 0
		.amdhsa_user_sgpr_private_segment_size 0
		.amdhsa_uses_dynamic_stack 0
		.amdhsa_enable_private_segment 0
		.amdhsa_system_sgpr_workgroup_id_x 1
		.amdhsa_system_sgpr_workgroup_id_y 0
		.amdhsa_system_sgpr_workgroup_id_z 0
		.amdhsa_system_sgpr_workgroup_info 0
		.amdhsa_system_vgpr_workitem_id 2
		.amdhsa_next_free_vgpr 255
		.amdhsa_next_free_sgpr 102
		.amdhsa_accum_offset 256
		.amdhsa_reserve_vcc 1
		.amdhsa_float_round_mode_32 0
		.amdhsa_float_round_mode_16_64 0
		.amdhsa_float_denorm_mode_32 3
		.amdhsa_float_denorm_mode_16_64 3
		.amdhsa_dx10_clamp 1
		.amdhsa_ieee_mode 1
		.amdhsa_fp16_overflow 0
		.amdhsa_tg_split 0
		.amdhsa_exception_fp_ieee_invalid_op 0
		.amdhsa_exception_fp_denorm_src 0
		.amdhsa_exception_fp_ieee_div_zero 0
		.amdhsa_exception_fp_ieee_overflow 0
		.amdhsa_exception_fp_ieee_underflow 0
		.amdhsa_exception_fp_ieee_inexact 0
		.amdhsa_exception_int_div_zero 0
	.end_amdhsa_kernel
